# hyena FFT passes: multiply-by-(+-i) operands folded into the packed f32 consumers with op_sel / neg_lo / neg_hi instead of a v_xor + v_mov per operand (about 1000 VALU instructions fewer per channel p
# speedup vs baseline: 1.1281x; 1.0142x over previous
.LBB0_536:
	s_nop 1
	v_lshlrev_b32_e32 v0, 2, v146
	s_add_i32 s47, 16, 0x10000
	v_add_u32_e32 v64, 16, v0
	v_add_u32_e32 v65, s47, v0
	s_waitcnt lgkmcnt(0)
	s_barrier
	ds_read2st64_b32 v[2:3], v64 offset1:8
	ds_read2st64_b32 v[4:5], v65 offset1:8
	ds_read2st64_b32 v[8:9], v64 offset0:16 offset1:24
	ds_read2st64_b32 v[10:11], v65 offset0:16 offset1:24
	ds_read2st64_b32 v[12:13], v64 offset0:32 offset1:40
	ds_read2st64_b32 v[14:15], v65 offset0:32 offset1:40
	s_mov_b32 s49, s40
	s_waitcnt lgkmcnt(5)
	v_mov_b32_e32 v6, v2
	s_waitcnt lgkmcnt(4)
	v_mov_b32_e32 v7, v4
	v_mov_b32_e32 v4, v3
	s_waitcnt lgkmcnt(3)
	v_mov_b32_e32 v2, v8
	s_waitcnt lgkmcnt(2)
	v_mov_b32_e32 v3, v10
	v_mov_b32_e32 v10, v9
	ds_read2st64_b32 v[8:9], v64 offset0:48 offset1:56
	ds_read2st64_b32 v[16:17], v65 offset0:48 offset1:56
	s_waitcnt lgkmcnt(3)
	v_mov_b32_e32 v18, v12
	s_waitcnt lgkmcnt(2)
	v_mov_b32_e32 v19, v14
	v_mov_b32_e32 v14, v13
	s_waitcnt lgkmcnt(1)
	v_mov_b32_e32 v12, v8
	s_waitcnt lgkmcnt(0)
	v_mov_b32_e32 v13, v16
	ds_read2st64_b32 v[20:21], v64 offset0:64 offset1:72
	ds_read2st64_b32 v[22:23], v65 offset0:64 offset1:72
	v_mov_b32_e32 v16, v9
	ds_read2st64_b32 v[8:9], v64 offset0:80 offset1:88
	ds_read2st64_b32 v[24:25], v65 offset0:80 offset1:88
	s_mov_b32 s41, s45
	s_waitcnt lgkmcnt(3)
	v_mov_b32_e32 v26, v20
	s_waitcnt lgkmcnt(2)
	v_mov_b32_e32 v27, v22
	v_mov_b32_e32 v22, v21
	s_waitcnt lgkmcnt(1)
	v_mov_b32_e32 v28, v8
	s_waitcnt lgkmcnt(0)
	v_mov_b32_e32 v29, v24
	ds_read2st64_b32 v[20:21], v64 offset0:96 offset1:104
	ds_read2st64_b32 v[30:31], v65 offset0:96 offset1:104
	v_mov_b32_e32 v24, v9
	ds_read2st64_b32 v[8:9], v64 offset0:112 offset1:120
	ds_read2st64_b32 v[32:33], v65 offset0:112 offset1:120
	v_and_b32_e32 v196, 63, v146
	v_lshlrev_b32_e32 v196, 2, v196
	v_and_b32_e32 v0, 0xffffffc0, v146
	v_lshl_add_u32 v0, v0, 5, v196
	v_add_u32_e32 v0, 0x400, v0
	s_waitcnt lgkmcnt(3)
	v_mov_b32_e32 v34, v20
	s_waitcnt lgkmcnt(2)
	v_mov_b32_e32 v35, v30
	v_mov_b32_e32 v30, v21
	s_waitcnt lgkmcnt(1)
	v_mov_b32_e32 v36, v8
	s_waitcnt lgkmcnt(0)
	v_mov_b32_e32 v37, v32
	ds_read2st64_b32 v[20:21], v64 offset0:128 offset1:136
	ds_read2st64_b32 v[38:39], v65 offset0:128 offset1:136
	v_mov_b32_e32 v32, v9
	ds_read2st64_b32 v[8:9], v64 offset0:144 offset1:152
	ds_read2st64_b32 v[40:41], v65 offset0:144 offset1:152
	v_readlane_b32 s0, v252, 48
	s_waitcnt lgkmcnt(3)
	v_mov_b32_e32 v42, v20
	s_waitcnt lgkmcnt(2)
	v_mov_b32_e32 v43, v38
	v_mov_b32_e32 v38, v21
	s_waitcnt lgkmcnt(1)
	v_mov_b32_e32 v44, v8
	s_waitcnt lgkmcnt(0)
	v_mov_b32_e32 v45, v40
	ds_read2st64_b32 v[20:21], v64 offset0:160 offset1:168
	ds_read2st64_b32 v[46:47], v65 offset0:160 offset1:168
	v_mov_b32_e32 v40, v9
	ds_read2st64_b32 v[8:9], v64 offset0:176 offset1:184
	ds_read2st64_b32 v[48:49], v65 offset0:176 offset1:184
	v_ashrrev_i32_e32 v1, 31, v0
	s_waitcnt lgkmcnt(3)
	v_mov_b32_e32 v50, v20
	s_waitcnt lgkmcnt(2)
	v_mov_b32_e32 v51, v46
	v_mov_b32_e32 v46, v21
	s_waitcnt lgkmcnt(1)
	v_mov_b32_e32 v52, v8
	s_waitcnt lgkmcnt(0)
	v_mov_b32_e32 v53, v48
	ds_read2st64_b32 v[20:21], v64 offset0:192 offset1:200
	ds_read2st64_b32 v[54:55], v65 offset0:192 offset1:200
	v_mov_b32_e32 v48, v9
	ds_read2st64_b32 v[8:9], v64 offset0:208 offset1:216
	ds_read2st64_b32 v[56:57], v65 offset0:208 offset1:216
	v_readlane_b32 s1, v252, 49
	s_waitcnt lgkmcnt(3)
	v_mov_b32_e32 v58, v20
	s_waitcnt lgkmcnt(2)
	v_mov_b32_e32 v59, v54
	v_mov_b32_e32 v54, v21
	s_waitcnt lgkmcnt(1)
	v_mov_b32_e32 v60, v8
	s_waitcnt lgkmcnt(0)
	v_mov_b32_e32 v61, v56
	ds_read2st64_b32 v[20:21], v64 offset0:224 offset1:232
	ds_read2st64_b32 v[62:63], v65 offset0:224 offset1:232
	v_mov_b32_e32 v56, v9
	ds_read2st64_b32 v[8:9], v64 offset0:240 offset1:248
	ds_read2st64_b32 v[64:65], v65 offset0:240 offset1:248
	s_waitcnt lgkmcnt(0)
	v_mov_b32_e32 v66, v20
	v_mov_b32_e32 v67, v62
	v_mov_b32_e32 v72, v8
	v_mov_b32_e32 v73, v64
	v_mov_b32_e32 v64, v9
	v_pk_add_f32 v[8:9], v[6:7], v[42:43]
	v_pk_add_f32 v[6:7], v[6:7], v[42:43] neg_lo:[0,1] neg_hi:[0,1]
	v_pk_add_f32 v[42:43], v[4:5], v[38:39]
	v_pk_add_f32 v[4:5], v[4:5], v[38:39] neg_lo:[0,1] neg_hi:[0,1]
	v_mov_b32_e32 v62, v21
	v_pk_mul_f32 v[38:39], v[4:5], s[58:59] op_sel:[1,0] op_sel_hi:[0,0] neg_hi:[1,0]
	v_mov_b32_e32 v21, v146
	v_pk_fma_f32 v[4:5], v[4:5], s[46:47], v[38:39] op_sel_hi:[1,0,1]
	v_pk_add_f32 v[38:39], v[2:3], v[44:45]
	v_pk_add_f32 v[2:3], v[2:3], v[44:45] neg_lo:[0,1] neg_hi:[0,1]
	s_barrier
	s_nop 0
	s_nop 0
	v_pk_mul_f32 v[44:45], v[2:3], s[62:63] op_sel:[1,0] op_sel_hi:[0,0] neg_hi:[1,0]
	s_nop 0
	v_pk_fma_f32 v[2:3], v[2:3], s[60:61], v[44:45] op_sel_hi:[1,0,1]
	v_pk_add_f32 v[44:45], v[10:11], v[40:41]
	v_pk_add_f32 v[10:11], v[10:11], v[40:41] neg_lo:[0,1] neg_hi:[0,1]
	s_lshl_b64 s[10:11], s[68:69], 2
	s_nop 0
	s_nop 0
	v_pk_mul_f32 v[40:41], v[10:11], s[66:67] op_sel:[1,0] op_sel_hi:[0,0] neg_hi:[1,0]
	s_add_u32 s90, s54, s10
	v_pk_fma_f32 v[10:11], v[10:11], s[64:65], v[40:41] op_sel_hi:[1,0,1]
	v_pk_add_f32 v[40:41], v[18:19], v[50:51]
	v_pk_add_f32 v[18:19], v[18:19], v[50:51] neg_lo:[0,1] neg_hi:[0,1]
	s_addc_u32 s91, s55, s11
	s_nop 0
	s_nop 0
	v_pk_mul_f32 v[50:51], v[18:19], s[70:71] op_sel:[1,0] op_sel_hi:[0,0] neg_hi:[1,0]
	v_add_u32_e32 v70, 0x200, v146
	v_pk_fma_f32 v[18:19], v[18:19], s[70:71], v[50:51] op_sel_hi:[1,0,1]
	v_pk_add_f32 v[50:51], v[14:15], v[46:47]
	v_pk_add_f32 v[14:15], v[14:15], v[46:47] neg_lo:[0,1] neg_hi:[0,1]
	v_ashrrev_i32_e32 v147, 31, v146
	s_nop 0
	s_nop 0
	v_pk_mul_f32 v[46:47], v[14:15], s[64:65] op_sel:[1,0] op_sel_hi:[0,0] neg_hi:[1,0]
	v_add_u32_e32 v69, 0x400, v146
	v_pk_fma_f32 v[14:15], v[14:15], s[66:67], v[46:47] op_sel_hi:[1,0,1]
	v_pk_add_f32 v[46:47], v[12:13], v[52:53]
	v_pk_add_f32 v[12:13], v[12:13], v[52:53] neg_lo:[0,1] neg_hi:[0,1]
	v_add_u32_e32 v68, 0x600, v146
	v_pk_mul_f32 v[52:53], v[12:13], s[60:61] op_sel:[1,0] op_sel_hi:[0,0] neg_hi:[1,0]
	s_mov_b32 s16, 0
	v_pk_fma_f32 v[12:13], v[12:13], s[62:63], v[52:53] op_sel_hi:[1,0,1]
	v_pk_add_f32 v[52:53], v[16:17], v[48:49]
	v_pk_add_f32 v[16:17], v[16:17], v[48:49] neg_lo:[0,1] neg_hi:[0,1]
	s_nop 0
	v_pk_mul_f32 v[48:49], v[16:17], s[46:47] op_sel:[1,0] op_sel_hi:[0,0] neg_hi:[1,0]
	s_nop 0
	v_pk_fma_f32 v[16:17], v[16:17], s[58:59], v[48:49] op_sel_hi:[1,0,1]
	v_pk_add_f32 v[48:49], v[26:27], v[58:59]
	v_pk_add_f32 v[26:27], v[26:27], v[58:59] neg_lo:[0,1] neg_hi:[0,1]
	s_nop 0
	v_xor_b32_e32 v59, 0x80000000, v26
	v_mov_b32_e32 v58, v27
	v_pk_add_f32 v[26:27], v[22:23], v[54:55]
	v_pk_add_f32 v[22:23], v[22:23], v[54:55] neg_lo:[0,1] neg_hi:[0,1]
	s_nop 0
	v_pk_mul_f32 v[54:55], v[22:23], s[58:59] op_sel_hi:[1,0]
	v_xor_b32_e32 v75, 0x80000000, v22
	v_mov_b32_e32 v74, v23
	v_pk_fma_f32 v[22:23], v[74:75], s[46:47], v[54:55] op_sel_hi:[1,0,1] neg_lo:[0,0,1] neg_hi:[0,0,1]
	v_pk_add_f32 v[54:55], v[28:29], v[60:61]
	v_pk_add_f32 v[28:29], v[28:29], v[60:61] neg_lo:[0,1] neg_hi:[0,1]
	s_nop 0
	v_pk_mul_f32 v[60:61], v[28:29], s[62:63] op_sel_hi:[1,0]
	v_xor_b32_e32 v75, 0x80000000, v28
	v_mov_b32_e32 v74, v29
	v_pk_fma_f32 v[28:29], v[74:75], s[60:61], v[60:61] op_sel_hi:[1,0,1] neg_lo:[0,0,1] neg_hi:[0,0,1]
	v_pk_add_f32 v[60:61], v[24:25], v[56:57]
	v_pk_add_f32 v[24:25], v[24:25], v[56:57] neg_lo:[0,1] neg_hi:[0,1]
	s_nop 0
	v_pk_mul_f32 v[56:57], v[24:25], s[66:67] op_sel_hi:[1,0]
	v_xor_b32_e32 v75, 0x80000000, v24
	v_mov_b32_e32 v74, v25
	v_pk_fma_f32 v[24:25], v[74:75], s[64:65], v[56:57] op_sel_hi:[1,0,1] neg_lo:[0,0,1] neg_hi:[0,0,1]
	v_pk_add_f32 v[56:57], v[34:35], v[66:67]
	v_pk_add_f32 v[34:35], v[34:35], v[66:67] neg_lo:[0,1] neg_hi:[0,1]
	s_nop 0
	v_pk_mul_f32 v[66:67], v[34:35], s[70:71] op_sel_hi:[1,0]
	v_xor_b32_e32 v75, 0x80000000, v34
	v_mov_b32_e32 v74, v35
	v_pk_fma_f32 v[34:35], v[74:75], s[70:71], v[66:67] op_sel_hi:[1,0,1] neg_lo:[0,0,1] neg_hi:[0,0,1]
	v_pk_add_f32 v[66:67], v[30:31], v[62:63]
	v_pk_add_f32 v[30:31], v[30:31], v[62:63] neg_lo:[0,1] neg_hi:[0,1]
	s_nop 0
	v_pk_mul_f32 v[62:63], v[30:31], s[64:65] op_sel_hi:[1,0]
	v_xor_b32_e32 v75, 0x80000000, v30
	v_mov_b32_e32 v74, v31
	v_pk_fma_f32 v[30:31], v[74:75], s[66:67], v[62:63] op_sel_hi:[1,0,1] neg_lo:[0,0,1] neg_hi:[0,0,1]
	v_pk_add_f32 v[62:63], v[36:37], v[72:73]
	v_pk_add_f32 v[36:37], v[36:37], v[72:73] neg_lo:[0,1] neg_hi:[0,1]
	s_nop 0
	v_pk_mul_f32 v[72:73], v[36:37], s[60:61] op_sel_hi:[1,0]
	v_xor_b32_e32 v75, 0x80000000, v36
	v_mov_b32_e32 v74, v37
	v_pk_fma_f32 v[36:37], v[74:75], s[62:63], v[72:73] op_sel_hi:[1,0,1] neg_lo:[0,0,1] neg_hi:[0,0,1]
	v_pk_add_f32 v[72:73], v[32:33], v[64:65]
	v_pk_add_f32 v[32:33], v[32:33], v[64:65] neg_lo:[0,1] neg_hi:[0,1]
	s_nop 0
	v_pk_mul_f32 v[64:65], v[32:33], s[46:47] op_sel_hi:[1,0]
	v_xor_b32_e32 v75, 0x80000000, v32
	v_mov_b32_e32 v74, v33
	v_pk_fma_f32 v[32:33], v[74:75], s[58:59], v[64:65] op_sel_hi:[1,0,1] neg_lo:[0,0,1] neg_hi:[0,0,1]
	v_pk_add_f32 v[64:65], v[8:9], v[48:49]
	v_pk_add_f32 v[8:9], v[8:9], v[48:49] neg_lo:[0,1] neg_hi:[0,1]
	v_pk_add_f32 v[48:49], v[42:43], v[26:27]
	v_pk_add_f32 v[26:27], v[42:43], v[26:27] neg_lo:[0,1] neg_hi:[0,1]
	s_nop 0
	v_pk_mul_f32 v[42:43], v[26:27], s[62:63] op_sel:[1,0] op_sel_hi:[0,0] neg_hi:[1,0]
	s_nop 0
	v_pk_fma_f32 v[26:27], v[26:27], s[60:61], v[42:43] op_sel_hi:[1,0,1]
	v_pk_add_f32 v[42:43], v[38:39], v[54:55]
	v_pk_add_f32 v[38:39], v[38:39], v[54:55] neg_lo:[0,1] neg_hi:[0,1]
	s_nop 0
	v_pk_mul_f32 v[54:55], v[38:39], s[70:71] op_sel:[1,0] op_sel_hi:[0,0] neg_hi:[1,0]
	s_nop 0
	v_pk_fma_f32 v[38:39], v[38:39], s[70:71], v[54:55] op_sel_hi:[1,0,1]
	v_pk_add_f32 v[54:55], v[44:45], v[60:61]
	v_pk_add_f32 v[44:45], v[44:45], v[60:61] neg_lo:[0,1] neg_hi:[0,1]
	s_nop 0
	v_pk_mul_f32 v[60:61], v[44:45], s[60:61] op_sel:[1,0] op_sel_hi:[0,0] neg_hi:[1,0]
	s_nop 0
	v_pk_fma_f32 v[44:45], v[44:45], s[62:63], v[60:61] op_sel_hi:[1,0,1]
	v_pk_add_f32 v[60:61], v[40:41], v[56:57]
	v_pk_add_f32 v[40:41], v[40:41], v[56:57] neg_lo:[0,1] neg_hi:[0,1]
	s_nop 0
	v_xor_b32_e32 v57, 0x80000000, v40
	v_mov_b32_e32 v56, v41
	v_pk_add_f32 v[40:41], v[50:51], v[66:67]
	v_pk_add_f32 v[50:51], v[50:51], v[66:67] neg_lo:[0,1] neg_hi:[0,1]
	s_nop 0
	v_pk_mul_f32 v[66:67], v[50:51], s[62:63] op_sel_hi:[1,0]
	v_xor_b32_e32 v75, 0x80000000, v50
	v_mov_b32_e32 v74, v51
	v_pk_fma_f32 v[50:51], v[74:75], s[60:61], v[66:67] op_sel_hi:[1,0,1] neg_lo:[0,0,1] neg_hi:[0,0,1]
	v_pk_add_f32 v[66:67], v[46:47], v[62:63]
	v_pk_add_f32 v[46:47], v[46:47], v[62:63] neg_lo:[0,1] neg_hi:[0,1]
	s_nop 0
	v_pk_mul_f32 v[62:63], v[46:47], s[70:71] op_sel_hi:[1,0]
	v_xor_b32_e32 v75, 0x80000000, v46
	v_mov_b32_e32 v74, v47
	v_pk_fma_f32 v[46:47], v[74:75], s[70:71], v[62:63] op_sel_hi:[1,0,1] neg_lo:[0,0,1] neg_hi:[0,0,1]
	v_pk_add_f32 v[62:63], v[52:53], v[72:73]
	v_pk_add_f32 v[52:53], v[52:53], v[72:73] neg_lo:[0,1] neg_hi:[0,1]
	s_nop 0
	v_pk_mul_f32 v[72:73], v[52:53], s[60:61] op_sel_hi:[1,0]
	v_xor_b32_e32 v75, 0x80000000, v52
	v_mov_b32_e32 v74, v53
	v_pk_fma_f32 v[52:53], v[74:75], s[62:63], v[72:73] op_sel_hi:[1,0,1] neg_lo:[0,0,1] neg_hi:[0,0,1]
	v_pk_add_f32 v[72:73], v[6:7], v[58:59]
	v_pk_add_f32 v[6:7], v[6:7], v[58:59] neg_lo:[0,1] neg_hi:[0,1]
	v_pk_add_f32 v[58:59], v[4:5], v[22:23]
	v_pk_add_f32 v[4:5], v[4:5], v[22:23] neg_lo:[0,1] neg_hi:[0,1]
	s_nop 0
	v_pk_mul_f32 v[22:23], v[4:5], s[62:63] op_sel:[1,0] op_sel_hi:[0,0] neg_hi:[1,0]
	s_nop 0
	v_pk_fma_f32 v[4:5], v[4:5], s[60:61], v[22:23] op_sel_hi:[1,0,1]
	v_pk_add_f32 v[22:23], v[2:3], v[28:29]
	v_pk_add_f32 v[2:3], v[2:3], v[28:29] neg_lo:[0,1] neg_hi:[0,1]
	s_nop 0
	v_pk_mul_f32 v[28:29], v[2:3], s[70:71] op_sel:[1,0] op_sel_hi:[0,0] neg_hi:[1,0]
	s_nop 0
	v_pk_fma_f32 v[2:3], v[2:3], s[70:71], v[28:29] op_sel_hi:[1,0,1]
	v_pk_add_f32 v[28:29], v[10:11], v[24:25]
	v_pk_add_f32 v[10:11], v[10:11], v[24:25] neg_lo:[0,1] neg_hi:[0,1]
	s_nop 0
	v_pk_mul_f32 v[24:25], v[10:11], s[60:61] op_sel:[1,0] op_sel_hi:[0,0] neg_hi:[1,0]
	s_nop 0
	v_pk_fma_f32 v[10:11], v[10:11], s[62:63], v[24:25] op_sel_hi:[1,0,1]
	v_pk_add_f32 v[24:25], v[18:19], v[34:35]
	v_pk_add_f32 v[18:19], v[18:19], v[34:35] neg_lo:[0,1] neg_hi:[0,1]
	s_nop 0
	v_xor_b32_e32 v35, 0x80000000, v18
	v_mov_b32_e32 v34, v19
	v_pk_add_f32 v[18:19], v[14:15], v[30:31]
	v_pk_add_f32 v[14:15], v[14:15], v[30:31] neg_lo:[0,1] neg_hi:[0,1]
	s_nop 0
	v_pk_mul_f32 v[30:31], v[14:15], s[62:63] op_sel_hi:[1,0]
	v_xor_b32_e32 v75, 0x80000000, v14
	v_mov_b32_e32 v74, v15
	v_pk_fma_f32 v[14:15], v[74:75], s[60:61], v[30:31] op_sel_hi:[1,0,1] neg_lo:[0,0,1] neg_hi:[0,0,1]
	v_pk_add_f32 v[30:31], v[12:13], v[36:37]
	v_pk_add_f32 v[12:13], v[12:13], v[36:37] neg_lo:[0,1] neg_hi:[0,1]
	s_nop 0
	v_pk_mul_f32 v[36:37], v[12:13], s[70:71] op_sel_hi:[1,0]
	v_xor_b32_e32 v75, 0x80000000, v12
	v_mov_b32_e32 v74, v13
	v_pk_fma_f32 v[12:13], v[74:75], s[70:71], v[36:37] op_sel_hi:[1,0,1] neg_lo:[0,0,1] neg_hi:[0,0,1]
	v_pk_add_f32 v[36:37], v[16:17], v[32:33]
	v_pk_add_f32 v[16:17], v[16:17], v[32:33] neg_lo:[0,1] neg_hi:[0,1]
	s_nop 0
	v_pk_mul_f32 v[32:33], v[16:17], s[60:61] op_sel_hi:[1,0]
	v_xor_b32_e32 v75, 0x80000000, v16
	v_mov_b32_e32 v74, v17
	v_pk_fma_f32 v[16:17], v[74:75], s[62:63], v[32:33] op_sel_hi:[1,0,1] neg_lo:[0,0,1] neg_hi:[0,0,1]
	v_pk_add_f32 v[32:33], v[64:65], v[60:61]
	v_pk_add_f32 v[60:61], v[64:65], v[60:61] neg_lo:[0,1] neg_hi:[0,1]
	v_pk_add_f32 v[64:65], v[48:49], v[40:41]
	v_pk_add_f32 v[40:41], v[48:49], v[40:41] neg_lo:[0,1] neg_hi:[0,1]
	s_nop 0
	v_pk_mul_f32 v[48:49], v[40:41], s[70:71] op_sel:[1,0] op_sel_hi:[0,0] neg_hi:[1,0]
	s_nop 0
	v_pk_fma_f32 v[40:41], v[40:41], s[70:71], v[48:49] op_sel_hi:[1,0,1]
	v_pk_add_f32 v[48:49], v[42:43], v[66:67]
	v_pk_add_f32 v[42:43], v[42:43], v[66:67] neg_lo:[0,1] neg_hi:[0,1]
	s_nop 0
	v_xor_b32_e32 v67, 0x80000000, v42
	v_mov_b32_e32 v66, v43
	v_pk_add_f32 v[42:43], v[54:55], v[62:63]
	v_pk_add_f32 v[54:55], v[54:55], v[62:63] neg_lo:[0,1] neg_hi:[0,1]
	s_nop 0
	v_pk_mul_f32 v[62:63], v[54:55], s[70:71] op_sel_hi:[1,0]
	v_xor_b32_e32 v75, 0x80000000, v54
	v_mov_b32_e32 v74, v55
	v_pk_fma_f32 v[54:55], v[74:75], s[70:71], v[62:63] op_sel_hi:[1,0,1] neg_lo:[0,0,1] neg_hi:[0,0,1]
	v_pk_add_f32 v[62:63], v[8:9], v[56:57]
	v_pk_add_f32 v[8:9], v[8:9], v[56:57] neg_lo:[0,1] neg_hi:[0,1]
	v_pk_add_f32 v[56:57], v[26:27], v[50:51]
	v_pk_add_f32 v[26:27], v[26:27], v[50:51] neg_lo:[0,1] neg_hi:[0,1]
	s_nop 0
	v_pk_mul_f32 v[50:51], v[26:27], s[70:71] op_sel:[1,0] op_sel_hi:[0,0] neg_hi:[1,0]
	s_nop 0
	v_pk_fma_f32 v[26:27], v[26:27], s[70:71], v[50:51] op_sel_hi:[1,0,1]
	v_pk_add_f32 v[50:51], v[38:39], v[46:47]
	v_pk_add_f32 v[38:39], v[38:39], v[46:47] neg_lo:[0,1] neg_hi:[0,1]
	s_nop 0
	v_xor_b32_e32 v47, 0x80000000, v38
	v_mov_b32_e32 v46, v39
	v_pk_add_f32 v[38:39], v[44:45], v[52:53]
	v_pk_add_f32 v[44:45], v[44:45], v[52:53] neg_lo:[0,1] neg_hi:[0,1]
	s_nop 0
	v_pk_mul_f32 v[52:53], v[44:45], s[70:71] op_sel_hi:[1,0]
	v_xor_b32_e32 v75, 0x80000000, v44
	v_mov_b32_e32 v74, v45
	v_pk_fma_f32 v[44:45], v[74:75], s[70:71], v[52:53] op_sel_hi:[1,0,1] neg_lo:[0,0,1] neg_hi:[0,0,1]
	v_pk_add_f32 v[52:53], v[72:73], v[24:25]
	v_pk_add_f32 v[24:25], v[72:73], v[24:25] neg_lo:[0,1] neg_hi:[0,1]
	v_pk_add_f32 v[72:73], v[58:59], v[18:19]
	v_pk_add_f32 v[18:19], v[58:59], v[18:19] neg_lo:[0,1] neg_hi:[0,1]
	s_nop 0
	v_pk_mul_f32 v[58:59], v[18:19], s[70:71] op_sel:[1,0] op_sel_hi:[0,0] neg_hi:[1,0]
	s_nop 0
	v_pk_fma_f32 v[18:19], v[18:19], s[70:71], v[58:59] op_sel_hi:[1,0,1]
	v_pk_add_f32 v[58:59], v[22:23], v[30:31]
	v_pk_add_f32 v[22:23], v[22:23], v[30:31] neg_lo:[0,1] neg_hi:[0,1]
	s_nop 0
	v_xor_b32_e32 v31, 0x80000000, v22
	v_mov_b32_e32 v30, v23
	v_pk_add_f32 v[22:23], v[28:29], v[36:37]
	v_pk_add_f32 v[28:29], v[28:29], v[36:37] neg_lo:[0,1] neg_hi:[0,1]
	v_pk_add_f32 v[76:77], v[24:25], v[30:31]
	v_pk_mul_f32 v[36:37], v[28:29], s[70:71] op_sel_hi:[1,0]
	v_xor_b32_e32 v75, 0x80000000, v28
	v_mov_b32_e32 v74, v29
	v_pk_fma_f32 v[28:29], v[74:75], s[70:71], v[36:37] op_sel_hi:[1,0,1] neg_lo:[0,0,1] neg_hi:[0,0,1]
	v_pk_add_f32 v[36:37], v[6:7], v[34:35]
	v_pk_add_f32 v[6:7], v[6:7], v[34:35] neg_lo:[0,1] neg_hi:[0,1]
	v_pk_add_f32 v[34:35], v[4:5], v[14:15]
	v_pk_add_f32 v[4:5], v[4:5], v[14:15] neg_lo:[0,1] neg_hi:[0,1]
	v_pk_add_f32 v[78:79], v[18:19], v[28:29]
	v_pk_mul_f32 v[14:15], v[4:5], s[70:71] op_sel:[1,0] op_sel_hi:[0,0] neg_hi:[1,0]
	v_pk_add_f32 v[18:19], v[18:19], v[28:29] neg_lo:[0,1] neg_hi:[0,1]
	v_pk_fma_f32 v[4:5], v[4:5], s[70:71], v[14:15] op_sel_hi:[1,0,1]
	v_pk_add_f32 v[14:15], v[2:3], v[12:13]
	v_pk_add_f32 v[2:3], v[2:3], v[12:13] neg_lo:[0,1] neg_hi:[0,1]
	v_xor_b32_e32 v81, 0x80000000, v18
	v_xor_b32_e32 v13, 0x80000000, v2
	v_mov_b32_e32 v12, v3
	v_pk_add_f32 v[2:3], v[10:11], v[16:17]
	v_pk_add_f32 v[10:11], v[10:11], v[16:17] neg_lo:[0,1] neg_hi:[0,1]
	v_mov_b32_e32 v80, v19
	v_pk_mul_f32 v[16:17], v[10:11], s[70:71] op_sel_hi:[1,0]
	s_nop 0
	v_pk_fma_f32 v[10:11], v[10:11], s[70:71], v[16:17] op_sel:[1,0,0] op_sel_hi:[0,0,1] neg_lo:[0,0,1] neg_hi:[1,0,1]
	v_pk_add_f32 v[74:75], v[62:63], v[50:51]
	v_pk_add_f32 v[50:51], v[62:63], v[50:51] neg_lo:[0,1] neg_hi:[0,1]
	v_pk_add_f32 v[62:63], v[56:57], v[38:39]
	v_pk_add_f32 v[38:39], v[56:57], v[38:39] neg_lo:[0,1] neg_hi:[0,1]
	v_pk_add_f32 v[16:17], v[32:33], v[48:49]
	v_pk_add_f32 v[32:33], v[32:33], v[48:49] neg_lo:[0,1] neg_hi:[0,1]
	v_pk_add_f32 v[48:49], v[64:65], v[42:43]
	v_pk_add_f32 v[42:43], v[64:65], v[42:43] neg_lo:[0,1] neg_hi:[0,1]
	v_xor_b32_e32 v57, 0x80000000, v38
	v_mov_b32_e32 v56, v39
	v_pk_add_f32 v[38:39], v[8:9], v[46:47]
	v_pk_add_f32 v[8:9], v[8:9], v[46:47] neg_lo:[0,1] neg_hi:[0,1]
	v_pk_add_f32 v[46:47], v[26:27], v[44:45]
	v_pk_add_f32 v[26:27], v[26:27], v[44:45] neg_lo:[0,1] neg_hi:[0,1]
	v_xor_b32_e32 v65, 0x80000000, v42
	v_mov_b32_e32 v64, v43
	v_pk_add_f32 v[42:43], v[60:61], v[66:67]
	v_pk_add_f32 v[60:61], v[60:61], v[66:67] neg_lo:[0,1] neg_hi:[0,1]
	v_pk_add_f32 v[66:67], v[40:41], v[54:55]
	v_pk_add_f32 v[40:41], v[40:41], v[54:55] neg_lo:[0,1] neg_hi:[0,1]
	v_xor_b32_e32 v45, 0x80000000, v26
	v_mov_b32_e32 v44, v27
	v_pk_add_f32 v[26:27], v[52:53], v[58:59]
	v_pk_add_f32 v[52:53], v[52:53], v[58:59] neg_lo:[0,1] neg_hi:[0,1]
	v_pk_add_f32 v[58:59], v[72:73], v[22:23]
	v_pk_add_f32 v[22:23], v[72:73], v[22:23] neg_lo:[0,1] neg_hi:[0,1]
	v_pk_add_f32 v[18:19], v[36:37], v[14:15]
	v_pk_add_f32 v[14:15], v[36:37], v[14:15] neg_lo:[0,1] neg_hi:[0,1]
	v_pk_add_f32 v[36:37], v[34:35], v[2:3]
	v_pk_add_f32 v[2:3], v[34:35], v[2:3] neg_lo:[0,1] neg_hi:[0,1]
	v_xor_b32_e32 v73, 0x80000000, v22
	v_mov_b32_e32 v72, v23
	v_xor_b32_e32 v35, 0x80000000, v2
	v_mov_b32_e32 v34, v3
	v_pk_add_f32 v[2:3], v[4:5], v[10:11] neg_lo:[0,1] neg_hi:[0,1]
	v_pk_add_f32 v[24:25], v[24:25], v[30:31] neg_lo:[0,1] neg_hi:[0,1]
	v_pk_add_f32 v[82:83], v[6:7], v[12:13]
	v_pk_add_f32 v[12:13], v[6:7], v[12:13] neg_lo:[0,1] neg_hi:[0,1]
	v_xor_b32_e32 v87, 0x80000000, v2
	v_mov_b32_e32 v86, v3
	v_pk_add_f32 v[2:3], v[16:17], v[48:49]
	v_pk_add_f32 v[88:89], v[16:17], v[48:49] neg_lo:[0,1] neg_hi:[0,1]
	v_pk_add_f32 v[48:49], v[32:33], v[64:65]
	v_pk_add_f32 v[28:29], v[32:33], v[64:65] neg_lo:[0,1] neg_hi:[0,1]
	v_pk_add_f32 v[64:65], v[60:61], v[40:41] op_sel:[0,1] op_sel_hi:[1,0] neg_hi:[0,1]
	v_pk_add_f32 v[6:7], v[60:61], v[40:41] op_sel:[0,1] op_sel_hi:[1,0] neg_lo:[0,1]
	v_pk_add_f32 v[60:61], v[50:51], v[56:57]
	v_pk_add_f32 v[22:23], v[50:51], v[56:57] neg_lo:[0,1] neg_hi:[0,1]
	v_pk_add_f32 v[50:51], v[52:53], v[72:73]
	v_pk_add_f32 v[30:31], v[52:53], v[72:73] neg_lo:[0,1] neg_hi:[0,1]
	v_pk_add_f32 v[52:53], v[18:19], v[36:37]
	v_pk_add_f32 v[56:57], v[18:19], v[36:37] neg_lo:[0,1] neg_hi:[0,1]
	v_mov_b32_e32 v18, v21
	v_pk_add_f32 v[84:85], v[4:5], v[10:11]
	v_cvt_f32_i32_e32 v18, v18
	v_pk_add_f32 v[32:33], v[42:43], v[66:67]
	v_pk_add_f32 v[40:41], v[42:43], v[66:67] neg_lo:[0,1] neg_hi:[0,1]
	v_pk_add_f32 v[66:67], v[24:25], v[80:81]
	v_pk_add_f32 v[10:11], v[24:25], v[80:81] neg_lo:[0,1] neg_hi:[0,1]
	v_pk_add_f32 v[72:73], v[14:15], v[34:35]
	v_pk_add_f32 v[24:25], v[14:15], v[34:35] neg_lo:[0,1] neg_hi:[0,1]
	v_mul_f32_e32 v15, 0x38800000, v18
	v_cos_f32_e32 v14, v15
	v_sin_f32_e32 v15, v15
	v_pk_add_f32 v[16:17], v[74:75], v[62:63]
	v_pk_add_f32 v[54:55], v[74:75], v[62:63] neg_lo:[0,1] neg_hi:[0,1]
	v_pk_add_f32 v[62:63], v[8:9], v[44:45]
	v_pk_add_f32 v[4:5], v[8:9], v[44:45] neg_lo:[0,1] neg_hi:[0,1]
	v_pk_add_f32 v[8:9], v[26:27], v[58:59]
	v_add_f32_e32 v20, v14, v14
	v_pk_add_f32 v[42:43], v[38:39], v[46:47]
	v_pk_add_f32 v[38:39], v[38:39], v[46:47] neg_lo:[0,1] neg_hi:[0,1]
	v_pk_add_f32 v[58:59], v[26:27], v[58:59] neg_lo:[0,1] neg_hi:[0,1]
	v_pk_add_f32 v[26:27], v[76:77], v[78:79]
	v_pk_add_f32 v[46:47], v[76:77], v[78:79] neg_lo:[0,1] neg_hi:[0,1]
	v_pk_mul_f32 v[18:19], v[14:15], v[14:15]
	v_mul_f32_e32 v20, v15, v20
	v_mov_b32_e32 v78, v15
	v_pk_add_f32 v[18:19], v[18:19], v[18:19] op_sel:[0,1] op_sel_hi:[0,1] neg_lo:[0,1] neg_hi:[0,1]
	v_pk_mul_f32 v[34:35], v[14:15], v[20:21] op_sel:[1,0] op_sel_hi:[0,0] neg_lo:[1,0]
	v_pk_mul_f32 v[36:37], v[78:79], v[8:9] op_sel:[0,1] op_sel_hi:[0,0] neg_hi:[0,1]
	v_pk_fma_f32 v[34:35], v[14:15], v[18:19], v[34:35]
	v_pk_fma_f32 v[8:9], v[14:15], v[8:9], v[36:37] op_sel_hi:[0,1,1]
	v_pk_mul_f32 v[14:15], v[20:21], s[48:49] op_sel_hi:[0,1]
	v_pk_fma_f32 v[36:37], v[18:19], s[40:41], v[14:15]
	s_nop 0
	v_pk_mul_f32 v[14:15], v[16:17], v[36:37] op_sel:[1,1] op_sel_hi:[0,1] neg_hi:[1,0]
	v_pk_add_f32 v[74:75], v[82:83], v[84:85]
	v_pk_fma_f32 v[16:17], v[16:17], v[36:37], v[14:15] op_sel_hi:[1,0,1]
	v_pk_mul_f32 v[14:15], v[20:21], v[34:35] op_sel:[0,1] op_sel_hi:[0,0] neg_lo:[0,1]
	v_pk_fma_f32 v[78:79], v[18:19], v[34:35], v[14:15]
	v_pk_mul_f32 v[14:15], v[34:35], v[52:53] op_sel:[1,1] op_sel_hi:[1,0] neg_hi:[0,1]
	v_pk_add_f32 v[76:77], v[12:13], v[86:87]
	v_pk_fma_f32 v[14:15], v[34:35], v[52:53], v[14:15] op_sel_hi:[0,1,1]
	v_pk_mul_f32 v[34:35], v[20:21], v[36:37] op_sel:[0,1] op_sel_hi:[0,0] neg_lo:[0,1]
	s_nop 0
	v_pk_fma_f32 v[36:37], v[18:19], v[36:37], v[34:35]
	v_pk_mul_f32 v[52:53], v[26:27], v[78:79] op_sel:[1,1] op_sel_hi:[0,1] neg_hi:[1,0]
	v_pk_mul_f32 v[34:35], v[32:33], v[36:37] op_sel:[1,1] op_sel_hi:[0,1] neg_hi:[1,0]
	v_pk_fma_f32 v[26:27], v[26:27], v[78:79], v[52:53] op_sel_hi:[1,0,1]
	v_pk_fma_f32 v[34:35], v[32:33], v[36:37], v[34:35] op_sel_hi:[1,0,1]
	v_pk_mul_f32 v[52:53], v[20:21], v[36:37] op_sel:[0,1] op_sel_hi:[0,0] neg_lo:[0,1]
	v_pk_mul_f32 v[32:33], v[20:21], v[78:79] op_sel:[0,1] op_sel_hi:[0,0] neg_lo:[0,1]
	v_pk_fma_f32 v[52:53], v[18:19], v[36:37], v[52:53]
	v_pk_fma_f32 v[32:33], v[18:19], v[78:79], v[32:33]
	v_pk_mul_f32 v[36:37], v[42:43], v[52:53] op_sel:[1,1] op_sel_hi:[0,1] neg_hi:[1,0]
	s_nop 0
	v_pk_fma_f32 v[36:37], v[42:43], v[52:53], v[36:37] op_sel_hi:[1,0,1]
	v_pk_mul_f32 v[42:43], v[20:21], v[32:33] op_sel:[0,1] op_sel_hi:[0,0] neg_lo:[0,1]
	v_pk_mul_f32 v[78:79], v[74:75], v[32:33] op_sel:[1,1] op_sel_hi:[0,1] neg_hi:[1,0]
	v_pk_fma_f32 v[42:43], v[18:19], v[32:33], v[42:43]
	v_pk_fma_f32 v[32:33], v[74:75], v[32:33], v[78:79] op_sel_hi:[1,0,1]
	v_pk_mul_f32 v[74:75], v[20:21], v[52:53] op_sel:[0,1] op_sel_hi:[0,0] neg_lo:[0,1]
	v_pk_fma_f32 v[52:53], v[18:19], v[52:53], v[74:75]
	s_nop 0
	v_pk_mul_f32 v[74:75], v[48:49], v[52:53] op_sel:[1,1] op_sel_hi:[0,1] neg_hi:[1,0]
	s_nop 0
	v_pk_fma_f32 v[48:49], v[48:49], v[52:53], v[74:75] op_sel_hi:[1,0,1]
	v_pk_mul_f32 v[74:75], v[20:21], v[42:43] op_sel:[0,1] op_sel_hi:[0,0] neg_lo:[0,1]
	v_pk_mul_f32 v[78:79], v[50:51], v[42:43] op_sel:[1,1] op_sel_hi:[0,1] neg_hi:[1,0]
	v_pk_fma_f32 v[74:75], v[18:19], v[42:43], v[74:75]
	v_pk_fma_f32 v[42:43], v[50:51], v[42:43], v[78:79] op_sel_hi:[1,0,1]
	v_pk_mul_f32 v[50:51], v[20:21], v[52:53] op_sel:[0,1] op_sel_hi:[0,0] neg_lo:[0,1]
	v_pk_fma_f32 v[78:79], v[18:19], v[52:53], v[50:51]
	s_nop 0
	v_pk_mul_f32 v[50:51], v[60:61], v[78:79] op_sel:[1,1] op_sel_hi:[0,1] neg_hi:[1,0]
	v_xor_b32_e32 v81, 0x80000000, v58
	v_pk_fma_f32 v[52:53], v[60:61], v[78:79], v[50:51] op_sel_hi:[1,0,1]
	v_pk_mul_f32 v[50:51], v[20:21], v[74:75] op_sel:[0,1] op_sel_hi:[0,0] neg_lo:[0,1]
	v_pk_fma_f32 v[60:61], v[18:19], v[74:75], v[50:51]
	v_pk_mul_f32 v[50:51], v[72:73], v[74:75] op_sel:[1,1] op_sel_hi:[0,1] neg_hi:[1,0]
	v_mov_b32_e32 v80, v59
	v_pk_fma_f32 v[50:51], v[72:73], v[74:75], v[50:51] op_sel_hi:[1,0,1]
	v_pk_mul_f32 v[72:73], v[20:21], v[78:79] op_sel:[0,1] op_sel_hi:[0,0] neg_lo:[0,1]
	v_pk_fma_f32 v[72:73], v[18:19], v[78:79], v[72:73]
	s_nop 0
	v_pk_mul_f32 v[74:75], v[64:65], v[72:73] op_sel:[1,1] op_sel_hi:[0,1] neg_hi:[1,0]
	s_nop 0
	v_pk_fma_f32 v[64:65], v[64:65], v[72:73], v[74:75] op_sel_hi:[1,0,1]
	v_pk_mul_f32 v[74:75], v[20:21], v[60:61] op_sel:[0,1] op_sel_hi:[0,0] neg_lo:[0,1]
	v_pk_mul_f32 v[78:79], v[66:67], v[60:61] op_sel:[1,1] op_sel_hi:[0,1] neg_hi:[1,0]
	v_pk_fma_f32 v[74:75], v[18:19], v[60:61], v[74:75]
	v_pk_fma_f32 v[60:61], v[66:67], v[60:61], v[78:79] op_sel_hi:[1,0,1]
	v_pk_mul_f32 v[66:67], v[20:21], v[72:73] op_sel:[0,1] op_sel_hi:[0,0] neg_lo:[0,1]
	v_pk_fma_f32 v[66:67], v[18:19], v[72:73], v[66:67]
	s_nop 0
	v_pk_mul_f32 v[72:73], v[62:63], v[66:67] op_sel:[1,1] op_sel_hi:[0,1] neg_hi:[1,0]
	s_nop 0
	v_pk_fma_f32 v[62:63], v[62:63], v[66:67], v[72:73] op_sel_hi:[1,0,1]
	v_pk_mul_f32 v[72:73], v[20:21], v[74:75] op_sel:[0,1] op_sel_hi:[0,0] neg_lo:[0,1]
	v_pk_mul_f32 v[78:79], v[76:77], v[74:75] op_sel:[1,1] op_sel_hi:[0,1] neg_hi:[1,0]
	v_pk_fma_f32 v[72:73], v[18:19], v[74:75], v[72:73]
	v_pk_fma_f32 v[74:75], v[76:77], v[74:75], v[78:79] op_sel_hi:[1,0,1]
	v_pk_mul_f32 v[76:77], v[20:21], v[66:67] op_sel:[0,1] op_sel_hi:[0,0] neg_lo:[0,1]
	s_nop 0
	v_pk_fma_f32 v[66:67], v[18:19], v[66:67], v[76:77]
	v_pk_mul_f32 v[78:79], v[20:21], v[72:73] op_sel:[0,1] op_sel_hi:[0,0] neg_lo:[0,1]
	v_pk_mul_f32 v[80:81], v[80:81], v[72:73] op_sel:[0,1]
	v_pk_fma_f32 v[78:79], v[18:19], v[72:73], v[78:79]
	v_pk_fma_f32 v[58:59], v[58:59], v[72:73], v[80:81] op_sel_hi:[1,0,1]
	v_pk_mul_f32 v[76:77], v[88:89], v[66:67] op_sel:[1,1] op_sel_hi:[0,1] neg_hi:[1,0]
	v_pk_mul_f32 v[72:73], v[20:21], v[66:67] op_sel:[0,1] op_sel_hi:[0,0] neg_lo:[0,1]
	v_pk_fma_f32 v[76:77], v[88:89], v[66:67], v[76:77] op_sel_hi:[1,0,1]
	v_pk_fma_f32 v[66:67], v[18:19], v[66:67], v[72:73]
	s_nop 0
	v_pk_mul_f32 v[72:73], v[54:55], v[66:67] op_sel:[1,1] op_sel_hi:[0,1] neg_hi:[1,0]
	s_nop 0
	v_pk_fma_f32 v[54:55], v[54:55], v[66:67], v[72:73] op_sel_hi:[1,0,1]
	v_pk_mul_f32 v[72:73], v[20:21], v[78:79] op_sel:[0,1] op_sel_hi:[0,0] neg_lo:[0,1]
	v_pk_mul_f32 v[80:81], v[56:57], v[78:79] op_sel:[1,1] op_sel_hi:[0,1] neg_hi:[1,0]
	v_pk_fma_f32 v[72:73], v[18:19], v[78:79], v[72:73]
	v_pk_fma_f32 v[56:57], v[56:57], v[78:79], v[80:81] op_sel_hi:[1,0,1]
	v_pk_mul_f32 v[78:79], v[20:21], v[66:67] op_sel:[0,1] op_sel_hi:[0,0] neg_lo:[0,1]
	v_pk_fma_f32 v[66:67], v[18:19], v[66:67], v[78:79]
	s_nop 0
	v_pk_mul_f32 v[78:79], v[40:41], v[66:67] op_sel:[1,1] op_sel_hi:[0,1] neg_hi:[1,0]
	s_nop 0
	v_pk_fma_f32 v[40:41], v[40:41], v[66:67], v[78:79] op_sel_hi:[1,0,1]
	v_pk_mul_f32 v[78:79], v[20:21], v[72:73] op_sel:[0,1] op_sel_hi:[0,0] neg_lo:[0,1]
	v_pk_mul_f32 v[80:81], v[46:47], v[72:73] op_sel:[1,1] op_sel_hi:[0,1] neg_hi:[1,0]
	v_pk_fma_f32 v[78:79], v[18:19], v[72:73], v[78:79]
	v_pk_fma_f32 v[46:47], v[46:47], v[72:73], v[80:81] op_sel_hi:[1,0,1]
	v_pk_mul_f32 v[72:73], v[20:21], v[66:67] op_sel:[0,1] op_sel_hi:[0,0] neg_lo:[0,1]
	v_pk_fma_f32 v[66:67], v[18:19], v[66:67], v[72:73]
	v_pk_add_f32 v[44:45], v[82:83], v[84:85] neg_lo:[0,1] neg_hi:[0,1]
	v_pk_mul_f32 v[72:73], v[38:39], v[66:67] op_sel:[1,1] op_sel_hi:[0,1] neg_hi:[1,0]
	s_nop 0
	v_pk_fma_f32 v[38:39], v[38:39], v[66:67], v[72:73] op_sel_hi:[1,0,1]
	v_pk_mul_f32 v[72:73], v[20:21], v[78:79] op_sel:[0,1] op_sel_hi:[0,0] neg_lo:[0,1]
	v_pk_mul_f32 v[80:81], v[44:45], v[78:79] op_sel:[1,1] op_sel_hi:[0,1] neg_hi:[1,0]
	v_pk_fma_f32 v[72:73], v[18:19], v[78:79], v[72:73]
	v_pk_fma_f32 v[44:45], v[44:45], v[78:79], v[80:81] op_sel_hi:[1,0,1]
	v_pk_mul_f32 v[78:79], v[20:21], v[66:67] op_sel:[0,1] op_sel_hi:[0,0] neg_lo:[0,1]
	v_pk_fma_f32 v[66:67], v[18:19], v[66:67], v[78:79]
	s_nop 0
	v_pk_mul_f32 v[78:79], v[28:29], v[66:67] op_sel:[1,1] op_sel_hi:[0,1] neg_hi:[1,0]
	s_nop 0
	v_pk_fma_f32 v[28:29], v[28:29], v[66:67], v[78:79] op_sel_hi:[1,0,1]
	v_pk_mul_f32 v[78:79], v[20:21], v[72:73] op_sel:[0,1] op_sel_hi:[0,0] neg_lo:[0,1]
	v_pk_mul_f32 v[80:81], v[30:31], v[72:73] op_sel:[1,1] op_sel_hi:[0,1] neg_hi:[1,0]
	v_pk_fma_f32 v[78:79], v[18:19], v[72:73], v[78:79]
	v_pk_fma_f32 v[30:31], v[30:31], v[72:73], v[80:81] op_sel_hi:[1,0,1]
	v_pk_mul_f32 v[72:73], v[20:21], v[66:67] op_sel:[0,1] op_sel_hi:[0,0] neg_lo:[0,1]
	v_pk_fma_f32 v[66:67], v[18:19], v[66:67], v[72:73]
	s_nop 0
	v_pk_mul_f32 v[72:73], v[22:23], v[66:67] op_sel:[1,1] op_sel_hi:[0,1] neg_hi:[1,0]
	s_nop 0
	v_pk_fma_f32 v[22:23], v[22:23], v[66:67], v[72:73] op_sel_hi:[1,0,1]
	v_pk_mul_f32 v[72:73], v[20:21], v[78:79] op_sel:[0,1] op_sel_hi:[0,0] neg_lo:[0,1]
	v_pk_mul_f32 v[80:81], v[24:25], v[78:79] op_sel:[1,1] op_sel_hi:[0,1] neg_hi:[1,0]
	v_pk_fma_f32 v[72:73], v[18:19], v[78:79], v[72:73]
	v_pk_fma_f32 v[24:25], v[24:25], v[78:79], v[80:81] op_sel_hi:[1,0,1]
	v_pk_mul_f32 v[78:79], v[20:21], v[66:67] op_sel:[0,1] op_sel_hi:[0,0] neg_lo:[0,1]
	v_pk_fma_f32 v[66:67], v[18:19], v[66:67], v[78:79]
	s_nop 0
	v_pk_mul_f32 v[78:79], v[6:7], v[66:67] op_sel:[1,1] op_sel_hi:[0,1] neg_hi:[1,0]
	s_nop 0
	v_pk_fma_f32 v[6:7], v[6:7], v[66:67], v[78:79] op_sel_hi:[1,0,1]
	v_pk_mul_f32 v[78:79], v[20:21], v[72:73] op_sel:[0,1] op_sel_hi:[0,0] neg_lo:[0,1]
	v_pk_mul_f32 v[80:81], v[10:11], v[72:73] op_sel:[1,1] op_sel_hi:[0,1] neg_hi:[1,0]
	v_pk_fma_f32 v[78:79], v[18:19], v[72:73], v[78:79]
	v_pk_fma_f32 v[10:11], v[10:11], v[72:73], v[80:81] op_sel_hi:[1,0,1]
	v_pk_mul_f32 v[72:73], v[20:21], v[66:67] op_sel:[0,1] op_sel_hi:[0,0] neg_lo:[0,1]
	v_pk_fma_f32 v[18:19], v[18:19], v[66:67], v[72:73]
	v_pk_add_f32 v[12:13], v[12:13], v[86:87] neg_lo:[0,1] neg_hi:[0,1]
	v_pk_mul_f32 v[66:67], v[4:5], v[18:19] op_sel:[1,1] op_sel_hi:[0,1] neg_hi:[1,0]
	s_nop 0
	v_pk_fma_f32 v[4:5], v[4:5], v[18:19], v[66:67] op_sel_hi:[1,0,1]
	s_nop 0
	s_nop 0
	v_pk_mul_f32 v[18:19], v[12:13], v[78:79] op_sel:[1,1] op_sel_hi:[0,1] neg_hi:[1,0]
	s_nop 0
	v_pk_fma_f32 v[12:13], v[12:13], v[78:79], v[18:19] op_sel_hi:[1,0,1]
	v_lshrrev_b32_e32 v18, 5, v21
	v_bitop3_b32 v18, v18, v21, 15 bitop3:0x6c
	v_lshlrev_b32_e32 v18, 3, v18
	v_bfe_u32 v19, v21, 5, 4
	v_add_u32_e32 v20, 16, v18
	ds_write_b64 v20, v[2:3]
	v_bitop3_b32 v2, v19, v21, 16 bitop3:0x36
	v_lshl_add_u32 v2, v2, 3, 16
	v_add_u32_e32 v3, s47, v18
	ds_write_b64 v2, v[76:77] offset:4096
	ds_write_b64 v20, v[48:49] offset:8192
	ds_write_b64 v2, v[28:29] offset:12288
	ds_write_b64 v20, v[34:35] offset:16384
	ds_write_b64 v2, v[40:41] offset:20480
	ds_write_b64 v20, v[64:65] offset:24576
	ds_write_b64 v2, v[6:7] offset:28672
	ds_write_b64 v20, v[16:17] offset:32768
	ds_write_b64 v2, v[54:55] offset:36864
	ds_write_b64 v20, v[52:53] offset:40960
	ds_write_b64 v2, v[22:23] offset:45056
	ds_write_b64 v20, v[36:37] offset:49152
	ds_write_b64 v2, v[38:39] offset:53248
	ds_write_b64 v20, v[62:63] offset:57344
	ds_write_b64 v2, v[4:5] offset:61440
	ds_write_b64 v3, v[8:9]
	v_add_u32_e32 v3, 0x11000, v2
	ds_write_b64 v3, v[58:59]
	v_add_u32_e32 v3, 0x12000, v20
	ds_write_b64 v3, v[42:43]
	v_add_u32_e32 v3, 0x13000, v2
	ds_write_b64 v3, v[30:31]
	v_add_u32_e32 v3, 0x14000, v20
	ds_write_b64 v3, v[26:27]
	v_add_u32_e32 v3, 0x15000, v2
	ds_write_b64 v3, v[46:47]
	v_add_u32_e32 v3, 0x16000, v20
	ds_write_b64 v3, v[60:61]
	v_add_u32_e32 v3, 0x17000, v2
	ds_write_b64 v3, v[10:11]
	v_add_u32_e32 v3, 0x18000, v20
	ds_write_b64 v3, v[14:15]
	v_add_u32_e32 v3, 0x19000, v2
	ds_write_b64 v3, v[56:57]
	v_add_u32_e32 v3, 0x1a000, v20
	ds_write_b64 v3, v[50:51]
	v_add_u32_e32 v3, 0x1b000, v2
	ds_write_b64 v3, v[24:25]
	v_add_u32_e32 v3, 0x1c000, v20
	ds_write_b64 v3, v[32:33]
	v_add_u32_e32 v3, 0x1d000, v2
	ds_write_b64 v3, v[44:45]
	v_add_u32_e32 v3, 0x1e000, v20
	v_add_u32_e32 v2, 0x1f000, v2
	v_mov_b32_e32 v11, v146
	ds_write_b64 v3, v[74:75]
	ds_write_b64 v2, v[12:13]
	s_waitcnt lgkmcnt(0)
	s_barrier
	s_nop 0
	v_lshlrev_b32_e32 v2, 5, v11
	v_and_b32_e32 v2, 0xfffffe00, v2
	v_and_or_b32 v3, v11, 16, v2
	v_bitop3_b32 v2, v2, 16, v11 bitop3:0x34
	v_bitop3_b32 v12, v11, 2, 15 bitop3:0x6c
	v_bitop3_b32 v22, v11, 4, 15 bitop3:0x6c
	v_bitop3_b32 v30, v11, 6, 15 bitop3:0x6c
	v_bitop3_b32 v38, v11, 8, 15 bitop3:0x6c
	v_and_b32_e32 v10, 15, v11
	v_lshl_add_u32 v18, v3, 3, 16
	v_lshl_add_u32 v87, v2, 3, 16
	v_lshlrev_b32_e32 v12, 3, v12
	v_lshlrev_b32_e32 v22, 3, v22
	v_lshlrev_b32_e32 v30, 3, v30
	v_lshlrev_b32_e32 v38, 3, v38
	v_lshlrev_b32_e32 v3, 3, v10
	v_bitop3_b32 v2, v11, 1, 15 bitop3:0x6c
	v_add_u32_e32 v57, v18, v12
	v_add_u32_e32 v58, v87, v12
	v_bitop3_b32 v12, v11, 3, 15 bitop3:0x6c
	v_add_u32_e32 v61, v18, v22
	v_add_u32_e32 v62, v87, v22
	v_bitop3_b32 v22, v11, 5, 15 bitop3:0x6c
	v_add_u32_e32 v65, v18, v30
	v_add_u32_e32 v66, v87, v30
	v_bitop3_b32 v30, v11, 7, 15 bitop3:0x6c
	v_add_u32_e32 v72, v18, v38
	v_add_u32_e32 v73, v87, v38
	v_bitop3_b32 v38, v11, 9, 15 bitop3:0x6c
	v_add_u32_e32 v19, v18, v3
	v_lshlrev_b32_e32 v2, 3, v2
	v_lshlrev_b32_e32 v12, 3, v12
	v_lshlrev_b32_e32 v22, 3, v22
	v_lshlrev_b32_e32 v30, 3, v30
	v_lshlrev_b32_e32 v38, 3, v38
	v_add_u32_e32 v54, v87, v3
	v_add_u32_e32 v55, v18, v2
	v_add_u32_e32 v56, v87, v2
	ds_read_b64 v[2:3], v19
	ds_read_b64 v[4:5], v54
	ds_read_b64 v[6:7], v55 offset:256
	ds_read_b64 v[8:9], v56 offset:256
	v_add_u32_e32 v59, v18, v12
	v_add_u32_e32 v60, v87, v12
	ds_read_b64 v[12:13], v57 offset:512
	ds_read_b64 v[14:15], v58 offset:512
	ds_read_b64 v[16:17], v59 offset:768
	ds_read_b64 v[20:21], v60 offset:768
	v_add_u32_e32 v63, v18, v22
	v_add_u32_e32 v64, v87, v22
	ds_read_b64 v[22:23], v61 offset:1024
	ds_read_b64 v[24:25], v62 offset:1024
	ds_read_b64 v[26:27], v63 offset:1280
	ds_read_b64 v[28:29], v64 offset:1280
	v_add_u32_e32 v67, v18, v30
	v_add_u32_e32 v71, v87, v30
	ds_read_b64 v[30:31], v65 offset:1536
	ds_read_b64 v[32:33], v66 offset:1536
	ds_read_b64 v[34:35], v67 offset:1792
	ds_read_b64 v[36:37], v71 offset:1792
	v_add_u32_e32 v74, v18, v38
	v_add_u32_e32 v75, v87, v38
	ds_read_b64 v[38:39], v72 offset:2048
	ds_read_b64 v[40:41], v73 offset:2048
	ds_read_b64 v[42:43], v74 offset:2304
	ds_read_b64 v[44:45], v75 offset:2304
	v_bitop3_b32 v46, v11, 10, 15 bitop3:0x6c
	s_waitcnt lgkmcnt(3)
	v_pk_add_f32 v[104:105], v[2:3], v[38:39]
	v_pk_add_f32 v[2:3], v[2:3], v[38:39] neg_lo:[0,1] neg_hi:[0,1]
	s_waitcnt lgkmcnt(2)
	v_pk_add_f32 v[38:39], v[4:5], v[40:41]
	v_pk_add_f32 v[4:5], v[4:5], v[40:41] neg_lo:[0,1] neg_hi:[0,1]
	v_lshlrev_b32_e32 v46, 3, v46
	v_pk_mul_f32 v[40:41], v[4:5], s[58:59] op_sel:[1,0] op_sel_hi:[0,0] neg_hi:[1,0]
	v_add_u32_e32 v76, v18, v46
	v_pk_fma_f32 v[4:5], v[4:5], s[46:47], v[40:41] op_sel_hi:[1,0,1]
	s_waitcnt lgkmcnt(1)
	v_pk_add_f32 v[40:41], v[6:7], v[42:43]
	v_pk_add_f32 v[6:7], v[6:7], v[42:43] neg_lo:[0,1] neg_hi:[0,1]
	v_add_u32_e32 v77, v87, v46
	v_bitop3_b32 v46, v11, 11, 15 bitop3:0x6c
	v_pk_mul_f32 v[42:43], v[6:7], s[62:63] op_sel:[1,0] op_sel_hi:[0,0] neg_hi:[1,0]
	v_lshlrev_b32_e32 v46, 3, v46
	v_pk_fma_f32 v[6:7], v[6:7], s[60:61], v[42:43] op_sel_hi:[1,0,1]
	s_waitcnt lgkmcnt(0)
	v_pk_add_f32 v[42:43], v[8:9], v[44:45]
	v_pk_add_f32 v[8:9], v[8:9], v[44:45] neg_lo:[0,1] neg_hi:[0,1]
	v_add_u32_e32 v78, v18, v46
	v_add_u32_e32 v79, v87, v46
	ds_read_b64 v[46:47], v76 offset:2560
	ds_read_b64 v[48:49], v77 offset:2560
	ds_read_b64 v[50:51], v78 offset:2816
	ds_read_b64 v[52:53], v79 offset:2816
	v_pk_mul_f32 v[44:45], v[8:9], s[66:67] op_sel:[1,0] op_sel_hi:[0,0] neg_hi:[1,0]
	v_bitop3_b32 v80, v11, 12, 15 bitop3:0x6c
	v_pk_fma_f32 v[8:9], v[8:9], s[64:65], v[44:45] op_sel_hi:[1,0,1]
	s_waitcnt lgkmcnt(3)
	v_pk_add_f32 v[44:45], v[12:13], v[46:47]
	v_pk_add_f32 v[12:13], v[12:13], v[46:47] neg_lo:[0,1] neg_hi:[0,1]
	v_lshlrev_b32_e32 v81, 3, v80
	v_pk_mul_f32 v[46:47], v[12:13], s[70:71] op_sel:[1,0] op_sel_hi:[0,0] neg_hi:[1,0]
	v_bitop3_b32 v82, v11, 13, 15 bitop3:0x6c
	v_pk_fma_f32 v[12:13], v[12:13], s[70:71], v[46:47] op_sel_hi:[1,0,1]
	s_waitcnt lgkmcnt(2)
	v_pk_add_f32 v[46:47], v[14:15], v[48:49]
	v_pk_add_f32 v[14:15], v[14:15], v[48:49] neg_lo:[0,1] neg_hi:[0,1]
	v_add_u32_e32 v80, v18, v81
	v_pk_mul_f32 v[48:49], v[14:15], s[64:65] op_sel:[1,0] op_sel_hi:[0,0] neg_hi:[1,0]
	v_lshlrev_b32_e32 v83, 3, v82
	v_pk_fma_f32 v[14:15], v[14:15], s[66:67], v[48:49] op_sel_hi:[1,0,1]
	s_waitcnt lgkmcnt(1)
	v_pk_add_f32 v[48:49], v[16:17], v[50:51]
	v_pk_add_f32 v[16:17], v[16:17], v[50:51] neg_lo:[0,1] neg_hi:[0,1]
	v_add_u32_e32 v81, v87, v81
	v_pk_mul_f32 v[50:51], v[16:17], s[60:61] op_sel:[1,0] op_sel_hi:[0,0] neg_hi:[1,0]
	v_add_u32_e32 v82, v18, v83
	v_pk_fma_f32 v[16:17], v[16:17], s[62:63], v[50:51] op_sel_hi:[1,0,1]
	s_waitcnt lgkmcnt(0)
	v_pk_add_f32 v[50:51], v[20:21], v[52:53]
	v_pk_add_f32 v[20:21], v[20:21], v[52:53] neg_lo:[0,1] neg_hi:[0,1]
	v_add_u32_e32 v83, v87, v83
	ds_read_b64 v[88:89], v80 offset:3072
	ds_read_b64 v[90:91], v81 offset:3072
	ds_read_b64 v[92:93], v82 offset:3328
	ds_read_b64 v[94:95], v83 offset:3328
	v_pk_mul_f32 v[52:53], v[20:21], s[46:47] op_sel:[1,0] op_sel_hi:[0,0] neg_hi:[1,0]
	v_bitop3_b32 v84, v11, 14, 15 bitop3:0x6c
	v_pk_fma_f32 v[20:21], v[20:21], s[58:59], v[52:53] op_sel_hi:[1,0,1]
	s_waitcnt lgkmcnt(3)
	v_pk_add_f32 v[52:53], v[22:23], v[88:89]
	v_pk_add_f32 v[22:23], v[22:23], v[88:89] neg_lo:[0,1] neg_hi:[0,1]
	v_lshlrev_b32_e32 v85, 3, v84
	v_xor_b32_e32 v89, 0x80000000, v22
	v_mov_b32_e32 v88, v23
	s_waitcnt lgkmcnt(2)
	v_pk_add_f32 v[22:23], v[24:25], v[90:91]
	v_pk_add_f32 v[24:25], v[24:25], v[90:91] neg_lo:[0,1] neg_hi:[0,1]
	v_bitop3_b32 v11, v11, 15, v11 bitop3:0xc
	v_pk_mul_f32 v[90:91], v[24:25], s[58:59] op_sel_hi:[1,0]
	v_xor_b32_e32 v107, 0x80000000, v24
	v_mov_b32_e32 v106, v25
	v_pk_fma_f32 v[24:25], v[106:107], s[46:47], v[90:91] op_sel_hi:[1,0,1] neg_lo:[0,0,1] neg_hi:[0,0,1]
	s_waitcnt lgkmcnt(1)
	v_pk_add_f32 v[90:91], v[26:27], v[92:93]
	v_pk_add_f32 v[26:27], v[26:27], v[92:93] neg_lo:[0,1] neg_hi:[0,1]
	v_add_u32_e32 v84, v18, v85
	v_lshlrev_b32_e32 v11, 3, v11
	v_pk_mul_f32 v[92:93], v[26:27], s[62:63] op_sel_hi:[1,0]
	v_xor_b32_e32 v107, 0x80000000, v26
	v_mov_b32_e32 v106, v27
	v_add_u32_e32 v85, v87, v85
	v_add_u32_e32 v86, v18, v11
	v_add_u32_e32 v87, v87, v11
	ds_read_b64 v[96:97], v84 offset:3584
	ds_read_b64 v[98:99], v85 offset:3584
	ds_read_b64 v[100:101], v86 offset:3840
	ds_read_b64 v[102:103], v87 offset:3840
	v_pk_fma_f32 v[26:27], v[106:107], s[60:61], v[92:93] op_sel_hi:[1,0,1] neg_lo:[0,0,1] neg_hi:[0,0,1]
	s_waitcnt lgkmcnt(4)
	v_pk_add_f32 v[92:93], v[28:29], v[94:95]
	v_pk_add_f32 v[28:29], v[28:29], v[94:95] neg_lo:[0,1] neg_hi:[0,1]
	s_nop 0
	v_pk_mul_f32 v[94:95], v[28:29], s[66:67] op_sel_hi:[1,0]
	v_xor_b32_e32 v107, 0x80000000, v28
	v_mov_b32_e32 v106, v29
	v_pk_fma_f32 v[28:29], v[106:107], s[64:65], v[94:95] op_sel_hi:[1,0,1] neg_lo:[0,0,1] neg_hi:[0,0,1]
	s_waitcnt lgkmcnt(3)
	v_pk_add_f32 v[94:95], v[30:31], v[96:97]
	v_pk_add_f32 v[30:31], v[30:31], v[96:97] neg_lo:[0,1] neg_hi:[0,1]
	v_cvt_f32_i32_e32 v10, v10
	v_pk_mul_f32 v[96:97], v[30:31], s[70:71] op_sel_hi:[1,0]
	v_xor_b32_e32 v107, 0x80000000, v30
	v_mov_b32_e32 v106, v31
	v_pk_fma_f32 v[30:31], v[106:107], s[70:71], v[96:97] op_sel_hi:[1,0,1] neg_lo:[0,0,1] neg_hi:[0,0,1]
	s_waitcnt lgkmcnt(2)
	v_pk_add_f32 v[96:97], v[32:33], v[98:99]
	v_pk_add_f32 v[32:33], v[32:33], v[98:99] neg_lo:[0,1] neg_hi:[0,1]
	v_mul_f32_e32 v10, 0x3b000000, v10
	v_pk_mul_f32 v[98:99], v[32:33], s[64:65] op_sel_hi:[1,0]
	v_xor_b32_e32 v107, 0x80000000, v32
	v_mov_b32_e32 v106, v33
	v_pk_fma_f32 v[32:33], v[106:107], s[66:67], v[98:99] op_sel_hi:[1,0,1] neg_lo:[0,0,1] neg_hi:[0,0,1]
	s_waitcnt lgkmcnt(1)
	v_pk_add_f32 v[98:99], v[34:35], v[100:101]
	v_pk_add_f32 v[34:35], v[34:35], v[100:101] neg_lo:[0,1] neg_hi:[0,1]
	s_nop 0
	v_pk_mul_f32 v[100:101], v[34:35], s[60:61] op_sel_hi:[1,0]
	v_xor_b32_e32 v107, 0x80000000, v34
	v_mov_b32_e32 v106, v35
	v_pk_fma_f32 v[34:35], v[106:107], s[62:63], v[100:101] op_sel_hi:[1,0,1] neg_lo:[0,0,1] neg_hi:[0,0,1]
	s_waitcnt lgkmcnt(0)
	v_pk_add_f32 v[100:101], v[36:37], v[102:103]
	v_pk_add_f32 v[36:37], v[36:37], v[102:103] neg_lo:[0,1] neg_hi:[0,1]
	s_nop 0
	v_pk_mul_f32 v[102:103], v[36:37], s[46:47] op_sel_hi:[1,0]
	v_xor_b32_e32 v107, 0x80000000, v36
	v_mov_b32_e32 v106, v37
	v_pk_fma_f32 v[36:37], v[106:107], s[58:59], v[102:103] op_sel_hi:[1,0,1] neg_lo:[0,0,1] neg_hi:[0,0,1]
	v_pk_add_f32 v[102:103], v[104:105], v[52:53]
	v_pk_add_f32 v[52:53], v[104:105], v[52:53] neg_lo:[0,1] neg_hi:[0,1]
	v_pk_add_f32 v[104:105], v[38:39], v[22:23]
	v_pk_add_f32 v[22:23], v[38:39], v[22:23] neg_lo:[0,1] neg_hi:[0,1]
	s_nop 0
	v_pk_mul_f32 v[38:39], v[22:23], s[62:63] op_sel:[1,0] op_sel_hi:[0,0] neg_hi:[1,0]
	s_nop 0
	v_pk_fma_f32 v[22:23], v[22:23], s[60:61], v[38:39] op_sel_hi:[1,0,1]
	v_pk_add_f32 v[38:39], v[40:41], v[90:91]
	v_pk_add_f32 v[40:41], v[40:41], v[90:91] neg_lo:[0,1] neg_hi:[0,1]
	s_nop 0
	v_pk_mul_f32 v[90:91], v[40:41], s[70:71] op_sel:[1,0] op_sel_hi:[0,0] neg_hi:[1,0]
	s_nop 0
	v_pk_fma_f32 v[40:41], v[40:41], s[70:71], v[90:91] op_sel_hi:[1,0,1]
	v_pk_add_f32 v[90:91], v[42:43], v[92:93]
	v_pk_add_f32 v[42:43], v[42:43], v[92:93] neg_lo:[0,1] neg_hi:[0,1]
	s_nop 0
	v_pk_mul_f32 v[92:93], v[42:43], s[60:61] op_sel:[1,0] op_sel_hi:[0,0] neg_hi:[1,0]
	s_nop 0
	v_pk_fma_f32 v[42:43], v[42:43], s[62:63], v[92:93] op_sel_hi:[1,0,1]
	v_pk_add_f32 v[92:93], v[44:45], v[94:95]
	v_pk_add_f32 v[44:45], v[44:45], v[94:95] neg_lo:[0,1] neg_hi:[0,1]
	s_nop 0
	v_xor_b32_e32 v95, 0x80000000, v44
	v_mov_b32_e32 v94, v45
	v_pk_add_f32 v[44:45], v[46:47], v[96:97]
	v_pk_add_f32 v[46:47], v[46:47], v[96:97] neg_lo:[0,1] neg_hi:[0,1]
	s_nop 0
	v_pk_mul_f32 v[96:97], v[46:47], s[62:63] op_sel_hi:[1,0]
	v_xor_b32_e32 v107, 0x80000000, v46
	v_mov_b32_e32 v106, v47
	v_pk_fma_f32 v[46:47], v[106:107], s[60:61], v[96:97] op_sel_hi:[1,0,1] neg_lo:[0,0,1] neg_hi:[0,0,1]
	v_pk_add_f32 v[96:97], v[48:49], v[98:99]
	v_pk_add_f32 v[48:49], v[48:49], v[98:99] neg_lo:[0,1] neg_hi:[0,1]
	s_nop 0
	v_pk_mul_f32 v[98:99], v[48:49], s[70:71] op_sel_hi:[1,0]
	v_xor_b32_e32 v107, 0x80000000, v48
	v_mov_b32_e32 v106, v49
	v_pk_fma_f32 v[48:49], v[106:107], s[70:71], v[98:99] op_sel_hi:[1,0,1] neg_lo:[0,0,1] neg_hi:[0,0,1]
	v_pk_add_f32 v[98:99], v[50:51], v[100:101]
	v_pk_add_f32 v[50:51], v[50:51], v[100:101] neg_lo:[0,1] neg_hi:[0,1]
	s_nop 0
	v_pk_mul_f32 v[100:101], v[50:51], s[60:61] op_sel_hi:[1,0]
	v_xor_b32_e32 v107, 0x80000000, v50
	v_mov_b32_e32 v106, v51
	v_pk_fma_f32 v[50:51], v[106:107], s[62:63], v[100:101] op_sel_hi:[1,0,1] neg_lo:[0,0,1] neg_hi:[0,0,1]
	v_pk_add_f32 v[100:101], v[2:3], v[88:89]
	v_pk_add_f32 v[2:3], v[2:3], v[88:89] neg_lo:[0,1] neg_hi:[0,1]
	v_pk_add_f32 v[88:89], v[4:5], v[24:25]
	v_pk_add_f32 v[4:5], v[4:5], v[24:25] neg_lo:[0,1] neg_hi:[0,1]
	s_nop 0
	v_pk_mul_f32 v[24:25], v[4:5], s[62:63] op_sel:[1,0] op_sel_hi:[0,0] neg_hi:[1,0]
	s_nop 0
	v_pk_fma_f32 v[4:5], v[4:5], s[60:61], v[24:25] op_sel_hi:[1,0,1]
	v_pk_add_f32 v[24:25], v[6:7], v[26:27]
	v_pk_add_f32 v[6:7], v[6:7], v[26:27] neg_lo:[0,1] neg_hi:[0,1]
	s_nop 0
	v_pk_mul_f32 v[26:27], v[6:7], s[70:71] op_sel:[1,0] op_sel_hi:[0,0] neg_hi:[1,0]
	s_nop 0
	v_pk_fma_f32 v[6:7], v[6:7], s[70:71], v[26:27] op_sel_hi:[1,0,1]
	v_pk_add_f32 v[26:27], v[8:9], v[28:29]
	v_pk_add_f32 v[8:9], v[8:9], v[28:29] neg_lo:[0,1] neg_hi:[0,1]
	s_nop 0
	v_pk_mul_f32 v[28:29], v[8:9], s[60:61] op_sel:[1,0] op_sel_hi:[0,0] neg_hi:[1,0]
	s_nop 0
	v_pk_fma_f32 v[8:9], v[8:9], s[62:63], v[28:29] op_sel_hi:[1,0,1]
	v_pk_add_f32 v[28:29], v[12:13], v[30:31]
	v_pk_add_f32 v[12:13], v[12:13], v[30:31] neg_lo:[0,1] neg_hi:[0,1]
	s_nop 0
	v_xor_b32_e32 v31, 0x80000000, v12
	v_mov_b32_e32 v30, v13
	v_pk_add_f32 v[12:13], v[14:15], v[32:33]
	v_pk_add_f32 v[14:15], v[14:15], v[32:33] neg_lo:[0,1] neg_hi:[0,1]
	s_nop 0
	v_pk_mul_f32 v[32:33], v[14:15], s[62:63] op_sel_hi:[1,0]
	v_xor_b32_e32 v107, 0x80000000, v14
	v_mov_b32_e32 v106, v15
	v_pk_fma_f32 v[14:15], v[106:107], s[60:61], v[32:33] op_sel_hi:[1,0,1] neg_lo:[0,0,1] neg_hi:[0,0,1]
	v_pk_add_f32 v[32:33], v[16:17], v[34:35]
	v_pk_add_f32 v[16:17], v[16:17], v[34:35] neg_lo:[0,1] neg_hi:[0,1]
	s_nop 0
	v_pk_mul_f32 v[34:35], v[16:17], s[70:71] op_sel_hi:[1,0]
	v_xor_b32_e32 v107, 0x80000000, v16
	v_mov_b32_e32 v106, v17
	v_pk_fma_f32 v[16:17], v[106:107], s[70:71], v[34:35] op_sel_hi:[1,0,1] neg_lo:[0,0,1] neg_hi:[0,0,1]
	v_pk_add_f32 v[34:35], v[20:21], v[36:37]
	v_pk_add_f32 v[20:21], v[20:21], v[36:37] neg_lo:[0,1] neg_hi:[0,1]
	s_nop 0
	v_pk_mul_f32 v[36:37], v[20:21], s[60:61] op_sel_hi:[1,0]
	v_xor_b32_e32 v107, 0x80000000, v20
	v_mov_b32_e32 v106, v21
	v_pk_fma_f32 v[20:21], v[106:107], s[62:63], v[36:37] op_sel_hi:[1,0,1] neg_lo:[0,0,1] neg_hi:[0,0,1]
	v_pk_add_f32 v[36:37], v[102:103], v[92:93]
	v_pk_add_f32 v[92:93], v[102:103], v[92:93] neg_lo:[0,1] neg_hi:[0,1]
	v_pk_add_f32 v[102:103], v[104:105], v[44:45]
	v_pk_add_f32 v[44:45], v[104:105], v[44:45] neg_lo:[0,1] neg_hi:[0,1]
	s_nop 0
	v_pk_mul_f32 v[104:105], v[44:45], s[70:71] op_sel:[1,0] op_sel_hi:[0,0] neg_hi:[1,0]
	s_nop 0
	v_pk_fma_f32 v[44:45], v[44:45], s[70:71], v[104:105] op_sel_hi:[1,0,1]
	v_pk_add_f32 v[104:105], v[38:39], v[96:97]
	v_pk_add_f32 v[38:39], v[38:39], v[96:97] neg_lo:[0,1] neg_hi:[0,1]
	s_nop 0
	v_xor_b32_e32 v97, 0x80000000, v38
	v_mov_b32_e32 v96, v39
	v_pk_add_f32 v[38:39], v[90:91], v[98:99]
	v_pk_add_f32 v[90:91], v[90:91], v[98:99] neg_lo:[0,1] neg_hi:[0,1]
	s_nop 0
	v_pk_mul_f32 v[98:99], v[90:91], s[70:71] op_sel_hi:[1,0]
	v_xor_b32_e32 v107, 0x80000000, v90
	v_mov_b32_e32 v106, v91
	v_pk_fma_f32 v[90:91], v[106:107], s[70:71], v[98:99] op_sel_hi:[1,0,1] neg_lo:[0,0,1] neg_hi:[0,0,1]
	v_pk_add_f32 v[98:99], v[52:53], v[94:95]
	v_pk_add_f32 v[52:53], v[52:53], v[94:95] neg_lo:[0,1] neg_hi:[0,1]
	v_pk_add_f32 v[94:95], v[22:23], v[46:47]
	v_pk_add_f32 v[22:23], v[22:23], v[46:47] neg_lo:[0,1] neg_hi:[0,1]
	s_nop 0
	v_pk_mul_f32 v[46:47], v[22:23], s[70:71] op_sel:[1,0] op_sel_hi:[0,0] neg_hi:[1,0]
	s_nop 0
	v_pk_fma_f32 v[22:23], v[22:23], s[70:71], v[46:47] op_sel_hi:[1,0,1]
	v_pk_add_f32 v[46:47], v[40:41], v[48:49]
	v_pk_add_f32 v[40:41], v[40:41], v[48:49] neg_lo:[0,1] neg_hi:[0,1]
	s_nop 0
	v_xor_b32_e32 v49, 0x80000000, v40
	v_mov_b32_e32 v48, v41
	v_pk_add_f32 v[40:41], v[42:43], v[50:51]
	v_pk_add_f32 v[42:43], v[42:43], v[50:51] neg_lo:[0,1] neg_hi:[0,1]
	s_nop 0
	v_pk_mul_f32 v[50:51], v[42:43], s[70:71] op_sel_hi:[1,0]
	v_xor_b32_e32 v107, 0x80000000, v42
	v_mov_b32_e32 v106, v43
	v_pk_fma_f32 v[42:43], v[106:107], s[70:71], v[50:51] op_sel_hi:[1,0,1] neg_lo:[0,0,1] neg_hi:[0,0,1]
	v_pk_add_f32 v[50:51], v[100:101], v[28:29]
	v_pk_add_f32 v[28:29], v[100:101], v[28:29] neg_lo:[0,1] neg_hi:[0,1]
	v_pk_add_f32 v[100:101], v[88:89], v[12:13]
	v_pk_add_f32 v[12:13], v[88:89], v[12:13] neg_lo:[0,1] neg_hi:[0,1]
	s_nop 0
	v_pk_mul_f32 v[88:89], v[12:13], s[70:71] op_sel:[1,0] op_sel_hi:[0,0] neg_hi:[1,0]
	s_nop 0
	v_pk_fma_f32 v[12:13], v[12:13], s[70:71], v[88:89] op_sel_hi:[1,0,1]
	v_pk_add_f32 v[88:89], v[24:25], v[32:33]
	v_pk_add_f32 v[24:25], v[24:25], v[32:33] neg_lo:[0,1] neg_hi:[0,1]
	v_pk_add_f32 v[108:109], v[50:51], v[88:89]
	v_xor_b32_e32 v33, 0x80000000, v24
	v_mov_b32_e32 v32, v25
	v_pk_add_f32 v[24:25], v[26:27], v[34:35]
	v_pk_add_f32 v[26:27], v[26:27], v[34:35] neg_lo:[0,1] neg_hi:[0,1]
	v_pk_add_f32 v[50:51], v[50:51], v[88:89] neg_lo:[0,1] neg_hi:[0,1]
	v_pk_mul_f32 v[34:35], v[26:27], s[70:71] op_sel_hi:[1,0]
	v_xor_b32_e32 v107, 0x80000000, v26
	v_mov_b32_e32 v106, v27
	v_pk_fma_f32 v[26:27], v[106:107], s[70:71], v[34:35] op_sel_hi:[1,0,1] neg_lo:[0,0,1] neg_hi:[0,0,1]
	v_pk_add_f32 v[34:35], v[2:3], v[30:31]
	v_pk_add_f32 v[2:3], v[2:3], v[30:31] neg_lo:[0,1] neg_hi:[0,1]
	v_pk_add_f32 v[30:31], v[4:5], v[14:15]
	v_pk_add_f32 v[4:5], v[4:5], v[14:15] neg_lo:[0,1] neg_hi:[0,1]
	v_pk_add_f32 v[110:111], v[12:13], v[26:27]
	v_pk_mul_f32 v[14:15], v[4:5], s[70:71] op_sel:[1,0] op_sel_hi:[0,0] neg_hi:[1,0]
	v_pk_add_f32 v[12:13], v[12:13], v[26:27] neg_lo:[0,1] neg_hi:[0,1]
	v_pk_fma_f32 v[4:5], v[4:5], s[70:71], v[14:15] op_sel_hi:[1,0,1]
	v_pk_add_f32 v[14:15], v[6:7], v[16:17]
	v_pk_add_f32 v[6:7], v[6:7], v[16:17] neg_lo:[0,1] neg_hi:[0,1]
	v_pk_add_f32 v[88:89], v[100:101], v[24:25]
	v_xor_b32_e32 v17, 0x80000000, v6
	v_mov_b32_e32 v16, v7
	v_pk_add_f32 v[6:7], v[8:9], v[20:21]
	v_pk_add_f32 v[8:9], v[8:9], v[20:21] neg_lo:[0,1] neg_hi:[0,1]
	v_xor_b32_e32 v113, 0x80000000, v12
	v_pk_mul_f32 v[20:21], v[8:9], s[70:71] op_sel_hi:[1,0]
	s_nop 0
	v_pk_fma_f32 v[8:9], v[8:9], s[70:71], v[20:21] op_sel:[1,0,0] op_sel_hi:[0,0,1] neg_lo:[0,0,1] neg_hi:[1,0,1]
	v_pk_add_f32 v[20:21], v[36:37], v[104:105]
	v_pk_add_f32 v[36:37], v[36:37], v[104:105] neg_lo:[0,1] neg_hi:[0,1]
	v_pk_add_f32 v[104:105], v[102:103], v[38:39]
	v_pk_add_f32 v[38:39], v[102:103], v[38:39] neg_lo:[0,1] neg_hi:[0,1]
	v_pk_add_f32 v[106:107], v[52:53], v[48:49]
	v_xor_b32_e32 v103, 0x80000000, v38
	v_mov_b32_e32 v102, v39
	v_pk_add_f32 v[38:39], v[92:93], v[96:97]
	v_pk_add_f32 v[92:93], v[92:93], v[96:97] neg_lo:[0,1] neg_hi:[0,1]
	v_pk_add_f32 v[96:97], v[44:45], v[90:91]
	v_pk_add_f32 v[44:45], v[44:45], v[90:91] neg_lo:[0,1] neg_hi:[0,1]
	v_pk_add_f32 v[48:49], v[52:53], v[48:49] neg_lo:[0,1] neg_hi:[0,1]
	v_pk_add_f32 v[52:53], v[22:23], v[42:43]
	v_pk_add_f32 v[22:23], v[22:23], v[42:43] neg_lo:[0,1] neg_hi:[0,1]
	v_xor_b32_e32 v91, 0x80000000, v44
	v_mov_b32_e32 v90, v45
	v_pk_add_f32 v[44:45], v[98:99], v[46:47]
	v_pk_add_f32 v[46:47], v[98:99], v[46:47] neg_lo:[0,1] neg_hi:[0,1]
	v_pk_add_f32 v[98:99], v[94:95], v[40:41]
	v_pk_add_f32 v[40:41], v[94:95], v[40:41] neg_lo:[0,1] neg_hi:[0,1]
	v_xor_b32_e32 v43, 0x80000000, v22
	v_mov_b32_e32 v42, v23
	v_pk_add_f32 v[22:23], v[100:101], v[24:25] neg_lo:[0,1] neg_hi:[0,1]
	v_xor_b32_e32 v95, 0x80000000, v40
	v_mov_b32_e32 v94, v41
	v_xor_b32_e32 v25, 0x80000000, v22
	v_mov_b32_e32 v24, v23
	v_pk_add_f32 v[100:101], v[28:29], v[32:33]
	v_pk_add_f32 v[32:33], v[28:29], v[32:33] neg_lo:[0,1] neg_hi:[0,1]
	v_mov_b32_e32 v112, v13
	v_pk_add_f32 v[12:13], v[34:35], v[14:15]
	v_pk_add_f32 v[14:15], v[34:35], v[14:15] neg_lo:[0,1] neg_hi:[0,1]
	v_pk_add_f32 v[34:35], v[30:31], v[6:7]
	v_pk_add_f32 v[6:7], v[30:31], v[6:7] neg_lo:[0,1] neg_hi:[0,1]
	v_pk_add_f32 v[114:115], v[2:3], v[16:17]
	v_pk_add_f32 v[16:17], v[2:3], v[16:17] neg_lo:[0,1] neg_hi:[0,1]
	v_pk_add_f32 v[2:3], v[4:5], v[8:9] neg_lo:[0,1] neg_hi:[0,1]
	v_xor_b32_e32 v31, 0x80000000, v6
	v_mov_b32_e32 v30, v7
	v_pk_add_f32 v[116:117], v[4:5], v[8:9]
	v_xor_b32_e32 v119, 0x80000000, v2
	v_mov_b32_e32 v118, v3
	v_pk_add_f32 v[2:3], v[20:21], v[104:105]
	v_pk_add_f32 v[104:105], v[20:21], v[104:105] neg_lo:[0,1] neg_hi:[0,1]
	v_pk_add_f32 v[120:121], v[36:37], v[102:103]
	v_pk_add_f32 v[26:27], v[36:37], v[102:103] neg_lo:[0,1] neg_hi:[0,1]
	v_pk_add_f32 v[36:37], v[38:39], v[96:97]
	v_pk_add_f32 v[40:41], v[38:39], v[96:97] neg_lo:[0,1] neg_hi:[0,1]
	v_pk_add_f32 v[96:97], v[92:93], v[90:91]
	v_pk_add_f32 v[6:7], v[92:93], v[90:91] neg_lo:[0,1] neg_hi:[0,1]
	v_pk_add_f32 v[20:21], v[44:45], v[98:99]
	v_pk_add_f32 v[90:91], v[44:45], v[98:99] neg_lo:[0,1] neg_hi:[0,1]
	v_pk_add_f32 v[92:93], v[46:47], v[94:95]
	v_pk_add_f32 v[22:23], v[46:47], v[94:95] neg_lo:[0,1] neg_hi:[0,1]
	v_pk_add_f32 v[46:47], v[106:107], v[52:53]
	v_pk_add_f32 v[38:39], v[106:107], v[52:53] neg_lo:[0,1] neg_hi:[0,1]
	v_pk_add_f32 v[52:53], v[50:51], v[24:25]
	v_pk_add_f32 v[28:29], v[50:51], v[24:25] neg_lo:[0,1] neg_hi:[0,1]
	v_pk_add_f32 v[50:51], v[100:101], v[110:111]
	v_pk_add_f32 v[44:45], v[100:101], v[110:111] neg_lo:[0,1] neg_hi:[0,1]
	v_pk_add_f32 v[98:99], v[32:33], v[112:113]
	v_pk_add_f32 v[8:9], v[32:33], v[112:113] neg_lo:[0,1] neg_hi:[0,1]
	v_pk_add_f32 v[32:33], v[12:13], v[34:35]
	v_pk_add_f32 v[100:101], v[12:13], v[34:35] neg_lo:[0,1] neg_hi:[0,1]
	v_cos_f32_e32 v12, v10
	v_sin_f32_e32 v13, v10
	v_pk_add_f32 v[94:95], v[48:49], v[42:43]
	v_pk_add_f32 v[4:5], v[48:49], v[42:43] neg_lo:[0,1] neg_hi:[0,1]
	v_pk_add_f32 v[48:49], v[108:109], v[88:89]
	v_pk_add_f32 v[102:103], v[14:15], v[30:31]
	v_pk_add_f32 v[24:25], v[14:15], v[30:31] neg_lo:[0,1] neg_hi:[0,1]
	v_pk_add_f32 v[106:107], v[16:17], v[118:119]
	v_pk_add_f32 v[10:11], v[16:17], v[118:119] neg_lo:[0,1] neg_hi:[0,1]
	v_pk_mul_f32 v[14:15], v[12:13], v[12:13]
	v_add_f32_e32 v16, v12, v12
	v_pk_add_f32 v[88:89], v[108:109], v[88:89] neg_lo:[0,1] neg_hi:[0,1]
	v_mul_f32_e32 v18, v13, v16
	v_pk_add_f32 v[16:17], v[14:15], v[14:15] op_sel:[0,1] op_sel_hi:[0,1] neg_lo:[0,1] neg_hi:[0,1]
	v_mov_b32_e32 v108, v13
	v_pk_mul_f32 v[14:15], v[12:13], v[18:19] op_sel:[1,0] op_sel_hi:[0,0] neg_lo:[1,0]
	v_pk_mul_f32 v[30:31], v[108:109], v[48:49] op_sel:[0,1] op_sel_hi:[0,0] neg_hi:[0,1]
	v_pk_fma_f32 v[14:15], v[12:13], v[16:17], v[14:15]
	v_pk_fma_f32 v[12:13], v[12:13], v[48:49], v[30:31] op_sel_hi:[0,1,1]
	v_pk_mul_f32 v[30:31], v[18:19], s[48:49] op_sel_hi:[0,1]
	v_pk_fma_f32 v[30:31], v[16:17], s[40:41], v[30:31]
	s_nop 0
	v_pk_mul_f32 v[48:49], v[30:31], v[20:21] op_sel:[1,1] op_sel_hi:[1,0] neg_hi:[0,1]
	s_nop 0
	v_pk_fma_f32 v[20:21], v[20:21], v[30:31], v[48:49] op_sel_hi:[1,0,1]
	v_pk_mul_f32 v[48:49], v[18:19], v[14:15] op_sel:[0,1] op_sel_hi:[0,0] neg_lo:[0,1]
	v_pk_mul_f32 v[108:109], v[14:15], v[32:33] op_sel:[1,1] op_sel_hi:[1,0] neg_hi:[0,1]
	v_pk_fma_f32 v[48:49], v[16:17], v[14:15], v[48:49]
	v_pk_fma_f32 v[14:15], v[14:15], v[32:33], v[108:109] op_sel_hi:[0,1,1]
	v_pk_mul_f32 v[32:33], v[18:19], v[30:31] op_sel:[0,1] op_sel_hi:[0,0] neg_lo:[0,1]
	v_pk_fma_f32 v[108:109], v[16:17], v[30:31], v[32:33]
	s_nop 0
	v_pk_mul_f32 v[30:31], v[36:37], v[108:109] op_sel:[1,1] op_sel_hi:[0,1] neg_hi:[1,0]
	v_pk_add_f32 v[34:35], v[114:115], v[116:117]
	v_pk_fma_f32 v[32:33], v[36:37], v[108:109], v[30:31] op_sel_hi:[1,0,1]
	v_pk_mul_f32 v[30:31], v[18:19], v[48:49] op_sel:[0,1] op_sel_hi:[0,0] neg_lo:[0,1]
	v_pk_fma_f32 v[110:111], v[16:17], v[48:49], v[30:31]
	v_pk_mul_f32 v[30:31], v[48:49], v[50:51] op_sel:[1,1] op_sel_hi:[1,0] neg_hi:[0,1]
	v_pk_mul_f32 v[36:37], v[18:19], v[108:109] op_sel:[0,1] op_sel_hi:[0,0] neg_lo:[0,1]
	v_pk_fma_f32 v[30:31], v[50:51], v[48:49], v[30:31] op_sel_hi:[1,0,1]
	v_pk_fma_f32 v[48:49], v[16:17], v[108:109], v[36:37]
	s_nop 0
	v_pk_mul_f32 v[36:37], v[46:47], v[48:49] op_sel:[1,1] op_sel_hi:[0,1] neg_hi:[1,0]
	s_nop 0
	v_pk_fma_f32 v[36:37], v[46:47], v[48:49], v[36:37] op_sel_hi:[1,0,1]
	v_pk_mul_f32 v[46:47], v[18:19], v[110:111] op_sel:[0,1] op_sel_hi:[0,0] neg_lo:[0,1]
	v_pk_mul_f32 v[50:51], v[110:111], v[34:35] op_sel:[1,1] op_sel_hi:[1,0] neg_hi:[0,1]
	v_pk_fma_f32 v[46:47], v[16:17], v[110:111], v[46:47]
	v_pk_fma_f32 v[34:35], v[34:35], v[110:111], v[50:51] op_sel_hi:[1,0,1]
	v_pk_mul_f32 v[50:51], v[18:19], v[48:49] op_sel:[0,1] op_sel_hi:[0,0] neg_lo:[0,1]
	s_nop 0
	v_pk_fma_f32 v[50:51], v[16:17], v[48:49], v[50:51]
	v_pk_mul_f32 v[108:109], v[18:19], v[46:47] op_sel:[0,1] op_sel_hi:[0,0] neg_lo:[0,1]
	v_pk_mul_f32 v[110:111], v[52:53], v[46:47] op_sel:[1,1] op_sel_hi:[0,1] neg_hi:[1,0]
	v_pk_fma_f32 v[108:109], v[16:17], v[46:47], v[108:109]
	v_pk_fma_f32 v[46:47], v[52:53], v[46:47], v[110:111] op_sel_hi:[1,0,1]
	v_pk_mul_f32 v[48:49], v[120:121], v[50:51] op_sel:[1,1] op_sel_hi:[0,1] neg_hi:[1,0]
	v_pk_mul_f32 v[52:53], v[18:19], v[50:51] op_sel:[0,1] op_sel_hi:[0,0] neg_lo:[0,1]
	v_pk_fma_f32 v[48:49], v[120:121], v[50:51], v[48:49] op_sel_hi:[1,0,1]
	v_pk_fma_f32 v[110:111], v[16:17], v[50:51], v[52:53]
	s_nop 0
	v_pk_mul_f32 v[50:51], v[92:93], v[110:111] op_sel:[1,1] op_sel_hi:[0,1] neg_hi:[1,0]
	v_pk_add_f32 v[42:43], v[114:115], v[116:117] neg_lo:[0,1] neg_hi:[0,1]
	v_pk_fma_f32 v[52:53], v[92:93], v[110:111], v[50:51] op_sel_hi:[1,0,1]
	v_pk_mul_f32 v[50:51], v[18:19], v[108:109] op_sel:[0,1] op_sel_hi:[0,0] neg_lo:[0,1]
	v_pk_fma_f32 v[92:93], v[16:17], v[108:109], v[50:51]
	v_pk_mul_f32 v[50:51], v[102:103], v[108:109] op_sel:[1,1] op_sel_hi:[0,1] neg_hi:[1,0]
	s_nop 0
	v_pk_fma_f32 v[50:51], v[102:103], v[108:109], v[50:51] op_sel_hi:[1,0,1]
	v_pk_mul_f32 v[102:103], v[18:19], v[110:111] op_sel:[0,1] op_sel_hi:[0,0] neg_lo:[0,1]
	v_pk_fma_f32 v[102:103], v[16:17], v[110:111], v[102:103]
	s_nop 0
	v_pk_mul_f32 v[108:109], v[96:97], v[102:103] op_sel:[1,1] op_sel_hi:[0,1] neg_hi:[1,0]
	s_nop 0
	v_pk_fma_f32 v[96:97], v[96:97], v[102:103], v[108:109] op_sel_hi:[1,0,1]
	v_pk_mul_f32 v[108:109], v[18:19], v[92:93] op_sel:[0,1] op_sel_hi:[0,0] neg_lo:[0,1]
	v_pk_mul_f32 v[110:111], v[98:99], v[92:93] op_sel:[1,1] op_sel_hi:[0,1] neg_hi:[1,0]
	v_pk_fma_f32 v[108:109], v[16:17], v[92:93], v[108:109]
	v_pk_fma_f32 v[92:93], v[98:99], v[92:93], v[110:111] op_sel_hi:[1,0,1]
	v_pk_mul_f32 v[98:99], v[18:19], v[102:103] op_sel:[0,1] op_sel_hi:[0,0] neg_lo:[0,1]
	v_pk_fma_f32 v[98:99], v[16:17], v[102:103], v[98:99]
	s_nop 0
	v_pk_mul_f32 v[102:103], v[94:95], v[98:99] op_sel:[1,1] op_sel_hi:[0,1] neg_hi:[1,0]
	s_nop 0
	v_pk_fma_f32 v[94:95], v[94:95], v[98:99], v[102:103] op_sel_hi:[1,0,1]
	v_pk_mul_f32 v[102:103], v[18:19], v[108:109] op_sel:[0,1] op_sel_hi:[0,0] neg_lo:[0,1]
	v_pk_mul_f32 v[110:111], v[106:107], v[108:109] op_sel:[1,1] op_sel_hi:[0,1] neg_hi:[1,0]
	v_pk_fma_f32 v[102:103], v[16:17], v[108:109], v[102:103]
	v_pk_fma_f32 v[106:107], v[106:107], v[108:109], v[110:111] op_sel_hi:[1,0,1]
	v_pk_mul_f32 v[108:109], v[18:19], v[98:99] op_sel:[0,1] op_sel_hi:[0,0] neg_lo:[0,1]
	v_pk_fma_f32 v[98:99], v[16:17], v[98:99], v[108:109]
	s_nop 0
	v_pk_mul_f32 v[108:109], v[104:105], v[98:99] op_sel:[1,1] op_sel_hi:[0,1] neg_hi:[1,0]
	s_nop 0
	v_pk_fma_f32 v[104:105], v[104:105], v[98:99], v[108:109] op_sel_hi:[1,0,1]
	v_pk_mul_f32 v[108:109], v[18:19], v[102:103] op_sel:[0,1] op_sel_hi:[0,0] neg_lo:[0,1]
	v_pk_mul_f32 v[110:111], v[88:89], v[102:103] op_sel:[1,1] op_sel_hi:[0,1] neg_hi:[1,0]
	v_pk_fma_f32 v[108:109], v[16:17], v[102:103], v[108:109]
	v_pk_fma_f32 v[88:89], v[88:89], v[102:103], v[110:111] op_sel_hi:[1,0,1]
	v_pk_mul_f32 v[102:103], v[18:19], v[98:99] op_sel:[0,1] op_sel_hi:[0,0] neg_lo:[0,1]
	v_pk_fma_f32 v[98:99], v[16:17], v[98:99], v[102:103]
	s_nop 0
	v_pk_mul_f32 v[102:103], v[90:91], v[98:99] op_sel:[1,1] op_sel_hi:[0,1] neg_hi:[1,0]
	s_nop 0
	v_pk_fma_f32 v[90:91], v[90:91], v[98:99], v[102:103] op_sel_hi:[1,0,1]
	v_pk_mul_f32 v[102:103], v[18:19], v[108:109] op_sel:[0,1] op_sel_hi:[0,0] neg_lo:[0,1]
	v_pk_mul_f32 v[110:111], v[100:101], v[108:109] op_sel:[1,1] op_sel_hi:[0,1] neg_hi:[1,0]
	v_pk_fma_f32 v[102:103], v[16:17], v[108:109], v[102:103]
	v_pk_fma_f32 v[100:101], v[100:101], v[108:109], v[110:111] op_sel_hi:[1,0,1]
	v_pk_mul_f32 v[108:109], v[18:19], v[98:99] op_sel:[0,1] op_sel_hi:[0,0] neg_lo:[0,1]
	v_pk_fma_f32 v[98:99], v[16:17], v[98:99], v[108:109]
	s_nop 0
	v_pk_mul_f32 v[108:109], v[40:41], v[98:99] op_sel:[1,1] op_sel_hi:[0,1] neg_hi:[1,0]
	s_nop 0
	v_pk_fma_f32 v[40:41], v[40:41], v[98:99], v[108:109] op_sel_hi:[1,0,1]
	v_pk_mul_f32 v[108:109], v[18:19], v[102:103] op_sel:[0,1] op_sel_hi:[0,0] neg_lo:[0,1]
	v_pk_mul_f32 v[110:111], v[44:45], v[102:103] op_sel:[1,1] op_sel_hi:[0,1] neg_hi:[1,0]
	v_pk_fma_f32 v[108:109], v[16:17], v[102:103], v[108:109]
	v_pk_fma_f32 v[44:45], v[44:45], v[102:103], v[110:111] op_sel_hi:[1,0,1]
	v_pk_mul_f32 v[102:103], v[18:19], v[98:99] op_sel:[0,1] op_sel_hi:[0,0] neg_lo:[0,1]
	v_pk_fma_f32 v[98:99], v[16:17], v[98:99], v[102:103]
	s_nop 0
	v_pk_mul_f32 v[102:103], v[38:39], v[98:99] op_sel:[1,1] op_sel_hi:[0,1] neg_hi:[1,0]
	s_nop 0
	v_pk_fma_f32 v[38:39], v[38:39], v[98:99], v[102:103] op_sel_hi:[1,0,1]
	v_pk_mul_f32 v[102:103], v[18:19], v[108:109] op_sel:[0,1] op_sel_hi:[0,0] neg_lo:[0,1]
	v_pk_mul_f32 v[110:111], v[42:43], v[108:109] op_sel:[1,1] op_sel_hi:[0,1] neg_hi:[1,0]
	v_pk_fma_f32 v[102:103], v[16:17], v[108:109], v[102:103]
	v_pk_fma_f32 v[42:43], v[42:43], v[108:109], v[110:111] op_sel_hi:[1,0,1]
	v_pk_mul_f32 v[108:109], v[18:19], v[98:99] op_sel:[0,1] op_sel_hi:[0,0] neg_lo:[0,1]
	v_pk_fma_f32 v[98:99], v[16:17], v[98:99], v[108:109]
	s_nop 0
	v_pk_mul_f32 v[108:109], v[26:27], v[98:99] op_sel:[1,1] op_sel_hi:[0,1] neg_hi:[1,0]
	s_nop 0
	v_pk_fma_f32 v[26:27], v[26:27], v[98:99], v[108:109] op_sel_hi:[1,0,1]
	v_pk_mul_f32 v[108:109], v[18:19], v[102:103] op_sel:[0,1] op_sel_hi:[0,0] neg_lo:[0,1]
	v_pk_mul_f32 v[110:111], v[28:29], v[102:103] op_sel:[1,1] op_sel_hi:[0,1] neg_hi:[1,0]
	v_pk_fma_f32 v[108:109], v[16:17], v[102:103], v[108:109]
	v_pk_fma_f32 v[28:29], v[28:29], v[102:103], v[110:111] op_sel_hi:[1,0,1]
	v_pk_mul_f32 v[102:103], v[18:19], v[98:99] op_sel:[0,1] op_sel_hi:[0,0] neg_lo:[0,1]
	v_pk_fma_f32 v[98:99], v[16:17], v[98:99], v[102:103]
	s_nop 0
	v_pk_mul_f32 v[102:103], v[22:23], v[98:99] op_sel:[1,1] op_sel_hi:[0,1] neg_hi:[1,0]
	s_nop 0
	v_pk_fma_f32 v[22:23], v[22:23], v[98:99], v[102:103] op_sel_hi:[1,0,1]
	v_pk_mul_f32 v[102:103], v[18:19], v[108:109] op_sel:[0,1] op_sel_hi:[0,0] neg_lo:[0,1]
	v_pk_mul_f32 v[110:111], v[24:25], v[108:109] op_sel:[1,1] op_sel_hi:[0,1] neg_hi:[1,0]
	v_pk_fma_f32 v[102:103], v[16:17], v[108:109], v[102:103]
	v_pk_fma_f32 v[24:25], v[24:25], v[108:109], v[110:111] op_sel_hi:[1,0,1]
	v_pk_mul_f32 v[108:109], v[18:19], v[98:99] op_sel:[0,1] op_sel_hi:[0,0] neg_lo:[0,1]
	v_pk_fma_f32 v[98:99], v[16:17], v[98:99], v[108:109]
	s_nop 0
	v_pk_mul_f32 v[108:109], v[6:7], v[98:99] op_sel:[1,1] op_sel_hi:[0,1] neg_hi:[1,0]
	s_nop 0
	v_pk_fma_f32 v[6:7], v[6:7], v[98:99], v[108:109] op_sel_hi:[1,0,1]
	v_pk_mul_f32 v[108:109], v[18:19], v[102:103] op_sel:[0,1] op_sel_hi:[0,0] neg_lo:[0,1]
	v_pk_mul_f32 v[110:111], v[8:9], v[102:103] op_sel:[1,1] op_sel_hi:[0,1] neg_hi:[1,0]
	v_pk_fma_f32 v[108:109], v[16:17], v[102:103], v[108:109]
	v_pk_fma_f32 v[8:9], v[8:9], v[102:103], v[110:111] op_sel_hi:[1,0,1]
	v_pk_mul_f32 v[102:103], v[18:19], v[98:99] op_sel:[0,1] op_sel_hi:[0,0] neg_lo:[0,1]
	v_pk_fma_f32 v[16:17], v[16:17], v[98:99], v[102:103]
	s_nop 0
	v_pk_mul_f32 v[98:99], v[4:5], v[16:17] op_sel:[1,1] op_sel_hi:[0,1] neg_hi:[1,0]
	s_nop 0
	v_pk_fma_f32 v[4:5], v[4:5], v[16:17], v[98:99] op_sel_hi:[1,0,1]
	v_pk_mul_f32 v[16:17], v[10:11], v[108:109] op_sel:[1,1] op_sel_hi:[0,1] neg_hi:[1,0]
	s_nop 0
	v_pk_fma_f32 v[10:11], v[10:11], v[108:109], v[16:17] op_sel_hi:[1,0,1]
	ds_write_b64 v19, v[2:3]
	ds_write_b64 v54, v[104:105]
	ds_write_b64 v55, v[48:49] offset:256
	ds_write_b64 v56, v[26:27] offset:256
	ds_write_b64 v57, v[32:33] offset:512
	ds_write_b64 v58, v[40:41] offset:512
	ds_write_b64 v59, v[96:97] offset:768
	ds_write_b64 v60, v[6:7] offset:768
	ds_write_b64 v61, v[20:21] offset:1024
	ds_write_b64 v62, v[90:91] offset:1024
	ds_write_b64 v63, v[52:53] offset:1280
	ds_write_b64 v64, v[22:23] offset:1280
	ds_write_b64 v65, v[36:37] offset:1536
	ds_write_b64 v66, v[38:39] offset:1536
	ds_write_b64 v67, v[94:95] offset:1792
	ds_write_b64 v71, v[4:5] offset:1792
	ds_write_b64 v72, v[12:13] offset:2048
	ds_write_b64 v73, v[88:89] offset:2048
	ds_write_b64 v74, v[46:47] offset:2304
	ds_write_b64 v75, v[28:29] offset:2304
	ds_write_b64 v76, v[30:31] offset:2560
	ds_write_b64 v77, v[44:45] offset:2560
	ds_write_b64 v78, v[92:93] offset:2816
	ds_write_b64 v79, v[8:9] offset:2816
	ds_write_b64 v80, v[14:15] offset:3072
	ds_write_b64 v81, v[100:101] offset:3072
	ds_write_b64 v82, v[50:51] offset:3328
	ds_write_b64 v83, v[24:25] offset:3328
	ds_write_b64 v84, v[34:35] offset:3584
	ds_write_b64 v85, v[42:43] offset:3584
	ds_write_b64 v86, v[106:107] offset:3840
	ds_write_b64 v87, v[10:11] offset:3840
	v_mov_b32_e32 v2, v146
	s_waitcnt lgkmcnt(0)
	s_barrier
	s_nop 0
	v_lshlrev_b32_e32 v34, 4, v2
	v_lshrrev_b32_e32 v35, 1, v2
	v_bitop3_b32 v3, v35, v34, 16 bitop3:0x6c
	v_lshl_add_u32 v26, v3, 3, 16
	v_bitop3_b32 v3, v35, 1, 15 bitop3:0x6c
	v_bitop3_b32 v11, v35, 5, 15 bitop3:0x6c
	v_bitop3_b32 v19, v35, 9, 15 bitop3:0x6c
	v_lshlrev_b32_e32 v37, 3, v3
	v_bitop3_b32 v3, v35, 2, 15 bitop3:0x6c
	v_lshlrev_b32_e32 v45, 3, v11
	v_bitop3_b32 v11, v35, 6, 15 bitop3:0x6c
	v_lshlrev_b32_e32 v49, 3, v19
	v_bitop3_b32 v19, v35, 10, 15 bitop3:0x6c
	v_bitop3_b32 v29, v35, 14, 15 bitop3:0x6c
	v_add_u32_e32 v34, 0x2000, v34
	v_bfe_u32 v2, v2, 1, 4
	v_lshlrev_b32_e32 v38, 3, v3
	v_bitop3_b32 v3, v35, 3, 15 bitop3:0x6c
	v_bitop3_b32 v10, v35, 4, 15 bitop3:0x6c
	v_lshlrev_b32_e32 v46, 3, v11
	v_bitop3_b32 v11, v35, 7, 15 bitop3:0x6c
	v_bitop3_b32 v18, v35, 8, 15 bitop3:0x6c
	v_lshlrev_b32_e32 v50, 3, v19
	v_bitop3_b32 v19, v35, 11, 15 bitop3:0x6c
	v_bitop3_b32 v27, v35, 12, 15 bitop3:0x6c
	v_bitop3_b32 v28, v35, 13, 15 bitop3:0x6c
	v_lshlrev_b32_e32 v54, 3, v29
	v_bitop3_b32 v29, v35, 15, v35 bitop3:0xc
	v_bitop3_b32 v34, v34, v35, 16 bitop3:0x78
	v_lshlrev_b32_e32 v36, 3, v2
	v_lshlrev_b32_e32 v39, 3, v3
	v_lshlrev_b32_e32 v44, 3, v10
	v_lshlrev_b32_e32 v47, 3, v11
	v_lshlrev_b32_e32 v48, 3, v18
	v_lshlrev_b32_e32 v51, 3, v19
	v_lshlrev_b32_e32 v52, 3, v27
	v_lshlrev_b32_e32 v53, 3, v28
	v_lshlrev_b32_e32 v55, 3, v29
	v_lshl_add_u32 v34, v34, 3, 16
	v_add_u32_e32 v2, v26, v36
	v_add_u32_e32 v4, v26, v37
	v_add_u32_e32 v6, v26, v38
	v_add_u32_e32 v8, v26, v39
	v_add_u32_e32 v10, v26, v44
	v_add_u32_e32 v12, v26, v45
	v_add_u32_e32 v14, v26, v46
	v_add_u32_e32 v16, v26, v47
	v_add_u32_e32 v18, v26, v48
	v_add_u32_e32 v20, v26, v49
	v_add_u32_e32 v22, v26, v50
	v_add_u32_e32 v24, v26, v51
	v_add_u32_e32 v27, v26, v52
	v_add_u32_e32 v28, v26, v53
	v_add_u32_e32 v30, v26, v54
	v_add_u32_e32 v32, v26, v55
	v_add_u32_e32 v35, v34, v36
	v_add_u32_e32 v40, v34, v37
	v_add_u32_e32 v41, v34, v38
	v_add_u32_e32 v42, v34, v39
	ds_read_b64 v[2:3], v2
	ds_read_b64 v[4:5], v4
	ds_read_b64 v[6:7], v6
	ds_read_b64 v[8:9], v8
	ds_read_b64 v[10:11], v10
	ds_read_b64 v[12:13], v12
	ds_read_b64 v[14:15], v14
	ds_read_b64 v[16:17], v16
	ds_read_b64 v[18:19], v18
	ds_read_b64 v[20:21], v20
	ds_read_b64 v[22:23], v22
	ds_read_b64 v[24:25], v24
	ds_read_b64 v[26:27], v27
	ds_read_b64 v[28:29], v28
	ds_read_b64 v[30:31], v30
	ds_read_b64 v[32:33], v32
	ds_read_b64 v[36:37], v35
	ds_read_b64 v[38:39], v40
	ds_read_b64 v[40:41], v41
	ds_read_b64 v[42:43], v42
	v_add_u32_e32 v35, v34, v44
	v_add_u32_e32 v44, v34, v45
	v_add_u32_e32 v45, v34, v46
	v_add_u32_e32 v46, v34, v47
	ds_read_b64 v[72:73], v35
	ds_read_b64 v[74:75], v44
	ds_read_b64 v[76:77], v45
	ds_read_b64 v[78:79], v46
	v_add_u32_e32 v35, v34, v48
	v_add_u32_e32 v44, v34, v49
	v_add_u32_e32 v45, v34, v50
	v_add_u32_e32 v46, v34, v51
	ds_read_b64 v[80:81], v35
	ds_read_b64 v[82:83], v44
	ds_read_b64 v[84:85], v45
	ds_read_b64 v[86:87], v46
	v_add_u32_e32 v35, v34, v52
	v_add_u32_e32 v44, v34, v53
	v_add_u32_e32 v45, v34, v54
	v_add_u32_e32 v34, v34, v55
	ds_read_b64 v[88:89], v35
	ds_read_b64 v[90:91], v44
	ds_read_b64 v[92:93], v45
	ds_read_b64 v[94:95], v34
	s_waitcnt lgkmcnt(14)
	v_pk_add_f32 v[34:35], v[2:3], v[18:19]
	v_pk_add_f32 v[2:3], v[2:3], v[18:19] neg_lo:[0,1] neg_hi:[0,1]
	v_pk_add_f32 v[18:19], v[4:5], v[20:21]
	v_pk_add_f32 v[4:5], v[4:5], v[20:21] neg_lo:[0,1] neg_hi:[0,1]
	s_nop 0
	v_pk_mul_f32 v[20:21], v[4:5], s[62:63] op_sel:[1,0] op_sel_hi:[0,0] neg_hi:[1,0]
	s_nop 0
	v_pk_fma_f32 v[4:5], v[4:5], s[60:61], v[20:21] op_sel_hi:[1,0,1]
	v_pk_add_f32 v[20:21], v[6:7], v[22:23]
	v_pk_add_f32 v[6:7], v[6:7], v[22:23] neg_lo:[0,1] neg_hi:[0,1]
	s_nop 0
	v_pk_mul_f32 v[22:23], v[6:7], s[70:71] op_sel:[1,0] op_sel_hi:[0,0] neg_hi:[1,0]
	s_nop 0
	v_pk_fma_f32 v[6:7], v[6:7], s[70:71], v[22:23] op_sel_hi:[1,0,1]
	v_pk_add_f32 v[22:23], v[8:9], v[24:25]
	v_pk_add_f32 v[8:9], v[8:9], v[24:25] neg_lo:[0,1] neg_hi:[0,1]
	s_nop 0
	v_pk_mul_f32 v[24:25], v[8:9], s[60:61] op_sel:[1,0] op_sel_hi:[0,0] neg_hi:[1,0]
	s_nop 0
	v_pk_fma_f32 v[8:9], v[8:9], s[62:63], v[24:25] op_sel_hi:[1,0,1]
	v_pk_add_f32 v[24:25], v[10:11], v[26:27]
	v_pk_add_f32 v[10:11], v[10:11], v[26:27] neg_lo:[0,1] neg_hi:[0,1]
	s_nop 0
	v_xor_b32_e32 v27, 0x80000000, v10
	v_mov_b32_e32 v26, v11
	v_pk_add_f32 v[10:11], v[12:13], v[28:29]
	v_pk_add_f32 v[12:13], v[12:13], v[28:29] neg_lo:[0,1] neg_hi:[0,1]
	s_nop 0
	v_pk_mul_f32 v[28:29], v[12:13], s[62:63] op_sel_hi:[1,0]
	v_xor_b32_e32 v45, 0x80000000, v12
	v_mov_b32_e32 v44, v13
	v_pk_fma_f32 v[12:13], v[44:45], s[60:61], v[28:29] op_sel_hi:[1,0,1] neg_lo:[0,0,1] neg_hi:[0,0,1]
	v_pk_add_f32 v[28:29], v[14:15], v[30:31]
	v_pk_add_f32 v[14:15], v[14:15], v[30:31] neg_lo:[0,1] neg_hi:[0,1]
	s_nop 0
	v_pk_mul_f32 v[30:31], v[14:15], s[70:71] op_sel_hi:[1,0]
	v_xor_b32_e32 v45, 0x80000000, v14
	v_mov_b32_e32 v44, v15
	v_pk_fma_f32 v[14:15], v[44:45], s[70:71], v[30:31] op_sel_hi:[1,0,1] neg_lo:[0,0,1] neg_hi:[0,0,1]
	v_pk_add_f32 v[30:31], v[16:17], v[32:33]
	v_pk_add_f32 v[16:17], v[16:17], v[32:33] neg_lo:[0,1] neg_hi:[0,1]
	s_nop 0
	v_pk_mul_f32 v[32:33], v[16:17], s[60:61] op_sel_hi:[1,0]
	v_xor_b32_e32 v45, 0x80000000, v16
	v_mov_b32_e32 v44, v17
	v_pk_fma_f32 v[16:17], v[44:45], s[62:63], v[32:33] op_sel_hi:[1,0,1] neg_lo:[0,0,1] neg_hi:[0,0,1]
	v_pk_add_f32 v[32:33], v[34:35], v[24:25]
	v_pk_add_f32 v[24:25], v[34:35], v[24:25] neg_lo:[0,1] neg_hi:[0,1]
	v_pk_add_f32 v[34:35], v[18:19], v[10:11]
	v_pk_add_f32 v[10:11], v[18:19], v[10:11] neg_lo:[0,1] neg_hi:[0,1]
	s_nop 0
	v_pk_mul_f32 v[18:19], v[10:11], s[70:71] op_sel:[1,0] op_sel_hi:[0,0] neg_hi:[1,0]
	s_nop 0
	v_pk_fma_f32 v[10:11], v[10:11], s[70:71], v[18:19] op_sel_hi:[1,0,1]
	v_pk_add_f32 v[18:19], v[20:21], v[28:29]
	v_pk_add_f32 v[20:21], v[20:21], v[28:29] neg_lo:[0,1] neg_hi:[0,1]
	s_nop 0
	v_xor_b32_e32 v29, 0x80000000, v20
	v_mov_b32_e32 v28, v21
	v_pk_add_f32 v[20:21], v[22:23], v[30:31]
	v_pk_add_f32 v[22:23], v[22:23], v[30:31] neg_lo:[0,1] neg_hi:[0,1]
	s_nop 0
	v_pk_mul_f32 v[30:31], v[22:23], s[70:71] op_sel_hi:[1,0]
	v_xor_b32_e32 v45, 0x80000000, v22
	v_mov_b32_e32 v44, v23
	v_pk_fma_f32 v[22:23], v[44:45], s[70:71], v[30:31] op_sel_hi:[1,0,1] neg_lo:[0,0,1] neg_hi:[0,0,1]
	v_pk_add_f32 v[30:31], v[2:3], v[26:27]
	v_pk_add_f32 v[2:3], v[2:3], v[26:27] neg_lo:[0,1] neg_hi:[0,1]
	v_pk_add_f32 v[26:27], v[4:5], v[12:13]
	v_pk_add_f32 v[4:5], v[4:5], v[12:13] neg_lo:[0,1] neg_hi:[0,1]
	s_nop 0
	v_pk_mul_f32 v[12:13], v[4:5], s[70:71] op_sel:[1,0] op_sel_hi:[0,0] neg_hi:[1,0]
	s_nop 0
	v_pk_fma_f32 v[4:5], v[4:5], s[70:71], v[12:13] op_sel_hi:[1,0,1]
	v_pk_add_f32 v[12:13], v[6:7], v[14:15]
	v_pk_add_f32 v[6:7], v[6:7], v[14:15] neg_lo:[0,1] neg_hi:[0,1]
	s_nop 0
	v_xor_b32_e32 v15, 0x80000000, v6
	v_mov_b32_e32 v14, v7
	v_pk_add_f32 v[6:7], v[8:9], v[16:17]
	v_pk_add_f32 v[8:9], v[8:9], v[16:17] neg_lo:[0,1] neg_hi:[0,1]
	s_nop 0
	v_pk_mul_f32 v[16:17], v[8:9], s[70:71] op_sel_hi:[1,0]
	s_nop 0
	v_pk_fma_f32 v[8:9], v[8:9], s[70:71], v[16:17] op_sel:[1,0,0] op_sel_hi:[0,0,1] neg_lo:[0,0,1] neg_hi:[1,0,1]
	v_pk_add_f32 v[16:17], v[32:33], v[18:19]
	v_pk_add_f32 v[18:19], v[32:33], v[18:19] neg_lo:[0,1] neg_hi:[0,1]
	v_pk_add_f32 v[32:33], v[34:35], v[20:21]
	v_pk_add_f32 v[20:21], v[34:35], v[20:21] neg_lo:[0,1] neg_hi:[0,1]
	v_pk_add_f32 v[66:67], v[16:17], v[32:33]
	v_xor_b32_e32 v35, 0x80000000, v20
	v_mov_b32_e32 v34, v21
	v_pk_add_f32 v[20:21], v[24:25], v[28:29]
	v_pk_add_f32 v[24:25], v[24:25], v[28:29] neg_lo:[0,1] neg_hi:[0,1]
	v_pk_add_f32 v[28:29], v[10:11], v[22:23]
	v_pk_add_f32 v[10:11], v[10:11], v[22:23] neg_lo:[0,1] neg_hi:[0,1]
	v_pk_add_f32 v[58:59], v[20:21], v[28:29]
	v_xor_b32_e32 v23, 0x80000000, v10
	v_mov_b32_e32 v22, v11
	v_pk_add_f32 v[10:11], v[30:31], v[12:13]
	v_pk_add_f32 v[12:13], v[30:31], v[12:13] neg_lo:[0,1] neg_hi:[0,1]
	v_pk_add_f32 v[30:31], v[26:27], v[6:7]
	v_pk_add_f32 v[6:7], v[26:27], v[6:7] neg_lo:[0,1] neg_hi:[0,1]
	v_pk_add_f32 v[54:55], v[24:25], v[22:23]
	v_xor_b32_e32 v27, 0x80000000, v6
	v_mov_b32_e32 v26, v7
	v_pk_add_f32 v[6:7], v[2:3], v[14:15]
	v_pk_add_f32 v[2:3], v[2:3], v[14:15] neg_lo:[0,1] neg_hi:[0,1]
	v_pk_add_f32 v[14:15], v[4:5], v[8:9]
	v_pk_add_f32 v[4:5], v[4:5], v[8:9] neg_lo:[0,1] neg_hi:[0,1]
	v_pk_add_f32 v[52:53], v[24:25], v[22:23] neg_lo:[0,1] neg_hi:[0,1]
	v_pk_add_f32 v[50:51], v[10:11], v[30:31]
	v_pk_add_f32 v[48:49], v[10:11], v[30:31] neg_lo:[0,1] neg_hi:[0,1]
	v_pk_add_f32 v[46:47], v[12:13], v[26:27]
	v_pk_add_f32 v[44:45], v[12:13], v[26:27] neg_lo:[0,1] neg_hi:[0,1]
	v_pk_add_f32 v[30:31], v[2:3], v[4:5] op_sel:[0,1] op_sel_hi:[1,0] neg_hi:[0,1]
	v_pk_add_f32 v[26:27], v[2:3], v[4:5] op_sel:[0,1] op_sel_hi:[1,0] neg_lo:[0,1]
	s_waitcnt lgkmcnt(6)
	v_pk_add_f32 v[8:9], v[38:39], v[82:83] neg_lo:[0,1] neg_hi:[0,1]
	s_waitcnt lgkmcnt(2)
	v_pk_add_f32 v[24:25], v[74:75], v[90:91] neg_lo:[0,1] neg_hi:[0,1]
	v_pk_add_f32 v[56:57], v[20:21], v[28:29] neg_lo:[0,1] neg_hi:[0,1]
	v_pk_add_f32 v[2:3], v[36:37], v[80:81]
	v_pk_add_f32 v[4:5], v[36:37], v[80:81] neg_lo:[0,1] neg_hi:[0,1]
	v_pk_mul_f32 v[28:29], v[24:25], s[62:63] op_sel_hi:[1,0]
	v_pk_add_f32 v[64:65], v[16:17], v[32:33] neg_lo:[0,1] neg_hi:[0,1]
	v_pk_mul_f32 v[10:11], v[8:9], s[62:63] op_sel:[1,0] op_sel_hi:[0,0] neg_hi:[1,0]
	v_pk_add_f32 v[12:13], v[40:41], v[84:85] neg_lo:[0,1] neg_hi:[0,1]
	v_pk_add_f32 v[16:17], v[42:43], v[86:87] neg_lo:[0,1] neg_hi:[0,1]
	v_pk_fma_f32 v[24:25], v[24:25], s[60:61], v[28:29] op_sel:[1,0,0] op_sel_hi:[0,0,1] neg_lo:[0,0,1] neg_hi:[1,0,1]
	s_waitcnt lgkmcnt(1)
	v_pk_add_f32 v[36:37], v[76:77], v[92:93] neg_lo:[0,1] neg_hi:[0,1]
	v_pk_add_f32 v[62:63], v[18:19], v[34:35]
	v_pk_add_f32 v[60:61], v[18:19], v[34:35] neg_lo:[0,1] neg_hi:[0,1]
	v_pk_add_f32 v[34:35], v[6:7], v[14:15]
	v_pk_add_f32 v[32:33], v[6:7], v[14:15] neg_lo:[0,1] neg_hi:[0,1]
	v_pk_add_f32 v[6:7], v[38:39], v[82:83]
	v_pk_fma_f32 v[8:9], v[8:9], s[60:61], v[10:11] op_sel_hi:[1,0,1]
	v_pk_add_f32 v[10:11], v[40:41], v[84:85]
	v_pk_mul_f32 v[38:39], v[36:37], s[70:71] op_sel_hi:[1,0]
	v_pk_mul_f32 v[14:15], v[12:13], s[70:71] op_sel:[1,0] op_sel_hi:[0,0] neg_hi:[1,0]
	v_pk_mul_f32 v[18:19], v[16:17], s[60:61] op_sel:[1,0] op_sel_hi:[0,0] neg_hi:[1,0]
	v_pk_add_f32 v[20:21], v[72:73], v[88:89] neg_lo:[0,1] neg_hi:[0,1]
	v_pk_fma_f32 v[36:37], v[36:37], s[70:71], v[38:39] op_sel:[1,0,0] op_sel_hi:[0,0,1] neg_lo:[0,0,1] neg_hi:[1,0,1]
	s_waitcnt lgkmcnt(0)
	v_pk_add_f32 v[40:41], v[78:79], v[94:95] neg_lo:[0,1] neg_hi:[0,1]
	v_pk_fma_f32 v[12:13], v[12:13], s[70:71], v[14:15] op_sel_hi:[1,0,1]
	v_pk_add_f32 v[14:15], v[42:43], v[86:87]
	v_pk_fma_f32 v[16:17], v[16:17], s[62:63], v[18:19] op_sel_hi:[1,0,1]
	v_pk_add_f32 v[18:19], v[72:73], v[88:89]
	v_xor_b32_e32 v23, 0x80000000, v20
	v_mov_b32_e32 v22, v21
	v_pk_add_f32 v[20:21], v[74:75], v[90:91]
	v_pk_mul_f32 v[42:43], v[40:41], s[60:61] op_sel_hi:[1,0]
	v_xor_b32_e32 v73, 0x80000000, v40
	v_mov_b32_e32 v72, v41
	v_pk_fma_f32 v[40:41], v[72:73], s[62:63], v[42:43] op_sel_hi:[1,0,1] neg_lo:[0,0,1] neg_hi:[0,0,1]
	v_pk_add_f32 v[42:43], v[2:3], v[18:19]
	v_pk_add_f32 v[2:3], v[2:3], v[18:19] neg_lo:[0,1] neg_hi:[0,1]
	v_pk_add_f32 v[18:19], v[6:7], v[20:21]
	v_pk_add_f32 v[6:7], v[6:7], v[20:21] neg_lo:[0,1] neg_hi:[0,1]
	v_pk_add_f32 v[28:29], v[76:77], v[92:93]
	v_pk_mul_f32 v[20:21], v[6:7], s[70:71] op_sel:[1,0] op_sel_hi:[0,0] neg_hi:[1,0]
	v_pk_add_f32 v[38:39], v[78:79], v[94:95]
	v_pk_fma_f32 v[6:7], v[6:7], s[70:71], v[20:21] op_sel_hi:[1,0,1]
	v_pk_add_f32 v[20:21], v[10:11], v[28:29]
	v_pk_add_f32 v[10:11], v[10:11], v[28:29] neg_lo:[0,1] neg_hi:[0,1]
	s_nop 0
	v_xor_b32_e32 v29, 0x80000000, v10
	v_mov_b32_e32 v28, v11
	v_pk_add_f32 v[10:11], v[14:15], v[38:39]
	v_pk_add_f32 v[14:15], v[14:15], v[38:39] neg_lo:[0,1] neg_hi:[0,1]
	s_nop 0
	v_pk_mul_f32 v[38:39], v[14:15], s[70:71] op_sel_hi:[1,0]
	v_xor_b32_e32 v73, 0x80000000, v14
	v_mov_b32_e32 v72, v15
	v_pk_fma_f32 v[14:15], v[72:73], s[70:71], v[38:39] op_sel_hi:[1,0,1] neg_lo:[0,0,1] neg_hi:[0,0,1]
	v_pk_add_f32 v[38:39], v[4:5], v[22:23]
	v_pk_add_f32 v[4:5], v[4:5], v[22:23] neg_lo:[0,1] neg_hi:[0,1]
	v_pk_add_f32 v[22:23], v[8:9], v[24:25]
	v_pk_add_f32 v[8:9], v[8:9], v[24:25] neg_lo:[0,1] neg_hi:[0,1]
	s_nop 0
	v_pk_mul_f32 v[24:25], v[8:9], s[70:71] op_sel:[1,0] op_sel_hi:[0,0] neg_hi:[1,0]
	s_nop 0
	v_pk_fma_f32 v[8:9], v[8:9], s[70:71], v[24:25] op_sel_hi:[1,0,1]
	v_pk_add_f32 v[24:25], v[12:13], v[36:37]
	v_pk_add_f32 v[12:13], v[12:13], v[36:37] neg_lo:[0,1] neg_hi:[0,1]
	v_pk_add_f32 v[74:75], v[38:39], v[24:25] neg_lo:[0,1] neg_hi:[0,1]
	v_xor_b32_e32 v37, 0x80000000, v12
	v_mov_b32_e32 v36, v13
	v_pk_add_f32 v[12:13], v[16:17], v[40:41]
	v_pk_add_f32 v[16:17], v[16:17], v[40:41] neg_lo:[0,1] neg_hi:[0,1]
	v_pk_add_f32 v[76:77], v[22:23], v[12:13]
	v_pk_mul_f32 v[40:41], v[16:17], s[70:71] op_sel_hi:[1,0]
	s_nop 0
	v_pk_fma_f32 v[16:17], v[16:17], s[70:71], v[40:41] op_sel:[1,0,0] op_sel_hi:[0,0,1] neg_lo:[0,0,1] neg_hi:[1,0,1]
	v_pk_add_f32 v[72:73], v[18:19], v[10:11]
	v_pk_add_f32 v[10:11], v[18:19], v[10:11] neg_lo:[0,1] neg_hi:[0,1]
	v_pk_add_f32 v[12:13], v[22:23], v[12:13] neg_lo:[0,1] neg_hi:[0,1]
	v_xor_b32_e32 v19, 0x80000000, v10
	v_mov_b32_e32 v18, v11
	v_pk_add_f32 v[10:11], v[2:3], v[28:29]
	v_pk_add_f32 v[2:3], v[2:3], v[28:29] neg_lo:[0,1] neg_hi:[0,1]
	v_pk_add_f32 v[28:29], v[6:7], v[14:15]
	v_pk_add_f32 v[6:7], v[6:7], v[14:15] neg_lo:[0,1] neg_hi:[0,1]
	v_pk_add_f32 v[22:23], v[10:11], v[28:29] neg_lo:[0,1] neg_hi:[0,1]
	v_xor_b32_e32 v15, 0x80000000, v6
	v_mov_b32_e32 v14, v7
	v_pk_add_f32 v[6:7], v[38:39], v[24:25]
	v_pk_add_f32 v[24:25], v[10:11], v[28:29]
	v_mov_b32_e32 v28, v146
	v_pk_add_f32 v[40:41], v[42:43], v[20:21]
	v_pk_add_f32 v[20:21], v[42:43], v[20:21] neg_lo:[0,1] neg_hi:[0,1]
	v_lshlrev_b32_e32 v71, 4, v28
	v_lshrrev_b32_e32 v29, 1, v28
	v_pk_add_f32 v[42:43], v[40:41], v[72:73]
	v_pk_add_f32 v[40:41], v[40:41], v[72:73] neg_lo:[0,1] neg_hi:[0,1]
	v_bfe_u32 v28, v28, 1, 4
	v_bitop3_b32 v72, v29, v71, 16 bitop3:0x6c
	v_lshl_add_u32 v72, v72, 3, 16
	v_lshlrev_b32_e32 v28, 3, v28
	v_add_u32_e32 v73, v72, v28
	ds_write_b64 v73, v[66:67]
	v_bitop3_b32 v73, v29, 1, 15 bitop3:0x6c
	v_xor_b32_e32 v79, 0x80000000, v12
	v_mov_b32_e32 v78, v13
	v_lshlrev_b32_e32 v73, 3, v73
	v_pk_add_f32 v[12:13], v[74:75], v[78:79]
	v_pk_add_f32 v[10:11], v[74:75], v[78:79] neg_lo:[0,1] neg_hi:[0,1]
	v_add_u32_e32 v74, v72, v73
	ds_write_b64 v74, v[64:65]
	v_bitop3_b32 v74, v29, 2, 15 bitop3:0x6c
	v_lshlrev_b32_e32 v74, 3, v74
	v_add_u32_e32 v75, v72, v74
	ds_write_b64 v75, v[62:63]
	v_bitop3_b32 v75, v29, 3, 15 bitop3:0x6c
	v_lshlrev_b32_e32 v75, 3, v75
	v_pk_add_f32 v[80:81], v[4:5], v[36:37]
	v_pk_add_f32 v[82:83], v[4:5], v[36:37] neg_lo:[0,1] neg_hi:[0,1]
	v_pk_add_f32 v[4:5], v[8:9], v[16:17]
	v_pk_add_f32 v[8:9], v[8:9], v[16:17] neg_lo:[0,1] neg_hi:[0,1]
	v_pk_add_f32 v[38:39], v[20:21], v[18:19]
	v_pk_add_f32 v[36:37], v[20:21], v[18:19] neg_lo:[0,1] neg_hi:[0,1]
	v_pk_add_f32 v[20:21], v[2:3], v[14:15]
	v_pk_add_f32 v[18:19], v[2:3], v[14:15] neg_lo:[0,1] neg_hi:[0,1]
	v_pk_add_f32 v[16:17], v[6:7], v[76:77]
	v_pk_add_f32 v[14:15], v[6:7], v[76:77] neg_lo:[0,1] neg_hi:[0,1]
	v_add_u32_e32 v76, v72, v75
	ds_write_b64 v76, v[60:61]
	v_bitop3_b32 v76, v29, 4, 15 bitop3:0x6c
	v_lshlrev_b32_e32 v76, 3, v76
	v_add_u32_e32 v77, v72, v76
	ds_write_b64 v77, v[58:59]
	v_bitop3_b32 v77, v29, 5, 15 bitop3:0x6c
	v_lshlrev_b32_e32 v77, 3, v77
	v_add_u32_e32 v78, v72, v77
	ds_write_b64 v78, v[56:57]
	v_bitop3_b32 v78, v29, 6, 15 bitop3:0x6c
	v_lshlrev_b32_e32 v78, 3, v78
	v_add_u32_e32 v79, v72, v78
	ds_write_b64 v79, v[54:55]
	v_bitop3_b32 v79, v29, 7, 15 bitop3:0x6c
	v_lshlrev_b32_e32 v79, 3, v79
	v_xor_b32_e32 v85, 0x80000000, v8
	v_mov_b32_e32 v84, v9
	v_pk_add_f32 v[8:9], v[80:81], v[4:5]
	v_pk_add_f32 v[6:7], v[80:81], v[4:5] neg_lo:[0,1] neg_hi:[0,1]
	v_add_u32_e32 v80, v72, v79
	ds_write_b64 v80, v[52:53]
	v_bitop3_b32 v80, v29, 8, 15 bitop3:0x6c
	v_lshlrev_b32_e32 v80, 3, v80
	v_add_u32_e32 v81, v72, v80
	ds_write_b64 v81, v[50:51]
	v_bitop3_b32 v81, v29, 9, 15 bitop3:0x6c
	v_lshlrev_b32_e32 v81, 3, v81
	v_pk_add_f32 v[4:5], v[82:83], v[84:85]
	v_pk_add_f32 v[2:3], v[82:83], v[84:85] neg_lo:[0,1] neg_hi:[0,1]
	v_add_u32_e32 v82, v72, v81
	ds_write_b64 v82, v[48:49]
	v_bitop3_b32 v82, v29, 10, 15 bitop3:0x6c
	v_lshlrev_b32_e32 v82, 3, v82
	v_add_u32_e32 v83, v72, v82
	ds_write_b64 v83, v[46:47]
	v_bitop3_b32 v83, v29, 11, 15 bitop3:0x6c
	v_lshlrev_b32_e32 v83, 3, v83
	v_add_u32_e32 v84, v72, v83
	ds_write_b64 v84, v[44:45]
	v_bitop3_b32 v84, v29, 12, 15 bitop3:0x6c
	v_lshlrev_b32_e32 v84, 3, v84
	v_add_u32_e32 v85, v72, v84
	ds_write_b64 v85, v[34:35]
	v_bitop3_b32 v85, v29, 13, 15 bitop3:0x6c
	v_lshlrev_b32_e32 v85, 3, v85
	v_add_u32_e32 v86, v72, v85
	ds_write_b64 v86, v[32:33]
	v_bitop3_b32 v86, v29, 14, 15 bitop3:0x6c
	v_lshlrev_b32_e32 v86, 3, v86
	v_add_u32_e32 v87, v72, v86
	v_add_u32_e32 v88, 0x2000, v71
	ds_write_b64 v87, v[30:31]
	v_bitop3_b32 v87, v29, 15, v29 bitop3:0xc
	v_bitop3_b32 v29, v88, v29, 16 bitop3:0x78
	v_lshlrev_b32_e32 v87, 3, v87
	v_lshl_add_u32 v29, v29, 3, 16
	v_add_u32_e32 v72, v72, v87
	v_add_u32_e32 v28, v29, v28
	ds_write_b64 v72, v[26:27]
	ds_write_b64 v28, v[42:43]
	v_add_u32_e32 v28, v29, v73
	ds_write_b64 v28, v[40:41]
	v_add_u32_e32 v28, v29, v74
	ds_write_b64 v28, v[38:39]
	v_add_u32_e32 v28, v29, v75
	ds_write_b64 v28, v[36:37]
	v_add_u32_e32 v28, v29, v76
	ds_write_b64 v28, v[24:25]
	v_add_u32_e32 v28, v29, v77
	ds_write_b64 v28, v[22:23]
	v_add_u32_e32 v28, v29, v78
	ds_write_b64 v28, v[20:21]
	v_add_u32_e32 v28, v29, v79
	ds_write_b64 v28, v[18:19]
	v_add_u32_e32 v28, v29, v80
	ds_write_b64 v28, v[16:17]
	v_add_u32_e32 v28, v29, v81
	ds_write_b64 v28, v[14:15]
	v_add_u32_e32 v28, v29, v82
	v_or_b32_e32 v72, 1, v71
	ds_write_b64 v28, v[12:13]
	v_add_u32_e32 v28, v29, v83
	v_bfrev_b32_e32 v72, v72
	ds_write_b64 v28, v[10:11]
	v_add_u32_e32 v28, v29, v84
	v_lshrrev_b32_e32 v72, 18, v72
	ds_write_b64 v28, v[8:9]
	v_add_u32_e32 v28, v29, v85
	v_sub_u32_e32 v72, 0, v72
	ds_write_b64 v28, v[6:7]
	v_add_u32_e32 v28, v29, v86
	v_and_b32_e32 v72, 0x3fff, v72
	ds_write_b64 v28, v[4:5]
	v_add_u32_e32 v28, v29, v87
	v_bfrev_b32_e32 v72, v72
	ds_write_b64 v28, v[2:3]
	v_lshl_add_u64 v[28:29], v[0:1], 2, s[0:1]
	v_bfrev_b32_e32 v0, v71
	v_lshrrev_b32_e32 v73, 18, v72
	v_lshrrev_b32_e32 v72, 23, v72
	v_lshrrev_b32_e32 v0, 18, v0
	v_bitop3_b32 v72, v72, v73, 31 bitop3:0x6c
	v_or_b32_e32 v73, 2, v71
	v_sub_u32_e32 v0, 0, v0
	v_bfrev_b32_e32 v73, v73
	v_and_b32_e32 v0, 0x3fff, v0
	v_lshrrev_b32_e32 v73, 18, v73
	v_bfrev_b32_e32 v0, v0
	v_sub_u32_e32 v73, 0, v73
	v_lshrrev_b32_e32 v1, 18, v0
	v_lshrrev_b32_e32 v0, 23, v0
	v_and_b32_e32 v74, 0x3fff, v73
	v_bitop3_b32 v0, v0, v1, 31 bitop3:0x6c
	v_bfrev_b32_e32 v74, v74
	v_and_b32_e32 v73, 0x1fff, v73
	v_lshl_add_u32 v0, v0, 3, 16
	v_lshrrev_b32_e32 v75, 18, v74
	v_lshrrev_b32_e32 v74, 23, v74
	v_bfrev_b32_e32 v73, v73
	s_waitcnt lgkmcnt(0)
	s_barrier
	ds_read_b64 v[0:1], v0
	v_bitop3_b32 v74, v74, v75, 31 bitop3:0x6c
	v_lshrrev_b32_e32 v75, 18, v73
	v_lshrrev_b32_e32 v73, 23, v73
	v_bitop3_b32 v73, v73, v75, 31 bitop3:0x6c
	v_lshl_add_u32 v72, v72, 3, 16
	v_lshl_add_u32 v74, v74, 3, 16
	v_lshl_add_u32 v76, v73, 3, 16
	ds_read_b64 v[72:73], v72
	ds_read_b64 v[74:75], v74
	ds_read_b64 v[76:77], v76
	s_waitcnt lgkmcnt(3)
	v_pk_add_f32 v[78:79], v[66:67], v[0:1]
	v_sub_f32_e32 v1, v67, v1
	v_sub_f32_e32 v0, v0, v66
	v_mul_f32_e32 v67, 0.5, v1
	v_mul_f32_e32 v66, 0.5, v0
	s_waitcnt lgkmcnt(2)
	v_pk_add_f32 v[0:1], v[64:65], v[72:73]
	v_mul_f32_e32 v78, 0.5, v78
	v_mul_f32_e32 v80, 0.5, v0
	v_sub_f32_e32 v0, v65, v73
	v_mul_f32_e32 v65, 0.5, v0
	v_sub_f32_e32 v0, v72, v64
	v_mul_f32_e32 v73, 0.5, v1
	v_mul_f32_e32 v64, 0.5, v0
	s_waitcnt lgkmcnt(1)
	v_pk_add_f32 v[0:1], v[62:63], v[74:75]
	s_mov_b32 s0, 0x10000
	v_mul_f32_e32 v72, 0.5, v0
	v_sub_f32_e32 v0, v63, v75
	v_mul_f32_e32 v75, 0.5, v0
	v_sub_f32_e32 v0, v74, v62
	v_mul_f32_e32 v81, 0.5, v1
	v_mul_f32_e32 v74, 0.5, v0
	s_waitcnt lgkmcnt(0)
	v_pk_add_f32 v[0:1], v[60:61], v[76:77]
	v_sub_f32_e32 v61, v61, v77
	v_mul_f32_e32 v0, 0.5, v0
	v_mul_f32_e32 v61, 0.5, v61
	v_sub_f32_e32 v60, v76, v60
	v_mul_f32_e32 v79, 0.5, v79
	v_mul_f32_e32 v1, 0.5, v1
	v_mul_f32_e32 v76, 0.5, v60
	v_cvt_pk_f16_f32 v63, v0, v61
	v_cvt_pk_f16_f32 v62, v72, v75
	v_cvt_pk_f16_f32 v61, v80, v65
	v_cvt_pk_f16_f32 v60, v78, v67
	v_add_co_u32_e32 v0, vcc, s0, v28
	global_store_dwordx4 v[28:29], v[60:63], off offset:-4096
	s_lshl_b64 s[0:1], s[68:69], 13
	s_add_u32 s92, s0, 0xc00000
	v_cvt_pk_f16_f32 v63, v1, v76
	v_cvt_pk_f16_f32 v62, v81, v74
	v_cvt_pk_f16_f32 v61, v73, v64
	v_cvt_pk_f16_f32 v60, v79, v66
	v_addc_co_u32_e32 v1, vcc, 0, v29, vcc
	global_store_dwordx4 v[0:1], v[60:63], off offset:-4096
	s_addc_u32 s93, s1, 0
	s_add_u32 s94, s56, s10
	v_or_b32_e32 v60, 4, v71
	v_bfrev_b32_e32 v60, v60
	v_lshrrev_b32_e32 v60, 18, v60
	v_sub_u32_e32 v62, 0, v60
	v_and_b32_e32 v63, 0x1fff, v62
	v_bfrev_b32_e32 v63, v63
	v_lshrrev_b32_e32 v64, 18, v63
	v_lshrrev_b32_e32 v63, 23, v63
	v_bitop3_b32 v63, v63, v64, 31 bitop3:0x6c
	v_or_b32_e32 v64, 6, v71
	v_bfrev_b32_e32 v64, v64
	v_and_b32_e32 v60, 0x3fff, v62
	v_lshrrev_b32_e32 v64, 18, v64
	v_bfrev_b32_e32 v60, v60
	v_sub_u32_e32 v64, 0, v64
	v_lshrrev_b32_e32 v61, 18, v60
	v_lshrrev_b32_e32 v60, 23, v60
	v_and_b32_e32 v64, 0x2fff, v64
	v_bitop3_b32 v60, v60, v61, 31 bitop3:0x6c
	v_bfrev_b32_e32 v64, v64
	v_and_b32_e32 v62, 0xfff, v62
	v_lshl_add_u32 v60, v60, 3, 16
	v_lshrrev_b32_e32 v65, 18, v64
	v_lshrrev_b32_e32 v64, 23, v64
	v_bfrev_b32_e32 v62, v62
	ds_read_b64 v[60:61], v60
	v_bitop3_b32 v64, v64, v65, 31 bitop3:0x6c
	v_lshrrev_b32_e32 v65, 18, v62
	v_lshrrev_b32_e32 v62, 23, v62
	v_bitop3_b32 v62, v62, v65, 31 bitop3:0x6c
	v_lshl_add_u32 v63, v63, 3, 16
	v_lshl_add_u32 v64, v64, 3, 16
	v_lshl_add_u32 v66, v62, 3, 16
	ds_read_b64 v[62:63], v63
	ds_read_b64 v[64:65], v64
	ds_read_b64 v[66:67], v66
	s_waitcnt lgkmcnt(3)
	v_pk_add_f32 v[72:73], v[58:59], v[60:61]
	v_sub_f32_e32 v59, v59, v61
	v_sub_f32_e32 v58, v60, v58
	v_mul_f32_e32 v61, 0.5, v59
	v_mul_f32_e32 v60, 0.5, v58
	s_waitcnt lgkmcnt(2)
	v_pk_add_f32 v[58:59], v[56:57], v[62:63]
	v_sub_f32_e32 v57, v57, v63
	v_sub_f32_e32 v56, v62, v56
	v_mul_f32_e32 v63, 0.5, v57
	v_mul_f32_e32 v62, 0.5, v56
	s_waitcnt lgkmcnt(1)
	v_pk_add_f32 v[56:57], v[54:55], v[64:65]
	v_sub_f32_e32 v55, v55, v65
	v_sub_f32_e32 v54, v64, v54
	v_mul_f32_e32 v65, 0.5, v55
	v_mul_f32_e32 v64, 0.5, v54
	s_waitcnt lgkmcnt(0)
	v_pk_add_f32 v[54:55], v[52:53], v[66:67]
	v_sub_f32_e32 v53, v53, v67
	v_mul_f32_e32 v72, 0.5, v72
	v_mul_f32_e32 v58, 0.5, v58
	v_mul_f32_e32 v56, 0.5, v56
	v_mul_f32_e32 v54, 0.5, v54
	v_mul_f32_e32 v53, 0.5, v53
	v_sub_f32_e32 v52, v66, v52
	v_mul_f32_e32 v73, 0.5, v73
	v_mul_f32_e32 v59, 0.5, v59
	v_mul_f32_e32 v57, 0.5, v57
	v_mul_f32_e32 v67, 0.5, v55
	v_mul_f32_e32 v66, 0.5, v52
	v_cvt_pk_f16_f32 v55, v54, v53
	v_cvt_pk_f16_f32 v54, v56, v65
	v_cvt_pk_f16_f32 v53, v58, v63
	v_cvt_pk_f16_f32 v52, v72, v61
	global_store_dwordx4 v[28:29], v[52:55], off offset:-3072
	s_addc_u32 s95, s57, s11
	s_lshl_b64 s[0:1], s[68:69], 14
	v_cvt_pk_f16_f32 v55, v67, v66
	v_cvt_pk_f16_f32 v54, v57, v64
	v_cvt_pk_f16_f32 v53, v59, v62
	v_cvt_pk_f16_f32 v52, v73, v60
	global_store_dwordx4 v[0:1], v[52:55], off offset:-3072
	s_add_u32 s12, s26, s0
	s_addc_u32 s13, s27, s1
	v_or_b32_e32 v52, 8, v71
	v_bfrev_b32_e32 v52, v52
	v_lshrrev_b32_e32 v52, 18, v52
	v_sub_u32_e32 v62, 0, v52
	v_and_b32_e32 v54, 0x1fff, v62
	v_bfrev_b32_e32 v54, v54
	v_lshrrev_b32_e32 v55, 18, v54
	v_lshrrev_b32_e32 v54, 23, v54
	v_bitop3_b32 v54, v54, v55, 31 bitop3:0x6c
	v_or_b32_e32 v55, 10, v71
	v_bfrev_b32_e32 v55, v55
	v_lshrrev_b32_e32 v55, 18, v55
	v_sub_u32_e32 v55, 0, v55
	v_and_b32_e32 v55, 0x2fff, v55
	v_and_b32_e32 v52, 0x3fff, v62
	v_bfrev_b32_e32 v55, v55
	v_bfrev_b32_e32 v52, v52
	v_lshrrev_b32_e32 v56, 18, v55
	v_lshrrev_b32_e32 v55, 23, v55
	v_lshrrev_b32_e32 v53, 18, v52
	v_lshrrev_b32_e32 v52, 23, v52
	v_bitop3_b32 v55, v55, v56, 31 bitop3:0x6c
	v_bitop3_b32 v52, v52, v53, 31 bitop3:0x6c
	v_lshl_add_u32 v56, v55, 3, 16
	v_and_b32_e32 v55, 0xfff, v62
	v_lshl_add_u32 v52, v52, 3, 16
	v_bfrev_b32_e32 v55, v55
	ds_read_b64 v[52:53], v52
	v_lshrrev_b32_e32 v57, 18, v55
	v_lshrrev_b32_e32 v55, 23, v55
	v_bitop3_b32 v55, v55, v57, 31 bitop3:0x6c
	v_lshl_add_u32 v54, v54, 3, 16
	v_lshl_add_u32 v58, v55, 3, 16
	ds_read_b64 v[54:55], v54
	ds_read_b64 v[56:57], v56
	ds_read_b64 v[58:59], v58
	s_waitcnt lgkmcnt(3)
	v_pk_add_f32 v[60:61], v[50:51], v[52:53]
	v_sub_f32_e32 v51, v51, v53
	v_sub_f32_e32 v50, v52, v50
	v_mul_f32_e32 v53, 0.5, v51
	v_mul_f32_e32 v52, 0.5, v50
	s_waitcnt lgkmcnt(2)
	v_pk_add_f32 v[50:51], v[48:49], v[54:55]
	v_sub_f32_e32 v49, v49, v55
	v_sub_f32_e32 v48, v54, v48
	v_mul_f32_e32 v55, 0.5, v49
	v_mul_f32_e32 v54, 0.5, v48
	s_waitcnt lgkmcnt(1)
	v_pk_add_f32 v[48:49], v[46:47], v[56:57]
	v_sub_f32_e32 v47, v47, v57
	v_sub_f32_e32 v46, v56, v46
	v_mul_f32_e32 v57, 0.5, v47
	v_mul_f32_e32 v56, 0.5, v46
	s_waitcnt lgkmcnt(0)
	v_pk_add_f32 v[46:47], v[44:45], v[58:59]
	v_sub_f32_e32 v45, v45, v59
	v_mul_f32_e32 v60, 0.5, v60
	v_mul_f32_e32 v50, 0.5, v50
	v_mul_f32_e32 v48, 0.5, v48
	v_mul_f32_e32 v46, 0.5, v46
	v_mul_f32_e32 v45, 0.5, v45
	v_sub_f32_e32 v44, v58, v44
	v_mul_f32_e32 v61, 0.5, v61
	v_mul_f32_e32 v51, 0.5, v51
	v_mul_f32_e32 v49, 0.5, v49
	v_mul_f32_e32 v59, 0.5, v47
	v_mul_f32_e32 v58, 0.5, v44
	v_cvt_pk_f16_f32 v47, v46, v45
	v_cvt_pk_f16_f32 v46, v48, v57
	v_cvt_pk_f16_f32 v45, v50, v55
	v_cvt_pk_f16_f32 v44, v60, v53
	global_store_dwordx4 v[28:29], v[44:47], off offset:-2048
	s_add_u32 s14, s30, s0
	s_addc_u32 s15, s31, s1
	v_cvt_pk_f16_f32 v47, v59, v58
	v_cvt_pk_f16_f32 v46, v49, v56
	v_cvt_pk_f16_f32 v45, v51, v54
	v_cvt_pk_f16_f32 v44, v61, v52
	global_store_dwordx4 v[0:1], v[44:47], off offset:-2048
	v_cmp_lt_i32_e32 vcc, s25, v146
	v_add_u32_e32 v55, 0xe00, v146
	v_or_b32_e32 v44, 12, v71
	v_bfrev_b32_e32 v44, v44
	v_lshrrev_b32_e32 v44, 18, v44
	v_sub_u32_e32 v46, 0, v44
	v_and_b32_e32 v44, 0x37ff, v46
	v_and_b32_e32 v46, 0x17ff, v46
	v_bfrev_b32_e32 v46, v46
	v_lshrrev_b32_e32 v47, 18, v46
	v_lshrrev_b32_e32 v46, 23, v46
	v_bitop3_b32 v46, v46, v47, 31 bitop3:0x6c
	v_or_b32_e32 v47, 14, v71
	v_bfrev_b32_e32 v47, v47
	v_lshrrev_b32_e32 v47, 18, v47
	v_sub_u32_e32 v47, 0, v47
	v_and_b32_e32 v47, 0x27ff, v47
	v_bfrev_b32_e32 v47, v47
	v_bfrev_b32_e32 v44, v44
	v_lshrrev_b32_e32 v48, 18, v47
	v_lshrrev_b32_e32 v47, 23, v47
	v_lshrrev_b32_e32 v45, 18, v44
	v_lshrrev_b32_e32 v44, 23, v44
	v_bitop3_b32 v47, v47, v48, 31 bitop3:0x6c
	v_bitop3_b32 v44, v44, v45, 31 bitop3:0x6c
	v_lshl_add_u32 v48, v47, 3, 16
	v_and_b32_e32 v47, 0x7ff, v62
	v_lshl_add_u32 v44, v44, 3, 16
	v_bfrev_b32_e32 v47, v47
	ds_read_b64 v[44:45], v44
	v_lshrrev_b32_e32 v49, 18, v47
	v_lshrrev_b32_e32 v47, 23, v47
	v_bitop3_b32 v47, v47, v49, 31 bitop3:0x6c
	v_lshl_add_u32 v46, v46, 3, 16
	v_lshl_add_u32 v50, v47, 3, 16
	ds_read_b64 v[46:47], v46
	ds_read_b64 v[48:49], v48
	ds_read_b64 v[50:51], v50
	s_waitcnt lgkmcnt(3)
	v_pk_add_f32 v[52:53], v[34:35], v[44:45]
	v_sub_f32_e32 v35, v35, v45
	v_sub_f32_e32 v34, v44, v34
	v_mul_f32_e32 v45, 0.5, v35
	v_mul_f32_e32 v44, 0.5, v34
	s_waitcnt lgkmcnt(2)
	v_pk_add_f32 v[34:35], v[32:33], v[46:47]
	v_sub_f32_e32 v33, v33, v47
	v_sub_f32_e32 v32, v46, v32
	v_mul_f32_e32 v47, 0.5, v33
	v_mul_f32_e32 v46, 0.5, v32
	s_waitcnt lgkmcnt(1)
	v_pk_add_f32 v[32:33], v[30:31], v[48:49]
	v_sub_f32_e32 v31, v31, v49
	v_sub_f32_e32 v30, v48, v30
	v_mul_f32_e32 v49, 0.5, v31
	v_mul_f32_e32 v48, 0.5, v30
	s_waitcnt lgkmcnt(0)
	v_pk_add_f32 v[30:31], v[26:27], v[50:51]
	v_sub_f32_e32 v27, v27, v51
	v_mul_f32_e32 v52, 0.5, v52
	v_mul_f32_e32 v34, 0.5, v34
	v_mul_f32_e32 v32, 0.5, v32
	v_mul_f32_e32 v30, 0.5, v30
	v_mul_f32_e32 v27, 0.5, v27
	v_sub_f32_e32 v26, v50, v26
	v_mul_f32_e32 v53, 0.5, v53
	v_mul_f32_e32 v35, 0.5, v35
	v_mul_f32_e32 v54, 0.5, v33
	v_mul_f32_e32 v51, 0.5, v31
	v_mul_f32_e32 v26, 0.5, v26
	v_cvt_pk_f16_f32 v33, v30, v27
	v_cvt_pk_f16_f32 v32, v32, v49
	v_cvt_pk_f16_f32 v31, v34, v47
	v_cvt_pk_f16_f32 v30, v52, v45
	global_store_dwordx4 v[28:29], v[30:33], off offset:-1024
	v_add_u32_e32 v52, 0x800, v146
	s_nop 0
	v_cvt_pk_f16_f32 v33, v51, v26
	v_cvt_pk_f16_f32 v32, v54, v48
	v_cvt_pk_f16_f32 v31, v35, v46
	v_cvt_pk_f16_f32 v30, v53, v44
	global_store_dwordx4 v[0:1], v[30:33], off offset:-1024
	v_bfrev_b32_e32 v26, v88
	v_lshrrev_b32_e32 v26, 18, v26
	v_add_u32_e32 v30, 0x2001, v71
	v_bfrev_b32_e32 v30, v30
	v_lshrrev_b32_e32 v30, 18, v30
	v_sub_u32_e32 v30, 0, v30
	v_and_b32_e32 v30, 0x3fff, v30
	v_bfrev_b32_e32 v30, v30
	v_lshrrev_b32_e32 v31, 18, v30
	v_lshrrev_b32_e32 v30, 23, v30
	v_bitop3_b32 v30, v30, v31, 31 bitop3:0x6c
	v_add_u32_e32 v31, 0x2002, v71
	v_bfrev_b32_e32 v31, v31
	v_lshrrev_b32_e32 v31, 18, v31
	v_sub_u32_e32 v31, 0, v31
	v_and_b32_e32 v31, 0x3fff, v31
	v_bfrev_b32_e32 v31, v31
	v_lshrrev_b32_e32 v32, 18, v31
	v_lshrrev_b32_e32 v31, 23, v31
	v_bitop3_b32 v31, v31, v32, 31 bitop3:0x6c
	v_sub_u32_e32 v26, 0, v26
	v_lshl_add_u32 v32, v31, 3, 16
	v_add_u32_e32 v31, 0x2003, v71
	v_and_b32_e32 v26, 0x3fff, v26
	v_bfrev_b32_e32 v31, v31
	v_bfrev_b32_e32 v26, v26
	v_lshrrev_b32_e32 v31, 18, v31
	v_lshrrev_b32_e32 v27, 18, v26
	v_lshrrev_b32_e32 v26, 23, v26
	v_sub_u32_e32 v31, 0, v31
	v_bitop3_b32 v26, v26, v27, 31 bitop3:0x6c
	v_and_b32_e32 v31, 0x1fff, v31
	v_lshl_add_u32 v26, v26, 3, 16
	v_bfrev_b32_e32 v31, v31
	ds_read_b64 v[26:27], v26
	v_lshrrev_b32_e32 v33, 18, v31
	v_lshrrev_b32_e32 v31, 23, v31
	v_bitop3_b32 v31, v31, v33, 31 bitop3:0x6c
	v_lshl_add_u32 v30, v30, 3, 16
	v_lshl_add_u32 v34, v31, 3, 16
	ds_read_b64 v[30:31], v30
	ds_read_b64 v[32:33], v32
	ds_read_b64 v[34:35], v34
	s_waitcnt lgkmcnt(3)
	v_pk_add_f32 v[44:45], v[42:43], v[26:27]
	v_sub_f32_e32 v27, v43, v27
	v_sub_f32_e32 v26, v26, v42
	v_mul_f32_e32 v43, 0.5, v27
	v_mul_f32_e32 v42, 0.5, v26
	s_waitcnt lgkmcnt(2)
	v_pk_add_f32 v[26:27], v[40:41], v[30:31]
	v_mul_f32_e32 v44, 0.5, v44
	v_mul_f32_e32 v46, 0.5, v26
	v_sub_f32_e32 v26, v41, v31
	v_mul_f32_e32 v31, 0.5, v26
	v_sub_f32_e32 v26, v30, v40
	v_mul_f32_e32 v41, 0.5, v27
	v_mul_f32_e32 v40, 0.5, v26
	s_waitcnt lgkmcnt(1)
	v_pk_add_f32 v[26:27], v[38:39], v[32:33]
	v_mul_f32_e32 v45, 0.5, v45
	v_mul_f32_e32 v30, 0.5, v26
	v_sub_f32_e32 v26, v39, v33
	v_mul_f32_e32 v39, 0.5, v26
	v_sub_f32_e32 v26, v32, v38
	v_mul_f32_e32 v47, 0.5, v27
	v_mul_f32_e32 v38, 0.5, v26
	s_waitcnt lgkmcnt(0)
	v_pk_add_f32 v[26:27], v[36:37], v[34:35]
	v_sub_f32_e32 v32, v37, v35
	v_mul_f32_e32 v26, 0.5, v26
	v_mul_f32_e32 v32, 0.5, v32
	v_sub_f32_e32 v33, v34, v36
	v_mul_f32_e32 v27, 0.5, v27
	v_mul_f32_e32 v34, 0.5, v33
	v_cvt_pk_f16_f32 v33, v26, v32
	v_cvt_pk_f16_f32 v32, v30, v39
	v_cvt_pk_f16_f32 v31, v46, v31
	v_cvt_pk_f16_f32 v30, v44, v43
	global_store_dwordx4 v[28:29], v[30:33], off
	v_add_u32_e32 v26, 0x2004, v71
	v_bfrev_b32_e32 v26, v26
	v_cvt_pk_f16_f32 v33, v27, v34
	v_cvt_pk_f16_f32 v32, v47, v38
	v_cvt_pk_f16_f32 v31, v41, v40
	v_cvt_pk_f16_f32 v30, v45, v42
	global_store_dwordx4 v[0:1], v[30:33], off
	v_lshrrev_b32_e32 v26, 18, v26
	v_sub_u32_e32 v26, 0, v26
	v_add_u32_e32 v30, 0x2005, v71
	v_bfrev_b32_e32 v30, v30
	v_lshrrev_b32_e32 v30, 18, v30
	v_sub_u32_e32 v30, 0, v30
	v_and_b32_e32 v30, 0x1fff, v30
	v_bfrev_b32_e32 v30, v30
	v_lshrrev_b32_e32 v31, 18, v30
	v_lshrrev_b32_e32 v30, 23, v30
	v_bitop3_b32 v30, v30, v31, 31 bitop3:0x6c
	v_add_u32_e32 v31, 0x2006, v71
	v_bfrev_b32_e32 v31, v31
	v_lshrrev_b32_e32 v31, 18, v31
	v_sub_u32_e32 v31, 0, v31
	v_and_b32_e32 v31, 0x2fff, v31
	v_bfrev_b32_e32 v31, v31
	v_lshrrev_b32_e32 v32, 18, v31
	v_lshrrev_b32_e32 v31, 23, v31
	v_bitop3_b32 v31, v31, v32, 31 bitop3:0x6c
	v_lshl_add_u32 v32, v31, 3, 16
	v_add_u32_e32 v31, 0x2007, v71
	v_and_b32_e32 v26, 0x3fff, v26
	v_bfrev_b32_e32 v31, v31
	v_bfrev_b32_e32 v26, v26
	v_lshrrev_b32_e32 v31, 18, v31
	v_lshrrev_b32_e32 v27, 18, v26
	v_lshrrev_b32_e32 v26, 23, v26
	v_sub_u32_e32 v31, 0, v31
	v_bitop3_b32 v26, v26, v27, 31 bitop3:0x6c
	v_and_b32_e32 v31, 0xfff, v31
	v_lshl_add_u32 v26, v26, 3, 16
	v_bfrev_b32_e32 v31, v31
	ds_read_b64 v[26:27], v26
	v_lshrrev_b32_e32 v33, 18, v31
	v_lshrrev_b32_e32 v31, 23, v31
	v_bitop3_b32 v31, v31, v33, 31 bitop3:0x6c
	v_lshl_add_u32 v30, v30, 3, 16
	v_lshl_add_u32 v34, v31, 3, 16
	ds_read_b64 v[30:31], v30
	ds_read_b64 v[32:33], v32
	ds_read_b64 v[34:35], v34
	s_waitcnt lgkmcnt(3)
	v_pk_add_f32 v[36:37], v[24:25], v[26:27]
	v_sub_f32_e32 v25, v25, v27
	v_sub_f32_e32 v24, v26, v24
	v_mul_f32_e32 v27, 0.5, v25
	v_mul_f32_e32 v26, 0.5, v24
	s_waitcnt lgkmcnt(2)
	v_pk_add_f32 v[24:25], v[22:23], v[30:31]
	v_sub_f32_e32 v23, v23, v31
	v_sub_f32_e32 v22, v30, v22
	v_mul_f32_e32 v31, 0.5, v23
	v_mul_f32_e32 v30, 0.5, v22
	s_waitcnt lgkmcnt(1)
	v_pk_add_f32 v[22:23], v[20:21], v[32:33]
	v_sub_f32_e32 v21, v21, v33
	v_sub_f32_e32 v20, v32, v20
	v_mul_f32_e32 v33, 0.5, v21
	v_mul_f32_e32 v32, 0.5, v20
	s_waitcnt lgkmcnt(0)
	v_pk_add_f32 v[20:21], v[18:19], v[34:35]
	v_sub_f32_e32 v19, v19, v35
	v_mul_f32_e32 v36, 0.5, v36
	v_mul_f32_e32 v24, 0.5, v24
	v_mul_f32_e32 v22, 0.5, v22
	v_mul_f32_e32 v20, 0.5, v20
	v_mul_f32_e32 v19, 0.5, v19
	v_sub_f32_e32 v18, v34, v18
	v_mul_f32_e32 v37, 0.5, v37
	v_mul_f32_e32 v25, 0.5, v25
	v_mul_f32_e32 v23, 0.5, v23
	v_mul_f32_e32 v35, 0.5, v21
	v_mul_f32_e32 v34, 0.5, v18
	v_cvt_pk_f16_f32 v21, v20, v19
	v_cvt_pk_f16_f32 v20, v22, v33
	v_cvt_pk_f16_f32 v19, v24, v31
	v_cvt_pk_f16_f32 v18, v36, v27
	global_store_dwordx4 v[28:29], v[18:21], off offset:1024
	v_add_u32_e32 v53, 0xa00, v146
	v_add_u32_e32 v54, 0xc00, v146
	v_cvt_pk_f16_f32 v21, v35, v34
	v_cvt_pk_f16_f32 v20, v23, v32
	v_cvt_pk_f16_f32 v19, v25, v30
	v_cvt_pk_f16_f32 v18, v37, v26
	global_store_dwordx4 v[0:1], v[18:21], off offset:1024
	v_add_u32_e32 v47, 0x1000, v146
	v_add_u32_e32 v46, 0x1200, v146
	v_add_u32_e32 v20, 0x2009, v71
	v_bfrev_b32_e32 v20, v20
	v_lshrrev_b32_e32 v20, 18, v20
	v_sub_u32_e32 v20, 0, v20
	v_and_b32_e32 v20, 0x1fff, v20
	v_bfrev_b32_e32 v20, v20
	v_lshrrev_b32_e32 v21, 18, v20
	v_lshrrev_b32_e32 v20, 23, v20
	v_bitop3_b32 v20, v20, v21, 31 bitop3:0x6c
	v_add_u32_e32 v21, 0x200a, v71
	v_bfrev_b32_e32 v21, v21
	v_lshrrev_b32_e32 v21, 18, v21
	v_sub_u32_e32 v21, 0, v21
	v_and_b32_e32 v21, 0x2fff, v21
	v_add_u32_e32 v18, 0x2008, v71
	v_bfrev_b32_e32 v21, v21
	v_bfrev_b32_e32 v18, v18
	v_lshrrev_b32_e32 v22, 18, v21
	v_lshrrev_b32_e32 v21, 23, v21
	v_lshrrev_b32_e32 v18, 18, v18
	v_bitop3_b32 v21, v21, v22, 31 bitop3:0x6c
	v_sub_u32_e32 v18, 0, v18
	v_lshl_add_u32 v22, v21, 3, 16
	v_add_u32_e32 v21, 0x200b, v71
	v_and_b32_e32 v18, 0x3fff, v18
	v_bfrev_b32_e32 v21, v21
	v_bfrev_b32_e32 v18, v18
	v_lshrrev_b32_e32 v21, 18, v21
	v_lshrrev_b32_e32 v19, 18, v18
	v_lshrrev_b32_e32 v18, 23, v18
	v_sub_u32_e32 v21, 0, v21
	v_bitop3_b32 v18, v18, v19, 31 bitop3:0x6c
	v_and_b32_e32 v21, 0xfff, v21
	v_lshl_add_u32 v18, v18, 3, 16
	v_bfrev_b32_e32 v21, v21
	ds_read_b64 v[18:19], v18
	v_lshrrev_b32_e32 v23, 18, v21
	v_lshrrev_b32_e32 v21, 23, v21
	v_bitop3_b32 v21, v21, v23, 31 bitop3:0x6c
	v_lshl_add_u32 v20, v20, 3, 16
	v_lshl_add_u32 v24, v21, 3, 16
	ds_read_b64 v[20:21], v20
	ds_read_b64 v[22:23], v22
	ds_read_b64 v[24:25], v24
	s_waitcnt lgkmcnt(3)
	v_pk_add_f32 v[26:27], v[16:17], v[18:19]
	v_sub_f32_e32 v17, v17, v19
	v_sub_f32_e32 v16, v18, v16
	v_mul_f32_e32 v19, 0.5, v17
	v_mul_f32_e32 v18, 0.5, v16
	s_waitcnt lgkmcnt(2)
	v_pk_add_f32 v[16:17], v[14:15], v[20:21]
	v_sub_f32_e32 v15, v15, v21
	v_sub_f32_e32 v14, v20, v14
	v_mul_f32_e32 v21, 0.5, v15
	v_mul_f32_e32 v20, 0.5, v14
	s_waitcnt lgkmcnt(1)
	v_pk_add_f32 v[14:15], v[12:13], v[22:23]
	v_sub_f32_e32 v13, v13, v23
	v_sub_f32_e32 v12, v22, v12
	v_mul_f32_e32 v23, 0.5, v13
	v_mul_f32_e32 v22, 0.5, v12
	s_waitcnt lgkmcnt(0)
	v_pk_add_f32 v[12:13], v[10:11], v[24:25]
	v_sub_f32_e32 v11, v11, v25
	v_mul_f32_e32 v26, 0.5, v26
	v_mul_f32_e32 v16, 0.5, v16
	v_mul_f32_e32 v14, 0.5, v14
	v_mul_f32_e32 v12, 0.5, v12
	v_mul_f32_e32 v11, 0.5, v11
	v_sub_f32_e32 v10, v24, v10
	v_mul_f32_e32 v27, 0.5, v27
	v_mul_f32_e32 v17, 0.5, v17
	v_mul_f32_e32 v15, 0.5, v15
	v_mul_f32_e32 v25, 0.5, v13
	v_mul_f32_e32 v24, 0.5, v10
	v_cvt_pk_f16_f32 v13, v12, v11
	v_cvt_pk_f16_f32 v12, v14, v23
	v_cvt_pk_f16_f32 v11, v16, v21
	v_cvt_pk_f16_f32 v10, v26, v19
	global_store_dwordx4 v[28:29], v[10:13], off offset:2048
	v_add_u32_e32 v26, 0x1600, v146
	s_nop 0
	v_cvt_pk_f16_f32 v13, v25, v24
	v_cvt_pk_f16_f32 v12, v15, v22
	v_cvt_pk_f16_f32 v11, v17, v20
	v_cvt_pk_f16_f32 v10, v27, v18
	global_store_dwordx4 v[0:1], v[10:13], off offset:2048
	v_add_u32_e32 v27, 0x1400, v146
	s_nop 0
	v_add_u32_e32 v12, 0x200d, v71
	v_bfrev_b32_e32 v12, v12
	v_lshrrev_b32_e32 v12, 18, v12
	v_sub_u32_e32 v12, 0, v12
	v_and_b32_e32 v12, 0x17ff, v12
	v_bfrev_b32_e32 v12, v12
	v_lshrrev_b32_e32 v13, 18, v12
	v_lshrrev_b32_e32 v12, 23, v12
	v_bitop3_b32 v12, v12, v13, 31 bitop3:0x6c
	v_add_u32_e32 v13, 0x200e, v71
	v_bfrev_b32_e32 v13, v13
	v_lshrrev_b32_e32 v13, 18, v13
	v_sub_u32_e32 v13, 0, v13
	v_and_b32_e32 v13, 0x27ff, v13
	v_add_u32_e32 v10, 0x200c, v71
	v_bfrev_b32_e32 v13, v13
	v_bfrev_b32_e32 v10, v10
	v_lshrrev_b32_e32 v14, 18, v13
	v_lshrrev_b32_e32 v13, 23, v13
	v_lshrrev_b32_e32 v10, 18, v10
	v_bitop3_b32 v13, v13, v14, 31 bitop3:0x6c
	v_sub_u32_e32 v10, 0, v10
	v_lshl_add_u32 v14, v13, 3, 16
	v_add_u32_e32 v13, 0x200f, v71
	v_and_b32_e32 v10, 0x37ff, v10
	v_bfrev_b32_e32 v13, v13
	v_bfrev_b32_e32 v10, v10
	v_lshrrev_b32_e32 v13, 18, v13
	v_lshrrev_b32_e32 v11, 18, v10
	v_lshrrev_b32_e32 v10, 23, v10
	v_sub_u32_e32 v13, 0, v13
	v_bitop3_b32 v10, v10, v11, 31 bitop3:0x6c
	v_and_b32_e32 v13, 0x7ff, v13
	v_lshl_add_u32 v10, v10, 3, 16
	v_bfrev_b32_e32 v13, v13
	ds_read_b64 v[10:11], v10
	v_lshrrev_b32_e32 v15, 18, v13
	v_lshrrev_b32_e32 v13, 23, v13
	v_bitop3_b32 v13, v13, v15, 31 bitop3:0x6c
	v_lshl_add_u32 v12, v12, 3, 16
	v_lshl_add_u32 v16, v13, 3, 16
	ds_read_b64 v[12:13], v12
	ds_read_b64 v[14:15], v14
	ds_read_b64 v[16:17], v16
	s_waitcnt lgkmcnt(3)
	v_pk_add_f32 v[18:19], v[8:9], v[10:11]
	v_sub_f32_e32 v9, v9, v11
	v_sub_f32_e32 v8, v10, v8
	v_mul_f32_e32 v11, 0.5, v9
	v_mul_f32_e32 v10, 0.5, v8
	s_waitcnt lgkmcnt(2)
	v_pk_add_f32 v[8:9], v[6:7], v[12:13]
	v_sub_f32_e32 v7, v7, v13
	v_sub_f32_e32 v6, v12, v6
	v_mul_f32_e32 v13, 0.5, v7
	v_mul_f32_e32 v12, 0.5, v6
	s_waitcnt lgkmcnt(1)
	v_pk_add_f32 v[6:7], v[4:5], v[14:15]
	v_sub_f32_e32 v5, v5, v15
	v_sub_f32_e32 v4, v14, v4
	v_mul_f32_e32 v15, 0.5, v5
	v_mul_f32_e32 v14, 0.5, v4
	s_waitcnt lgkmcnt(0)
	v_pk_add_f32 v[4:5], v[2:3], v[16:17]
	v_sub_f32_e32 v3, v3, v17
	v_mul_f32_e32 v18, 0.5, v18
	v_mul_f32_e32 v8, 0.5, v8
	v_mul_f32_e32 v6, 0.5, v6
	v_mul_f32_e32 v4, 0.5, v4
	v_mul_f32_e32 v3, 0.5, v3
	v_sub_f32_e32 v2, v16, v2
	v_mul_f32_e32 v19, 0.5, v19
	v_mul_f32_e32 v9, 0.5, v9
	v_mul_f32_e32 v7, 0.5, v7
	v_mul_f32_e32 v17, 0.5, v5
	v_mul_f32_e32 v16, 0.5, v2
	v_cvt_pk_f16_f32 v5, v4, v3
	v_cvt_pk_f16_f32 v4, v6, v15
	v_cvt_pk_f16_f32 v3, v8, v13
	v_cvt_pk_f16_f32 v2, v18, v11
	global_store_dwordx4 v[28:29], v[2:5], off offset:3072
	s_nop 1
	v_cvt_pk_f16_f32 v5, v17, v16
	v_cvt_pk_f16_f32 v4, v7, v14
	v_cvt_pk_f16_f32 v3, v9, v12
	v_cvt_pk_f16_f32 v2, v19, v10
	global_store_dwordx4 v[0:1], v[2:5], off offset:3072
	global_load_dword v2, v153, s[90:91] offset:2048
	global_load_dword v0, v154, s[90:91]
	global_load_dword v6, v145, s[90:91]
	global_load_dword v4, v145, s[94:95]
	v_lshlrev_b32_e32 v8, 1, v146
	v_max_i32_e32 v12, 1, v146
	v_add_u32_e32 v13, 0x1e00, v146
	v_cmp_lt_i32_e32 vcc, 0, v146
	v_add_u32_e32 v9, 0x1000, v8
	v_add_u32_e32 v10, 0x2000, v8
	v_add_u32_e32 v11, 0x3000, v8
	v_lshlrev_b32_e32 v12, 1, v12
	v_cndmask_b32_e64 v14, 0, 1.0, vcc
	v_cmp_gt_i32_e32 vcc, 0x1fff, v13
	v_min_i32_e32 v13, 0x1ffe, v13
	v_lshlrev_b32_e32 v13, 1, v13
	s_nop 0
	v_cndmask_b32_e64 v15, 0, 1.0, vcc
	global_load_ushort v163, v12, s[12:13] offset:-2
	global_load_ushort v164, v8, s[12:13]
	global_load_ushort v165, v8, s[12:13] offset:2
	global_load_ushort v166, v12, s[14:15] offset:-2
	global_load_ushort v167, v8, s[14:15]
	global_load_ushort v168, v8, s[14:15] offset:2
	global_load_ushort v169, v8, s[12:13] offset:1022
	global_load_ushort v170, v8, s[12:13] offset:1024
	global_load_ushort v171, v8, s[12:13] offset:1026
	global_load_ushort v172, v8, s[14:15] offset:1022
	global_load_ushort v173, v8, s[14:15] offset:1024
	global_load_ushort v174, v8, s[14:15] offset:1026
	global_load_ushort v175, v8, s[12:13] offset:2046
	global_load_ushort v176, v8, s[12:13] offset:2048
	global_load_ushort v177, v8, s[12:13] offset:2050
	global_load_ushort v178, v8, s[14:15] offset:2046
	global_load_ushort v179, v8, s[14:15] offset:2048
	global_load_ushort v180, v8, s[14:15] offset:2050
	global_load_ushort v181, v8, s[12:13] offset:3070
	global_load_ushort v182, v8, s[12:13] offset:3072
	global_load_ushort v183, v8, s[12:13] offset:3074
	global_load_ushort v184, v8, s[14:15] offset:3070
	global_load_ushort v185, v8, s[14:15] offset:3072
	global_load_ushort v186, v8, s[14:15] offset:3074
	global_load_ushort v187, v9, s[12:13] offset:-2
	global_load_ushort v188, v9, s[12:13]
	global_load_ushort v189, v9, s[12:13] offset:2
	global_load_ushort v190, v9, s[14:15] offset:-2
	global_load_ushort v191, v9, s[14:15]
	global_load_ushort v192, v9, s[14:15] offset:2
	global_load_ushort v193, v9, s[12:13] offset:1022
	global_load_ushort v194, v9, s[12:13] offset:1024
	global_load_ushort v195, v9, s[12:13] offset:1026
	global_load_ushort v196, v9, s[14:15] offset:1022
	global_load_ushort v197, v9, s[14:15] offset:1024
	global_load_ushort v198, v9, s[14:15] offset:1026
	global_load_ushort v199, v9, s[12:13] offset:2046
	global_load_ushort v200, v9, s[12:13] offset:2048
	global_load_ushort v201, v9, s[12:13] offset:2050
	global_load_ushort v202, v9, s[14:15] offset:2046
	global_load_ushort v203, v9, s[14:15] offset:2048
	global_load_ushort v204, v9, s[14:15] offset:2050
	global_load_ushort v205, v9, s[12:13] offset:3070
	global_load_ushort v206, v9, s[12:13] offset:3072
	global_load_ushort v207, v9, s[12:13] offset:3074
	global_load_ushort v208, v9, s[14:15] offset:3070
	global_load_ushort v209, v9, s[14:15] offset:3072
	global_load_ushort v210, v9, s[14:15] offset:3074
	global_load_ushort v211, v10, s[12:13] offset:-2
	global_load_ushort v212, v10, s[12:13]
	global_load_ushort v213, v10, s[12:13] offset:2
	global_load_ushort v221, v10, s[14:15] offset:-2
	global_load_ushort v222, v10, s[14:15]
	global_load_ushort v223, v10, s[14:15] offset:2
	global_load_ushort v224, v10, s[12:13] offset:1022
	global_load_ushort v225, v10, s[12:13] offset:1024
	global_load_ushort v226, v10, s[12:13] offset:1026
	global_load_ushort v227, v10, s[14:15] offset:1022
	global_load_ushort v228, v10, s[14:15] offset:1024
	global_load_ushort v229, v10, s[14:15] offset:1026
	global_load_ushort v230, v10, s[12:13] offset:2046
	global_load_ushort v231, v10, s[12:13] offset:2048
	global_load_ushort v232, v10, s[12:13] offset:2050
	global_load_ushort v233, v10, s[14:15] offset:2046
	global_load_ushort v234, v10, s[14:15] offset:2048
	global_load_ushort v235, v10, s[14:15] offset:2050
	global_load_ushort v236, v10, s[12:13] offset:3070
	global_load_ushort v237, v10, s[12:13] offset:3072
	global_load_ushort v238, v10, s[12:13] offset:3074
	global_load_ushort v239, v10, s[14:15] offset:3070
	global_load_ushort v240, v10, s[14:15] offset:3072
	global_load_ushort v241, v10, s[14:15] offset:3074
	global_load_ushort v242, v11, s[12:13] offset:-2
	global_load_ushort v243, v11, s[12:13]
	global_load_ushort v244, v11, s[12:13] offset:2
	global_load_ushort v245, v11, s[14:15] offset:-2
	global_load_ushort v246, v11, s[14:15]
	global_load_ushort v247, v11, s[14:15] offset:2
	global_load_ushort v248, v11, s[12:13] offset:1022
	global_load_ushort v249, v11, s[12:13] offset:1024
	global_load_ushort v250, v11, s[12:13] offset:1026
	global_load_ushort v251, v11, s[14:15] offset:1022
	global_load_ushort v253, v11, s[14:15] offset:1024
	global_load_ushort v254, v11, s[14:15] offset:1026
	global_load_ushort v255, v11, s[12:13] offset:2046
	global_load_ushort v1, v11, s[12:13] offset:2048
	global_load_ushort v3, v11, s[12:13] offset:2050
	global_load_ushort v5, v11, s[14:15] offset:2046
	global_load_ushort v7, v11, s[14:15] offset:2048
	global_load_ushort v16, v11, s[14:15] offset:2050
	global_load_ushort v17, v11, s[12:13] offset:3070
	global_load_ushort v18, v11, s[12:13] offset:3072
	global_load_ushort v19, v13, s[12:13] offset:2
	global_load_ushort v20, v11, s[14:15] offset:3070
	global_load_ushort v21, v11, s[14:15] offset:3072
	global_load_ushort v22, v13, s[14:15] offset:2
	s_waitcnt vmcnt(48)
	v_lshlrev_b32_e32 v163, 16, v163
	v_lshlrev_b32_e32 v164, 16, v164
	v_lshlrev_b32_e32 v165, 16, v165
	v_mul_f32_e32 v163, v14, v163
	v_mul_f32_e32 v163, v6, v163
	v_fmac_f32_e32 v163, v2, v164
	v_fmac_f32_e32 v163, v0, v165
	v_add_f32_e32 v32, v4, v163
	v_lshlrev_b32_e32 v166, 16, v166
	v_lshlrev_b32_e32 v167, 16, v167
	v_lshlrev_b32_e32 v168, 16, v168
	v_mul_f32_e32 v166, v14, v166
	v_mul_f32_e32 v166, v6, v166
	v_fmac_f32_e32 v166, v2, v167
	v_fmac_f32_e32 v166, v0, v168
	v_add_f32_e32 v34, v4, v166
	v_lshlrev_b32_e32 v169, 16, v169
	v_lshlrev_b32_e32 v170, 16, v170
	v_lshlrev_b32_e32 v171, 16, v171
	v_mul_f32_e32 v169, v6, v169
	v_fmac_f32_e32 v169, v2, v170
	v_fmac_f32_e32 v169, v0, v171
	v_add_f32_e32 v33, v4, v169
	v_lshlrev_b32_e32 v172, 16, v172
	v_lshlrev_b32_e32 v173, 16, v173
	v_lshlrev_b32_e32 v174, 16, v174
	v_mul_f32_e32 v172, v6, v172
	v_fmac_f32_e32 v172, v2, v173
	v_fmac_f32_e32 v172, v0, v174
	v_add_f32_e32 v35, v4, v172
	v_lshlrev_b32_e32 v175, 16, v175
	v_lshlrev_b32_e32 v176, 16, v176
	v_lshlrev_b32_e32 v177, 16, v177
	v_mul_f32_e32 v175, v6, v175
	v_fmac_f32_e32 v175, v2, v176
	v_fmac_f32_e32 v175, v0, v177
	v_add_f32_e32 v37, v4, v175
	v_lshlrev_b32_e32 v178, 16, v178
	v_lshlrev_b32_e32 v179, 16, v179
	v_lshlrev_b32_e32 v180, 16, v180
	v_mul_f32_e32 v178, v6, v178
	v_fmac_f32_e32 v178, v2, v179
	v_fmac_f32_e32 v178, v0, v180
	v_add_f32_e32 v31, v4, v178
	v_lshlrev_b32_e32 v181, 16, v181
	v_lshlrev_b32_e32 v182, 16, v182
	v_lshlrev_b32_e32 v183, 16, v183
	v_mul_f32_e32 v181, v6, v181
	v_fmac_f32_e32 v181, v2, v182
	v_fmac_f32_e32 v181, v0, v183
	v_add_f32_e32 v36, v4, v181
	v_lshlrev_b32_e32 v184, 16, v184
	v_lshlrev_b32_e32 v185, 16, v185
	v_lshlrev_b32_e32 v186, 16, v186
	v_mul_f32_e32 v184, v6, v184
	v_fmac_f32_e32 v184, v2, v185
	v_fmac_f32_e32 v184, v0, v186
	v_add_f32_e32 v30, v4, v184
	v_lshlrev_b32_e32 v187, 16, v187
	v_lshlrev_b32_e32 v188, 16, v188
	v_lshlrev_b32_e32 v189, 16, v189
	v_mul_f32_e32 v187, v6, v187
	v_fmac_f32_e32 v187, v2, v188
	v_fmac_f32_e32 v187, v0, v189
	v_add_f32_e32 v39, v4, v187
	v_lshlrev_b32_e32 v190, 16, v190
	v_lshlrev_b32_e32 v191, 16, v191
	v_lshlrev_b32_e32 v192, 16, v192
	v_mul_f32_e32 v190, v6, v190
	v_fmac_f32_e32 v190, v2, v191
	v_fmac_f32_e32 v190, v0, v192
	v_add_f32_e32 v41, v4, v190
	v_lshlrev_b32_e32 v193, 16, v193
	v_lshlrev_b32_e32 v194, 16, v194
	v_lshlrev_b32_e32 v195, 16, v195
	v_mul_f32_e32 v193, v6, v193
	v_fmac_f32_e32 v193, v2, v194
	v_fmac_f32_e32 v193, v0, v195
	v_add_f32_e32 v38, v4, v193
	v_lshlrev_b32_e32 v196, 16, v196
	v_lshlrev_b32_e32 v197, 16, v197
	v_lshlrev_b32_e32 v198, 16, v198
	v_mul_f32_e32 v196, v6, v196
	v_fmac_f32_e32 v196, v2, v197
	v_fmac_f32_e32 v196, v0, v198
	v_add_f32_e32 v40, v4, v196
	v_lshlrev_b32_e32 v199, 16, v199
	v_lshlrev_b32_e32 v200, 16, v200
	v_lshlrev_b32_e32 v201, 16, v201
	v_mul_f32_e32 v199, v6, v199
	v_fmac_f32_e32 v199, v2, v200
	v_fmac_f32_e32 v199, v0, v201
	v_add_f32_e32 v43, v4, v199
	v_lshlrev_b32_e32 v202, 16, v202
	v_lshlrev_b32_e32 v203, 16, v203
	v_lshlrev_b32_e32 v204, 16, v204
	v_mul_f32_e32 v202, v6, v202
	v_fmac_f32_e32 v202, v2, v203
	v_fmac_f32_e32 v202, v0, v204
	v_add_f32_e32 v45, v4, v202
	v_lshlrev_b32_e32 v205, 16, v205
	v_lshlrev_b32_e32 v206, 16, v206
	v_lshlrev_b32_e32 v207, 16, v207
	v_mul_f32_e32 v205, v6, v205
	v_fmac_f32_e32 v205, v2, v206
	v_fmac_f32_e32 v205, v0, v207
	v_add_f32_e32 v42, v4, v205
	v_lshlrev_b32_e32 v208, 16, v208
	v_lshlrev_b32_e32 v209, 16, v209
	v_lshlrev_b32_e32 v210, 16, v210
	v_mul_f32_e32 v208, v6, v208
	v_fmac_f32_e32 v208, v2, v209
	v_fmac_f32_e32 v208, v0, v210
	v_add_f32_e32 v44, v4, v208
	s_waitcnt vmcnt(0)
	v_lshlrev_b32_e32 v211, 16, v211
	v_lshlrev_b32_e32 v212, 16, v212
	v_lshlrev_b32_e32 v213, 16, v213
	v_mul_f32_e32 v211, v6, v211
	v_fmac_f32_e32 v211, v2, v212
	v_fmac_f32_e32 v211, v0, v213
	v_add_f32_e32 v47, v4, v211
	v_lshlrev_b32_e32 v221, 16, v221
	v_lshlrev_b32_e32 v222, 16, v222
	v_lshlrev_b32_e32 v223, 16, v223
	v_mul_f32_e32 v221, v6, v221
	v_fmac_f32_e32 v221, v2, v222
	v_fmac_f32_e32 v221, v0, v223
	v_add_f32_e32 v49, v4, v221
	v_lshlrev_b32_e32 v224, 16, v224
	v_lshlrev_b32_e32 v225, 16, v225
	v_lshlrev_b32_e32 v226, 16, v226
	v_mul_f32_e32 v224, v6, v224
	v_fmac_f32_e32 v224, v2, v225
	v_fmac_f32_e32 v224, v0, v226
	v_add_f32_e32 v46, v4, v224
	v_lshlrev_b32_e32 v227, 16, v227
	v_lshlrev_b32_e32 v228, 16, v228
	v_lshlrev_b32_e32 v229, 16, v229
	v_mul_f32_e32 v227, v6, v227
	v_fmac_f32_e32 v227, v2, v228
	v_fmac_f32_e32 v227, v0, v229
	v_add_f32_e32 v48, v4, v227
	v_lshlrev_b32_e32 v230, 16, v230
	v_lshlrev_b32_e32 v231, 16, v231
	v_lshlrev_b32_e32 v232, 16, v232
	v_mul_f32_e32 v230, v6, v230
	v_fmac_f32_e32 v230, v2, v231
	v_fmac_f32_e32 v230, v0, v232
	v_add_f32_e32 v51, v4, v230
	v_lshlrev_b32_e32 v233, 16, v233
	v_lshlrev_b32_e32 v234, 16, v234
	v_lshlrev_b32_e32 v235, 16, v235
	v_mul_f32_e32 v233, v6, v233
	v_fmac_f32_e32 v233, v2, v234
	v_fmac_f32_e32 v233, v0, v235
	v_add_f32_e32 v53, v4, v233
	v_lshlrev_b32_e32 v236, 16, v236
	v_lshlrev_b32_e32 v237, 16, v237
	v_lshlrev_b32_e32 v238, 16, v238
	v_mul_f32_e32 v236, v6, v236
	v_fmac_f32_e32 v236, v2, v237
	v_fmac_f32_e32 v236, v0, v238
	v_add_f32_e32 v50, v4, v236
	v_lshlrev_b32_e32 v239, 16, v239
	v_lshlrev_b32_e32 v240, 16, v240
	v_lshlrev_b32_e32 v241, 16, v241
	v_mul_f32_e32 v239, v6, v239
	v_fmac_f32_e32 v239, v2, v240
	v_fmac_f32_e32 v239, v0, v241
	v_add_f32_e32 v52, v4, v239
	v_lshlrev_b32_e32 v242, 16, v242
	v_lshlrev_b32_e32 v243, 16, v243
	v_lshlrev_b32_e32 v244, 16, v244
	v_mul_f32_e32 v242, v6, v242
	v_fmac_f32_e32 v242, v2, v243
	v_fmac_f32_e32 v242, v0, v244
	v_add_f32_e32 v55, v4, v242
	v_lshlrev_b32_e32 v245, 16, v245
	v_lshlrev_b32_e32 v246, 16, v246
	v_lshlrev_b32_e32 v247, 16, v247
	v_mul_f32_e32 v245, v6, v245
	v_fmac_f32_e32 v245, v2, v246
	v_fmac_f32_e32 v245, v0, v247
	v_add_f32_e32 v57, v4, v245
	v_lshlrev_b32_e32 v248, 16, v248
	v_lshlrev_b32_e32 v249, 16, v249
	v_lshlrev_b32_e32 v250, 16, v250
	v_mul_f32_e32 v248, v6, v248
	v_fmac_f32_e32 v248, v2, v249
	v_fmac_f32_e32 v248, v0, v250
	v_add_f32_e32 v54, v4, v248
	v_lshlrev_b32_e32 v251, 16, v251
	v_lshlrev_b32_e32 v253, 16, v253
	v_lshlrev_b32_e32 v254, 16, v254
	v_mul_f32_e32 v251, v6, v251
	v_fmac_f32_e32 v251, v2, v253
	v_fmac_f32_e32 v251, v0, v254
	v_add_f32_e32 v56, v4, v251
	v_lshlrev_b32_e32 v255, 16, v255
	v_lshlrev_b32_e32 v1, 16, v1
	v_lshlrev_b32_e32 v3, 16, v3
	v_mul_f32_e32 v255, v6, v255
	v_fmac_f32_e32 v255, v2, v1
	v_fmac_f32_e32 v255, v0, v3
	v_add_f32_e32 v59, v4, v255
	v_lshlrev_b32_e32 v5, 16, v5
	v_lshlrev_b32_e32 v7, 16, v7
	v_lshlrev_b32_e32 v16, 16, v16
	v_mul_f32_e32 v5, v6, v5
	v_fmac_f32_e32 v5, v2, v7
	v_fmac_f32_e32 v5, v0, v16
	v_add_f32_e32 v61, v4, v5
	v_lshlrev_b32_e32 v17, 16, v17
	v_lshlrev_b32_e32 v18, 16, v18
	v_lshlrev_b32_e32 v19, 16, v19
	v_mul_f32_e32 v19, v15, v19
	v_mul_f32_e32 v17, v6, v17
	v_fmac_f32_e32 v17, v2, v18
	v_fmac_f32_e32 v17, v0, v19
	v_add_f32_e32 v58, v4, v17
	v_lshlrev_b32_e32 v20, 16, v20
	v_lshlrev_b32_e32 v21, 16, v21
	v_lshlrev_b32_e32 v22, 16, v22
	v_mul_f32_e32 v22, v15, v22
	v_mul_f32_e32 v20, v6, v20
	v_fmac_f32_e32 v20, v2, v21
	v_fmac_f32_e32 v20, v0, v22
	v_add_f32_e32 v60, v4, v20
	v_readlane_b32 s72, v252, 22
	v_readlane_b32 s78, v252, 28
	v_readlane_b32 s79, v252, 29
	s_add_u32 s24, s78, s10
	s_addc_u32 s59, s79, s11
	s_lshl_b64 s[0:1], s[68:69], 1
	v_readlane_b32 s4, v252, 50
	v_readlane_b32 s73, v252, 23
	v_readlane_b32 s74, v252, 24
	v_readlane_b32 s75, v252, 25
	v_readlane_b32 s76, v252, 26
	v_readlane_b32 s77, v252, 27
	v_readlane_b32 s80, v252, 30
	v_readlane_b32 s81, v252, 31
	v_readlane_b32 s82, v252, 32
	v_readlane_b32 s83, v252, 33
	s_add_u32 s96, s4, s0
	v_readlane_b32 s0, v252, 51
	s_movk_i32 s83, 0xea00
	s_movk_i32 s82, 0xdff
	s_movk_i32 s81, 0xee00
	s_movk_i32 s80, 0x13ff
	s_movk_i32 s77, 0xf200
	s_movk_i32 s76, 0x7ff
	s_movk_i32 s73, 0xf000
	s_movk_i32 s72, 0x1ff
	s_movk_i32 s75, 0xfff
	s_movk_i32 s74, 0x1fff
	s_movk_i32 s78, 0xf400
	s_movk_i32 s79, 0x11ff
	s_movk_i32 s69, 0xec00
	s_addc_u32 s97, s0, s1
	s_mov_b64 s[14:15], -1
	v_readlane_b32 s84, v252, 34
	v_readlane_b32 s85, v252, 35
	v_readlane_b32 s86, v252, 36
	v_readlane_b32 s87, v252, 37
	s_branch .LBB0_538

.LBB0_538:
	s_lshl_b32 s98, s16, 16
	s_mov_b32 s99, 0
	v_lshl_add_u64 v[196:197], s[98:99], 0, v[28:29]
	global_load_dwordx4 v[164:167], v[196:197], off offset:-4096
	global_load_dwordx4 v[168:171], v[196:197], off offset:-3072
	global_load_dwordx4 v[172:175], v[196:197], off offset:-2048
	global_load_dwordx4 v[176:179], v[196:197], off offset:-1024
	global_load_dwordx4 v[180:183], v[196:197], off
	global_load_dwordx4 v[184:187], v[196:197], off offset:1024
	global_load_dwordx4 v[188:191], v[196:197], off offset:2048
	global_load_dwordx4 v[192:195], v[196:197], off offset:3072
	v_mov_b32_e32 v20, v46
	v_mov_b32_e32 v21, v48
	v_mov_b32_e32 v22, v51
	v_mov_b32_e32 v23, v53
	v_pk_add_f32 v[88:89], v[20:21], 0 op_sel_hi:[1,0]
	v_pk_mul_f32 v[20:21], v[20:21], s[58:59] op_sel_hi:[1,0]
	v_xor_b32_e32 v91, 0x80000000, v46
	v_mov_b32_e32 v90, v48
	v_pk_add_f32 v[92:93], v[50:51], 0 neg_lo:[1,1] neg_hi:[1,1]
	v_mov_b32_e32 v24, v50
	v_mov_b32_e32 v25, v52
	v_pk_fma_f32 v[20:21], v[90:91], s[46:47], v[20:21] op_sel_hi:[1,0,1] neg_lo:[0,0,1] neg_hi:[0,0,1]
	v_pk_add_f32 v[90:91], v[22:23], 0 op_sel_hi:[1,0]
	v_pk_mul_f32 v[22:23], v[22:23], s[62:63] op_sel_hi:[1,0]
	v_mov_b32_e32 v92, v53
	v_mov_b32_e32 v26, v55
	v_mov_b32_e32 v27, v57
	v_pk_fma_f32 v[22:23], v[92:93], s[60:61], v[22:23] op_sel_hi:[1,0,1] neg_lo:[0,0,1] neg_hi:[0,0,1]
	v_pk_add_f32 v[92:93], v[24:25], 0 op_sel_hi:[1,0]
	v_pk_mul_f32 v[24:25], v[24:25], s[66:67] op_sel_hi:[1,0]
	v_xor_b32_e32 v95, 0x80000000, v50
	v_mov_b32_e32 v94, v52
	v_pk_add_f32 v[96:97], v[54:55], 0 neg_lo:[1,1] neg_hi:[1,1]
	v_mov_b32_e32 v64, v54
	v_mov_b32_e32 v65, v56
	v_pk_fma_f32 v[24:25], v[94:95], s[64:65], v[24:25] op_sel_hi:[1,0,1] neg_lo:[0,0,1] neg_hi:[0,0,1]
	v_pk_add_f32 v[94:95], v[26:27], 0 op_sel_hi:[1,0]
	v_pk_mul_f32 v[26:27], v[26:27], s[70:71] op_sel_hi:[1,0]
	v_mov_b32_e32 v96, v57
	v_mov_b32_e32 v66, v59
	v_mov_b32_e32 v67, v61
	v_pk_fma_f32 v[26:27], v[96:97], s[70:71], v[26:27] op_sel_hi:[1,0,1] neg_lo:[0,0,1] neg_hi:[0,0,1]
	v_pk_add_f32 v[96:97], v[64:65], 0 op_sel_hi:[1,0]
	v_pk_mul_f32 v[64:65], v[64:65], s[64:65] op_sel_hi:[1,0]
	v_xor_b32_e32 v99, 0x80000000, v54
	v_mov_b32_e32 v98, v56
	v_pk_add_f32 v[100:101], v[58:59], 0 neg_lo:[1,1] neg_hi:[1,1]
	v_mov_b32_e32 v2, v32
	v_mov_b32_e32 v3, v34
	v_mov_b32_e32 v4, v33
	v_mov_b32_e32 v5, v35
	v_mov_b32_e32 v18, v47
	v_mov_b32_e32 v19, v49
	v_mov_b32_e32 v68, v58
	v_mov_b32_e32 v69, v60
	v_pk_fma_f32 v[64:65], v[98:99], s[66:67], v[64:65] op_sel_hi:[1,0,1] neg_lo:[0,0,1] neg_hi:[0,0,1]
	v_pk_add_f32 v[98:99], v[66:67], 0 op_sel_hi:[1,0]
	v_pk_mul_f32 v[66:67], v[66:67], s[60:61] op_sel_hi:[1,0]
	v_mov_b32_e32 v100, v61
	v_pk_add_f32 v[70:71], v[2:3], 0 op_sel_hi:[1,0]
	v_pk_add_f32 v[72:73], v[4:5], 0 op_sel_hi:[1,0]
	v_pk_add_f32 v[74:75], v[32:33], 0 neg_lo:[1,1] neg_hi:[1,1]
	v_pk_add_f32 v[18:19], v[18:19], 0 op_sel_hi:[1,0]
	v_pk_fma_f32 v[66:67], v[100:101], s[62:63], v[66:67] op_sel_hi:[1,0,1] neg_lo:[0,0,1] neg_hi:[0,0,1]
	v_pk_add_f32 v[100:101], v[68:69], 0 op_sel_hi:[1,0]
	v_pk_mul_f32 v[68:69], v[68:69], s[46:47] op_sel_hi:[1,0]
	v_xor_b32_e32 v103, 0x80000000, v58
	v_mov_b32_e32 v102, v60
	v_mov_b32_e32 v74, v35
	v_pk_fma_f32 v[68:69], v[102:103], s[58:59], v[68:69] op_sel_hi:[1,0,1] neg_lo:[0,0,1] neg_hi:[0,0,1]
	v_pk_add_f32 v[102:103], v[18:19], v[70:71]
	v_pk_add_f32 v[18:19], v[70:71], v[18:19] neg_lo:[0,1] neg_hi:[0,1]
	v_pk_add_f32 v[70:71], v[88:89], v[72:73]
	v_pk_add_f32 v[72:73], v[72:73], v[88:89] neg_lo:[0,1] neg_hi:[0,1]
	v_mov_b32_e32 v6, v37
	v_mov_b32_e32 v7, v31
	v_pk_mul_f32 v[74:75], v[74:75], s[58:59] op_sel_hi:[1,0]
	s_nop 0
	v_pk_fma_f32 v[4:5], v[4:5], s[46:47], v[74:75] op_sel_hi:[1,0,1]
	v_pk_add_f32 v[74:75], v[6:7], 0 op_sel_hi:[1,0]
	v_pk_add_f32 v[76:77], v[36:37], 0 neg_lo:[1,1] neg_hi:[1,1]
	v_pk_mul_f32 v[88:89], v[72:73], s[62:63] op_sel:[1,0] op_sel_hi:[0,0] neg_hi:[1,0]
	v_mov_b32_e32 v76, v31
	v_pk_fma_f32 v[72:73], v[72:73], s[60:61], v[88:89] op_sel_hi:[1,0,1]
	v_pk_add_f32 v[88:89], v[90:91], v[74:75]
	v_pk_add_f32 v[74:75], v[74:75], v[90:91] neg_lo:[0,1] neg_hi:[0,1]
	v_mov_b32_e32 v8, v36
	v_mov_b32_e32 v9, v30
	v_pk_mul_f32 v[76:77], v[76:77], s[62:63] op_sel_hi:[1,0]
	s_nop 0
	v_pk_fma_f32 v[6:7], v[6:7], s[60:61], v[76:77] op_sel_hi:[1,0,1]
	v_pk_add_f32 v[76:77], v[8:9], 0 op_sel_hi:[1,0]
	v_pk_mul_f32 v[90:91], v[74:75], s[70:71] op_sel:[1,0] op_sel_hi:[0,0] neg_hi:[1,0]
	v_xor_b32_e32 v79, 0x80000000, v36
	v_mov_b32_e32 v78, v30
	v_pk_add_f32 v[80:81], v[38:39], 0 neg_lo:[1,1] neg_hi:[1,1]
	v_pk_fma_f32 v[74:75], v[74:75], s[70:71], v[90:91] op_sel_hi:[1,0,1]
	v_pk_add_f32 v[90:91], v[92:93], v[76:77]
	v_pk_add_f32 v[76:77], v[76:77], v[92:93] neg_lo:[0,1] neg_hi:[0,1]
	v_mov_b32_e32 v10, v39
	v_mov_b32_e32 v11, v41
	v_pk_mul_f32 v[78:79], v[78:79], s[66:67] op_sel_hi:[1,0]
	v_mov_b32_e32 v80, v41
	v_mov_b32_e32 v12, v38
	v_mov_b32_e32 v13, v40
	v_pk_fma_f32 v[8:9], v[8:9], s[64:65], v[78:79] op_sel_hi:[1,0,1]
	v_pk_add_f32 v[78:79], v[10:11], 0 op_sel_hi:[1,0]
	v_pk_mul_f32 v[80:81], v[80:81], s[70:71] op_sel_hi:[1,0]
	v_pk_mul_f32 v[92:93], v[76:77], s[60:61] op_sel:[1,0] op_sel_hi:[0,0] neg_hi:[1,0]
	v_pk_fma_f32 v[10:11], v[10:11], s[70:71], v[80:81] op_sel_hi:[1,0,1]
	v_pk_add_f32 v[80:81], v[12:13], 0 op_sel_hi:[1,0]
	v_xor_b32_e32 v83, 0x80000000, v38
	v_mov_b32_e32 v82, v40
	v_pk_fma_f32 v[76:77], v[76:77], s[62:63], v[92:93] op_sel_hi:[1,0,1]
	v_pk_add_f32 v[92:93], v[94:95], v[78:79]
	v_pk_add_f32 v[78:79], v[78:79], v[94:95] neg_lo:[0,1] neg_hi:[0,1]
	v_mov_b32_e32 v14, v43
	v_mov_b32_e32 v15, v45
	v_pk_mul_f32 v[82:83], v[82:83], s[64:65] op_sel_hi:[1,0]
	v_pk_add_f32 v[84:85], v[42:43], 0 neg_lo:[1,1] neg_hi:[1,1]
	v_xor_b32_e32 v95, 0x80000000, v78
	v_mov_b32_e32 v94, v79
	v_pk_add_f32 v[78:79], v[96:97], v[80:81]
	v_pk_add_f32 v[80:81], v[80:81], v[96:97] neg_lo:[0,1] neg_hi:[0,1]
	v_pk_fma_f32 v[12:13], v[12:13], s[66:67], v[82:83] op_sel_hi:[1,0,1]
	v_pk_add_f32 v[82:83], v[14:15], 0 op_sel_hi:[1,0]
	v_mov_b32_e32 v84, v45
	v_pk_mul_f32 v[96:97], v[80:81], s[62:63] op_sel_hi:[1,0]
	v_xor_b32_e32 v105, 0x80000000, v80
	v_mov_b32_e32 v104, v81
	v_mov_b32_e32 v16, v42
	v_mov_b32_e32 v17, v44
	v_pk_mul_f32 v[84:85], v[84:85], s[60:61] op_sel_hi:[1,0]
	v_xor_b32_e32 v87, 0x80000000, v42
	v_mov_b32_e32 v86, v44
	v_pk_fma_f32 v[80:81], v[104:105], s[60:61], v[96:97] op_sel_hi:[1,0,1] neg_lo:[0,0,1] neg_hi:[0,0,1]
	v_pk_add_f32 v[96:97], v[98:99], v[82:83]
	v_pk_add_f32 v[82:83], v[82:83], v[98:99] neg_lo:[0,1] neg_hi:[0,1]
	v_pk_fma_f32 v[14:15], v[14:15], s[62:63], v[84:85] op_sel_hi:[1,0,1]
	v_pk_add_f32 v[84:85], v[16:17], 0 op_sel_hi:[1,0]
	v_pk_mul_f32 v[86:87], v[86:87], s[46:47] op_sel_hi:[1,0]
	v_pk_mul_f32 v[98:99], v[82:83], s[70:71] op_sel_hi:[1,0]
	v_xor_b32_e32 v105, 0x80000000, v82
	v_mov_b32_e32 v104, v83
	v_pk_fma_f32 v[16:17], v[16:17], s[58:59], v[86:87] op_sel_hi:[1,0,1]
	v_pk_add_f32 v[86:87], v[46:47], 0 neg_lo:[1,1] neg_hi:[1,1]
	v_pk_fma_f32 v[82:83], v[104:105], s[70:71], v[98:99] op_sel_hi:[1,0,1] neg_lo:[0,0,1] neg_hi:[0,0,1]
	v_pk_add_f32 v[98:99], v[100:101], v[84:85]
	v_pk_add_f32 v[84:85], v[84:85], v[100:101] neg_lo:[0,1] neg_hi:[0,1]
	v_mov_b32_e32 v86, v49
	v_pk_mul_f32 v[100:101], v[84:85], s[60:61] op_sel_hi:[1,0]
	v_xor_b32_e32 v105, 0x80000000, v84
	v_mov_b32_e32 v104, v85
	v_pk_fma_f32 v[84:85], v[104:105], s[62:63], v[100:101] op_sel_hi:[1,0,1] neg_lo:[0,0,1] neg_hi:[0,0,1]
	v_pk_add_f32 v[100:101], v[86:87], v[2:3]
	v_pk_add_f32 v[2:3], v[2:3], v[86:87] neg_lo:[0,1] neg_hi:[0,1]
	v_pk_add_f32 v[86:87], v[20:21], v[4:5]
	v_pk_add_f32 v[4:5], v[4:5], v[20:21] neg_lo:[0,1] neg_hi:[0,1]
	v_mov_b32_e32 v63, v146
	v_pk_mul_f32 v[20:21], v[4:5], s[62:63] op_sel:[1,0] op_sel_hi:[0,0] neg_hi:[1,0]
	s_nop 0
	v_pk_fma_f32 v[4:5], v[4:5], s[60:61], v[20:21] op_sel_hi:[1,0,1]
	v_pk_add_f32 v[20:21], v[22:23], v[6:7]
	v_pk_add_f32 v[6:7], v[6:7], v[22:23] neg_lo:[0,1] neg_hi:[0,1]
	s_barrier
	v_pk_mul_f32 v[22:23], v[6:7], s[70:71] op_sel:[1,0] op_sel_hi:[0,0] neg_hi:[1,0]
	s_nop 0
	v_pk_fma_f32 v[6:7], v[6:7], s[70:71], v[22:23] op_sel_hi:[1,0,1]
	v_pk_add_f32 v[22:23], v[24:25], v[8:9]
	v_pk_add_f32 v[8:9], v[8:9], v[24:25] neg_lo:[0,1] neg_hi:[0,1]
	s_add_i32 s19, 16, 0x11000
	v_pk_mul_f32 v[24:25], v[8:9], s[60:61] op_sel:[1,0] op_sel_hi:[0,0] neg_hi:[1,0]
	s_add_i32 s18, 16, 0x12000
	v_pk_fma_f32 v[8:9], v[8:9], s[62:63], v[24:25] op_sel_hi:[1,0,1]
	v_pk_add_f32 v[24:25], v[26:27], v[10:11]
	v_pk_add_f32 v[10:11], v[10:11], v[26:27] neg_lo:[0,1] neg_hi:[0,1]
	s_add_i32 s17, 16, 0x13000
	v_xor_b32_e32 v27, 0x80000000, v10
	v_mov_b32_e32 v26, v11
	v_pk_add_f32 v[10:11], v[64:65], v[12:13]
	v_pk_add_f32 v[12:13], v[12:13], v[64:65] neg_lo:[0,1] neg_hi:[0,1]
	s_add_i32 s13, 16, 0x14000
	v_pk_mul_f32 v[64:65], v[12:13], s[62:63] op_sel_hi:[1,0]
	v_xor_b32_e32 v105, 0x80000000, v12
	v_mov_b32_e32 v104, v13
	v_pk_fma_f32 v[12:13], v[104:105], s[60:61], v[64:65] op_sel_hi:[1,0,1] neg_lo:[0,0,1] neg_hi:[0,0,1]
	v_pk_add_f32 v[64:65], v[66:67], v[14:15]
	v_pk_add_f32 v[14:15], v[14:15], v[66:67] neg_lo:[0,1] neg_hi:[0,1]
	s_add_i32 s12, 16, 0x15000
	v_pk_mul_f32 v[66:67], v[14:15], s[70:71] op_sel_hi:[1,0]
	v_xor_b32_e32 v105, 0x80000000, v14
	v_mov_b32_e32 v104, v15
	v_pk_fma_f32 v[14:15], v[104:105], s[70:71], v[66:67] op_sel_hi:[1,0,1] neg_lo:[0,0,1] neg_hi:[0,0,1]
	v_pk_add_f32 v[66:67], v[68:69], v[16:17]
	v_pk_add_f32 v[16:17], v[16:17], v[68:69] neg_lo:[0,1] neg_hi:[0,1]
	s_add_i32 s11, 16, 0x16000
	v_pk_mul_f32 v[68:69], v[16:17], s[60:61] op_sel_hi:[1,0]
	v_xor_b32_e32 v105, 0x80000000, v16
	v_mov_b32_e32 v104, v17
	v_pk_fma_f32 v[16:17], v[104:105], s[62:63], v[68:69] op_sel_hi:[1,0,1] neg_lo:[0,0,1] neg_hi:[0,0,1]
	v_pk_add_f32 v[68:69], v[92:93], v[102:103]
	v_pk_add_f32 v[92:93], v[102:103], v[92:93] neg_lo:[0,1] neg_hi:[0,1]
	v_pk_add_f32 v[102:103], v[78:79], v[70:71]
	v_pk_add_f32 v[70:71], v[70:71], v[78:79] neg_lo:[0,1] neg_hi:[0,1]
	s_add_i32 s10, 16, 0x17000
	v_pk_mul_f32 v[78:79], v[70:71], s[70:71] op_sel:[1,0] op_sel_hi:[0,0] neg_hi:[1,0]
	s_add_i32 s9, 16, 0x18000
	v_pk_fma_f32 v[70:71], v[70:71], s[70:71], v[78:79] op_sel_hi:[1,0,1]
	v_pk_add_f32 v[78:79], v[96:97], v[88:89]
	v_pk_add_f32 v[88:89], v[88:89], v[96:97] neg_lo:[0,1] neg_hi:[0,1]
	s_add_i32 s8, 16, 0x19000
	v_xor_b32_e32 v97, 0x80000000, v88
	v_mov_b32_e32 v96, v89
	v_pk_add_f32 v[88:89], v[98:99], v[90:91]
	v_pk_add_f32 v[90:91], v[90:91], v[98:99] neg_lo:[0,1] neg_hi:[0,1]
	s_add_i32 s7, 16, 0x1a000
	v_pk_mul_f32 v[98:99], v[90:91], s[70:71] op_sel_hi:[1,0]
	v_xor_b32_e32 v105, 0x80000000, v90
	v_mov_b32_e32 v104, v91
	v_pk_fma_f32 v[90:91], v[104:105], s[70:71], v[98:99] op_sel_hi:[1,0,1] neg_lo:[0,0,1] neg_hi:[0,0,1]
	v_pk_add_f32 v[98:99], v[94:95], v[18:19]
	v_pk_add_f32 v[18:19], v[18:19], v[94:95] neg_lo:[0,1] neg_hi:[0,1]
	v_pk_add_f32 v[94:95], v[80:81], v[72:73]
	v_pk_add_f32 v[72:73], v[72:73], v[80:81] neg_lo:[0,1] neg_hi:[0,1]
	s_add_i32 s6, 16, 0x1b000
	v_pk_mul_f32 v[80:81], v[72:73], s[70:71] op_sel:[1,0] op_sel_hi:[0,0] neg_hi:[1,0]
	s_add_i32 s5, 16, 0x1c000
	v_pk_fma_f32 v[72:73], v[72:73], s[70:71], v[80:81] op_sel_hi:[1,0,1]
	v_pk_add_f32 v[80:81], v[82:83], v[74:75]
	v_pk_add_f32 v[74:75], v[74:75], v[82:83] neg_lo:[0,1] neg_hi:[0,1]
	s_add_i32 s4, 16, 0x1d000
	v_xor_b32_e32 v83, 0x80000000, v74
	v_mov_b32_e32 v82, v75
	v_pk_add_f32 v[74:75], v[84:85], v[76:77]
	v_pk_add_f32 v[76:77], v[76:77], v[84:85] neg_lo:[0,1] neg_hi:[0,1]
	v_pk_add_f32 v[106:107], v[18:19], v[82:83]
	v_pk_mul_f32 v[84:85], v[76:77], s[70:71] op_sel_hi:[1,0]
	v_xor_b32_e32 v105, 0x80000000, v76
	v_mov_b32_e32 v104, v77
	v_pk_fma_f32 v[76:77], v[104:105], s[70:71], v[84:85] op_sel_hi:[1,0,1] neg_lo:[0,0,1] neg_hi:[0,0,1]
	v_pk_add_f32 v[84:85], v[24:25], v[100:101]
	v_pk_add_f32 v[24:25], v[100:101], v[24:25] neg_lo:[0,1] neg_hi:[0,1]
	v_pk_add_f32 v[100:101], v[10:11], v[86:87]
	v_pk_add_f32 v[10:11], v[86:87], v[10:11] neg_lo:[0,1] neg_hi:[0,1]
	v_pk_add_f32 v[18:19], v[18:19], v[82:83] neg_lo:[0,1] neg_hi:[0,1]
	v_pk_mul_f32 v[86:87], v[10:11], s[70:71] op_sel:[1,0] op_sel_hi:[0,0] neg_hi:[1,0]
	v_pk_add_f32 v[82:83], v[76:77], v[72:73]
	v_pk_fma_f32 v[10:11], v[10:11], s[70:71], v[86:87] op_sel_hi:[1,0,1]
	v_pk_add_f32 v[86:87], v[64:65], v[20:21]
	v_pk_add_f32 v[20:21], v[20:21], v[64:65] neg_lo:[0,1] neg_hi:[0,1]
	v_pk_add_f32 v[72:73], v[72:73], v[76:77] neg_lo:[0,1] neg_hi:[0,1]
	v_xor_b32_e32 v65, 0x80000000, v20
	v_mov_b32_e32 v64, v21
	v_pk_add_f32 v[20:21], v[66:67], v[22:23]
	v_pk_add_f32 v[22:23], v[22:23], v[66:67] neg_lo:[0,1] neg_hi:[0,1]
	v_xor_b32_e32 v77, 0x80000000, v72
	v_pk_mul_f32 v[66:67], v[22:23], s[70:71] op_sel_hi:[1,0]
	v_xor_b32_e32 v105, 0x80000000, v22
	v_mov_b32_e32 v104, v23
	v_pk_fma_f32 v[22:23], v[104:105], s[70:71], v[66:67] op_sel_hi:[1,0,1] neg_lo:[0,0,1] neg_hi:[0,0,1]
	v_pk_add_f32 v[66:67], v[2:3], v[26:27]
	v_pk_add_f32 v[2:3], v[2:3], v[26:27] neg_lo:[0,1] neg_hi:[0,1]
	v_pk_add_f32 v[26:27], v[12:13], v[4:5]
	v_pk_add_f32 v[4:5], v[4:5], v[12:13] neg_lo:[0,1] neg_hi:[0,1]
	v_mov_b32_e32 v76, v73
	v_pk_mul_f32 v[12:13], v[4:5], s[70:71] op_sel:[1,0] op_sel_hi:[0,0] neg_hi:[1,0]
	v_pk_add_f32 v[72:73], v[84:85], v[86:87]
	v_pk_fma_f32 v[4:5], v[4:5], s[70:71], v[12:13] op_sel_hi:[1,0,1]
	v_pk_add_f32 v[12:13], v[14:15], v[6:7]
	v_pk_add_f32 v[6:7], v[6:7], v[14:15] neg_lo:[0,1] neg_hi:[0,1]
	v_pk_add_f32 v[84:85], v[84:85], v[86:87] neg_lo:[0,1] neg_hi:[0,1]
	v_xor_b32_e32 v15, 0x80000000, v6
	v_mov_b32_e32 v14, v7
	v_pk_add_f32 v[6:7], v[16:17], v[8:9]
	v_pk_add_f32 v[8:9], v[8:9], v[16:17] neg_lo:[0,1] neg_hi:[0,1]
	v_pk_add_f32 v[86:87], v[20:21], v[100:101]
	v_pk_mul_f32 v[16:17], v[8:9], s[70:71] op_sel_hi:[1,0]
	s_nop 0
	v_pk_fma_f32 v[8:9], v[8:9], s[70:71], v[16:17] op_sel:[1,0,0] op_sel_hi:[0,0,1] neg_lo:[0,0,1] neg_hi:[1,0,1]
	v_pk_add_f32 v[104:105], v[92:93], v[96:97]
	v_pk_add_f32 v[92:93], v[92:93], v[96:97] neg_lo:[0,1] neg_hi:[0,1]
	v_pk_add_f32 v[96:97], v[90:91], v[70:71]
	v_pk_add_f32 v[70:71], v[70:71], v[90:91] neg_lo:[0,1] neg_hi:[0,1]
	v_pk_add_f32 v[16:17], v[78:79], v[68:69]
	v_pk_add_f32 v[68:69], v[68:69], v[78:79] neg_lo:[0,1] neg_hi:[0,1]
	v_pk_add_f32 v[78:79], v[88:89], v[102:103]
	v_pk_add_f32 v[88:89], v[102:103], v[88:89] neg_lo:[0,1] neg_hi:[0,1]
	v_xor_b32_e32 v91, 0x80000000, v70
	v_mov_b32_e32 v90, v71
	v_pk_add_f32 v[70:71], v[98:99], v[80:81]
	v_pk_add_f32 v[98:99], v[98:99], v[80:81] neg_lo:[0,1] neg_hi:[0,1]
	v_pk_add_f32 v[80:81], v[74:75], v[94:95]
	v_pk_add_f32 v[74:75], v[94:95], v[74:75] neg_lo:[0,1] neg_hi:[0,1]
	v_pk_add_f32 v[20:21], v[100:101], v[20:21] neg_lo:[0,1] neg_hi:[0,1]
	v_pk_add_f32 v[108:109], v[24:25], v[64:65]
	v_pk_add_f32 v[24:25], v[24:25], v[64:65] neg_lo:[0,1] neg_hi:[0,1]
	v_pk_add_f32 v[64:65], v[22:23], v[10:11]
	v_pk_add_f32 v[10:11], v[10:11], v[22:23] neg_lo:[0,1] neg_hi:[0,1]
	v_pk_add_f32 v[114:115], v[6:7], v[26:27]
	v_pk_add_f32 v[6:7], v[26:27], v[6:7] neg_lo:[0,1] neg_hi:[0,1]
	v_xor_b32_e32 v103, 0x80000000, v88
	v_mov_b32_e32 v102, v89
	v_xor_b32_e32 v95, 0x80000000, v74
	v_mov_b32_e32 v94, v75
	v_xor_b32_e32 v101, 0x80000000, v20
	v_mov_b32_e32 v100, v21
	v_xor_b32_e32 v27, 0x80000000, v6
	v_mov_b32_e32 v26, v7
	v_pk_add_f32 v[6:7], v[2:3], v[14:15]
	v_pk_add_f32 v[116:117], v[2:3], v[14:15] neg_lo:[0,1] neg_hi:[0,1]
	v_pk_add_f32 v[2:3], v[4:5], v[8:9] neg_lo:[0,1] neg_hi:[0,1]
	v_pk_add_f32 v[112:113], v[66:67], v[12:13]
	v_pk_add_f32 v[66:67], v[66:67], v[12:13] neg_lo:[0,1] neg_hi:[0,1]
	v_pk_add_f32 v[118:119], v[8:9], v[4:5]
	v_xor_b32_e32 v121, 0x80000000, v2
	v_mov_b32_e32 v120, v3
	v_pk_add_f32 v[2:3], v[78:79], v[16:17]
	v_pk_add_f32 v[88:89], v[16:17], v[78:79] neg_lo:[0,1] neg_hi:[0,1]
	v_pk_add_f32 v[122:123], v[68:69], v[102:103]
	v_pk_add_f32 v[20:21], v[68:69], v[102:103] neg_lo:[0,1] neg_hi:[0,1]
	v_pk_add_f32 v[78:79], v[104:105], v[96:97]
	v_pk_add_f32 v[74:75], v[104:105], v[96:97] neg_lo:[0,1] neg_hi:[0,1]
	v_pk_add_f32 v[96:97], v[92:93], v[90:91]
	v_pk_add_f32 v[8:9], v[92:93], v[90:91] neg_lo:[0,1] neg_hi:[0,1]
	v_pk_add_f32 v[102:103], v[98:99], v[94:95]
	v_pk_add_f32 v[12:13], v[98:99], v[94:95] neg_lo:[0,1] neg_hi:[0,1]
	v_pk_add_f32 v[98:99], v[18:19], v[76:77]
	v_pk_add_f32 v[4:5], v[18:19], v[76:77] neg_lo:[0,1] neg_hi:[0,1]
	v_pk_add_f32 v[18:19], v[72:73], v[86:87]
	v_pk_add_f32 v[92:93], v[72:73], v[86:87] neg_lo:[0,1] neg_hi:[0,1]
	v_pk_add_f32 v[86:87], v[84:85], v[100:101]
	v_pk_add_f32 v[22:23], v[84:85], v[100:101] neg_lo:[0,1] neg_hi:[0,1]
	v_pk_add_f32 v[100:101], v[24:25], v[10:11] op_sel:[0,1] op_sel_hi:[1,0] neg_hi:[0,1]
	v_pk_add_f32 v[10:11], v[24:25], v[10:11] op_sel:[0,1] op_sel_hi:[1,0] neg_lo:[0,1]
	v_mov_b32_e32 v24, v63
	v_pk_add_f32 v[84:85], v[108:109], v[64:65]
	v_cvt_f32_i32_e32 v24, v24
	v_pk_add_f32 v[76:77], v[108:109], v[64:65] neg_lo:[0,1] neg_hi:[0,1]
	v_pk_add_f32 v[104:105], v[66:67], v[26:27]
	v_pk_add_f32 v[14:15], v[66:67], v[26:27] neg_lo:[0,1] neg_hi:[0,1]
	v_mul_f32_e32 v25, 0x38800000, v24
	v_cos_f32_e32 v24, v25
	v_sin_f32_e32 v25, v25
	s_nop 0
	s_nop 0
	v_add_f32_e32 v62, v24, v24
	v_pk_mul_f32 v[26:27], v[24:25], v[24:25]
	v_mul_f32_e32 v62, v25, v62
	s_nop 0
	s_nop 0
	v_mov_b32_e32 v108, v25
	v_pk_add_f32 v[26:27], v[26:27], v[26:27] op_sel:[0,1] op_sel_hi:[0,1] neg_lo:[0,1] neg_hi:[0,1]
	v_pk_mul_f32 v[72:73], v[24:25], v[62:63] op_sel:[1,0] op_sel_hi:[0,0] neg_lo:[1,0]
	v_pk_mul_f32 v[94:95], v[18:19], v[108:109] op_sel:[1,0] op_sel_hi:[0,0] neg_hi:[1,0]
	v_pk_add_f32 v[16:17], v[70:71], v[80:81]
	v_pk_fma_f32 v[72:73], v[24:25], v[26:27], v[72:73]
	v_pk_fma_f32 v[18:19], v[18:19], v[24:25], v[94:95] op_sel_hi:[1,0,1]
	v_pk_mul_f32 v[24:25], v[62:63], s[48:49] op_sel_hi:[0,1]
	v_pk_fma_f32 v[94:95], v[26:27], s[40:41], v[24:25]
	s_nop 0
	v_pk_mul_f32 v[24:25], v[16:17], v[94:95] op_sel:[1,1] op_sel_hi:[0,1] neg_hi:[1,0]
	v_pk_add_f32 v[64:65], v[112:113], v[114:115]
	v_pk_fma_f32 v[24:25], v[16:17], v[94:95], v[24:25] op_sel_hi:[1,0,1]
	v_pk_mul_f32 v[16:17], v[62:63], v[72:73] op_sel:[0,1] op_sel_hi:[0,0] neg_lo:[0,1]
	v_pk_fma_f32 v[108:109], v[26:27], v[72:73], v[16:17]
	v_pk_mul_f32 v[16:17], v[64:65], v[72:73] op_sel:[1,1] op_sel_hi:[0,1] neg_hi:[1,0]
	v_pk_add_f32 v[90:91], v[106:107], v[82:83]
	v_pk_fma_f32 v[16:17], v[64:65], v[72:73], v[16:17] op_sel_hi:[1,0,1]
	v_pk_mul_f32 v[64:65], v[62:63], v[94:95] op_sel:[0,1] op_sel_hi:[0,0] neg_lo:[0,1]
	v_pk_fma_f32 v[94:95], v[26:27], v[94:95], v[64:65]
	s_nop 0
	v_pk_mul_f32 v[64:65], v[78:79], v[94:95] op_sel:[1,1] op_sel_hi:[0,1] neg_hi:[1,0]
	v_pk_add_f32 v[66:67], v[6:7], v[118:119]
	v_pk_fma_f32 v[72:73], v[78:79], v[94:95], v[64:65] op_sel_hi:[1,0,1]
	v_pk_mul_f32 v[64:65], v[62:63], v[108:109] op_sel:[0,1] op_sel_hi:[0,0] neg_lo:[0,1]
	v_pk_fma_f32 v[110:111], v[26:27], v[108:109], v[64:65]
	v_pk_mul_f32 v[64:65], v[84:85], v[108:109] op_sel:[1,1] op_sel_hi:[0,1] neg_hi:[1,0]
	v_pk_mul_f32 v[78:79], v[62:63], v[94:95] op_sel:[0,1] op_sel_hi:[0,0] neg_lo:[0,1]
	v_pk_fma_f32 v[64:65], v[84:85], v[108:109], v[64:65] op_sel_hi:[1,0,1]
	v_pk_fma_f32 v[84:85], v[26:27], v[94:95], v[78:79]
	s_nop 0
	v_pk_mul_f32 v[78:79], v[90:91], v[84:85] op_sel:[1,1] op_sel_hi:[0,1] neg_hi:[1,0]
	v_pk_add_f32 v[68:69], v[106:107], v[82:83] neg_lo:[0,1] neg_hi:[0,1]
	v_pk_fma_f32 v[78:79], v[90:91], v[84:85], v[78:79] op_sel_hi:[1,0,1]
	v_pk_mul_f32 v[90:91], v[62:63], v[110:111] op_sel:[0,1] op_sel_hi:[0,0] neg_lo:[0,1]
	v_pk_fma_f32 v[94:95], v[26:27], v[110:111], v[90:91]
	v_pk_mul_f32 v[90:91], v[66:67], v[110:111] op_sel:[1,1] op_sel_hi:[0,1] neg_hi:[1,0]
	v_pk_add_f32 v[106:107], v[116:117], v[120:121]
	v_pk_fma_f32 v[66:67], v[66:67], v[110:111], v[90:91] op_sel_hi:[1,0,1]
	v_pk_mul_f32 v[90:91], v[62:63], v[84:85] op_sel:[0,1] op_sel_hi:[0,0] neg_lo:[0,1]
	v_pk_fma_f32 v[108:109], v[26:27], v[84:85], v[90:91]
	s_nop 0
	v_pk_mul_f32 v[84:85], v[122:123], v[108:109] op_sel:[1,1] op_sel_hi:[0,1] neg_hi:[1,0]
	v_pk_add_f32 v[80:81], v[70:71], v[80:81] neg_lo:[0,1] neg_hi:[0,1]
	v_pk_fma_f32 v[90:91], v[122:123], v[108:109], v[84:85] op_sel_hi:[1,0,1]
	v_pk_mul_f32 v[84:85], v[62:63], v[94:95] op_sel:[0,1] op_sel_hi:[0,0] neg_lo:[0,1]
	v_pk_fma_f32 v[110:111], v[26:27], v[94:95], v[84:85]
	v_pk_mul_f32 v[84:85], v[86:87], v[94:95] op_sel:[1,1] op_sel_hi:[0,1] neg_hi:[1,0]
	v_pk_add_f32 v[82:83], v[112:113], v[114:115] neg_lo:[0,1] neg_hi:[0,1]
	v_pk_fma_f32 v[84:85], v[86:87], v[94:95], v[84:85] op_sel_hi:[1,0,1]
	v_pk_mul_f32 v[86:87], v[62:63], v[108:109] op_sel:[0,1] op_sel_hi:[0,0] neg_lo:[0,1]
	v_pk_fma_f32 v[108:109], v[26:27], v[108:109], v[86:87]
	s_nop 0
	v_pk_mul_f32 v[86:87], v[102:103], v[108:109] op_sel:[1,1] op_sel_hi:[0,1] neg_hi:[1,0]
	v_pk_add_f32 v[70:71], v[6:7], v[118:119] neg_lo:[0,1] neg_hi:[0,1]
	v_pk_fma_f32 v[94:95], v[102:103], v[108:109], v[86:87] op_sel_hi:[1,0,1]
	v_pk_mul_f32 v[86:87], v[62:63], v[110:111] op_sel:[0,1] op_sel_hi:[0,0] neg_lo:[0,1]
	v_pk_fma_f32 v[102:103], v[26:27], v[110:111], v[86:87]
	v_pk_mul_f32 v[86:87], v[104:105], v[110:111] op_sel:[1,1] op_sel_hi:[0,1] neg_hi:[1,0]
	v_pk_add_f32 v[6:7], v[116:117], v[120:121] neg_lo:[0,1] neg_hi:[0,1]
	v_pk_fma_f32 v[86:87], v[104:105], v[110:111], v[86:87] op_sel_hi:[1,0,1]
	v_pk_mul_f32 v[104:105], v[62:63], v[108:109] op_sel:[0,1] op_sel_hi:[0,0] neg_lo:[0,1]
	v_pk_fma_f32 v[104:105], v[26:27], v[108:109], v[104:105]
	s_nop 0
	v_pk_mul_f32 v[108:109], v[96:97], v[104:105] op_sel:[1,1] op_sel_hi:[0,1] neg_hi:[1,0]
	s_nop 0
	v_pk_fma_f32 v[96:97], v[96:97], v[104:105], v[108:109] op_sel_hi:[1,0,1]
	v_pk_mul_f32 v[108:109], v[62:63], v[102:103] op_sel:[0,1] op_sel_hi:[0,0] neg_lo:[0,1]
	v_pk_mul_f32 v[110:111], v[100:101], v[102:103] op_sel:[1,1] op_sel_hi:[0,1] neg_hi:[1,0]
	v_pk_fma_f32 v[108:109], v[26:27], v[102:103], v[108:109]
	v_pk_fma_f32 v[100:101], v[100:101], v[102:103], v[110:111] op_sel_hi:[1,0,1]
	v_pk_mul_f32 v[102:103], v[62:63], v[104:105] op_sel:[0,1] op_sel_hi:[0,0] neg_lo:[0,1]
	v_pk_fma_f32 v[102:103], v[26:27], v[104:105], v[102:103]
	s_nop 0
	v_pk_mul_f32 v[104:105], v[98:99], v[102:103] op_sel:[1,1] op_sel_hi:[0,1] neg_hi:[1,0]
	s_nop 0
	v_pk_fma_f32 v[98:99], v[98:99], v[102:103], v[104:105] op_sel_hi:[1,0,1]
	v_pk_mul_f32 v[104:105], v[62:63], v[108:109] op_sel:[0,1] op_sel_hi:[0,0] neg_lo:[0,1]
	v_pk_mul_f32 v[110:111], v[106:107], v[108:109] op_sel:[1,1] op_sel_hi:[0,1] neg_hi:[1,0]
	v_pk_fma_f32 v[104:105], v[26:27], v[108:109], v[104:105]
	v_pk_fma_f32 v[106:107], v[106:107], v[108:109], v[110:111] op_sel_hi:[1,0,1]
	v_pk_mul_f32 v[108:109], v[62:63], v[102:103] op_sel:[0,1] op_sel_hi:[0,0] neg_lo:[0,1]
	v_pk_fma_f32 v[102:103], v[26:27], v[102:103], v[108:109]
	s_nop 0
	v_pk_mul_f32 v[108:109], v[88:89], v[102:103] op_sel:[1,1] op_sel_hi:[0,1] neg_hi:[1,0]
	s_nop 0
	v_pk_fma_f32 v[88:89], v[88:89], v[102:103], v[108:109] op_sel_hi:[1,0,1]
	v_pk_mul_f32 v[108:109], v[62:63], v[104:105] op_sel:[0,1] op_sel_hi:[0,0] neg_lo:[0,1]
	v_pk_mul_f32 v[110:111], v[92:93], v[104:105] op_sel:[1,1] op_sel_hi:[0,1] neg_hi:[1,0]
	v_pk_fma_f32 v[108:109], v[26:27], v[104:105], v[108:109]
	v_pk_fma_f32 v[92:93], v[92:93], v[104:105], v[110:111] op_sel_hi:[1,0,1]
	v_pk_mul_f32 v[104:105], v[62:63], v[102:103] op_sel:[0,1] op_sel_hi:[0,0] neg_lo:[0,1]
	v_pk_fma_f32 v[102:103], v[26:27], v[102:103], v[104:105]
	s_nop 0
	v_pk_mul_f32 v[104:105], v[80:81], v[102:103] op_sel:[1,1] op_sel_hi:[0,1] neg_hi:[1,0]
	s_nop 0
	v_pk_fma_f32 v[80:81], v[80:81], v[102:103], v[104:105] op_sel_hi:[1,0,1]
	v_pk_mul_f32 v[104:105], v[62:63], v[108:109] op_sel:[0,1] op_sel_hi:[0,0] neg_lo:[0,1]
	v_pk_mul_f32 v[110:111], v[82:83], v[108:109] op_sel:[1,1] op_sel_hi:[0,1] neg_hi:[1,0]
	v_pk_fma_f32 v[104:105], v[26:27], v[108:109], v[104:105]
	v_pk_fma_f32 v[82:83], v[82:83], v[108:109], v[110:111] op_sel_hi:[1,0,1]
	v_pk_mul_f32 v[108:109], v[62:63], v[102:103] op_sel:[0,1] op_sel_hi:[0,0] neg_lo:[0,1]
	v_pk_fma_f32 v[102:103], v[26:27], v[102:103], v[108:109]
	s_nop 0
	v_pk_mul_f32 v[108:109], v[74:75], v[102:103] op_sel:[1,1] op_sel_hi:[0,1] neg_hi:[1,0]
	s_nop 0
	v_pk_fma_f32 v[74:75], v[74:75], v[102:103], v[108:109] op_sel_hi:[1,0,1]
	v_pk_mul_f32 v[108:109], v[62:63], v[104:105] op_sel:[0,1] op_sel_hi:[0,0] neg_lo:[0,1]
	v_pk_mul_f32 v[110:111], v[76:77], v[104:105] op_sel:[1,1] op_sel_hi:[0,1] neg_hi:[1,0]
	v_pk_fma_f32 v[108:109], v[26:27], v[104:105], v[108:109]
	v_pk_fma_f32 v[76:77], v[76:77], v[104:105], v[110:111] op_sel_hi:[1,0,1]
	v_pk_mul_f32 v[104:105], v[62:63], v[102:103] op_sel:[0,1] op_sel_hi:[0,0] neg_lo:[0,1]
	v_pk_fma_f32 v[102:103], v[26:27], v[102:103], v[104:105]
	s_nop 0
	v_pk_mul_f32 v[104:105], v[68:69], v[102:103] op_sel:[1,1] op_sel_hi:[0,1] neg_hi:[1,0]
	s_nop 0
	v_pk_fma_f32 v[68:69], v[68:69], v[102:103], v[104:105] op_sel_hi:[1,0,1]
	v_pk_mul_f32 v[104:105], v[62:63], v[108:109] op_sel:[0,1] op_sel_hi:[0,0] neg_lo:[0,1]
	v_pk_mul_f32 v[110:111], v[70:71], v[108:109] op_sel:[1,1] op_sel_hi:[0,1] neg_hi:[1,0]
	v_pk_fma_f32 v[104:105], v[26:27], v[108:109], v[104:105]
	v_pk_fma_f32 v[70:71], v[70:71], v[108:109], v[110:111] op_sel_hi:[1,0,1]
	v_pk_mul_f32 v[108:109], v[62:63], v[102:103] op_sel:[0,1] op_sel_hi:[0,0] neg_lo:[0,1]
	v_pk_fma_f32 v[102:103], v[26:27], v[102:103], v[108:109]
	s_nop 0
	v_pk_mul_f32 v[108:109], v[20:21], v[102:103] op_sel:[1,1] op_sel_hi:[0,1] neg_hi:[1,0]
	s_nop 0
	v_pk_fma_f32 v[20:21], v[20:21], v[102:103], v[108:109] op_sel_hi:[1,0,1]
	v_pk_mul_f32 v[108:109], v[62:63], v[104:105] op_sel:[0,1] op_sel_hi:[0,0] neg_lo:[0,1]
	v_pk_mul_f32 v[110:111], v[22:23], v[104:105] op_sel:[1,1] op_sel_hi:[0,1] neg_hi:[1,0]
	v_pk_fma_f32 v[108:109], v[26:27], v[104:105], v[108:109]
	v_pk_fma_f32 v[22:23], v[22:23], v[104:105], v[110:111] op_sel_hi:[1,0,1]
	v_pk_mul_f32 v[104:105], v[62:63], v[102:103] op_sel:[0,1] op_sel_hi:[0,0] neg_lo:[0,1]
	v_pk_fma_f32 v[102:103], v[26:27], v[102:103], v[104:105]
	s_nop 0
	v_pk_mul_f32 v[104:105], v[12:13], v[102:103] op_sel:[1,1] op_sel_hi:[0,1] neg_hi:[1,0]
	s_nop 0
	v_pk_fma_f32 v[12:13], v[12:13], v[102:103], v[104:105] op_sel_hi:[1,0,1]
	v_pk_mul_f32 v[104:105], v[62:63], v[108:109] op_sel:[0,1] op_sel_hi:[0,0] neg_lo:[0,1]
	v_pk_mul_f32 v[110:111], v[14:15], v[108:109] op_sel:[1,1] op_sel_hi:[0,1] neg_hi:[1,0]
	v_pk_fma_f32 v[104:105], v[26:27], v[108:109], v[104:105]
	v_pk_fma_f32 v[14:15], v[14:15], v[108:109], v[110:111] op_sel_hi:[1,0,1]
	v_pk_mul_f32 v[108:109], v[62:63], v[102:103] op_sel:[0,1] op_sel_hi:[0,0] neg_lo:[0,1]
	v_pk_fma_f32 v[102:103], v[26:27], v[102:103], v[108:109]
	s_nop 0
	v_pk_mul_f32 v[108:109], v[8:9], v[102:103] op_sel:[1,1] op_sel_hi:[0,1] neg_hi:[1,0]
	s_nop 0
	v_pk_fma_f32 v[8:9], v[8:9], v[102:103], v[108:109] op_sel_hi:[1,0,1]
	v_pk_mul_f32 v[108:109], v[62:63], v[104:105] op_sel:[0,1] op_sel_hi:[0,0] neg_lo:[0,1]
	v_pk_mul_f32 v[110:111], v[10:11], v[104:105] op_sel:[1,1] op_sel_hi:[0,1] neg_hi:[1,0]
	v_pk_fma_f32 v[108:109], v[26:27], v[104:105], v[108:109]
	v_pk_fma_f32 v[10:11], v[10:11], v[104:105], v[110:111] op_sel_hi:[1,0,1]
	v_pk_mul_f32 v[104:105], v[62:63], v[102:103] op_sel:[0,1] op_sel_hi:[0,0] neg_lo:[0,1]
	v_pk_fma_f32 v[26:27], v[26:27], v[102:103], v[104:105]
	s_nop 0
	v_pk_mul_f32 v[102:103], v[4:5], v[26:27] op_sel:[1,1] op_sel_hi:[0,1] neg_hi:[1,0]
	s_add_i32 s1, 16, 0x1e000
	v_pk_fma_f32 v[4:5], v[4:5], v[26:27], v[102:103] op_sel_hi:[1,0,1]
	s_nop 0
	s_nop 0
	v_pk_mul_f32 v[26:27], v[6:7], v[108:109] op_sel:[1,1] op_sel_hi:[0,1] neg_hi:[1,0]
	s_add_i32 s0, 16, 0x1f000
	v_pk_fma_f32 v[6:7], v[6:7], v[108:109], v[26:27] op_sel_hi:[1,0,1]
	v_lshrrev_b32_e32 v26, 5, v63
	v_bitop3_b32 v26, v26, v63, 15 bitop3:0x6c
	v_lshlrev_b32_e32 v26, 3, v26
	v_bfe_u32 v27, v63, 5, 4
	v_add_u32_e32 v62, 16, v26
	ds_write_b64 v62, v[2:3]
	v_bitop3_b32 v2, v27, v63, 16 bitop3:0x36
	v_lshlrev_b32_e32 v2, 3, v2
	v_add_u32_e32 v3, 16, v2
	ds_write_b64 v3, v[88:89] offset:4096
	ds_write_b64 v62, v[90:91] offset:8192
	ds_write_b64 v3, v[20:21] offset:12288
	ds_write_b64 v62, v[72:73] offset:16384
	ds_write_b64 v3, v[74:75] offset:20480
	ds_write_b64 v62, v[96:97] offset:24576
	ds_write_b64 v3, v[8:9] offset:28672
	ds_write_b64 v62, v[24:25] offset:32768
	ds_write_b64 v3, v[80:81] offset:36864
	ds_write_b64 v62, v[94:95] offset:40960
	ds_write_b64 v3, v[12:13] offset:45056
	ds_write_b64 v62, v[78:79] offset:49152
	ds_write_b64 v3, v[68:69] offset:53248
	ds_write_b64 v62, v[98:99] offset:57344
	ds_write_b64 v3, v[4:5] offset:61440
	v_add_u32_e32 v3, s47, v26
	ds_write_b64 v3, v[18:19]
	v_add_u32_e32 v3, s19, v2
	ds_write_b64 v3, v[92:93]
	v_add_u32_e32 v3, s18, v26
	ds_write_b64 v3, v[84:85]
	v_add_u32_e32 v3, s17, v2
	ds_write_b64 v3, v[22:23]
	v_add_u32_e32 v3, s13, v26
	ds_write_b64 v3, v[64:65]
	v_add_u32_e32 v3, s12, v2
	ds_write_b64 v3, v[76:77]
	v_add_u32_e32 v3, s11, v26
	ds_write_b64 v3, v[100:101]
	v_add_u32_e32 v3, s10, v2
	ds_write_b64 v3, v[10:11]
	v_add_u32_e32 v3, s9, v26
	ds_write_b64 v3, v[16:17]
	v_add_u32_e32 v3, s8, v2
	ds_write_b64 v3, v[82:83]
	v_add_u32_e32 v3, s7, v26
	ds_write_b64 v3, v[86:87]
	v_add_u32_e32 v3, s6, v2
	ds_write_b64 v3, v[14:15]
	v_add_u32_e32 v3, s5, v26
	ds_write_b64 v3, v[66:67]
	v_add_u32_e32 v3, s4, v2
	ds_write_b64 v3, v[70:71]
	v_add_u32_e32 v3, s1, v26
	v_add_u32_e32 v2, s0, v2
	v_mov_b32_e32 v21, v146
	ds_write_b64 v3, v[106:107]
	ds_write_b64 v2, v[6:7]
	s_waitcnt lgkmcnt(0)
	s_barrier
	s_lshl_b32 s44, s16, 14
	v_lshlrev_b32_e32 v2, 5, v21
	v_and_b32_e32 v4, 0xfffffe00, v2
	v_and_b32_e32 v20, 15, v21
	v_and_or_b32 v2, v21, 16, v4
	v_bitop3_b32 v4, v4, 16, v21 bitop3:0x34
	v_bitop3_b32 v72, v21, 8, 15 bitop3:0x6c
	v_lshl_add_u32 v26, v2, 3, 16
	v_lshlrev_b32_e32 v5, 3, v20
	v_lshl_add_u32 v126, v4, 3, 16
	v_lshlrev_b32_e32 v74, 3, v72
	v_add_u32_e32 v27, v26, v5
	v_add_u32_e32 v96, v126, v5
	v_add_u32_e32 v111, v26, v74
	v_add_u32_e32 v112, v126, v74
	ds_read_b64 v[2:3], v27
	ds_read_b64 v[4:5], v96
	v_bitop3_b32 v6, v21, 1, 15 bitop3:0x6c
	ds_read_b64 v[72:73], v111 offset:2048
	ds_read_b64 v[74:75], v112 offset:2048
	v_bitop3_b32 v76, v21, 9, 15 bitop3:0x6c
	v_lshlrev_b32_e32 v8, 3, v6
	v_lshlrev_b32_e32 v78, 3, v76
	v_add_u32_e32 v97, v26, v8
	v_add_u32_e32 v113, v26, v78
	ds_read_b64 v[6:7], v97 offset:256
	ds_read_b64 v[76:77], v113 offset:2304
	v_add_u32_e32 v98, v126, v8
	v_add_u32_e32 v114, v126, v78
	ds_read_b64 v[8:9], v98 offset:256
	ds_read_b64 v[78:79], v114 offset:2304
	s_waitcnt lgkmcnt(5)
	v_pk_add_f32 v[136:137], v[2:3], v[72:73]
	v_pk_add_f32 v[2:3], v[2:3], v[72:73] neg_lo:[0,1] neg_hi:[0,1]
	s_waitcnt lgkmcnt(4)
	v_pk_add_f32 v[72:73], v[4:5], v[74:75]
	v_pk_add_f32 v[4:5], v[4:5], v[74:75] neg_lo:[0,1] neg_hi:[0,1]
	v_bitop3_b32 v10, v21, 2, 15 bitop3:0x6c
	v_bitop3_b32 v80, v21, 10, 15 bitop3:0x6c
	v_lshlrev_b32_e32 v12, 3, v10
	v_lshlrev_b32_e32 v82, 3, v80
	v_pk_mul_f32 v[74:75], v[4:5], s[58:59] op_sel:[1,0] op_sel_hi:[0,0] neg_hi:[1,0]
	v_add_u32_e32 v99, v26, v12
	v_add_u32_e32 v115, v26, v82
	v_pk_fma_f32 v[4:5], v[4:5], s[46:47], v[74:75] op_sel_hi:[1,0,1]
	s_waitcnt lgkmcnt(2)
	v_pk_add_f32 v[74:75], v[6:7], v[76:77]
	v_pk_add_f32 v[6:7], v[6:7], v[76:77] neg_lo:[0,1] neg_hi:[0,1]
	ds_read_b64 v[10:11], v99 offset:512
	ds_read_b64 v[80:81], v115 offset:2560
	v_pk_mul_f32 v[76:77], v[6:7], s[62:63] op_sel:[1,0] op_sel_hi:[0,0] neg_hi:[1,0]
	v_add_u32_e32 v100, v126, v12
	v_bitop3_b32 v14, v21, 3, 15 bitop3:0x6c
	v_add_u32_e32 v116, v126, v82
	v_bitop3_b32 v84, v21, 11, 15 bitop3:0x6c
	v_pk_fma_f32 v[6:7], v[6:7], s[60:61], v[76:77] op_sel_hi:[1,0,1]
	s_waitcnt lgkmcnt(2)
	v_pk_add_f32 v[76:77], v[8:9], v[78:79]
	v_pk_add_f32 v[8:9], v[8:9], v[78:79] neg_lo:[0,1] neg_hi:[0,1]
	ds_read_b64 v[12:13], v100 offset:512
	v_lshlrev_b32_e32 v16, 3, v14
	ds_read_b64 v[82:83], v116 offset:2560
	v_lshlrev_b32_e32 v86, 3, v84
	v_add_u32_e32 v101, v26, v16
	v_add_u32_e32 v102, v126, v16
	v_add_u32_e32 v117, v26, v86
	v_add_u32_e32 v118, v126, v86
	v_pk_mul_f32 v[78:79], v[8:9], s[66:67] op_sel:[1,0] op_sel_hi:[0,0] neg_hi:[1,0]
	ds_read_b64 v[14:15], v101 offset:768
	ds_read_b64 v[16:17], v102 offset:768
	ds_read_b64 v[84:85], v117 offset:2816
	ds_read_b64 v[86:87], v118 offset:2816
	v_pk_fma_f32 v[8:9], v[8:9], s[64:65], v[78:79] op_sel_hi:[1,0,1]
	s_waitcnt lgkmcnt(6)
	v_pk_add_f32 v[78:79], v[10:11], v[80:81]
	v_pk_add_f32 v[10:11], v[10:11], v[80:81] neg_lo:[0,1] neg_hi:[0,1]
	v_bitop3_b32 v18, v21, 4, 15 bitop3:0x6c
	v_pk_mul_f32 v[80:81], v[10:11], s[70:71] op_sel:[1,0] op_sel_hi:[0,0] neg_hi:[1,0]
	v_bitop3_b32 v88, v21, 12, 15 bitop3:0x6c
	v_pk_fma_f32 v[10:11], v[10:11], s[70:71], v[80:81] op_sel_hi:[1,0,1]
	s_waitcnt lgkmcnt(4)
	v_pk_add_f32 v[80:81], v[12:13], v[82:83]
	v_pk_add_f32 v[12:13], v[12:13], v[82:83] neg_lo:[0,1] neg_hi:[0,1]
	v_lshlrev_b32_e32 v22, 3, v18
	v_lshlrev_b32_e32 v90, 3, v88
	v_pk_mul_f32 v[82:83], v[12:13], s[64:65] op_sel:[1,0] op_sel_hi:[0,0] neg_hi:[1,0]
	v_add_u32_e32 v103, v26, v22
	v_add_u32_e32 v119, v26, v90
	v_pk_fma_f32 v[12:13], v[12:13], s[66:67], v[82:83] op_sel_hi:[1,0,1]
	s_waitcnt lgkmcnt(1)
	v_pk_add_f32 v[82:83], v[14:15], v[84:85]
	v_pk_add_f32 v[14:15], v[14:15], v[84:85] neg_lo:[0,1] neg_hi:[0,1]
	ds_read_b64 v[18:19], v103 offset:1024
	v_add_u32_e32 v104, v126, v22
	v_bitop3_b32 v24, v21, 5, 15 bitop3:0x6c
	ds_read_b64 v[88:89], v119 offset:3072
	v_add_u32_e32 v120, v126, v90
	v_bitop3_b32 v92, v21, 13, 15 bitop3:0x6c
	ds_read_b64 v[22:23], v104 offset:1024
	v_lshlrev_b32_e32 v62, 3, v24
	ds_read_b64 v[90:91], v120 offset:3072
	v_lshlrev_b32_e32 v94, 3, v92
	v_pk_mul_f32 v[84:85], v[14:15], s[60:61] op_sel:[1,0] op_sel_hi:[0,0] neg_hi:[1,0]
	v_add_u32_e32 v105, v26, v62
	v_add_u32_e32 v121, v26, v94
	v_pk_fma_f32 v[14:15], v[14:15], s[62:63], v[84:85] op_sel_hi:[1,0,1]
	s_waitcnt lgkmcnt(4)
	v_pk_add_f32 v[84:85], v[16:17], v[86:87]
	v_pk_add_f32 v[16:17], v[16:17], v[86:87] neg_lo:[0,1] neg_hi:[0,1]
	ds_read_b64 v[24:25], v105 offset:1280
	ds_read_b64 v[92:93], v121 offset:3328
	v_add_u32_e32 v106, v126, v62
	v_bitop3_b32 v64, v21, 6, 15 bitop3:0x6c
	v_add_u32_e32 v122, v126, v94
	v_bitop3_b32 v123, v21, 14, 15 bitop3:0x6c
	v_pk_mul_f32 v[86:87], v[16:17], s[46:47] op_sel:[1,0] op_sel_hi:[0,0] neg_hi:[1,0]
	ds_read_b64 v[62:63], v106 offset:1280
	v_lshlrev_b32_e32 v66, 3, v64
	ds_read_b64 v[94:95], v122 offset:3328
	v_lshlrev_b32_e32 v124, 3, v123
	v_pk_fma_f32 v[16:17], v[16:17], s[58:59], v[86:87] op_sel_hi:[1,0,1]
	s_waitcnt lgkmcnt(6)
	v_pk_add_f32 v[86:87], v[18:19], v[88:89]
	v_pk_add_f32 v[18:19], v[18:19], v[88:89] neg_lo:[0,1] neg_hi:[0,1]
	v_add_u32_e32 v107, v26, v66
	v_add_u32_e32 v123, v26, v124
	v_xor_b32_e32 v89, 0x80000000, v18
	v_mov_b32_e32 v88, v19
	s_waitcnt lgkmcnt(4)
	v_pk_add_f32 v[18:19], v[22:23], v[90:91]
	v_pk_add_f32 v[22:23], v[22:23], v[90:91] neg_lo:[0,1] neg_hi:[0,1]
	ds_read_b64 v[64:65], v107 offset:1536
	ds_read_b64 v[128:129], v123 offset:3584
	v_pk_mul_f32 v[90:91], v[22:23], s[58:59] op_sel_hi:[1,0]
	v_xor_b32_e32 v139, 0x80000000, v22
	v_mov_b32_e32 v138, v23
	v_add_u32_e32 v108, v126, v66
	v_bitop3_b32 v68, v21, 7, 15 bitop3:0x6c
	v_add_u32_e32 v124, v126, v124
	v_bitop3_b32 v21, v21, 15, v21 bitop3:0xc
	v_pk_fma_f32 v[22:23], v[138:139], s[46:47], v[90:91] op_sel_hi:[1,0,1] neg_lo:[0,0,1] neg_hi:[0,0,1]
	s_waitcnt lgkmcnt(4)
	v_pk_add_f32 v[90:91], v[24:25], v[92:93]
	v_pk_add_f32 v[24:25], v[24:25], v[92:93] neg_lo:[0,1] neg_hi:[0,1]
	ds_read_b64 v[66:67], v108 offset:1536
	v_lshlrev_b32_e32 v70, 3, v68
	ds_read_b64 v[130:131], v124 offset:3584
	v_lshlrev_b32_e32 v21, 3, v21
	v_pk_mul_f32 v[92:93], v[24:25], s[62:63] op_sel_hi:[1,0]
	v_xor_b32_e32 v139, 0x80000000, v24
	v_mov_b32_e32 v138, v25
	v_add_u32_e32 v109, v26, v70
	v_add_u32_e32 v125, v26, v21
	v_pk_fma_f32 v[24:25], v[138:139], s[60:61], v[92:93] op_sel_hi:[1,0,1] neg_lo:[0,0,1] neg_hi:[0,0,1]
	s_waitcnt lgkmcnt(4)
	v_pk_add_f32 v[92:93], v[62:63], v[94:95]
	v_pk_add_f32 v[62:63], v[62:63], v[94:95] neg_lo:[0,1] neg_hi:[0,1]
	ds_read_b64 v[68:69], v109 offset:1792
	v_add_u32_e32 v110, v126, v70
	ds_read_b64 v[132:133], v125 offset:3840
	v_add_u32_e32 v126, v126, v21
	v_pk_mul_f32 v[94:95], v[62:63], s[66:67] op_sel_hi:[1,0]
	v_xor_b32_e32 v139, 0x80000000, v62
	v_mov_b32_e32 v138, v63
	ds_read_b64 v[70:71], v110 offset:1792
	ds_read_b64 v[134:135], v126 offset:3840
	v_pk_fma_f32 v[62:63], v[138:139], s[64:65], v[94:95] op_sel_hi:[1,0,1] neg_lo:[0,0,1] neg_hi:[0,0,1]
	s_waitcnt lgkmcnt(6)
	v_pk_add_f32 v[94:95], v[64:65], v[128:129]
	v_pk_add_f32 v[64:65], v[64:65], v[128:129] neg_lo:[0,1] neg_hi:[0,1]
	v_lshl_add_u64 v[0:1], s[44:45], 2, v[28:29]
	v_pk_mul_f32 v[128:129], v[64:65], s[70:71] op_sel_hi:[1,0]
	v_xor_b32_e32 v139, 0x80000000, v64
	v_mov_b32_e32 v138, v65
	v_pk_fma_f32 v[64:65], v[138:139], s[70:71], v[128:129] op_sel_hi:[1,0,1] neg_lo:[0,0,1] neg_hi:[0,0,1]
	s_waitcnt lgkmcnt(4)
	v_pk_add_f32 v[128:129], v[66:67], v[130:131]
	v_pk_add_f32 v[66:67], v[66:67], v[130:131] neg_lo:[0,1] neg_hi:[0,1]
	v_cvt_f32_i32_e32 v20, v20
	v_pk_mul_f32 v[130:131], v[66:67], s[64:65] op_sel_hi:[1,0]
	v_xor_b32_e32 v139, 0x80000000, v66
	v_mov_b32_e32 v138, v67
	v_pk_fma_f32 v[66:67], v[138:139], s[66:67], v[130:131] op_sel_hi:[1,0,1] neg_lo:[0,0,1] neg_hi:[0,0,1]
	s_waitcnt lgkmcnt(2)
	v_pk_add_f32 v[130:131], v[68:69], v[132:133]
	v_pk_add_f32 v[68:69], v[68:69], v[132:133] neg_lo:[0,1] neg_hi:[0,1]
	v_mul_f32_e32 v21, 0x3b000000, v20
	v_pk_mul_f32 v[132:133], v[68:69], s[60:61] op_sel_hi:[1,0]
	v_xor_b32_e32 v139, 0x80000000, v68
	v_mov_b32_e32 v138, v69
	v_pk_fma_f32 v[68:69], v[138:139], s[62:63], v[132:133] op_sel_hi:[1,0,1] neg_lo:[0,0,1] neg_hi:[0,0,1]
	s_waitcnt lgkmcnt(0)
	v_pk_add_f32 v[132:133], v[70:71], v[134:135]
	v_pk_add_f32 v[70:71], v[70:71], v[134:135] neg_lo:[0,1] neg_hi:[0,1]
	v_cos_f32_e32 v20, v21
	v_pk_mul_f32 v[134:135], v[70:71], s[46:47] op_sel_hi:[1,0]
	v_xor_b32_e32 v139, 0x80000000, v70
	v_mov_b32_e32 v138, v71
	v_pk_fma_f32 v[70:71], v[138:139], s[58:59], v[134:135] op_sel_hi:[1,0,1] neg_lo:[0,0,1] neg_hi:[0,0,1]
	v_pk_add_f32 v[134:135], v[136:137], v[86:87]
	v_pk_add_f32 v[86:87], v[136:137], v[86:87] neg_lo:[0,1] neg_hi:[0,1]
	v_pk_add_f32 v[136:137], v[72:73], v[18:19]
	v_pk_add_f32 v[18:19], v[72:73], v[18:19] neg_lo:[0,1] neg_hi:[0,1]
	v_sin_f32_e32 v21, v21
	s_nop 0
	s_nop 0
	v_pk_mul_f32 v[72:73], v[18:19], s[62:63] op_sel:[1,0] op_sel_hi:[0,0] neg_hi:[1,0]
	v_add_f32_e32 v26, v20, v20
	v_pk_fma_f32 v[18:19], v[18:19], s[60:61], v[72:73] op_sel_hi:[1,0,1]
	v_pk_add_f32 v[72:73], v[74:75], v[90:91]
	v_pk_add_f32 v[74:75], v[74:75], v[90:91] neg_lo:[0,1] neg_hi:[0,1]
	v_mul_f32_e32 v26, v21, v26
	s_nop 0
	s_nop 0
	v_pk_mul_f32 v[90:91], v[74:75], s[70:71] op_sel:[1,0] op_sel_hi:[0,0] neg_hi:[1,0]
	s_lshl_b32 s44, s16, 9
	v_pk_fma_f32 v[74:75], v[74:75], s[70:71], v[90:91] op_sel_hi:[1,0,1]
	v_pk_add_f32 v[90:91], v[76:77], v[92:93]
	v_pk_add_f32 v[76:77], v[76:77], v[92:93] neg_lo:[0,1] neg_hi:[0,1]
	s_mov_b64 s[28:29], -1
	s_nop 0
	s_nop 0
	v_pk_mul_f32 v[92:93], v[76:77], s[60:61] op_sel:[1,0] op_sel_hi:[0,0] neg_hi:[1,0]
	s_nop 0
	v_pk_fma_f32 v[76:77], v[76:77], s[62:63], v[92:93] op_sel_hi:[1,0,1]
	v_pk_add_f32 v[92:93], v[78:79], v[94:95]
	v_pk_add_f32 v[78:79], v[78:79], v[94:95] neg_lo:[0,1] neg_hi:[0,1]
	s_nop 0
	v_xor_b32_e32 v95, 0x80000000, v78
	v_mov_b32_e32 v94, v79
	v_pk_add_f32 v[78:79], v[80:81], v[128:129]
	v_pk_add_f32 v[80:81], v[80:81], v[128:129] neg_lo:[0,1] neg_hi:[0,1]
	s_nop 0
	v_pk_mul_f32 v[128:129], v[80:81], s[62:63] op_sel_hi:[1,0]
	v_xor_b32_e32 v139, 0x80000000, v80
	v_mov_b32_e32 v138, v81
	v_pk_fma_f32 v[80:81], v[138:139], s[60:61], v[128:129] op_sel_hi:[1,0,1] neg_lo:[0,0,1] neg_hi:[0,0,1]
	v_pk_add_f32 v[128:129], v[82:83], v[130:131]
	v_pk_add_f32 v[82:83], v[82:83], v[130:131] neg_lo:[0,1] neg_hi:[0,1]
	s_nop 0
	v_pk_mul_f32 v[130:131], v[82:83], s[70:71] op_sel_hi:[1,0]
	v_xor_b32_e32 v139, 0x80000000, v82
	v_mov_b32_e32 v138, v83
	v_pk_fma_f32 v[82:83], v[138:139], s[70:71], v[130:131] op_sel_hi:[1,0,1] neg_lo:[0,0,1] neg_hi:[0,0,1]
	v_pk_add_f32 v[130:131], v[84:85], v[132:133]
	v_pk_add_f32 v[84:85], v[84:85], v[132:133] neg_lo:[0,1] neg_hi:[0,1]
	s_nop 0
	v_pk_mul_f32 v[132:133], v[84:85], s[60:61] op_sel_hi:[1,0]
	v_xor_b32_e32 v139, 0x80000000, v84
	v_mov_b32_e32 v138, v85
	v_pk_fma_f32 v[84:85], v[138:139], s[62:63], v[132:133] op_sel_hi:[1,0,1] neg_lo:[0,0,1] neg_hi:[0,0,1]
	v_pk_add_f32 v[132:133], v[2:3], v[88:89]
	v_pk_add_f32 v[2:3], v[2:3], v[88:89] neg_lo:[0,1] neg_hi:[0,1]
	v_pk_add_f32 v[88:89], v[4:5], v[22:23]
	v_pk_add_f32 v[4:5], v[4:5], v[22:23] neg_lo:[0,1] neg_hi:[0,1]
	s_nop 0
	v_pk_mul_f32 v[22:23], v[4:5], s[62:63] op_sel:[1,0] op_sel_hi:[0,0] neg_hi:[1,0]
	s_nop 0
	v_pk_fma_f32 v[4:5], v[4:5], s[60:61], v[22:23] op_sel_hi:[1,0,1]
	v_pk_add_f32 v[22:23], v[6:7], v[24:25]
	v_pk_add_f32 v[6:7], v[6:7], v[24:25] neg_lo:[0,1] neg_hi:[0,1]
	s_nop 0
	v_pk_mul_f32 v[24:25], v[6:7], s[70:71] op_sel:[1,0] op_sel_hi:[0,0] neg_hi:[1,0]
	s_nop 0
	v_pk_fma_f32 v[6:7], v[6:7], s[70:71], v[24:25] op_sel_hi:[1,0,1]
	v_pk_add_f32 v[24:25], v[8:9], v[62:63]
	v_pk_add_f32 v[8:9], v[8:9], v[62:63] neg_lo:[0,1] neg_hi:[0,1]
	s_nop 0
	v_pk_mul_f32 v[62:63], v[8:9], s[60:61] op_sel:[1,0] op_sel_hi:[0,0] neg_hi:[1,0]
	s_nop 0
	v_pk_fma_f32 v[8:9], v[8:9], s[62:63], v[62:63] op_sel_hi:[1,0,1]
	v_pk_add_f32 v[62:63], v[10:11], v[64:65]
	v_pk_add_f32 v[10:11], v[10:11], v[64:65] neg_lo:[0,1] neg_hi:[0,1]
	s_nop 0
	v_xor_b32_e32 v65, 0x80000000, v10
	v_mov_b32_e32 v64, v11
	v_pk_add_f32 v[10:11], v[12:13], v[66:67]
	v_pk_add_f32 v[12:13], v[12:13], v[66:67] neg_lo:[0,1] neg_hi:[0,1]
	s_nop 0
	v_pk_mul_f32 v[66:67], v[12:13], s[62:63] op_sel_hi:[1,0]
	v_xor_b32_e32 v139, 0x80000000, v12
	v_mov_b32_e32 v138, v13
	v_pk_fma_f32 v[12:13], v[138:139], s[60:61], v[66:67] op_sel_hi:[1,0,1] neg_lo:[0,0,1] neg_hi:[0,0,1]
	v_pk_add_f32 v[66:67], v[14:15], v[68:69]
	v_pk_add_f32 v[14:15], v[14:15], v[68:69] neg_lo:[0,1] neg_hi:[0,1]
	s_nop 0
	v_pk_mul_f32 v[68:69], v[14:15], s[70:71] op_sel_hi:[1,0]
	v_xor_b32_e32 v139, 0x80000000, v14
	v_mov_b32_e32 v138, v15
	v_pk_fma_f32 v[14:15], v[138:139], s[70:71], v[68:69] op_sel_hi:[1,0,1] neg_lo:[0,0,1] neg_hi:[0,0,1]
	v_pk_add_f32 v[68:69], v[16:17], v[70:71]
	v_pk_add_f32 v[16:17], v[16:17], v[70:71] neg_lo:[0,1] neg_hi:[0,1]
	s_nop 0
	v_pk_mul_f32 v[70:71], v[16:17], s[60:61] op_sel_hi:[1,0]
	v_xor_b32_e32 v139, 0x80000000, v16
	v_mov_b32_e32 v138, v17
	v_pk_fma_f32 v[16:17], v[138:139], s[62:63], v[70:71] op_sel_hi:[1,0,1] neg_lo:[0,0,1] neg_hi:[0,0,1]
	v_pk_add_f32 v[70:71], v[134:135], v[92:93]
	v_pk_add_f32 v[92:93], v[134:135], v[92:93] neg_lo:[0,1] neg_hi:[0,1]
	v_pk_add_f32 v[134:135], v[136:137], v[78:79]
	v_pk_add_f32 v[78:79], v[136:137], v[78:79] neg_lo:[0,1] neg_hi:[0,1]
	s_nop 0
	v_pk_mul_f32 v[136:137], v[78:79], s[70:71] op_sel:[1,0] op_sel_hi:[0,0] neg_hi:[1,0]
	s_nop 0
	v_pk_fma_f32 v[78:79], v[78:79], s[70:71], v[136:137] op_sel_hi:[1,0,1]
	v_pk_add_f32 v[136:137], v[72:73], v[128:129]
	v_pk_add_f32 v[72:73], v[72:73], v[128:129] neg_lo:[0,1] neg_hi:[0,1]
	s_nop 0
	v_xor_b32_e32 v129, 0x80000000, v72
	v_mov_b32_e32 v128, v73
	v_pk_add_f32 v[72:73], v[90:91], v[130:131]
	v_pk_add_f32 v[90:91], v[90:91], v[130:131] neg_lo:[0,1] neg_hi:[0,1]
	s_nop 0
	v_pk_mul_f32 v[130:131], v[90:91], s[70:71] op_sel_hi:[1,0]
	v_xor_b32_e32 v139, 0x80000000, v90
	v_mov_b32_e32 v138, v91
	v_pk_fma_f32 v[90:91], v[138:139], s[70:71], v[130:131] op_sel_hi:[1,0,1] neg_lo:[0,0,1] neg_hi:[0,0,1]
	v_pk_add_f32 v[130:131], v[86:87], v[94:95]
	v_pk_add_f32 v[86:87], v[86:87], v[94:95] neg_lo:[0,1] neg_hi:[0,1]
	v_pk_add_f32 v[94:95], v[18:19], v[80:81]
	v_pk_add_f32 v[18:19], v[18:19], v[80:81] neg_lo:[0,1] neg_hi:[0,1]
	s_nop 0
	v_pk_mul_f32 v[80:81], v[18:19], s[70:71] op_sel:[1,0] op_sel_hi:[0,0] neg_hi:[1,0]
	s_nop 0
	v_pk_fma_f32 v[18:19], v[18:19], s[70:71], v[80:81] op_sel_hi:[1,0,1]
	v_pk_add_f32 v[80:81], v[74:75], v[82:83]
	v_pk_add_f32 v[74:75], v[74:75], v[82:83] neg_lo:[0,1] neg_hi:[0,1]
	s_nop 0
	v_xor_b32_e32 v83, 0x80000000, v74
	v_mov_b32_e32 v82, v75
	v_pk_add_f32 v[74:75], v[76:77], v[84:85]
	v_pk_add_f32 v[76:77], v[76:77], v[84:85] neg_lo:[0,1] neg_hi:[0,1]
	s_nop 0
	v_pk_mul_f32 v[84:85], v[76:77], s[70:71] op_sel_hi:[1,0]
	v_xor_b32_e32 v139, 0x80000000, v76
	v_mov_b32_e32 v138, v77
	v_pk_fma_f32 v[76:77], v[138:139], s[70:71], v[84:85] op_sel_hi:[1,0,1] neg_lo:[0,0,1] neg_hi:[0,0,1]
	v_pk_add_f32 v[84:85], v[132:133], v[62:63]
	v_pk_add_f32 v[62:63], v[132:133], v[62:63] neg_lo:[0,1] neg_hi:[0,1]
	v_pk_add_f32 v[132:133], v[88:89], v[10:11]
	v_pk_add_f32 v[10:11], v[88:89], v[10:11] neg_lo:[0,1] neg_hi:[0,1]
	s_nop 0
	v_pk_mul_f32 v[88:89], v[10:11], s[70:71] op_sel:[1,0] op_sel_hi:[0,0] neg_hi:[1,0]
	s_nop 0
	v_pk_fma_f32 v[10:11], v[10:11], s[70:71], v[88:89] op_sel_hi:[1,0,1]
	v_pk_add_f32 v[88:89], v[22:23], v[66:67]
	v_pk_add_f32 v[22:23], v[22:23], v[66:67] neg_lo:[0,1] neg_hi:[0,1]
	s_nop 0
	v_xor_b32_e32 v67, 0x80000000, v22
	v_mov_b32_e32 v66, v23
	v_pk_add_f32 v[22:23], v[24:25], v[68:69]
	v_pk_add_f32 v[24:25], v[24:25], v[68:69] neg_lo:[0,1] neg_hi:[0,1]
	s_nop 0
	v_pk_mul_f32 v[68:69], v[24:25], s[70:71] op_sel_hi:[1,0]
	v_xor_b32_e32 v139, 0x80000000, v24
	v_mov_b32_e32 v138, v25
	v_pk_fma_f32 v[24:25], v[138:139], s[70:71], v[68:69] op_sel_hi:[1,0,1] neg_lo:[0,0,1] neg_hi:[0,0,1]
	v_pk_add_f32 v[68:69], v[2:3], v[64:65]
	v_pk_add_f32 v[2:3], v[2:3], v[64:65] neg_lo:[0,1] neg_hi:[0,1]
	v_pk_add_f32 v[64:65], v[4:5], v[12:13]
	v_pk_add_f32 v[4:5], v[4:5], v[12:13] neg_lo:[0,1] neg_hi:[0,1]
	s_nop 0
	v_pk_mul_f32 v[12:13], v[4:5], s[70:71] op_sel:[1,0] op_sel_hi:[0,0] neg_hi:[1,0]
	s_nop 0
	v_pk_fma_f32 v[4:5], v[4:5], s[70:71], v[12:13] op_sel_hi:[1,0,1]
	v_pk_add_f32 v[12:13], v[6:7], v[14:15]
	v_pk_add_f32 v[6:7], v[6:7], v[14:15] neg_lo:[0,1] neg_hi:[0,1]
	v_pk_add_f32 v[140:141], v[68:69], v[12:13]
	v_xor_b32_e32 v15, 0x80000000, v6
	v_mov_b32_e32 v14, v7
	v_pk_add_f32 v[6:7], v[8:9], v[16:17]
	v_pk_add_f32 v[8:9], v[8:9], v[16:17] neg_lo:[0,1] neg_hi:[0,1]
	v_pk_add_f32 v[142:143], v[64:65], v[6:7]
	v_pk_mul_f32 v[16:17], v[8:9], s[70:71] op_sel_hi:[1,0]
	s_nop 0
	v_pk_fma_f32 v[8:9], v[8:9], s[70:71], v[16:17] op_sel:[1,0,0] op_sel_hi:[0,0,1] neg_lo:[0,0,1] neg_hi:[1,0,1]
	v_pk_add_f32 v[16:17], v[70:71], v[136:137]
	v_pk_add_f32 v[70:71], v[70:71], v[136:137] neg_lo:[0,1] neg_hi:[0,1]
	v_pk_add_f32 v[136:137], v[134:135], v[72:73]
	v_pk_add_f32 v[72:73], v[134:135], v[72:73] neg_lo:[0,1] neg_hi:[0,1]
	v_pk_add_f32 v[138:139], v[84:85], v[88:89] neg_lo:[0,1] neg_hi:[0,1]
	v_xor_b32_e32 v135, 0x80000000, v72
	v_mov_b32_e32 v134, v73
	v_pk_add_f32 v[72:73], v[92:93], v[128:129]
	v_pk_add_f32 v[92:93], v[92:93], v[128:129] neg_lo:[0,1] neg_hi:[0,1]
	v_pk_add_f32 v[128:129], v[78:79], v[90:91]
	v_pk_add_f32 v[78:79], v[78:79], v[90:91] neg_lo:[0,1] neg_hi:[0,1]
	v_pk_add_f32 v[6:7], v[64:65], v[6:7] neg_lo:[0,1] neg_hi:[0,1]
	v_xor_b32_e32 v91, 0x80000000, v78
	v_mov_b32_e32 v90, v79
	v_pk_add_f32 v[78:79], v[130:131], v[80:81]
	v_pk_add_f32 v[130:131], v[130:131], v[80:81] neg_lo:[0,1] neg_hi:[0,1]
	v_pk_add_f32 v[80:81], v[94:95], v[74:75]
	v_pk_add_f32 v[74:75], v[94:95], v[74:75] neg_lo:[0,1] neg_hi:[0,1]
	v_xor_b32_e32 v149, 0x80000000, v6
	v_xor_b32_e32 v95, 0x80000000, v74
	v_mov_b32_e32 v94, v75
	v_pk_add_f32 v[74:75], v[86:87], v[82:83]
	v_pk_add_f32 v[82:83], v[86:87], v[82:83] neg_lo:[0,1] neg_hi:[0,1]
	v_pk_add_f32 v[86:87], v[18:19], v[76:77]
	v_pk_add_f32 v[18:19], v[18:19], v[76:77] neg_lo:[0,1] neg_hi:[0,1]
	v_mov_b32_e32 v148, v7
	v_xor_b32_e32 v77, 0x80000000, v18
	v_mov_b32_e32 v76, v19
	v_pk_add_f32 v[18:19], v[84:85], v[88:89]
	v_pk_add_f32 v[88:89], v[132:133], v[22:23]
	v_pk_add_f32 v[22:23], v[132:133], v[22:23] neg_lo:[0,1] neg_hi:[0,1]
	v_pk_add_f32 v[6:7], v[2:3], v[14:15]
	v_xor_b32_e32 v133, 0x80000000, v22
	v_mov_b32_e32 v132, v23
	v_pk_add_f32 v[22:23], v[62:63], v[66:67]
	v_pk_add_f32 v[62:63], v[62:63], v[66:67] neg_lo:[0,1] neg_hi:[0,1]
	v_pk_add_f32 v[66:67], v[10:11], v[24:25]
	v_pk_add_f32 v[10:11], v[10:11], v[24:25] neg_lo:[0,1] neg_hi:[0,1]
	v_pk_add_f32 v[150:151], v[2:3], v[14:15] neg_lo:[0,1] neg_hi:[0,1]
	v_pk_add_f32 v[2:3], v[4:5], v[8:9] neg_lo:[0,1] neg_hi:[0,1]
	v_pk_add_f32 v[68:69], v[68:69], v[12:13] neg_lo:[0,1] neg_hi:[0,1]
	v_pk_add_f32 v[156:157], v[4:5], v[8:9]
	v_xor_b32_e32 v159, 0x80000000, v2
	v_mov_b32_e32 v158, v3
	v_pk_add_f32 v[2:3], v[16:17], v[136:137]
	v_pk_add_f32 v[84:85], v[16:17], v[136:137] neg_lo:[0,1] neg_hi:[0,1]
	v_pk_add_f32 v[136:137], v[70:71], v[134:135]
	v_pk_add_f32 v[16:17], v[70:71], v[134:135] neg_lo:[0,1] neg_hi:[0,1]
	v_pk_add_f32 v[134:135], v[72:73], v[128:129]
	v_pk_add_f32 v[70:71], v[72:73], v[128:129] neg_lo:[0,1] neg_hi:[0,1]
	v_pk_add_f32 v[128:129], v[92:93], v[90:91]
	v_pk_add_f32 v[8:9], v[92:93], v[90:91] neg_lo:[0,1] neg_hi:[0,1]
	v_pk_add_f32 v[72:73], v[78:79], v[80:81]
	v_pk_add_f32 v[80:81], v[78:79], v[80:81] neg_lo:[0,1] neg_hi:[0,1]
	v_pk_add_f32 v[92:93], v[130:131], v[94:95]
	v_pk_add_f32 v[12:13], v[130:131], v[94:95] neg_lo:[0,1] neg_hi:[0,1]
	v_pk_add_f32 v[78:79], v[74:75], v[86:87]
	v_pk_add_f32 v[64:65], v[74:75], v[86:87] neg_lo:[0,1] neg_hi:[0,1]
	v_pk_add_f32 v[130:131], v[82:83], v[76:77]
	v_pk_add_f32 v[4:5], v[82:83], v[76:77] neg_lo:[0,1] neg_hi:[0,1]
	v_pk_add_f32 v[76:77], v[18:19], v[88:89]
	v_pk_add_f32 v[88:89], v[18:19], v[88:89] neg_lo:[0,1] neg_hi:[0,1]
	v_pk_add_f32 v[86:87], v[138:139], v[132:133]
	v_pk_add_f32 v[18:19], v[138:139], v[132:133] neg_lo:[0,1] neg_hi:[0,1]
	v_pk_add_f32 v[132:133], v[62:63], v[10:11] op_sel:[0,1] op_sel_hi:[1,0] neg_hi:[0,1]
	v_pk_add_f32 v[10:11], v[62:63], v[10:11] op_sel:[0,1] op_sel_hi:[1,0] neg_lo:[0,1]
	v_pk_mul_f32 v[24:25], v[20:21], v[20:21]
	s_nop 0
	v_pk_add_f32 v[24:25], v[24:25], v[24:25] op_sel:[0,1] op_sel_hi:[0,1] neg_lo:[0,1] neg_hi:[0,1]
	v_pk_mul_f32 v[62:63], v[20:21], v[26:27] op_sel:[1,0] op_sel_hi:[0,0] neg_lo:[1,0]
	v_pk_add_f32 v[90:91], v[22:23], v[66:67]
	v_pk_add_f32 v[74:75], v[22:23], v[66:67] neg_lo:[0,1] neg_hi:[0,1]
	v_pk_add_f32 v[22:23], v[140:141], v[142:143]
	v_pk_add_f32 v[82:83], v[140:141], v[142:143] neg_lo:[0,1] neg_hi:[0,1]
	v_pk_add_f32 v[138:139], v[68:69], v[148:149]
	v_pk_add_f32 v[14:15], v[68:69], v[148:149] neg_lo:[0,1] neg_hi:[0,1]
	v_pk_fma_f32 v[68:69], v[20:21], v[24:25], v[62:63]
	v_mov_b32_e32 v142, v21
	s_nop 0
	v_pk_mul_f32 v[62:63], v[142:143], v[76:77] op_sel:[0,1] op_sel_hi:[0,0] neg_hi:[0,1]
	v_pk_fma_f32 v[20:21], v[20:21], v[76:77], v[62:63] op_sel_hi:[0,1,1]
	v_pk_mul_f32 v[62:63], v[26:27], s[48:49] op_sel_hi:[0,1]
	v_pk_fma_f32 v[76:77], v[24:25], s[40:41], v[62:63]
	s_nop 0
	v_pk_mul_f32 v[62:63], v[76:77], v[72:73] op_sel:[1,1] op_sel_hi:[1,0] neg_hi:[0,1]
	v_pk_add_f32 v[94:95], v[6:7], v[156:157]
	v_pk_fma_f32 v[62:63], v[72:73], v[76:77], v[62:63] op_sel_hi:[1,0,1]
	v_pk_mul_f32 v[72:73], v[26:27], v[68:69] op_sel:[0,1] op_sel_hi:[0,0] neg_lo:[0,1]
	v_pk_fma_f32 v[142:143], v[24:25], v[68:69], v[72:73]
	v_pk_mul_f32 v[72:73], v[68:69], v[22:23] op_sel:[1,1] op_sel_hi:[1,0] neg_hi:[0,1]
	v_pk_add_f32 v[140:141], v[150:151], v[158:159]
	v_pk_fma_f32 v[22:23], v[68:69], v[22:23], v[72:73] op_sel_hi:[0,1,1]
	v_pk_mul_f32 v[68:69], v[26:27], v[76:77] op_sel:[0,1] op_sel_hi:[0,0] neg_lo:[0,1]
	v_pk_fma_f32 v[76:77], v[24:25], v[76:77], v[68:69]
	s_nop 0
	v_pk_mul_f32 v[68:69], v[134:135], v[76:77] op_sel:[1,1] op_sel_hi:[0,1] neg_hi:[1,0]
	v_pk_add_f32 v[66:67], v[6:7], v[156:157] neg_lo:[0,1] neg_hi:[0,1]
	v_pk_fma_f32 v[72:73], v[134:135], v[76:77], v[68:69] op_sel_hi:[1,0,1]
	v_pk_mul_f32 v[68:69], v[26:27], v[142:143] op_sel:[0,1] op_sel_hi:[0,0] neg_lo:[0,1]
	v_pk_fma_f32 v[134:135], v[24:25], v[142:143], v[68:69]
	v_pk_mul_f32 v[68:69], v[142:143], v[90:91] op_sel:[1,1] op_sel_hi:[1,0] neg_hi:[0,1]
	v_pk_add_f32 v[6:7], v[150:151], v[158:159] neg_lo:[0,1] neg_hi:[0,1]
	v_pk_fma_f32 v[68:69], v[90:91], v[142:143], v[68:69] op_sel_hi:[1,0,1]
	v_pk_mul_f32 v[90:91], v[26:27], v[76:77] op_sel:[0,1] op_sel_hi:[0,0] neg_lo:[0,1]
	v_pk_fma_f32 v[90:91], v[24:25], v[76:77], v[90:91]
	s_nop 0
	v_pk_mul_f32 v[76:77], v[78:79], v[90:91] op_sel:[1,1] op_sel_hi:[0,1] neg_hi:[1,0]
	s_nop 0
	v_pk_fma_f32 v[78:79], v[78:79], v[90:91], v[76:77] op_sel_hi:[1,0,1]
	v_pk_mul_f32 v[76:77], v[26:27], v[134:135] op_sel:[0,1] op_sel_hi:[0,0] neg_lo:[0,1]
	v_pk_fma_f32 v[142:143], v[24:25], v[134:135], v[76:77]
	v_pk_mul_f32 v[76:77], v[134:135], v[94:95] op_sel:[1,1] op_sel_hi:[1,0] neg_hi:[0,1]
	s_nop 0
	v_pk_fma_f32 v[76:77], v[94:95], v[134:135], v[76:77] op_sel_hi:[1,0,1]
	v_pk_mul_f32 v[94:95], v[26:27], v[90:91] op_sel:[0,1] op_sel_hi:[0,0] neg_lo:[0,1]
	v_pk_fma_f32 v[94:95], v[24:25], v[90:91], v[94:95]
	s_nop 0
	v_pk_mul_f32 v[90:91], v[136:137], v[94:95] op_sel:[1,1] op_sel_hi:[0,1] neg_hi:[1,0]
	v_xor_b32_e32 v134, 0x80000000, v143
	v_pk_fma_f32 v[90:91], v[136:137], v[94:95], v[90:91] op_sel_hi:[1,0,1]
	v_pk_mul_f32 v[136:137], v[86:87], v[142:143] op_sel:[1,1] op_sel_hi:[0,1] neg_hi:[1,0]
	v_mov_b32_e32 v135, v142
	v_pk_fma_f32 v[86:87], v[86:87], v[142:143], v[136:137] op_sel_hi:[1,0,1]
	v_pk_mul_f32 v[136:137], v[26:27], v[94:95] op_sel:[0,1] op_sel_hi:[0,0] neg_lo:[0,1]
	v_pk_mul_f32 v[134:135], v[26:27], v[134:135] op_sel_hi:[0,1]
	v_pk_fma_f32 v[136:137], v[24:25], v[94:95], v[136:137]
	v_pk_fma_f32 v[134:135], v[24:25], v[142:143], v[134:135]
	v_pk_mul_f32 v[94:95], v[92:93], v[136:137] op_sel:[1,1] op_sel_hi:[0,1] neg_hi:[1,0]
	s_nop 0
	v_pk_fma_f32 v[94:95], v[92:93], v[136:137], v[94:95] op_sel_hi:[1,0,1]
	v_pk_mul_f32 v[92:93], v[26:27], v[134:135] op_sel:[0,1] op_sel_hi:[0,0] neg_lo:[0,1]
	v_pk_fma_f32 v[142:143], v[24:25], v[134:135], v[92:93]
	v_pk_mul_f32 v[92:93], v[138:139], v[134:135] op_sel:[1,1] op_sel_hi:[0,1] neg_hi:[1,0]
	s_nop 0
	v_pk_fma_f32 v[92:93], v[138:139], v[134:135], v[92:93] op_sel_hi:[1,0,1]
	v_pk_mul_f32 v[134:135], v[26:27], v[136:137] op_sel:[0,1] op_sel_hi:[0,0] neg_lo:[0,1]
	s_nop 0
	v_pk_fma_f32 v[134:135], v[24:25], v[136:137], v[134:135]
	v_pk_mul_f32 v[138:139], v[132:133], v[142:143] op_sel:[1,1] op_sel_hi:[0,1] neg_hi:[1,0]
	v_pk_mul_f32 v[136:137], v[128:129], v[134:135] op_sel:[1,1] op_sel_hi:[0,1] neg_hi:[1,0]
	v_pk_fma_f32 v[132:133], v[132:133], v[142:143], v[138:139] op_sel_hi:[1,0,1]
	v_pk_fma_f32 v[128:129], v[128:129], v[134:135], v[136:137] op_sel_hi:[1,0,1]
	v_pk_mul_f32 v[138:139], v[26:27], v[134:135] op_sel:[0,1] op_sel_hi:[0,0] neg_lo:[0,1]
	v_pk_mul_f32 v[136:137], v[26:27], v[142:143] op_sel:[0,1] op_sel_hi:[0,0] neg_lo:[0,1]
	v_pk_fma_f32 v[134:135], v[24:25], v[134:135], v[138:139]
	v_pk_fma_f32 v[136:137], v[24:25], v[142:143], v[136:137]
	v_pk_mul_f32 v[138:139], v[130:131], v[134:135] op_sel:[1,1] op_sel_hi:[0,1] neg_hi:[1,0]
	s_nop 0
	v_pk_fma_f32 v[130:131], v[130:131], v[134:135], v[138:139] op_sel_hi:[1,0,1]
	v_pk_mul_f32 v[138:139], v[26:27], v[136:137] op_sel:[0,1] op_sel_hi:[0,0] neg_lo:[0,1]
	v_pk_mul_f32 v[142:143], v[140:141], v[136:137] op_sel:[1,1] op_sel_hi:[0,1] neg_hi:[1,0]
	v_pk_fma_f32 v[138:139], v[24:25], v[136:137], v[138:139]
	v_pk_fma_f32 v[136:137], v[140:141], v[136:137], v[142:143] op_sel_hi:[1,0,1]
	v_pk_mul_f32 v[140:141], v[26:27], v[134:135] op_sel:[0,1] op_sel_hi:[0,0] neg_lo:[0,1]
	v_pk_fma_f32 v[134:135], v[24:25], v[134:135], v[140:141]
	s_nop 0
	v_pk_mul_f32 v[140:141], v[84:85], v[134:135] op_sel:[1,1] op_sel_hi:[0,1] neg_hi:[1,0]
	s_nop 0
	v_pk_fma_f32 v[84:85], v[84:85], v[134:135], v[140:141] op_sel_hi:[1,0,1]
	v_pk_mul_f32 v[140:141], v[26:27], v[138:139] op_sel:[0,1] op_sel_hi:[0,0] neg_lo:[0,1]
	v_pk_mul_f32 v[142:143], v[88:89], v[138:139] op_sel:[1,1] op_sel_hi:[0,1] neg_hi:[1,0]
	v_pk_fma_f32 v[140:141], v[24:25], v[138:139], v[140:141]
	v_pk_fma_f32 v[88:89], v[88:89], v[138:139], v[142:143] op_sel_hi:[1,0,1]
	v_pk_mul_f32 v[138:139], v[26:27], v[134:135] op_sel:[0,1] op_sel_hi:[0,0] neg_lo:[0,1]
	v_pk_fma_f32 v[134:135], v[24:25], v[134:135], v[138:139]
	s_nop 0
	v_pk_mul_f32 v[138:139], v[80:81], v[134:135] op_sel:[1,1] op_sel_hi:[0,1] neg_hi:[1,0]
	s_nop 0
	v_pk_fma_f32 v[80:81], v[80:81], v[134:135], v[138:139] op_sel_hi:[1,0,1]
	v_pk_mul_f32 v[138:139], v[26:27], v[140:141] op_sel:[0,1] op_sel_hi:[0,0] neg_lo:[0,1]
	v_pk_mul_f32 v[142:143], v[82:83], v[140:141] op_sel:[1,1] op_sel_hi:[0,1] neg_hi:[1,0]
	v_pk_fma_f32 v[138:139], v[24:25], v[140:141], v[138:139]
	v_pk_fma_f32 v[82:83], v[82:83], v[140:141], v[142:143] op_sel_hi:[1,0,1]
	v_pk_mul_f32 v[140:141], v[26:27], v[134:135] op_sel:[0,1] op_sel_hi:[0,0] neg_lo:[0,1]
	v_pk_fma_f32 v[134:135], v[24:25], v[134:135], v[140:141]
	s_nop 0
	v_pk_mul_f32 v[140:141], v[70:71], v[134:135] op_sel:[1,1] op_sel_hi:[0,1] neg_hi:[1,0]
	s_nop 0
	v_pk_fma_f32 v[70:71], v[70:71], v[134:135], v[140:141] op_sel_hi:[1,0,1]
	v_pk_mul_f32 v[140:141], v[26:27], v[138:139] op_sel:[0,1] op_sel_hi:[0,0] neg_lo:[0,1]
	v_pk_mul_f32 v[142:143], v[74:75], v[138:139] op_sel:[1,1] op_sel_hi:[0,1] neg_hi:[1,0]
	v_pk_fma_f32 v[140:141], v[24:25], v[138:139], v[140:141]
	v_pk_fma_f32 v[74:75], v[74:75], v[138:139], v[142:143] op_sel_hi:[1,0,1]
	v_pk_mul_f32 v[138:139], v[26:27], v[134:135] op_sel:[0,1] op_sel_hi:[0,0] neg_lo:[0,1]
	v_pk_fma_f32 v[134:135], v[24:25], v[134:135], v[138:139]
	s_nop 0
	v_pk_mul_f32 v[138:139], v[64:65], v[134:135] op_sel:[1,1] op_sel_hi:[0,1] neg_hi:[1,0]
	s_nop 0
	v_pk_fma_f32 v[64:65], v[64:65], v[134:135], v[138:139] op_sel_hi:[1,0,1]
	v_pk_mul_f32 v[138:139], v[26:27], v[140:141] op_sel:[0,1] op_sel_hi:[0,0] neg_lo:[0,1]
	v_pk_mul_f32 v[142:143], v[66:67], v[140:141] op_sel:[1,1] op_sel_hi:[0,1] neg_hi:[1,0]
	v_pk_fma_f32 v[138:139], v[24:25], v[140:141], v[138:139]
	v_pk_fma_f32 v[66:67], v[66:67], v[140:141], v[142:143] op_sel_hi:[1,0,1]
	v_pk_mul_f32 v[140:141], v[26:27], v[134:135] op_sel:[0,1] op_sel_hi:[0,0] neg_lo:[0,1]
	v_pk_fma_f32 v[134:135], v[24:25], v[134:135], v[140:141]
	s_nop 0
	v_pk_mul_f32 v[140:141], v[16:17], v[134:135] op_sel:[1,1] op_sel_hi:[0,1] neg_hi:[1,0]
	s_nop 0
	v_pk_fma_f32 v[16:17], v[16:17], v[134:135], v[140:141] op_sel_hi:[1,0,1]
	v_pk_mul_f32 v[140:141], v[26:27], v[138:139] op_sel:[0,1] op_sel_hi:[0,0] neg_lo:[0,1]
	v_pk_mul_f32 v[142:143], v[18:19], v[138:139] op_sel:[1,1] op_sel_hi:[0,1] neg_hi:[1,0]
	v_pk_fma_f32 v[140:141], v[24:25], v[138:139], v[140:141]
	v_pk_fma_f32 v[18:19], v[18:19], v[138:139], v[142:143] op_sel_hi:[1,0,1]
	v_pk_mul_f32 v[138:139], v[26:27], v[134:135] op_sel:[0,1] op_sel_hi:[0,0] neg_lo:[0,1]
	v_pk_fma_f32 v[134:135], v[24:25], v[134:135], v[138:139]
	s_nop 0
	v_pk_mul_f32 v[138:139], v[12:13], v[134:135] op_sel:[1,1] op_sel_hi:[0,1] neg_hi:[1,0]
	s_nop 0
	v_pk_fma_f32 v[12:13], v[12:13], v[134:135], v[138:139] op_sel_hi:[1,0,1]
	v_pk_mul_f32 v[138:139], v[26:27], v[140:141] op_sel:[0,1] op_sel_hi:[0,0] neg_lo:[0,1]
	v_pk_mul_f32 v[142:143], v[14:15], v[140:141] op_sel:[1,1] op_sel_hi:[0,1] neg_hi:[1,0]
	v_pk_fma_f32 v[138:139], v[24:25], v[140:141], v[138:139]
	v_pk_fma_f32 v[14:15], v[14:15], v[140:141], v[142:143] op_sel_hi:[1,0,1]
	v_pk_mul_f32 v[140:141], v[26:27], v[134:135] op_sel:[0,1] op_sel_hi:[0,0] neg_lo:[0,1]
	v_pk_fma_f32 v[134:135], v[24:25], v[134:135], v[140:141]
	s_nop 0
	v_pk_mul_f32 v[140:141], v[8:9], v[134:135] op_sel:[1,1] op_sel_hi:[0,1] neg_hi:[1,0]
	s_nop 0
	v_pk_fma_f32 v[8:9], v[8:9], v[134:135], v[140:141] op_sel_hi:[1,0,1]
	v_pk_mul_f32 v[140:141], v[26:27], v[138:139] op_sel:[0,1] op_sel_hi:[0,0] neg_lo:[0,1]
	v_pk_mul_f32 v[142:143], v[10:11], v[138:139] op_sel:[1,1] op_sel_hi:[0,1] neg_hi:[1,0]
	v_pk_fma_f32 v[140:141], v[24:25], v[138:139], v[140:141]
	v_pk_fma_f32 v[10:11], v[10:11], v[138:139], v[142:143] op_sel_hi:[1,0,1]
	v_pk_mul_f32 v[138:139], v[26:27], v[134:135] op_sel:[0,1] op_sel_hi:[0,0] neg_lo:[0,1]
	v_pk_fma_f32 v[24:25], v[24:25], v[134:135], v[138:139]
	s_nop 0
	v_pk_mul_f32 v[134:135], v[4:5], v[24:25] op_sel:[1,1] op_sel_hi:[0,1] neg_hi:[1,0]
	s_nop 0
	v_pk_fma_f32 v[4:5], v[4:5], v[24:25], v[134:135] op_sel_hi:[1,0,1]
	v_pk_mul_f32 v[24:25], v[6:7], v[140:141] op_sel:[1,1] op_sel_hi:[0,1] neg_hi:[1,0]
	s_nop 0
	v_pk_fma_f32 v[6:7], v[6:7], v[140:141], v[24:25] op_sel_hi:[1,0,1]
	ds_write_b64 v27, v[2:3]
	ds_write_b64 v96, v[84:85]
	ds_write_b64 v97, v[90:91] offset:256
	ds_write_b64 v98, v[16:17] offset:256
	ds_write_b64 v99, v[72:73] offset:512
	ds_write_b64 v100, v[70:71] offset:512
	ds_write_b64 v101, v[128:129] offset:768
	ds_write_b64 v102, v[8:9] offset:768
	ds_write_b64 v103, v[62:63] offset:1024
	ds_write_b64 v104, v[80:81] offset:1024
	ds_write_b64 v105, v[94:95] offset:1280
	ds_write_b64 v106, v[12:13] offset:1280
	ds_write_b64 v107, v[78:79] offset:1536
	ds_write_b64 v108, v[64:65] offset:1536
	ds_write_b64 v109, v[130:131] offset:1792
	ds_write_b64 v110, v[4:5] offset:1792
	ds_write_b64 v111, v[20:21] offset:2048
	ds_write_b64 v112, v[88:89] offset:2048
	ds_write_b64 v113, v[86:87] offset:2304
	ds_write_b64 v114, v[18:19] offset:2304
	ds_write_b64 v115, v[68:69] offset:2560
	ds_write_b64 v116, v[74:75] offset:2560
	ds_write_b64 v117, v[132:133] offset:2816
	ds_write_b64 v118, v[10:11] offset:2816
	ds_write_b64 v119, v[22:23] offset:3072
	ds_write_b64 v120, v[82:83] offset:3072
	ds_write_b64 v121, v[92:93] offset:3328
	ds_write_b64 v122, v[14:15] offset:3328
	ds_write_b64 v123, v[76:77] offset:3584
	ds_write_b64 v124, v[66:67] offset:3584
	ds_write_b64 v125, v[136:137] offset:3840
	ds_write_b64 v126, v[6:7] offset:3840
	v_mov_b32_e32 v2, v146
	s_waitcnt lgkmcnt(0)
	s_barrier
	s_nop 0
	v_lshlrev_b32_e32 v3, 4, v2
	v_lshrrev_b32_e32 v4, 1, v2
	v_bfe_u32 v2, v2, 1, 4
	v_bitop3_b32 v5, v4, v3, 16 bitop3:0x6c
	v_lshl_add_u32 v5, v5, 3, 16
	v_lshlrev_b32_e32 v2, 3, v2
	v_add_u32_e32 v6, v5, v2
	ds_read_b64 v[12:13], v6
	v_bitop3_b32 v6, v4, 1, 15 bitop3:0x6c
	v_lshlrev_b32_e32 v8, 3, v6
	v_add_u32_e32 v6, v5, v8
	ds_read_b64 v[14:15], v6
	v_bitop3_b32 v6, v4, 2, 15 bitop3:0x6c
	v_lshlrev_b32_e32 v9, 3, v6
	v_add_u32_e32 v6, v5, v9
	ds_read_b64 v[16:17], v6
	v_bitop3_b32 v6, v4, 3, 15 bitop3:0x6c
	v_lshlrev_b32_e32 v10, 3, v6
	v_add_u32_e32 v6, v5, v10
	ds_read_b64 v[18:19], v6
	v_bitop3_b32 v6, v4, 4, 15 bitop3:0x6c
	v_lshlrev_b32_e32 v11, 3, v6
	v_add_u32_e32 v6, v5, v11
	ds_read_b64 v[20:21], v6
	v_bitop3_b32 v6, v4, 5, 15 bitop3:0x6c
	v_lshlrev_b32_e32 v82, 3, v6
	v_add_u32_e32 v6, v5, v82
	ds_read_b64 v[22:23], v6
	v_bitop3_b32 v6, v4, 6, 15 bitop3:0x6c
	v_lshlrev_b32_e32 v83, 3, v6
	v_add_u32_e32 v6, v5, v83
	ds_read_b64 v[24:25], v6
	v_bitop3_b32 v6, v4, 7, 15 bitop3:0x6c
	v_lshlrev_b32_e32 v84, 3, v6
	v_add_u32_e32 v6, v5, v84
	ds_read_b64 v[26:27], v6
	v_bitop3_b32 v6, v4, 8, 15 bitop3:0x6c
	v_lshlrev_b32_e32 v85, 3, v6
	v_add_u32_e32 v6, v5, v85
	ds_read_b64 v[62:63], v6
	v_bitop3_b32 v6, v4, 9, 15 bitop3:0x6c
	v_lshlrev_b32_e32 v86, 3, v6
	v_add_u32_e32 v6, v5, v86
	ds_read_b64 v[64:65], v6
	v_bitop3_b32 v6, v4, 10, 15 bitop3:0x6c
	v_lshlrev_b32_e32 v87, 3, v6
	v_add_u32_e32 v6, v5, v87
	ds_read_b64 v[66:67], v6
	v_bitop3_b32 v6, v4, 11, 15 bitop3:0x6c
	v_lshlrev_b32_e32 v88, 3, v6
	v_add_u32_e32 v6, v5, v88
	ds_read_b64 v[68:69], v6
	v_bitop3_b32 v6, v4, 12, 15 bitop3:0x6c
	v_lshlrev_b32_e32 v89, 3, v6
	v_add_u32_e32 v6, v5, v89
	ds_read_b64 v[70:71], v6
	v_bitop3_b32 v6, v4, 13, 15 bitop3:0x6c
	v_lshlrev_b32_e32 v90, 3, v6
	v_add_u32_e32 v6, v5, v90
	ds_read_b64 v[72:73], v6
	v_bitop3_b32 v6, v4, 14, 15 bitop3:0x6c
	v_lshlrev_b32_e32 v91, 3, v6
	v_add_u32_e32 v6, v5, v91
	v_add_u32_e32 v3, 0x2000, v3
	ds_read_b64 v[74:75], v6
	v_bitop3_b32 v6, v4, 15, v4 bitop3:0xc
	v_bitop3_b32 v3, v3, v4, 16 bitop3:0x78
	v_lshlrev_b32_e32 v106, 3, v6
	v_lshl_add_u32 v107, v3, 3, 16
	v_add_u32_e32 v5, v5, v106
	v_add_u32_e32 v2, v107, v2
	ds_read_b64 v[76:77], v5
	ds_read_b64 v[6:7], v2
	v_add_u32_e32 v2, v107, v8
	ds_read_b64 v[78:79], v2
	v_add_u32_e32 v2, v107, v9
	ds_read_b64 v[8:9], v2
	v_add_u32_e32 v2, v107, v10
	ds_read_b64 v[80:81], v2
	v_add_u32_e32 v2, v107, v11
	ds_read_b64 v[10:11], v2
	v_add_u32_e32 v2, v107, v82
	v_add_u32_e32 v82, v107, v84
	v_add_u32_e32 v84, v107, v85
	ds_read_b64 v[4:5], v2
	ds_read_b64 v[92:93], v84
	v_add_u32_e32 v2, v107, v83
	v_add_u32_e32 v84, v107, v86
	ds_read_b64 v[2:3], v2
	ds_read_b64 v[82:83], v82
	ds_read_b64 v[94:95], v84
	v_add_u32_e32 v84, v107, v87
	ds_read_b64 v[96:97], v84
	v_add_u32_e32 v84, v107, v88
	ds_read_b64 v[98:99], v84
	v_add_u32_e32 v84, v107, v89
	ds_read_b64 v[100:101], v84
	v_add_u32_e32 v84, v107, v90
	ds_read_b64 v[102:103], v84
	v_add_u32_e32 v84, v107, v91
	ds_read_b64 v[104:105], v84
	v_add_u32_e32 v84, v107, v106
	ds_read_b64 v[106:107], v84
	s_waitcnt lgkmcnt(14)
	v_pk_add_f32 v[84:85], v[12:13], v[62:63]
	v_pk_add_f32 v[12:13], v[12:13], v[62:63] neg_lo:[0,1] neg_hi:[0,1]
	v_pk_add_f32 v[62:63], v[14:15], v[64:65]
	v_pk_add_f32 v[14:15], v[14:15], v[64:65] neg_lo:[0,1] neg_hi:[0,1]
	s_nop 0
	v_pk_mul_f32 v[64:65], v[14:15], s[62:63] op_sel:[1,0] op_sel_hi:[0,0] neg_hi:[1,0]
	s_nop 0
	v_pk_fma_f32 v[14:15], v[14:15], s[60:61], v[64:65] op_sel_hi:[1,0,1]
	v_pk_add_f32 v[64:65], v[16:17], v[66:67]
	v_pk_add_f32 v[16:17], v[16:17], v[66:67] neg_lo:[0,1] neg_hi:[0,1]
	s_nop 0
	v_pk_mul_f32 v[66:67], v[16:17], s[70:71] op_sel:[1,0] op_sel_hi:[0,0] neg_hi:[1,0]
	s_nop 0
	v_pk_fma_f32 v[16:17], v[16:17], s[70:71], v[66:67] op_sel_hi:[1,0,1]
	v_pk_add_f32 v[66:67], v[18:19], v[68:69]
	v_pk_add_f32 v[18:19], v[18:19], v[68:69] neg_lo:[0,1] neg_hi:[0,1]
	s_nop 0
	v_pk_mul_f32 v[68:69], v[18:19], s[60:61] op_sel:[1,0] op_sel_hi:[0,0] neg_hi:[1,0]
	s_nop 0
	v_pk_fma_f32 v[18:19], v[18:19], s[62:63], v[68:69] op_sel_hi:[1,0,1]
	v_pk_add_f32 v[68:69], v[20:21], v[70:71]
	v_pk_add_f32 v[20:21], v[20:21], v[70:71] neg_lo:[0,1] neg_hi:[0,1]
	s_nop 0
	v_xor_b32_e32 v71, 0x80000000, v20
	v_mov_b32_e32 v70, v21
	v_pk_add_f32 v[20:21], v[22:23], v[72:73]
	v_pk_add_f32 v[22:23], v[22:23], v[72:73] neg_lo:[0,1] neg_hi:[0,1]
	s_nop 0
	v_pk_mul_f32 v[72:73], v[22:23], s[62:63] op_sel_hi:[1,0]
	v_xor_b32_e32 v87, 0x80000000, v22
	v_mov_b32_e32 v86, v23
	v_pk_fma_f32 v[22:23], v[86:87], s[60:61], v[72:73] op_sel_hi:[1,0,1] neg_lo:[0,0,1] neg_hi:[0,0,1]
	v_pk_add_f32 v[72:73], v[24:25], v[74:75]
	v_pk_add_f32 v[24:25], v[24:25], v[74:75] neg_lo:[0,1] neg_hi:[0,1]
	s_nop 0
	v_pk_mul_f32 v[74:75], v[24:25], s[70:71] op_sel_hi:[1,0]
	v_xor_b32_e32 v87, 0x80000000, v24
	v_mov_b32_e32 v86, v25
	v_pk_fma_f32 v[24:25], v[86:87], s[70:71], v[74:75] op_sel_hi:[1,0,1] neg_lo:[0,0,1] neg_hi:[0,0,1]
	v_pk_add_f32 v[74:75], v[26:27], v[76:77]
	v_pk_add_f32 v[26:27], v[26:27], v[76:77] neg_lo:[0,1] neg_hi:[0,1]
	s_nop 0
	v_pk_mul_f32 v[76:77], v[26:27], s[60:61] op_sel_hi:[1,0]
	v_xor_b32_e32 v87, 0x80000000, v26
	v_mov_b32_e32 v86, v27
	v_pk_fma_f32 v[26:27], v[86:87], s[62:63], v[76:77] op_sel_hi:[1,0,1] neg_lo:[0,0,1] neg_hi:[0,0,1]
	v_pk_add_f32 v[76:77], v[84:85], v[68:69]
	v_pk_add_f32 v[68:69], v[84:85], v[68:69] neg_lo:[0,1] neg_hi:[0,1]
	v_pk_add_f32 v[84:85], v[62:63], v[20:21]
	v_pk_add_f32 v[20:21], v[62:63], v[20:21] neg_lo:[0,1] neg_hi:[0,1]
	s_nop 0
	v_pk_mul_f32 v[62:63], v[20:21], s[70:71] op_sel:[1,0] op_sel_hi:[0,0] neg_hi:[1,0]
	s_nop 0
	v_pk_fma_f32 v[20:21], v[20:21], s[70:71], v[62:63] op_sel_hi:[1,0,1]
	v_pk_add_f32 v[62:63], v[64:65], v[72:73]
	v_pk_add_f32 v[64:65], v[64:65], v[72:73] neg_lo:[0,1] neg_hi:[0,1]
	s_nop 0
	v_xor_b32_e32 v73, 0x80000000, v64
	v_mov_b32_e32 v72, v65
	v_pk_add_f32 v[64:65], v[66:67], v[74:75]
	v_pk_add_f32 v[66:67], v[66:67], v[74:75] neg_lo:[0,1] neg_hi:[0,1]
	s_nop 0
	v_pk_mul_f32 v[74:75], v[66:67], s[70:71] op_sel_hi:[1,0]
	v_xor_b32_e32 v87, 0x80000000, v66
	v_mov_b32_e32 v86, v67
	v_pk_fma_f32 v[66:67], v[86:87], s[70:71], v[74:75] op_sel_hi:[1,0,1] neg_lo:[0,0,1] neg_hi:[0,0,1]
	v_pk_add_f32 v[74:75], v[12:13], v[70:71]
	v_pk_add_f32 v[12:13], v[12:13], v[70:71] neg_lo:[0,1] neg_hi:[0,1]
	v_pk_add_f32 v[70:71], v[14:15], v[22:23]
	v_pk_add_f32 v[14:15], v[14:15], v[22:23] neg_lo:[0,1] neg_hi:[0,1]
	s_nop 0
	v_pk_mul_f32 v[22:23], v[14:15], s[70:71] op_sel:[1,0] op_sel_hi:[0,0] neg_hi:[1,0]
	s_nop 0
	v_pk_fma_f32 v[14:15], v[14:15], s[70:71], v[22:23] op_sel_hi:[1,0,1]
	v_pk_add_f32 v[22:23], v[16:17], v[24:25]
	v_pk_add_f32 v[16:17], v[16:17], v[24:25] neg_lo:[0,1] neg_hi:[0,1]
	s_nop 0
	v_xor_b32_e32 v25, 0x80000000, v16
	v_mov_b32_e32 v24, v17
	v_pk_add_f32 v[16:17], v[18:19], v[26:27]
	v_pk_add_f32 v[18:19], v[18:19], v[26:27] neg_lo:[0,1] neg_hi:[0,1]
	v_pk_add_f32 v[108:109], v[12:13], v[24:25]
	v_pk_mul_f32 v[26:27], v[18:19], s[70:71] op_sel_hi:[1,0]
	s_nop 0
	v_pk_fma_f32 v[18:19], v[18:19], s[70:71], v[26:27] op_sel:[1,0,0] op_sel_hi:[0,0,1] neg_lo:[0,0,1] neg_hi:[1,0,1]
	v_pk_add_f32 v[26:27], v[76:77], v[62:63]
	v_pk_add_f32 v[62:63], v[76:77], v[62:63] neg_lo:[0,1] neg_hi:[0,1]
	v_pk_add_f32 v[76:77], v[84:85], v[64:65]
	v_pk_add_f32 v[64:65], v[84:85], v[64:65] neg_lo:[0,1] neg_hi:[0,1]
	v_pk_add_f32 v[110:111], v[12:13], v[24:25] neg_lo:[0,1] neg_hi:[0,1]
	v_xor_b32_e32 v85, 0x80000000, v64
	v_mov_b32_e32 v84, v65
	v_pk_add_f32 v[64:65], v[68:69], v[72:73]
	v_pk_add_f32 v[68:69], v[68:69], v[72:73] neg_lo:[0,1] neg_hi:[0,1]
	v_pk_add_f32 v[72:73], v[20:21], v[66:67]
	v_pk_add_f32 v[20:21], v[20:21], v[66:67] neg_lo:[0,1] neg_hi:[0,1]
	v_pk_add_f32 v[12:13], v[14:15], v[18:19] neg_lo:[0,1] neg_hi:[0,1]
	v_pk_add_f32 v[112:113], v[14:15], v[18:19]
	v_xor_b32_e32 v115, 0x80000000, v12
	v_mov_b32_e32 v114, v13
	v_pk_add_f32 v[12:13], v[26:27], v[76:77]
	v_pk_add_f32 v[14:15], v[26:27], v[76:77] neg_lo:[0,1] neg_hi:[0,1]
	v_pk_add_f32 v[24:25], v[68:69], v[20:21] op_sel:[0,1] op_sel_hi:[1,0] neg_hi:[0,1]
	v_pk_add_f32 v[26:27], v[68:69], v[20:21] op_sel:[0,1] op_sel_hi:[1,0] neg_lo:[0,1]
	s_waitcnt lgkmcnt(6)
	v_pk_add_f32 v[66:67], v[78:79], v[94:95] neg_lo:[0,1] neg_hi:[0,1]
	v_pk_add_f32 v[86:87], v[74:75], v[22:23]
	v_pk_mul_f32 v[76:77], v[66:67], s[62:63] op_sel:[1,0] op_sel_hi:[0,0] neg_hi:[1,0]
	v_pk_add_f32 v[74:75], v[74:75], v[22:23] neg_lo:[0,1] neg_hi:[0,1]
	v_pk_fma_f32 v[66:67], v[66:67], s[60:61], v[76:77] op_sel_hi:[1,0,1]
	s_waitcnt lgkmcnt(5)
	v_pk_add_f32 v[76:77], v[8:9], v[96:97]
	v_pk_add_f32 v[8:9], v[8:9], v[96:97] neg_lo:[0,1] neg_hi:[0,1]
	v_pk_add_f32 v[20:21], v[64:65], v[72:73]
	v_pk_add_f32 v[22:23], v[64:65], v[72:73] neg_lo:[0,1] neg_hi:[0,1]
	v_pk_add_f32 v[64:65], v[78:79], v[94:95]
	v_pk_mul_f32 v[78:79], v[8:9], s[70:71] op_sel:[1,0] op_sel_hi:[0,0] neg_hi:[1,0]
	v_pk_add_f32 v[88:89], v[70:71], v[16:17]
	v_pk_add_f32 v[16:17], v[70:71], v[16:17] neg_lo:[0,1] neg_hi:[0,1]
	v_pk_fma_f32 v[8:9], v[8:9], s[70:71], v[78:79] op_sel_hi:[1,0,1]
	s_waitcnt lgkmcnt(4)
	v_pk_add_f32 v[78:79], v[80:81], v[98:99]
	v_pk_add_f32 v[80:81], v[80:81], v[98:99] neg_lo:[0,1] neg_hi:[0,1]
	v_xor_b32_e32 v91, 0x80000000, v16
	v_mov_b32_e32 v90, v17
	v_pk_add_f32 v[16:17], v[62:63], v[84:85]
	v_pk_add_f32 v[18:19], v[62:63], v[84:85] neg_lo:[0,1] neg_hi:[0,1]
	v_pk_add_f32 v[62:63], v[6:7], v[92:93]
	v_pk_add_f32 v[6:7], v[6:7], v[92:93] neg_lo:[0,1] neg_hi:[0,1]
	v_pk_mul_f32 v[92:93], v[80:81], s[60:61] op_sel:[1,0] op_sel_hi:[0,0] neg_hi:[1,0]
	v_pk_add_f32 v[68:69], v[86:87], v[88:89]
	v_pk_fma_f32 v[80:81], v[80:81], s[62:63], v[92:93] op_sel_hi:[1,0,1]
	s_waitcnt lgkmcnt(3)
	v_pk_add_f32 v[92:93], v[10:11], v[100:101]
	v_pk_add_f32 v[10:11], v[10:11], v[100:101] neg_lo:[0,1] neg_hi:[0,1]
	v_pk_add_f32 v[70:71], v[86:87], v[88:89] neg_lo:[0,1] neg_hi:[0,1]
	v_xor_b32_e32 v95, 0x80000000, v10
	v_mov_b32_e32 v94, v11
	s_waitcnt lgkmcnt(2)
	v_pk_add_f32 v[10:11], v[4:5], v[102:103]
	v_pk_add_f32 v[4:5], v[4:5], v[102:103] neg_lo:[0,1] neg_hi:[0,1]
	v_pk_add_f32 v[84:85], v[108:109], v[112:113]
	v_pk_mul_f32 v[96:97], v[4:5], s[62:63] op_sel_hi:[1,0]
	s_nop 0
	v_pk_fma_f32 v[4:5], v[4:5], s[60:61], v[96:97] op_sel:[1,0,0] op_sel_hi:[0,0,1] neg_lo:[0,0,1] neg_hi:[1,0,1]
	s_waitcnt lgkmcnt(1)
	v_pk_add_f32 v[96:97], v[2:3], v[104:105]
	v_pk_add_f32 v[2:3], v[2:3], v[104:105] neg_lo:[0,1] neg_hi:[0,1]
	v_pk_add_f32 v[86:87], v[108:109], v[112:113] neg_lo:[0,1] neg_hi:[0,1]
	v_pk_mul_f32 v[98:99], v[2:3], s[70:71] op_sel_hi:[1,0]
	s_nop 0
	v_pk_fma_f32 v[2:3], v[2:3], s[70:71], v[98:99] op_sel:[1,0,0] op_sel_hi:[0,0,1] neg_lo:[0,0,1] neg_hi:[1,0,1]
	s_waitcnt lgkmcnt(0)
	v_pk_add_f32 v[98:99], v[82:83], v[106:107]
	v_pk_add_f32 v[82:83], v[82:83], v[106:107] neg_lo:[0,1] neg_hi:[0,1]
	v_pk_add_f32 v[72:73], v[74:75], v[90:91]
	v_pk_mul_f32 v[100:101], v[82:83], s[60:61] op_sel_hi:[1,0]
	v_xor_b32_e32 v103, 0x80000000, v82
	v_mov_b32_e32 v102, v83
	v_pk_fma_f32 v[82:83], v[102:103], s[62:63], v[100:101] op_sel_hi:[1,0,1] neg_lo:[0,0,1] neg_hi:[0,0,1]
	v_pk_add_f32 v[100:101], v[62:63], v[92:93]
	v_pk_add_f32 v[62:63], v[62:63], v[92:93] neg_lo:[0,1] neg_hi:[0,1]
	v_pk_add_f32 v[92:93], v[64:65], v[10:11]
	v_pk_add_f32 v[10:11], v[64:65], v[10:11] neg_lo:[0,1] neg_hi:[0,1]
	v_pk_add_f32 v[74:75], v[74:75], v[90:91] neg_lo:[0,1] neg_hi:[0,1]
	v_pk_mul_f32 v[64:65], v[10:11], s[70:71] op_sel:[1,0] op_sel_hi:[0,0] neg_hi:[1,0]
	v_pk_add_f32 v[88:89], v[110:111], v[114:115]
	v_pk_fma_f32 v[10:11], v[10:11], s[70:71], v[64:65] op_sel_hi:[1,0,1]
	v_pk_add_f32 v[64:65], v[76:77], v[96:97]
	v_pk_add_f32 v[76:77], v[76:77], v[96:97] neg_lo:[0,1] neg_hi:[0,1]
	v_pk_add_f32 v[90:91], v[110:111], v[114:115] neg_lo:[0,1] neg_hi:[0,1]
	v_xor_b32_e32 v97, 0x80000000, v76
	v_mov_b32_e32 v96, v77
	v_pk_add_f32 v[76:77], v[78:79], v[98:99]
	v_pk_add_f32 v[78:79], v[78:79], v[98:99] neg_lo:[0,1] neg_hi:[0,1]
	s_nop 0
	v_pk_mul_f32 v[98:99], v[78:79], s[70:71] op_sel_hi:[1,0]
	v_xor_b32_e32 v103, 0x80000000, v78
	v_mov_b32_e32 v102, v79
	v_pk_fma_f32 v[78:79], v[102:103], s[70:71], v[98:99] op_sel_hi:[1,0,1] neg_lo:[0,0,1] neg_hi:[0,0,1]
	v_pk_add_f32 v[98:99], v[6:7], v[94:95]
	v_pk_add_f32 v[6:7], v[6:7], v[94:95] neg_lo:[0,1] neg_hi:[0,1]
	v_pk_add_f32 v[94:95], v[66:67], v[4:5]
	v_pk_add_f32 v[4:5], v[66:67], v[4:5] neg_lo:[0,1] neg_hi:[0,1]
	s_nop 0
	v_pk_mul_f32 v[66:67], v[4:5], s[70:71] op_sel:[1,0] op_sel_hi:[0,0] neg_hi:[1,0]
	s_nop 0
	v_pk_fma_f32 v[4:5], v[4:5], s[70:71], v[66:67] op_sel_hi:[1,0,1]
	v_pk_add_f32 v[66:67], v[8:9], v[2:3]
	v_pk_add_f32 v[2:3], v[8:9], v[2:3] neg_lo:[0,1] neg_hi:[0,1]
	v_pk_add_f32 v[106:107], v[98:99], v[66:67] neg_lo:[0,1] neg_hi:[0,1]
	v_xor_b32_e32 v9, 0x80000000, v2
	v_mov_b32_e32 v8, v3
	v_pk_add_f32 v[2:3], v[80:81], v[82:83]
	v_pk_add_f32 v[80:81], v[80:81], v[82:83] neg_lo:[0,1] neg_hi:[0,1]
	v_pk_add_f32 v[108:109], v[94:95], v[2:3]
	v_pk_mul_f32 v[82:83], v[80:81], s[70:71] op_sel_hi:[1,0]
	s_nop 0
	v_pk_fma_f32 v[80:81], v[80:81], s[70:71], v[82:83] op_sel:[1,0,0] op_sel_hi:[0,0,1] neg_lo:[0,0,1] neg_hi:[1,0,1]
	v_pk_add_f32 v[82:83], v[100:101], v[64:65]
	v_pk_add_f32 v[64:65], v[100:101], v[64:65] neg_lo:[0,1] neg_hi:[0,1]
	v_pk_add_f32 v[100:101], v[92:93], v[76:77]
	v_pk_add_f32 v[76:77], v[92:93], v[76:77] neg_lo:[0,1] neg_hi:[0,1]
	v_pk_add_f32 v[102:103], v[10:11], v[78:79]
	v_xor_b32_e32 v93, 0x80000000, v76
	v_mov_b32_e32 v92, v77
	v_pk_add_f32 v[76:77], v[62:63], v[96:97]
	v_pk_add_f32 v[10:11], v[10:11], v[78:79] neg_lo:[0,1] neg_hi:[0,1]
	v_pk_add_f32 v[2:3], v[94:95], v[2:3] neg_lo:[0,1] neg_hi:[0,1]
	v_pk_add_f32 v[62:63], v[62:63], v[96:97] neg_lo:[0,1] neg_hi:[0,1]
	v_xor_b32_e32 v105, 0x80000000, v10
	v_mov_b32_e32 v104, v11
	v_pk_add_f32 v[10:11], v[98:99], v[66:67]
	v_xor_b32_e32 v111, 0x80000000, v2
	v_mov_b32_e32 v110, v3
	v_pk_add_f32 v[112:113], v[6:7], v[8:9]
	v_pk_add_f32 v[114:115], v[6:7], v[8:9] neg_lo:[0,1] neg_hi:[0,1]
	v_pk_add_f32 v[6:7], v[4:5], v[80:81]
	v_pk_add_f32 v[2:3], v[4:5], v[80:81] neg_lo:[0,1] neg_hi:[0,1]
	v_pk_add_f32 v[98:99], v[82:83], v[100:101]
	v_pk_add_f32 v[96:97], v[82:83], v[100:101] neg_lo:[0,1] neg_hi:[0,1]
	v_pk_add_f32 v[82:83], v[76:77], v[102:103]
	v_pk_add_f32 v[80:81], v[76:77], v[102:103] neg_lo:[0,1] neg_hi:[0,1]
	s_waitcnt vmcnt(7)
	v_mov_b64 v[100:101], v[164:165]
	v_mov_b64 v[102:103], v[166:167]
	v_pk_add_f32 v[78:79], v[62:63], v[104:105]
	v_pk_add_f32 v[76:77], v[62:63], v[104:105] neg_lo:[0,1] neg_hi:[0,1]
	v_xor_b32_e32 v5, 0x80000000, v2
	v_mov_b32_e32 v4, v3
	v_pk_add_f32 v[62:63], v[106:107], v[110:111]
	v_pk_add_f32 v[2:3], v[106:107], v[110:111] neg_lo:[0,1] neg_hi:[0,1]
	v_pk_add_f32 v[94:95], v[64:65], v[92:93]
	v_pk_add_f32 v[92:93], v[64:65], v[92:93] neg_lo:[0,1] neg_hi:[0,1]
	v_pk_add_f32 v[66:67], v[10:11], v[108:109]
	v_pk_add_f32 v[64:65], v[10:11], v[108:109] neg_lo:[0,1] neg_hi:[0,1]
	v_pk_add_f32 v[10:11], v[112:113], v[6:7]
	v_pk_add_f32 v[8:9], v[112:113], v[6:7] neg_lo:[0,1] neg_hi:[0,1]
	v_pk_add_f32 v[6:7], v[114:115], v[4:5]
	v_pk_add_f32 v[4:5], v[114:115], v[4:5] neg_lo:[0,1] neg_hi:[0,1]
	v_cvt_f32_f16_e32 v104, v100
	v_cvt_f32_f16_sdwa v100, v100 dst_sel:DWORD dst_unused:UNUSED_PAD src0_sel:WORD_1
	v_mul_f32_e32 v104, 0x38800000, v104
	v_mul_f32_e32 v100, 0x38800000, v100
	s_nop 0
	v_pk_mul_f32 v[106:107], v[12:13], v[100:101] op_sel:[1,0] op_sel_hi:[0,0] neg_lo:[1,0]
	v_cvt_f32_f16_e32 v100, v101
	v_cvt_f32_f16_sdwa v101, v101 dst_sel:DWORD dst_unused:UNUSED_PAD src0_sel:WORD_1
	v_pk_fma_f32 v[12:13], v[12:13], v[104:105], v[106:107] op_sel_hi:[1,0,1]
	v_xor_b32_e32 v106, 0x80000000, v15
	v_mov_b32_e32 v107, v14
	v_mul_f32_e32 v104, 0x38800000, v101
	v_mul_f32_e32 v100, 0x38800000, v100
	v_pk_mul_f32 v[104:105], v[106:107], v[104:105] op_sel_hi:[1,0]
	v_xor_b32_e32 v106, 0x80000000, v21
	v_pk_fma_f32 v[14:15], v[14:15], v[100:101], v[104:105] op_sel_hi:[1,0,1]
	v_cvt_f32_f16_sdwa v101, v102 dst_sel:DWORD dst_unused:UNUSED_PAD src0_sel:WORD_1
	v_cvt_f32_f16_e32 v100, v102
	s_nop 0
	s_nop 0
	v_mul_f32_e32 v102, 0x38800000, v101
	v_mul_f32_e32 v100, 0x38800000, v100
	v_pk_mul_f32 v[104:105], v[16:17], v[102:103] op_sel:[1,0] op_sel_hi:[0,0] neg_lo:[1,0]
	v_mov_b32_e32 v107, v20
	v_pk_fma_f32 v[16:17], v[16:17], v[100:101], v[104:105] op_sel_hi:[1,0,1]
	v_cvt_f32_f16_sdwa v101, v103 dst_sel:DWORD dst_unused:UNUSED_PAD src0_sel:WORD_1
	v_cvt_f32_f16_e32 v100, v103
	v_xor_b32_e32 v104, 0x80000000, v19
	v_mov_b32_e32 v105, v18
	v_mul_f32_e32 v102, 0x38800000, v101
	v_mul_f32_e32 v100, 0x38800000, v100
	v_pk_mul_f32 v[102:103], v[104:105], v[102:103] op_sel_hi:[1,0]
	s_nop 0
	v_pk_fma_f32 v[18:19], v[18:19], v[100:101], v[102:103] op_sel_hi:[1,0,1]
	s_waitcnt vmcnt(6)
	v_mov_b64 v[100:101], v[168:169]
	v_mov_b64 v[102:103], v[170:171]
	v_cvt_f32_f16_e32 v104, v100
	v_cvt_f32_f16_sdwa v100, v100 dst_sel:DWORD dst_unused:UNUSED_PAD src0_sel:WORD_1
	v_mul_f32_e32 v104, 0x38800000, v104
	v_mul_f32_e32 v100, 0x38800000, v100
	v_pk_mul_f32 v[106:107], v[106:107], v[100:101] op_sel_hi:[1,0]
	v_cvt_f32_f16_e32 v100, v101
	v_cvt_f32_f16_sdwa v101, v101 dst_sel:DWORD dst_unused:UNUSED_PAD src0_sel:WORD_1
	v_pk_fma_f32 v[20:21], v[20:21], v[104:105], v[106:107] op_sel_hi:[1,0,1]
	v_xor_b32_e32 v106, 0x80000000, v23
	v_mov_b32_e32 v107, v22
	v_mul_f32_e32 v104, 0x38800000, v101
	v_mul_f32_e32 v100, 0x38800000, v100
	v_pk_mul_f32 v[104:105], v[106:107], v[104:105] op_sel_hi:[1,0]
	v_xor_b32_e32 v106, 0x80000000, v69
	v_pk_fma_f32 v[22:23], v[22:23], v[100:101], v[104:105] op_sel_hi:[1,0,1]
	v_cvt_f32_f16_sdwa v101, v102 dst_sel:DWORD dst_unused:UNUSED_PAD src0_sel:WORD_1
	v_cvt_f32_f16_e32 v100, v102
	s_nop 0
	s_nop 0
	v_mul_f32_e32 v102, 0x38800000, v101
	v_mul_f32_e32 v100, 0x38800000, v100
	v_pk_mul_f32 v[104:105], v[24:25], v[102:103] op_sel:[1,0] op_sel_hi:[0,0] neg_lo:[1,0]
	v_mov_b32_e32 v107, v68
	v_pk_fma_f32 v[24:25], v[24:25], v[100:101], v[104:105] op_sel_hi:[1,0,1]
	v_cvt_f32_f16_sdwa v101, v103 dst_sel:DWORD dst_unused:UNUSED_PAD src0_sel:WORD_1
	v_cvt_f32_f16_e32 v100, v103
	v_xor_b32_e32 v104, 0x80000000, v27
	v_mov_b32_e32 v105, v26
	v_mul_f32_e32 v102, 0x38800000, v101
	v_mul_f32_e32 v100, 0x38800000, v100
	v_pk_mul_f32 v[102:103], v[104:105], v[102:103] op_sel_hi:[1,0]
	s_nop 0
	v_pk_fma_f32 v[26:27], v[26:27], v[100:101], v[102:103] op_sel_hi:[1,0,1]
	s_waitcnt vmcnt(5)
	v_mov_b64 v[100:101], v[172:173]
	v_mov_b64 v[102:103], v[174:175]
	v_cvt_f32_f16_e32 v104, v100
	v_cvt_f32_f16_sdwa v100, v100 dst_sel:DWORD dst_unused:UNUSED_PAD src0_sel:WORD_1
	v_mul_f32_e32 v104, 0x38800000, v104
	v_mul_f32_e32 v100, 0x38800000, v100
	v_pk_mul_f32 v[106:107], v[106:107], v[100:101] op_sel_hi:[1,0]
	v_cvt_f32_f16_e32 v100, v101
	v_cvt_f32_f16_sdwa v101, v101 dst_sel:DWORD dst_unused:UNUSED_PAD src0_sel:WORD_1
	v_pk_fma_f32 v[68:69], v[68:69], v[104:105], v[106:107] op_sel_hi:[1,0,1]
	v_xor_b32_e32 v106, 0x80000000, v71
	v_mov_b32_e32 v107, v70
	v_mul_f32_e32 v104, 0x38800000, v101
	v_mul_f32_e32 v100, 0x38800000, v100
	v_pk_mul_f32 v[104:105], v[106:107], v[104:105] op_sel_hi:[1,0]
	v_xor_b32_e32 v106, 0x80000000, v85
	v_pk_fma_f32 v[70:71], v[70:71], v[100:101], v[104:105] op_sel_hi:[1,0,1]
	v_cvt_f32_f16_sdwa v101, v102 dst_sel:DWORD dst_unused:UNUSED_PAD src0_sel:WORD_1
	v_cvt_f32_f16_e32 v100, v102
	s_nop 0
	s_nop 0
	v_mul_f32_e32 v102, 0x38800000, v101
	v_mul_f32_e32 v100, 0x38800000, v100
	v_pk_mul_f32 v[104:105], v[72:73], v[102:103] op_sel:[1,0] op_sel_hi:[0,0] neg_lo:[1,0]
	v_mov_b32_e32 v107, v84
	v_pk_fma_f32 v[72:73], v[72:73], v[100:101], v[104:105] op_sel_hi:[1,0,1]
	v_cvt_f32_f16_sdwa v101, v103 dst_sel:DWORD dst_unused:UNUSED_PAD src0_sel:WORD_1
	v_cvt_f32_f16_e32 v100, v103
	v_xor_b32_e32 v104, 0x80000000, v75
	v_mov_b32_e32 v105, v74
	v_mul_f32_e32 v102, 0x38800000, v101
	v_mul_f32_e32 v100, 0x38800000, v100
	v_pk_mul_f32 v[102:103], v[104:105], v[102:103] op_sel_hi:[1,0]
	s_nop 0
	v_pk_fma_f32 v[74:75], v[74:75], v[100:101], v[102:103] op_sel_hi:[1,0,1]
	s_waitcnt vmcnt(4)
	v_mov_b64 v[100:101], v[176:177]
	v_mov_b64 v[102:103], v[178:179]
	v_cvt_f32_f16_e32 v104, v100
	v_cvt_f32_f16_sdwa v100, v100 dst_sel:DWORD dst_unused:UNUSED_PAD src0_sel:WORD_1
	v_mul_f32_e32 v104, 0x38800000, v104
	v_mul_f32_e32 v100, 0x38800000, v100
	v_pk_mul_f32 v[106:107], v[106:107], v[100:101] op_sel_hi:[1,0]
	v_cvt_f32_f16_e32 v100, v101
	v_cvt_f32_f16_sdwa v101, v101 dst_sel:DWORD dst_unused:UNUSED_PAD src0_sel:WORD_1
	v_pk_fma_f32 v[84:85], v[84:85], v[104:105], v[106:107] op_sel_hi:[1,0,1]
	v_xor_b32_e32 v106, 0x80000000, v87
	v_mov_b32_e32 v107, v86
	v_mul_f32_e32 v104, 0x38800000, v101
	v_mul_f32_e32 v100, 0x38800000, v100
	v_pk_mul_f32 v[104:105], v[106:107], v[104:105] op_sel_hi:[1,0]
	v_xor_b32_e32 v106, 0x80000000, v99
	v_pk_fma_f32 v[86:87], v[86:87], v[100:101], v[104:105] op_sel_hi:[1,0,1]
	v_cvt_f32_f16_sdwa v101, v102 dst_sel:DWORD dst_unused:UNUSED_PAD src0_sel:WORD_1
	v_cvt_f32_f16_e32 v100, v102
	s_nop 0
	s_nop 0
	v_mul_f32_e32 v102, 0x38800000, v101
	v_mul_f32_e32 v100, 0x38800000, v100
	v_pk_mul_f32 v[104:105], v[88:89], v[102:103] op_sel:[1,0] op_sel_hi:[0,0] neg_lo:[1,0]
	v_mov_b32_e32 v107, v98
	v_pk_fma_f32 v[88:89], v[88:89], v[100:101], v[104:105] op_sel_hi:[1,0,1]
	v_cvt_f32_f16_sdwa v101, v103 dst_sel:DWORD dst_unused:UNUSED_PAD src0_sel:WORD_1
	v_cvt_f32_f16_e32 v100, v103
	v_xor_b32_e32 v104, 0x80000000, v91
	v_mov_b32_e32 v105, v90
	v_mul_f32_e32 v102, 0x38800000, v101
	v_mul_f32_e32 v100, 0x38800000, v100
	v_pk_mul_f32 v[102:103], v[104:105], v[102:103] op_sel_hi:[1,0]
	s_nop 0
	v_pk_fma_f32 v[90:91], v[90:91], v[100:101], v[102:103] op_sel_hi:[1,0,1]
	s_waitcnt vmcnt(3)
	v_mov_b64 v[100:101], v[180:181]
	v_mov_b64 v[102:103], v[182:183]
	v_cvt_f32_f16_e32 v104, v100
	v_cvt_f32_f16_sdwa v100, v100 dst_sel:DWORD dst_unused:UNUSED_PAD src0_sel:WORD_1
	v_mul_f32_e32 v104, 0x38800000, v104
	v_mul_f32_e32 v100, 0x38800000, v100
	v_pk_mul_f32 v[106:107], v[106:107], v[100:101] op_sel_hi:[1,0]
	v_cvt_f32_f16_e32 v100, v101
	v_cvt_f32_f16_sdwa v101, v101 dst_sel:DWORD dst_unused:UNUSED_PAD src0_sel:WORD_1
	v_pk_fma_f32 v[98:99], v[98:99], v[104:105], v[106:107] op_sel_hi:[1,0,1]
	v_xor_b32_e32 v106, 0x80000000, v97
	v_mov_b32_e32 v107, v96
	v_mul_f32_e32 v104, 0x38800000, v101
	v_mul_f32_e32 v100, 0x38800000, v100
	v_pk_mul_f32 v[104:105], v[106:107], v[104:105] op_sel_hi:[1,0]
	v_xor_b32_e32 v106, 0x80000000, v83
	v_pk_fma_f32 v[96:97], v[96:97], v[100:101], v[104:105] op_sel_hi:[1,0,1]
	v_cvt_f32_f16_sdwa v101, v102 dst_sel:DWORD dst_unused:UNUSED_PAD src0_sel:WORD_1
	v_cvt_f32_f16_e32 v100, v102
	s_nop 0
	s_nop 0
	v_mul_f32_e32 v102, 0x38800000, v101
	v_mul_f32_e32 v100, 0x38800000, v100
	v_pk_mul_f32 v[104:105], v[94:95], v[102:103] op_sel:[1,0] op_sel_hi:[0,0] neg_lo:[1,0]
	v_mov_b32_e32 v107, v82
	v_pk_fma_f32 v[94:95], v[94:95], v[100:101], v[104:105] op_sel_hi:[1,0,1]
	v_cvt_f32_f16_sdwa v101, v103 dst_sel:DWORD dst_unused:UNUSED_PAD src0_sel:WORD_1
	v_cvt_f32_f16_e32 v100, v103
	v_xor_b32_e32 v104, 0x80000000, v93
	v_mov_b32_e32 v105, v92
	v_mul_f32_e32 v102, 0x38800000, v101
	v_mul_f32_e32 v100, 0x38800000, v100
	v_pk_mul_f32 v[102:103], v[104:105], v[102:103] op_sel_hi:[1,0]
	s_nop 0
	v_pk_fma_f32 v[92:93], v[92:93], v[100:101], v[102:103] op_sel_hi:[1,0,1]
	s_waitcnt vmcnt(2)
	v_mov_b64 v[100:101], v[184:185]
	v_mov_b64 v[102:103], v[186:187]
	v_cvt_f32_f16_e32 v104, v100
	v_cvt_f32_f16_sdwa v100, v100 dst_sel:DWORD dst_unused:UNUSED_PAD src0_sel:WORD_1
	v_mul_f32_e32 v104, 0x38800000, v104
	v_mul_f32_e32 v100, 0x38800000, v100
	v_pk_mul_f32 v[106:107], v[106:107], v[100:101] op_sel_hi:[1,0]
	v_cvt_f32_f16_e32 v100, v101
	v_cvt_f32_f16_sdwa v101, v101 dst_sel:DWORD dst_unused:UNUSED_PAD src0_sel:WORD_1
	v_pk_fma_f32 v[82:83], v[82:83], v[104:105], v[106:107] op_sel_hi:[1,0,1]
	v_xor_b32_e32 v106, 0x80000000, v81
	v_mov_b32_e32 v107, v80
	v_mul_f32_e32 v104, 0x38800000, v101
	v_mul_f32_e32 v100, 0x38800000, v100
	v_pk_mul_f32 v[104:105], v[106:107], v[104:105] op_sel_hi:[1,0]
	v_xor_b32_e32 v106, 0x80000000, v67
	v_pk_fma_f32 v[80:81], v[80:81], v[100:101], v[104:105] op_sel_hi:[1,0,1]
	v_cvt_f32_f16_sdwa v101, v102 dst_sel:DWORD dst_unused:UNUSED_PAD src0_sel:WORD_1
	v_cvt_f32_f16_e32 v100, v102
	s_nop 0
	s_nop 0
	v_mul_f32_e32 v102, 0x38800000, v101
	v_mul_f32_e32 v100, 0x38800000, v100
	v_pk_mul_f32 v[104:105], v[78:79], v[102:103] op_sel:[1,0] op_sel_hi:[0,0] neg_lo:[1,0]
	v_mov_b32_e32 v107, v66
	v_pk_fma_f32 v[78:79], v[78:79], v[100:101], v[104:105] op_sel_hi:[1,0,1]
	v_cvt_f32_f16_sdwa v101, v103 dst_sel:DWORD dst_unused:UNUSED_PAD src0_sel:WORD_1
	v_cvt_f32_f16_e32 v100, v103
	v_xor_b32_e32 v104, 0x80000000, v77
	v_mov_b32_e32 v105, v76
	v_mul_f32_e32 v102, 0x38800000, v101
	v_mul_f32_e32 v100, 0x38800000, v100
	v_pk_mul_f32 v[102:103], v[104:105], v[102:103] op_sel_hi:[1,0]
	s_nop 0
	v_pk_fma_f32 v[76:77], v[76:77], v[100:101], v[102:103] op_sel_hi:[1,0,1]
	s_waitcnt vmcnt(1)
	v_mov_b64 v[100:101], v[188:189]
	v_mov_b64 v[102:103], v[190:191]
	v_cvt_f32_f16_e32 v104, v100
	v_cvt_f32_f16_sdwa v100, v100 dst_sel:DWORD dst_unused:UNUSED_PAD src0_sel:WORD_1
	v_mul_f32_e32 v104, 0x38800000, v104
	v_mul_f32_e32 v100, 0x38800000, v100
	v_pk_mul_f32 v[106:107], v[106:107], v[100:101] op_sel_hi:[1,0]
	v_cvt_f32_f16_e32 v100, v101
	v_cvt_f32_f16_sdwa v101, v101 dst_sel:DWORD dst_unused:UNUSED_PAD src0_sel:WORD_1
	v_pk_fma_f32 v[66:67], v[66:67], v[104:105], v[106:107] op_sel_hi:[1,0,1]
	v_xor_b32_e32 v106, 0x80000000, v65
	v_mov_b32_e32 v107, v64
	v_mul_f32_e32 v104, 0x38800000, v101
	v_mul_f32_e32 v100, 0x38800000, v100
	v_pk_mul_f32 v[104:105], v[106:107], v[104:105] op_sel_hi:[1,0]
	s_nop 0
	v_pk_fma_f32 v[64:65], v[64:65], v[100:101], v[104:105] op_sel_hi:[1,0,1]
	v_cvt_f32_f16_sdwa v101, v102 dst_sel:DWORD dst_unused:UNUSED_PAD src0_sel:WORD_1
	v_cvt_f32_f16_e32 v100, v102
	s_nop 0
	s_nop 0
	v_mul_f32_e32 v102, 0x38800000, v101
	v_mul_f32_e32 v100, 0x38800000, v100
	v_pk_mul_f32 v[104:105], v[62:63], v[102:103] op_sel:[1,0] op_sel_hi:[0,0] neg_lo:[1,0]
	s_nop 0
	v_pk_fma_f32 v[62:63], v[62:63], v[100:101], v[104:105] op_sel_hi:[1,0,1]
	v_cvt_f32_f16_sdwa v101, v103 dst_sel:DWORD dst_unused:UNUSED_PAD src0_sel:WORD_1
	v_cvt_f32_f16_e32 v100, v103
	v_xor_b32_e32 v104, 0x80000000, v3
	v_mov_b32_e32 v105, v2
	v_mul_f32_e32 v102, 0x38800000, v101
	v_mul_f32_e32 v100, 0x38800000, v100
	v_pk_mul_f32 v[102:103], v[104:105], v[102:103] op_sel_hi:[1,0]
	v_xor_b32_e32 v104, 0x80000000, v11
	v_pk_fma_f32 v[100:101], v[2:3], v[100:101], v[102:103] op_sel_hi:[1,0,1]
	s_waitcnt vmcnt(0)
	v_mov_b64 v[0:1], v[192:193]
	v_mov_b64 v[2:3], v[194:195]
	v_mov_b32_e32 v105, v10
	v_cvt_f32_f16_e32 v102, v0
	v_cvt_f32_f16_sdwa v0, v0 dst_sel:DWORD dst_unused:UNUSED_PAD src0_sel:WORD_1
	v_mul_f32_e32 v102, 0x38800000, v102
	v_mul_f32_e32 v0, 0x38800000, v0
	v_pk_mul_f32 v[104:105], v[104:105], v[0:1] op_sel_hi:[1,0]
	v_cvt_f32_f16_e32 v0, v1
	v_cvt_f32_f16_sdwa v1, v1 dst_sel:DWORD dst_unused:UNUSED_PAD src0_sel:WORD_1
	v_pk_fma_f32 v[10:11], v[10:11], v[102:103], v[104:105] op_sel_hi:[1,0,1]
	v_xor_b32_e32 v104, 0x80000000, v9
	v_mov_b32_e32 v105, v8
	v_mul_f32_e32 v102, 0x38800000, v1
	v_mul_f32_e32 v0, 0x38800000, v0
	v_pk_mul_f32 v[102:103], v[104:105], v[102:103] op_sel_hi:[1,0]
	s_nop 0
	v_pk_fma_f32 v[0:1], v[8:9], v[0:1], v[102:103] op_sel_hi:[1,0,1]
	v_cvt_f32_f16_e32 v8, v2
	v_cvt_f32_f16_sdwa v2, v2 dst_sel:DWORD dst_unused:UNUSED_PAD src0_sel:WORD_1
	s_nop 0
	s_nop 0
	v_mul_f32_e32 v8, 0x38800000, v8
	v_mul_f32_e32 v2, 0x38800000, v2
	s_nop 0
	v_pk_mul_f32 v[102:103], v[6:7], v[2:3] op_sel:[1,0] op_sel_hi:[0,0] neg_lo:[1,0]
	v_cvt_f32_f16_e32 v2, v3
	v_cvt_f32_f16_sdwa v3, v3 dst_sel:DWORD dst_unused:UNUSED_PAD src0_sel:WORD_1
	v_pk_fma_f32 v[6:7], v[6:7], v[8:9], v[102:103] op_sel_hi:[1,0,1]
	v_xor_b32_e32 v102, 0x80000000, v5
	v_mov_b32_e32 v103, v4
	v_mul_f32_e32 v8, 0x38800000, v3
	v_mul_f32_e32 v2, 0x38800000, v2
	v_pk_mul_f32 v[8:9], v[102:103], v[8:9] op_sel_hi:[1,0]
	v_mov_b32_e32 v102, v146
	v_pk_fma_f32 v[2:3], v[4:5], v[2:3], v[8:9] op_sel_hi:[1,0,1]
	v_pk_add_f32 v[4:5], v[12:13], v[14:15]
	v_pk_add_f32 v[8:9], v[12:13], v[14:15] neg_lo:[0,1] neg_hi:[0,1]
	v_pk_add_f32 v[12:13], v[16:17], v[18:19]
	v_pk_add_f32 v[14:15], v[16:17], v[18:19] neg_lo:[0,1] neg_hi:[0,1]
	v_pk_add_f32 v[16:17], v[20:21], v[22:23]
	v_pk_add_f32 v[18:19], v[20:21], v[22:23] neg_lo:[0,1] neg_hi:[0,1]
	v_pk_add_f32 v[20:21], v[24:25], v[26:27]
	v_pk_add_f32 v[22:23], v[24:25], v[26:27] neg_lo:[0,1] neg_hi:[0,1]
	v_pk_add_f32 v[24:25], v[68:69], v[70:71]
	v_pk_add_f32 v[26:27], v[68:69], v[70:71] neg_lo:[0,1] neg_hi:[0,1]
	v_pk_add_f32 v[68:69], v[72:73], v[74:75]
	v_pk_add_f32 v[70:71], v[72:73], v[74:75] neg_lo:[0,1] neg_hi:[0,1]
	v_pk_add_f32 v[72:73], v[84:85], v[86:87]
	v_pk_add_f32 v[74:75], v[84:85], v[86:87] neg_lo:[0,1] neg_hi:[0,1]
	v_pk_add_f32 v[84:85], v[88:89], v[90:91]
	v_pk_add_f32 v[86:87], v[88:89], v[90:91] neg_lo:[0,1] neg_hi:[0,1]
	v_pk_add_f32 v[88:89], v[4:5], v[12:13]
	v_pk_add_f32 v[4:5], v[4:5], v[12:13] neg_lo:[0,1] neg_hi:[0,1]
	v_xor_b32_e32 v12, 0x80000000, v15
	v_mov_b32_e32 v13, v14
	v_pk_add_f32 v[14:15], v[8:9], v[12:13]
	v_pk_add_f32 v[8:9], v[8:9], v[12:13] neg_lo:[0,1] neg_hi:[0,1]
	v_pk_add_f32 v[12:13], v[16:17], v[20:21]
	v_pk_add_f32 v[16:17], v[16:17], v[20:21] neg_lo:[0,1] neg_hi:[0,1]
	v_xor_b32_e32 v20, 0x80000000, v23
	v_mov_b32_e32 v21, v22
	v_pk_add_f32 v[22:23], v[18:19], v[20:21]
	v_pk_add_f32 v[18:19], v[18:19], v[20:21] neg_lo:[0,1] neg_hi:[0,1]
	v_pk_add_f32 v[20:21], v[24:25], v[68:69]
	v_pk_add_f32 v[24:25], v[24:25], v[68:69] neg_lo:[0,1] neg_hi:[0,1]
	v_xor_b32_e32 v68, 0x80000000, v71
	v_mov_b32_e32 v69, v70
	v_pk_add_f32 v[70:71], v[26:27], v[68:69]
	v_pk_add_f32 v[26:27], v[26:27], v[68:69] neg_lo:[0,1] neg_hi:[0,1]
	v_pk_add_f32 v[68:69], v[72:73], v[84:85]
	v_pk_add_f32 v[72:73], v[72:73], v[84:85] neg_lo:[0,1] neg_hi:[0,1]
	v_xor_b32_e32 v84, 0x80000000, v87
	v_mov_b32_e32 v85, v86
	v_pk_add_f32 v[86:87], v[74:75], v[84:85]
	v_pk_add_f32 v[74:75], v[74:75], v[84:85] neg_lo:[0,1] neg_hi:[0,1]
	v_pk_add_f32 v[84:85], v[88:89], v[12:13]
	v_pk_add_f32 v[12:13], v[88:89], v[12:13] neg_lo:[0,1] neg_hi:[0,1]
	v_pk_mul_f32 v[88:89], v[22:23], s[70:71] op_sel:[1,0] op_sel_hi:[0,0] neg_lo:[1,0]
	v_xor_b32_e32 v90, 0x80000000, v19
	v_pk_fma_f32 v[22:23], v[22:23], s[70:71], v[88:89] op_sel_hi:[1,0,1]
	v_mov_b32_e32 v91, v18
	v_pk_add_f32 v[88:89], v[14:15], v[22:23]
	v_pk_add_f32 v[14:15], v[14:15], v[22:23] neg_lo:[0,1] neg_hi:[0,1]
	v_xor_b32_e32 v22, 0x80000000, v17
	v_mov_b32_e32 v23, v16
	v_pk_add_f32 v[16:17], v[4:5], v[22:23]
	v_pk_add_f32 v[4:5], v[4:5], v[22:23] neg_lo:[0,1] neg_hi:[0,1]
	v_pk_mul_f32 v[22:23], v[18:19], s[70:71] op_sel_hi:[1,0]
	s_nop 0
	v_pk_fma_f32 v[18:19], v[90:91], s[70:71], v[22:23] op_sel_hi:[1,0,1] neg_lo:[0,0,1] neg_hi:[0,0,1]
	v_xor_b32_e32 v90, 0x80000000, v75
	v_pk_add_f32 v[22:23], v[8:9], v[18:19]
	v_pk_add_f32 v[8:9], v[8:9], v[18:19] neg_lo:[0,1] neg_hi:[0,1]
	v_pk_add_f32 v[18:19], v[20:21], v[68:69]
	v_pk_add_f32 v[20:21], v[20:21], v[68:69] neg_lo:[0,1] neg_hi:[0,1]
	v_pk_mul_f32 v[68:69], v[86:87], s[70:71] op_sel:[1,0] op_sel_hi:[0,0] neg_lo:[1,0]
	v_mov_b32_e32 v91, v74
	v_pk_fma_f32 v[68:69], v[86:87], s[70:71], v[68:69] op_sel_hi:[1,0,1]
	s_nop 0
	v_pk_add_f32 v[86:87], v[70:71], v[68:69]
	v_pk_add_f32 v[68:69], v[70:71], v[68:69] neg_lo:[0,1] neg_hi:[0,1]
	v_xor_b32_e32 v70, 0x80000000, v73
	v_mov_b32_e32 v71, v72
	v_pk_add_f32 v[72:73], v[24:25], v[70:71]
	v_pk_add_f32 v[24:25], v[24:25], v[70:71] neg_lo:[0,1] neg_hi:[0,1]
	v_pk_mul_f32 v[70:71], v[74:75], s[70:71] op_sel_hi:[1,0]
	s_nop 0
	v_pk_fma_f32 v[70:71], v[90:91], s[70:71], v[70:71] op_sel_hi:[1,0,1] neg_lo:[0,0,1] neg_hi:[0,0,1]
	v_xor_b32_e32 v90, 0x80000000, v69
	v_pk_add_f32 v[74:75], v[26:27], v[70:71]
	v_pk_add_f32 v[26:27], v[26:27], v[70:71] neg_lo:[0,1] neg_hi:[0,1]
	v_pk_add_f32 v[70:71], v[84:85], v[18:19]
	v_pk_add_f32 v[18:19], v[84:85], v[18:19] neg_lo:[0,1] neg_hi:[0,1]
	v_pk_mul_f32 v[84:85], v[86:87], s[62:63] op_sel:[1,0] op_sel_hi:[0,0] neg_lo:[1,0]
	v_mov_b32_e32 v91, v68
	v_pk_fma_f32 v[84:85], v[86:87], s[60:61], v[84:85] op_sel_hi:[1,0,1]
	s_nop 0
	v_pk_add_f32 v[86:87], v[88:89], v[84:85]
	v_pk_add_f32 v[84:85], v[88:89], v[84:85] neg_lo:[0,1] neg_hi:[0,1]
	v_pk_mul_f32 v[88:89], v[72:73], s[70:71] op_sel:[1,0] op_sel_hi:[0,0] neg_lo:[1,0]
	s_nop 0
	v_pk_fma_f32 v[72:73], v[72:73], s[70:71], v[88:89] op_sel_hi:[1,0,1]
	s_nop 0
	v_pk_add_f32 v[88:89], v[16:17], v[72:73]
	v_pk_add_f32 v[16:17], v[16:17], v[72:73] neg_lo:[0,1] neg_hi:[0,1]
	v_pk_mul_f32 v[72:73], v[74:75], s[60:61] op_sel:[1,0] op_sel_hi:[0,0] neg_lo:[1,0]
	s_nop 0
	v_pk_fma_f32 v[72:73], v[74:75], s[62:63], v[72:73] op_sel_hi:[1,0,1]
	s_nop 0
	v_pk_add_f32 v[74:75], v[22:23], v[72:73]
	v_pk_add_f32 v[22:23], v[22:23], v[72:73] neg_lo:[0,1] neg_hi:[0,1]
	v_xor_b32_e32 v72, 0x80000000, v21
	v_mov_b32_e32 v73, v20
	v_pk_add_f32 v[20:21], v[12:13], v[72:73]
	v_pk_add_f32 v[12:13], v[12:13], v[72:73] neg_lo:[0,1] neg_hi:[0,1]
	v_pk_mul_f32 v[72:73], v[68:69], s[62:63] op_sel_hi:[1,0]
	s_nop 0
	v_pk_fma_f32 v[68:69], v[90:91], s[60:61], v[72:73] op_sel_hi:[1,0,1] neg_lo:[0,0,1] neg_hi:[0,0,1]
	v_xor_b32_e32 v90, 0x80000000, v25
	v_pk_add_f32 v[72:73], v[14:15], v[68:69]
	v_pk_add_f32 v[14:15], v[14:15], v[68:69] neg_lo:[0,1] neg_hi:[0,1]
	v_pk_mul_f32 v[68:69], v[24:25], s[70:71] op_sel_hi:[1,0]
	v_mov_b32_e32 v91, v24
	v_pk_fma_f32 v[24:25], v[90:91], s[70:71], v[68:69] op_sel_hi:[1,0,1] neg_lo:[0,0,1] neg_hi:[0,0,1]
	s_nop 0
	v_pk_add_f32 v[68:69], v[4:5], v[24:25]
	v_pk_add_f32 v[4:5], v[4:5], v[24:25] neg_lo:[0,1] neg_hi:[0,1]
	v_pk_mul_f32 v[24:25], v[26:27], s[60:61] op_sel_hi:[1,0]
	s_nop 0
	v_pk_fma_f32 v[24:25], v[26:27], s[62:63], v[24:25] op_sel:[1,0,0] op_sel_hi:[0,0,1] neg_lo:[1,0,1] neg_hi:[0,0,1]
	v_pk_add_f32 v[90:91], v[98:99], v[96:97] neg_lo:[0,1] neg_hi:[0,1]
	v_pk_add_f32 v[26:27], v[8:9], v[24:25]
	v_pk_add_f32 v[8:9], v[8:9], v[24:25] neg_lo:[0,1] neg_hi:[0,1]
	v_pk_add_f32 v[24:25], v[98:99], v[96:97]
	v_pk_add_f32 v[96:97], v[94:95], v[92:93]
	v_pk_add_f32 v[92:93], v[94:95], v[92:93] neg_lo:[0,1] neg_hi:[0,1]
	v_pk_add_f32 v[94:95], v[82:83], v[80:81]
	v_pk_add_f32 v[80:81], v[82:83], v[80:81] neg_lo:[0,1] neg_hi:[0,1]
	v_pk_add_f32 v[82:83], v[78:79], v[76:77]
	v_pk_add_f32 v[76:77], v[78:79], v[76:77] neg_lo:[0,1] neg_hi:[0,1]
	v_pk_add_f32 v[98:99], v[10:11], v[0:1]
	v_pk_add_f32 v[0:1], v[10:11], v[0:1] neg_lo:[0,1] neg_hi:[0,1]
	v_pk_add_f32 v[10:11], v[6:7], v[2:3]
	v_pk_add_f32 v[2:3], v[6:7], v[2:3] neg_lo:[0,1] neg_hi:[0,1]
	v_pk_add_f32 v[6:7], v[24:25], v[96:97]
	v_pk_add_f32 v[24:25], v[24:25], v[96:97] neg_lo:[0,1] neg_hi:[0,1]
	v_xor_b32_e32 v96, 0x80000000, v93
	v_mov_b32_e32 v97, v92
	v_pk_add_f32 v[78:79], v[66:67], v[64:65]
	v_pk_add_f32 v[64:65], v[66:67], v[64:65] neg_lo:[0,1] neg_hi:[0,1]
	v_pk_add_f32 v[66:67], v[62:63], v[100:101]
	v_pk_add_f32 v[62:63], v[62:63], v[100:101] neg_lo:[0,1] neg_hi:[0,1]
	v_pk_add_f32 v[92:93], v[90:91], v[96:97]
	v_pk_add_f32 v[90:91], v[90:91], v[96:97] neg_lo:[0,1] neg_hi:[0,1]
	v_pk_add_f32 v[96:97], v[94:95], v[82:83]
	v_pk_add_f32 v[82:83], v[94:95], v[82:83] neg_lo:[0,1] neg_hi:[0,1]
	v_xor_b32_e32 v94, 0x80000000, v77
	v_mov_b32_e32 v95, v76
	v_pk_add_f32 v[76:77], v[80:81], v[94:95]
	v_pk_add_f32 v[80:81], v[80:81], v[94:95] neg_lo:[0,1] neg_hi:[0,1]
	v_pk_add_f32 v[94:95], v[78:79], v[66:67]
	v_pk_add_f32 v[66:67], v[78:79], v[66:67] neg_lo:[0,1] neg_hi:[0,1]
	v_xor_b32_e32 v78, 0x80000000, v63
	v_mov_b32_e32 v79, v62
	v_pk_add_f32 v[62:63], v[64:65], v[78:79]
	v_pk_add_f32 v[64:65], v[64:65], v[78:79] neg_lo:[0,1] neg_hi:[0,1]
	v_pk_add_f32 v[78:79], v[98:99], v[10:11]
	v_pk_add_f32 v[10:11], v[98:99], v[10:11] neg_lo:[0,1] neg_hi:[0,1]
	v_xor_b32_e32 v98, 0x80000000, v3
	v_mov_b32_e32 v99, v2
	v_pk_add_f32 v[2:3], v[0:1], v[98:99]
	v_pk_add_f32 v[0:1], v[0:1], v[98:99] neg_lo:[0,1] neg_hi:[0,1]
	v_pk_add_f32 v[98:99], v[6:7], v[96:97]
	v_pk_add_f32 v[6:7], v[6:7], v[96:97] neg_lo:[0,1] neg_hi:[0,1]
	v_pk_mul_f32 v[96:97], v[76:77], s[70:71] op_sel:[1,0] op_sel_hi:[0,0] neg_lo:[1,0]
	v_xor_b32_e32 v100, 0x80000000, v81
	v_pk_fma_f32 v[76:77], v[76:77], s[70:71], v[96:97] op_sel_hi:[1,0,1]
	v_mov_b32_e32 v101, v80
	v_pk_add_f32 v[96:97], v[92:93], v[76:77]
	v_pk_add_f32 v[76:77], v[92:93], v[76:77] neg_lo:[0,1] neg_hi:[0,1]
	v_xor_b32_e32 v92, 0x80000000, v83
	v_mov_b32_e32 v93, v82
	v_pk_add_f32 v[82:83], v[24:25], v[92:93]
	v_pk_add_f32 v[24:25], v[24:25], v[92:93] neg_lo:[0,1] neg_hi:[0,1]
	v_pk_mul_f32 v[92:93], v[80:81], s[70:71] op_sel_hi:[1,0]
	s_nop 0
	v_pk_fma_f32 v[80:81], v[100:101], s[70:71], v[92:93] op_sel_hi:[1,0,1] neg_lo:[0,0,1] neg_hi:[0,0,1]
	v_xor_b32_e32 v100, 0x80000000, v1
	v_pk_add_f32 v[92:93], v[90:91], v[80:81]
	v_pk_add_f32 v[80:81], v[90:91], v[80:81] neg_lo:[0,1] neg_hi:[0,1]
	v_pk_add_f32 v[90:91], v[94:95], v[78:79]
	v_pk_add_f32 v[78:79], v[94:95], v[78:79] neg_lo:[0,1] neg_hi:[0,1]
	v_pk_mul_f32 v[94:95], v[2:3], s[70:71] op_sel:[1,0] op_sel_hi:[0,0] neg_lo:[1,0]
	v_mov_b32_e32 v101, v0
	v_pk_fma_f32 v[2:3], v[2:3], s[70:71], v[94:95] op_sel_hi:[1,0,1]
	s_nop 0
	v_pk_add_f32 v[94:95], v[62:63], v[2:3]
	v_pk_add_f32 v[2:3], v[62:63], v[2:3] neg_lo:[0,1] neg_hi:[0,1]
	v_xor_b32_e32 v62, 0x80000000, v11
	v_mov_b32_e32 v63, v10
	v_pk_add_f32 v[10:11], v[66:67], v[62:63]
	v_pk_add_f32 v[62:63], v[66:67], v[62:63] neg_lo:[0,1] neg_hi:[0,1]
	v_pk_mul_f32 v[66:67], v[0:1], s[70:71] op_sel_hi:[1,0]
	s_nop 0
	v_pk_fma_f32 v[0:1], v[100:101], s[70:71], v[66:67] op_sel_hi:[1,0,1] neg_lo:[0,0,1] neg_hi:[0,0,1]
	v_xor_b32_e32 v100, 0x80000000, v3
	v_pk_add_f32 v[66:67], v[64:65], v[0:1]
	v_pk_add_f32 v[0:1], v[64:65], v[0:1] neg_lo:[0,1] neg_hi:[0,1]
	v_pk_add_f32 v[64:65], v[98:99], v[90:91]
	v_pk_add_f32 v[90:91], v[98:99], v[90:91] neg_lo:[0,1] neg_hi:[0,1]
	v_pk_mul_f32 v[98:99], v[94:95], s[62:63] op_sel:[1,0] op_sel_hi:[0,0] neg_lo:[1,0]
	v_mov_b32_e32 v101, v2
	v_pk_fma_f32 v[94:95], v[94:95], s[60:61], v[98:99] op_sel_hi:[1,0,1]
	s_nop 0
	v_pk_add_f32 v[98:99], v[96:97], v[94:95]
	v_pk_add_f32 v[94:95], v[96:97], v[94:95] neg_lo:[0,1] neg_hi:[0,1]
	v_pk_mul_f32 v[96:97], v[10:11], s[70:71] op_sel:[1,0] op_sel_hi:[0,0] neg_lo:[1,0]
	s_nop 0
	v_pk_fma_f32 v[10:11], v[10:11], s[70:71], v[96:97] op_sel_hi:[1,0,1]
	s_nop 0
	v_pk_add_f32 v[96:97], v[82:83], v[10:11]
	v_pk_add_f32 v[10:11], v[82:83], v[10:11] neg_lo:[0,1] neg_hi:[0,1]
	v_pk_mul_f32 v[82:83], v[66:67], s[60:61] op_sel:[1,0] op_sel_hi:[0,0] neg_lo:[1,0]
	s_nop 0
	v_pk_fma_f32 v[66:67], v[66:67], s[62:63], v[82:83] op_sel_hi:[1,0,1]
	s_nop 0
	v_pk_add_f32 v[82:83], v[92:93], v[66:67]
	v_pk_add_f32 v[66:67], v[92:93], v[66:67] neg_lo:[0,1] neg_hi:[0,1]
	v_xor_b32_e32 v92, 0x80000000, v79
	v_mov_b32_e32 v93, v78
	v_pk_add_f32 v[78:79], v[6:7], v[92:93]
	v_pk_add_f32 v[6:7], v[6:7], v[92:93] neg_lo:[0,1] neg_hi:[0,1]
	v_pk_mul_f32 v[92:93], v[2:3], s[62:63] op_sel_hi:[1,0]
	s_nop 0
	v_pk_fma_f32 v[2:3], v[100:101], s[60:61], v[92:93] op_sel_hi:[1,0,1] neg_lo:[0,0,1] neg_hi:[0,0,1]
	v_xor_b32_e32 v100, 0x80000000, v63
	v_pk_add_f32 v[92:93], v[76:77], v[2:3]
	v_pk_add_f32 v[2:3], v[76:77], v[2:3] neg_lo:[0,1] neg_hi:[0,1]
	v_pk_mul_f32 v[76:77], v[62:63], s[70:71] op_sel_hi:[1,0]
	v_mov_b32_e32 v101, v62
	v_pk_fma_f32 v[62:63], v[100:101], s[70:71], v[76:77] op_sel_hi:[1,0,1] neg_lo:[0,0,1] neg_hi:[0,0,1]
	v_xor_b32_e32 v100, 0x80000000, v1
	v_pk_add_f32 v[76:77], v[24:25], v[62:63]
	v_pk_add_f32 v[24:25], v[24:25], v[62:63] neg_lo:[0,1] neg_hi:[0,1]
	v_pk_mul_f32 v[62:63], v[0:1], s[60:61] op_sel_hi:[1,0]
	v_mov_b32_e32 v101, v0
	v_pk_fma_f32 v[0:1], v[100:101], s[62:63], v[62:63] op_sel_hi:[1,0,1] neg_lo:[0,0,1] neg_hi:[0,0,1]
	v_bfe_u32 v100, v102, 1, 4
	v_pk_add_f32 v[62:63], v[80:81], v[0:1]
	v_pk_add_f32 v[0:1], v[80:81], v[0:1] neg_lo:[0,1] neg_hi:[0,1]
	v_lshlrev_b32_e32 v80, 4, v102
	v_lshrrev_b32_e32 v81, 1, v102
	v_bitop3_b32 v101, v81, v80, 16 bitop3:0x6c
	v_lshl_add_u32 v101, v101, 3, 16
	v_lshlrev_b32_e32 v100, 3, v100
	v_add_u32_e32 v102, v101, v100
	ds_write_b64 v102, v[70:71]
	v_bitop3_b32 v70, v81, 1, 15 bitop3:0x6c
	v_lshlrev_b32_e32 v70, 3, v70
	v_add_u32_e32 v71, v101, v70
	ds_write_b64 v71, v[86:87]
	v_bitop3_b32 v71, v81, 2, 15 bitop3:0x6c
	v_lshlrev_b32_e32 v71, 3, v71
	v_add_u32_e32 v86, v101, v71
	ds_write_b64 v86, v[88:89]
	v_bitop3_b32 v86, v81, 3, 15 bitop3:0x6c
	v_lshlrev_b32_e32 v86, 3, v86
	v_add_u32_e32 v87, v101, v86
	ds_write_b64 v87, v[74:75]
	v_bitop3_b32 v74, v81, 4, 15 bitop3:0x6c
	v_lshlrev_b32_e32 v74, 3, v74
	v_add_u32_e32 v75, v101, v74
	ds_write_b64 v75, v[20:21]
	v_bitop3_b32 v20, v81, 5, 15 bitop3:0x6c
	v_lshlrev_b32_e32 v20, 3, v20
	v_add_u32_e32 v21, v101, v20
	ds_write_b64 v21, v[72:73]
	v_bitop3_b32 v21, v81, 6, 15 bitop3:0x6c
	v_lshlrev_b32_e32 v21, 3, v21
	v_add_u32_e32 v72, v101, v21
	ds_write_b64 v72, v[68:69]
	v_bitop3_b32 v68, v81, 7, 15 bitop3:0x6c
	v_lshlrev_b32_e32 v68, 3, v68
	v_add_u32_e32 v69, v101, v68
	ds_write_b64 v69, v[26:27]
	v_bitop3_b32 v26, v81, 8, 15 bitop3:0x6c
	v_lshlrev_b32_e32 v26, 3, v26
	v_add_u32_e32 v27, v101, v26
	ds_write_b64 v27, v[18:19]
	v_bitop3_b32 v18, v81, 9, 15 bitop3:0x6c
	v_lshlrev_b32_e32 v18, 3, v18
	v_add_u32_e32 v19, v101, v18
	ds_write_b64 v19, v[84:85]
	v_bitop3_b32 v19, v81, 10, 15 bitop3:0x6c
	v_lshlrev_b32_e32 v19, 3, v19
	v_add_u32_e32 v27, v101, v19
	ds_write_b64 v27, v[16:17]
	v_bitop3_b32 v16, v81, 11, 15 bitop3:0x6c
	v_lshlrev_b32_e32 v16, 3, v16
	v_add_u32_e32 v17, v101, v16
	ds_write_b64 v17, v[22:23]
	v_bitop3_b32 v17, v81, 12, 15 bitop3:0x6c
	v_lshlrev_b32_e32 v17, 3, v17
	v_add_u32_e32 v22, v101, v17
	ds_write_b64 v22, v[12:13]
	v_bitop3_b32 v12, v81, 13, 15 bitop3:0x6c
	v_lshlrev_b32_e32 v12, 3, v12
	v_add_u32_e32 v13, v101, v12
	ds_write_b64 v13, v[14:15]
	v_bitop3_b32 v13, v81, 14, 15 bitop3:0x6c
	v_lshlrev_b32_e32 v13, 3, v13
	v_add_u32_e32 v14, v101, v13
	ds_write_b64 v14, v[4:5]
	v_bitop3_b32 v4, v81, 15, v81 bitop3:0xc
	v_lshlrev_b32_e32 v4, 3, v4
	v_add_u32_e32 v5, v101, v4
	ds_write_b64 v5, v[8:9]
	v_add_u32_e32 v5, 0x2000, v80
	v_bitop3_b32 v5, v5, v81, 16 bitop3:0x78
	v_lshl_add_u32 v5, v5, 3, 16
	v_add_u32_e32 v8, v5, v100
	ds_write_b64 v8, v[64:65]
	v_add_u32_e32 v8, v5, v70
	ds_write_b64 v8, v[98:99]
	v_add_u32_e32 v8, v5, v71
	ds_write_b64 v8, v[96:97]
	v_add_u32_e32 v8, v5, v86
	ds_write_b64 v8, v[82:83]
	v_add_u32_e32 v8, v5, v74
	ds_write_b64 v8, v[78:79]
	v_add_u32_e32 v8, v5, v20
	ds_write_b64 v8, v[92:93]
	v_add_u32_e32 v8, v5, v21
	ds_write_b64 v8, v[76:77]
	v_add_u32_e32 v8, v5, v68
	ds_write_b64 v8, v[62:63]
	v_add_u32_e32 v8, v5, v26
	ds_write_b64 v8, v[90:91]
	v_add_u32_e32 v8, v5, v18
	ds_write_b64 v8, v[94:95]
	v_add_u32_e32 v8, v5, v19
	ds_write_b64 v8, v[10:11]
	v_add_u32_e32 v8, v5, v16
	ds_write_b64 v8, v[66:67]
	v_add_u32_e32 v8, v5, v17
	ds_write_b64 v8, v[6:7]
	v_add_u32_e32 v6, v5, v12
	ds_write_b64 v6, v[2:3]
	v_add_u32_e32 v2, v5, v13
	ds_write_b64 v2, v[24:25]
	v_add_u32_e32 v2, v5, v4
	v_mov_b32_e32 v22, v146
	ds_write_b64 v2, v[0:1]
	s_waitcnt lgkmcnt(0)
	s_barrier
	s_nop 0
	v_lshlrev_b32_e32 v0, 5, v22
	v_and_b32_e32 v2, 0xfffffe00, v0
	v_and_or_b32 v0, v22, 16, v2
	v_bitop3_b32 v2, v2, 16, v22 bitop3:0x34
	v_bitop3_b32 v6, v22, 4, 15 bitop3:0x6c
	v_bitop3_b32 v14, v22, 8, 15 bitop3:0x6c
	v_lshl_add_u32 v23, v0, 3, 16
	v_lshl_add_u32 v65, v2, 3, 16
	v_lshlrev_b32_e32 v6, 3, v6
	v_lshlrev_b32_e32 v14, 3, v14
	v_bitop3_b32 v2, v22, 1, 15 bitop3:0x6c
	v_add_u32_e32 v105, v23, v6
	v_add_u32_e32 v106, v65, v6
	v_bitop3_b32 v6, v22, 5, 15 bitop3:0x6c
	v_add_u32_e32 v113, v23, v14
	v_add_u32_e32 v114, v65, v14
	v_bitop3_b32 v14, v22, 9, 15 bitop3:0x6c
	v_lshlrev_b32_e32 v2, 3, v2
	v_lshlrev_b32_e32 v6, 3, v6
	v_lshlrev_b32_e32 v14, 3, v14
	v_add_u32_e32 v99, v23, v2
	v_add_u32_e32 v100, v65, v2
	v_bitop3_b32 v2, v22, 2, 15 bitop3:0x6c
	v_add_u32_e32 v107, v23, v6
	v_add_u32_e32 v108, v65, v6
	v_bitop3_b32 v6, v22, 6, 15 bitop3:0x6c
	v_add_u32_e32 v115, v23, v14
	v_add_u32_e32 v116, v65, v14
	v_bitop3_b32 v14, v22, 10, 15 bitop3:0x6c
	v_bitop3_b32 v26, v22, 12, 15 bitop3:0x6c
	v_lshlrev_b32_e32 v2, 3, v2
	v_lshlrev_b32_e32 v6, 3, v6
	v_lshlrev_b32_e32 v14, 3, v14
	v_lshlrev_b32_e32 v26, 3, v26
	v_and_b32_e32 v64, 15, v22
	v_add_u32_e32 v101, v23, v2
	v_add_u32_e32 v102, v65, v2
	v_bitop3_b32 v2, v22, 3, 15 bitop3:0x6c
	v_add_u32_e32 v109, v23, v6
	v_add_u32_e32 v110, v65, v6
	v_bitop3_b32 v6, v22, 7, 15 bitop3:0x6c
	v_add_u32_e32 v117, v23, v14
	v_add_u32_e32 v118, v65, v14
	v_bitop3_b32 v14, v22, 11, 15 bitop3:0x6c
	v_add_u32_e32 v121, v23, v26
	v_add_u32_e32 v122, v65, v26
	v_bitop3_b32 v26, v22, 13, 15 bitop3:0x6c
	v_bitop3_b32 v66, v22, 14, 15 bitop3:0x6c
	v_bitop3_b32 v22, v22, 15, v22 bitop3:0xc
	v_lshlrev_b32_e32 v3, 3, v64
	v_lshlrev_b32_e32 v2, 3, v2
	v_lshlrev_b32_e32 v6, 3, v6
	v_lshlrev_b32_e32 v14, 3, v14
	v_lshlrev_b32_e32 v26, 3, v26
	v_lshlrev_b32_e32 v66, 3, v66
	v_lshlrev_b32_e32 v22, 3, v22
	v_add_u32_e32 v67, v23, v3
	v_add_u32_e32 v98, v65, v3
	v_add_u32_e32 v103, v23, v2
	v_add_u32_e32 v104, v65, v2
	v_add_u32_e32 v111, v23, v6
	v_add_u32_e32 v112, v65, v6
	v_add_u32_e32 v119, v23, v14
	v_add_u32_e32 v120, v65, v14
	v_add_u32_e32 v123, v23, v26
	v_add_u32_e32 v124, v65, v26
	v_add_u32_e32 v125, v23, v66
	v_add_u32_e32 v126, v65, v66
	v_add_u32_e32 v127, v23, v22
	v_add_u32_e32 v128, v65, v22
	ds_read_b64 v[0:1], v67
	ds_read_b64 v[12:13], v98
	ds_read_b64 v[74:75], v99 offset:256
	ds_read_b64 v[4:5], v100 offset:256
	ds_read_b64 v[76:77], v101 offset:512
	ds_read_b64 v[10:11], v102 offset:512
	ds_read_b64 v[70:71], v103 offset:768
	ds_read_b64 v[2:3], v104 offset:768
	ds_read_b64 v[62:63], v105 offset:1024
	ds_read_b64 v[20:21], v106 offset:1024
	ds_read_b64 v[90:91], v107 offset:1280
	ds_read_b64 v[8:9], v108 offset:1280
	ds_read_b64 v[84:85], v109 offset:1536
	ds_read_b64 v[16:17], v110 offset:1536
	ds_read_b64 v[82:83], v111 offset:1792
	ds_read_b64 v[6:7], v112 offset:1792
	ds_read_b64 v[24:25], v113 offset:2048
	ds_read_b64 v[78:79], v114 offset:2048
	ds_read_b64 v[96:97], v115 offset:2304
	ds_read_b64 v[18:19], v116 offset:2304
	ds_read_b64 v[86:87], v117 offset:2560
	ds_read_b64 v[72:73], v118 offset:2560
	ds_read_b64 v[130:131], v119 offset:2816
	ds_read_b64 v[14:15], v120 offset:2816
	ds_read_b64 v[80:81], v121 offset:3072
	ds_read_b64 v[92:93], v122 offset:3072
	ds_read_b64 v[132:133], v123 offset:3328
	ds_read_b64 v[26:27], v124 offset:3328
	ds_read_b64 v[94:95], v125 offset:3584
	ds_read_b64 v[88:89], v126 offset:3584
	ds_read_b64 v[134:135], v127 offset:3840
	ds_read_b64 v[22:23], v128 offset:3840
	s_waitcnt lgkmcnt(14)
	s_nop 0
	v_cvt_f32_i32_e32 v64, v64
	s_nop 0
	v_mul_f32_e32 v64, 0x3b000000, v64
	v_cos_f32_e32 v68, v64
	v_sin_f32_e32 v69, v64
	v_add_f32_e32 v66, v68, v68
	v_pk_mul_f32 v[64:65], v[68:69], v[68:69]
	v_mul_f32_e32 v66, v69, v66
	s_nop 0
	s_nop 0
	v_mov_b32_e32 v140, v69
	v_pk_add_f32 v[64:65], v[64:65], v[64:65] op_sel:[0,1] op_sel_hi:[0,1] neg_lo:[0,1] neg_hi:[0,1]
	v_pk_mul_f32 v[136:137], v[68:69], v[66:67] op_sel:[1,0] op_sel_hi:[0,0] neg_lo:[1,0]
	v_pk_mul_f32 v[138:139], v[24:25], v[140:141] op_sel:[1,0] op_sel_hi:[0,0] neg_lo:[1,0]
	v_pk_fma_f32 v[136:137], v[68:69], v[64:65], v[136:137]
	v_pk_fma_f32 v[24:25], v[24:25], v[68:69], v[138:139] op_sel_hi:[1,0,1]
	v_pk_mul_f32 v[68:69], v[66:67], s[48:49] op_sel_hi:[0,1]
	v_pk_fma_f32 v[138:139], v[64:65], s[40:41], v[68:69]
	s_nop 0
	v_pk_mul_f32 v[68:69], v[62:63], v[138:139] op_sel:[1,1] op_sel_hi:[0,1] neg_lo:[1,0]
	s_nop 0
	v_pk_fma_f32 v[68:69], v[62:63], v[138:139], v[68:69] op_sel_hi:[1,0,1]
	v_pk_mul_f32 v[62:63], v[66:67], v[136:137] op_sel:[0,1] op_sel_hi:[0,0] neg_lo:[0,1]
	v_pk_fma_f32 v[140:141], v[64:65], v[136:137], v[62:63]
	s_waitcnt lgkmcnt(7)
	v_pk_mul_f32 v[62:63], v[80:81], v[136:137] op_sel:[1,1] op_sel_hi:[0,1] neg_lo:[1,0]
	s_nop 0
	v_pk_fma_f32 v[62:63], v[80:81], v[136:137], v[62:63] op_sel_hi:[1,0,1]
	v_pk_mul_f32 v[80:81], v[66:67], v[138:139] op_sel:[0,1] op_sel_hi:[0,0] neg_lo:[0,1]
	v_pk_fma_f32 v[136:137], v[64:65], v[138:139], v[80:81]
	s_nop 0
	v_pk_mul_f32 v[80:81], v[76:77], v[136:137] op_sel:[1,1] op_sel_hi:[0,1] neg_lo:[1,0]
	s_nop 0
	v_pk_fma_f32 v[80:81], v[76:77], v[136:137], v[80:81] op_sel_hi:[1,0,1]
	v_pk_mul_f32 v[76:77], v[66:67], v[140:141] op_sel:[0,1] op_sel_hi:[0,0] neg_lo:[0,1]
	v_pk_fma_f32 v[138:139], v[64:65], v[140:141], v[76:77]
	v_pk_mul_f32 v[76:77], v[86:87], v[140:141] op_sel:[1,1] op_sel_hi:[0,1] neg_lo:[1,0]
	s_nop 0
	v_pk_fma_f32 v[76:77], v[86:87], v[140:141], v[76:77] op_sel_hi:[1,0,1]
	v_pk_mul_f32 v[86:87], v[66:67], v[136:137] op_sel:[0,1] op_sel_hi:[0,0] neg_lo:[0,1]
	v_pk_fma_f32 v[136:137], v[64:65], v[136:137], v[86:87]
	s_nop 0
	v_pk_mul_f32 v[86:87], v[84:85], v[136:137] op_sel:[1,1] op_sel_hi:[0,1] neg_lo:[1,0]
	s_nop 0
	v_pk_fma_f32 v[86:87], v[84:85], v[136:137], v[86:87] op_sel_hi:[1,0,1]
	v_pk_mul_f32 v[84:85], v[66:67], v[138:139] op_sel:[0,1] op_sel_hi:[0,0] neg_lo:[0,1]
	v_pk_fma_f32 v[140:141], v[64:65], v[138:139], v[84:85]
	s_waitcnt lgkmcnt(3)
	v_pk_mul_f32 v[84:85], v[94:95], v[138:139] op_sel:[1,1] op_sel_hi:[0,1] neg_lo:[1,0]
	s_nop 0
	v_pk_fma_f32 v[84:85], v[94:95], v[138:139], v[84:85] op_sel_hi:[1,0,1]
	v_pk_mul_f32 v[94:95], v[66:67], v[136:137] op_sel:[0,1] op_sel_hi:[0,0] neg_lo:[0,1]
	v_pk_fma_f32 v[136:137], v[64:65], v[136:137], v[94:95]
	s_nop 0
	v_pk_mul_f32 v[94:95], v[74:75], v[136:137] op_sel:[1,1] op_sel_hi:[0,1] neg_lo:[1,0]
	s_nop 0
	v_pk_fma_f32 v[94:95], v[74:75], v[136:137], v[94:95] op_sel_hi:[1,0,1]
	v_pk_mul_f32 v[74:75], v[66:67], v[140:141] op_sel:[0,1] op_sel_hi:[0,0] neg_lo:[0,1]
	v_pk_fma_f32 v[138:139], v[64:65], v[140:141], v[74:75]
	v_pk_mul_f32 v[74:75], v[96:97], v[140:141] op_sel:[1,1] op_sel_hi:[0,1] neg_lo:[1,0]
	s_nop 0
	v_pk_fma_f32 v[74:75], v[96:97], v[140:141], v[74:75] op_sel_hi:[1,0,1]
	v_pk_mul_f32 v[96:97], v[66:67], v[136:137] op_sel:[0,1] op_sel_hi:[0,0] neg_lo:[0,1]
	v_pk_fma_f32 v[136:137], v[64:65], v[136:137], v[96:97]
	s_nop 0
	v_pk_mul_f32 v[96:97], v[90:91], v[136:137] op_sel:[1,1] op_sel_hi:[0,1] neg_lo:[1,0]
	s_nop 0
	v_pk_fma_f32 v[96:97], v[90:91], v[136:137], v[96:97] op_sel_hi:[1,0,1]
	v_pk_mul_f32 v[90:91], v[66:67], v[138:139] op_sel:[0,1] op_sel_hi:[0,0] neg_lo:[0,1]
	v_pk_fma_f32 v[140:141], v[64:65], v[138:139], v[90:91]
	v_pk_mul_f32 v[90:91], v[132:133], v[138:139] op_sel:[1,1] op_sel_hi:[0,1] neg_lo:[1,0]
	s_nop 0
	v_pk_fma_f32 v[90:91], v[132:133], v[138:139], v[90:91] op_sel_hi:[1,0,1]
	v_pk_mul_f32 v[132:133], v[66:67], v[136:137] op_sel:[0,1] op_sel_hi:[0,0] neg_lo:[0,1]
	s_nop 0
	v_pk_fma_f32 v[132:133], v[64:65], v[136:137], v[132:133]
	v_pk_mul_f32 v[138:139], v[130:131], v[140:141] op_sel:[1,1] op_sel_hi:[0,1] neg_lo:[1,0]
	v_pk_mul_f32 v[136:137], v[70:71], v[132:133] op_sel:[1,1] op_sel_hi:[0,1] neg_lo:[1,0]
	v_pk_fma_f32 v[130:131], v[130:131], v[140:141], v[138:139] op_sel_hi:[1,0,1]
	v_pk_fma_f32 v[70:71], v[70:71], v[132:133], v[136:137] op_sel_hi:[1,0,1]
	v_pk_mul_f32 v[138:139], v[66:67], v[132:133] op_sel:[0,1] op_sel_hi:[0,0] neg_lo:[0,1]
	v_pk_mul_f32 v[136:137], v[66:67], v[140:141] op_sel:[0,1] op_sel_hi:[0,0] neg_lo:[0,1]
	v_pk_fma_f32 v[132:133], v[64:65], v[132:133], v[138:139]
	v_pk_fma_f32 v[136:137], v[64:65], v[140:141], v[136:137]
	v_pk_mul_f32 v[138:139], v[82:83], v[132:133] op_sel:[1,1] op_sel_hi:[0,1] neg_lo:[1,0]
	s_waitcnt lgkmcnt(1)
	v_pk_fma_f32 v[82:83], v[82:83], v[132:133], v[138:139] op_sel_hi:[1,0,1]
	v_pk_mul_f32 v[138:139], v[66:67], v[136:137] op_sel:[0,1] op_sel_hi:[0,0] neg_lo:[0,1]
	v_pk_mul_f32 v[140:141], v[134:135], v[136:137] op_sel:[1,1] op_sel_hi:[0,1] neg_lo:[1,0]
	v_pk_fma_f32 v[138:139], v[64:65], v[136:137], v[138:139]
	v_pk_fma_f32 v[134:135], v[134:135], v[136:137], v[140:141] op_sel_hi:[1,0,1]
	v_pk_mul_f32 v[136:137], v[66:67], v[132:133] op_sel:[0,1] op_sel_hi:[0,0] neg_lo:[0,1]
	v_pk_fma_f32 v[132:133], v[64:65], v[132:133], v[136:137]
	s_nop 0
	v_pk_mul_f32 v[136:137], v[12:13], v[132:133] op_sel:[1,1] op_sel_hi:[0,1] neg_lo:[1,0]
	s_nop 0
	v_pk_fma_f32 v[12:13], v[12:13], v[132:133], v[136:137] op_sel_hi:[1,0,1]
	v_pk_mul_f32 v[136:137], v[66:67], v[138:139] op_sel:[0,1] op_sel_hi:[0,0] neg_lo:[0,1]
	v_pk_mul_f32 v[140:141], v[78:79], v[138:139] op_sel:[1,1] op_sel_hi:[0,1] neg_lo:[1,0]
	v_pk_fma_f32 v[136:137], v[64:65], v[138:139], v[136:137]
	v_pk_fma_f32 v[78:79], v[78:79], v[138:139], v[140:141] op_sel_hi:[1,0,1]
	v_pk_mul_f32 v[138:139], v[66:67], v[132:133] op_sel:[0,1] op_sel_hi:[0,0] neg_lo:[0,1]
	v_pk_fma_f32 v[132:133], v[64:65], v[132:133], v[138:139]
	s_nop 0
	v_pk_mul_f32 v[138:139], v[20:21], v[132:133] op_sel:[1,1] op_sel_hi:[0,1] neg_lo:[1,0]
	s_nop 0
	v_pk_fma_f32 v[20:21], v[20:21], v[132:133], v[138:139] op_sel_hi:[1,0,1]
	v_pk_mul_f32 v[138:139], v[66:67], v[136:137] op_sel:[0,1] op_sel_hi:[0,0] neg_lo:[0,1]
	v_pk_mul_f32 v[140:141], v[92:93], v[136:137] op_sel:[1,1] op_sel_hi:[0,1] neg_lo:[1,0]
	v_pk_fma_f32 v[138:139], v[64:65], v[136:137], v[138:139]
	v_pk_fma_f32 v[92:93], v[92:93], v[136:137], v[140:141] op_sel_hi:[1,0,1]
	v_pk_mul_f32 v[136:137], v[66:67], v[132:133] op_sel:[0,1] op_sel_hi:[0,0] neg_lo:[0,1]
	v_pk_fma_f32 v[132:133], v[64:65], v[132:133], v[136:137]
	s_nop 0
	v_pk_mul_f32 v[136:137], v[10:11], v[132:133] op_sel:[1,1] op_sel_hi:[0,1] neg_lo:[1,0]
	s_nop 0
	v_pk_fma_f32 v[10:11], v[10:11], v[132:133], v[136:137] op_sel_hi:[1,0,1]
	v_pk_mul_f32 v[136:137], v[66:67], v[138:139] op_sel:[0,1] op_sel_hi:[0,0] neg_lo:[0,1]
	v_pk_mul_f32 v[140:141], v[72:73], v[138:139] op_sel:[1,1] op_sel_hi:[0,1] neg_lo:[1,0]
	v_pk_fma_f32 v[136:137], v[64:65], v[138:139], v[136:137]
	v_pk_fma_f32 v[72:73], v[72:73], v[138:139], v[140:141] op_sel_hi:[1,0,1]
	v_pk_mul_f32 v[138:139], v[66:67], v[132:133] op_sel:[0,1] op_sel_hi:[0,0] neg_lo:[0,1]
	v_pk_fma_f32 v[132:133], v[64:65], v[132:133], v[138:139]
	s_nop 0
	v_pk_mul_f32 v[138:139], v[16:17], v[132:133] op_sel:[1,1] op_sel_hi:[0,1] neg_lo:[1,0]
	s_nop 0
	v_pk_fma_f32 v[16:17], v[16:17], v[132:133], v[138:139] op_sel_hi:[1,0,1]
	v_pk_mul_f32 v[138:139], v[66:67], v[136:137] op_sel:[0,1] op_sel_hi:[0,0] neg_lo:[0,1]
	v_pk_mul_f32 v[140:141], v[88:89], v[136:137] op_sel:[1,1] op_sel_hi:[0,1] neg_lo:[1,0]
	v_pk_fma_f32 v[138:139], v[64:65], v[136:137], v[138:139]
	v_pk_fma_f32 v[88:89], v[88:89], v[136:137], v[140:141] op_sel_hi:[1,0,1]
	v_pk_mul_f32 v[136:137], v[66:67], v[132:133] op_sel:[0,1] op_sel_hi:[0,0] neg_lo:[0,1]
	v_pk_fma_f32 v[132:133], v[64:65], v[132:133], v[136:137]
	s_nop 0
	v_pk_mul_f32 v[136:137], v[4:5], v[132:133] op_sel:[1,1] op_sel_hi:[0,1] neg_lo:[1,0]
	s_nop 0
	v_pk_fma_f32 v[4:5], v[4:5], v[132:133], v[136:137] op_sel_hi:[1,0,1]
	v_pk_mul_f32 v[136:137], v[66:67], v[138:139] op_sel:[0,1] op_sel_hi:[0,0] neg_lo:[0,1]
	v_pk_mul_f32 v[140:141], v[18:19], v[138:139] op_sel:[1,1] op_sel_hi:[0,1] neg_lo:[1,0]
	v_pk_fma_f32 v[136:137], v[64:65], v[138:139], v[136:137]
	v_pk_fma_f32 v[18:19], v[18:19], v[138:139], v[140:141] op_sel_hi:[1,0,1]
	v_pk_mul_f32 v[138:139], v[66:67], v[132:133] op_sel:[0,1] op_sel_hi:[0,0] neg_lo:[0,1]
	v_pk_fma_f32 v[132:133], v[64:65], v[132:133], v[138:139]
	s_nop 0
	v_pk_mul_f32 v[138:139], v[8:9], v[132:133] op_sel:[1,1] op_sel_hi:[0,1] neg_lo:[1,0]
	s_nop 0
	v_pk_fma_f32 v[8:9], v[8:9], v[132:133], v[138:139] op_sel_hi:[1,0,1]
	v_pk_mul_f32 v[138:139], v[66:67], v[136:137] op_sel:[0,1] op_sel_hi:[0,0] neg_lo:[0,1]
	v_pk_mul_f32 v[140:141], v[26:27], v[136:137] op_sel:[1,1] op_sel_hi:[0,1] neg_lo:[1,0]
	v_pk_fma_f32 v[138:139], v[64:65], v[136:137], v[138:139]
	v_pk_fma_f32 v[26:27], v[26:27], v[136:137], v[140:141] op_sel_hi:[1,0,1]
	v_pk_mul_f32 v[136:137], v[66:67], v[132:133] op_sel:[0,1] op_sel_hi:[0,0] neg_lo:[0,1]
	v_pk_fma_f32 v[132:133], v[64:65], v[132:133], v[136:137]
	s_nop 0
	v_pk_mul_f32 v[136:137], v[2:3], v[132:133] op_sel:[1,1] op_sel_hi:[0,1] neg_lo:[1,0]
	s_nop 0
	v_pk_fma_f32 v[2:3], v[2:3], v[132:133], v[136:137] op_sel_hi:[1,0,1]
	v_pk_mul_f32 v[136:137], v[66:67], v[138:139] op_sel:[0,1] op_sel_hi:[0,0] neg_lo:[0,1]
	v_pk_mul_f32 v[140:141], v[14:15], v[138:139] op_sel:[1,1] op_sel_hi:[0,1] neg_lo:[1,0]
	v_pk_fma_f32 v[136:137], v[64:65], v[138:139], v[136:137]
	v_pk_fma_f32 v[14:15], v[14:15], v[138:139], v[140:141] op_sel_hi:[1,0,1]
	v_pk_mul_f32 v[138:139], v[66:67], v[132:133] op_sel:[0,1] op_sel_hi:[0,0] neg_lo:[0,1]
	v_pk_fma_f32 v[64:65], v[64:65], v[132:133], v[138:139]
	s_nop 0
	v_pk_mul_f32 v[132:133], v[6:7], v[64:65] op_sel:[1,1] op_sel_hi:[0,1] neg_lo:[1,0]
	s_nop 0
	v_pk_fma_f32 v[6:7], v[6:7], v[64:65], v[132:133] op_sel_hi:[1,0,1]
	s_waitcnt lgkmcnt(0)
	v_pk_mul_f32 v[64:65], v[22:23], v[136:137] op_sel:[1,1] op_sel_hi:[0,1] neg_lo:[1,0]
	s_nop 0
	v_pk_fma_f32 v[22:23], v[22:23], v[136:137], v[64:65] op_sel_hi:[1,0,1]
	v_pk_add_f32 v[64:65], v[0:1], v[12:13]
	v_pk_add_f32 v[0:1], v[0:1], v[12:13] neg_lo:[0,1] neg_hi:[0,1]
	v_pk_add_f32 v[12:13], v[94:95], v[4:5]
	v_pk_add_f32 v[4:5], v[94:95], v[4:5] neg_lo:[0,1] neg_hi:[0,1]
	v_pk_add_f32 v[94:95], v[80:81], v[10:11]
	v_pk_add_f32 v[10:11], v[80:81], v[10:11] neg_lo:[0,1] neg_hi:[0,1]
	v_pk_add_f32 v[80:81], v[70:71], v[2:3]
	v_pk_add_f32 v[2:3], v[70:71], v[2:3] neg_lo:[0,1] neg_hi:[0,1]
	v_pk_add_f32 v[132:133], v[64:65], v[12:13]
	v_pk_add_f32 v[12:13], v[64:65], v[12:13] neg_lo:[0,1] neg_hi:[0,1]
	v_xor_b32_e32 v64, 0x80000000, v5
	v_mov_b32_e32 v65, v4
	v_pk_add_f32 v[70:71], v[68:69], v[20:21]
	v_pk_add_f32 v[20:21], v[68:69], v[20:21] neg_lo:[0,1] neg_hi:[0,1]
	v_pk_add_f32 v[68:69], v[96:97], v[8:9]
	v_pk_add_f32 v[8:9], v[96:97], v[8:9] neg_lo:[0,1] neg_hi:[0,1]
	v_pk_add_f32 v[4:5], v[0:1], v[64:65]
	v_pk_add_f32 v[0:1], v[0:1], v[64:65] neg_lo:[0,1] neg_hi:[0,1]
	v_pk_add_f32 v[64:65], v[94:95], v[80:81]
	v_pk_add_f32 v[80:81], v[94:95], v[80:81] neg_lo:[0,1] neg_hi:[0,1]
	v_xor_b32_e32 v94, 0x80000000, v3
	v_mov_b32_e32 v95, v2
	v_pk_add_f32 v[96:97], v[86:87], v[16:17]
	v_pk_add_f32 v[16:17], v[86:87], v[16:17] neg_lo:[0,1] neg_hi:[0,1]
	v_pk_add_f32 v[86:87], v[82:83], v[6:7]
	v_pk_add_f32 v[6:7], v[82:83], v[6:7] neg_lo:[0,1] neg_hi:[0,1]
	v_pk_add_f32 v[2:3], v[10:11], v[94:95]
	v_pk_add_f32 v[10:11], v[10:11], v[94:95] neg_lo:[0,1] neg_hi:[0,1]
	v_pk_add_f32 v[94:95], v[70:71], v[68:69]
	v_pk_add_f32 v[68:69], v[70:71], v[68:69] neg_lo:[0,1] neg_hi:[0,1]
	v_xor_b32_e32 v70, 0x80000000, v9
	v_mov_b32_e32 v71, v8
	v_pk_add_f32 v[82:83], v[24:25], v[78:79]
	v_pk_add_f32 v[24:25], v[24:25], v[78:79] neg_lo:[0,1] neg_hi:[0,1]
	v_pk_add_f32 v[78:79], v[74:75], v[18:19]
	v_pk_add_f32 v[18:19], v[74:75], v[18:19] neg_lo:[0,1] neg_hi:[0,1]
	v_pk_add_f32 v[8:9], v[20:21], v[70:71]
	v_pk_add_f32 v[20:21], v[20:21], v[70:71] neg_lo:[0,1] neg_hi:[0,1]
	v_pk_add_f32 v[70:71], v[96:97], v[86:87]
	v_pk_add_f32 v[86:87], v[96:97], v[86:87] neg_lo:[0,1] neg_hi:[0,1]
	v_xor_b32_e32 v96, 0x80000000, v7
	v_mov_b32_e32 v97, v6
	v_pk_add_f32 v[74:75], v[76:77], v[72:73]
	v_pk_add_f32 v[72:73], v[76:77], v[72:73] neg_lo:[0,1] neg_hi:[0,1]
	v_pk_add_f32 v[76:77], v[130:131], v[14:15]
	v_pk_add_f32 v[14:15], v[130:131], v[14:15] neg_lo:[0,1] neg_hi:[0,1]
	v_pk_add_f32 v[6:7], v[16:17], v[96:97]
	v_pk_add_f32 v[16:17], v[16:17], v[96:97] neg_lo:[0,1] neg_hi:[0,1]
	v_pk_add_f32 v[96:97], v[82:83], v[78:79]
	v_pk_add_f32 v[78:79], v[82:83], v[78:79] neg_lo:[0,1] neg_hi:[0,1]
	v_xor_b32_e32 v82, 0x80000000, v19
	v_mov_b32_e32 v83, v18
	v_pk_add_f32 v[130:131], v[62:63], v[92:93]
	v_pk_add_f32 v[62:63], v[62:63], v[92:93] neg_lo:[0,1] neg_hi:[0,1]
	v_pk_add_f32 v[92:93], v[90:91], v[26:27]
	v_pk_add_f32 v[26:27], v[90:91], v[26:27] neg_lo:[0,1] neg_hi:[0,1]
	v_pk_add_f32 v[18:19], v[24:25], v[82:83]
	v_pk_add_f32 v[24:25], v[24:25], v[82:83] neg_lo:[0,1] neg_hi:[0,1]
	v_pk_add_f32 v[82:83], v[74:75], v[76:77]
	v_pk_add_f32 v[74:75], v[74:75], v[76:77] neg_lo:[0,1] neg_hi:[0,1]
	v_xor_b32_e32 v76, 0x80000000, v15
	v_mov_b32_e32 v77, v14
	v_pk_add_f32 v[90:91], v[84:85], v[88:89]
	v_pk_add_f32 v[84:85], v[84:85], v[88:89] neg_lo:[0,1] neg_hi:[0,1]
	v_pk_add_f32 v[88:89], v[134:135], v[22:23]
	v_pk_add_f32 v[22:23], v[134:135], v[22:23] neg_lo:[0,1] neg_hi:[0,1]
	v_pk_add_f32 v[14:15], v[72:73], v[76:77]
	v_pk_add_f32 v[72:73], v[72:73], v[76:77] neg_lo:[0,1] neg_hi:[0,1]
	v_pk_add_f32 v[76:77], v[130:131], v[92:93]
	v_pk_add_f32 v[92:93], v[130:131], v[92:93] neg_lo:[0,1] neg_hi:[0,1]
	v_xor_b32_e32 v130, 0x80000000, v27
	v_mov_b32_e32 v131, v26
	v_pk_add_f32 v[26:27], v[62:63], v[130:131]
	v_pk_add_f32 v[62:63], v[62:63], v[130:131] neg_lo:[0,1] neg_hi:[0,1]
	v_pk_add_f32 v[130:131], v[90:91], v[88:89]
	v_pk_add_f32 v[88:89], v[90:91], v[88:89] neg_lo:[0,1] neg_hi:[0,1]
	v_xor_b32_e32 v90, 0x80000000, v23
	v_mov_b32_e32 v91, v22
	v_pk_add_f32 v[22:23], v[84:85], v[90:91]
	v_pk_add_f32 v[84:85], v[84:85], v[90:91] neg_lo:[0,1] neg_hi:[0,1]
	v_pk_add_f32 v[90:91], v[132:133], v[64:65]
	v_pk_add_f32 v[64:65], v[132:133], v[64:65] neg_lo:[0,1] neg_hi:[0,1]
	v_pk_mul_f32 v[132:133], v[2:3], s[70:71] op_sel:[1,0] op_sel_hi:[0,0] neg_lo:[1,0]
	v_xor_b32_e32 v134, 0x80000000, v11
	v_pk_fma_f32 v[2:3], v[2:3], s[70:71], v[132:133] op_sel_hi:[1,0,1]
	v_mov_b32_e32 v135, v10
	v_pk_add_f32 v[132:133], v[4:5], v[2:3]
	v_pk_add_f32 v[2:3], v[4:5], v[2:3] neg_lo:[0,1] neg_hi:[0,1]
	v_xor_b32_e32 v4, 0x80000000, v81
	v_mov_b32_e32 v5, v80
	v_pk_add_f32 v[80:81], v[12:13], v[4:5]
	v_pk_add_f32 v[4:5], v[12:13], v[4:5] neg_lo:[0,1] neg_hi:[0,1]
	v_pk_mul_f32 v[12:13], v[10:11], s[70:71] op_sel_hi:[1,0]
	s_nop 0
	v_pk_fma_f32 v[10:11], v[134:135], s[70:71], v[12:13] op_sel_hi:[1,0,1] neg_lo:[0,0,1] neg_hi:[0,0,1]
	v_xor_b32_e32 v134, 0x80000000, v17
	v_pk_add_f32 v[12:13], v[0:1], v[10:11]
	v_pk_add_f32 v[0:1], v[0:1], v[10:11] neg_lo:[0,1] neg_hi:[0,1]
	v_pk_add_f32 v[10:11], v[94:95], v[70:71]
	v_pk_add_f32 v[70:71], v[94:95], v[70:71] neg_lo:[0,1] neg_hi:[0,1]
	v_pk_mul_f32 v[94:95], v[6:7], s[70:71] op_sel:[1,0] op_sel_hi:[0,0] neg_lo:[1,0]
	v_mov_b32_e32 v135, v16
	v_pk_fma_f32 v[6:7], v[6:7], s[70:71], v[94:95] op_sel_hi:[1,0,1]
	s_nop 0
	v_pk_add_f32 v[94:95], v[8:9], v[6:7]
	v_pk_add_f32 v[6:7], v[8:9], v[6:7] neg_lo:[0,1] neg_hi:[0,1]
	v_xor_b32_e32 v8, 0x80000000, v87
	v_mov_b32_e32 v9, v86
	v_pk_add_f32 v[86:87], v[68:69], v[8:9]
	v_pk_add_f32 v[8:9], v[68:69], v[8:9] neg_lo:[0,1] neg_hi:[0,1]
	v_pk_mul_f32 v[68:69], v[16:17], s[70:71] op_sel_hi:[1,0]
	s_nop 0
	v_pk_fma_f32 v[16:17], v[134:135], s[70:71], v[68:69] op_sel_hi:[1,0,1] neg_lo:[0,0,1] neg_hi:[0,0,1]
	v_xor_b32_e32 v134, 0x80000000, v73
	v_pk_add_f32 v[68:69], v[20:21], v[16:17]
	v_pk_add_f32 v[16:17], v[20:21], v[16:17] neg_lo:[0,1] neg_hi:[0,1]
	v_pk_add_f32 v[20:21], v[96:97], v[82:83]
	v_pk_add_f32 v[82:83], v[96:97], v[82:83] neg_lo:[0,1] neg_hi:[0,1]
	v_pk_mul_f32 v[96:97], v[14:15], s[70:71] op_sel:[1,0] op_sel_hi:[0,0] neg_lo:[1,0]
	v_mov_b32_e32 v135, v72
	v_pk_fma_f32 v[14:15], v[14:15], s[70:71], v[96:97] op_sel_hi:[1,0,1]
	s_nop 0
	v_pk_add_f32 v[96:97], v[18:19], v[14:15]
	v_pk_add_f32 v[14:15], v[18:19], v[14:15] neg_lo:[0,1] neg_hi:[0,1]
	v_xor_b32_e32 v18, 0x80000000, v75
	v_mov_b32_e32 v19, v74
	v_pk_add_f32 v[74:75], v[78:79], v[18:19]
	v_pk_add_f32 v[18:19], v[78:79], v[18:19] neg_lo:[0,1] neg_hi:[0,1]
	v_pk_mul_f32 v[78:79], v[72:73], s[70:71] op_sel_hi:[1,0]
	s_nop 0
	v_pk_fma_f32 v[72:73], v[134:135], s[70:71], v[78:79] op_sel_hi:[1,0,1] neg_lo:[0,0,1] neg_hi:[0,0,1]
	v_xor_b32_e32 v134, 0x80000000, v85
	v_pk_add_f32 v[78:79], v[24:25], v[72:73]
	v_pk_add_f32 v[24:25], v[24:25], v[72:73] neg_lo:[0,1] neg_hi:[0,1]
	v_pk_add_f32 v[72:73], v[76:77], v[130:131]
	v_pk_add_f32 v[76:77], v[76:77], v[130:131] neg_lo:[0,1] neg_hi:[0,1]
	v_pk_mul_f32 v[130:131], v[22:23], s[70:71] op_sel:[1,0] op_sel_hi:[0,0] neg_lo:[1,0]
	v_mov_b32_e32 v135, v84
	v_pk_fma_f32 v[22:23], v[22:23], s[70:71], v[130:131] op_sel_hi:[1,0,1]
	s_nop 0
	v_pk_add_f32 v[130:131], v[26:27], v[22:23]
	v_pk_add_f32 v[22:23], v[26:27], v[22:23] neg_lo:[0,1] neg_hi:[0,1]
	v_xor_b32_e32 v26, 0x80000000, v89
	v_mov_b32_e32 v27, v88
	v_pk_add_f32 v[88:89], v[92:93], v[26:27]
	v_pk_add_f32 v[26:27], v[92:93], v[26:27] neg_lo:[0,1] neg_hi:[0,1]
	v_pk_mul_f32 v[92:93], v[84:85], s[70:71] op_sel_hi:[1,0]
	s_nop 0
	v_pk_fma_f32 v[84:85], v[134:135], s[70:71], v[92:93] op_sel_hi:[1,0,1] neg_lo:[0,0,1] neg_hi:[0,0,1]
	v_xor_b32_e32 v134, 0x80000000, v7
	v_pk_add_f32 v[92:93], v[62:63], v[84:85]
	v_pk_add_f32 v[62:63], v[62:63], v[84:85] neg_lo:[0,1] neg_hi:[0,1]
	v_pk_add_f32 v[84:85], v[90:91], v[10:11]
	v_pk_add_f32 v[10:11], v[90:91], v[10:11] neg_lo:[0,1] neg_hi:[0,1]
	v_pk_mul_f32 v[90:91], v[94:95], s[62:63] op_sel:[1,0] op_sel_hi:[0,0] neg_lo:[1,0]
	v_mov_b32_e32 v135, v6
	v_pk_fma_f32 v[90:91], v[94:95], s[60:61], v[90:91] op_sel_hi:[1,0,1]
	s_nop 0
	v_pk_add_f32 v[94:95], v[132:133], v[90:91]
	v_pk_add_f32 v[90:91], v[132:133], v[90:91] neg_lo:[0,1] neg_hi:[0,1]
	v_pk_mul_f32 v[132:133], v[86:87], s[70:71] op_sel:[1,0] op_sel_hi:[0,0] neg_lo:[1,0]
	s_nop 0
	v_pk_fma_f32 v[86:87], v[86:87], s[70:71], v[132:133] op_sel_hi:[1,0,1]
	s_nop 0
	v_pk_add_f32 v[132:133], v[80:81], v[86:87]
	v_pk_add_f32 v[80:81], v[80:81], v[86:87] neg_lo:[0,1] neg_hi:[0,1]
	v_pk_mul_f32 v[86:87], v[68:69], s[60:61] op_sel:[1,0] op_sel_hi:[0,0] neg_lo:[1,0]
	s_nop 0
	v_pk_fma_f32 v[68:69], v[68:69], s[62:63], v[86:87] op_sel_hi:[1,0,1]
	s_nop 0
	v_pk_add_f32 v[86:87], v[12:13], v[68:69]
	v_pk_add_f32 v[12:13], v[12:13], v[68:69] neg_lo:[0,1] neg_hi:[0,1]
	v_xor_b32_e32 v68, 0x80000000, v71
	v_mov_b32_e32 v69, v70
	v_pk_add_f32 v[70:71], v[64:65], v[68:69]
	v_pk_add_f32 v[64:65], v[64:65], v[68:69] neg_lo:[0,1] neg_hi:[0,1]
	v_pk_mul_f32 v[68:69], v[6:7], s[62:63] op_sel_hi:[1,0]
	s_nop 0
	v_pk_fma_f32 v[6:7], v[134:135], s[60:61], v[68:69] op_sel_hi:[1,0,1] neg_lo:[0,0,1] neg_hi:[0,0,1]
	v_xor_b32_e32 v134, 0x80000000, v9
	v_pk_add_f32 v[68:69], v[2:3], v[6:7]
	v_pk_add_f32 v[2:3], v[2:3], v[6:7] neg_lo:[0,1] neg_hi:[0,1]
	v_pk_mul_f32 v[6:7], v[8:9], s[70:71] op_sel_hi:[1,0]
	v_mov_b32_e32 v135, v8
	v_pk_fma_f32 v[6:7], v[134:135], s[70:71], v[6:7] op_sel_hi:[1,0,1] neg_lo:[0,0,1] neg_hi:[0,0,1]
	v_xor_b32_e32 v134, 0x80000000, v17
	v_pk_add_f32 v[8:9], v[4:5], v[6:7]
	v_pk_add_f32 v[4:5], v[4:5], v[6:7] neg_lo:[0,1] neg_hi:[0,1]
	v_pk_mul_f32 v[6:7], v[16:17], s[60:61] op_sel_hi:[1,0]
	v_mov_b32_e32 v135, v16
	v_pk_fma_f32 v[6:7], v[134:135], s[62:63], v[6:7] op_sel_hi:[1,0,1] neg_lo:[0,0,1] neg_hi:[0,0,1]
	v_xor_b32_e32 v134, 0x80000000, v23
	v_pk_add_f32 v[16:17], v[0:1], v[6:7]
	v_pk_add_f32 v[0:1], v[0:1], v[6:7] neg_lo:[0,1] neg_hi:[0,1]
	v_pk_add_f32 v[6:7], v[20:21], v[72:73]
	v_pk_add_f32 v[20:21], v[20:21], v[72:73] neg_lo:[0,1] neg_hi:[0,1]
	v_pk_mul_f32 v[72:73], v[130:131], s[62:63] op_sel:[1,0] op_sel_hi:[0,0] neg_lo:[1,0]
	v_mov_b32_e32 v135, v22
	v_pk_fma_f32 v[72:73], v[130:131], s[60:61], v[72:73] op_sel_hi:[1,0,1]
	s_nop 0
	v_pk_add_f32 v[130:131], v[96:97], v[72:73]
	v_pk_add_f32 v[72:73], v[96:97], v[72:73] neg_lo:[0,1] neg_hi:[0,1]
	v_pk_mul_f32 v[96:97], v[88:89], s[70:71] op_sel:[1,0] op_sel_hi:[0,0] neg_lo:[1,0]
	s_nop 0
	v_pk_fma_f32 v[88:89], v[88:89], s[70:71], v[96:97] op_sel_hi:[1,0,1]
	s_nop 0
	v_pk_add_f32 v[96:97], v[74:75], v[88:89]
	v_pk_add_f32 v[74:75], v[74:75], v[88:89] neg_lo:[0,1] neg_hi:[0,1]
	v_pk_mul_f32 v[88:89], v[92:93], s[60:61] op_sel:[1,0] op_sel_hi:[0,0] neg_lo:[1,0]
	s_nop 0
	v_pk_fma_f32 v[88:89], v[92:93], s[62:63], v[88:89] op_sel_hi:[1,0,1]
	s_nop 0
	v_pk_add_f32 v[92:93], v[78:79], v[88:89]
	v_pk_add_f32 v[78:79], v[78:79], v[88:89] neg_lo:[0,1] neg_hi:[0,1]
	v_xor_b32_e32 v88, 0x80000000, v77
	v_mov_b32_e32 v89, v76
	v_pk_add_f32 v[76:77], v[82:83], v[88:89]
	v_pk_add_f32 v[82:83], v[82:83], v[88:89] neg_lo:[0,1] neg_hi:[0,1]
	v_pk_mul_f32 v[88:89], v[22:23], s[62:63] op_sel_hi:[1,0]
	s_nop 0
	v_pk_fma_f32 v[22:23], v[134:135], s[60:61], v[88:89] op_sel_hi:[1,0,1] neg_lo:[0,0,1] neg_hi:[0,0,1]
	v_xor_b32_e32 v134, 0x80000000, v27
	v_pk_add_f32 v[88:89], v[14:15], v[22:23]
	v_pk_add_f32 v[14:15], v[14:15], v[22:23] neg_lo:[0,1] neg_hi:[0,1]
	v_pk_mul_f32 v[22:23], v[26:27], s[70:71] op_sel_hi:[1,0]
	v_mov_b32_e32 v135, v26
	v_pk_fma_f32 v[22:23], v[134:135], s[70:71], v[22:23] op_sel_hi:[1,0,1] neg_lo:[0,0,1] neg_hi:[0,0,1]
	v_xor_b32_e32 v134, 0x80000000, v63
	v_pk_add_f32 v[26:27], v[18:19], v[22:23]
	v_pk_add_f32 v[18:19], v[18:19], v[22:23] neg_lo:[0,1] neg_hi:[0,1]
	v_pk_mul_f32 v[22:23], v[62:63], s[60:61] op_sel_hi:[1,0]
	v_mov_b32_e32 v135, v62
	v_pk_fma_f32 v[22:23], v[134:135], s[62:63], v[22:23] op_sel_hi:[1,0,1] neg_lo:[0,0,1] neg_hi:[0,0,1]
	v_xor_b32_e32 v134, 0x80000000, v73
	v_pk_add_f32 v[62:63], v[24:25], v[22:23]
	v_pk_add_f32 v[22:23], v[24:25], v[22:23] neg_lo:[0,1] neg_hi:[0,1]
	v_pk_add_f32 v[24:25], v[84:85], v[6:7]
	v_pk_add_f32 v[6:7], v[84:85], v[6:7] neg_lo:[0,1] neg_hi:[0,1]
	v_pk_mul_f32 v[84:85], v[130:131], s[58:59] op_sel:[1,0] op_sel_hi:[0,0] neg_lo:[1,0]
	v_mov_b32_e32 v135, v72
	v_pk_fma_f32 v[84:85], v[130:131], s[46:47], v[84:85] op_sel_hi:[1,0,1]
	s_nop 0
	v_pk_add_f32 v[130:131], v[94:95], v[84:85]
	v_pk_add_f32 v[84:85], v[94:95], v[84:85] neg_lo:[0,1] neg_hi:[0,1]
	v_pk_mul_f32 v[94:95], v[96:97], s[62:63] op_sel:[1,0] op_sel_hi:[0,0] neg_lo:[1,0]
	s_nop 0
	v_pk_fma_f32 v[94:95], v[96:97], s[60:61], v[94:95] op_sel_hi:[1,0,1]
	s_nop 0
	v_pk_add_f32 v[96:97], v[132:133], v[94:95]
	v_pk_add_f32 v[94:95], v[132:133], v[94:95] neg_lo:[0,1] neg_hi:[0,1]
	v_pk_mul_f32 v[132:133], v[92:93], s[66:67] op_sel:[1,0] op_sel_hi:[0,0] neg_lo:[1,0]
	s_nop 0
	v_pk_fma_f32 v[92:93], v[92:93], s[64:65], v[132:133] op_sel_hi:[1,0,1]
	s_nop 0
	v_pk_add_f32 v[132:133], v[86:87], v[92:93]
	v_pk_add_f32 v[86:87], v[86:87], v[92:93] neg_lo:[0,1] neg_hi:[0,1]
	v_pk_mul_f32 v[92:93], v[76:77], s[70:71] op_sel:[1,0] op_sel_hi:[0,0] neg_lo:[1,0]
	s_nop 0
	v_pk_fma_f32 v[76:77], v[76:77], s[70:71], v[92:93] op_sel_hi:[1,0,1]
	s_nop 0
	v_pk_add_f32 v[92:93], v[70:71], v[76:77]
	v_pk_add_f32 v[70:71], v[70:71], v[76:77] neg_lo:[0,1] neg_hi:[0,1]
	v_pk_mul_f32 v[76:77], v[88:89], s[64:65] op_sel:[1,0] op_sel_hi:[0,0] neg_lo:[1,0]
	s_nop 0
	v_pk_fma_f32 v[76:77], v[88:89], s[66:67], v[76:77] op_sel_hi:[1,0,1]
	s_nop 0
	v_pk_add_f32 v[88:89], v[68:69], v[76:77]
	v_pk_add_f32 v[68:69], v[68:69], v[76:77] neg_lo:[0,1] neg_hi:[0,1]
	v_pk_mul_f32 v[76:77], v[26:27], s[60:61] op_sel:[1,0] op_sel_hi:[0,0] neg_lo:[1,0]
	s_nop 0
	v_pk_fma_f32 v[26:27], v[26:27], s[62:63], v[76:77] op_sel_hi:[1,0,1]
	s_nop 0
	v_pk_add_f32 v[76:77], v[8:9], v[26:27]
	v_pk_add_f32 v[8:9], v[8:9], v[26:27] neg_lo:[0,1] neg_hi:[0,1]
	v_pk_mul_f32 v[26:27], v[62:63], s[46:47] op_sel:[1,0] op_sel_hi:[0,0] neg_lo:[1,0]
	s_nop 0
	v_pk_fma_f32 v[26:27], v[62:63], s[58:59], v[26:27] op_sel_hi:[1,0,1]
	s_nop 0
	v_pk_add_f32 v[62:63], v[16:17], v[26:27]
	v_pk_add_f32 v[16:17], v[16:17], v[26:27] neg_lo:[0,1] neg_hi:[0,1]
	v_xor_b32_e32 v26, 0x80000000, v21
	v_mov_b32_e32 v27, v20
	v_pk_add_f32 v[20:21], v[10:11], v[26:27]
	v_pk_add_f32 v[10:11], v[10:11], v[26:27] neg_lo:[0,1] neg_hi:[0,1]
	v_pk_mul_f32 v[26:27], v[72:73], s[58:59] op_sel_hi:[1,0]
	s_nop 0
	v_pk_fma_f32 v[26:27], v[134:135], s[46:47], v[26:27] op_sel_hi:[1,0,1] neg_lo:[0,0,1] neg_hi:[0,0,1]
	v_xor_b32_e32 v134, 0x80000000, v75
	v_pk_add_f32 v[72:73], v[90:91], v[26:27]
	v_pk_add_f32 v[26:27], v[90:91], v[26:27] neg_lo:[0,1] neg_hi:[0,1]
	v_pk_mul_f32 v[90:91], v[74:75], s[62:63] op_sel_hi:[1,0]
	v_mov_b32_e32 v135, v74
	v_pk_fma_f32 v[74:75], v[134:135], s[60:61], v[90:91] op_sel_hi:[1,0,1] neg_lo:[0,0,1] neg_hi:[0,0,1]
	v_xor_b32_e32 v134, 0x80000000, v79
	v_pk_add_f32 v[90:91], v[80:81], v[74:75]
	v_pk_add_f32 v[74:75], v[80:81], v[74:75] neg_lo:[0,1] neg_hi:[0,1]
	v_pk_mul_f32 v[80:81], v[78:79], s[66:67] op_sel_hi:[1,0]
	v_mov_b32_e32 v135, v78
	v_pk_fma_f32 v[78:79], v[134:135], s[64:65], v[80:81] op_sel_hi:[1,0,1] neg_lo:[0,0,1] neg_hi:[0,0,1]
	v_xor_b32_e32 v134, 0x80000000, v83
	v_pk_add_f32 v[80:81], v[12:13], v[78:79]
	v_pk_add_f32 v[12:13], v[12:13], v[78:79] neg_lo:[0,1] neg_hi:[0,1]
	v_pk_mul_f32 v[78:79], v[82:83], s[70:71] op_sel_hi:[1,0]
	v_mov_b32_e32 v135, v82
	v_pk_fma_f32 v[78:79], v[134:135], s[70:71], v[78:79] op_sel_hi:[1,0,1] neg_lo:[0,0,1] neg_hi:[0,0,1]
	v_xor_b32_e32 v134, 0x80000000, v15
	v_pk_add_f32 v[82:83], v[64:65], v[78:79]
	v_pk_add_f32 v[64:65], v[64:65], v[78:79] neg_lo:[0,1] neg_hi:[0,1]
	v_pk_mul_f32 v[78:79], v[14:15], s[64:65] op_sel_hi:[1,0]
	v_mov_b32_e32 v135, v14
	v_pk_fma_f32 v[14:15], v[134:135], s[66:67], v[78:79] op_sel_hi:[1,0,1] neg_lo:[0,0,1] neg_hi:[0,0,1]
	v_xor_b32_e32 v134, 0x80000000, v19
	v_pk_add_f32 v[78:79], v[2:3], v[14:15]
	v_pk_add_f32 v[2:3], v[2:3], v[14:15] neg_lo:[0,1] neg_hi:[0,1]
	v_pk_mul_f32 v[14:15], v[18:19], s[60:61] op_sel_hi:[1,0]
	v_mov_b32_e32 v135, v18
	v_pk_fma_f32 v[14:15], v[134:135], s[62:63], v[14:15] op_sel_hi:[1,0,1] neg_lo:[0,0,1] neg_hi:[0,0,1]
	v_xor_b32_e32 v134, 0x80000000, v23
	v_pk_add_f32 v[18:19], v[4:5], v[14:15]
	v_pk_add_f32 v[4:5], v[4:5], v[14:15] neg_lo:[0,1] neg_hi:[0,1]
	v_pk_mul_f32 v[14:15], v[22:23], s[46:47] op_sel_hi:[1,0]
	v_mov_b32_e32 v135, v22
	v_pk_fma_f32 v[14:15], v[134:135], s[58:59], v[14:15] op_sel_hi:[1,0,1] neg_lo:[0,0,1] neg_hi:[0,0,1]
	s_nop 0
	v_pk_add_f32 v[22:23], v[0:1], v[14:15]
	v_pk_add_f32 v[0:1], v[0:1], v[14:15] neg_lo:[0,1] neg_hi:[0,1]
	ds_write_b64 v67, v[24:25]
	ds_write_b64 v98, v[130:131]
	ds_write_b64 v99, v[96:97] offset:256
	ds_write_b64 v100, v[132:133] offset:256
	ds_write_b64 v101, v[92:93] offset:512
	ds_write_b64 v102, v[88:89] offset:512
	ds_write_b64 v103, v[76:77] offset:768
	ds_write_b64 v104, v[62:63] offset:768
	ds_write_b64 v105, v[20:21] offset:1024
	ds_write_b64 v106, v[72:73] offset:1024
	ds_write_b64 v107, v[90:91] offset:1280
	ds_write_b64 v108, v[80:81] offset:1280
	ds_write_b64 v109, v[82:83] offset:1536
	ds_write_b64 v110, v[78:79] offset:1536
	ds_write_b64 v111, v[18:19] offset:1792
	ds_write_b64 v112, v[22:23] offset:1792
	ds_write_b64 v113, v[6:7] offset:2048
	ds_write_b64 v114, v[84:85] offset:2048
	ds_write_b64 v115, v[94:95] offset:2304
	ds_write_b64 v116, v[86:87] offset:2304
	ds_write_b64 v117, v[70:71] offset:2560
	ds_write_b64 v118, v[68:69] offset:2560
	ds_write_b64 v119, v[8:9] offset:2816
	ds_write_b64 v120, v[16:17] offset:2816
	ds_write_b64 v121, v[10:11] offset:3072
	ds_write_b64 v122, v[26:27] offset:3072
	ds_write_b64 v123, v[74:75] offset:3328
	ds_write_b64 v124, v[12:13] offset:3328
	ds_write_b64 v125, v[64:65] offset:3584
	ds_write_b64 v126, v[2:3] offset:3584
	ds_write_b64 v127, v[4:5] offset:3840
	ds_write_b64 v128, v[0:1] offset:3840
	v_mov_b32_e32 v74, v146
	s_waitcnt lgkmcnt(0)
	s_barrier
	s_nop 0
	v_lshrrev_b32_e32 v0, 5, v74
	v_bfe_u32 v4, v74, 5, 4
	v_bitop3_b32 v0, v0, v74, 15 bitop3:0x6c
	v_bitop3_b32 v4, v4, v74, 16 bitop3:0x36
	v_lshlrev_b32_e32 v66, 3, v0
	v_lshlrev_b32_e32 v67, 3, v4
	v_add_u32_e32 v5, 16, v66
	v_add_u32_e32 v4, 16, v67
	v_add_u32_e32 v62, s47, v66
	v_add_u32_e32 v70, s9, v66
	ds_read2st64_b64 v[0:3], v5 offset1:16
	ds_read2st64_b64 v[16:19], v4 offset0:8 offset1:24
	ds_read2st64_b64 v[24:27], v5 offset0:32 offset1:48
	ds_read2st64_b64 v[8:11], v4 offset0:40 offset1:56
	ds_read2st64_b64 v[92:95], v5 offset0:64 offset1:80
	ds_read2st64_b64 v[12:15], v4 offset0:72 offset1:88
	ds_read2st64_b64 v[20:23], v5 offset0:96 offset1:112
	ds_read2st64_b64 v[4:7], v4 offset0:104 offset1:120
	ds_read_b64 v[68:69], v62
	ds_read_b64 v[72:73], v70
	v_add_u32_e32 v62, s19, v67
	v_add_u32_e32 v70, s8, v67
	ds_read_b64 v[84:85], v62
	ds_read_b64 v[90:91], v70
	v_add_u32_e32 v62, s18, v66
	v_add_u32_e32 v70, s7, v66
	ds_read_b64 v[96:97], v62
	ds_read_b64 v[100:101], v70
	v_add_u32_e32 v62, s17, v67
	v_add_u32_e32 v70, s6, v67
	ds_read_b64 v[64:65], v62
	ds_read_b64 v[70:71], v70
	v_add_u32_e32 v62, s13, v66
	v_add_u32_e32 v75, s5, v66
	ds_read_b64 v[86:87], v62
	ds_read_b64 v[102:103], v75
	v_add_u32_e32 v62, s12, v67
	v_add_u32_e32 v75, s4, v67
	ds_read_b64 v[80:81], v62
	ds_read_b64 v[88:89], v75
	v_add_u32_e32 v62, s11, v66
	v_add_u32_e32 v66, s1, v66
	ds_read_b64 v[98:99], v62
	ds_read_b64 v[104:105], v66
	v_add_u32_e32 v62, s10, v67
	v_add_u32_e32 v66, s0, v67
	ds_read_b64 v[62:63], v62
	ds_read_b64 v[66:67], v66
	s_waitcnt lgkmcnt(14)
	s_nop 0
	v_cvt_f32_i32_e32 v74, v74
	s_nop 0
	s_lshl_b64 s[0:1], s[44:45], 2
	s_add_u32 s0, s24, s0
	v_mul_f32_e32 v74, 0x38800000, v74
	v_cos_f32_e32 v78, v74
	v_sin_f32_e32 v79, v74
	s_addc_u32 s1, s59, s1
	s_and_b64 vcc, s[14:15], exec
	v_add_f32_e32 v76, v78, v78
	v_pk_mul_f32 v[74:75], v[78:79], v[78:79]
	v_mul_f32_e32 v76, v79, v76
	s_nop 0
	s_nop 0
	v_mov_b32_e32 v108, v79
	v_pk_add_f32 v[74:75], v[74:75], v[74:75] op_sel:[0,1] op_sel_hi:[0,1] neg_lo:[0,1] neg_hi:[0,1]
	v_pk_mul_f32 v[82:83], v[78:79], v[76:77] op_sel:[1,0] op_sel_hi:[0,0] neg_lo:[1,0]
	v_pk_mul_f32 v[106:107], v[68:69], v[108:109] op_sel:[1,0] op_sel_hi:[0,0] neg_lo:[1,0]
	v_pk_fma_f32 v[82:83], v[78:79], v[74:75], v[82:83]
	v_pk_fma_f32 v[68:69], v[68:69], v[78:79], v[106:107] op_sel_hi:[1,0,1]
	v_pk_mul_f32 v[78:79], v[76:77], s[48:49] op_sel_hi:[0,1]
	v_pk_fma_f32 v[106:107], v[74:75], s[40:41], v[78:79]
	s_nop 0
	v_pk_mul_f32 v[78:79], v[92:93], v[106:107] op_sel:[1,1] op_sel_hi:[0,1] neg_lo:[1,0]
	s_nop 0
	v_pk_fma_f32 v[78:79], v[92:93], v[106:107], v[78:79] op_sel_hi:[1,0,1]
	v_pk_mul_f32 v[92:93], v[76:77], v[82:83] op_sel:[0,1] op_sel_hi:[0,0] neg_lo:[0,1]
	v_pk_mul_f32 v[108:109], v[72:73], v[82:83] op_sel:[1,1] op_sel_hi:[0,1] neg_lo:[1,0]
	v_pk_fma_f32 v[92:93], v[74:75], v[82:83], v[92:93]
	v_pk_fma_f32 v[72:73], v[72:73], v[82:83], v[108:109] op_sel_hi:[1,0,1]
	v_pk_mul_f32 v[82:83], v[76:77], v[106:107] op_sel:[0,1] op_sel_hi:[0,0] neg_lo:[0,1]
	v_pk_fma_f32 v[106:107], v[74:75], v[106:107], v[82:83]
	s_nop 0
	v_pk_mul_f32 v[82:83], v[24:25], v[106:107] op_sel:[1,1] op_sel_hi:[0,1] neg_lo:[1,0]
	s_nop 0
	v_pk_fma_f32 v[82:83], v[24:25], v[106:107], v[82:83] op_sel_hi:[1,0,1]
	v_pk_mul_f32 v[24:25], v[76:77], v[92:93] op_sel:[0,1] op_sel_hi:[0,0] neg_lo:[0,1]
	v_pk_fma_f32 v[108:109], v[74:75], v[92:93], v[24:25]
	s_waitcnt lgkmcnt(7)
	v_pk_mul_f32 v[24:25], v[86:87], v[92:93] op_sel:[1,1] op_sel_hi:[0,1] neg_lo:[1,0]
	s_nop 0
	v_pk_fma_f32 v[24:25], v[86:87], v[92:93], v[24:25] op_sel_hi:[1,0,1]
	v_pk_mul_f32 v[86:87], v[76:77], v[106:107] op_sel:[0,1] op_sel_hi:[0,0] neg_lo:[0,1]
	v_pk_fma_f32 v[92:93], v[74:75], v[106:107], v[86:87]
	s_nop 0
	v_pk_mul_f32 v[86:87], v[20:21], v[92:93] op_sel:[1,1] op_sel_hi:[0,1] neg_lo:[1,0]
	s_nop 0
	v_pk_fma_f32 v[86:87], v[20:21], v[92:93], v[86:87] op_sel_hi:[1,0,1]
	v_pk_mul_f32 v[20:21], v[76:77], v[108:109] op_sel:[0,1] op_sel_hi:[0,0] neg_lo:[0,1]
	v_pk_fma_f32 v[106:107], v[74:75], v[108:109], v[20:21]
	s_waitcnt lgkmcnt(6)
	v_pk_mul_f32 v[20:21], v[102:103], v[108:109] op_sel:[1,1] op_sel_hi:[0,1] neg_lo:[1,0]
	s_nop 0
	v_pk_fma_f32 v[20:21], v[102:103], v[108:109], v[20:21] op_sel_hi:[1,0,1]
	v_pk_mul_f32 v[102:103], v[76:77], v[92:93] op_sel:[0,1] op_sel_hi:[0,0] neg_lo:[0,1]
	v_pk_fma_f32 v[102:103], v[74:75], v[92:93], v[102:103]
	s_nop 0
	v_pk_mul_f32 v[92:93], v[2:3], v[102:103] op_sel:[1,1] op_sel_hi:[0,1] neg_lo:[1,0]
	s_nop 0
	v_pk_fma_f32 v[92:93], v[2:3], v[102:103], v[92:93] op_sel_hi:[1,0,1]
	v_pk_mul_f32 v[2:3], v[76:77], v[106:107] op_sel:[0,1] op_sel_hi:[0,0] neg_lo:[0,1]
	v_pk_fma_f32 v[108:109], v[74:75], v[106:107], v[2:3]
	v_pk_mul_f32 v[2:3], v[96:97], v[106:107] op_sel:[1,1] op_sel_hi:[0,1] neg_lo:[1,0]
	s_nop 0
	v_pk_fma_f32 v[2:3], v[96:97], v[106:107], v[2:3] op_sel_hi:[1,0,1]
	v_pk_mul_f32 v[96:97], v[76:77], v[102:103] op_sel:[0,1] op_sel_hi:[0,0] neg_lo:[0,1]
	v_pk_fma_f32 v[102:103], v[74:75], v[102:103], v[96:97]
	s_nop 0
	v_pk_mul_f32 v[96:97], v[94:95], v[102:103] op_sel:[1,1] op_sel_hi:[0,1] neg_lo:[1,0]
	s_nop 0
	v_pk_fma_f32 v[96:97], v[94:95], v[102:103], v[96:97] op_sel_hi:[1,0,1]
	v_pk_mul_f32 v[94:95], v[76:77], v[108:109] op_sel:[0,1] op_sel_hi:[0,0] neg_lo:[0,1]
	v_pk_fma_f32 v[106:107], v[74:75], v[108:109], v[94:95]
	v_pk_mul_f32 v[94:95], v[100:101], v[108:109] op_sel:[1,1] op_sel_hi:[0,1] neg_lo:[1,0]
	s_nop 0
	v_pk_fma_f32 v[94:95], v[100:101], v[108:109], v[94:95] op_sel_hi:[1,0,1]
	v_pk_mul_f32 v[100:101], v[76:77], v[102:103] op_sel:[0,1] op_sel_hi:[0,0] neg_lo:[0,1]
	v_pk_fma_f32 v[100:101], v[74:75], v[102:103], v[100:101]
	s_nop 0
	v_pk_mul_f32 v[102:103], v[26:27], v[100:101] op_sel:[1,1] op_sel_hi:[0,1] neg_lo:[1,0]
	s_waitcnt lgkmcnt(3)
	v_pk_fma_f32 v[26:27], v[26:27], v[100:101], v[102:103] op_sel_hi:[1,0,1]
	v_pk_mul_f32 v[102:103], v[76:77], v[106:107] op_sel:[0,1] op_sel_hi:[0,0] neg_lo:[0,1]
	v_pk_mul_f32 v[108:109], v[98:99], v[106:107] op_sel:[1,1] op_sel_hi:[0,1] neg_lo:[1,0]
	v_pk_fma_f32 v[102:103], v[74:75], v[106:107], v[102:103]
	v_pk_fma_f32 v[98:99], v[98:99], v[106:107], v[108:109] op_sel_hi:[1,0,1]
	v_pk_mul_f32 v[106:107], v[76:77], v[100:101] op_sel:[0,1] op_sel_hi:[0,0] neg_lo:[0,1]
	v_pk_fma_f32 v[100:101], v[74:75], v[100:101], v[106:107]
	s_nop 0
	v_pk_mul_f32 v[106:107], v[22:23], v[100:101] op_sel:[1,1] op_sel_hi:[0,1] neg_lo:[1,0]
	s_waitcnt lgkmcnt(2)
	v_pk_fma_f32 v[22:23], v[22:23], v[100:101], v[106:107] op_sel_hi:[1,0,1]
	v_pk_mul_f32 v[106:107], v[76:77], v[102:103] op_sel:[0,1] op_sel_hi:[0,0] neg_lo:[0,1]
	v_pk_mul_f32 v[108:109], v[104:105], v[102:103] op_sel:[1,1] op_sel_hi:[0,1] neg_lo:[1,0]
	v_pk_fma_f32 v[106:107], v[74:75], v[102:103], v[106:107]
	v_pk_fma_f32 v[102:103], v[104:105], v[102:103], v[108:109] op_sel_hi:[1,0,1]
	v_pk_mul_f32 v[104:105], v[76:77], v[100:101] op_sel:[0,1] op_sel_hi:[0,0] neg_lo:[0,1]
	v_pk_fma_f32 v[100:101], v[74:75], v[100:101], v[104:105]
	s_nop 0
	v_pk_mul_f32 v[104:105], v[16:17], v[100:101] op_sel:[1,1] op_sel_hi:[0,1] neg_lo:[1,0]
	s_nop 0
	v_pk_fma_f32 v[16:17], v[16:17], v[100:101], v[104:105] op_sel_hi:[1,0,1]
	v_pk_mul_f32 v[104:105], v[76:77], v[106:107] op_sel:[0,1] op_sel_hi:[0,0] neg_lo:[0,1]
	v_pk_mul_f32 v[108:109], v[84:85], v[106:107] op_sel:[1,1] op_sel_hi:[0,1] neg_lo:[1,0]
	v_pk_fma_f32 v[104:105], v[74:75], v[106:107], v[104:105]
	v_pk_fma_f32 v[84:85], v[84:85], v[106:107], v[108:109] op_sel_hi:[1,0,1]
	v_pk_mul_f32 v[106:107], v[76:77], v[100:101] op_sel:[0,1] op_sel_hi:[0,0] neg_lo:[0,1]
	v_pk_fma_f32 v[100:101], v[74:75], v[100:101], v[106:107]
	s_nop 0
	v_pk_mul_f32 v[106:107], v[12:13], v[100:101] op_sel:[1,1] op_sel_hi:[0,1] neg_lo:[1,0]
	s_nop 0
	v_pk_fma_f32 v[12:13], v[12:13], v[100:101], v[106:107] op_sel_hi:[1,0,1]
	v_pk_mul_f32 v[106:107], v[76:77], v[104:105] op_sel:[0,1] op_sel_hi:[0,0] neg_lo:[0,1]
	v_pk_mul_f32 v[108:109], v[90:91], v[104:105] op_sel:[1,1] op_sel_hi:[0,1] neg_lo:[1,0]
	v_pk_fma_f32 v[106:107], v[74:75], v[104:105], v[106:107]
	v_pk_fma_f32 v[90:91], v[90:91], v[104:105], v[108:109] op_sel_hi:[1,0,1]
	v_pk_mul_f32 v[104:105], v[76:77], v[100:101] op_sel:[0,1] op_sel_hi:[0,0] neg_lo:[0,1]
	v_pk_fma_f32 v[100:101], v[74:75], v[100:101], v[104:105]
	s_nop 0
	v_pk_mul_f32 v[104:105], v[8:9], v[100:101] op_sel:[1,1] op_sel_hi:[0,1] neg_lo:[1,0]
	s_nop 0
	v_pk_fma_f32 v[8:9], v[8:9], v[100:101], v[104:105] op_sel_hi:[1,0,1]
	v_pk_mul_f32 v[104:105], v[76:77], v[106:107] op_sel:[0,1] op_sel_hi:[0,0] neg_lo:[0,1]
	v_pk_mul_f32 v[108:109], v[80:81], v[106:107] op_sel:[1,1] op_sel_hi:[0,1] neg_lo:[1,0]
	v_pk_fma_f32 v[104:105], v[74:75], v[106:107], v[104:105]
	v_pk_fma_f32 v[80:81], v[80:81], v[106:107], v[108:109] op_sel_hi:[1,0,1]
	v_pk_mul_f32 v[106:107], v[76:77], v[100:101] op_sel:[0,1] op_sel_hi:[0,0] neg_lo:[0,1]
	v_pk_fma_f32 v[100:101], v[74:75], v[100:101], v[106:107]
	s_nop 0
	v_pk_mul_f32 v[106:107], v[4:5], v[100:101] op_sel:[1,1] op_sel_hi:[0,1] neg_lo:[1,0]
	s_nop 0
	v_pk_fma_f32 v[4:5], v[4:5], v[100:101], v[106:107] op_sel_hi:[1,0,1]
	v_pk_mul_f32 v[106:107], v[76:77], v[104:105] op_sel:[0,1] op_sel_hi:[0,0] neg_lo:[0,1]
	v_pk_mul_f32 v[108:109], v[88:89], v[104:105] op_sel:[1,1] op_sel_hi:[0,1] neg_lo:[1,0]
	v_pk_fma_f32 v[106:107], v[74:75], v[104:105], v[106:107]
	v_pk_fma_f32 v[88:89], v[88:89], v[104:105], v[108:109] op_sel_hi:[1,0,1]
	v_pk_mul_f32 v[104:105], v[76:77], v[100:101] op_sel:[0,1] op_sel_hi:[0,0] neg_lo:[0,1]
	v_pk_fma_f32 v[100:101], v[74:75], v[100:101], v[104:105]
	s_nop 0
	v_pk_mul_f32 v[104:105], v[18:19], v[100:101] op_sel:[1,1] op_sel_hi:[0,1] neg_lo:[1,0]
	s_nop 0
	v_pk_fma_f32 v[18:19], v[18:19], v[100:101], v[104:105] op_sel_hi:[1,0,1]
	v_pk_mul_f32 v[104:105], v[76:77], v[106:107] op_sel:[0,1] op_sel_hi:[0,0] neg_lo:[0,1]
	v_pk_mul_f32 v[108:109], v[64:65], v[106:107] op_sel:[1,1] op_sel_hi:[0,1] neg_lo:[1,0]
	v_pk_fma_f32 v[104:105], v[74:75], v[106:107], v[104:105]
	v_pk_fma_f32 v[64:65], v[64:65], v[106:107], v[108:109] op_sel_hi:[1,0,1]
	v_pk_mul_f32 v[106:107], v[76:77], v[100:101] op_sel:[0,1] op_sel_hi:[0,0] neg_lo:[0,1]
	v_pk_fma_f32 v[100:101], v[74:75], v[100:101], v[106:107]
	s_nop 0
	v_pk_mul_f32 v[106:107], v[14:15], v[100:101] op_sel:[1,1] op_sel_hi:[0,1] neg_lo:[1,0]
	s_nop 0
	v_pk_fma_f32 v[14:15], v[14:15], v[100:101], v[106:107] op_sel_hi:[1,0,1]
	v_pk_mul_f32 v[106:107], v[76:77], v[104:105] op_sel:[0,1] op_sel_hi:[0,0] neg_lo:[0,1]
	v_pk_mul_f32 v[108:109], v[70:71], v[104:105] op_sel:[1,1] op_sel_hi:[0,1] neg_lo:[1,0]
	v_pk_fma_f32 v[106:107], v[74:75], v[104:105], v[106:107]
	v_pk_fma_f32 v[70:71], v[70:71], v[104:105], v[108:109] op_sel_hi:[1,0,1]
	v_pk_mul_f32 v[104:105], v[76:77], v[100:101] op_sel:[0,1] op_sel_hi:[0,0] neg_lo:[0,1]
	v_pk_fma_f32 v[100:101], v[74:75], v[100:101], v[104:105]
	s_nop 0
	v_pk_mul_f32 v[104:105], v[10:11], v[100:101] op_sel:[1,1] op_sel_hi:[0,1] neg_lo:[1,0]
	s_waitcnt lgkmcnt(1)
	v_pk_fma_f32 v[10:11], v[10:11], v[100:101], v[104:105] op_sel_hi:[1,0,1]
	v_pk_mul_f32 v[104:105], v[76:77], v[106:107] op_sel:[0,1] op_sel_hi:[0,0] neg_lo:[0,1]
	v_pk_mul_f32 v[108:109], v[62:63], v[106:107] op_sel:[1,1] op_sel_hi:[0,1] neg_lo:[1,0]
	v_pk_fma_f32 v[104:105], v[74:75], v[106:107], v[104:105]
	v_pk_fma_f32 v[62:63], v[62:63], v[106:107], v[108:109] op_sel_hi:[1,0,1]
	v_pk_mul_f32 v[76:77], v[76:77], v[100:101] op_sel:[0,1] op_sel_hi:[0,0] neg_lo:[0,1]
	v_pk_fma_f32 v[74:75], v[74:75], v[100:101], v[76:77]
	s_nop 0
	v_pk_mul_f32 v[76:77], v[6:7], v[74:75] op_sel:[1,1] op_sel_hi:[0,1] neg_lo:[1,0]
	s_nop 0
	v_pk_fma_f32 v[6:7], v[6:7], v[74:75], v[76:77] op_sel_hi:[1,0,1]
	s_waitcnt lgkmcnt(0)
	v_pk_mul_f32 v[74:75], v[66:67], v[104:105] op_sel:[1,1] op_sel_hi:[0,1] neg_lo:[1,0]
	v_pk_add_f32 v[76:77], v[82:83], v[8:9]
	v_pk_fma_f32 v[66:67], v[66:67], v[104:105], v[74:75] op_sel_hi:[1,0,1]
	v_pk_add_f32 v[74:75], v[0:1], v[16:17]
	v_pk_add_f32 v[0:1], v[0:1], v[16:17] neg_lo:[0,1] neg_hi:[0,1]
	v_pk_add_f32 v[16:17], v[92:93], v[18:19]
	v_pk_add_f32 v[18:19], v[92:93], v[18:19] neg_lo:[0,1] neg_hi:[0,1]
	v_pk_add_f32 v[8:9], v[82:83], v[8:9] neg_lo:[0,1] neg_hi:[0,1]
	v_pk_add_f32 v[82:83], v[26:27], v[10:11]
	v_pk_add_f32 v[10:11], v[26:27], v[10:11] neg_lo:[0,1] neg_hi:[0,1]
	v_pk_add_f32 v[92:93], v[86:87], v[4:5]
	v_pk_add_f32 v[4:5], v[86:87], v[4:5] neg_lo:[0,1] neg_hi:[0,1]
	v_pk_add_f32 v[86:87], v[22:23], v[6:7]
	v_pk_add_f32 v[6:7], v[22:23], v[6:7] neg_lo:[0,1] neg_hi:[0,1]
	v_pk_add_f32 v[22:23], v[68:69], v[84:85]
	v_pk_add_f32 v[68:69], v[68:69], v[84:85] neg_lo:[0,1] neg_hi:[0,1]
	v_pk_add_f32 v[84:85], v[2:3], v[64:65]
	v_pk_add_f32 v[2:3], v[2:3], v[64:65] neg_lo:[0,1] neg_hi:[0,1]
	v_pk_add_f32 v[64:65], v[24:25], v[80:81]
	v_pk_add_f32 v[24:25], v[24:25], v[80:81] neg_lo:[0,1] neg_hi:[0,1]
	v_pk_add_f32 v[80:81], v[98:99], v[62:63]
	v_pk_add_f32 v[62:63], v[98:99], v[62:63] neg_lo:[0,1] neg_hi:[0,1]
	v_pk_add_f32 v[98:99], v[74:75], v[16:17]
	v_pk_add_f32 v[16:17], v[74:75], v[16:17] neg_lo:[0,1] neg_hi:[0,1]
	v_xor_b32_e32 v74, 0x80000000, v19
	v_mov_b32_e32 v75, v18
	v_pk_add_f32 v[26:27], v[78:79], v[12:13]
	v_pk_add_f32 v[12:13], v[78:79], v[12:13] neg_lo:[0,1] neg_hi:[0,1]
	v_pk_add_f32 v[78:79], v[96:97], v[14:15]
	v_pk_add_f32 v[14:15], v[96:97], v[14:15] neg_lo:[0,1] neg_hi:[0,1]
	v_pk_add_f32 v[18:19], v[0:1], v[74:75]
	v_pk_add_f32 v[0:1], v[0:1], v[74:75] neg_lo:[0,1] neg_hi:[0,1]
	v_pk_add_f32 v[74:75], v[76:77], v[82:83]
	v_pk_add_f32 v[76:77], v[76:77], v[82:83] neg_lo:[0,1] neg_hi:[0,1]
	v_xor_b32_e32 v82, 0x80000000, v11
	v_mov_b32_e32 v83, v10
	v_pk_add_f32 v[10:11], v[8:9], v[82:83]
	v_pk_add_f32 v[8:9], v[8:9], v[82:83] neg_lo:[0,1] neg_hi:[0,1]
	v_pk_add_f32 v[82:83], v[26:27], v[78:79]
	v_pk_add_f32 v[26:27], v[26:27], v[78:79] neg_lo:[0,1] neg_hi:[0,1]
	v_xor_b32_e32 v78, 0x80000000, v15
	v_mov_b32_e32 v79, v14
	v_pk_add_f32 v[14:15], v[12:13], v[78:79]
	v_pk_add_f32 v[12:13], v[12:13], v[78:79] neg_lo:[0,1] neg_hi:[0,1]
	v_pk_add_f32 v[78:79], v[92:93], v[86:87]
	v_pk_add_f32 v[86:87], v[92:93], v[86:87] neg_lo:[0,1] neg_hi:[0,1]
	v_xor_b32_e32 v92, 0x80000000, v7
	v_mov_b32_e32 v93, v6
	v_pk_add_f32 v[6:7], v[4:5], v[92:93]
	v_pk_add_f32 v[4:5], v[4:5], v[92:93] neg_lo:[0,1] neg_hi:[0,1]
	v_pk_add_f32 v[92:93], v[22:23], v[84:85]
	v_pk_add_f32 v[22:23], v[22:23], v[84:85] neg_lo:[0,1] neg_hi:[0,1]
	v_xor_b32_e32 v84, 0x80000000, v3
	v_mov_b32_e32 v85, v2
	v_pk_add_f32 v[96:97], v[72:73], v[90:91]
	v_pk_add_f32 v[72:73], v[72:73], v[90:91] neg_lo:[0,1] neg_hi:[0,1]
	v_pk_add_f32 v[90:91], v[94:95], v[70:71]
	v_pk_add_f32 v[70:71], v[94:95], v[70:71] neg_lo:[0,1] neg_hi:[0,1]
	v_pk_add_f32 v[2:3], v[68:69], v[84:85]
	v_pk_add_f32 v[68:69], v[68:69], v[84:85] neg_lo:[0,1] neg_hi:[0,1]
	v_pk_add_f32 v[84:85], v[64:65], v[80:81]
	v_pk_add_f32 v[64:65], v[64:65], v[80:81] neg_lo:[0,1] neg_hi:[0,1]
	v_xor_b32_e32 v80, 0x80000000, v63
	v_mov_b32_e32 v81, v62
	v_pk_add_f32 v[94:95], v[20:21], v[88:89]
	v_pk_add_f32 v[20:21], v[20:21], v[88:89] neg_lo:[0,1] neg_hi:[0,1]
	v_pk_add_f32 v[88:89], v[102:103], v[66:67]
	v_pk_add_f32 v[66:67], v[102:103], v[66:67] neg_lo:[0,1] neg_hi:[0,1]
	v_pk_add_f32 v[62:63], v[24:25], v[80:81]
	v_pk_add_f32 v[24:25], v[24:25], v[80:81] neg_lo:[0,1] neg_hi:[0,1]
	v_pk_add_f32 v[80:81], v[96:97], v[90:91]
	v_pk_add_f32 v[90:91], v[96:97], v[90:91] neg_lo:[0,1] neg_hi:[0,1]
	v_xor_b32_e32 v96, 0x80000000, v71
	v_mov_b32_e32 v97, v70
	v_pk_add_f32 v[70:71], v[72:73], v[96:97]
	v_pk_add_f32 v[72:73], v[72:73], v[96:97] neg_lo:[0,1] neg_hi:[0,1]
	v_pk_add_f32 v[96:97], v[94:95], v[88:89]
	v_pk_add_f32 v[88:89], v[94:95], v[88:89] neg_lo:[0,1] neg_hi:[0,1]
	v_xor_b32_e32 v94, 0x80000000, v67
	v_mov_b32_e32 v95, v66
	v_pk_add_f32 v[66:67], v[20:21], v[94:95]
	v_pk_add_f32 v[20:21], v[20:21], v[94:95] neg_lo:[0,1] neg_hi:[0,1]
	v_pk_add_f32 v[94:95], v[98:99], v[74:75]
	v_pk_add_f32 v[74:75], v[98:99], v[74:75] neg_lo:[0,1] neg_hi:[0,1]
	v_pk_mul_f32 v[98:99], v[10:11], s[70:71] op_sel:[1,0] op_sel_hi:[0,0] neg_lo:[1,0]
	v_xor_b32_e32 v100, 0x80000000, v9
	v_pk_fma_f32 v[10:11], v[10:11], s[70:71], v[98:99] op_sel_hi:[1,0,1]
	v_mov_b32_e32 v101, v8
	v_pk_add_f32 v[98:99], v[18:19], v[10:11]
	v_pk_add_f32 v[10:11], v[18:19], v[10:11] neg_lo:[0,1] neg_hi:[0,1]
	v_xor_b32_e32 v18, 0x80000000, v77
	v_mov_b32_e32 v19, v76
	v_pk_add_f32 v[76:77], v[16:17], v[18:19]
	v_pk_add_f32 v[16:17], v[16:17], v[18:19] neg_lo:[0,1] neg_hi:[0,1]
	v_pk_mul_f32 v[18:19], v[8:9], s[70:71] op_sel_hi:[1,0]
	s_nop 0
	v_pk_fma_f32 v[8:9], v[100:101], s[70:71], v[18:19] op_sel_hi:[1,0,1] neg_lo:[0,0,1] neg_hi:[0,0,1]
	v_xor_b32_e32 v100, 0x80000000, v5
	v_pk_add_f32 v[18:19], v[0:1], v[8:9]
	v_pk_add_f32 v[0:1], v[0:1], v[8:9] neg_lo:[0,1] neg_hi:[0,1]
	v_pk_add_f32 v[8:9], v[82:83], v[78:79]
	v_pk_add_f32 v[78:79], v[82:83], v[78:79] neg_lo:[0,1] neg_hi:[0,1]
	v_pk_mul_f32 v[82:83], v[6:7], s[70:71] op_sel:[1,0] op_sel_hi:[0,0] neg_lo:[1,0]
	v_mov_b32_e32 v101, v4
	v_pk_fma_f32 v[6:7], v[6:7], s[70:71], v[82:83] op_sel_hi:[1,0,1]
	s_nop 0
	v_pk_add_f32 v[82:83], v[14:15], v[6:7]
	v_pk_add_f32 v[6:7], v[14:15], v[6:7] neg_lo:[0,1] neg_hi:[0,1]
	v_xor_b32_e32 v14, 0x80000000, v87
	v_mov_b32_e32 v15, v86
	v_pk_add_f32 v[86:87], v[26:27], v[14:15]
	v_pk_add_f32 v[14:15], v[26:27], v[14:15] neg_lo:[0,1] neg_hi:[0,1]
	v_pk_mul_f32 v[26:27], v[4:5], s[70:71] op_sel_hi:[1,0]
	s_nop 0
	v_pk_fma_f32 v[4:5], v[100:101], s[70:71], v[26:27] op_sel_hi:[1,0,1] neg_lo:[0,0,1] neg_hi:[0,0,1]
	v_xor_b32_e32 v100, 0x80000000, v25
	v_pk_add_f32 v[26:27], v[12:13], v[4:5]
	v_pk_add_f32 v[4:5], v[12:13], v[4:5] neg_lo:[0,1] neg_hi:[0,1]
	v_pk_add_f32 v[12:13], v[92:93], v[84:85]
	v_pk_add_f32 v[84:85], v[92:93], v[84:85] neg_lo:[0,1] neg_hi:[0,1]
	v_pk_mul_f32 v[92:93], v[62:63], s[70:71] op_sel:[1,0] op_sel_hi:[0,0] neg_lo:[1,0]
	v_mov_b32_e32 v101, v24
	v_pk_fma_f32 v[62:63], v[62:63], s[70:71], v[92:93] op_sel_hi:[1,0,1]
	s_nop 0
	v_pk_add_f32 v[92:93], v[2:3], v[62:63]
	v_pk_add_f32 v[2:3], v[2:3], v[62:63] neg_lo:[0,1] neg_hi:[0,1]
	v_xor_b32_e32 v62, 0x80000000, v65
	v_mov_b32_e32 v63, v64
	v_pk_add_f32 v[64:65], v[22:23], v[62:63]
	v_pk_add_f32 v[22:23], v[22:23], v[62:63] neg_lo:[0,1] neg_hi:[0,1]
	v_pk_mul_f32 v[62:63], v[24:25], s[70:71] op_sel_hi:[1,0]
	s_nop 0
	v_pk_fma_f32 v[24:25], v[100:101], s[70:71], v[62:63] op_sel_hi:[1,0,1] neg_lo:[0,0,1] neg_hi:[0,0,1]
	v_xor_b32_e32 v100, 0x80000000, v21
	v_pk_add_f32 v[62:63], v[68:69], v[24:25]
	v_pk_add_f32 v[24:25], v[68:69], v[24:25] neg_lo:[0,1] neg_hi:[0,1]
	v_pk_add_f32 v[68:69], v[80:81], v[96:97]
	v_pk_add_f32 v[80:81], v[80:81], v[96:97] neg_lo:[0,1] neg_hi:[0,1]
	v_pk_mul_f32 v[96:97], v[66:67], s[70:71] op_sel:[1,0] op_sel_hi:[0,0] neg_lo:[1,0]
	v_mov_b32_e32 v101, v20
	v_pk_fma_f32 v[66:67], v[66:67], s[70:71], v[96:97] op_sel_hi:[1,0,1]
	s_nop 0
	v_pk_add_f32 v[96:97], v[70:71], v[66:67]
	v_pk_add_f32 v[66:67], v[70:71], v[66:67] neg_lo:[0,1] neg_hi:[0,1]
	v_xor_b32_e32 v70, 0x80000000, v89
	v_mov_b32_e32 v71, v88
	v_pk_add_f32 v[88:89], v[90:91], v[70:71]
	v_pk_add_f32 v[70:71], v[90:91], v[70:71] neg_lo:[0,1] neg_hi:[0,1]
	v_pk_mul_f32 v[90:91], v[20:21], s[70:71] op_sel_hi:[1,0]
	s_nop 0
	v_pk_fma_f32 v[20:21], v[100:101], s[70:71], v[90:91] op_sel_hi:[1,0,1] neg_lo:[0,0,1] neg_hi:[0,0,1]
	s_nop 0
	v_pk_add_f32 v[90:91], v[72:73], v[20:21]
	v_pk_add_f32 v[20:21], v[72:73], v[20:21] neg_lo:[0,1] neg_hi:[0,1]
	v_pk_add_f32 v[72:73], v[94:95], v[8:9]
	v_pk_add_f32 v[8:9], v[94:95], v[8:9] neg_lo:[0,1] neg_hi:[0,1]
	v_pk_mul_f32 v[94:95], v[82:83], s[62:63] op_sel:[1,0] op_sel_hi:[0,0] neg_lo:[1,0]
	s_nop 0
	v_pk_fma_f32 v[82:83], v[82:83], s[60:61], v[94:95] op_sel_hi:[1,0,1]
	s_nop 0
	v_pk_add_f32 v[94:95], v[98:99], v[82:83]
	v_pk_add_f32 v[82:83], v[98:99], v[82:83] neg_lo:[0,1] neg_hi:[0,1]
	v_pk_mul_f32 v[98:99], v[86:87], s[70:71] op_sel:[1,0] op_sel_hi:[0,0] neg_lo:[1,0]
	s_nop 0
	v_pk_fma_f32 v[86:87], v[86:87], s[70:71], v[98:99] op_sel_hi:[1,0,1]
	s_nop 0
	v_pk_add_f32 v[98:99], v[76:77], v[86:87]
	v_pk_add_f32 v[86:87], v[76:77], v[86:87] neg_lo:[0,1] neg_hi:[0,1]
	v_pk_mul_f32 v[76:77], v[26:27], s[60:61] op_sel:[1,0] op_sel_hi:[0,0] neg_lo:[1,0]
	s_nop 0
	v_pk_fma_f32 v[26:27], v[26:27], s[62:63], v[76:77] op_sel_hi:[1,0,1]
	v_xor_b32_e32 v76, 0x80000000, v67
	v_pk_add_f32 v[100:101], v[18:19], v[26:27]
	v_pk_add_f32 v[26:27], v[18:19], v[26:27] neg_lo:[0,1] neg_hi:[0,1]
	v_pk_add_f32 v[102:103], v[74:75], v[78:79] op_sel:[0,1] op_sel_hi:[1,0] neg_lo:[0,1]
	v_pk_add_f32 v[104:105], v[74:75], v[78:79] op_sel:[0,1] op_sel_hi:[1,0] neg_hi:[0,1]
	v_pk_mul_f32 v[18:19], v[6:7], s[62:63] op_sel_hi:[1,0]
	v_xor_b32_e32 v74, 0x80000000, v7
	v_mov_b32_e32 v75, v6
	v_pk_fma_f32 v[6:7], v[74:75], s[60:61], v[18:19] op_sel_hi:[1,0,1] neg_lo:[0,0,1] neg_hi:[0,0,1]
	v_xor_b32_e32 v74, 0x80000000, v15
	v_pk_add_f32 v[18:19], v[10:11], v[6:7]
	v_pk_add_f32 v[6:7], v[10:11], v[6:7] neg_lo:[0,1] neg_hi:[0,1]
	v_pk_mul_f32 v[10:11], v[14:15], s[70:71] op_sel_hi:[1,0]
	v_mov_b32_e32 v75, v14
	v_pk_fma_f32 v[10:11], v[74:75], s[70:71], v[10:11] op_sel_hi:[1,0,1] neg_lo:[0,0,1] neg_hi:[0,0,1]
	v_xor_b32_e32 v74, 0x80000000, v5
	v_pk_add_f32 v[14:15], v[16:17], v[10:11]
	v_pk_add_f32 v[10:11], v[16:17], v[10:11] neg_lo:[0,1] neg_hi:[0,1]
	v_pk_mul_f32 v[16:17], v[4:5], s[60:61] op_sel_hi:[1,0]
	v_mov_b32_e32 v75, v4
	v_pk_fma_f32 v[4:5], v[74:75], s[62:63], v[16:17] op_sel_hi:[1,0,1] neg_lo:[0,0,1] neg_hi:[0,0,1]
	v_xor_b32_e32 v74, 0x80000000, v89
	v_pk_add_f32 v[16:17], v[0:1], v[4:5]
	v_pk_add_f32 v[106:107], v[0:1], v[4:5] neg_lo:[0,1] neg_hi:[0,1]
	v_pk_add_f32 v[0:1], v[12:13], v[68:69]
	v_pk_add_f32 v[4:5], v[12:13], v[68:69] neg_lo:[0,1] neg_hi:[0,1]
	v_mov_b32_e32 v75, v88
	v_pk_mul_f32 v[12:13], v[96:97], s[62:63] op_sel:[1,0] op_sel_hi:[0,0] neg_lo:[1,0]
	v_pk_mul_f32 v[74:75], v[74:75], s[70:71] op_sel_hi:[1,0]
	v_pk_fma_f32 v[12:13], v[96:97], s[60:61], v[12:13] op_sel_hi:[1,0,1]
	v_pk_fma_f32 v[74:75], v[88:89], s[70:71], v[74:75] op_sel_hi:[1,0,1]
	v_pk_add_f32 v[68:69], v[92:93], v[12:13]
	v_pk_add_f32 v[12:13], v[92:93], v[12:13] neg_lo:[0,1] neg_hi:[0,1]
	v_pk_add_f32 v[88:89], v[64:65], v[74:75]
	v_pk_add_f32 v[92:93], v[64:65], v[74:75] neg_lo:[0,1] neg_hi:[0,1]
	v_pk_mul_f32 v[64:65], v[90:91], s[60:61] op_sel:[1,0] op_sel_hi:[0,0] neg_lo:[1,0]
	v_pk_add_f32 v[78:79], v[72:73], v[0:1]
	v_pk_fma_f32 v[64:65], v[90:91], s[62:63], v[64:65] op_sel_hi:[1,0,1]
	s_nop 0
	v_pk_add_f32 v[74:75], v[62:63], v[64:65]
	v_pk_add_f32 v[90:91], v[62:63], v[64:65] neg_lo:[0,1] neg_hi:[0,1]
	v_pk_mul_f32 v[0:1], v[68:69], s[58:59] op_sel:[1,0] op_sel_hi:[0,0] neg_lo:[1,0]
	v_pk_add_f32 v[64:65], v[84:85], v[80:81] op_sel:[0,1] op_sel_hi:[1,0] neg_lo:[0,1]
	v_pk_add_f32 v[80:81], v[84:85], v[80:81] op_sel:[0,1] op_sel_hi:[1,0] neg_hi:[0,1]
	v_pk_mul_f32 v[62:63], v[66:67], s[62:63] op_sel_hi:[1,0]
	v_mov_b32_e32 v77, v66
	v_pk_fma_f32 v[0:1], v[68:69], s[46:47], v[0:1] op_sel_hi:[1,0,1]
	v_pk_fma_f32 v[62:63], v[76:77], s[60:61], v[62:63] op_sel_hi:[1,0,1] neg_lo:[0,0,1] neg_hi:[0,0,1]
	v_pk_add_f32 v[76:77], v[94:95], v[0:1]
	v_pk_mul_f32 v[0:1], v[88:89], s[62:63] op_sel:[1,0] op_sel_hi:[0,0] neg_lo:[1,0]
	v_pk_add_f32 v[84:85], v[2:3], v[62:63]
	v_pk_fma_f32 v[0:1], v[88:89], s[60:61], v[0:1] op_sel_hi:[1,0,1]
	v_pk_add_f32 v[2:3], v[2:3], v[62:63] neg_lo:[0,1] neg_hi:[0,1]
	v_pk_add_f32 v[72:73], v[98:99], v[0:1]
	v_pk_mul_f32 v[0:1], v[74:75], s[66:67] op_sel:[1,0] op_sel_hi:[0,0] neg_lo:[1,0]
	v_pk_mul_f32 v[62:63], v[70:71], s[70:71] op_sel_hi:[1,0]
	v_pk_fma_f32 v[0:1], v[74:75], s[64:65], v[0:1] op_sel_hi:[1,0,1]
	v_xor_b32_e32 v66, 0x80000000, v71
	v_pk_add_f32 v[74:75], v[100:101], v[0:1]
	v_pk_mul_f32 v[0:1], v[64:65], s[70:71] op_sel:[1,0] op_sel_hi:[0,0] neg_lo:[1,0]
	v_mov_b32_e32 v67, v70
	v_pk_fma_f32 v[0:1], v[64:65], s[70:71], v[0:1] op_sel_hi:[1,0,1]
	v_pk_fma_f32 v[62:63], v[66:67], s[70:71], v[62:63] op_sel_hi:[1,0,1] neg_lo:[0,0,1] neg_hi:[0,0,1]
	v_pk_add_f32 v[66:67], v[102:103], v[0:1]
	v_pk_mul_f32 v[0:1], v[84:85], s[64:65] op_sel:[1,0] op_sel_hi:[0,0] neg_lo:[1,0]
	v_pk_add_f32 v[70:71], v[22:23], v[62:63]
	v_pk_fma_f32 v[0:1], v[84:85], s[66:67], v[0:1] op_sel_hi:[1,0,1]
	v_pk_add_f32 v[96:97], v[22:23], v[62:63] neg_lo:[0,1] neg_hi:[0,1]
	v_pk_mul_f32 v[22:23], v[20:21], s[60:61] op_sel_hi:[1,0]
	v_pk_add_f32 v[68:69], v[18:19], v[0:1]
	v_pk_fma_f32 v[20:21], v[20:21], s[62:63], v[22:23] op_sel:[1,0,0] op_sel_hi:[0,0,1] neg_lo:[1,0,1] neg_hi:[0,0,1]
	v_pk_mul_f32 v[0:1], v[70:71], s[60:61] op_sel:[1,0] op_sel_hi:[0,0] neg_lo:[1,0]
	v_pk_add_f32 v[22:23], v[24:25], v[20:21]
	v_pk_fma_f32 v[0:1], v[70:71], s[62:63], v[0:1] op_sel_hi:[1,0,1]
	v_pk_add_f32 v[108:109], v[24:25], v[20:21] neg_lo:[0,1] neg_hi:[0,1]
	v_pk_add_f32 v[62:63], v[14:15], v[0:1]
	v_pk_mul_f32 v[0:1], v[22:23], s[46:47] op_sel:[1,0] op_sel_hi:[0,0] neg_lo:[1,0]
	s_nop 0
	v_pk_fma_f32 v[0:1], v[22:23], s[58:59], v[0:1] op_sel_hi:[1,0,1]
	s_nop 0
	v_pk_add_f32 v[64:65], v[16:17], v[0:1]
	v_pk_add_f32 v[22:23], v[8:9], v[4:5] op_sel:[0,1] op_sel_hi:[1,0] neg_lo:[0,1]
	v_pk_mul_f32 v[0:1], v[12:13], s[58:59] op_sel_hi:[1,0]
	v_xor_b32_e32 v4, 0x80000000, v13
	v_mov_b32_e32 v5, v12
	v_pk_fma_f32 v[0:1], v[4:5], s[46:47], v[0:1] op_sel_hi:[1,0,1] neg_lo:[0,0,1] neg_hi:[0,0,1]
	v_xor_b32_e32 v4, 0x80000000, v93
	v_pk_add_f32 v[24:25], v[82:83], v[0:1]
	v_pk_mul_f32 v[0:1], v[92:93], s[62:63] op_sel_hi:[1,0]
	v_mov_b32_e32 v5, v92
	v_pk_fma_f32 v[0:1], v[4:5], s[60:61], v[0:1] op_sel_hi:[1,0,1] neg_lo:[0,0,1] neg_hi:[0,0,1]
	v_xor_b32_e32 v4, 0x80000000, v91
	v_pk_add_f32 v[18:19], v[86:87], v[0:1]
	v_pk_mul_f32 v[0:1], v[90:91], s[66:67] op_sel_hi:[1,0]
	v_mov_b32_e32 v5, v90
	v_pk_fma_f32 v[0:1], v[4:5], s[64:65], v[0:1] op_sel_hi:[1,0,1] neg_lo:[0,0,1] neg_hi:[0,0,1]
	s_nop 0
	v_pk_add_f32 v[20:21], v[26:27], v[0:1]
	v_pk_mul_f32 v[0:1], v[80:81], s[70:71] op_sel_hi:[1,0]
	s_nop 0
	v_pk_fma_f32 v[0:1], v[80:81], s[70:71], v[0:1] op_sel:[1,0,0] op_sel_hi:[0,0,1] neg_lo:[1,0,1] neg_hi:[0,0,1]
	v_xor_b32_e32 v8, 0x80000000, v3
	v_pk_add_f32 v[4:5], v[104:105], v[0:1]
	v_pk_mul_f32 v[0:1], v[2:3], s[64:65] op_sel_hi:[1,0]
	v_mov_b32_e32 v9, v2
	v_pk_fma_f32 v[0:1], v[8:9], s[66:67], v[0:1] op_sel_hi:[1,0,1] neg_lo:[0,0,1] neg_hi:[0,0,1]
	s_nop 0
	v_pk_add_f32 v[6:7], v[6:7], v[0:1]
	v_pk_mul_f32 v[0:1], v[96:97], s[60:61] op_sel_hi:[1,0]
	s_nop 0
	v_pk_fma_f32 v[0:1], v[96:97], s[62:63], v[0:1] op_sel:[1,0,0] op_sel_hi:[0,0,1] neg_lo:[1,0,1] neg_hi:[0,0,1]
	v_pk_mul_f32 v[2:3], v[108:109], s[46:47] op_sel_hi:[1,0]
	v_pk_add_f32 v[0:1], v[10:11], v[0:1]
	v_xor_b32_e32 v8, 0x80000000, v109
	v_mov_b32_e32 v9, v108
	v_mov_b32_e32 v10, v146
	v_pk_fma_f32 v[2:3], v[8:9], s[58:59], v[2:3] op_sel_hi:[1,0,1] neg_lo:[0,0,1] neg_hi:[0,0,1]
	global_load_dword v8, v145, s[0:1]
	s_movk_i32 s0, 0x200
	s_cselect_b32 s4, s0, 0x400
	s_add_i32 s0, s4, s68
	s_ashr_i32 s1, s0, 31
	s_lshl_b32 s6, s4, 2
	s_add_u32 s4, s90, s6
	s_addc_u32 s5, s91, 0
	s_lshl_b64 s[0:1], s[0:1], 14
	v_min_i32_e32 v70, 0x1ffe, v10
	v_mov_b32_e32 v9, s6
	s_add_u32 s36, s26, s0
	v_ashrrev_i32_e32 v11, 31, v10
	v_ashrrev_i32_e32 v71, 31, v70
	global_load_dword v16, v9, s[90:91]
	global_load_dword v14, v153, s[4:5] offset:2048
	global_load_dword v17, v154, s[4:5]
	global_load_dword v12, v9, s[94:95]
	s_addc_u32 s37, s27, s1
	v_max_i32_e32 v9, 1, v10
	v_lshlrev_b64 v[82:83], 1, v[10:11]
	v_lshlrev_b64 v[84:85], 1, v[70:71]
	v_lshl_add_u64 v[26:27], s[36:37], 0, v[82:83]
	v_lshlrev_b32_e32 v9, 1, v9
	v_lshl_add_u64 v[70:71], s[36:37], 0, v[84:85]
	global_load_ushort v13, v[26:27], off
	s_add_u32 s88, s30, s0
	global_load_ushort v70, v[70:71], off offset:2
	s_addc_u32 s89, s31, s1
	global_load_ushort v15, v9, s[36:37] offset:-2
	v_cmp_lt_i32_e64 s[0:1], 0, v10
	v_cmp_gt_i32_e64 s[4:5], s74, v10
	v_pk_add_f32 v[2:3], v[106:107], v[2:3]
	v_cndmask_b32_e64 v81, 0, 1.0, s[0:1]
	v_cndmask_b32_e64 v86, 0, 1.0, s[4:5]
	v_add_u32_e32 v92, 0x200, v10
	v_cmp_lt_i32_e64 s[20:21], s25, v10
	v_cmp_gt_i32_e64 s[18:19], s42, v10
	v_add_u32_e32 v90, 0x400, v10
	v_cmp_lt_i32_e64 s[16:17], s33, v10
	v_cmp_gt_i32_e64 s[0:1], s51, v10
	v_add_u32_e32 v88, 0x600, v10
	v_cmp_lt_i32_e64 s[12:13], s43, v10
	v_cmp_gt_i32_e64 s[10:11], s50, v10
	v_cmp_lt_i32_e64 s[8:9], s2, v10
	v_cmp_gt_i32_e64 s[6:7], s38, v10
	v_cmp_lt_i32_e64 s[4:5], s65, v10
	v_cmp_gt_i32_e64 s[22:23], s34, v10
	s_waitcnt vmcnt(2)
	v_lshlrev_b32_e32 v13, 16, v13
	s_waitcnt vmcnt(1)
	v_lshlrev_b32_e32 v70, 16, v70
	v_mul_f32_e32 v70, v86, v70
	s_waitcnt vmcnt(0)
	v_lshlrev_b32_e32 v15, 16, v15
	v_mul_f32_e32 v15, v81, v15
	v_mul_f32_e32 v15, v16, v15
	v_fmac_f32_e32 v15, v14, v13
	v_fmac_f32_e32 v15, v17, v70
	v_lshl_add_u64 v[70:71], s[88:89], 0, v[82:83]
	v_lshl_add_u64 v[82:83], s[88:89], 0, v[84:85]
	v_add_f32_e32 v80, v12, v15
	global_load_ushort v13, v[70:71], off
	global_load_ushort v15, v[82:83], off offset:2
	v_add_u32_e32 v84, 0x800, v10
	global_load_ushort v9, v9, s[88:89] offset:-2
	v_add_u32_e32 v82, 0xa00, v10
	s_waitcnt vmcnt(2)
	v_lshlrev_b32_e32 v13, 16, v13
	s_waitcnt vmcnt(1)
	v_lshlrev_b32_e32 v15, 16, v15
	v_mul_f32_e32 v15, v86, v15
	s_waitcnt vmcnt(0)
	v_lshlrev_b32_e32 v9, 16, v9
	v_mul_f32_e32 v9, v81, v9
	v_mul_f32_e32 v9, v16, v9
	v_fmac_f32_e32 v9, v14, v13
	v_fmac_f32_e32 v9, v17, v15
	v_add_f32_e32 v86, v12, v9
	s_cbranch_vccnz .LBB0_540
	s_lshl_b64 s[0:1], s[92:93], 1
	s_add_u32 s4, s0, s30
	s_addc_u32 s5, s1, s31
	s_add_u32 s0, s0, s26
	s_addc_u32 s1, s1, s27
	s_add_u32 s18, s96, 0x800000
	s_addc_u32 s19, s97, 0
	v_lshlrev_b32_e32 v109, 1, v10
	global_load_ushort v9, v109, s[0:1]
	global_load_ushort v11, v109, s[4:5]
	global_load_ushort v13, v109, s[36:37] offset:1022
	global_load_ushort v15, v109, s[36:37] offset:1024
	global_load_ushort v81, v109, s[36:37] offset:1026
	global_load_ushort v83, v109, s[88:89] offset:1022
	global_load_ushort v85, v109, s[88:89] offset:1024
	global_load_ushort v87, v109, s[88:89] offset:1026
	global_load_ushort v89, v109, s[0:1] offset:1024
	global_load_ushort v91, v109, s[4:5] offset:1024
	global_load_ushort v93, v109, s[36:37] offset:2046
	global_load_ushort v94, v109, s[36:37] offset:2048
	global_load_ushort v95, v109, s[36:37] offset:2050
	global_load_ushort v96, v109, s[88:89] offset:2046
	global_load_ushort v97, v109, s[88:89] offset:2048
	global_load_ushort v98, v109, s[88:89] offset:2050
	global_load_ushort v99, v109, s[0:1] offset:2048
	global_load_ushort v100, v109, s[4:5] offset:2048
	global_load_ushort v101, v109, s[36:37] offset:3070
	global_load_ushort v102, v109, s[36:37] offset:3072
	global_load_ushort v103, v109, s[36:37] offset:3074
	global_load_ushort v104, v109, s[88:89] offset:3070
	global_load_ushort v105, v109, s[88:89] offset:3072
	global_load_ushort v106, v109, s[88:89] offset:3074
	global_load_ushort v107, v109, s[0:1] offset:3072
	global_load_ushort v108, v109, s[4:5] offset:3072
	s_waitcnt vmcnt(0)
	v_lshlrev_b32_e32 v26, 10, v10
	v_fma_f32 v27, v32, v8, v78
	v_mul_f32_e32 v70, v80, v27
	v_lshlrev_b32_e32 v9, 16, v9
	v_mul_f32_e32 v84, 0xbfb8aa3b, v9
	v_exp_f32_e32 v84, v84
	s_nop 0
	v_add_f32_e32 v84, 1.0, v84
	v_div_scale_f32 v71, s[28:29], v84, v84, v9
	v_rcp_f32_e32 v82, v71
	s_nop 0
	v_fma_f32 v92, -v71, v82, 1.0
	v_fmac_f32_e32 v82, v92, v82
	v_div_scale_f32 v88, vcc, v9, v84, v9
	v_mul_f32_e32 v90, v88, v82
	v_fma_f32 v92, -v71, v90, v88
	v_fmac_f32_e32 v90, v92, v82
	v_fma_f32 v71, -v71, v90, v88
	v_div_fmas_f32 v71, v71, v82, v90
	v_div_fixup_f32 v9, v71, v84, v9
	v_mul_f32_e32 v70, v70, v9
	v_cvt_pk_bf16_f32 v70, v70, s0
	global_store_short v26, v70, s[96:97]
	v_fma_f32 v27, v34, v8, v79
	v_mul_f32_e32 v70, v86, v27
	v_lshlrev_b32_e32 v11, 16, v11
	v_mul_f32_e32 v84, 0xbfb8aa3b, v11
	v_exp_f32_e32 v84, v84
	s_nop 0
	v_add_f32_e32 v84, 1.0, v84
	v_div_scale_f32 v71, s[28:29], v84, v84, v11
	v_rcp_f32_e32 v82, v71
	s_nop 0
	v_fma_f32 v92, -v71, v82, 1.0
	v_fmac_f32_e32 v82, v92, v82
	v_div_scale_f32 v88, vcc, v11, v84, v11
	v_mul_f32_e32 v90, v88, v82
	v_fma_f32 v92, -v71, v90, v88
	v_fmac_f32_e32 v90, v92, v82
	v_fma_f32 v71, -v71, v90, v88
	v_div_fmas_f32 v71, v71, v82, v90
	v_div_fixup_f32 v11, v71, v84, v11
	v_mul_f32_e32 v70, v70, v11
	v_cvt_pk_bf16_f32 v70, v70, s0
	global_store_short v26, v70, s[18:19]
	v_add_u32_e32 v26, 0x80000, v26
	v_lshlrev_b32_e32 v15, 16, v15
	v_lshlrev_b32_e32 v81, 16, v81
	v_lshlrev_b32_e32 v13, 16, v13
	v_mul_f32_e32 v13, v16, v13
	v_fmac_f32_e32 v13, v14, v15
	v_fmac_f32_e32 v13, v17, v81
	v_add_f32_e32 v13, v12, v13
	v_fma_f32 v27, v33, v8, v76
	v_mul_f32_e32 v70, v27, v13
	v_lshlrev_b32_e32 v89, 16, v89
	v_mul_f32_e32 v84, 0xbfb8aa3b, v89
	v_exp_f32_e32 v84, v84
	s_nop 0
	v_add_f32_e32 v84, 1.0, v84
	v_div_scale_f32 v71, s[28:29], v84, v84, v89
	v_rcp_f32_e32 v82, v71
	s_nop 0
	v_fma_f32 v92, -v71, v82, 1.0
	v_fmac_f32_e32 v82, v92, v82
	v_div_scale_f32 v88, vcc, v89, v84, v89
	v_mul_f32_e32 v90, v88, v82
	v_fma_f32 v92, -v71, v90, v88
	v_fmac_f32_e32 v90, v92, v82
	v_fma_f32 v71, -v71, v90, v88
	v_div_fmas_f32 v71, v71, v82, v90
	v_div_fixup_f32 v89, v71, v84, v89
	v_mul_f32_e32 v70, v70, v89
	v_cvt_pk_bf16_f32 v70, v70, s0
	global_store_short v26, v70, s[96:97]
	v_lshlrev_b32_e32 v85, 16, v85
	v_lshlrev_b32_e32 v87, 16, v87
	v_lshlrev_b32_e32 v83, 16, v83
	v_mul_f32_e32 v83, v16, v83
	v_fmac_f32_e32 v83, v14, v85
	v_fmac_f32_e32 v83, v17, v87
	v_add_f32_e32 v83, v12, v83
	v_fma_f32 v27, v35, v8, v77
	v_mul_f32_e32 v70, v27, v83
	v_lshlrev_b32_e32 v91, 16, v91
	v_mul_f32_e32 v84, 0xbfb8aa3b, v91
	v_exp_f32_e32 v84, v84
	s_nop 0
	v_add_f32_e32 v84, 1.0, v84
	v_div_scale_f32 v71, s[28:29], v84, v84, v91
	v_rcp_f32_e32 v82, v71
	s_nop 0
	v_fma_f32 v92, -v71, v82, 1.0
	v_fmac_f32_e32 v82, v92, v82
	v_div_scale_f32 v88, vcc, v91, v84, v91
	v_mul_f32_e32 v90, v88, v82
	v_fma_f32 v92, -v71, v90, v88
	v_fmac_f32_e32 v90, v92, v82
	v_fma_f32 v71, -v71, v90, v88
	v_div_fmas_f32 v71, v71, v82, v90
	v_div_fixup_f32 v91, v71, v84, v91
	v_mul_f32_e32 v70, v70, v91
	v_cvt_pk_bf16_f32 v70, v70, s0
	global_store_short v26, v70, s[18:19]
	v_add_u32_e32 v26, 0x80000, v26
	v_lshlrev_b32_e32 v94, 16, v94
	v_lshlrev_b32_e32 v95, 16, v95
	v_lshlrev_b32_e32 v93, 16, v93
	v_mul_f32_e32 v93, v16, v93
	v_fmac_f32_e32 v93, v14, v94
	v_fmac_f32_e32 v93, v17, v95
	v_add_f32_e32 v93, v12, v93
	v_fma_f32 v27, v37, v8, v72
	v_mul_f32_e32 v70, v27, v93
	v_lshlrev_b32_e32 v99, 16, v99
	v_mul_f32_e32 v84, 0xbfb8aa3b, v99
	v_exp_f32_e32 v84, v84
	s_nop 0
	v_add_f32_e32 v84, 1.0, v84
	v_div_scale_f32 v71, s[28:29], v84, v84, v99
	v_rcp_f32_e32 v82, v71
	s_nop 0
	v_fma_f32 v92, -v71, v82, 1.0
	v_fmac_f32_e32 v82, v92, v82
	v_div_scale_f32 v88, vcc, v99, v84, v99
	v_mul_f32_e32 v90, v88, v82
	v_fma_f32 v92, -v71, v90, v88
	v_fmac_f32_e32 v90, v92, v82
	v_fma_f32 v71, -v71, v90, v88
	v_div_fmas_f32 v71, v71, v82, v90
	v_div_fixup_f32 v99, v71, v84, v99
	v_mul_f32_e32 v70, v70, v99
	v_cvt_pk_bf16_f32 v70, v70, s0
	global_store_short v26, v70, s[96:97]
	v_lshlrev_b32_e32 v97, 16, v97
	v_lshlrev_b32_e32 v98, 16, v98
	v_lshlrev_b32_e32 v96, 16, v96
	v_mul_f32_e32 v96, v16, v96
	v_fmac_f32_e32 v96, v14, v97
	v_fmac_f32_e32 v96, v17, v98
	v_add_f32_e32 v96, v12, v96
	v_fma_f32 v27, v31, v8, v73
	v_mul_f32_e32 v70, v27, v96
	v_lshlrev_b32_e32 v100, 16, v100
	v_mul_f32_e32 v84, 0xbfb8aa3b, v100
	v_exp_f32_e32 v84, v84
	s_nop 0
	v_add_f32_e32 v84, 1.0, v84
	v_div_scale_f32 v71, s[28:29], v84, v84, v100
	v_rcp_f32_e32 v82, v71
	s_nop 0
	v_fma_f32 v92, -v71, v82, 1.0
	v_fmac_f32_e32 v82, v92, v82
	v_div_scale_f32 v88, vcc, v100, v84, v100
	v_mul_f32_e32 v90, v88, v82
	v_fma_f32 v92, -v71, v90, v88
	v_fmac_f32_e32 v90, v92, v82
	v_fma_f32 v71, -v71, v90, v88
	v_div_fmas_f32 v71, v71, v82, v90
	v_div_fixup_f32 v100, v71, v84, v100
	v_mul_f32_e32 v70, v70, v100
	v_cvt_pk_bf16_f32 v70, v70, s0
	global_store_short v26, v70, s[18:19]
	v_add_u32_e32 v26, 0x80000, v26
	v_lshlrev_b32_e32 v102, 16, v102
	v_lshlrev_b32_e32 v103, 16, v103
	v_lshlrev_b32_e32 v101, 16, v101
	v_mul_f32_e32 v101, v16, v101
	v_fmac_f32_e32 v101, v14, v102
	v_fmac_f32_e32 v101, v17, v103
	v_add_f32_e32 v101, v12, v101
	v_fma_f32 v27, v36, v8, v74
	v_mul_f32_e32 v70, v27, v101
	v_lshlrev_b32_e32 v107, 16, v107
	v_mul_f32_e32 v84, 0xbfb8aa3b, v107
	v_exp_f32_e32 v84, v84
	s_nop 0
	v_add_f32_e32 v84, 1.0, v84
	v_div_scale_f32 v71, s[28:29], v84, v84, v107
	v_rcp_f32_e32 v82, v71
	s_nop 0
	v_fma_f32 v92, -v71, v82, 1.0
	v_fmac_f32_e32 v82, v92, v82
	v_div_scale_f32 v88, vcc, v107, v84, v107
	v_mul_f32_e32 v90, v88, v82
	v_fma_f32 v92, -v71, v90, v88
	v_fmac_f32_e32 v90, v92, v82
	v_fma_f32 v71, -v71, v90, v88
	v_div_fmas_f32 v71, v71, v82, v90
	v_div_fixup_f32 v107, v71, v84, v107
	v_mul_f32_e32 v70, v70, v107
	v_cvt_pk_bf16_f32 v70, v70, s0
	global_store_short v26, v70, s[96:97]
	v_lshlrev_b32_e32 v105, 16, v105
	v_lshlrev_b32_e32 v106, 16, v106
	v_lshlrev_b32_e32 v104, 16, v104
	v_mul_f32_e32 v104, v16, v104
	v_fmac_f32_e32 v104, v14, v105
	v_fmac_f32_e32 v104, v17, v106
	v_add_f32_e32 v104, v12, v104
	v_fma_f32 v27, v30, v8, v75
	v_mul_f32_e32 v70, v27, v104
	v_lshlrev_b32_e32 v108, 16, v108
	v_mul_f32_e32 v84, 0xbfb8aa3b, v108
	v_exp_f32_e32 v84, v84
	s_nop 0
	v_add_f32_e32 v84, 1.0, v84
	v_div_scale_f32 v71, s[28:29], v84, v84, v108
	v_rcp_f32_e32 v82, v71
	s_nop 0
	v_fma_f32 v92, -v71, v82, 1.0
	v_fmac_f32_e32 v82, v92, v82
	v_div_scale_f32 v88, vcc, v108, v84, v108
	v_mul_f32_e32 v90, v88, v82
	v_fma_f32 v92, -v71, v90, v88
	v_fmac_f32_e32 v90, v92, v82
	v_fma_f32 v71, -v71, v90, v88
	v_div_fmas_f32 v71, v71, v82, v90
	v_div_fixup_f32 v108, v71, v84, v108
	v_mul_f32_e32 v70, v70, v108
	v_cvt_pk_bf16_f32 v70, v70, s0
	global_store_short v26, v70, s[18:19]
	v_add_u32_e32 v109, 0x1000, v109
	global_load_ushort v9, v109, s[36:37] offset:-2
	global_load_ushort v11, v109, s[36:37]
	global_load_ushort v13, v109, s[36:37] offset:2
	global_load_ushort v15, v109, s[88:89] offset:-2
	global_load_ushort v81, v109, s[88:89]
	global_load_ushort v83, v109, s[88:89] offset:2
	global_load_ushort v85, v109, s[0:1]
	global_load_ushort v87, v109, s[4:5]
	global_load_ushort v89, v109, s[36:37] offset:1022
	global_load_ushort v91, v109, s[36:37] offset:1024
	global_load_ushort v93, v109, s[36:37] offset:1026
	global_load_ushort v94, v109, s[88:89] offset:1022
	global_load_ushort v95, v109, s[88:89] offset:1024
	global_load_ushort v96, v109, s[88:89] offset:1026
	global_load_ushort v97, v109, s[0:1] offset:1024
	global_load_ushort v98, v109, s[4:5] offset:1024
	global_load_ushort v99, v109, s[36:37] offset:2046
	global_load_ushort v100, v109, s[36:37] offset:2048
	global_load_ushort v101, v109, s[36:37] offset:2050
	global_load_ushort v102, v109, s[88:89] offset:2046
	global_load_ushort v103, v109, s[88:89] offset:2048
	global_load_ushort v104, v109, s[88:89] offset:2050
	global_load_ushort v105, v109, s[0:1] offset:2048
	global_load_ushort v106, v109, s[4:5] offset:2048
	global_load_ushort v107, v109, s[36:37] offset:3070
	global_load_ushort v108, v109, s[36:37] offset:3072
	global_load_ushort v32, v109, s[36:37] offset:3074
	global_load_ushort v78, v109, s[88:89] offset:3070
	global_load_ushort v34, v109, s[88:89] offset:3072
	global_load_ushort v79, v109, s[88:89] offset:3074
	global_load_ushort v33, v109, s[0:1] offset:3072
	global_load_ushort v76, v109, s[4:5] offset:3072
	s_waitcnt vmcnt(0)
	v_add_u32_e32 v26, 0x80000, v26
	v_lshlrev_b32_e32 v11, 16, v11
	v_lshlrev_b32_e32 v13, 16, v13
	v_lshlrev_b32_e32 v9, 16, v9
	v_mul_f32_e32 v9, v16, v9
	v_fmac_f32_e32 v9, v14, v11
	v_fmac_f32_e32 v9, v17, v13
	v_add_f32_e32 v9, v12, v9
	v_fma_f32 v27, v39, v8, v66
	v_mul_f32_e32 v70, v27, v9
	v_lshlrev_b32_e32 v85, 16, v85
	v_mul_f32_e32 v84, 0xbfb8aa3b, v85
	v_exp_f32_e32 v84, v84
	s_nop 0
	v_add_f32_e32 v84, 1.0, v84
	v_div_scale_f32 v71, s[28:29], v84, v84, v85
	v_rcp_f32_e32 v82, v71
	s_nop 0
	v_fma_f32 v92, -v71, v82, 1.0
	v_fmac_f32_e32 v82, v92, v82
	v_div_scale_f32 v88, vcc, v85, v84, v85
	v_mul_f32_e32 v90, v88, v82
	v_fma_f32 v92, -v71, v90, v88
	v_fmac_f32_e32 v90, v92, v82
	v_fma_f32 v71, -v71, v90, v88
	v_div_fmas_f32 v71, v71, v82, v90
	v_div_fixup_f32 v85, v71, v84, v85
	v_mul_f32_e32 v70, v70, v85
	v_cvt_pk_bf16_f32 v70, v70, s0
	global_store_short v26, v70, s[96:97]
	v_lshlrev_b32_e32 v81, 16, v81
	v_lshlrev_b32_e32 v83, 16, v83
	v_lshlrev_b32_e32 v15, 16, v15
	v_mul_f32_e32 v15, v16, v15
	v_fmac_f32_e32 v15, v14, v81
	v_fmac_f32_e32 v15, v17, v83
	v_add_f32_e32 v15, v12, v15
	v_fma_f32 v27, v41, v8, v67
	v_mul_f32_e32 v70, v27, v15
	v_lshlrev_b32_e32 v87, 16, v87
	v_mul_f32_e32 v84, 0xbfb8aa3b, v87
	v_exp_f32_e32 v84, v84
	s_nop 0
	v_add_f32_e32 v84, 1.0, v84
	v_div_scale_f32 v71, s[28:29], v84, v84, v87
	v_rcp_f32_e32 v82, v71
	s_nop 0
	v_fma_f32 v92, -v71, v82, 1.0
	v_fmac_f32_e32 v82, v92, v82
	v_div_scale_f32 v88, vcc, v87, v84, v87
	v_mul_f32_e32 v90, v88, v82
	v_fma_f32 v92, -v71, v90, v88
	v_fmac_f32_e32 v90, v92, v82
	v_fma_f32 v71, -v71, v90, v88
	v_div_fmas_f32 v71, v71, v82, v90
	v_div_fixup_f32 v87, v71, v84, v87
	v_mul_f32_e32 v70, v70, v87
	v_cvt_pk_bf16_f32 v70, v70, s0
	global_store_short v26, v70, s[18:19]
	v_add_u32_e32 v26, 0x80000, v26
	v_lshlrev_b32_e32 v91, 16, v91
	v_lshlrev_b32_e32 v93, 16, v93
	v_lshlrev_b32_e32 v89, 16, v89
	v_mul_f32_e32 v89, v16, v89
	v_fmac_f32_e32 v89, v14, v91
	v_fmac_f32_e32 v89, v17, v93
	v_add_f32_e32 v89, v12, v89
	v_fma_f32 v27, v38, v8, v68
	v_mul_f32_e32 v70, v27, v89
	v_lshlrev_b32_e32 v97, 16, v97
	v_mul_f32_e32 v84, 0xbfb8aa3b, v97
	v_exp_f32_e32 v84, v84
	s_nop 0
	v_add_f32_e32 v84, 1.0, v84
	v_div_scale_f32 v71, s[28:29], v84, v84, v97
	v_rcp_f32_e32 v82, v71
	s_nop 0
	v_fma_f32 v92, -v71, v82, 1.0
	v_fmac_f32_e32 v82, v92, v82
	v_div_scale_f32 v88, vcc, v97, v84, v97
	v_mul_f32_e32 v90, v88, v82
	v_fma_f32 v92, -v71, v90, v88
	v_fmac_f32_e32 v90, v92, v82
	v_fma_f32 v71, -v71, v90, v88
	v_div_fmas_f32 v71, v71, v82, v90
	v_div_fixup_f32 v97, v71, v84, v97
	v_mul_f32_e32 v70, v70, v97
	v_cvt_pk_bf16_f32 v70, v70, s0
	global_store_short v26, v70, s[96:97]
	v_lshlrev_b32_e32 v95, 16, v95
	v_lshlrev_b32_e32 v96, 16, v96
	v_lshlrev_b32_e32 v94, 16, v94
	v_mul_f32_e32 v94, v16, v94
	v_fmac_f32_e32 v94, v14, v95
	v_fmac_f32_e32 v94, v17, v96
	v_add_f32_e32 v94, v12, v94
	v_fma_f32 v27, v40, v8, v69
	v_mul_f32_e32 v70, v27, v94
	v_lshlrev_b32_e32 v98, 16, v98
	v_mul_f32_e32 v84, 0xbfb8aa3b, v98
	v_exp_f32_e32 v84, v84
	s_nop 0
	v_add_f32_e32 v84, 1.0, v84
	v_div_scale_f32 v71, s[28:29], v84, v84, v98
	v_rcp_f32_e32 v82, v71
	s_nop 0
	v_fma_f32 v92, -v71, v82, 1.0
	v_fmac_f32_e32 v82, v92, v82
	v_div_scale_f32 v88, vcc, v98, v84, v98
	v_mul_f32_e32 v90, v88, v82
	v_fma_f32 v92, -v71, v90, v88
	v_fmac_f32_e32 v90, v92, v82
	v_fma_f32 v71, -v71, v90, v88
	v_div_fmas_f32 v71, v71, v82, v90
	v_div_fixup_f32 v98, v71, v84, v98
	v_mul_f32_e32 v70, v70, v98
	v_cvt_pk_bf16_f32 v70, v70, s0
	global_store_short v26, v70, s[18:19]
	v_add_u32_e32 v26, 0x80000, v26
	v_lshlrev_b32_e32 v100, 16, v100
	v_lshlrev_b32_e32 v101, 16, v101
	v_lshlrev_b32_e32 v99, 16, v99
	v_mul_f32_e32 v99, v16, v99
	v_fmac_f32_e32 v99, v14, v100
	v_fmac_f32_e32 v99, v17, v101
	v_add_f32_e32 v99, v12, v99
	v_fma_f32 v27, v43, v8, v62
	v_mul_f32_e32 v70, v27, v99
	v_lshlrev_b32_e32 v105, 16, v105
	v_mul_f32_e32 v84, 0xbfb8aa3b, v105
	v_exp_f32_e32 v84, v84
	s_nop 0
	v_add_f32_e32 v84, 1.0, v84
	v_div_scale_f32 v71, s[28:29], v84, v84, v105
	v_rcp_f32_e32 v82, v71
	s_nop 0
	v_fma_f32 v92, -v71, v82, 1.0
	v_fmac_f32_e32 v82, v92, v82
	v_div_scale_f32 v88, vcc, v105, v84, v105
	v_mul_f32_e32 v90, v88, v82
	v_fma_f32 v92, -v71, v90, v88
	v_fmac_f32_e32 v90, v92, v82
	v_fma_f32 v71, -v71, v90, v88
	v_div_fmas_f32 v71, v71, v82, v90
	v_div_fixup_f32 v105, v71, v84, v105
	v_mul_f32_e32 v70, v70, v105
	v_cvt_pk_bf16_f32 v70, v70, s0
	global_store_short v26, v70, s[96:97]
	v_lshlrev_b32_e32 v103, 16, v103
	v_lshlrev_b32_e32 v104, 16, v104
	v_lshlrev_b32_e32 v102, 16, v102
	v_mul_f32_e32 v102, v16, v102
	v_fmac_f32_e32 v102, v14, v103
	v_fmac_f32_e32 v102, v17, v104
	v_add_f32_e32 v102, v12, v102
	v_fma_f32 v27, v45, v8, v63
	v_mul_f32_e32 v70, v27, v102
	v_lshlrev_b32_e32 v106, 16, v106
	v_mul_f32_e32 v84, 0xbfb8aa3b, v106
	v_exp_f32_e32 v84, v84
	s_nop 0
	v_add_f32_e32 v84, 1.0, v84
	v_div_scale_f32 v71, s[28:29], v84, v84, v106
	v_rcp_f32_e32 v82, v71
	s_nop 0
	v_fma_f32 v92, -v71, v82, 1.0
	v_fmac_f32_e32 v82, v92, v82
	v_div_scale_f32 v88, vcc, v106, v84, v106
	v_mul_f32_e32 v90, v88, v82
	v_fma_f32 v92, -v71, v90, v88
	v_fmac_f32_e32 v90, v92, v82
	v_fma_f32 v71, -v71, v90, v88
	v_div_fmas_f32 v71, v71, v82, v90
	v_div_fixup_f32 v106, v71, v84, v106
	v_mul_f32_e32 v70, v70, v106
	v_cvt_pk_bf16_f32 v70, v70, s0
	global_store_short v26, v70, s[18:19]
	v_add_u32_e32 v26, 0x80000, v26
	v_lshlrev_b32_e32 v108, 16, v108
	v_lshlrev_b32_e32 v32, 16, v32
	v_lshlrev_b32_e32 v107, 16, v107
	v_mul_f32_e32 v107, v16, v107
	v_fmac_f32_e32 v107, v14, v108
	v_fmac_f32_e32 v107, v17, v32
	v_add_f32_e32 v107, v12, v107
	v_fma_f32 v27, v42, v8, v64
	v_mul_f32_e32 v70, v27, v107
	v_lshlrev_b32_e32 v33, 16, v33
	v_mul_f32_e32 v84, 0xbfb8aa3b, v33
	v_exp_f32_e32 v84, v84
	s_nop 0
	v_add_f32_e32 v84, 1.0, v84
	v_div_scale_f32 v71, s[28:29], v84, v84, v33
	v_rcp_f32_e32 v82, v71
	s_nop 0
	v_fma_f32 v92, -v71, v82, 1.0
	v_fmac_f32_e32 v82, v92, v82
	v_div_scale_f32 v88, vcc, v33, v84, v33
	v_mul_f32_e32 v90, v88, v82
	v_fma_f32 v92, -v71, v90, v88
	v_fmac_f32_e32 v90, v92, v82
	v_fma_f32 v71, -v71, v90, v88
	v_div_fmas_f32 v71, v71, v82, v90
	v_div_fixup_f32 v33, v71, v84, v33
	v_mul_f32_e32 v70, v70, v33
	v_cvt_pk_bf16_f32 v70, v70, s0
	global_store_short v26, v70, s[96:97]
	v_lshlrev_b32_e32 v34, 16, v34
	v_lshlrev_b32_e32 v79, 16, v79
	v_lshlrev_b32_e32 v78, 16, v78
	v_mul_f32_e32 v78, v16, v78
	v_fmac_f32_e32 v78, v14, v34
	v_fmac_f32_e32 v78, v17, v79
	v_add_f32_e32 v78, v12, v78
	v_fma_f32 v27, v44, v8, v65
	v_mul_f32_e32 v70, v27, v78
	v_lshlrev_b32_e32 v76, 16, v76
	v_mul_f32_e32 v84, 0xbfb8aa3b, v76
	v_exp_f32_e32 v84, v84
	s_nop 0
	v_add_f32_e32 v84, 1.0, v84
	v_div_scale_f32 v71, s[28:29], v84, v84, v76
	v_rcp_f32_e32 v82, v71
	s_nop 0
	v_fma_f32 v92, -v71, v82, 1.0
	v_fmac_f32_e32 v82, v92, v82
	v_div_scale_f32 v88, vcc, v76, v84, v76
	v_mul_f32_e32 v90, v88, v82
	v_fma_f32 v92, -v71, v90, v88
	v_fmac_f32_e32 v90, v92, v82
	v_fma_f32 v71, -v71, v90, v88
	v_div_fmas_f32 v71, v71, v82, v90
	v_div_fixup_f32 v76, v71, v84, v76
	v_mul_f32_e32 v70, v70, v76
	v_cvt_pk_bf16_f32 v70, v70, s0
	global_store_short v26, v70, s[18:19]
	v_add_u32_e32 v109, 0x1000, v109
	global_load_ushort v9, v109, s[36:37] offset:-2
	global_load_ushort v11, v109, s[36:37]
	global_load_ushort v13, v109, s[36:37] offset:2
	global_load_ushort v15, v109, s[88:89] offset:-2
	global_load_ushort v81, v109, s[88:89]
	global_load_ushort v83, v109, s[88:89] offset:2
	global_load_ushort v85, v109, s[0:1]
	global_load_ushort v87, v109, s[4:5]
	global_load_ushort v89, v109, s[36:37] offset:1022
	global_load_ushort v91, v109, s[36:37] offset:1024
	global_load_ushort v93, v109, s[36:37] offset:1026
	global_load_ushort v94, v109, s[88:89] offset:1022
	global_load_ushort v95, v109, s[88:89] offset:1024
	global_load_ushort v96, v109, s[88:89] offset:1026
	global_load_ushort v97, v109, s[0:1] offset:1024
	global_load_ushort v98, v109, s[4:5] offset:1024
	global_load_ushort v99, v109, s[36:37] offset:2046
	global_load_ushort v100, v109, s[36:37] offset:2048
	global_load_ushort v101, v109, s[36:37] offset:2050
	global_load_ushort v102, v109, s[88:89] offset:2046
	global_load_ushort v103, v109, s[88:89] offset:2048
	global_load_ushort v104, v109, s[88:89] offset:2050
	global_load_ushort v105, v109, s[0:1] offset:2048
	global_load_ushort v106, v109, s[4:5] offset:2048
	global_load_ushort v107, v109, s[36:37] offset:3070
	global_load_ushort v108, v109, s[36:37] offset:3072
	global_load_ushort v32, v109, s[36:37] offset:3074
	global_load_ushort v78, v109, s[88:89] offset:3070
	global_load_ushort v34, v109, s[88:89] offset:3072
	global_load_ushort v79, v109, s[88:89] offset:3074
	global_load_ushort v33, v109, s[0:1] offset:3072
	global_load_ushort v76, v109, s[4:5] offset:3072
	s_waitcnt vmcnt(0)
	v_add_u32_e32 v26, 0x80000, v26
	v_lshlrev_b32_e32 v11, 16, v11
	v_lshlrev_b32_e32 v13, 16, v13
	v_lshlrev_b32_e32 v9, 16, v9
	v_mul_f32_e32 v9, v16, v9
	v_fmac_f32_e32 v9, v14, v11
	v_fmac_f32_e32 v9, v17, v13
	v_add_f32_e32 v9, v12, v9
	v_fma_f32 v27, v47, v8, v22
	v_mul_f32_e32 v70, v27, v9
	v_lshlrev_b32_e32 v85, 16, v85
	v_mul_f32_e32 v84, 0xbfb8aa3b, v85
	v_exp_f32_e32 v84, v84
	s_nop 0
	v_add_f32_e32 v84, 1.0, v84
	v_div_scale_f32 v71, s[28:29], v84, v84, v85
	v_rcp_f32_e32 v82, v71
	s_nop 0
	v_fma_f32 v92, -v71, v82, 1.0
	v_fmac_f32_e32 v82, v92, v82
	v_div_scale_f32 v88, vcc, v85, v84, v85
	v_mul_f32_e32 v90, v88, v82
	v_fma_f32 v92, -v71, v90, v88
	v_fmac_f32_e32 v90, v92, v82
	v_fma_f32 v71, -v71, v90, v88
	v_div_fmas_f32 v71, v71, v82, v90
	v_div_fixup_f32 v85, v71, v84, v85
	v_mul_f32_e32 v70, v70, v85
	v_cvt_pk_bf16_f32 v70, v70, s0
	global_store_short v26, v70, s[96:97]
	v_lshlrev_b32_e32 v81, 16, v81
	v_lshlrev_b32_e32 v83, 16, v83
	v_lshlrev_b32_e32 v15, 16, v15
	v_mul_f32_e32 v15, v16, v15
	v_fmac_f32_e32 v15, v14, v81
	v_fmac_f32_e32 v15, v17, v83
	v_add_f32_e32 v15, v12, v15
	v_fma_f32 v27, v49, v8, v23
	v_mul_f32_e32 v70, v27, v15
	v_lshlrev_b32_e32 v87, 16, v87
	v_mul_f32_e32 v84, 0xbfb8aa3b, v87
	v_exp_f32_e32 v84, v84
	s_nop 0
	v_add_f32_e32 v84, 1.0, v84
	v_div_scale_f32 v71, s[28:29], v84, v84, v87
	v_rcp_f32_e32 v82, v71
	s_nop 0
	v_fma_f32 v92, -v71, v82, 1.0
	v_fmac_f32_e32 v82, v92, v82
	v_div_scale_f32 v88, vcc, v87, v84, v87
	v_mul_f32_e32 v90, v88, v82
	v_fma_f32 v92, -v71, v90, v88
	v_fmac_f32_e32 v90, v92, v82
	v_fma_f32 v71, -v71, v90, v88
	v_div_fmas_f32 v71, v71, v82, v90
	v_div_fixup_f32 v87, v71, v84, v87
	v_mul_f32_e32 v70, v70, v87
	v_cvt_pk_bf16_f32 v70, v70, s0
	global_store_short v26, v70, s[18:19]
	v_add_u32_e32 v26, 0x80000, v26
	v_lshlrev_b32_e32 v91, 16, v91
	v_lshlrev_b32_e32 v93, 16, v93
	v_lshlrev_b32_e32 v89, 16, v89
	v_mul_f32_e32 v89, v16, v89
	v_fmac_f32_e32 v89, v14, v91
	v_fmac_f32_e32 v89, v17, v93
	v_add_f32_e32 v89, v12, v89
	v_fma_f32 v27, v46, v8, v24
	v_mul_f32_e32 v70, v27, v89
	v_lshlrev_b32_e32 v97, 16, v97
	v_mul_f32_e32 v84, 0xbfb8aa3b, v97
	v_exp_f32_e32 v84, v84
	s_nop 0
	v_add_f32_e32 v84, 1.0, v84
	v_div_scale_f32 v71, s[28:29], v84, v84, v97
	v_rcp_f32_e32 v82, v71
	s_nop 0
	v_fma_f32 v92, -v71, v82, 1.0
	v_fmac_f32_e32 v82, v92, v82
	v_div_scale_f32 v88, vcc, v97, v84, v97
	v_mul_f32_e32 v90, v88, v82
	v_fma_f32 v92, -v71, v90, v88
	v_fmac_f32_e32 v90, v92, v82
	v_fma_f32 v71, -v71, v90, v88
	v_div_fmas_f32 v71, v71, v82, v90
	v_div_fixup_f32 v97, v71, v84, v97
	v_mul_f32_e32 v70, v70, v97
	v_cvt_pk_bf16_f32 v70, v70, s0
	global_store_short v26, v70, s[96:97]
	v_lshlrev_b32_e32 v95, 16, v95
	v_lshlrev_b32_e32 v96, 16, v96
	v_lshlrev_b32_e32 v94, 16, v94
	v_mul_f32_e32 v94, v16, v94
	v_fmac_f32_e32 v94, v14, v95
	v_fmac_f32_e32 v94, v17, v96
	v_add_f32_e32 v94, v12, v94
	v_fma_f32 v27, v48, v8, v25
	v_mul_f32_e32 v70, v27, v94
	v_lshlrev_b32_e32 v98, 16, v98
	v_mul_f32_e32 v84, 0xbfb8aa3b, v98
	v_exp_f32_e32 v84, v84
	s_nop 0
	v_add_f32_e32 v84, 1.0, v84
	v_div_scale_f32 v71, s[28:29], v84, v84, v98
	v_rcp_f32_e32 v82, v71
	s_nop 0
	v_fma_f32 v92, -v71, v82, 1.0
	v_fmac_f32_e32 v82, v92, v82
	v_div_scale_f32 v88, vcc, v98, v84, v98
	v_mul_f32_e32 v90, v88, v82
	v_fma_f32 v92, -v71, v90, v88
	v_fmac_f32_e32 v90, v92, v82
	v_fma_f32 v71, -v71, v90, v88
	v_div_fmas_f32 v71, v71, v82, v90
	v_div_fixup_f32 v98, v71, v84, v98
	v_mul_f32_e32 v70, v70, v98
	v_cvt_pk_bf16_f32 v70, v70, s0
	global_store_short v26, v70, s[18:19]
	v_add_u32_e32 v26, 0x80000, v26
	v_lshlrev_b32_e32 v100, 16, v100
	v_lshlrev_b32_e32 v101, 16, v101
	v_lshlrev_b32_e32 v99, 16, v99
	v_mul_f32_e32 v99, v16, v99
	v_fmac_f32_e32 v99, v14, v100
	v_fmac_f32_e32 v99, v17, v101
	v_add_f32_e32 v99, v12, v99
	v_fma_f32 v27, v51, v8, v18
	v_mul_f32_e32 v70, v27, v99
	v_lshlrev_b32_e32 v105, 16, v105
	v_mul_f32_e32 v84, 0xbfb8aa3b, v105
	v_exp_f32_e32 v84, v84
	s_nop 0
	v_add_f32_e32 v84, 1.0, v84
	v_div_scale_f32 v71, s[28:29], v84, v84, v105
	v_rcp_f32_e32 v82, v71
	s_nop 0
	v_fma_f32 v92, -v71, v82, 1.0
	v_fmac_f32_e32 v82, v92, v82
	v_div_scale_f32 v88, vcc, v105, v84, v105
	v_mul_f32_e32 v90, v88, v82
	v_fma_f32 v92, -v71, v90, v88
	v_fmac_f32_e32 v90, v92, v82
	v_fma_f32 v71, -v71, v90, v88
	v_div_fmas_f32 v71, v71, v82, v90
	v_div_fixup_f32 v105, v71, v84, v105
	v_mul_f32_e32 v70, v70, v105
	v_cvt_pk_bf16_f32 v70, v70, s0
	global_store_short v26, v70, s[96:97]
	v_lshlrev_b32_e32 v103, 16, v103
	v_lshlrev_b32_e32 v104, 16, v104
	v_lshlrev_b32_e32 v102, 16, v102
	v_mul_f32_e32 v102, v16, v102
	v_fmac_f32_e32 v102, v14, v103
	v_fmac_f32_e32 v102, v17, v104
	v_add_f32_e32 v102, v12, v102
	v_fma_f32 v27, v53, v8, v19
	v_mul_f32_e32 v70, v27, v102
	v_lshlrev_b32_e32 v106, 16, v106
	v_mul_f32_e32 v84, 0xbfb8aa3b, v106
	v_exp_f32_e32 v84, v84
	s_nop 0
	v_add_f32_e32 v84, 1.0, v84
	v_div_scale_f32 v71, s[28:29], v84, v84, v106
	v_rcp_f32_e32 v82, v71
	s_nop 0
	v_fma_f32 v92, -v71, v82, 1.0
	v_fmac_f32_e32 v82, v92, v82
	v_div_scale_f32 v88, vcc, v106, v84, v106
	v_mul_f32_e32 v90, v88, v82
	v_fma_f32 v92, -v71, v90, v88
	v_fmac_f32_e32 v90, v92, v82
	v_fma_f32 v71, -v71, v90, v88
	v_div_fmas_f32 v71, v71, v82, v90
	v_div_fixup_f32 v106, v71, v84, v106
	v_mul_f32_e32 v70, v70, v106
	v_cvt_pk_bf16_f32 v70, v70, s0
	global_store_short v26, v70, s[18:19]
	v_add_u32_e32 v26, 0x80000, v26
	v_lshlrev_b32_e32 v108, 16, v108
	v_lshlrev_b32_e32 v32, 16, v32
	v_lshlrev_b32_e32 v107, 16, v107
	v_mul_f32_e32 v107, v16, v107
	v_fmac_f32_e32 v107, v14, v108
	v_fmac_f32_e32 v107, v17, v32
	v_add_f32_e32 v107, v12, v107
	v_fma_f32 v27, v50, v8, v20
	v_mul_f32_e32 v70, v27, v107
	v_lshlrev_b32_e32 v33, 16, v33
	v_mul_f32_e32 v84, 0xbfb8aa3b, v33
	v_exp_f32_e32 v84, v84
	s_nop 0
	v_add_f32_e32 v84, 1.0, v84
	v_div_scale_f32 v71, s[28:29], v84, v84, v33
	v_rcp_f32_e32 v82, v71
	s_nop 0
	v_fma_f32 v92, -v71, v82, 1.0
	v_fmac_f32_e32 v82, v92, v82
	v_div_scale_f32 v88, vcc, v33, v84, v33
	v_mul_f32_e32 v90, v88, v82
	v_fma_f32 v92, -v71, v90, v88
	v_fmac_f32_e32 v90, v92, v82
	v_fma_f32 v71, -v71, v90, v88
	v_div_fmas_f32 v71, v71, v82, v90
	v_div_fixup_f32 v33, v71, v84, v33
	v_mul_f32_e32 v70, v70, v33
	v_cvt_pk_bf16_f32 v70, v70, s0
	global_store_short v26, v70, s[96:97]
	v_lshlrev_b32_e32 v34, 16, v34
	v_lshlrev_b32_e32 v79, 16, v79
	v_lshlrev_b32_e32 v78, 16, v78
	v_mul_f32_e32 v78, v16, v78
	v_fmac_f32_e32 v78, v14, v34
	v_fmac_f32_e32 v78, v17, v79
	v_add_f32_e32 v78, v12, v78
	v_fma_f32 v27, v52, v8, v21
	v_mul_f32_e32 v70, v27, v78
	v_lshlrev_b32_e32 v76, 16, v76
	v_mul_f32_e32 v84, 0xbfb8aa3b, v76
	v_exp_f32_e32 v84, v84
	s_nop 0
	v_add_f32_e32 v84, 1.0, v84
	v_div_scale_f32 v71, s[28:29], v84, v84, v76
	v_rcp_f32_e32 v82, v71
	s_nop 0
	v_fma_f32 v92, -v71, v82, 1.0
	v_fmac_f32_e32 v82, v92, v82
	v_div_scale_f32 v88, vcc, v76, v84, v76
	v_mul_f32_e32 v90, v88, v82
	v_fma_f32 v92, -v71, v90, v88
	v_fmac_f32_e32 v90, v92, v82
	v_fma_f32 v71, -v71, v90, v88
	v_div_fmas_f32 v71, v71, v82, v90
	v_div_fixup_f32 v76, v71, v84, v76
	v_mul_f32_e32 v70, v70, v76
	v_cvt_pk_bf16_f32 v70, v70, s0
	global_store_short v26, v70, s[18:19]
	v_add_u32_e32 v52, 0x1e00, v10
	v_cmp_gt_i32_e32 vcc, 0x1fff, v52
	v_min_i32_e32 v52, 0x1ffe, v52
	v_lshlrev_b32_e32 v52, 1, v52
	s_nop 0
	v_cndmask_b32_e64 v21, 0, 1.0, vcc
	v_add_u32_e32 v109, 0x1000, v109
	global_load_ushort v9, v109, s[36:37] offset:-2
	global_load_ushort v11, v109, s[36:37]
	global_load_ushort v13, v109, s[36:37] offset:2
	global_load_ushort v15, v109, s[88:89] offset:-2
	global_load_ushort v81, v109, s[88:89]
	global_load_ushort v83, v109, s[88:89] offset:2
	global_load_ushort v85, v109, s[0:1]
	global_load_ushort v87, v109, s[4:5]
	global_load_ushort v89, v109, s[36:37] offset:1022
	global_load_ushort v91, v109, s[36:37] offset:1024
	global_load_ushort v93, v109, s[36:37] offset:1026
	global_load_ushort v94, v109, s[88:89] offset:1022
	global_load_ushort v95, v109, s[88:89] offset:1024
	global_load_ushort v96, v109, s[88:89] offset:1026
	global_load_ushort v97, v109, s[0:1] offset:1024
	global_load_ushort v98, v109, s[4:5] offset:1024
	global_load_ushort v99, v109, s[36:37] offset:2046
	global_load_ushort v100, v109, s[36:37] offset:2048
	global_load_ushort v101, v109, s[36:37] offset:2050
	global_load_ushort v102, v109, s[88:89] offset:2046
	global_load_ushort v103, v109, s[88:89] offset:2048
	global_load_ushort v104, v109, s[88:89] offset:2050
	global_load_ushort v105, v109, s[0:1] offset:2048
	global_load_ushort v106, v109, s[4:5] offset:2048
	global_load_ushort v107, v109, s[36:37] offset:3070
	global_load_ushort v108, v109, s[36:37] offset:3072
	global_load_ushort v32, v52, s[36:37] offset:2
	global_load_ushort v78, v109, s[88:89] offset:3070
	global_load_ushort v34, v109, s[88:89] offset:3072
	global_load_ushort v79, v52, s[88:89] offset:2
	global_load_ushort v33, v109, s[0:1] offset:3072
	global_load_ushort v76, v109, s[4:5] offset:3072
	s_waitcnt vmcnt(0)
	v_add_u32_e32 v26, 0x80000, v26
	v_lshlrev_b32_e32 v11, 16, v11
	v_lshlrev_b32_e32 v13, 16, v13
	v_lshlrev_b32_e32 v9, 16, v9
	v_mul_f32_e32 v9, v16, v9
	v_fmac_f32_e32 v9, v14, v11
	v_fmac_f32_e32 v9, v17, v13
	v_add_f32_e32 v9, v12, v9
	v_fma_f32 v27, v55, v8, v4
	v_mul_f32_e32 v70, v27, v9
	v_lshlrev_b32_e32 v85, 16, v85
	v_mul_f32_e32 v84, 0xbfb8aa3b, v85
	v_exp_f32_e32 v84, v84
	s_nop 0
	v_add_f32_e32 v84, 1.0, v84
	v_div_scale_f32 v71, s[28:29], v84, v84, v85
	v_rcp_f32_e32 v82, v71
	s_nop 0
	v_fma_f32 v92, -v71, v82, 1.0
	v_fmac_f32_e32 v82, v92, v82
	v_div_scale_f32 v88, vcc, v85, v84, v85
	v_mul_f32_e32 v90, v88, v82
	v_fma_f32 v92, -v71, v90, v88
	v_fmac_f32_e32 v90, v92, v82
	v_fma_f32 v71, -v71, v90, v88
	v_div_fmas_f32 v71, v71, v82, v90
	v_div_fixup_f32 v85, v71, v84, v85
	v_mul_f32_e32 v70, v70, v85
	v_cvt_pk_bf16_f32 v70, v70, s0
	global_store_short v26, v70, s[96:97]
	v_lshlrev_b32_e32 v81, 16, v81
	v_lshlrev_b32_e32 v83, 16, v83
	v_lshlrev_b32_e32 v15, 16, v15
	v_mul_f32_e32 v15, v16, v15
	v_fmac_f32_e32 v15, v14, v81
	v_fmac_f32_e32 v15, v17, v83
	v_add_f32_e32 v15, v12, v15
	v_fma_f32 v27, v57, v8, v5
	v_mul_f32_e32 v70, v27, v15
	v_lshlrev_b32_e32 v87, 16, v87
	v_mul_f32_e32 v84, 0xbfb8aa3b, v87
	v_exp_f32_e32 v84, v84
	s_nop 0
	v_add_f32_e32 v84, 1.0, v84
	v_div_scale_f32 v71, s[28:29], v84, v84, v87
	v_rcp_f32_e32 v82, v71
	s_nop 0
	v_fma_f32 v92, -v71, v82, 1.0
	v_fmac_f32_e32 v82, v92, v82
	v_div_scale_f32 v88, vcc, v87, v84, v87
	v_mul_f32_e32 v90, v88, v82
	v_fma_f32 v92, -v71, v90, v88
	v_fmac_f32_e32 v90, v92, v82
	v_fma_f32 v71, -v71, v90, v88
	v_div_fmas_f32 v71, v71, v82, v90
	v_div_fixup_f32 v87, v71, v84, v87
	v_mul_f32_e32 v70, v70, v87
	v_cvt_pk_bf16_f32 v70, v70, s0
	global_store_short v26, v70, s[18:19]
	v_add_u32_e32 v26, 0x80000, v26
	v_lshlrev_b32_e32 v91, 16, v91
	v_lshlrev_b32_e32 v93, 16, v93
	v_lshlrev_b32_e32 v89, 16, v89
	v_mul_f32_e32 v89, v16, v89
	v_fmac_f32_e32 v89, v14, v91
	v_fmac_f32_e32 v89, v17, v93
	v_add_f32_e32 v89, v12, v89
	v_fma_f32 v27, v54, v8, v6
	v_mul_f32_e32 v70, v27, v89
	v_lshlrev_b32_e32 v97, 16, v97
	v_mul_f32_e32 v84, 0xbfb8aa3b, v97
	v_exp_f32_e32 v84, v84
	s_nop 0
	v_add_f32_e32 v84, 1.0, v84
	v_div_scale_f32 v71, s[28:29], v84, v84, v97
	v_rcp_f32_e32 v82, v71
	s_nop 0
	v_fma_f32 v92, -v71, v82, 1.0
	v_fmac_f32_e32 v82, v92, v82
	v_div_scale_f32 v88, vcc, v97, v84, v97
	v_mul_f32_e32 v90, v88, v82
	v_fma_f32 v92, -v71, v90, v88
	v_fmac_f32_e32 v90, v92, v82
	v_fma_f32 v71, -v71, v90, v88
	v_div_fmas_f32 v71, v71, v82, v90
	v_div_fixup_f32 v97, v71, v84, v97
	v_mul_f32_e32 v70, v70, v97
	v_cvt_pk_bf16_f32 v70, v70, s0
	global_store_short v26, v70, s[96:97]
	v_lshlrev_b32_e32 v95, 16, v95
	v_lshlrev_b32_e32 v96, 16, v96
	v_lshlrev_b32_e32 v94, 16, v94
	v_mul_f32_e32 v94, v16, v94
	v_fmac_f32_e32 v94, v14, v95
	v_fmac_f32_e32 v94, v17, v96
	v_add_f32_e32 v94, v12, v94
	v_fma_f32 v27, v56, v8, v7
	v_mul_f32_e32 v70, v27, v94
	v_lshlrev_b32_e32 v98, 16, v98
	v_mul_f32_e32 v84, 0xbfb8aa3b, v98
	v_exp_f32_e32 v84, v84
	s_nop 0
	v_add_f32_e32 v84, 1.0, v84
	v_div_scale_f32 v71, s[28:29], v84, v84, v98
	v_rcp_f32_e32 v82, v71
	s_nop 0
	v_fma_f32 v92, -v71, v82, 1.0
	v_fmac_f32_e32 v82, v92, v82
	v_div_scale_f32 v88, vcc, v98, v84, v98
	v_mul_f32_e32 v90, v88, v82
	v_fma_f32 v92, -v71, v90, v88
	v_fmac_f32_e32 v90, v92, v82
	v_fma_f32 v71, -v71, v90, v88
	v_div_fmas_f32 v71, v71, v82, v90
	v_div_fixup_f32 v98, v71, v84, v98
	v_mul_f32_e32 v70, v70, v98
	v_cvt_pk_bf16_f32 v70, v70, s0
	global_store_short v26, v70, s[18:19]
	v_add_u32_e32 v26, 0x80000, v26
	v_lshlrev_b32_e32 v100, 16, v100
	v_lshlrev_b32_e32 v101, 16, v101
	v_lshlrev_b32_e32 v99, 16, v99
	v_mul_f32_e32 v99, v16, v99
	v_fmac_f32_e32 v99, v14, v100
	v_fmac_f32_e32 v99, v17, v101
	v_add_f32_e32 v99, v12, v99
	v_fma_f32 v27, v59, v8, v0
	v_mul_f32_e32 v70, v27, v99
	v_lshlrev_b32_e32 v105, 16, v105
	v_mul_f32_e32 v84, 0xbfb8aa3b, v105
	v_exp_f32_e32 v84, v84
	s_nop 0
	v_add_f32_e32 v84, 1.0, v84
	v_div_scale_f32 v71, s[28:29], v84, v84, v105
	v_rcp_f32_e32 v82, v71
	s_nop 0
	v_fma_f32 v92, -v71, v82, 1.0
	v_fmac_f32_e32 v82, v92, v82
	v_div_scale_f32 v88, vcc, v105, v84, v105
	v_mul_f32_e32 v90, v88, v82
	v_fma_f32 v92, -v71, v90, v88
	v_fmac_f32_e32 v90, v92, v82
	v_fma_f32 v71, -v71, v90, v88
	v_div_fmas_f32 v71, v71, v82, v90
	v_div_fixup_f32 v105, v71, v84, v105
	v_mul_f32_e32 v70, v70, v105
	v_cvt_pk_bf16_f32 v70, v70, s0
	global_store_short v26, v70, s[96:97]
	v_lshlrev_b32_e32 v103, 16, v103
	v_lshlrev_b32_e32 v104, 16, v104
	v_lshlrev_b32_e32 v102, 16, v102
	v_mul_f32_e32 v102, v16, v102
	v_fmac_f32_e32 v102, v14, v103
	v_fmac_f32_e32 v102, v17, v104
	v_add_f32_e32 v102, v12, v102
	v_fma_f32 v27, v61, v8, v1
	v_mul_f32_e32 v70, v27, v102
	v_lshlrev_b32_e32 v106, 16, v106
	v_mul_f32_e32 v84, 0xbfb8aa3b, v106
	v_exp_f32_e32 v84, v84
	s_nop 0
	v_add_f32_e32 v84, 1.0, v84
	v_div_scale_f32 v71, s[28:29], v84, v84, v106
	v_rcp_f32_e32 v82, v71
	s_nop 0
	v_fma_f32 v92, -v71, v82, 1.0
	v_fmac_f32_e32 v82, v92, v82
	v_div_scale_f32 v88, vcc, v106, v84, v106
	v_mul_f32_e32 v90, v88, v82
	v_fma_f32 v92, -v71, v90, v88
	v_fmac_f32_e32 v90, v92, v82
	v_fma_f32 v71, -v71, v90, v88
	v_div_fmas_f32 v71, v71, v82, v90
	v_div_fixup_f32 v106, v71, v84, v106
	v_mul_f32_e32 v70, v70, v106
	v_cvt_pk_bf16_f32 v70, v70, s0
	global_store_short v26, v70, s[18:19]
	v_add_u32_e32 v26, 0x80000, v26
	v_lshlrev_b32_e32 v108, 16, v108
	v_lshlrev_b32_e32 v32, 16, v32
	v_lshlrev_b32_e32 v107, 16, v107
	v_mul_f32_e32 v107, v16, v107
	v_mul_f32_e32 v32, v21, v32
	v_fmac_f32_e32 v107, v14, v108
	v_fmac_f32_e32 v107, v17, v32
	v_add_f32_e32 v107, v12, v107
	v_fma_f32 v27, v58, v8, v2
	v_mul_f32_e32 v70, v27, v107
	v_lshlrev_b32_e32 v33, 16, v33
	v_mul_f32_e32 v84, 0xbfb8aa3b, v33
	v_exp_f32_e32 v84, v84
	s_nop 0
	v_add_f32_e32 v84, 1.0, v84
	v_div_scale_f32 v71, s[28:29], v84, v84, v33
	v_rcp_f32_e32 v82, v71
	s_nop 0
	v_fma_f32 v92, -v71, v82, 1.0
	v_fmac_f32_e32 v82, v92, v82
	v_div_scale_f32 v88, vcc, v33, v84, v33
	v_mul_f32_e32 v90, v88, v82
	v_fma_f32 v92, -v71, v90, v88
	v_fmac_f32_e32 v90, v92, v82
	v_fma_f32 v71, -v71, v90, v88
	v_div_fmas_f32 v71, v71, v82, v90
	v_div_fixup_f32 v33, v71, v84, v33
	v_mul_f32_e32 v70, v70, v33
	v_cvt_pk_bf16_f32 v70, v70, s0
	global_store_short v26, v70, s[96:97]
	v_lshlrev_b32_e32 v34, 16, v34
	v_lshlrev_b32_e32 v79, 16, v79
	v_lshlrev_b32_e32 v78, 16, v78
	v_mul_f32_e32 v78, v16, v78
	v_mul_f32_e32 v79, v21, v79
	v_fmac_f32_e32 v78, v14, v34
	v_fmac_f32_e32 v78, v17, v79
	v_add_f32_e32 v78, v12, v78
	v_fma_f32 v27, v60, v8, v3
	v_mul_f32_e32 v70, v27, v78
	v_lshlrev_b32_e32 v76, 16, v76
	v_mul_f32_e32 v84, 0xbfb8aa3b, v76
	v_exp_f32_e32 v84, v84
	s_nop 0
	v_add_f32_e32 v84, 1.0, v84
	v_div_scale_f32 v71, s[28:29], v84, v84, v76
	v_rcp_f32_e32 v82, v71
	s_nop 0
	v_fma_f32 v92, -v71, v82, 1.0
	v_fmac_f32_e32 v82, v92, v82
	v_div_scale_f32 v88, vcc, v76, v84, v76
	v_mul_f32_e32 v90, v88, v82
	v_fma_f32 v92, -v71, v90, v88
	v_fmac_f32_e32 v90, v92, v82
	v_fma_f32 v71, -v71, v90, v88
	v_div_fmas_f32 v71, v71, v82, v90
	v_div_fixup_f32 v76, v71, v84, v76
	v_mul_f32_e32 v70, v70, v76
	v_cvt_pk_bf16_f32 v70, v70, s0
	global_store_short v26, v70, s[18:19]
	s_mov_b64 s[28:29], 0

.LBB0_908:
	s_nop 1
	v_lshlrev_b32_e32 v0, 2, v146
	s_add_i32 s79, 16, 0x10000
	v_add_u32_e32 v64, 16, v0
	v_add_u32_e32 v65, s79, v0
	s_waitcnt lgkmcnt(0)
	s_barrier
	ds_read2st64_b32 v[2:3], v64 offset1:8
	ds_read2st64_b32 v[4:5], v65 offset1:8
	ds_read2st64_b32 v[8:9], v64 offset0:16 offset1:24
	ds_read2st64_b32 v[10:11], v65 offset0:16 offset1:24
	ds_read2st64_b32 v[12:13], v64 offset0:32 offset1:40
	ds_read2st64_b32 v[14:15], v65 offset0:32 offset1:40
	s_mov_b32 s47, s40
	s_waitcnt lgkmcnt(5)
	v_mov_b32_e32 v6, v2
	s_waitcnt lgkmcnt(4)
	v_mov_b32_e32 v7, v4
	v_mov_b32_e32 v4, v3
	s_waitcnt lgkmcnt(3)
	v_mov_b32_e32 v2, v8
	s_waitcnt lgkmcnt(2)
	v_mov_b32_e32 v3, v10
	v_mov_b32_e32 v10, v9
	ds_read2st64_b32 v[8:9], v64 offset0:48 offset1:56
	ds_read2st64_b32 v[16:17], v65 offset0:48 offset1:56
	s_waitcnt lgkmcnt(3)
	v_mov_b32_e32 v18, v12
	s_waitcnt lgkmcnt(2)
	v_mov_b32_e32 v19, v14
	v_mov_b32_e32 v14, v13
	s_waitcnt lgkmcnt(1)
	v_mov_b32_e32 v12, v8
	s_waitcnt lgkmcnt(0)
	v_mov_b32_e32 v13, v16
	ds_read2st64_b32 v[20:21], v64 offset0:64 offset1:72
	ds_read2st64_b32 v[22:23], v65 offset0:64 offset1:72
	v_mov_b32_e32 v16, v9
	ds_read2st64_b32 v[8:9], v64 offset0:80 offset1:88
	ds_read2st64_b32 v[24:25], v65 offset0:80 offset1:88
	s_mov_b32 s41, s43
	s_waitcnt lgkmcnt(3)
	v_mov_b32_e32 v26, v20
	s_waitcnt lgkmcnt(2)
	v_mov_b32_e32 v27, v22
	v_mov_b32_e32 v22, v21
	s_waitcnt lgkmcnt(1)
	v_mov_b32_e32 v28, v8
	s_waitcnt lgkmcnt(0)
	v_mov_b32_e32 v29, v24
	ds_read2st64_b32 v[20:21], v64 offset0:96 offset1:104
	ds_read2st64_b32 v[30:31], v65 offset0:96 offset1:104
	v_mov_b32_e32 v24, v9
	ds_read2st64_b32 v[8:9], v64 offset0:112 offset1:120
	ds_read2st64_b32 v[32:33], v65 offset0:112 offset1:120
	v_and_b32_e32 v196, 63, v146
	v_lshlrev_b32_e32 v196, 2, v196
	v_and_b32_e32 v0, 0xffffffc0, v146
	v_lshl_add_u32 v0, v0, 5, v196
	v_add_u32_e32 v0, 0x400, v0
	s_waitcnt lgkmcnt(3)
	v_mov_b32_e32 v34, v20
	s_waitcnt lgkmcnt(2)
	v_mov_b32_e32 v35, v30
	v_mov_b32_e32 v30, v21
	s_waitcnt lgkmcnt(1)
	v_mov_b32_e32 v36, v8
	s_waitcnt lgkmcnt(0)
	v_mov_b32_e32 v37, v32
	ds_read2st64_b32 v[20:21], v64 offset0:128 offset1:136
	ds_read2st64_b32 v[38:39], v65 offset0:128 offset1:136
	v_mov_b32_e32 v32, v9
	ds_read2st64_b32 v[8:9], v64 offset0:144 offset1:152
	ds_read2st64_b32 v[40:41], v65 offset0:144 offset1:152
	v_readlane_b32 s0, v252, 48
	s_waitcnt lgkmcnt(3)
	v_mov_b32_e32 v42, v20
	s_waitcnt lgkmcnt(2)
	v_mov_b32_e32 v43, v38
	v_mov_b32_e32 v38, v21
	s_waitcnt lgkmcnt(1)
	v_mov_b32_e32 v44, v8
	s_waitcnt lgkmcnt(0)
	v_mov_b32_e32 v45, v40
	ds_read2st64_b32 v[20:21], v64 offset0:160 offset1:168
	ds_read2st64_b32 v[46:47], v65 offset0:160 offset1:168
	v_mov_b32_e32 v40, v9
	ds_read2st64_b32 v[8:9], v64 offset0:176 offset1:184
	ds_read2st64_b32 v[48:49], v65 offset0:176 offset1:184
	v_ashrrev_i32_e32 v1, 31, v0
	s_waitcnt lgkmcnt(3)
	v_mov_b32_e32 v50, v20
	s_waitcnt lgkmcnt(2)
	v_mov_b32_e32 v51, v46
	v_mov_b32_e32 v46, v21
	s_waitcnt lgkmcnt(1)
	v_mov_b32_e32 v52, v8
	s_waitcnt lgkmcnt(0)
	v_mov_b32_e32 v53, v48
	ds_read2st64_b32 v[20:21], v64 offset0:192 offset1:200
	ds_read2st64_b32 v[54:55], v65 offset0:192 offset1:200
	v_mov_b32_e32 v48, v9
	ds_read2st64_b32 v[8:9], v64 offset0:208 offset1:216
	ds_read2st64_b32 v[56:57], v65 offset0:208 offset1:216
	v_readlane_b32 s1, v252, 49
	s_waitcnt lgkmcnt(3)
	v_mov_b32_e32 v58, v20
	s_waitcnt lgkmcnt(2)
	v_mov_b32_e32 v59, v54
	v_mov_b32_e32 v54, v21
	s_waitcnt lgkmcnt(1)
	v_mov_b32_e32 v60, v8
	s_waitcnt lgkmcnt(0)
	v_mov_b32_e32 v61, v56
	ds_read2st64_b32 v[20:21], v64 offset0:224 offset1:232
	ds_read2st64_b32 v[62:63], v65 offset0:224 offset1:232
	v_mov_b32_e32 v56, v9
	ds_read2st64_b32 v[8:9], v64 offset0:240 offset1:248
	ds_read2st64_b32 v[64:65], v65 offset0:240 offset1:248
	s_waitcnt lgkmcnt(0)
	v_mov_b32_e32 v66, v20
	v_mov_b32_e32 v67, v62
	v_mov_b32_e32 v72, v8
	v_mov_b32_e32 v73, v64
	v_mov_b32_e32 v64, v9
	v_pk_add_f32 v[8:9], v[6:7], v[42:43]
	v_pk_add_f32 v[6:7], v[6:7], v[42:43] neg_lo:[0,1] neg_hi:[0,1]
	v_pk_add_f32 v[42:43], v[4:5], v[38:39]
	v_pk_add_f32 v[4:5], v[4:5], v[38:39] neg_lo:[0,1] neg_hi:[0,1]
	v_mov_b32_e32 v62, v21
	v_pk_mul_f32 v[38:39], v[4:5], s[48:49] op_sel:[1,0] op_sel_hi:[0,0] neg_hi:[1,0]
	v_mov_b32_e32 v21, v146
	v_pk_fma_f32 v[4:5], v[4:5], s[44:45], v[38:39] op_sel_hi:[1,0,1]
	v_pk_add_f32 v[38:39], v[2:3], v[44:45]
	v_pk_add_f32 v[2:3], v[2:3], v[44:45] neg_lo:[0,1] neg_hi:[0,1]
	s_barrier
	s_nop 0
	s_nop 0
	v_pk_mul_f32 v[44:45], v[2:3], s[54:55] op_sel:[1,0] op_sel_hi:[0,0] neg_hi:[1,0]
	s_nop 0
	v_pk_fma_f32 v[2:3], v[2:3], s[52:53], v[44:45] op_sel_hi:[1,0,1]
	v_pk_add_f32 v[44:45], v[10:11], v[40:41]
	v_pk_add_f32 v[10:11], v[10:11], v[40:41] neg_lo:[0,1] neg_hi:[0,1]
	s_lshl_b64 s[10:11], s[62:63], 2
	s_nop 0
	s_nop 0
	v_pk_mul_f32 v[40:41], v[10:11], s[58:59] op_sel:[1,0] op_sel_hi:[0,0] neg_hi:[1,0]
	v_add_u32_e32 v70, 0x200, v146
	v_pk_fma_f32 v[10:11], v[10:11], s[56:57], v[40:41] op_sel_hi:[1,0,1]
	v_pk_add_f32 v[40:41], v[18:19], v[50:51]
	v_pk_add_f32 v[18:19], v[18:19], v[50:51] neg_lo:[0,1] neg_hi:[0,1]
	v_ashrrev_i32_e32 v147, 31, v146
	s_nop 0
	s_nop 0
	v_pk_mul_f32 v[50:51], v[18:19], s[60:61] op_sel:[1,0] op_sel_hi:[0,0] neg_hi:[1,0]
	v_add_u32_e32 v69, 0x400, v146
	v_pk_fma_f32 v[18:19], v[18:19], s[60:61], v[50:51] op_sel_hi:[1,0,1]
	v_pk_add_f32 v[50:51], v[14:15], v[46:47]
	v_pk_add_f32 v[14:15], v[14:15], v[46:47] neg_lo:[0,1] neg_hi:[0,1]
	v_add_u32_e32 v68, 0x600, v146
	v_pk_mul_f32 v[46:47], v[14:15], s[56:57] op_sel:[1,0] op_sel_hi:[0,0] neg_hi:[1,0]
	s_mov_b32 s16, 0
	v_pk_fma_f32 v[14:15], v[14:15], s[58:59], v[46:47] op_sel_hi:[1,0,1]
	v_pk_add_f32 v[46:47], v[12:13], v[52:53]
	v_pk_add_f32 v[12:13], v[12:13], v[52:53] neg_lo:[0,1] neg_hi:[0,1]
	s_nop 0
	v_pk_mul_f32 v[52:53], v[12:13], s[52:53] op_sel:[1,0] op_sel_hi:[0,0] neg_hi:[1,0]
	s_nop 0
	v_pk_fma_f32 v[12:13], v[12:13], s[54:55], v[52:53] op_sel_hi:[1,0,1]
	v_pk_add_f32 v[52:53], v[16:17], v[48:49]
	v_pk_add_f32 v[16:17], v[16:17], v[48:49] neg_lo:[0,1] neg_hi:[0,1]
	s_nop 0
	v_pk_mul_f32 v[48:49], v[16:17], s[44:45] op_sel:[1,0] op_sel_hi:[0,0] neg_hi:[1,0]
	s_nop 0
	v_pk_fma_f32 v[16:17], v[16:17], s[48:49], v[48:49] op_sel_hi:[1,0,1]
	v_pk_add_f32 v[48:49], v[26:27], v[58:59]
	v_pk_add_f32 v[26:27], v[26:27], v[58:59] neg_lo:[0,1] neg_hi:[0,1]
	s_nop 0
	v_xor_b32_e32 v59, 0x80000000, v26
	v_mov_b32_e32 v58, v27
	v_pk_add_f32 v[26:27], v[22:23], v[54:55]
	v_pk_add_f32 v[22:23], v[22:23], v[54:55] neg_lo:[0,1] neg_hi:[0,1]
	s_nop 0
	v_pk_mul_f32 v[54:55], v[22:23], s[48:49] op_sel_hi:[1,0]
	v_xor_b32_e32 v75, 0x80000000, v22
	v_mov_b32_e32 v74, v23
	v_pk_fma_f32 v[22:23], v[74:75], s[44:45], v[54:55] op_sel_hi:[1,0,1] neg_lo:[0,0,1] neg_hi:[0,0,1]
	v_pk_add_f32 v[54:55], v[28:29], v[60:61]
	v_pk_add_f32 v[28:29], v[28:29], v[60:61] neg_lo:[0,1] neg_hi:[0,1]
	s_nop 0
	v_pk_mul_f32 v[60:61], v[28:29], s[54:55] op_sel_hi:[1,0]
	v_xor_b32_e32 v75, 0x80000000, v28
	v_mov_b32_e32 v74, v29
	v_pk_fma_f32 v[28:29], v[74:75], s[52:53], v[60:61] op_sel_hi:[1,0,1] neg_lo:[0,0,1] neg_hi:[0,0,1]
	v_pk_add_f32 v[60:61], v[24:25], v[56:57]
	v_pk_add_f32 v[24:25], v[24:25], v[56:57] neg_lo:[0,1] neg_hi:[0,1]
	s_nop 0
	v_pk_mul_f32 v[56:57], v[24:25], s[58:59] op_sel_hi:[1,0]
	v_xor_b32_e32 v75, 0x80000000, v24
	v_mov_b32_e32 v74, v25
	v_pk_fma_f32 v[24:25], v[74:75], s[56:57], v[56:57] op_sel_hi:[1,0,1] neg_lo:[0,0,1] neg_hi:[0,0,1]
	v_pk_add_f32 v[56:57], v[34:35], v[66:67]
	v_pk_add_f32 v[34:35], v[34:35], v[66:67] neg_lo:[0,1] neg_hi:[0,1]
	s_nop 0
	v_pk_mul_f32 v[66:67], v[34:35], s[60:61] op_sel_hi:[1,0]
	v_xor_b32_e32 v75, 0x80000000, v34
	v_mov_b32_e32 v74, v35
	v_pk_fma_f32 v[34:35], v[74:75], s[60:61], v[66:67] op_sel_hi:[1,0,1] neg_lo:[0,0,1] neg_hi:[0,0,1]
	v_pk_add_f32 v[66:67], v[30:31], v[62:63]
	v_pk_add_f32 v[30:31], v[30:31], v[62:63] neg_lo:[0,1] neg_hi:[0,1]
	s_nop 0
	v_pk_mul_f32 v[62:63], v[30:31], s[56:57] op_sel_hi:[1,0]
	v_xor_b32_e32 v75, 0x80000000, v30
	v_mov_b32_e32 v74, v31
	v_pk_fma_f32 v[30:31], v[74:75], s[58:59], v[62:63] op_sel_hi:[1,0,1] neg_lo:[0,0,1] neg_hi:[0,0,1]
	v_pk_add_f32 v[62:63], v[36:37], v[72:73]
	v_pk_add_f32 v[36:37], v[36:37], v[72:73] neg_lo:[0,1] neg_hi:[0,1]
	s_nop 0
	v_pk_mul_f32 v[72:73], v[36:37], s[52:53] op_sel_hi:[1,0]
	v_xor_b32_e32 v75, 0x80000000, v36
	v_mov_b32_e32 v74, v37
	v_pk_fma_f32 v[36:37], v[74:75], s[54:55], v[72:73] op_sel_hi:[1,0,1] neg_lo:[0,0,1] neg_hi:[0,0,1]
	v_pk_add_f32 v[72:73], v[32:33], v[64:65]
	v_pk_add_f32 v[32:33], v[32:33], v[64:65] neg_lo:[0,1] neg_hi:[0,1]
	s_nop 0
	v_pk_mul_f32 v[64:65], v[32:33], s[44:45] op_sel_hi:[1,0]
	v_xor_b32_e32 v75, 0x80000000, v32
	v_mov_b32_e32 v74, v33
	v_pk_fma_f32 v[32:33], v[74:75], s[48:49], v[64:65] op_sel_hi:[1,0,1] neg_lo:[0,0,1] neg_hi:[0,0,1]
	v_pk_add_f32 v[64:65], v[8:9], v[48:49]
	v_pk_add_f32 v[8:9], v[8:9], v[48:49] neg_lo:[0,1] neg_hi:[0,1]
	v_pk_add_f32 v[48:49], v[42:43], v[26:27]
	v_pk_add_f32 v[26:27], v[42:43], v[26:27] neg_lo:[0,1] neg_hi:[0,1]
	s_nop 0
	v_pk_mul_f32 v[42:43], v[26:27], s[54:55] op_sel:[1,0] op_sel_hi:[0,0] neg_hi:[1,0]
	s_nop 0
	v_pk_fma_f32 v[26:27], v[26:27], s[52:53], v[42:43] op_sel_hi:[1,0,1]
	v_pk_add_f32 v[42:43], v[38:39], v[54:55]
	v_pk_add_f32 v[38:39], v[38:39], v[54:55] neg_lo:[0,1] neg_hi:[0,1]
	s_nop 0
	v_pk_mul_f32 v[54:55], v[38:39], s[60:61] op_sel:[1,0] op_sel_hi:[0,0] neg_hi:[1,0]
	s_nop 0
	v_pk_fma_f32 v[38:39], v[38:39], s[60:61], v[54:55] op_sel_hi:[1,0,1]
	v_pk_add_f32 v[54:55], v[44:45], v[60:61]
	v_pk_add_f32 v[44:45], v[44:45], v[60:61] neg_lo:[0,1] neg_hi:[0,1]
	s_nop 0
	v_pk_mul_f32 v[60:61], v[44:45], s[52:53] op_sel:[1,0] op_sel_hi:[0,0] neg_hi:[1,0]
	s_nop 0
	v_pk_fma_f32 v[44:45], v[44:45], s[54:55], v[60:61] op_sel_hi:[1,0,1]
	v_pk_add_f32 v[60:61], v[40:41], v[56:57]
	v_pk_add_f32 v[40:41], v[40:41], v[56:57] neg_lo:[0,1] neg_hi:[0,1]
	s_nop 0
	v_xor_b32_e32 v57, 0x80000000, v40
	v_mov_b32_e32 v56, v41
	v_pk_add_f32 v[40:41], v[50:51], v[66:67]
	v_pk_add_f32 v[50:51], v[50:51], v[66:67] neg_lo:[0,1] neg_hi:[0,1]
	s_nop 0
	v_pk_mul_f32 v[66:67], v[50:51], s[54:55] op_sel_hi:[1,0]
	v_xor_b32_e32 v75, 0x80000000, v50
	v_mov_b32_e32 v74, v51
	v_pk_fma_f32 v[50:51], v[74:75], s[52:53], v[66:67] op_sel_hi:[1,0,1] neg_lo:[0,0,1] neg_hi:[0,0,1]
	v_pk_add_f32 v[66:67], v[46:47], v[62:63]
	v_pk_add_f32 v[46:47], v[46:47], v[62:63] neg_lo:[0,1] neg_hi:[0,1]
	s_nop 0
	v_pk_mul_f32 v[62:63], v[46:47], s[60:61] op_sel_hi:[1,0]
	v_xor_b32_e32 v75, 0x80000000, v46
	v_mov_b32_e32 v74, v47
	v_pk_fma_f32 v[46:47], v[74:75], s[60:61], v[62:63] op_sel_hi:[1,0,1] neg_lo:[0,0,1] neg_hi:[0,0,1]
	v_pk_add_f32 v[62:63], v[52:53], v[72:73]
	v_pk_add_f32 v[52:53], v[52:53], v[72:73] neg_lo:[0,1] neg_hi:[0,1]
	s_nop 0
	v_pk_mul_f32 v[72:73], v[52:53], s[52:53] op_sel_hi:[1,0]
	v_xor_b32_e32 v75, 0x80000000, v52
	v_mov_b32_e32 v74, v53
	v_pk_fma_f32 v[52:53], v[74:75], s[54:55], v[72:73] op_sel_hi:[1,0,1] neg_lo:[0,0,1] neg_hi:[0,0,1]
	v_pk_add_f32 v[72:73], v[6:7], v[58:59]
	v_pk_add_f32 v[6:7], v[6:7], v[58:59] neg_lo:[0,1] neg_hi:[0,1]
	v_pk_add_f32 v[58:59], v[4:5], v[22:23]
	v_pk_add_f32 v[4:5], v[4:5], v[22:23] neg_lo:[0,1] neg_hi:[0,1]
	s_nop 0
	v_pk_mul_f32 v[22:23], v[4:5], s[54:55] op_sel:[1,0] op_sel_hi:[0,0] neg_hi:[1,0]
	s_nop 0
	v_pk_fma_f32 v[4:5], v[4:5], s[52:53], v[22:23] op_sel_hi:[1,0,1]
	v_pk_add_f32 v[22:23], v[2:3], v[28:29]
	v_pk_add_f32 v[2:3], v[2:3], v[28:29] neg_lo:[0,1] neg_hi:[0,1]
	s_nop 0
	v_pk_mul_f32 v[28:29], v[2:3], s[60:61] op_sel:[1,0] op_sel_hi:[0,0] neg_hi:[1,0]
	s_nop 0
	v_pk_fma_f32 v[2:3], v[2:3], s[60:61], v[28:29] op_sel_hi:[1,0,1]
	v_pk_add_f32 v[28:29], v[10:11], v[24:25]
	v_pk_add_f32 v[10:11], v[10:11], v[24:25] neg_lo:[0,1] neg_hi:[0,1]
	s_nop 0
	v_pk_mul_f32 v[24:25], v[10:11], s[52:53] op_sel:[1,0] op_sel_hi:[0,0] neg_hi:[1,0]
	s_nop 0
	v_pk_fma_f32 v[10:11], v[10:11], s[54:55], v[24:25] op_sel_hi:[1,0,1]
	v_pk_add_f32 v[24:25], v[18:19], v[34:35]
	v_pk_add_f32 v[18:19], v[18:19], v[34:35] neg_lo:[0,1] neg_hi:[0,1]
	s_nop 0
	v_xor_b32_e32 v35, 0x80000000, v18
	v_mov_b32_e32 v34, v19
	v_pk_add_f32 v[18:19], v[14:15], v[30:31]
	v_pk_add_f32 v[14:15], v[14:15], v[30:31] neg_lo:[0,1] neg_hi:[0,1]
	s_nop 0
	v_pk_mul_f32 v[30:31], v[14:15], s[54:55] op_sel_hi:[1,0]
	v_xor_b32_e32 v75, 0x80000000, v14
	v_mov_b32_e32 v74, v15
	v_pk_fma_f32 v[14:15], v[74:75], s[52:53], v[30:31] op_sel_hi:[1,0,1] neg_lo:[0,0,1] neg_hi:[0,0,1]
	v_pk_add_f32 v[30:31], v[12:13], v[36:37]
	v_pk_add_f32 v[12:13], v[12:13], v[36:37] neg_lo:[0,1] neg_hi:[0,1]
	s_nop 0
	v_pk_mul_f32 v[36:37], v[12:13], s[60:61] op_sel_hi:[1,0]
	v_xor_b32_e32 v75, 0x80000000, v12
	v_mov_b32_e32 v74, v13
	v_pk_fma_f32 v[12:13], v[74:75], s[60:61], v[36:37] op_sel_hi:[1,0,1] neg_lo:[0,0,1] neg_hi:[0,0,1]
	v_pk_add_f32 v[36:37], v[16:17], v[32:33]
	v_pk_add_f32 v[16:17], v[16:17], v[32:33] neg_lo:[0,1] neg_hi:[0,1]
	s_nop 0
	v_pk_mul_f32 v[32:33], v[16:17], s[52:53] op_sel_hi:[1,0]
	v_xor_b32_e32 v75, 0x80000000, v16
	v_mov_b32_e32 v74, v17
	v_pk_fma_f32 v[16:17], v[74:75], s[54:55], v[32:33] op_sel_hi:[1,0,1] neg_lo:[0,0,1] neg_hi:[0,0,1]
	v_pk_add_f32 v[32:33], v[64:65], v[60:61]
	v_pk_add_f32 v[60:61], v[64:65], v[60:61] neg_lo:[0,1] neg_hi:[0,1]
	v_pk_add_f32 v[64:65], v[48:49], v[40:41]
	v_pk_add_f32 v[40:41], v[48:49], v[40:41] neg_lo:[0,1] neg_hi:[0,1]
	s_nop 0
	v_pk_mul_f32 v[48:49], v[40:41], s[60:61] op_sel:[1,0] op_sel_hi:[0,0] neg_hi:[1,0]
	s_nop 0
	v_pk_fma_f32 v[40:41], v[40:41], s[60:61], v[48:49] op_sel_hi:[1,0,1]
	v_pk_add_f32 v[48:49], v[42:43], v[66:67]
	v_pk_add_f32 v[42:43], v[42:43], v[66:67] neg_lo:[0,1] neg_hi:[0,1]
	s_nop 0
	v_xor_b32_e32 v67, 0x80000000, v42
	v_mov_b32_e32 v66, v43
	v_pk_add_f32 v[42:43], v[54:55], v[62:63]
	v_pk_add_f32 v[54:55], v[54:55], v[62:63] neg_lo:[0,1] neg_hi:[0,1]
	s_nop 0
	v_pk_mul_f32 v[62:63], v[54:55], s[60:61] op_sel_hi:[1,0]
	v_xor_b32_e32 v75, 0x80000000, v54
	v_mov_b32_e32 v74, v55
	v_pk_fma_f32 v[54:55], v[74:75], s[60:61], v[62:63] op_sel_hi:[1,0,1] neg_lo:[0,0,1] neg_hi:[0,0,1]
	v_pk_add_f32 v[62:63], v[8:9], v[56:57]
	v_pk_add_f32 v[8:9], v[8:9], v[56:57] neg_lo:[0,1] neg_hi:[0,1]
	v_pk_add_f32 v[56:57], v[26:27], v[50:51]
	v_pk_add_f32 v[26:27], v[26:27], v[50:51] neg_lo:[0,1] neg_hi:[0,1]
	s_nop 0
	v_pk_mul_f32 v[50:51], v[26:27], s[60:61] op_sel:[1,0] op_sel_hi:[0,0] neg_hi:[1,0]
	s_nop 0
	v_pk_fma_f32 v[26:27], v[26:27], s[60:61], v[50:51] op_sel_hi:[1,0,1]
	v_pk_add_f32 v[50:51], v[38:39], v[46:47]
	v_pk_add_f32 v[38:39], v[38:39], v[46:47] neg_lo:[0,1] neg_hi:[0,1]
	s_nop 0
	v_xor_b32_e32 v47, 0x80000000, v38
	v_mov_b32_e32 v46, v39
	v_pk_add_f32 v[38:39], v[44:45], v[52:53]
	v_pk_add_f32 v[44:45], v[44:45], v[52:53] neg_lo:[0,1] neg_hi:[0,1]
	s_nop 0
	v_pk_mul_f32 v[52:53], v[44:45], s[60:61] op_sel_hi:[1,0]
	v_xor_b32_e32 v75, 0x80000000, v44
	v_mov_b32_e32 v74, v45
	v_pk_fma_f32 v[44:45], v[74:75], s[60:61], v[52:53] op_sel_hi:[1,0,1] neg_lo:[0,0,1] neg_hi:[0,0,1]
	v_pk_add_f32 v[52:53], v[72:73], v[24:25]
	v_pk_add_f32 v[24:25], v[72:73], v[24:25] neg_lo:[0,1] neg_hi:[0,1]
	v_pk_add_f32 v[72:73], v[58:59], v[18:19]
	v_pk_add_f32 v[18:19], v[58:59], v[18:19] neg_lo:[0,1] neg_hi:[0,1]
	s_nop 0
	v_pk_mul_f32 v[58:59], v[18:19], s[60:61] op_sel:[1,0] op_sel_hi:[0,0] neg_hi:[1,0]
	s_nop 0
	v_pk_fma_f32 v[18:19], v[18:19], s[60:61], v[58:59] op_sel_hi:[1,0,1]
	v_pk_add_f32 v[58:59], v[22:23], v[30:31]
	v_pk_add_f32 v[22:23], v[22:23], v[30:31] neg_lo:[0,1] neg_hi:[0,1]
	s_nop 0
	v_xor_b32_e32 v31, 0x80000000, v22
	v_mov_b32_e32 v30, v23
	v_pk_add_f32 v[22:23], v[28:29], v[36:37]
	v_pk_add_f32 v[28:29], v[28:29], v[36:37] neg_lo:[0,1] neg_hi:[0,1]
	v_pk_add_f32 v[76:77], v[24:25], v[30:31]
	v_pk_mul_f32 v[36:37], v[28:29], s[60:61] op_sel_hi:[1,0]
	v_xor_b32_e32 v75, 0x80000000, v28
	v_mov_b32_e32 v74, v29
	v_pk_fma_f32 v[28:29], v[74:75], s[60:61], v[36:37] op_sel_hi:[1,0,1] neg_lo:[0,0,1] neg_hi:[0,0,1]
	v_pk_add_f32 v[36:37], v[6:7], v[34:35]
	v_pk_add_f32 v[6:7], v[6:7], v[34:35] neg_lo:[0,1] neg_hi:[0,1]
	v_pk_add_f32 v[34:35], v[4:5], v[14:15]
	v_pk_add_f32 v[4:5], v[4:5], v[14:15] neg_lo:[0,1] neg_hi:[0,1]
	v_pk_add_f32 v[78:79], v[18:19], v[28:29]
	v_pk_mul_f32 v[14:15], v[4:5], s[60:61] op_sel:[1,0] op_sel_hi:[0,0] neg_hi:[1,0]
	v_pk_add_f32 v[18:19], v[18:19], v[28:29] neg_lo:[0,1] neg_hi:[0,1]
	v_pk_fma_f32 v[4:5], v[4:5], s[60:61], v[14:15] op_sel_hi:[1,0,1]
	v_pk_add_f32 v[14:15], v[2:3], v[12:13]
	v_pk_add_f32 v[2:3], v[2:3], v[12:13] neg_lo:[0,1] neg_hi:[0,1]
	v_xor_b32_e32 v81, 0x80000000, v18
	v_xor_b32_e32 v13, 0x80000000, v2
	v_mov_b32_e32 v12, v3
	v_pk_add_f32 v[2:3], v[10:11], v[16:17]
	v_pk_add_f32 v[10:11], v[10:11], v[16:17] neg_lo:[0,1] neg_hi:[0,1]
	v_mov_b32_e32 v80, v19
	v_pk_mul_f32 v[16:17], v[10:11], s[60:61] op_sel_hi:[1,0]
	s_nop 0
	v_pk_fma_f32 v[10:11], v[10:11], s[60:61], v[16:17] op_sel:[1,0,0] op_sel_hi:[0,0,1] neg_lo:[0,0,1] neg_hi:[1,0,1]
	v_pk_add_f32 v[74:75], v[62:63], v[50:51]
	v_pk_add_f32 v[50:51], v[62:63], v[50:51] neg_lo:[0,1] neg_hi:[0,1]
	v_pk_add_f32 v[62:63], v[56:57], v[38:39]
	v_pk_add_f32 v[38:39], v[56:57], v[38:39] neg_lo:[0,1] neg_hi:[0,1]
	v_pk_add_f32 v[16:17], v[32:33], v[48:49]
	v_pk_add_f32 v[32:33], v[32:33], v[48:49] neg_lo:[0,1] neg_hi:[0,1]
	v_pk_add_f32 v[48:49], v[64:65], v[42:43]
	v_pk_add_f32 v[42:43], v[64:65], v[42:43] neg_lo:[0,1] neg_hi:[0,1]
	v_xor_b32_e32 v57, 0x80000000, v38
	v_mov_b32_e32 v56, v39
	v_pk_add_f32 v[38:39], v[8:9], v[46:47]
	v_pk_add_f32 v[8:9], v[8:9], v[46:47] neg_lo:[0,1] neg_hi:[0,1]
	v_pk_add_f32 v[46:47], v[26:27], v[44:45]
	v_pk_add_f32 v[26:27], v[26:27], v[44:45] neg_lo:[0,1] neg_hi:[0,1]
	v_xor_b32_e32 v65, 0x80000000, v42
	v_mov_b32_e32 v64, v43
	v_pk_add_f32 v[42:43], v[60:61], v[66:67]
	v_pk_add_f32 v[60:61], v[60:61], v[66:67] neg_lo:[0,1] neg_hi:[0,1]
	v_pk_add_f32 v[66:67], v[40:41], v[54:55]
	v_pk_add_f32 v[40:41], v[40:41], v[54:55] neg_lo:[0,1] neg_hi:[0,1]
	v_xor_b32_e32 v45, 0x80000000, v26
	v_mov_b32_e32 v44, v27
	v_pk_add_f32 v[26:27], v[52:53], v[58:59]
	v_pk_add_f32 v[52:53], v[52:53], v[58:59] neg_lo:[0,1] neg_hi:[0,1]
	v_pk_add_f32 v[58:59], v[72:73], v[22:23]
	v_pk_add_f32 v[22:23], v[72:73], v[22:23] neg_lo:[0,1] neg_hi:[0,1]
	v_pk_add_f32 v[18:19], v[36:37], v[14:15]
	v_pk_add_f32 v[14:15], v[36:37], v[14:15] neg_lo:[0,1] neg_hi:[0,1]
	v_pk_add_f32 v[36:37], v[34:35], v[2:3]
	v_pk_add_f32 v[2:3], v[34:35], v[2:3] neg_lo:[0,1] neg_hi:[0,1]
	v_xor_b32_e32 v73, 0x80000000, v22
	v_mov_b32_e32 v72, v23
	v_xor_b32_e32 v35, 0x80000000, v2
	v_mov_b32_e32 v34, v3
	v_pk_add_f32 v[2:3], v[4:5], v[10:11] neg_lo:[0,1] neg_hi:[0,1]
	v_pk_add_f32 v[24:25], v[24:25], v[30:31] neg_lo:[0,1] neg_hi:[0,1]
	v_pk_add_f32 v[82:83], v[6:7], v[12:13]
	v_pk_add_f32 v[12:13], v[6:7], v[12:13] neg_lo:[0,1] neg_hi:[0,1]
	v_xor_b32_e32 v87, 0x80000000, v2
	v_mov_b32_e32 v86, v3
	v_pk_add_f32 v[2:3], v[16:17], v[48:49]
	v_pk_add_f32 v[88:89], v[16:17], v[48:49] neg_lo:[0,1] neg_hi:[0,1]
	v_pk_add_f32 v[48:49], v[32:33], v[64:65]
	v_pk_add_f32 v[28:29], v[32:33], v[64:65] neg_lo:[0,1] neg_hi:[0,1]
	v_pk_add_f32 v[64:65], v[60:61], v[40:41] op_sel:[0,1] op_sel_hi:[1,0] neg_hi:[0,1]
	v_pk_add_f32 v[6:7], v[60:61], v[40:41] op_sel:[0,1] op_sel_hi:[1,0] neg_lo:[0,1]
	v_pk_add_f32 v[60:61], v[50:51], v[56:57]
	v_pk_add_f32 v[22:23], v[50:51], v[56:57] neg_lo:[0,1] neg_hi:[0,1]
	v_pk_add_f32 v[50:51], v[52:53], v[72:73]
	v_pk_add_f32 v[30:31], v[52:53], v[72:73] neg_lo:[0,1] neg_hi:[0,1]
	v_pk_add_f32 v[52:53], v[18:19], v[36:37]
	v_pk_add_f32 v[56:57], v[18:19], v[36:37] neg_lo:[0,1] neg_hi:[0,1]
	v_mov_b32_e32 v18, v21
	v_pk_add_f32 v[84:85], v[4:5], v[10:11]
	v_cvt_f32_i32_e32 v18, v18
	v_pk_add_f32 v[32:33], v[42:43], v[66:67]
	v_pk_add_f32 v[40:41], v[42:43], v[66:67] neg_lo:[0,1] neg_hi:[0,1]
	v_pk_add_f32 v[66:67], v[24:25], v[80:81]
	v_pk_add_f32 v[10:11], v[24:25], v[80:81] neg_lo:[0,1] neg_hi:[0,1]
	v_pk_add_f32 v[72:73], v[14:15], v[34:35]
	v_pk_add_f32 v[24:25], v[14:15], v[34:35] neg_lo:[0,1] neg_hi:[0,1]
	v_mul_f32_e32 v15, 0x38800000, v18
	v_cos_f32_e32 v14, v15
	v_sin_f32_e32 v15, v15
	v_pk_add_f32 v[16:17], v[74:75], v[62:63]
	v_pk_add_f32 v[54:55], v[74:75], v[62:63] neg_lo:[0,1] neg_hi:[0,1]
	v_pk_add_f32 v[62:63], v[8:9], v[44:45]
	v_pk_add_f32 v[4:5], v[8:9], v[44:45] neg_lo:[0,1] neg_hi:[0,1]
	v_pk_add_f32 v[8:9], v[26:27], v[58:59]
	v_add_f32_e32 v20, v14, v14
	v_pk_add_f32 v[42:43], v[38:39], v[46:47]
	v_pk_add_f32 v[38:39], v[38:39], v[46:47] neg_lo:[0,1] neg_hi:[0,1]
	v_pk_add_f32 v[58:59], v[26:27], v[58:59] neg_lo:[0,1] neg_hi:[0,1]
	v_pk_add_f32 v[26:27], v[76:77], v[78:79]
	v_pk_add_f32 v[46:47], v[76:77], v[78:79] neg_lo:[0,1] neg_hi:[0,1]
	v_pk_mul_f32 v[18:19], v[14:15], v[14:15]
	v_mul_f32_e32 v20, v15, v20
	v_mov_b32_e32 v78, v15
	v_pk_add_f32 v[18:19], v[18:19], v[18:19] op_sel:[0,1] op_sel_hi:[0,1] neg_lo:[0,1] neg_hi:[0,1]
	v_pk_mul_f32 v[34:35], v[14:15], v[20:21] op_sel:[1,0] op_sel_hi:[0,0] neg_lo:[1,0]
	v_pk_mul_f32 v[36:37], v[78:79], v[8:9] op_sel:[0,1] op_sel_hi:[0,0] neg_hi:[0,1]
	v_pk_fma_f32 v[34:35], v[14:15], v[18:19], v[34:35]
	v_pk_fma_f32 v[8:9], v[14:15], v[8:9], v[36:37] op_sel_hi:[0,1,1]
	v_pk_mul_f32 v[14:15], v[20:21], s[46:47] op_sel_hi:[0,1]
	v_pk_fma_f32 v[36:37], v[18:19], s[40:41], v[14:15]
	s_nop 0
	v_pk_mul_f32 v[14:15], v[16:17], v[36:37] op_sel:[1,1] op_sel_hi:[0,1] neg_hi:[1,0]
	v_pk_add_f32 v[74:75], v[82:83], v[84:85]
	v_pk_fma_f32 v[16:17], v[16:17], v[36:37], v[14:15] op_sel_hi:[1,0,1]
	v_pk_mul_f32 v[14:15], v[20:21], v[34:35] op_sel:[0,1] op_sel_hi:[0,0] neg_lo:[0,1]
	v_pk_fma_f32 v[78:79], v[18:19], v[34:35], v[14:15]
	v_pk_mul_f32 v[14:15], v[34:35], v[52:53] op_sel:[1,1] op_sel_hi:[1,0] neg_hi:[0,1]
	v_pk_add_f32 v[76:77], v[12:13], v[86:87]
	v_pk_fma_f32 v[14:15], v[34:35], v[52:53], v[14:15] op_sel_hi:[0,1,1]
	v_pk_mul_f32 v[34:35], v[20:21], v[36:37] op_sel:[0,1] op_sel_hi:[0,0] neg_lo:[0,1]
	s_nop 0
	v_pk_fma_f32 v[36:37], v[18:19], v[36:37], v[34:35]
	v_pk_mul_f32 v[52:53], v[26:27], v[78:79] op_sel:[1,1] op_sel_hi:[0,1] neg_hi:[1,0]
	v_pk_mul_f32 v[34:35], v[32:33], v[36:37] op_sel:[1,1] op_sel_hi:[0,1] neg_hi:[1,0]
	v_pk_fma_f32 v[26:27], v[26:27], v[78:79], v[52:53] op_sel_hi:[1,0,1]
	v_pk_fma_f32 v[34:35], v[32:33], v[36:37], v[34:35] op_sel_hi:[1,0,1]
	v_pk_mul_f32 v[52:53], v[20:21], v[36:37] op_sel:[0,1] op_sel_hi:[0,0] neg_lo:[0,1]
	v_pk_mul_f32 v[32:33], v[20:21], v[78:79] op_sel:[0,1] op_sel_hi:[0,0] neg_lo:[0,1]
	v_pk_fma_f32 v[52:53], v[18:19], v[36:37], v[52:53]
	v_pk_fma_f32 v[32:33], v[18:19], v[78:79], v[32:33]
	v_pk_mul_f32 v[36:37], v[42:43], v[52:53] op_sel:[1,1] op_sel_hi:[0,1] neg_hi:[1,0]
	s_nop 0
	v_pk_fma_f32 v[36:37], v[42:43], v[52:53], v[36:37] op_sel_hi:[1,0,1]
	v_pk_mul_f32 v[42:43], v[20:21], v[32:33] op_sel:[0,1] op_sel_hi:[0,0] neg_lo:[0,1]
	v_pk_mul_f32 v[78:79], v[74:75], v[32:33] op_sel:[1,1] op_sel_hi:[0,1] neg_hi:[1,0]
	v_pk_fma_f32 v[42:43], v[18:19], v[32:33], v[42:43]
	v_pk_fma_f32 v[32:33], v[74:75], v[32:33], v[78:79] op_sel_hi:[1,0,1]
	v_pk_mul_f32 v[74:75], v[20:21], v[52:53] op_sel:[0,1] op_sel_hi:[0,0] neg_lo:[0,1]
	v_pk_fma_f32 v[52:53], v[18:19], v[52:53], v[74:75]
	s_nop 0
	v_pk_mul_f32 v[74:75], v[48:49], v[52:53] op_sel:[1,1] op_sel_hi:[0,1] neg_hi:[1,0]
	s_nop 0
	v_pk_fma_f32 v[48:49], v[48:49], v[52:53], v[74:75] op_sel_hi:[1,0,1]
	v_pk_mul_f32 v[74:75], v[20:21], v[42:43] op_sel:[0,1] op_sel_hi:[0,0] neg_lo:[0,1]
	v_pk_mul_f32 v[78:79], v[50:51], v[42:43] op_sel:[1,1] op_sel_hi:[0,1] neg_hi:[1,0]
	v_pk_fma_f32 v[74:75], v[18:19], v[42:43], v[74:75]
	v_pk_fma_f32 v[42:43], v[50:51], v[42:43], v[78:79] op_sel_hi:[1,0,1]
	v_pk_mul_f32 v[50:51], v[20:21], v[52:53] op_sel:[0,1] op_sel_hi:[0,0] neg_lo:[0,1]
	v_pk_fma_f32 v[78:79], v[18:19], v[52:53], v[50:51]
	s_nop 0
	v_pk_mul_f32 v[50:51], v[60:61], v[78:79] op_sel:[1,1] op_sel_hi:[0,1] neg_hi:[1,0]
	v_xor_b32_e32 v81, 0x80000000, v58
	v_pk_fma_f32 v[52:53], v[60:61], v[78:79], v[50:51] op_sel_hi:[1,0,1]
	v_pk_mul_f32 v[50:51], v[20:21], v[74:75] op_sel:[0,1] op_sel_hi:[0,0] neg_lo:[0,1]
	v_pk_fma_f32 v[60:61], v[18:19], v[74:75], v[50:51]
	v_pk_mul_f32 v[50:51], v[72:73], v[74:75] op_sel:[1,1] op_sel_hi:[0,1] neg_hi:[1,0]
	v_mov_b32_e32 v80, v59
	v_pk_fma_f32 v[50:51], v[72:73], v[74:75], v[50:51] op_sel_hi:[1,0,1]
	v_pk_mul_f32 v[72:73], v[20:21], v[78:79] op_sel:[0,1] op_sel_hi:[0,0] neg_lo:[0,1]
	v_pk_fma_f32 v[72:73], v[18:19], v[78:79], v[72:73]
	s_nop 0
	v_pk_mul_f32 v[74:75], v[64:65], v[72:73] op_sel:[1,1] op_sel_hi:[0,1] neg_hi:[1,0]
	s_nop 0
	v_pk_fma_f32 v[64:65], v[64:65], v[72:73], v[74:75] op_sel_hi:[1,0,1]
	v_pk_mul_f32 v[74:75], v[20:21], v[60:61] op_sel:[0,1] op_sel_hi:[0,0] neg_lo:[0,1]
	v_pk_mul_f32 v[78:79], v[66:67], v[60:61] op_sel:[1,1] op_sel_hi:[0,1] neg_hi:[1,0]
	v_pk_fma_f32 v[74:75], v[18:19], v[60:61], v[74:75]
	v_pk_fma_f32 v[60:61], v[66:67], v[60:61], v[78:79] op_sel_hi:[1,0,1]
	v_pk_mul_f32 v[66:67], v[20:21], v[72:73] op_sel:[0,1] op_sel_hi:[0,0] neg_lo:[0,1]
	v_pk_fma_f32 v[66:67], v[18:19], v[72:73], v[66:67]
	s_nop 0
	v_pk_mul_f32 v[72:73], v[62:63], v[66:67] op_sel:[1,1] op_sel_hi:[0,1] neg_hi:[1,0]
	s_nop 0
	v_pk_fma_f32 v[62:63], v[62:63], v[66:67], v[72:73] op_sel_hi:[1,0,1]
	v_pk_mul_f32 v[72:73], v[20:21], v[74:75] op_sel:[0,1] op_sel_hi:[0,0] neg_lo:[0,1]
	v_pk_mul_f32 v[78:79], v[76:77], v[74:75] op_sel:[1,1] op_sel_hi:[0,1] neg_hi:[1,0]
	v_pk_fma_f32 v[72:73], v[18:19], v[74:75], v[72:73]
	v_pk_fma_f32 v[74:75], v[76:77], v[74:75], v[78:79] op_sel_hi:[1,0,1]
	v_pk_mul_f32 v[76:77], v[20:21], v[66:67] op_sel:[0,1] op_sel_hi:[0,0] neg_lo:[0,1]
	s_nop 0
	v_pk_fma_f32 v[66:67], v[18:19], v[66:67], v[76:77]
	v_pk_mul_f32 v[78:79], v[20:21], v[72:73] op_sel:[0,1] op_sel_hi:[0,0] neg_lo:[0,1]
	v_pk_mul_f32 v[80:81], v[80:81], v[72:73] op_sel:[0,1]
	v_pk_fma_f32 v[78:79], v[18:19], v[72:73], v[78:79]
	v_pk_fma_f32 v[58:59], v[58:59], v[72:73], v[80:81] op_sel_hi:[1,0,1]
	v_pk_mul_f32 v[76:77], v[88:89], v[66:67] op_sel:[1,1] op_sel_hi:[0,1] neg_hi:[1,0]
	v_pk_mul_f32 v[72:73], v[20:21], v[66:67] op_sel:[0,1] op_sel_hi:[0,0] neg_lo:[0,1]
	v_pk_fma_f32 v[76:77], v[88:89], v[66:67], v[76:77] op_sel_hi:[1,0,1]
	v_pk_fma_f32 v[66:67], v[18:19], v[66:67], v[72:73]
	s_nop 0
	v_pk_mul_f32 v[72:73], v[54:55], v[66:67] op_sel:[1,1] op_sel_hi:[0,1] neg_hi:[1,0]
	s_nop 0
	v_pk_fma_f32 v[54:55], v[54:55], v[66:67], v[72:73] op_sel_hi:[1,0,1]
	v_pk_mul_f32 v[72:73], v[20:21], v[78:79] op_sel:[0,1] op_sel_hi:[0,0] neg_lo:[0,1]
	v_pk_mul_f32 v[80:81], v[56:57], v[78:79] op_sel:[1,1] op_sel_hi:[0,1] neg_hi:[1,0]
	v_pk_fma_f32 v[72:73], v[18:19], v[78:79], v[72:73]
	v_pk_fma_f32 v[56:57], v[56:57], v[78:79], v[80:81] op_sel_hi:[1,0,1]
	v_pk_mul_f32 v[78:79], v[20:21], v[66:67] op_sel:[0,1] op_sel_hi:[0,0] neg_lo:[0,1]
	v_pk_fma_f32 v[66:67], v[18:19], v[66:67], v[78:79]
	s_nop 0
	v_pk_mul_f32 v[78:79], v[40:41], v[66:67] op_sel:[1,1] op_sel_hi:[0,1] neg_hi:[1,0]
	s_nop 0
	v_pk_fma_f32 v[40:41], v[40:41], v[66:67], v[78:79] op_sel_hi:[1,0,1]
	v_pk_mul_f32 v[78:79], v[20:21], v[72:73] op_sel:[0,1] op_sel_hi:[0,0] neg_lo:[0,1]
	v_pk_mul_f32 v[80:81], v[46:47], v[72:73] op_sel:[1,1] op_sel_hi:[0,1] neg_hi:[1,0]
	v_pk_fma_f32 v[78:79], v[18:19], v[72:73], v[78:79]
	v_pk_fma_f32 v[46:47], v[46:47], v[72:73], v[80:81] op_sel_hi:[1,0,1]
	v_pk_mul_f32 v[72:73], v[20:21], v[66:67] op_sel:[0,1] op_sel_hi:[0,0] neg_lo:[0,1]
	v_pk_fma_f32 v[66:67], v[18:19], v[66:67], v[72:73]
	v_pk_add_f32 v[44:45], v[82:83], v[84:85] neg_lo:[0,1] neg_hi:[0,1]
	v_pk_mul_f32 v[72:73], v[38:39], v[66:67] op_sel:[1,1] op_sel_hi:[0,1] neg_hi:[1,0]
	s_nop 0
	v_pk_fma_f32 v[38:39], v[38:39], v[66:67], v[72:73] op_sel_hi:[1,0,1]
	v_pk_mul_f32 v[72:73], v[20:21], v[78:79] op_sel:[0,1] op_sel_hi:[0,0] neg_lo:[0,1]
	v_pk_mul_f32 v[80:81], v[44:45], v[78:79] op_sel:[1,1] op_sel_hi:[0,1] neg_hi:[1,0]
	v_pk_fma_f32 v[72:73], v[18:19], v[78:79], v[72:73]
	v_pk_fma_f32 v[44:45], v[44:45], v[78:79], v[80:81] op_sel_hi:[1,0,1]
	v_pk_mul_f32 v[78:79], v[20:21], v[66:67] op_sel:[0,1] op_sel_hi:[0,0] neg_lo:[0,1]
	v_pk_fma_f32 v[66:67], v[18:19], v[66:67], v[78:79]
	s_nop 0
	v_pk_mul_f32 v[78:79], v[28:29], v[66:67] op_sel:[1,1] op_sel_hi:[0,1] neg_hi:[1,0]
	s_nop 0
	v_pk_fma_f32 v[28:29], v[28:29], v[66:67], v[78:79] op_sel_hi:[1,0,1]
	v_pk_mul_f32 v[78:79], v[20:21], v[72:73] op_sel:[0,1] op_sel_hi:[0,0] neg_lo:[0,1]
	v_pk_mul_f32 v[80:81], v[30:31], v[72:73] op_sel:[1,1] op_sel_hi:[0,1] neg_hi:[1,0]
	v_pk_fma_f32 v[78:79], v[18:19], v[72:73], v[78:79]
	v_pk_fma_f32 v[30:31], v[30:31], v[72:73], v[80:81] op_sel_hi:[1,0,1]
	v_pk_mul_f32 v[72:73], v[20:21], v[66:67] op_sel:[0,1] op_sel_hi:[0,0] neg_lo:[0,1]
	v_pk_fma_f32 v[66:67], v[18:19], v[66:67], v[72:73]
	s_nop 0
	v_pk_mul_f32 v[72:73], v[22:23], v[66:67] op_sel:[1,1] op_sel_hi:[0,1] neg_hi:[1,0]
	s_nop 0
	v_pk_fma_f32 v[22:23], v[22:23], v[66:67], v[72:73] op_sel_hi:[1,0,1]
	v_pk_mul_f32 v[72:73], v[20:21], v[78:79] op_sel:[0,1] op_sel_hi:[0,0] neg_lo:[0,1]
	v_pk_mul_f32 v[80:81], v[24:25], v[78:79] op_sel:[1,1] op_sel_hi:[0,1] neg_hi:[1,0]
	v_pk_fma_f32 v[72:73], v[18:19], v[78:79], v[72:73]
	v_pk_fma_f32 v[24:25], v[24:25], v[78:79], v[80:81] op_sel_hi:[1,0,1]
	v_pk_mul_f32 v[78:79], v[20:21], v[66:67] op_sel:[0,1] op_sel_hi:[0,0] neg_lo:[0,1]
	v_pk_fma_f32 v[66:67], v[18:19], v[66:67], v[78:79]
	s_nop 0
	v_pk_mul_f32 v[78:79], v[6:7], v[66:67] op_sel:[1,1] op_sel_hi:[0,1] neg_hi:[1,0]
	s_nop 0
	v_pk_fma_f32 v[6:7], v[6:7], v[66:67], v[78:79] op_sel_hi:[1,0,1]
	v_pk_mul_f32 v[78:79], v[20:21], v[72:73] op_sel:[0,1] op_sel_hi:[0,0] neg_lo:[0,1]
	v_pk_mul_f32 v[80:81], v[10:11], v[72:73] op_sel:[1,1] op_sel_hi:[0,1] neg_hi:[1,0]
	v_pk_fma_f32 v[78:79], v[18:19], v[72:73], v[78:79]
	v_pk_fma_f32 v[10:11], v[10:11], v[72:73], v[80:81] op_sel_hi:[1,0,1]
	v_pk_mul_f32 v[72:73], v[20:21], v[66:67] op_sel:[0,1] op_sel_hi:[0,0] neg_lo:[0,1]
	v_pk_fma_f32 v[18:19], v[18:19], v[66:67], v[72:73]
	v_pk_add_f32 v[12:13], v[12:13], v[86:87] neg_lo:[0,1] neg_hi:[0,1]
	v_pk_mul_f32 v[66:67], v[4:5], v[18:19] op_sel:[1,1] op_sel_hi:[0,1] neg_hi:[1,0]
	s_nop 0
	v_pk_fma_f32 v[4:5], v[4:5], v[18:19], v[66:67] op_sel_hi:[1,0,1]
	s_nop 0
	s_nop 0
	v_pk_mul_f32 v[18:19], v[12:13], v[78:79] op_sel:[1,1] op_sel_hi:[0,1] neg_hi:[1,0]
	s_nop 0
	v_pk_fma_f32 v[12:13], v[12:13], v[78:79], v[18:19] op_sel_hi:[1,0,1]
	v_lshrrev_b32_e32 v18, 5, v21
	v_bitop3_b32 v18, v18, v21, 15 bitop3:0x6c
	v_lshlrev_b32_e32 v18, 3, v18
	v_bfe_u32 v19, v21, 5, 4
	v_add_u32_e32 v20, 16, v18
	ds_write_b64 v20, v[2:3]
	v_bitop3_b32 v2, v19, v21, 16 bitop3:0x36
	v_lshl_add_u32 v2, v2, 3, 16
	v_add_u32_e32 v3, s79, v18
	ds_write_b64 v2, v[76:77] offset:4096
	ds_write_b64 v20, v[48:49] offset:8192
	ds_write_b64 v2, v[28:29] offset:12288
	ds_write_b64 v20, v[34:35] offset:16384
	ds_write_b64 v2, v[40:41] offset:20480
	ds_write_b64 v20, v[64:65] offset:24576
	ds_write_b64 v2, v[6:7] offset:28672
	ds_write_b64 v20, v[16:17] offset:32768
	ds_write_b64 v2, v[54:55] offset:36864
	ds_write_b64 v20, v[52:53] offset:40960
	ds_write_b64 v2, v[22:23] offset:45056
	ds_write_b64 v20, v[36:37] offset:49152
	ds_write_b64 v2, v[38:39] offset:53248
	ds_write_b64 v20, v[62:63] offset:57344
	ds_write_b64 v2, v[4:5] offset:61440
	ds_write_b64 v3, v[8:9]
	v_add_u32_e32 v3, 0x11000, v2
	ds_write_b64 v3, v[58:59]
	v_add_u32_e32 v3, 0x12000, v20
	ds_write_b64 v3, v[42:43]
	v_add_u32_e32 v3, 0x13000, v2
	ds_write_b64 v3, v[30:31]
	v_add_u32_e32 v3, 0x14000, v20
	ds_write_b64 v3, v[26:27]
	v_add_u32_e32 v3, 0x15000, v2
	ds_write_b64 v3, v[46:47]
	v_add_u32_e32 v3, 0x16000, v20
	ds_write_b64 v3, v[60:61]
	v_add_u32_e32 v3, 0x17000, v2
	ds_write_b64 v3, v[10:11]
	v_add_u32_e32 v3, 0x18000, v20
	ds_write_b64 v3, v[14:15]
	v_add_u32_e32 v3, 0x19000, v2
	ds_write_b64 v3, v[56:57]
	v_add_u32_e32 v3, 0x1a000, v20
	ds_write_b64 v3, v[50:51]
	v_add_u32_e32 v3, 0x1b000, v2
	ds_write_b64 v3, v[24:25]
	v_add_u32_e32 v3, 0x1c000, v20
	ds_write_b64 v3, v[32:33]
	v_add_u32_e32 v3, 0x1d000, v2
	ds_write_b64 v3, v[44:45]
	v_add_u32_e32 v3, 0x1e000, v20
	v_add_u32_e32 v2, 0x1f000, v2
	v_mov_b32_e32 v11, v146
	ds_write_b64 v3, v[74:75]
	ds_write_b64 v2, v[12:13]
	s_waitcnt lgkmcnt(0)
	s_barrier
	s_nop 0
	v_lshlrev_b32_e32 v2, 5, v11
	v_and_b32_e32 v2, 0xfffffe00, v2
	v_and_or_b32 v3, v11, 16, v2
	v_bitop3_b32 v2, v2, 16, v11 bitop3:0x34
	v_bitop3_b32 v12, v11, 2, 15 bitop3:0x6c
	v_bitop3_b32 v22, v11, 4, 15 bitop3:0x6c
	v_bitop3_b32 v30, v11, 6, 15 bitop3:0x6c
	v_bitop3_b32 v38, v11, 8, 15 bitop3:0x6c
	v_and_b32_e32 v10, 15, v11
	v_lshl_add_u32 v18, v3, 3, 16
	v_lshl_add_u32 v87, v2, 3, 16
	v_lshlrev_b32_e32 v12, 3, v12
	v_lshlrev_b32_e32 v22, 3, v22
	v_lshlrev_b32_e32 v30, 3, v30
	v_lshlrev_b32_e32 v38, 3, v38
	v_lshlrev_b32_e32 v3, 3, v10
	v_bitop3_b32 v2, v11, 1, 15 bitop3:0x6c
	v_add_u32_e32 v57, v18, v12
	v_add_u32_e32 v58, v87, v12
	v_bitop3_b32 v12, v11, 3, 15 bitop3:0x6c
	v_add_u32_e32 v61, v18, v22
	v_add_u32_e32 v62, v87, v22
	v_bitop3_b32 v22, v11, 5, 15 bitop3:0x6c
	v_add_u32_e32 v65, v18, v30
	v_add_u32_e32 v66, v87, v30
	v_bitop3_b32 v30, v11, 7, 15 bitop3:0x6c
	v_add_u32_e32 v72, v18, v38
	v_add_u32_e32 v73, v87, v38
	v_bitop3_b32 v38, v11, 9, 15 bitop3:0x6c
	v_add_u32_e32 v19, v18, v3
	v_lshlrev_b32_e32 v2, 3, v2
	v_lshlrev_b32_e32 v12, 3, v12
	v_lshlrev_b32_e32 v22, 3, v22
	v_lshlrev_b32_e32 v30, 3, v30
	v_lshlrev_b32_e32 v38, 3, v38
	v_add_u32_e32 v54, v87, v3
	v_add_u32_e32 v55, v18, v2
	v_add_u32_e32 v56, v87, v2
	ds_read_b64 v[2:3], v19
	ds_read_b64 v[4:5], v54
	ds_read_b64 v[6:7], v55 offset:256
	ds_read_b64 v[8:9], v56 offset:256
	v_add_u32_e32 v59, v18, v12
	v_add_u32_e32 v60, v87, v12
	ds_read_b64 v[12:13], v57 offset:512
	ds_read_b64 v[14:15], v58 offset:512
	ds_read_b64 v[16:17], v59 offset:768
	ds_read_b64 v[20:21], v60 offset:768
	v_add_u32_e32 v63, v18, v22
	v_add_u32_e32 v64, v87, v22
	ds_read_b64 v[22:23], v61 offset:1024
	ds_read_b64 v[24:25], v62 offset:1024
	ds_read_b64 v[26:27], v63 offset:1280
	ds_read_b64 v[28:29], v64 offset:1280
	v_add_u32_e32 v67, v18, v30
	v_add_u32_e32 v71, v87, v30
	ds_read_b64 v[30:31], v65 offset:1536
	ds_read_b64 v[32:33], v66 offset:1536
	ds_read_b64 v[34:35], v67 offset:1792
	ds_read_b64 v[36:37], v71 offset:1792
	v_add_u32_e32 v74, v18, v38
	v_add_u32_e32 v75, v87, v38
	ds_read_b64 v[38:39], v72 offset:2048
	ds_read_b64 v[40:41], v73 offset:2048
	ds_read_b64 v[42:43], v74 offset:2304
	ds_read_b64 v[44:45], v75 offset:2304
	v_bitop3_b32 v46, v11, 10, 15 bitop3:0x6c
	s_waitcnt lgkmcnt(3)
	v_pk_add_f32 v[104:105], v[2:3], v[38:39]
	v_pk_add_f32 v[2:3], v[2:3], v[38:39] neg_lo:[0,1] neg_hi:[0,1]
	s_waitcnt lgkmcnt(2)
	v_pk_add_f32 v[38:39], v[4:5], v[40:41]
	v_pk_add_f32 v[4:5], v[4:5], v[40:41] neg_lo:[0,1] neg_hi:[0,1]
	v_lshlrev_b32_e32 v46, 3, v46
	v_pk_mul_f32 v[40:41], v[4:5], s[48:49] op_sel:[1,0] op_sel_hi:[0,0] neg_hi:[1,0]
	v_add_u32_e32 v76, v18, v46
	v_pk_fma_f32 v[4:5], v[4:5], s[44:45], v[40:41] op_sel_hi:[1,0,1]
	s_waitcnt lgkmcnt(1)
	v_pk_add_f32 v[40:41], v[6:7], v[42:43]
	v_pk_add_f32 v[6:7], v[6:7], v[42:43] neg_lo:[0,1] neg_hi:[0,1]
	v_add_u32_e32 v77, v87, v46
	v_bitop3_b32 v46, v11, 11, 15 bitop3:0x6c
	v_pk_mul_f32 v[42:43], v[6:7], s[54:55] op_sel:[1,0] op_sel_hi:[0,0] neg_hi:[1,0]
	v_lshlrev_b32_e32 v46, 3, v46
	v_pk_fma_f32 v[6:7], v[6:7], s[52:53], v[42:43] op_sel_hi:[1,0,1]
	s_waitcnt lgkmcnt(0)
	v_pk_add_f32 v[42:43], v[8:9], v[44:45]
	v_pk_add_f32 v[8:9], v[8:9], v[44:45] neg_lo:[0,1] neg_hi:[0,1]
	v_add_u32_e32 v78, v18, v46
	v_add_u32_e32 v79, v87, v46
	ds_read_b64 v[46:47], v76 offset:2560
	ds_read_b64 v[48:49], v77 offset:2560
	ds_read_b64 v[50:51], v78 offset:2816
	ds_read_b64 v[52:53], v79 offset:2816
	v_pk_mul_f32 v[44:45], v[8:9], s[58:59] op_sel:[1,0] op_sel_hi:[0,0] neg_hi:[1,0]
	v_bitop3_b32 v80, v11, 12, 15 bitop3:0x6c
	v_pk_fma_f32 v[8:9], v[8:9], s[56:57], v[44:45] op_sel_hi:[1,0,1]
	s_waitcnt lgkmcnt(3)
	v_pk_add_f32 v[44:45], v[12:13], v[46:47]
	v_pk_add_f32 v[12:13], v[12:13], v[46:47] neg_lo:[0,1] neg_hi:[0,1]
	v_lshlrev_b32_e32 v81, 3, v80
	v_pk_mul_f32 v[46:47], v[12:13], s[60:61] op_sel:[1,0] op_sel_hi:[0,0] neg_hi:[1,0]
	v_bitop3_b32 v82, v11, 13, 15 bitop3:0x6c
	v_pk_fma_f32 v[12:13], v[12:13], s[60:61], v[46:47] op_sel_hi:[1,0,1]
	s_waitcnt lgkmcnt(2)
	v_pk_add_f32 v[46:47], v[14:15], v[48:49]
	v_pk_add_f32 v[14:15], v[14:15], v[48:49] neg_lo:[0,1] neg_hi:[0,1]
	v_add_u32_e32 v80, v18, v81
	v_pk_mul_f32 v[48:49], v[14:15], s[56:57] op_sel:[1,0] op_sel_hi:[0,0] neg_hi:[1,0]
	v_lshlrev_b32_e32 v83, 3, v82
	v_pk_fma_f32 v[14:15], v[14:15], s[58:59], v[48:49] op_sel_hi:[1,0,1]
	s_waitcnt lgkmcnt(1)
	v_pk_add_f32 v[48:49], v[16:17], v[50:51]
	v_pk_add_f32 v[16:17], v[16:17], v[50:51] neg_lo:[0,1] neg_hi:[0,1]
	v_add_u32_e32 v81, v87, v81
	v_pk_mul_f32 v[50:51], v[16:17], s[52:53] op_sel:[1,0] op_sel_hi:[0,0] neg_hi:[1,0]
	v_add_u32_e32 v82, v18, v83
	v_pk_fma_f32 v[16:17], v[16:17], s[54:55], v[50:51] op_sel_hi:[1,0,1]
	s_waitcnt lgkmcnt(0)
	v_pk_add_f32 v[50:51], v[20:21], v[52:53]
	v_pk_add_f32 v[20:21], v[20:21], v[52:53] neg_lo:[0,1] neg_hi:[0,1]
	v_add_u32_e32 v83, v87, v83
	ds_read_b64 v[88:89], v80 offset:3072
	ds_read_b64 v[90:91], v81 offset:3072
	ds_read_b64 v[92:93], v82 offset:3328
	ds_read_b64 v[94:95], v83 offset:3328
	v_pk_mul_f32 v[52:53], v[20:21], s[44:45] op_sel:[1,0] op_sel_hi:[0,0] neg_hi:[1,0]
	v_bitop3_b32 v84, v11, 14, 15 bitop3:0x6c
	v_pk_fma_f32 v[20:21], v[20:21], s[48:49], v[52:53] op_sel_hi:[1,0,1]
	s_waitcnt lgkmcnt(3)
	v_pk_add_f32 v[52:53], v[22:23], v[88:89]
	v_pk_add_f32 v[22:23], v[22:23], v[88:89] neg_lo:[0,1] neg_hi:[0,1]
	v_lshlrev_b32_e32 v85, 3, v84
	v_xor_b32_e32 v89, 0x80000000, v22
	v_mov_b32_e32 v88, v23
	s_waitcnt lgkmcnt(2)
	v_pk_add_f32 v[22:23], v[24:25], v[90:91]
	v_pk_add_f32 v[24:25], v[24:25], v[90:91] neg_lo:[0,1] neg_hi:[0,1]
	v_bitop3_b32 v11, v11, 15, v11 bitop3:0xc
	v_pk_mul_f32 v[90:91], v[24:25], s[48:49] op_sel_hi:[1,0]
	v_xor_b32_e32 v107, 0x80000000, v24
	v_mov_b32_e32 v106, v25
	v_pk_fma_f32 v[24:25], v[106:107], s[44:45], v[90:91] op_sel_hi:[1,0,1] neg_lo:[0,0,1] neg_hi:[0,0,1]
	s_waitcnt lgkmcnt(1)
	v_pk_add_f32 v[90:91], v[26:27], v[92:93]
	v_pk_add_f32 v[26:27], v[26:27], v[92:93] neg_lo:[0,1] neg_hi:[0,1]
	v_add_u32_e32 v84, v18, v85
	v_lshlrev_b32_e32 v11, 3, v11
	v_pk_mul_f32 v[92:93], v[26:27], s[54:55] op_sel_hi:[1,0]
	v_xor_b32_e32 v107, 0x80000000, v26
	v_mov_b32_e32 v106, v27
	v_add_u32_e32 v85, v87, v85
	v_add_u32_e32 v86, v18, v11
	v_add_u32_e32 v87, v87, v11
	ds_read_b64 v[96:97], v84 offset:3584
	ds_read_b64 v[98:99], v85 offset:3584
	ds_read_b64 v[100:101], v86 offset:3840
	ds_read_b64 v[102:103], v87 offset:3840
	v_pk_fma_f32 v[26:27], v[106:107], s[52:53], v[92:93] op_sel_hi:[1,0,1] neg_lo:[0,0,1] neg_hi:[0,0,1]
	s_waitcnt lgkmcnt(4)
	v_pk_add_f32 v[92:93], v[28:29], v[94:95]
	v_pk_add_f32 v[28:29], v[28:29], v[94:95] neg_lo:[0,1] neg_hi:[0,1]
	s_nop 0
	v_pk_mul_f32 v[94:95], v[28:29], s[58:59] op_sel_hi:[1,0]
	v_xor_b32_e32 v107, 0x80000000, v28
	v_mov_b32_e32 v106, v29
	v_pk_fma_f32 v[28:29], v[106:107], s[56:57], v[94:95] op_sel_hi:[1,0,1] neg_lo:[0,0,1] neg_hi:[0,0,1]
	s_waitcnt lgkmcnt(3)
	v_pk_add_f32 v[94:95], v[30:31], v[96:97]
	v_pk_add_f32 v[30:31], v[30:31], v[96:97] neg_lo:[0,1] neg_hi:[0,1]
	v_cvt_f32_i32_e32 v10, v10
	v_pk_mul_f32 v[96:97], v[30:31], s[60:61] op_sel_hi:[1,0]
	v_xor_b32_e32 v107, 0x80000000, v30
	v_mov_b32_e32 v106, v31
	v_pk_fma_f32 v[30:31], v[106:107], s[60:61], v[96:97] op_sel_hi:[1,0,1] neg_lo:[0,0,1] neg_hi:[0,0,1]
	s_waitcnt lgkmcnt(2)
	v_pk_add_f32 v[96:97], v[32:33], v[98:99]
	v_pk_add_f32 v[32:33], v[32:33], v[98:99] neg_lo:[0,1] neg_hi:[0,1]
	v_mul_f32_e32 v10, 0x3b000000, v10
	v_pk_mul_f32 v[98:99], v[32:33], s[56:57] op_sel_hi:[1,0]
	v_xor_b32_e32 v107, 0x80000000, v32
	v_mov_b32_e32 v106, v33
	v_pk_fma_f32 v[32:33], v[106:107], s[58:59], v[98:99] op_sel_hi:[1,0,1] neg_lo:[0,0,1] neg_hi:[0,0,1]
	s_waitcnt lgkmcnt(1)
	v_pk_add_f32 v[98:99], v[34:35], v[100:101]
	v_pk_add_f32 v[34:35], v[34:35], v[100:101] neg_lo:[0,1] neg_hi:[0,1]
	s_nop 0
	v_pk_mul_f32 v[100:101], v[34:35], s[52:53] op_sel_hi:[1,0]
	v_xor_b32_e32 v107, 0x80000000, v34
	v_mov_b32_e32 v106, v35
	v_pk_fma_f32 v[34:35], v[106:107], s[54:55], v[100:101] op_sel_hi:[1,0,1] neg_lo:[0,0,1] neg_hi:[0,0,1]
	s_waitcnt lgkmcnt(0)
	v_pk_add_f32 v[100:101], v[36:37], v[102:103]
	v_pk_add_f32 v[36:37], v[36:37], v[102:103] neg_lo:[0,1] neg_hi:[0,1]
	s_nop 0
	v_pk_mul_f32 v[102:103], v[36:37], s[44:45] op_sel_hi:[1,0]
	v_xor_b32_e32 v107, 0x80000000, v36
	v_mov_b32_e32 v106, v37
	v_pk_fma_f32 v[36:37], v[106:107], s[48:49], v[102:103] op_sel_hi:[1,0,1] neg_lo:[0,0,1] neg_hi:[0,0,1]
	v_pk_add_f32 v[102:103], v[104:105], v[52:53]
	v_pk_add_f32 v[52:53], v[104:105], v[52:53] neg_lo:[0,1] neg_hi:[0,1]
	v_pk_add_f32 v[104:105], v[38:39], v[22:23]
	v_pk_add_f32 v[22:23], v[38:39], v[22:23] neg_lo:[0,1] neg_hi:[0,1]
	s_nop 0
	v_pk_mul_f32 v[38:39], v[22:23], s[54:55] op_sel:[1,0] op_sel_hi:[0,0] neg_hi:[1,0]
	s_nop 0
	v_pk_fma_f32 v[22:23], v[22:23], s[52:53], v[38:39] op_sel_hi:[1,0,1]
	v_pk_add_f32 v[38:39], v[40:41], v[90:91]
	v_pk_add_f32 v[40:41], v[40:41], v[90:91] neg_lo:[0,1] neg_hi:[0,1]
	s_nop 0
	v_pk_mul_f32 v[90:91], v[40:41], s[60:61] op_sel:[1,0] op_sel_hi:[0,0] neg_hi:[1,0]
	s_nop 0
	v_pk_fma_f32 v[40:41], v[40:41], s[60:61], v[90:91] op_sel_hi:[1,0,1]
	v_pk_add_f32 v[90:91], v[42:43], v[92:93]
	v_pk_add_f32 v[42:43], v[42:43], v[92:93] neg_lo:[0,1] neg_hi:[0,1]
	s_nop 0
	v_pk_mul_f32 v[92:93], v[42:43], s[52:53] op_sel:[1,0] op_sel_hi:[0,0] neg_hi:[1,0]
	s_nop 0
	v_pk_fma_f32 v[42:43], v[42:43], s[54:55], v[92:93] op_sel_hi:[1,0,1]
	v_pk_add_f32 v[92:93], v[44:45], v[94:95]
	v_pk_add_f32 v[44:45], v[44:45], v[94:95] neg_lo:[0,1] neg_hi:[0,1]
	s_nop 0
	v_xor_b32_e32 v95, 0x80000000, v44
	v_mov_b32_e32 v94, v45
	v_pk_add_f32 v[44:45], v[46:47], v[96:97]
	v_pk_add_f32 v[46:47], v[46:47], v[96:97] neg_lo:[0,1] neg_hi:[0,1]
	s_nop 0
	v_pk_mul_f32 v[96:97], v[46:47], s[54:55] op_sel_hi:[1,0]
	v_xor_b32_e32 v107, 0x80000000, v46
	v_mov_b32_e32 v106, v47
	v_pk_fma_f32 v[46:47], v[106:107], s[52:53], v[96:97] op_sel_hi:[1,0,1] neg_lo:[0,0,1] neg_hi:[0,0,1]
	v_pk_add_f32 v[96:97], v[48:49], v[98:99]
	v_pk_add_f32 v[48:49], v[48:49], v[98:99] neg_lo:[0,1] neg_hi:[0,1]
	s_nop 0
	v_pk_mul_f32 v[98:99], v[48:49], s[60:61] op_sel_hi:[1,0]
	v_xor_b32_e32 v107, 0x80000000, v48
	v_mov_b32_e32 v106, v49
	v_pk_fma_f32 v[48:49], v[106:107], s[60:61], v[98:99] op_sel_hi:[1,0,1] neg_lo:[0,0,1] neg_hi:[0,0,1]
	v_pk_add_f32 v[98:99], v[50:51], v[100:101]
	v_pk_add_f32 v[50:51], v[50:51], v[100:101] neg_lo:[0,1] neg_hi:[0,1]
	s_nop 0
	v_pk_mul_f32 v[100:101], v[50:51], s[52:53] op_sel_hi:[1,0]
	v_xor_b32_e32 v107, 0x80000000, v50
	v_mov_b32_e32 v106, v51
	v_pk_fma_f32 v[50:51], v[106:107], s[54:55], v[100:101] op_sel_hi:[1,0,1] neg_lo:[0,0,1] neg_hi:[0,0,1]
	v_pk_add_f32 v[100:101], v[2:3], v[88:89]
	v_pk_add_f32 v[2:3], v[2:3], v[88:89] neg_lo:[0,1] neg_hi:[0,1]
	v_pk_add_f32 v[88:89], v[4:5], v[24:25]
	v_pk_add_f32 v[4:5], v[4:5], v[24:25] neg_lo:[0,1] neg_hi:[0,1]
	s_nop 0
	v_pk_mul_f32 v[24:25], v[4:5], s[54:55] op_sel:[1,0] op_sel_hi:[0,0] neg_hi:[1,0]
	s_nop 0
	v_pk_fma_f32 v[4:5], v[4:5], s[52:53], v[24:25] op_sel_hi:[1,0,1]
	v_pk_add_f32 v[24:25], v[6:7], v[26:27]
	v_pk_add_f32 v[6:7], v[6:7], v[26:27] neg_lo:[0,1] neg_hi:[0,1]
	s_nop 0
	v_pk_mul_f32 v[26:27], v[6:7], s[60:61] op_sel:[1,0] op_sel_hi:[0,0] neg_hi:[1,0]
	s_nop 0
	v_pk_fma_f32 v[6:7], v[6:7], s[60:61], v[26:27] op_sel_hi:[1,0,1]
	v_pk_add_f32 v[26:27], v[8:9], v[28:29]
	v_pk_add_f32 v[8:9], v[8:9], v[28:29] neg_lo:[0,1] neg_hi:[0,1]
	s_nop 0
	v_pk_mul_f32 v[28:29], v[8:9], s[52:53] op_sel:[1,0] op_sel_hi:[0,0] neg_hi:[1,0]
	s_nop 0
	v_pk_fma_f32 v[8:9], v[8:9], s[54:55], v[28:29] op_sel_hi:[1,0,1]
	v_pk_add_f32 v[28:29], v[12:13], v[30:31]
	v_pk_add_f32 v[12:13], v[12:13], v[30:31] neg_lo:[0,1] neg_hi:[0,1]
	s_nop 0
	v_xor_b32_e32 v31, 0x80000000, v12
	v_mov_b32_e32 v30, v13
	v_pk_add_f32 v[12:13], v[14:15], v[32:33]
	v_pk_add_f32 v[14:15], v[14:15], v[32:33] neg_lo:[0,1] neg_hi:[0,1]
	s_nop 0
	v_pk_mul_f32 v[32:33], v[14:15], s[54:55] op_sel_hi:[1,0]
	v_xor_b32_e32 v107, 0x80000000, v14
	v_mov_b32_e32 v106, v15
	v_pk_fma_f32 v[14:15], v[106:107], s[52:53], v[32:33] op_sel_hi:[1,0,1] neg_lo:[0,0,1] neg_hi:[0,0,1]
	v_pk_add_f32 v[32:33], v[16:17], v[34:35]
	v_pk_add_f32 v[16:17], v[16:17], v[34:35] neg_lo:[0,1] neg_hi:[0,1]
	s_nop 0
	v_pk_mul_f32 v[34:35], v[16:17], s[60:61] op_sel_hi:[1,0]
	v_xor_b32_e32 v107, 0x80000000, v16
	v_mov_b32_e32 v106, v17
	v_pk_fma_f32 v[16:17], v[106:107], s[60:61], v[34:35] op_sel_hi:[1,0,1] neg_lo:[0,0,1] neg_hi:[0,0,1]
	v_pk_add_f32 v[34:35], v[20:21], v[36:37]
	v_pk_add_f32 v[20:21], v[20:21], v[36:37] neg_lo:[0,1] neg_hi:[0,1]
	s_nop 0
	v_pk_mul_f32 v[36:37], v[20:21], s[52:53] op_sel_hi:[1,0]
	v_xor_b32_e32 v107, 0x80000000, v20
	v_mov_b32_e32 v106, v21
	v_pk_fma_f32 v[20:21], v[106:107], s[54:55], v[36:37] op_sel_hi:[1,0,1] neg_lo:[0,0,1] neg_hi:[0,0,1]
	v_pk_add_f32 v[36:37], v[102:103], v[92:93]
	v_pk_add_f32 v[92:93], v[102:103], v[92:93] neg_lo:[0,1] neg_hi:[0,1]
	v_pk_add_f32 v[102:103], v[104:105], v[44:45]
	v_pk_add_f32 v[44:45], v[104:105], v[44:45] neg_lo:[0,1] neg_hi:[0,1]
	s_nop 0
	v_pk_mul_f32 v[104:105], v[44:45], s[60:61] op_sel:[1,0] op_sel_hi:[0,0] neg_hi:[1,0]
	s_nop 0
	v_pk_fma_f32 v[44:45], v[44:45], s[60:61], v[104:105] op_sel_hi:[1,0,1]
	v_pk_add_f32 v[104:105], v[38:39], v[96:97]
	v_pk_add_f32 v[38:39], v[38:39], v[96:97] neg_lo:[0,1] neg_hi:[0,1]
	s_nop 0
	v_xor_b32_e32 v97, 0x80000000, v38
	v_mov_b32_e32 v96, v39
	v_pk_add_f32 v[38:39], v[90:91], v[98:99]
	v_pk_add_f32 v[90:91], v[90:91], v[98:99] neg_lo:[0,1] neg_hi:[0,1]
	s_nop 0
	v_pk_mul_f32 v[98:99], v[90:91], s[60:61] op_sel_hi:[1,0]
	v_xor_b32_e32 v107, 0x80000000, v90
	v_mov_b32_e32 v106, v91
	v_pk_fma_f32 v[90:91], v[106:107], s[60:61], v[98:99] op_sel_hi:[1,0,1] neg_lo:[0,0,1] neg_hi:[0,0,1]
	v_pk_add_f32 v[98:99], v[52:53], v[94:95]
	v_pk_add_f32 v[52:53], v[52:53], v[94:95] neg_lo:[0,1] neg_hi:[0,1]
	v_pk_add_f32 v[94:95], v[22:23], v[46:47]
	v_pk_add_f32 v[22:23], v[22:23], v[46:47] neg_lo:[0,1] neg_hi:[0,1]
	s_nop 0
	v_pk_mul_f32 v[46:47], v[22:23], s[60:61] op_sel:[1,0] op_sel_hi:[0,0] neg_hi:[1,0]
	s_nop 0
	v_pk_fma_f32 v[22:23], v[22:23], s[60:61], v[46:47] op_sel_hi:[1,0,1]
	v_pk_add_f32 v[46:47], v[40:41], v[48:49]
	v_pk_add_f32 v[40:41], v[40:41], v[48:49] neg_lo:[0,1] neg_hi:[0,1]
	s_nop 0
	v_xor_b32_e32 v49, 0x80000000, v40
	v_mov_b32_e32 v48, v41
	v_pk_add_f32 v[40:41], v[42:43], v[50:51]
	v_pk_add_f32 v[42:43], v[42:43], v[50:51] neg_lo:[0,1] neg_hi:[0,1]
	s_nop 0
	v_pk_mul_f32 v[50:51], v[42:43], s[60:61] op_sel_hi:[1,0]
	v_xor_b32_e32 v107, 0x80000000, v42
	v_mov_b32_e32 v106, v43
	v_pk_fma_f32 v[42:43], v[106:107], s[60:61], v[50:51] op_sel_hi:[1,0,1] neg_lo:[0,0,1] neg_hi:[0,0,1]
	v_pk_add_f32 v[50:51], v[100:101], v[28:29]
	v_pk_add_f32 v[28:29], v[100:101], v[28:29] neg_lo:[0,1] neg_hi:[0,1]
	v_pk_add_f32 v[100:101], v[88:89], v[12:13]
	v_pk_add_f32 v[12:13], v[88:89], v[12:13] neg_lo:[0,1] neg_hi:[0,1]
	s_nop 0
	v_pk_mul_f32 v[88:89], v[12:13], s[60:61] op_sel:[1,0] op_sel_hi:[0,0] neg_hi:[1,0]
	s_nop 0
	v_pk_fma_f32 v[12:13], v[12:13], s[60:61], v[88:89] op_sel_hi:[1,0,1]
	v_pk_add_f32 v[88:89], v[24:25], v[32:33]
	v_pk_add_f32 v[24:25], v[24:25], v[32:33] neg_lo:[0,1] neg_hi:[0,1]
	v_pk_add_f32 v[108:109], v[50:51], v[88:89]
	v_xor_b32_e32 v33, 0x80000000, v24
	v_mov_b32_e32 v32, v25
	v_pk_add_f32 v[24:25], v[26:27], v[34:35]
	v_pk_add_f32 v[26:27], v[26:27], v[34:35] neg_lo:[0,1] neg_hi:[0,1]
	v_pk_add_f32 v[50:51], v[50:51], v[88:89] neg_lo:[0,1] neg_hi:[0,1]
	v_pk_mul_f32 v[34:35], v[26:27], s[60:61] op_sel_hi:[1,0]
	v_xor_b32_e32 v107, 0x80000000, v26
	v_mov_b32_e32 v106, v27
	v_pk_fma_f32 v[26:27], v[106:107], s[60:61], v[34:35] op_sel_hi:[1,0,1] neg_lo:[0,0,1] neg_hi:[0,0,1]
	v_pk_add_f32 v[34:35], v[2:3], v[30:31]
	v_pk_add_f32 v[2:3], v[2:3], v[30:31] neg_lo:[0,1] neg_hi:[0,1]
	v_pk_add_f32 v[30:31], v[4:5], v[14:15]
	v_pk_add_f32 v[4:5], v[4:5], v[14:15] neg_lo:[0,1] neg_hi:[0,1]
	v_pk_add_f32 v[110:111], v[12:13], v[26:27]
	v_pk_mul_f32 v[14:15], v[4:5], s[60:61] op_sel:[1,0] op_sel_hi:[0,0] neg_hi:[1,0]
	v_pk_add_f32 v[12:13], v[12:13], v[26:27] neg_lo:[0,1] neg_hi:[0,1]
	v_pk_fma_f32 v[4:5], v[4:5], s[60:61], v[14:15] op_sel_hi:[1,0,1]
	v_pk_add_f32 v[14:15], v[6:7], v[16:17]
	v_pk_add_f32 v[6:7], v[6:7], v[16:17] neg_lo:[0,1] neg_hi:[0,1]
	v_pk_add_f32 v[88:89], v[100:101], v[24:25]
	v_xor_b32_e32 v17, 0x80000000, v6
	v_mov_b32_e32 v16, v7
	v_pk_add_f32 v[6:7], v[8:9], v[20:21]
	v_pk_add_f32 v[8:9], v[8:9], v[20:21] neg_lo:[0,1] neg_hi:[0,1]
	v_xor_b32_e32 v113, 0x80000000, v12
	v_pk_mul_f32 v[20:21], v[8:9], s[60:61] op_sel_hi:[1,0]
	s_nop 0
	v_pk_fma_f32 v[8:9], v[8:9], s[60:61], v[20:21] op_sel:[1,0,0] op_sel_hi:[0,0,1] neg_lo:[0,0,1] neg_hi:[1,0,1]
	v_pk_add_f32 v[20:21], v[36:37], v[104:105]
	v_pk_add_f32 v[36:37], v[36:37], v[104:105] neg_lo:[0,1] neg_hi:[0,1]
	v_pk_add_f32 v[104:105], v[102:103], v[38:39]
	v_pk_add_f32 v[38:39], v[102:103], v[38:39] neg_lo:[0,1] neg_hi:[0,1]
	v_pk_add_f32 v[106:107], v[52:53], v[48:49]
	v_xor_b32_e32 v103, 0x80000000, v38
	v_mov_b32_e32 v102, v39
	v_pk_add_f32 v[38:39], v[92:93], v[96:97]
	v_pk_add_f32 v[92:93], v[92:93], v[96:97] neg_lo:[0,1] neg_hi:[0,1]
	v_pk_add_f32 v[96:97], v[44:45], v[90:91]
	v_pk_add_f32 v[44:45], v[44:45], v[90:91] neg_lo:[0,1] neg_hi:[0,1]
	v_pk_add_f32 v[48:49], v[52:53], v[48:49] neg_lo:[0,1] neg_hi:[0,1]
	v_pk_add_f32 v[52:53], v[22:23], v[42:43]
	v_pk_add_f32 v[22:23], v[22:23], v[42:43] neg_lo:[0,1] neg_hi:[0,1]
	v_xor_b32_e32 v91, 0x80000000, v44
	v_mov_b32_e32 v90, v45
	v_pk_add_f32 v[44:45], v[98:99], v[46:47]
	v_pk_add_f32 v[46:47], v[98:99], v[46:47] neg_lo:[0,1] neg_hi:[0,1]
	v_pk_add_f32 v[98:99], v[94:95], v[40:41]
	v_pk_add_f32 v[40:41], v[94:95], v[40:41] neg_lo:[0,1] neg_hi:[0,1]
	v_xor_b32_e32 v43, 0x80000000, v22
	v_mov_b32_e32 v42, v23
	v_pk_add_f32 v[22:23], v[100:101], v[24:25] neg_lo:[0,1] neg_hi:[0,1]
	v_xor_b32_e32 v95, 0x80000000, v40
	v_mov_b32_e32 v94, v41
	v_xor_b32_e32 v25, 0x80000000, v22
	v_mov_b32_e32 v24, v23
	v_pk_add_f32 v[100:101], v[28:29], v[32:33]
	v_pk_add_f32 v[32:33], v[28:29], v[32:33] neg_lo:[0,1] neg_hi:[0,1]
	v_mov_b32_e32 v112, v13
	v_pk_add_f32 v[12:13], v[34:35], v[14:15]
	v_pk_add_f32 v[14:15], v[34:35], v[14:15] neg_lo:[0,1] neg_hi:[0,1]
	v_pk_add_f32 v[34:35], v[30:31], v[6:7]
	v_pk_add_f32 v[6:7], v[30:31], v[6:7] neg_lo:[0,1] neg_hi:[0,1]
	v_pk_add_f32 v[114:115], v[2:3], v[16:17]
	v_pk_add_f32 v[16:17], v[2:3], v[16:17] neg_lo:[0,1] neg_hi:[0,1]
	v_pk_add_f32 v[2:3], v[4:5], v[8:9] neg_lo:[0,1] neg_hi:[0,1]
	v_xor_b32_e32 v31, 0x80000000, v6
	v_mov_b32_e32 v30, v7
	v_pk_add_f32 v[116:117], v[4:5], v[8:9]
	v_xor_b32_e32 v119, 0x80000000, v2
	v_mov_b32_e32 v118, v3
	v_pk_add_f32 v[2:3], v[20:21], v[104:105]
	v_pk_add_f32 v[104:105], v[20:21], v[104:105] neg_lo:[0,1] neg_hi:[0,1]
	v_pk_add_f32 v[120:121], v[36:37], v[102:103]
	v_pk_add_f32 v[26:27], v[36:37], v[102:103] neg_lo:[0,1] neg_hi:[0,1]
	v_pk_add_f32 v[36:37], v[38:39], v[96:97]
	v_pk_add_f32 v[40:41], v[38:39], v[96:97] neg_lo:[0,1] neg_hi:[0,1]
	v_pk_add_f32 v[96:97], v[92:93], v[90:91]
	v_pk_add_f32 v[6:7], v[92:93], v[90:91] neg_lo:[0,1] neg_hi:[0,1]
	v_pk_add_f32 v[20:21], v[44:45], v[98:99]
	v_pk_add_f32 v[90:91], v[44:45], v[98:99] neg_lo:[0,1] neg_hi:[0,1]
	v_pk_add_f32 v[92:93], v[46:47], v[94:95]
	v_pk_add_f32 v[22:23], v[46:47], v[94:95] neg_lo:[0,1] neg_hi:[0,1]
	v_pk_add_f32 v[46:47], v[106:107], v[52:53]
	v_pk_add_f32 v[38:39], v[106:107], v[52:53] neg_lo:[0,1] neg_hi:[0,1]
	v_pk_add_f32 v[52:53], v[50:51], v[24:25]
	v_pk_add_f32 v[28:29], v[50:51], v[24:25] neg_lo:[0,1] neg_hi:[0,1]
	v_pk_add_f32 v[50:51], v[100:101], v[110:111]
	v_pk_add_f32 v[44:45], v[100:101], v[110:111] neg_lo:[0,1] neg_hi:[0,1]
	v_pk_add_f32 v[98:99], v[32:33], v[112:113]
	v_pk_add_f32 v[8:9], v[32:33], v[112:113] neg_lo:[0,1] neg_hi:[0,1]
	v_pk_add_f32 v[32:33], v[12:13], v[34:35]
	v_pk_add_f32 v[100:101], v[12:13], v[34:35] neg_lo:[0,1] neg_hi:[0,1]
	v_cos_f32_e32 v12, v10
	v_sin_f32_e32 v13, v10
	v_pk_add_f32 v[94:95], v[48:49], v[42:43]
	v_pk_add_f32 v[4:5], v[48:49], v[42:43] neg_lo:[0,1] neg_hi:[0,1]
	v_pk_add_f32 v[48:49], v[108:109], v[88:89]
	v_pk_add_f32 v[102:103], v[14:15], v[30:31]
	v_pk_add_f32 v[24:25], v[14:15], v[30:31] neg_lo:[0,1] neg_hi:[0,1]
	v_pk_add_f32 v[106:107], v[16:17], v[118:119]
	v_pk_add_f32 v[10:11], v[16:17], v[118:119] neg_lo:[0,1] neg_hi:[0,1]
	v_pk_mul_f32 v[14:15], v[12:13], v[12:13]
	v_add_f32_e32 v16, v12, v12
	v_pk_add_f32 v[88:89], v[108:109], v[88:89] neg_lo:[0,1] neg_hi:[0,1]
	v_mul_f32_e32 v18, v13, v16
	v_pk_add_f32 v[16:17], v[14:15], v[14:15] op_sel:[0,1] op_sel_hi:[0,1] neg_lo:[0,1] neg_hi:[0,1]
	v_mov_b32_e32 v108, v13
	v_pk_mul_f32 v[14:15], v[12:13], v[18:19] op_sel:[1,0] op_sel_hi:[0,0] neg_lo:[1,0]
	v_pk_mul_f32 v[30:31], v[108:109], v[48:49] op_sel:[0,1] op_sel_hi:[0,0] neg_hi:[0,1]
	v_pk_fma_f32 v[14:15], v[12:13], v[16:17], v[14:15]
	v_pk_fma_f32 v[12:13], v[12:13], v[48:49], v[30:31] op_sel_hi:[0,1,1]
	v_pk_mul_f32 v[30:31], v[18:19], s[46:47] op_sel_hi:[0,1]
	v_pk_fma_f32 v[30:31], v[16:17], s[40:41], v[30:31]
	s_nop 0
	v_pk_mul_f32 v[48:49], v[30:31], v[20:21] op_sel:[1,1] op_sel_hi:[1,0] neg_hi:[0,1]
	s_nop 0
	v_pk_fma_f32 v[20:21], v[20:21], v[30:31], v[48:49] op_sel_hi:[1,0,1]
	v_pk_mul_f32 v[48:49], v[18:19], v[14:15] op_sel:[0,1] op_sel_hi:[0,0] neg_lo:[0,1]
	v_pk_mul_f32 v[108:109], v[14:15], v[32:33] op_sel:[1,1] op_sel_hi:[1,0] neg_hi:[0,1]
	v_pk_fma_f32 v[48:49], v[16:17], v[14:15], v[48:49]
	v_pk_fma_f32 v[14:15], v[14:15], v[32:33], v[108:109] op_sel_hi:[0,1,1]
	v_pk_mul_f32 v[32:33], v[18:19], v[30:31] op_sel:[0,1] op_sel_hi:[0,0] neg_lo:[0,1]
	v_pk_fma_f32 v[108:109], v[16:17], v[30:31], v[32:33]
	s_nop 0
	v_pk_mul_f32 v[30:31], v[36:37], v[108:109] op_sel:[1,1] op_sel_hi:[0,1] neg_hi:[1,0]
	v_pk_add_f32 v[34:35], v[114:115], v[116:117]
	v_pk_fma_f32 v[32:33], v[36:37], v[108:109], v[30:31] op_sel_hi:[1,0,1]
	v_pk_mul_f32 v[30:31], v[18:19], v[48:49] op_sel:[0,1] op_sel_hi:[0,0] neg_lo:[0,1]
	v_pk_fma_f32 v[110:111], v[16:17], v[48:49], v[30:31]
	v_pk_mul_f32 v[30:31], v[48:49], v[50:51] op_sel:[1,1] op_sel_hi:[1,0] neg_hi:[0,1]
	v_pk_mul_f32 v[36:37], v[18:19], v[108:109] op_sel:[0,1] op_sel_hi:[0,0] neg_lo:[0,1]
	v_pk_fma_f32 v[30:31], v[50:51], v[48:49], v[30:31] op_sel_hi:[1,0,1]
	v_pk_fma_f32 v[48:49], v[16:17], v[108:109], v[36:37]
	s_nop 0
	v_pk_mul_f32 v[36:37], v[46:47], v[48:49] op_sel:[1,1] op_sel_hi:[0,1] neg_hi:[1,0]
	s_nop 0
	v_pk_fma_f32 v[36:37], v[46:47], v[48:49], v[36:37] op_sel_hi:[1,0,1]
	v_pk_mul_f32 v[46:47], v[18:19], v[110:111] op_sel:[0,1] op_sel_hi:[0,0] neg_lo:[0,1]
	v_pk_mul_f32 v[50:51], v[110:111], v[34:35] op_sel:[1,1] op_sel_hi:[1,0] neg_hi:[0,1]
	v_pk_fma_f32 v[46:47], v[16:17], v[110:111], v[46:47]
	v_pk_fma_f32 v[34:35], v[34:35], v[110:111], v[50:51] op_sel_hi:[1,0,1]
	v_pk_mul_f32 v[50:51], v[18:19], v[48:49] op_sel:[0,1] op_sel_hi:[0,0] neg_lo:[0,1]
	s_nop 0
	v_pk_fma_f32 v[50:51], v[16:17], v[48:49], v[50:51]
	v_pk_mul_f32 v[108:109], v[18:19], v[46:47] op_sel:[0,1] op_sel_hi:[0,0] neg_lo:[0,1]
	v_pk_mul_f32 v[110:111], v[52:53], v[46:47] op_sel:[1,1] op_sel_hi:[0,1] neg_hi:[1,0]
	v_pk_fma_f32 v[108:109], v[16:17], v[46:47], v[108:109]
	v_pk_fma_f32 v[46:47], v[52:53], v[46:47], v[110:111] op_sel_hi:[1,0,1]
	v_pk_mul_f32 v[48:49], v[120:121], v[50:51] op_sel:[1,1] op_sel_hi:[0,1] neg_hi:[1,0]
	v_pk_mul_f32 v[52:53], v[18:19], v[50:51] op_sel:[0,1] op_sel_hi:[0,0] neg_lo:[0,1]
	v_pk_fma_f32 v[48:49], v[120:121], v[50:51], v[48:49] op_sel_hi:[1,0,1]
	v_pk_fma_f32 v[110:111], v[16:17], v[50:51], v[52:53]
	s_nop 0
	v_pk_mul_f32 v[50:51], v[92:93], v[110:111] op_sel:[1,1] op_sel_hi:[0,1] neg_hi:[1,0]
	v_pk_add_f32 v[42:43], v[114:115], v[116:117] neg_lo:[0,1] neg_hi:[0,1]
	v_pk_fma_f32 v[52:53], v[92:93], v[110:111], v[50:51] op_sel_hi:[1,0,1]
	v_pk_mul_f32 v[50:51], v[18:19], v[108:109] op_sel:[0,1] op_sel_hi:[0,0] neg_lo:[0,1]
	v_pk_fma_f32 v[92:93], v[16:17], v[108:109], v[50:51]
	v_pk_mul_f32 v[50:51], v[102:103], v[108:109] op_sel:[1,1] op_sel_hi:[0,1] neg_hi:[1,0]
	s_nop 0
	v_pk_fma_f32 v[50:51], v[102:103], v[108:109], v[50:51] op_sel_hi:[1,0,1]
	v_pk_mul_f32 v[102:103], v[18:19], v[110:111] op_sel:[0,1] op_sel_hi:[0,0] neg_lo:[0,1]
	v_pk_fma_f32 v[102:103], v[16:17], v[110:111], v[102:103]
	s_nop 0
	v_pk_mul_f32 v[108:109], v[96:97], v[102:103] op_sel:[1,1] op_sel_hi:[0,1] neg_hi:[1,0]
	s_nop 0
	v_pk_fma_f32 v[96:97], v[96:97], v[102:103], v[108:109] op_sel_hi:[1,0,1]
	v_pk_mul_f32 v[108:109], v[18:19], v[92:93] op_sel:[0,1] op_sel_hi:[0,0] neg_lo:[0,1]
	v_pk_mul_f32 v[110:111], v[98:99], v[92:93] op_sel:[1,1] op_sel_hi:[0,1] neg_hi:[1,0]
	v_pk_fma_f32 v[108:109], v[16:17], v[92:93], v[108:109]
	v_pk_fma_f32 v[92:93], v[98:99], v[92:93], v[110:111] op_sel_hi:[1,0,1]
	v_pk_mul_f32 v[98:99], v[18:19], v[102:103] op_sel:[0,1] op_sel_hi:[0,0] neg_lo:[0,1]
	v_pk_fma_f32 v[98:99], v[16:17], v[102:103], v[98:99]
	s_nop 0
	v_pk_mul_f32 v[102:103], v[94:95], v[98:99] op_sel:[1,1] op_sel_hi:[0,1] neg_hi:[1,0]
	s_nop 0
	v_pk_fma_f32 v[94:95], v[94:95], v[98:99], v[102:103] op_sel_hi:[1,0,1]
	v_pk_mul_f32 v[102:103], v[18:19], v[108:109] op_sel:[0,1] op_sel_hi:[0,0] neg_lo:[0,1]
	v_pk_mul_f32 v[110:111], v[106:107], v[108:109] op_sel:[1,1] op_sel_hi:[0,1] neg_hi:[1,0]
	v_pk_fma_f32 v[102:103], v[16:17], v[108:109], v[102:103]
	v_pk_fma_f32 v[106:107], v[106:107], v[108:109], v[110:111] op_sel_hi:[1,0,1]
	v_pk_mul_f32 v[108:109], v[18:19], v[98:99] op_sel:[0,1] op_sel_hi:[0,0] neg_lo:[0,1]
	v_pk_fma_f32 v[98:99], v[16:17], v[98:99], v[108:109]
	s_nop 0
	v_pk_mul_f32 v[108:109], v[104:105], v[98:99] op_sel:[1,1] op_sel_hi:[0,1] neg_hi:[1,0]
	s_nop 0
	v_pk_fma_f32 v[104:105], v[104:105], v[98:99], v[108:109] op_sel_hi:[1,0,1]
	v_pk_mul_f32 v[108:109], v[18:19], v[102:103] op_sel:[0,1] op_sel_hi:[0,0] neg_lo:[0,1]
	v_pk_mul_f32 v[110:111], v[88:89], v[102:103] op_sel:[1,1] op_sel_hi:[0,1] neg_hi:[1,0]
	v_pk_fma_f32 v[108:109], v[16:17], v[102:103], v[108:109]
	v_pk_fma_f32 v[88:89], v[88:89], v[102:103], v[110:111] op_sel_hi:[1,0,1]
	v_pk_mul_f32 v[102:103], v[18:19], v[98:99] op_sel:[0,1] op_sel_hi:[0,0] neg_lo:[0,1]
	v_pk_fma_f32 v[98:99], v[16:17], v[98:99], v[102:103]
	s_nop 0
	v_pk_mul_f32 v[102:103], v[90:91], v[98:99] op_sel:[1,1] op_sel_hi:[0,1] neg_hi:[1,0]
	s_nop 0
	v_pk_fma_f32 v[90:91], v[90:91], v[98:99], v[102:103] op_sel_hi:[1,0,1]
	v_pk_mul_f32 v[102:103], v[18:19], v[108:109] op_sel:[0,1] op_sel_hi:[0,0] neg_lo:[0,1]
	v_pk_mul_f32 v[110:111], v[100:101], v[108:109] op_sel:[1,1] op_sel_hi:[0,1] neg_hi:[1,0]
	v_pk_fma_f32 v[102:103], v[16:17], v[108:109], v[102:103]
	v_pk_fma_f32 v[100:101], v[100:101], v[108:109], v[110:111] op_sel_hi:[1,0,1]
	v_pk_mul_f32 v[108:109], v[18:19], v[98:99] op_sel:[0,1] op_sel_hi:[0,0] neg_lo:[0,1]
	v_pk_fma_f32 v[98:99], v[16:17], v[98:99], v[108:109]
	s_nop 0
	v_pk_mul_f32 v[108:109], v[40:41], v[98:99] op_sel:[1,1] op_sel_hi:[0,1] neg_hi:[1,0]
	s_nop 0
	v_pk_fma_f32 v[40:41], v[40:41], v[98:99], v[108:109] op_sel_hi:[1,0,1]
	v_pk_mul_f32 v[108:109], v[18:19], v[102:103] op_sel:[0,1] op_sel_hi:[0,0] neg_lo:[0,1]
	v_pk_mul_f32 v[110:111], v[44:45], v[102:103] op_sel:[1,1] op_sel_hi:[0,1] neg_hi:[1,0]
	v_pk_fma_f32 v[108:109], v[16:17], v[102:103], v[108:109]
	v_pk_fma_f32 v[44:45], v[44:45], v[102:103], v[110:111] op_sel_hi:[1,0,1]
	v_pk_mul_f32 v[102:103], v[18:19], v[98:99] op_sel:[0,1] op_sel_hi:[0,0] neg_lo:[0,1]
	v_pk_fma_f32 v[98:99], v[16:17], v[98:99], v[102:103]
	s_nop 0
	v_pk_mul_f32 v[102:103], v[38:39], v[98:99] op_sel:[1,1] op_sel_hi:[0,1] neg_hi:[1,0]
	s_nop 0
	v_pk_fma_f32 v[38:39], v[38:39], v[98:99], v[102:103] op_sel_hi:[1,0,1]
	v_pk_mul_f32 v[102:103], v[18:19], v[108:109] op_sel:[0,1] op_sel_hi:[0,0] neg_lo:[0,1]
	v_pk_mul_f32 v[110:111], v[42:43], v[108:109] op_sel:[1,1] op_sel_hi:[0,1] neg_hi:[1,0]
	v_pk_fma_f32 v[102:103], v[16:17], v[108:109], v[102:103]
	v_pk_fma_f32 v[42:43], v[42:43], v[108:109], v[110:111] op_sel_hi:[1,0,1]
	v_pk_mul_f32 v[108:109], v[18:19], v[98:99] op_sel:[0,1] op_sel_hi:[0,0] neg_lo:[0,1]
	v_pk_fma_f32 v[98:99], v[16:17], v[98:99], v[108:109]
	s_nop 0
	v_pk_mul_f32 v[108:109], v[26:27], v[98:99] op_sel:[1,1] op_sel_hi:[0,1] neg_hi:[1,0]
	s_nop 0
	v_pk_fma_f32 v[26:27], v[26:27], v[98:99], v[108:109] op_sel_hi:[1,0,1]
	v_pk_mul_f32 v[108:109], v[18:19], v[102:103] op_sel:[0,1] op_sel_hi:[0,0] neg_lo:[0,1]
	v_pk_mul_f32 v[110:111], v[28:29], v[102:103] op_sel:[1,1] op_sel_hi:[0,1] neg_hi:[1,0]
	v_pk_fma_f32 v[108:109], v[16:17], v[102:103], v[108:109]
	v_pk_fma_f32 v[28:29], v[28:29], v[102:103], v[110:111] op_sel_hi:[1,0,1]
	v_pk_mul_f32 v[102:103], v[18:19], v[98:99] op_sel:[0,1] op_sel_hi:[0,0] neg_lo:[0,1]
	v_pk_fma_f32 v[98:99], v[16:17], v[98:99], v[102:103]
	s_nop 0
	v_pk_mul_f32 v[102:103], v[22:23], v[98:99] op_sel:[1,1] op_sel_hi:[0,1] neg_hi:[1,0]
	s_nop 0
	v_pk_fma_f32 v[22:23], v[22:23], v[98:99], v[102:103] op_sel_hi:[1,0,1]
	v_pk_mul_f32 v[102:103], v[18:19], v[108:109] op_sel:[0,1] op_sel_hi:[0,0] neg_lo:[0,1]
	v_pk_mul_f32 v[110:111], v[24:25], v[108:109] op_sel:[1,1] op_sel_hi:[0,1] neg_hi:[1,0]
	v_pk_fma_f32 v[102:103], v[16:17], v[108:109], v[102:103]
	v_pk_fma_f32 v[24:25], v[24:25], v[108:109], v[110:111] op_sel_hi:[1,0,1]
	v_pk_mul_f32 v[108:109], v[18:19], v[98:99] op_sel:[0,1] op_sel_hi:[0,0] neg_lo:[0,1]
	v_pk_fma_f32 v[98:99], v[16:17], v[98:99], v[108:109]
	s_nop 0
	v_pk_mul_f32 v[108:109], v[6:7], v[98:99] op_sel:[1,1] op_sel_hi:[0,1] neg_hi:[1,0]
	s_nop 0
	v_pk_fma_f32 v[6:7], v[6:7], v[98:99], v[108:109] op_sel_hi:[1,0,1]
	v_pk_mul_f32 v[108:109], v[18:19], v[102:103] op_sel:[0,1] op_sel_hi:[0,0] neg_lo:[0,1]
	v_pk_mul_f32 v[110:111], v[8:9], v[102:103] op_sel:[1,1] op_sel_hi:[0,1] neg_hi:[1,0]
	v_pk_fma_f32 v[108:109], v[16:17], v[102:103], v[108:109]
	v_pk_fma_f32 v[8:9], v[8:9], v[102:103], v[110:111] op_sel_hi:[1,0,1]
	v_pk_mul_f32 v[102:103], v[18:19], v[98:99] op_sel:[0,1] op_sel_hi:[0,0] neg_lo:[0,1]
	v_pk_fma_f32 v[16:17], v[16:17], v[98:99], v[102:103]
	s_nop 0
	v_pk_mul_f32 v[98:99], v[4:5], v[16:17] op_sel:[1,1] op_sel_hi:[0,1] neg_hi:[1,0]
	s_nop 0
	v_pk_fma_f32 v[4:5], v[4:5], v[16:17], v[98:99] op_sel_hi:[1,0,1]
	v_pk_mul_f32 v[16:17], v[10:11], v[108:109] op_sel:[1,1] op_sel_hi:[0,1] neg_hi:[1,0]
	s_nop 0
	v_pk_fma_f32 v[10:11], v[10:11], v[108:109], v[16:17] op_sel_hi:[1,0,1]
	ds_write_b64 v19, v[2:3]
	ds_write_b64 v54, v[104:105]
	ds_write_b64 v55, v[48:49] offset:256
	ds_write_b64 v56, v[26:27] offset:256
	ds_write_b64 v57, v[32:33] offset:512
	ds_write_b64 v58, v[40:41] offset:512
	ds_write_b64 v59, v[96:97] offset:768
	ds_write_b64 v60, v[6:7] offset:768
	ds_write_b64 v61, v[20:21] offset:1024
	ds_write_b64 v62, v[90:91] offset:1024
	ds_write_b64 v63, v[52:53] offset:1280
	ds_write_b64 v64, v[22:23] offset:1280
	ds_write_b64 v65, v[36:37] offset:1536
	ds_write_b64 v66, v[38:39] offset:1536
	ds_write_b64 v67, v[94:95] offset:1792
	ds_write_b64 v71, v[4:5] offset:1792
	ds_write_b64 v72, v[12:13] offset:2048
	ds_write_b64 v73, v[88:89] offset:2048
	ds_write_b64 v74, v[46:47] offset:2304
	ds_write_b64 v75, v[28:29] offset:2304
	ds_write_b64 v76, v[30:31] offset:2560
	ds_write_b64 v77, v[44:45] offset:2560
	ds_write_b64 v78, v[92:93] offset:2816
	ds_write_b64 v79, v[8:9] offset:2816
	ds_write_b64 v80, v[14:15] offset:3072
	ds_write_b64 v81, v[100:101] offset:3072
	ds_write_b64 v82, v[50:51] offset:3328
	ds_write_b64 v83, v[24:25] offset:3328
	ds_write_b64 v84, v[34:35] offset:3584
	ds_write_b64 v85, v[42:43] offset:3584
	ds_write_b64 v86, v[106:107] offset:3840
	ds_write_b64 v87, v[10:11] offset:3840
	v_mov_b32_e32 v2, v146
	s_waitcnt lgkmcnt(0)
	s_barrier
	s_nop 0
	v_lshlrev_b32_e32 v34, 4, v2
	v_lshrrev_b32_e32 v35, 1, v2
	v_bitop3_b32 v3, v35, v34, 16 bitop3:0x6c
	v_lshl_add_u32 v26, v3, 3, 16
	v_bitop3_b32 v3, v35, 1, 15 bitop3:0x6c
	v_bitop3_b32 v11, v35, 5, 15 bitop3:0x6c
	v_bitop3_b32 v19, v35, 9, 15 bitop3:0x6c
	v_lshlrev_b32_e32 v37, 3, v3
	v_bitop3_b32 v3, v35, 2, 15 bitop3:0x6c
	v_lshlrev_b32_e32 v45, 3, v11
	v_bitop3_b32 v11, v35, 6, 15 bitop3:0x6c
	v_lshlrev_b32_e32 v49, 3, v19
	v_bitop3_b32 v19, v35, 10, 15 bitop3:0x6c
	v_bitop3_b32 v29, v35, 14, 15 bitop3:0x6c
	v_add_u32_e32 v34, 0x2000, v34
	v_bfe_u32 v2, v2, 1, 4
	v_lshlrev_b32_e32 v38, 3, v3
	v_bitop3_b32 v3, v35, 3, 15 bitop3:0x6c
	v_bitop3_b32 v10, v35, 4, 15 bitop3:0x6c
	v_lshlrev_b32_e32 v46, 3, v11
	v_bitop3_b32 v11, v35, 7, 15 bitop3:0x6c
	v_bitop3_b32 v18, v35, 8, 15 bitop3:0x6c
	v_lshlrev_b32_e32 v50, 3, v19
	v_bitop3_b32 v19, v35, 11, 15 bitop3:0x6c
	v_bitop3_b32 v27, v35, 12, 15 bitop3:0x6c
	v_bitop3_b32 v28, v35, 13, 15 bitop3:0x6c
	v_lshlrev_b32_e32 v54, 3, v29
	v_bitop3_b32 v29, v35, 15, v35 bitop3:0xc
	v_bitop3_b32 v34, v34, v35, 16 bitop3:0x78
	v_lshlrev_b32_e32 v36, 3, v2
	v_lshlrev_b32_e32 v39, 3, v3
	v_lshlrev_b32_e32 v44, 3, v10
	v_lshlrev_b32_e32 v47, 3, v11
	v_lshlrev_b32_e32 v48, 3, v18
	v_lshlrev_b32_e32 v51, 3, v19
	v_lshlrev_b32_e32 v52, 3, v27
	v_lshlrev_b32_e32 v53, 3, v28
	v_lshlrev_b32_e32 v55, 3, v29
	v_lshl_add_u32 v34, v34, 3, 16
	v_add_u32_e32 v2, v26, v36
	v_add_u32_e32 v4, v26, v37
	v_add_u32_e32 v6, v26, v38
	v_add_u32_e32 v8, v26, v39
	v_add_u32_e32 v10, v26, v44
	v_add_u32_e32 v12, v26, v45
	v_add_u32_e32 v14, v26, v46
	v_add_u32_e32 v16, v26, v47
	v_add_u32_e32 v18, v26, v48
	v_add_u32_e32 v20, v26, v49
	v_add_u32_e32 v22, v26, v50
	v_add_u32_e32 v24, v26, v51
	v_add_u32_e32 v27, v26, v52
	v_add_u32_e32 v28, v26, v53
	v_add_u32_e32 v30, v26, v54
	v_add_u32_e32 v32, v26, v55
	v_add_u32_e32 v35, v34, v36
	v_add_u32_e32 v40, v34, v37
	v_add_u32_e32 v41, v34, v38
	v_add_u32_e32 v42, v34, v39
	ds_read_b64 v[2:3], v2
	ds_read_b64 v[4:5], v4
	ds_read_b64 v[6:7], v6
	ds_read_b64 v[8:9], v8
	ds_read_b64 v[10:11], v10
	ds_read_b64 v[12:13], v12
	ds_read_b64 v[14:15], v14
	ds_read_b64 v[16:17], v16
	ds_read_b64 v[18:19], v18
	ds_read_b64 v[20:21], v20
	ds_read_b64 v[22:23], v22
	ds_read_b64 v[24:25], v24
	ds_read_b64 v[26:27], v27
	ds_read_b64 v[28:29], v28
	ds_read_b64 v[30:31], v30
	ds_read_b64 v[32:33], v32
	ds_read_b64 v[36:37], v35
	ds_read_b64 v[38:39], v40
	ds_read_b64 v[40:41], v41
	ds_read_b64 v[42:43], v42
	v_add_u32_e32 v35, v34, v44
	v_add_u32_e32 v44, v34, v45
	v_add_u32_e32 v45, v34, v46
	v_add_u32_e32 v46, v34, v47
	ds_read_b64 v[72:73], v35
	ds_read_b64 v[74:75], v44
	ds_read_b64 v[76:77], v45
	ds_read_b64 v[78:79], v46
	v_add_u32_e32 v35, v34, v48
	v_add_u32_e32 v44, v34, v49
	v_add_u32_e32 v45, v34, v50
	v_add_u32_e32 v46, v34, v51
	ds_read_b64 v[80:81], v35
	ds_read_b64 v[82:83], v44
	ds_read_b64 v[84:85], v45
	ds_read_b64 v[86:87], v46
	v_add_u32_e32 v35, v34, v52
	v_add_u32_e32 v44, v34, v53
	v_add_u32_e32 v45, v34, v54
	v_add_u32_e32 v34, v34, v55
	ds_read_b64 v[88:89], v35
	ds_read_b64 v[90:91], v44
	ds_read_b64 v[92:93], v45
	ds_read_b64 v[94:95], v34
	s_waitcnt lgkmcnt(14)
	v_pk_add_f32 v[34:35], v[2:3], v[18:19]
	v_pk_add_f32 v[2:3], v[2:3], v[18:19] neg_lo:[0,1] neg_hi:[0,1]
	v_pk_add_f32 v[18:19], v[4:5], v[20:21]
	v_pk_add_f32 v[4:5], v[4:5], v[20:21] neg_lo:[0,1] neg_hi:[0,1]
	s_nop 0
	v_pk_mul_f32 v[20:21], v[4:5], s[54:55] op_sel:[1,0] op_sel_hi:[0,0] neg_hi:[1,0]
	s_nop 0
	v_pk_fma_f32 v[4:5], v[4:5], s[52:53], v[20:21] op_sel_hi:[1,0,1]
	v_pk_add_f32 v[20:21], v[6:7], v[22:23]
	v_pk_add_f32 v[6:7], v[6:7], v[22:23] neg_lo:[0,1] neg_hi:[0,1]
	s_nop 0
	v_pk_mul_f32 v[22:23], v[6:7], s[60:61] op_sel:[1,0] op_sel_hi:[0,0] neg_hi:[1,0]
	s_nop 0
	v_pk_fma_f32 v[6:7], v[6:7], s[60:61], v[22:23] op_sel_hi:[1,0,1]
	v_pk_add_f32 v[22:23], v[8:9], v[24:25]
	v_pk_add_f32 v[8:9], v[8:9], v[24:25] neg_lo:[0,1] neg_hi:[0,1]
	s_nop 0
	v_pk_mul_f32 v[24:25], v[8:9], s[52:53] op_sel:[1,0] op_sel_hi:[0,0] neg_hi:[1,0]
	s_nop 0
	v_pk_fma_f32 v[8:9], v[8:9], s[54:55], v[24:25] op_sel_hi:[1,0,1]
	v_pk_add_f32 v[24:25], v[10:11], v[26:27]
	v_pk_add_f32 v[10:11], v[10:11], v[26:27] neg_lo:[0,1] neg_hi:[0,1]
	s_nop 0
	v_xor_b32_e32 v27, 0x80000000, v10
	v_mov_b32_e32 v26, v11
	v_pk_add_f32 v[10:11], v[12:13], v[28:29]
	v_pk_add_f32 v[12:13], v[12:13], v[28:29] neg_lo:[0,1] neg_hi:[0,1]
	s_nop 0
	v_pk_mul_f32 v[28:29], v[12:13], s[54:55] op_sel_hi:[1,0]
	v_xor_b32_e32 v45, 0x80000000, v12
	v_mov_b32_e32 v44, v13
	v_pk_fma_f32 v[12:13], v[44:45], s[52:53], v[28:29] op_sel_hi:[1,0,1] neg_lo:[0,0,1] neg_hi:[0,0,1]
	v_pk_add_f32 v[28:29], v[14:15], v[30:31]
	v_pk_add_f32 v[14:15], v[14:15], v[30:31] neg_lo:[0,1] neg_hi:[0,1]
	s_nop 0
	v_pk_mul_f32 v[30:31], v[14:15], s[60:61] op_sel_hi:[1,0]
	v_xor_b32_e32 v45, 0x80000000, v14
	v_mov_b32_e32 v44, v15
	v_pk_fma_f32 v[14:15], v[44:45], s[60:61], v[30:31] op_sel_hi:[1,0,1] neg_lo:[0,0,1] neg_hi:[0,0,1]
	v_pk_add_f32 v[30:31], v[16:17], v[32:33]
	v_pk_add_f32 v[16:17], v[16:17], v[32:33] neg_lo:[0,1] neg_hi:[0,1]
	s_nop 0
	v_pk_mul_f32 v[32:33], v[16:17], s[52:53] op_sel_hi:[1,0]
	v_xor_b32_e32 v45, 0x80000000, v16
	v_mov_b32_e32 v44, v17
	v_pk_fma_f32 v[16:17], v[44:45], s[54:55], v[32:33] op_sel_hi:[1,0,1] neg_lo:[0,0,1] neg_hi:[0,0,1]
	v_pk_add_f32 v[32:33], v[34:35], v[24:25]
	v_pk_add_f32 v[24:25], v[34:35], v[24:25] neg_lo:[0,1] neg_hi:[0,1]
	v_pk_add_f32 v[34:35], v[18:19], v[10:11]
	v_pk_add_f32 v[10:11], v[18:19], v[10:11] neg_lo:[0,1] neg_hi:[0,1]
	s_nop 0
	v_pk_mul_f32 v[18:19], v[10:11], s[60:61] op_sel:[1,0] op_sel_hi:[0,0] neg_hi:[1,0]
	s_nop 0
	v_pk_fma_f32 v[10:11], v[10:11], s[60:61], v[18:19] op_sel_hi:[1,0,1]
	v_pk_add_f32 v[18:19], v[20:21], v[28:29]
	v_pk_add_f32 v[20:21], v[20:21], v[28:29] neg_lo:[0,1] neg_hi:[0,1]
	s_nop 0
	v_xor_b32_e32 v29, 0x80000000, v20
	v_mov_b32_e32 v28, v21
	v_pk_add_f32 v[20:21], v[22:23], v[30:31]
	v_pk_add_f32 v[22:23], v[22:23], v[30:31] neg_lo:[0,1] neg_hi:[0,1]
	s_nop 0
	v_pk_mul_f32 v[30:31], v[22:23], s[60:61] op_sel_hi:[1,0]
	v_xor_b32_e32 v45, 0x80000000, v22
	v_mov_b32_e32 v44, v23
	v_pk_fma_f32 v[22:23], v[44:45], s[60:61], v[30:31] op_sel_hi:[1,0,1] neg_lo:[0,0,1] neg_hi:[0,0,1]
	v_pk_add_f32 v[30:31], v[2:3], v[26:27]
	v_pk_add_f32 v[2:3], v[2:3], v[26:27] neg_lo:[0,1] neg_hi:[0,1]
	v_pk_add_f32 v[26:27], v[4:5], v[12:13]
	v_pk_add_f32 v[4:5], v[4:5], v[12:13] neg_lo:[0,1] neg_hi:[0,1]
	s_nop 0
	v_pk_mul_f32 v[12:13], v[4:5], s[60:61] op_sel:[1,0] op_sel_hi:[0,0] neg_hi:[1,0]
	s_nop 0
	v_pk_fma_f32 v[4:5], v[4:5], s[60:61], v[12:13] op_sel_hi:[1,0,1]
	v_pk_add_f32 v[12:13], v[6:7], v[14:15]
	v_pk_add_f32 v[6:7], v[6:7], v[14:15] neg_lo:[0,1] neg_hi:[0,1]
	s_nop 0
	v_xor_b32_e32 v15, 0x80000000, v6
	v_mov_b32_e32 v14, v7
	v_pk_add_f32 v[6:7], v[8:9], v[16:17]
	v_pk_add_f32 v[8:9], v[8:9], v[16:17] neg_lo:[0,1] neg_hi:[0,1]
	s_nop 0
	v_pk_mul_f32 v[16:17], v[8:9], s[60:61] op_sel_hi:[1,0]
	s_nop 0
	v_pk_fma_f32 v[8:9], v[8:9], s[60:61], v[16:17] op_sel:[1,0,0] op_sel_hi:[0,0,1] neg_lo:[0,0,1] neg_hi:[1,0,1]
	v_pk_add_f32 v[16:17], v[32:33], v[18:19]
	v_pk_add_f32 v[18:19], v[32:33], v[18:19] neg_lo:[0,1] neg_hi:[0,1]
	v_pk_add_f32 v[32:33], v[34:35], v[20:21]
	v_pk_add_f32 v[20:21], v[34:35], v[20:21] neg_lo:[0,1] neg_hi:[0,1]
	v_pk_add_f32 v[66:67], v[16:17], v[32:33]
	v_xor_b32_e32 v35, 0x80000000, v20
	v_mov_b32_e32 v34, v21
	v_pk_add_f32 v[20:21], v[24:25], v[28:29]
	v_pk_add_f32 v[24:25], v[24:25], v[28:29] neg_lo:[0,1] neg_hi:[0,1]
	v_pk_add_f32 v[28:29], v[10:11], v[22:23]
	v_pk_add_f32 v[10:11], v[10:11], v[22:23] neg_lo:[0,1] neg_hi:[0,1]
	v_pk_add_f32 v[58:59], v[20:21], v[28:29]
	v_xor_b32_e32 v23, 0x80000000, v10
	v_mov_b32_e32 v22, v11
	v_pk_add_f32 v[10:11], v[30:31], v[12:13]
	v_pk_add_f32 v[12:13], v[30:31], v[12:13] neg_lo:[0,1] neg_hi:[0,1]
	v_pk_add_f32 v[30:31], v[26:27], v[6:7]
	v_pk_add_f32 v[6:7], v[26:27], v[6:7] neg_lo:[0,1] neg_hi:[0,1]
	v_pk_add_f32 v[54:55], v[24:25], v[22:23]
	v_xor_b32_e32 v27, 0x80000000, v6
	v_mov_b32_e32 v26, v7
	v_pk_add_f32 v[6:7], v[2:3], v[14:15]
	v_pk_add_f32 v[2:3], v[2:3], v[14:15] neg_lo:[0,1] neg_hi:[0,1]
	v_pk_add_f32 v[14:15], v[4:5], v[8:9]
	v_pk_add_f32 v[4:5], v[4:5], v[8:9] neg_lo:[0,1] neg_hi:[0,1]
	v_pk_add_f32 v[52:53], v[24:25], v[22:23] neg_lo:[0,1] neg_hi:[0,1]
	v_pk_add_f32 v[50:51], v[10:11], v[30:31]
	v_pk_add_f32 v[48:49], v[10:11], v[30:31] neg_lo:[0,1] neg_hi:[0,1]
	v_pk_add_f32 v[46:47], v[12:13], v[26:27]
	v_pk_add_f32 v[44:45], v[12:13], v[26:27] neg_lo:[0,1] neg_hi:[0,1]
	v_pk_add_f32 v[30:31], v[2:3], v[4:5] op_sel:[0,1] op_sel_hi:[1,0] neg_hi:[0,1]
	v_pk_add_f32 v[26:27], v[2:3], v[4:5] op_sel:[0,1] op_sel_hi:[1,0] neg_lo:[0,1]
	s_waitcnt lgkmcnt(6)
	v_pk_add_f32 v[8:9], v[38:39], v[82:83] neg_lo:[0,1] neg_hi:[0,1]
	s_waitcnt lgkmcnt(2)
	v_pk_add_f32 v[24:25], v[74:75], v[90:91] neg_lo:[0,1] neg_hi:[0,1]
	v_pk_add_f32 v[56:57], v[20:21], v[28:29] neg_lo:[0,1] neg_hi:[0,1]
	v_pk_add_f32 v[2:3], v[36:37], v[80:81]
	v_pk_add_f32 v[4:5], v[36:37], v[80:81] neg_lo:[0,1] neg_hi:[0,1]
	v_pk_mul_f32 v[28:29], v[24:25], s[54:55] op_sel_hi:[1,0]
	v_pk_add_f32 v[64:65], v[16:17], v[32:33] neg_lo:[0,1] neg_hi:[0,1]
	v_pk_mul_f32 v[10:11], v[8:9], s[54:55] op_sel:[1,0] op_sel_hi:[0,0] neg_hi:[1,0]
	v_pk_add_f32 v[12:13], v[40:41], v[84:85] neg_lo:[0,1] neg_hi:[0,1]
	v_pk_add_f32 v[16:17], v[42:43], v[86:87] neg_lo:[0,1] neg_hi:[0,1]
	v_pk_fma_f32 v[24:25], v[24:25], s[52:53], v[28:29] op_sel:[1,0,0] op_sel_hi:[0,0,1] neg_lo:[0,0,1] neg_hi:[1,0,1]
	s_waitcnt lgkmcnt(1)
	v_pk_add_f32 v[36:37], v[76:77], v[92:93] neg_lo:[0,1] neg_hi:[0,1]
	v_pk_add_f32 v[62:63], v[18:19], v[34:35]
	v_pk_add_f32 v[60:61], v[18:19], v[34:35] neg_lo:[0,1] neg_hi:[0,1]
	v_pk_add_f32 v[34:35], v[6:7], v[14:15]
	v_pk_add_f32 v[32:33], v[6:7], v[14:15] neg_lo:[0,1] neg_hi:[0,1]
	v_pk_add_f32 v[6:7], v[38:39], v[82:83]
	v_pk_fma_f32 v[8:9], v[8:9], s[52:53], v[10:11] op_sel_hi:[1,0,1]
	v_pk_add_f32 v[10:11], v[40:41], v[84:85]
	v_pk_mul_f32 v[38:39], v[36:37], s[60:61] op_sel_hi:[1,0]
	v_pk_mul_f32 v[14:15], v[12:13], s[60:61] op_sel:[1,0] op_sel_hi:[0,0] neg_hi:[1,0]
	v_pk_mul_f32 v[18:19], v[16:17], s[52:53] op_sel:[1,0] op_sel_hi:[0,0] neg_hi:[1,0]
	v_pk_add_f32 v[20:21], v[72:73], v[88:89] neg_lo:[0,1] neg_hi:[0,1]
	v_pk_fma_f32 v[36:37], v[36:37], s[60:61], v[38:39] op_sel:[1,0,0] op_sel_hi:[0,0,1] neg_lo:[0,0,1] neg_hi:[1,0,1]
	s_waitcnt lgkmcnt(0)
	v_pk_add_f32 v[40:41], v[78:79], v[94:95] neg_lo:[0,1] neg_hi:[0,1]
	v_pk_fma_f32 v[12:13], v[12:13], s[60:61], v[14:15] op_sel_hi:[1,0,1]
	v_pk_add_f32 v[14:15], v[42:43], v[86:87]
	v_pk_fma_f32 v[16:17], v[16:17], s[54:55], v[18:19] op_sel_hi:[1,0,1]
	v_pk_add_f32 v[18:19], v[72:73], v[88:89]
	v_xor_b32_e32 v23, 0x80000000, v20
	v_mov_b32_e32 v22, v21
	v_pk_add_f32 v[20:21], v[74:75], v[90:91]
	v_pk_mul_f32 v[42:43], v[40:41], s[52:53] op_sel_hi:[1,0]
	v_xor_b32_e32 v73, 0x80000000, v40
	v_mov_b32_e32 v72, v41
	v_pk_fma_f32 v[40:41], v[72:73], s[54:55], v[42:43] op_sel_hi:[1,0,1] neg_lo:[0,0,1] neg_hi:[0,0,1]
	v_pk_add_f32 v[42:43], v[2:3], v[18:19]
	v_pk_add_f32 v[2:3], v[2:3], v[18:19] neg_lo:[0,1] neg_hi:[0,1]
	v_pk_add_f32 v[18:19], v[6:7], v[20:21]
	v_pk_add_f32 v[6:7], v[6:7], v[20:21] neg_lo:[0,1] neg_hi:[0,1]
	v_pk_add_f32 v[28:29], v[76:77], v[92:93]
	v_pk_mul_f32 v[20:21], v[6:7], s[60:61] op_sel:[1,0] op_sel_hi:[0,0] neg_hi:[1,0]
	v_pk_add_f32 v[38:39], v[78:79], v[94:95]
	v_pk_fma_f32 v[6:7], v[6:7], s[60:61], v[20:21] op_sel_hi:[1,0,1]
	v_pk_add_f32 v[20:21], v[10:11], v[28:29]
	v_pk_add_f32 v[10:11], v[10:11], v[28:29] neg_lo:[0,1] neg_hi:[0,1]
	s_nop 0
	v_xor_b32_e32 v29, 0x80000000, v10
	v_mov_b32_e32 v28, v11
	v_pk_add_f32 v[10:11], v[14:15], v[38:39]
	v_pk_add_f32 v[14:15], v[14:15], v[38:39] neg_lo:[0,1] neg_hi:[0,1]
	s_nop 0
	v_pk_mul_f32 v[38:39], v[14:15], s[60:61] op_sel_hi:[1,0]
	v_xor_b32_e32 v73, 0x80000000, v14
	v_mov_b32_e32 v72, v15
	v_pk_fma_f32 v[14:15], v[72:73], s[60:61], v[38:39] op_sel_hi:[1,0,1] neg_lo:[0,0,1] neg_hi:[0,0,1]
	v_pk_add_f32 v[38:39], v[4:5], v[22:23]
	v_pk_add_f32 v[4:5], v[4:5], v[22:23] neg_lo:[0,1] neg_hi:[0,1]
	v_pk_add_f32 v[22:23], v[8:9], v[24:25]
	v_pk_add_f32 v[8:9], v[8:9], v[24:25] neg_lo:[0,1] neg_hi:[0,1]
	s_nop 0
	v_pk_mul_f32 v[24:25], v[8:9], s[60:61] op_sel:[1,0] op_sel_hi:[0,0] neg_hi:[1,0]
	s_nop 0
	v_pk_fma_f32 v[8:9], v[8:9], s[60:61], v[24:25] op_sel_hi:[1,0,1]
	v_pk_add_f32 v[24:25], v[12:13], v[36:37]
	v_pk_add_f32 v[12:13], v[12:13], v[36:37] neg_lo:[0,1] neg_hi:[0,1]
	v_pk_add_f32 v[74:75], v[38:39], v[24:25] neg_lo:[0,1] neg_hi:[0,1]
	v_xor_b32_e32 v37, 0x80000000, v12
	v_mov_b32_e32 v36, v13
	v_pk_add_f32 v[12:13], v[16:17], v[40:41]
	v_pk_add_f32 v[16:17], v[16:17], v[40:41] neg_lo:[0,1] neg_hi:[0,1]
	v_pk_add_f32 v[76:77], v[22:23], v[12:13]
	v_pk_mul_f32 v[40:41], v[16:17], s[60:61] op_sel_hi:[1,0]
	s_nop 0
	v_pk_fma_f32 v[16:17], v[16:17], s[60:61], v[40:41] op_sel:[1,0,0] op_sel_hi:[0,0,1] neg_lo:[0,0,1] neg_hi:[1,0,1]
	v_pk_add_f32 v[72:73], v[18:19], v[10:11]
	v_pk_add_f32 v[10:11], v[18:19], v[10:11] neg_lo:[0,1] neg_hi:[0,1]
	v_pk_add_f32 v[12:13], v[22:23], v[12:13] neg_lo:[0,1] neg_hi:[0,1]
	v_xor_b32_e32 v19, 0x80000000, v10
	v_mov_b32_e32 v18, v11
	v_pk_add_f32 v[10:11], v[2:3], v[28:29]
	v_pk_add_f32 v[2:3], v[2:3], v[28:29] neg_lo:[0,1] neg_hi:[0,1]
	v_pk_add_f32 v[28:29], v[6:7], v[14:15]
	v_pk_add_f32 v[6:7], v[6:7], v[14:15] neg_lo:[0,1] neg_hi:[0,1]
	v_pk_add_f32 v[22:23], v[10:11], v[28:29] neg_lo:[0,1] neg_hi:[0,1]
	v_xor_b32_e32 v15, 0x80000000, v6
	v_mov_b32_e32 v14, v7
	v_pk_add_f32 v[6:7], v[38:39], v[24:25]
	v_pk_add_f32 v[24:25], v[10:11], v[28:29]
	v_mov_b32_e32 v28, v146
	v_pk_add_f32 v[40:41], v[42:43], v[20:21]
	v_pk_add_f32 v[20:21], v[42:43], v[20:21] neg_lo:[0,1] neg_hi:[0,1]
	v_lshlrev_b32_e32 v71, 4, v28
	v_lshrrev_b32_e32 v29, 1, v28
	v_pk_add_f32 v[42:43], v[40:41], v[72:73]
	v_pk_add_f32 v[40:41], v[40:41], v[72:73] neg_lo:[0,1] neg_hi:[0,1]
	v_bfe_u32 v28, v28, 1, 4
	v_bitop3_b32 v72, v29, v71, 16 bitop3:0x6c
	v_lshl_add_u32 v72, v72, 3, 16
	v_lshlrev_b32_e32 v28, 3, v28
	v_add_u32_e32 v73, v72, v28
	ds_write_b64 v73, v[66:67]
	v_bitop3_b32 v73, v29, 1, 15 bitop3:0x6c
	v_xor_b32_e32 v79, 0x80000000, v12
	v_mov_b32_e32 v78, v13
	v_lshlrev_b32_e32 v73, 3, v73
	v_pk_add_f32 v[12:13], v[74:75], v[78:79]
	v_pk_add_f32 v[10:11], v[74:75], v[78:79] neg_lo:[0,1] neg_hi:[0,1]
	v_add_u32_e32 v74, v72, v73
	ds_write_b64 v74, v[64:65]
	v_bitop3_b32 v74, v29, 2, 15 bitop3:0x6c
	v_lshlrev_b32_e32 v74, 3, v74
	v_add_u32_e32 v75, v72, v74
	ds_write_b64 v75, v[62:63]
	v_bitop3_b32 v75, v29, 3, 15 bitop3:0x6c
	v_lshlrev_b32_e32 v75, 3, v75
	v_pk_add_f32 v[80:81], v[4:5], v[36:37]
	v_pk_add_f32 v[82:83], v[4:5], v[36:37] neg_lo:[0,1] neg_hi:[0,1]
	v_pk_add_f32 v[4:5], v[8:9], v[16:17]
	v_pk_add_f32 v[8:9], v[8:9], v[16:17] neg_lo:[0,1] neg_hi:[0,1]
	v_pk_add_f32 v[38:39], v[20:21], v[18:19]
	v_pk_add_f32 v[36:37], v[20:21], v[18:19] neg_lo:[0,1] neg_hi:[0,1]
	v_pk_add_f32 v[20:21], v[2:3], v[14:15]
	v_pk_add_f32 v[18:19], v[2:3], v[14:15] neg_lo:[0,1] neg_hi:[0,1]
	v_pk_add_f32 v[16:17], v[6:7], v[76:77]
	v_pk_add_f32 v[14:15], v[6:7], v[76:77] neg_lo:[0,1] neg_hi:[0,1]
	v_add_u32_e32 v76, v72, v75
	ds_write_b64 v76, v[60:61]
	v_bitop3_b32 v76, v29, 4, 15 bitop3:0x6c
	v_lshlrev_b32_e32 v76, 3, v76
	v_add_u32_e32 v77, v72, v76
	ds_write_b64 v77, v[58:59]
	v_bitop3_b32 v77, v29, 5, 15 bitop3:0x6c
	v_lshlrev_b32_e32 v77, 3, v77
	v_add_u32_e32 v78, v72, v77
	ds_write_b64 v78, v[56:57]
	v_bitop3_b32 v78, v29, 6, 15 bitop3:0x6c
	v_lshlrev_b32_e32 v78, 3, v78
	v_add_u32_e32 v79, v72, v78
	ds_write_b64 v79, v[54:55]
	v_bitop3_b32 v79, v29, 7, 15 bitop3:0x6c
	v_lshlrev_b32_e32 v79, 3, v79
	v_xor_b32_e32 v85, 0x80000000, v8
	v_mov_b32_e32 v84, v9
	v_pk_add_f32 v[8:9], v[80:81], v[4:5]
	v_pk_add_f32 v[6:7], v[80:81], v[4:5] neg_lo:[0,1] neg_hi:[0,1]
	v_add_u32_e32 v80, v72, v79
	ds_write_b64 v80, v[52:53]
	v_bitop3_b32 v80, v29, 8, 15 bitop3:0x6c
	v_lshlrev_b32_e32 v80, 3, v80
	v_add_u32_e32 v81, v72, v80
	ds_write_b64 v81, v[50:51]
	v_bitop3_b32 v81, v29, 9, 15 bitop3:0x6c
	v_lshlrev_b32_e32 v81, 3, v81
	v_pk_add_f32 v[4:5], v[82:83], v[84:85]
	v_pk_add_f32 v[2:3], v[82:83], v[84:85] neg_lo:[0,1] neg_hi:[0,1]
	v_add_u32_e32 v82, v72, v81
	ds_write_b64 v82, v[48:49]
	v_bitop3_b32 v82, v29, 10, 15 bitop3:0x6c
	v_lshlrev_b32_e32 v82, 3, v82
	v_add_u32_e32 v83, v72, v82
	ds_write_b64 v83, v[46:47]
	v_bitop3_b32 v83, v29, 11, 15 bitop3:0x6c
	v_lshlrev_b32_e32 v83, 3, v83
	v_add_u32_e32 v84, v72, v83
	ds_write_b64 v84, v[44:45]
	v_bitop3_b32 v84, v29, 12, 15 bitop3:0x6c
	v_lshlrev_b32_e32 v84, 3, v84
	v_add_u32_e32 v85, v72, v84
	ds_write_b64 v85, v[34:35]
	v_bitop3_b32 v85, v29, 13, 15 bitop3:0x6c
	v_lshlrev_b32_e32 v85, 3, v85
	v_add_u32_e32 v86, v72, v85
	ds_write_b64 v86, v[32:33]
	v_bitop3_b32 v86, v29, 14, 15 bitop3:0x6c
	v_lshlrev_b32_e32 v86, 3, v86
	v_add_u32_e32 v87, v72, v86
	v_add_u32_e32 v88, 0x2000, v71
	ds_write_b64 v87, v[30:31]
	v_bitop3_b32 v87, v29, 15, v29 bitop3:0xc
	v_bitop3_b32 v29, v88, v29, 16 bitop3:0x78
	v_lshlrev_b32_e32 v87, 3, v87
	v_lshl_add_u32 v29, v29, 3, 16
	v_add_u32_e32 v72, v72, v87
	v_add_u32_e32 v28, v29, v28
	ds_write_b64 v72, v[26:27]
	ds_write_b64 v28, v[42:43]
	v_add_u32_e32 v28, v29, v73
	ds_write_b64 v28, v[40:41]
	v_add_u32_e32 v28, v29, v74
	ds_write_b64 v28, v[38:39]
	v_add_u32_e32 v28, v29, v75
	ds_write_b64 v28, v[36:37]
	v_add_u32_e32 v28, v29, v76
	ds_write_b64 v28, v[24:25]
	v_add_u32_e32 v28, v29, v77
	ds_write_b64 v28, v[22:23]
	v_add_u32_e32 v28, v29, v78
	ds_write_b64 v28, v[20:21]
	v_add_u32_e32 v28, v29, v79
	ds_write_b64 v28, v[18:19]
	v_add_u32_e32 v28, v29, v80
	ds_write_b64 v28, v[16:17]
	v_add_u32_e32 v28, v29, v81
	ds_write_b64 v28, v[14:15]
	v_add_u32_e32 v28, v29, v82
	v_or_b32_e32 v72, 1, v71
	ds_write_b64 v28, v[12:13]
	v_add_u32_e32 v28, v29, v83
	v_bfrev_b32_e32 v72, v72
	ds_write_b64 v28, v[10:11]
	v_add_u32_e32 v28, v29, v84
	v_lshrrev_b32_e32 v72, 18, v72
	ds_write_b64 v28, v[8:9]
	v_add_u32_e32 v28, v29, v85
	v_sub_u32_e32 v72, 0, v72
	ds_write_b64 v28, v[6:7]
	v_add_u32_e32 v28, v29, v86
	v_and_b32_e32 v72, 0x3fff, v72
	ds_write_b64 v28, v[4:5]
	v_add_u32_e32 v28, v29, v87
	v_bfrev_b32_e32 v72, v72
	ds_write_b64 v28, v[2:3]
	v_lshl_add_u64 v[28:29], v[0:1], 2, s[0:1]
	v_bfrev_b32_e32 v0, v71
	v_lshrrev_b32_e32 v73, 18, v72
	v_lshrrev_b32_e32 v72, 23, v72
	v_lshrrev_b32_e32 v0, 18, v0
	v_bitop3_b32 v72, v72, v73, 31 bitop3:0x6c
	v_or_b32_e32 v73, 2, v71
	v_sub_u32_e32 v0, 0, v0
	v_bfrev_b32_e32 v73, v73
	v_and_b32_e32 v0, 0x3fff, v0
	v_lshrrev_b32_e32 v73, 18, v73
	v_bfrev_b32_e32 v0, v0
	v_sub_u32_e32 v73, 0, v73
	v_lshrrev_b32_e32 v1, 18, v0
	v_lshrrev_b32_e32 v0, 23, v0
	v_and_b32_e32 v74, 0x3fff, v73
	v_bitop3_b32 v0, v0, v1, 31 bitop3:0x6c
	v_bfrev_b32_e32 v74, v74
	v_and_b32_e32 v73, 0x1fff, v73
	v_lshl_add_u32 v0, v0, 3, 16
	v_lshrrev_b32_e32 v75, 18, v74
	v_lshrrev_b32_e32 v74, 23, v74
	v_bfrev_b32_e32 v73, v73
	s_waitcnt lgkmcnt(0)
	s_barrier
	ds_read_b64 v[0:1], v0
	v_bitop3_b32 v74, v74, v75, 31 bitop3:0x6c
	v_lshrrev_b32_e32 v75, 18, v73
	v_lshrrev_b32_e32 v73, 23, v73
	v_bitop3_b32 v73, v73, v75, 31 bitop3:0x6c
	v_lshl_add_u32 v72, v72, 3, 16
	v_lshl_add_u32 v74, v74, 3, 16
	v_lshl_add_u32 v76, v73, 3, 16
	ds_read_b64 v[72:73], v72
	ds_read_b64 v[74:75], v74
	ds_read_b64 v[76:77], v76
	s_waitcnt lgkmcnt(3)
	v_pk_add_f32 v[78:79], v[66:67], v[0:1]
	v_sub_f32_e32 v1, v67, v1
	v_sub_f32_e32 v0, v0, v66
	v_mul_f32_e32 v67, 0.5, v1
	v_mul_f32_e32 v66, 0.5, v0
	s_waitcnt lgkmcnt(2)
	v_pk_add_f32 v[0:1], v[64:65], v[72:73]
	v_mul_f32_e32 v78, 0.5, v78
	v_mul_f32_e32 v80, 0.5, v0
	v_sub_f32_e32 v0, v65, v73
	v_mul_f32_e32 v65, 0.5, v0
	v_sub_f32_e32 v0, v72, v64
	v_mul_f32_e32 v73, 0.5, v1
	v_mul_f32_e32 v64, 0.5, v0
	s_waitcnt lgkmcnt(1)
	v_pk_add_f32 v[0:1], v[62:63], v[74:75]
	s_mov_b32 s0, 0x10000
	v_mul_f32_e32 v72, 0.5, v0
	v_sub_f32_e32 v0, v63, v75
	v_mul_f32_e32 v75, 0.5, v0
	v_sub_f32_e32 v0, v74, v62
	v_mul_f32_e32 v81, 0.5, v1
	v_mul_f32_e32 v74, 0.5, v0
	s_waitcnt lgkmcnt(0)
	v_pk_add_f32 v[0:1], v[60:61], v[76:77]
	v_sub_f32_e32 v61, v61, v77
	v_mul_f32_e32 v0, 0.5, v0
	v_mul_f32_e32 v61, 0.5, v61
	v_sub_f32_e32 v60, v76, v60
	v_mul_f32_e32 v79, 0.5, v79
	v_mul_f32_e32 v1, 0.5, v1
	v_mul_f32_e32 v76, 0.5, v60
	v_cvt_pk_f16_f32 v63, v0, v61
	v_cvt_pk_f16_f32 v62, v72, v75
	v_cvt_pk_f16_f32 v61, v80, v65
	v_cvt_pk_f16_f32 v60, v78, v67
	v_add_co_u32_e32 v0, vcc, s0, v28
	global_store_dwordx4 v[28:29], v[60:63], off offset:-4096
	v_readlane_b32 s0, v252, 50
	s_add_u32 s64, s0, s10
	v_cvt_pk_f16_f32 v63, v1, v76
	v_cvt_pk_f16_f32 v62, v81, v74
	v_cvt_pk_f16_f32 v61, v73, v64
	v_cvt_pk_f16_f32 v60, v79, v66
	v_addc_co_u32_e32 v1, vcc, 0, v29, vcc
	global_store_dwordx4 v[0:1], v[60:63], off offset:-4096
	v_readlane_b32 s0, v252, 51
	s_addc_u32 s65, s0, s11
	v_or_b32_e32 v60, 4, v71
	v_bfrev_b32_e32 v60, v60
	v_lshrrev_b32_e32 v60, 18, v60
	v_sub_u32_e32 v62, 0, v60
	v_and_b32_e32 v63, 0x1fff, v62
	v_bfrev_b32_e32 v63, v63
	v_lshrrev_b32_e32 v64, 18, v63
	v_lshrrev_b32_e32 v63, 23, v63
	v_bitop3_b32 v63, v63, v64, 31 bitop3:0x6c
	v_or_b32_e32 v64, 6, v71
	v_bfrev_b32_e32 v64, v64
	v_and_b32_e32 v60, 0x3fff, v62
	v_lshrrev_b32_e32 v64, 18, v64
	v_bfrev_b32_e32 v60, v60
	v_sub_u32_e32 v64, 0, v64
	v_lshrrev_b32_e32 v61, 18, v60
	v_lshrrev_b32_e32 v60, 23, v60
	v_and_b32_e32 v64, 0x2fff, v64
	v_bitop3_b32 v60, v60, v61, 31 bitop3:0x6c
	v_bfrev_b32_e32 v64, v64
	v_and_b32_e32 v62, 0xfff, v62
	v_lshl_add_u32 v60, v60, 3, 16
	v_lshrrev_b32_e32 v65, 18, v64
	v_lshrrev_b32_e32 v64, 23, v64
	v_bfrev_b32_e32 v62, v62
	ds_read_b64 v[60:61], v60
	v_bitop3_b32 v64, v64, v65, 31 bitop3:0x6c
	v_lshrrev_b32_e32 v65, 18, v62
	v_lshrrev_b32_e32 v62, 23, v62
	v_bitop3_b32 v62, v62, v65, 31 bitop3:0x6c
	v_lshl_add_u32 v63, v63, 3, 16
	v_lshl_add_u32 v64, v64, 3, 16
	v_lshl_add_u32 v66, v62, 3, 16
	ds_read_b64 v[62:63], v63
	ds_read_b64 v[64:65], v64
	ds_read_b64 v[66:67], v66
	s_waitcnt lgkmcnt(3)
	v_pk_add_f32 v[72:73], v[58:59], v[60:61]
	v_sub_f32_e32 v59, v59, v61
	v_sub_f32_e32 v58, v60, v58
	v_mul_f32_e32 v61, 0.5, v59
	v_mul_f32_e32 v60, 0.5, v58
	s_waitcnt lgkmcnt(2)
	v_pk_add_f32 v[58:59], v[56:57], v[62:63]
	v_sub_f32_e32 v57, v57, v63
	v_sub_f32_e32 v56, v62, v56
	v_mul_f32_e32 v63, 0.5, v57
	v_mul_f32_e32 v62, 0.5, v56
	s_waitcnt lgkmcnt(1)
	v_pk_add_f32 v[56:57], v[54:55], v[64:65]
	v_sub_f32_e32 v55, v55, v65
	v_sub_f32_e32 v54, v64, v54
	v_mul_f32_e32 v65, 0.5, v55
	v_mul_f32_e32 v64, 0.5, v54
	s_waitcnt lgkmcnt(0)
	v_pk_add_f32 v[54:55], v[52:53], v[66:67]
	v_sub_f32_e32 v53, v53, v67
	v_mul_f32_e32 v72, 0.5, v72
	v_mul_f32_e32 v58, 0.5, v58
	v_mul_f32_e32 v56, 0.5, v56
	v_mul_f32_e32 v54, 0.5, v54
	v_mul_f32_e32 v53, 0.5, v53
	v_sub_f32_e32 v52, v66, v52
	v_mul_f32_e32 v73, 0.5, v73
	v_mul_f32_e32 v59, 0.5, v59
	v_mul_f32_e32 v57, 0.5, v57
	v_mul_f32_e32 v67, 0.5, v55
	v_mul_f32_e32 v66, 0.5, v52
	v_cvt_pk_f16_f32 v55, v54, v53
	v_cvt_pk_f16_f32 v54, v56, v65
	v_cvt_pk_f16_f32 v53, v58, v63
	v_cvt_pk_f16_f32 v52, v72, v61
	global_store_dwordx4 v[28:29], v[52:55], off offset:-3072
	s_lshl_b64 s[0:1], s[62:63], 13
	s_add_u32 s66, s0, 0xc00000
	v_cvt_pk_f16_f32 v55, v67, v66
	v_cvt_pk_f16_f32 v54, v57, v64
	v_cvt_pk_f16_f32 v53, v59, v62
	v_cvt_pk_f16_f32 v52, v73, v60
	global_store_dwordx4 v[0:1], v[52:55], off offset:-3072
	s_addc_u32 s67, s1, 0
	v_readlane_b32 s0, v252, 6
	v_or_b32_e32 v52, 8, v71
	v_bfrev_b32_e32 v52, v52
	v_lshrrev_b32_e32 v52, 18, v52
	v_sub_u32_e32 v62, 0, v52
	v_and_b32_e32 v54, 0x1fff, v62
	v_bfrev_b32_e32 v54, v54
	v_lshrrev_b32_e32 v55, 18, v54
	v_lshrrev_b32_e32 v54, 23, v54
	v_bitop3_b32 v54, v54, v55, 31 bitop3:0x6c
	v_or_b32_e32 v55, 10, v71
	v_bfrev_b32_e32 v55, v55
	v_lshrrev_b32_e32 v55, 18, v55
	v_sub_u32_e32 v55, 0, v55
	v_and_b32_e32 v55, 0x2fff, v55
	v_and_b32_e32 v52, 0x3fff, v62
	v_bfrev_b32_e32 v55, v55
	v_bfrev_b32_e32 v52, v52
	v_lshrrev_b32_e32 v56, 18, v55
	v_lshrrev_b32_e32 v55, 23, v55
	v_lshrrev_b32_e32 v53, 18, v52
	v_lshrrev_b32_e32 v52, 23, v52
	v_bitop3_b32 v55, v55, v56, 31 bitop3:0x6c
	v_bitop3_b32 v52, v52, v53, 31 bitop3:0x6c
	v_lshl_add_u32 v56, v55, 3, 16
	v_and_b32_e32 v55, 0xfff, v62
	v_lshl_add_u32 v52, v52, 3, 16
	v_bfrev_b32_e32 v55, v55
	ds_read_b64 v[52:53], v52
	v_lshrrev_b32_e32 v57, 18, v55
	v_lshrrev_b32_e32 v55, 23, v55
	v_bitop3_b32 v55, v55, v57, 31 bitop3:0x6c
	v_lshl_add_u32 v54, v54, 3, 16
	v_lshl_add_u32 v58, v55, 3, 16
	ds_read_b64 v[54:55], v54
	ds_read_b64 v[56:57], v56
	ds_read_b64 v[58:59], v58
	s_waitcnt lgkmcnt(3)
	v_pk_add_f32 v[60:61], v[50:51], v[52:53]
	v_sub_f32_e32 v51, v51, v53
	v_sub_f32_e32 v50, v52, v50
	v_mul_f32_e32 v53, 0.5, v51
	v_mul_f32_e32 v52, 0.5, v50
	s_waitcnt lgkmcnt(2)
	v_pk_add_f32 v[50:51], v[48:49], v[54:55]
	v_sub_f32_e32 v49, v49, v55
	v_sub_f32_e32 v48, v54, v48
	v_mul_f32_e32 v55, 0.5, v49
	v_mul_f32_e32 v54, 0.5, v48
	s_waitcnt lgkmcnt(1)
	v_pk_add_f32 v[48:49], v[46:47], v[56:57]
	v_sub_f32_e32 v47, v47, v57
	v_sub_f32_e32 v46, v56, v46
	v_mul_f32_e32 v57, 0.5, v47
	v_mul_f32_e32 v56, 0.5, v46
	s_waitcnt lgkmcnt(0)
	v_pk_add_f32 v[46:47], v[44:45], v[58:59]
	v_sub_f32_e32 v45, v45, v59
	v_mul_f32_e32 v60, 0.5, v60
	v_mul_f32_e32 v50, 0.5, v50
	v_mul_f32_e32 v48, 0.5, v48
	v_mul_f32_e32 v46, 0.5, v46
	v_mul_f32_e32 v45, 0.5, v45
	v_sub_f32_e32 v44, v58, v44
	v_mul_f32_e32 v61, 0.5, v61
	v_mul_f32_e32 v51, 0.5, v51
	v_mul_f32_e32 v49, 0.5, v49
	v_mul_f32_e32 v59, 0.5, v47
	v_mul_f32_e32 v58, 0.5, v44
	v_cvt_pk_f16_f32 v47, v46, v45
	v_cvt_pk_f16_f32 v46, v48, v57
	v_cvt_pk_f16_f32 v45, v50, v55
	v_cvt_pk_f16_f32 v44, v60, v53
	global_store_dwordx4 v[28:29], v[44:47], off offset:-2048
	s_add_u32 s68, s0, s10
	v_readlane_b32 s0, v252, 47
	v_cvt_pk_f16_f32 v47, v59, v58
	v_cvt_pk_f16_f32 v46, v49, v56
	v_cvt_pk_f16_f32 v45, v51, v54
	v_cvt_pk_f16_f32 v44, v61, v52
	global_store_dwordx4 v[0:1], v[44:47], off offset:-2048
	s_addc_u32 s69, s0, s11
	s_lshl_b64 s[0:1], s[62:63], 14
	v_or_b32_e32 v44, 12, v71
	v_bfrev_b32_e32 v44, v44
	v_lshrrev_b32_e32 v44, 18, v44
	v_sub_u32_e32 v46, 0, v44
	v_and_b32_e32 v44, 0x37ff, v46
	v_and_b32_e32 v46, 0x17ff, v46
	v_bfrev_b32_e32 v46, v46
	v_lshrrev_b32_e32 v47, 18, v46
	v_lshrrev_b32_e32 v46, 23, v46
	v_bitop3_b32 v46, v46, v47, 31 bitop3:0x6c
	v_or_b32_e32 v47, 14, v71
	v_bfrev_b32_e32 v47, v47
	v_lshrrev_b32_e32 v47, 18, v47
	v_sub_u32_e32 v47, 0, v47
	v_and_b32_e32 v47, 0x27ff, v47
	v_bfrev_b32_e32 v47, v47
	v_bfrev_b32_e32 v44, v44
	v_lshrrev_b32_e32 v48, 18, v47
	v_lshrrev_b32_e32 v47, 23, v47
	v_lshrrev_b32_e32 v45, 18, v44
	v_lshrrev_b32_e32 v44, 23, v44
	v_bitop3_b32 v47, v47, v48, 31 bitop3:0x6c
	v_bitop3_b32 v44, v44, v45, 31 bitop3:0x6c
	v_lshl_add_u32 v48, v47, 3, 16
	v_and_b32_e32 v47, 0x7ff, v62
	v_lshl_add_u32 v44, v44, 3, 16
	v_bfrev_b32_e32 v47, v47
	ds_read_b64 v[44:45], v44
	v_lshrrev_b32_e32 v49, 18, v47
	v_lshrrev_b32_e32 v47, 23, v47
	v_bitop3_b32 v47, v47, v49, 31 bitop3:0x6c
	v_lshl_add_u32 v46, v46, 3, 16
	v_lshl_add_u32 v50, v47, 3, 16
	ds_read_b64 v[46:47], v46
	ds_read_b64 v[48:49], v48
	ds_read_b64 v[50:51], v50
	s_waitcnt lgkmcnt(3)
	v_pk_add_f32 v[52:53], v[34:35], v[44:45]
	v_sub_f32_e32 v35, v35, v45
	v_sub_f32_e32 v34, v44, v34
	v_mul_f32_e32 v45, 0.5, v35
	v_mul_f32_e32 v44, 0.5, v34
	s_waitcnt lgkmcnt(2)
	v_pk_add_f32 v[34:35], v[32:33], v[46:47]
	v_sub_f32_e32 v33, v33, v47
	v_sub_f32_e32 v32, v46, v32
	v_mul_f32_e32 v47, 0.5, v33
	v_mul_f32_e32 v46, 0.5, v32
	s_waitcnt lgkmcnt(1)
	v_pk_add_f32 v[32:33], v[30:31], v[48:49]
	v_sub_f32_e32 v31, v31, v49
	v_sub_f32_e32 v30, v48, v30
	v_mul_f32_e32 v49, 0.5, v31
	v_mul_f32_e32 v48, 0.5, v30
	s_waitcnt lgkmcnt(0)
	v_pk_add_f32 v[30:31], v[26:27], v[50:51]
	v_sub_f32_e32 v27, v27, v51
	v_mul_f32_e32 v52, 0.5, v52
	v_mul_f32_e32 v34, 0.5, v34
	v_mul_f32_e32 v32, 0.5, v32
	v_mul_f32_e32 v30, 0.5, v30
	v_mul_f32_e32 v27, 0.5, v27
	v_sub_f32_e32 v26, v50, v26
	v_mul_f32_e32 v53, 0.5, v53
	v_mul_f32_e32 v35, 0.5, v35
	v_mul_f32_e32 v54, 0.5, v33
	v_mul_f32_e32 v51, 0.5, v31
	v_mul_f32_e32 v26, 0.5, v26
	v_cvt_pk_f16_f32 v33, v30, v27
	v_cvt_pk_f16_f32 v32, v32, v49
	v_cvt_pk_f16_f32 v31, v34, v47
	v_cvt_pk_f16_f32 v30, v52, v45
	global_store_dwordx4 v[28:29], v[30:33], off offset:-1024
	s_add_u32 s12, s26, s0
	s_addc_u32 s13, s27, s1
	v_cvt_pk_f16_f32 v33, v51, v26
	v_cvt_pk_f16_f32 v32, v54, v48
	v_cvt_pk_f16_f32 v31, v35, v46
	v_cvt_pk_f16_f32 v30, v53, v44
	global_store_dwordx4 v[0:1], v[30:33], off offset:-1024
	v_bfrev_b32_e32 v26, v88
	v_lshrrev_b32_e32 v26, 18, v26
	v_add_u32_e32 v30, 0x2001, v71
	v_bfrev_b32_e32 v30, v30
	v_lshrrev_b32_e32 v30, 18, v30
	v_sub_u32_e32 v30, 0, v30
	v_and_b32_e32 v30, 0x3fff, v30
	v_bfrev_b32_e32 v30, v30
	v_lshrrev_b32_e32 v31, 18, v30
	v_lshrrev_b32_e32 v30, 23, v30
	v_bitop3_b32 v30, v30, v31, 31 bitop3:0x6c
	v_add_u32_e32 v31, 0x2002, v71
	v_bfrev_b32_e32 v31, v31
	v_lshrrev_b32_e32 v31, 18, v31
	v_sub_u32_e32 v31, 0, v31
	v_and_b32_e32 v31, 0x3fff, v31
	v_bfrev_b32_e32 v31, v31
	v_lshrrev_b32_e32 v32, 18, v31
	v_lshrrev_b32_e32 v31, 23, v31
	v_bitop3_b32 v31, v31, v32, 31 bitop3:0x6c
	v_sub_u32_e32 v26, 0, v26
	v_lshl_add_u32 v32, v31, 3, 16
	v_add_u32_e32 v31, 0x2003, v71
	v_and_b32_e32 v26, 0x3fff, v26
	v_bfrev_b32_e32 v31, v31
	v_bfrev_b32_e32 v26, v26
	v_lshrrev_b32_e32 v31, 18, v31
	v_lshrrev_b32_e32 v27, 18, v26
	v_lshrrev_b32_e32 v26, 23, v26
	v_sub_u32_e32 v31, 0, v31
	v_bitop3_b32 v26, v26, v27, 31 bitop3:0x6c
	v_and_b32_e32 v31, 0x1fff, v31
	v_lshl_add_u32 v26, v26, 3, 16
	v_bfrev_b32_e32 v31, v31
	ds_read_b64 v[26:27], v26
	v_lshrrev_b32_e32 v33, 18, v31
	v_lshrrev_b32_e32 v31, 23, v31
	v_bitop3_b32 v31, v31, v33, 31 bitop3:0x6c
	v_lshl_add_u32 v30, v30, 3, 16
	v_lshl_add_u32 v34, v31, 3, 16
	ds_read_b64 v[30:31], v30
	ds_read_b64 v[32:33], v32
	ds_read_b64 v[34:35], v34
	s_waitcnt lgkmcnt(3)
	v_pk_add_f32 v[44:45], v[42:43], v[26:27]
	v_sub_f32_e32 v27, v43, v27
	v_sub_f32_e32 v26, v26, v42
	v_mul_f32_e32 v43, 0.5, v27
	v_mul_f32_e32 v42, 0.5, v26
	s_waitcnt lgkmcnt(2)
	v_pk_add_f32 v[26:27], v[40:41], v[30:31]
	v_mul_f32_e32 v44, 0.5, v44
	v_mul_f32_e32 v46, 0.5, v26
	v_sub_f32_e32 v26, v41, v31
	v_mul_f32_e32 v31, 0.5, v26
	v_sub_f32_e32 v26, v30, v40
	v_mul_f32_e32 v41, 0.5, v27
	v_mul_f32_e32 v40, 0.5, v26
	s_waitcnt lgkmcnt(1)
	v_pk_add_f32 v[26:27], v[38:39], v[32:33]
	v_mul_f32_e32 v45, 0.5, v45
	v_mul_f32_e32 v30, 0.5, v26
	v_sub_f32_e32 v26, v39, v33
	v_mul_f32_e32 v39, 0.5, v26
	v_sub_f32_e32 v26, v32, v38
	v_mul_f32_e32 v47, 0.5, v27
	v_mul_f32_e32 v38, 0.5, v26
	s_waitcnt lgkmcnt(0)
	v_pk_add_f32 v[26:27], v[36:37], v[34:35]
	v_sub_f32_e32 v32, v37, v35
	v_mul_f32_e32 v26, 0.5, v26
	v_mul_f32_e32 v32, 0.5, v32
	v_sub_f32_e32 v33, v34, v36
	v_mul_f32_e32 v27, 0.5, v27
	v_mul_f32_e32 v34, 0.5, v33
	v_cvt_pk_f16_f32 v33, v26, v32
	v_cvt_pk_f16_f32 v32, v30, v39
	v_cvt_pk_f16_f32 v31, v46, v31
	v_cvt_pk_f16_f32 v30, v44, v43
	global_store_dwordx4 v[28:29], v[30:33], off
	v_add_u32_e32 v26, 0x2004, v71
	v_bfrev_b32_e32 v26, v26
	v_cvt_pk_f16_f32 v33, v27, v34
	v_cvt_pk_f16_f32 v32, v47, v38
	v_cvt_pk_f16_f32 v31, v41, v40
	v_cvt_pk_f16_f32 v30, v45, v42
	global_store_dwordx4 v[0:1], v[30:33], off
	v_lshrrev_b32_e32 v26, 18, v26
	v_sub_u32_e32 v26, 0, v26
	v_add_u32_e32 v30, 0x2005, v71
	v_bfrev_b32_e32 v30, v30
	v_lshrrev_b32_e32 v30, 18, v30
	v_sub_u32_e32 v30, 0, v30
	v_and_b32_e32 v30, 0x1fff, v30
	v_bfrev_b32_e32 v30, v30
	v_lshrrev_b32_e32 v31, 18, v30
	v_lshrrev_b32_e32 v30, 23, v30
	v_bitop3_b32 v30, v30, v31, 31 bitop3:0x6c
	v_add_u32_e32 v31, 0x2006, v71
	v_bfrev_b32_e32 v31, v31
	v_lshrrev_b32_e32 v31, 18, v31
	v_sub_u32_e32 v31, 0, v31
	v_and_b32_e32 v31, 0x2fff, v31
	v_bfrev_b32_e32 v31, v31
	v_lshrrev_b32_e32 v32, 18, v31
	v_lshrrev_b32_e32 v31, 23, v31
	v_bitop3_b32 v31, v31, v32, 31 bitop3:0x6c
	v_lshl_add_u32 v32, v31, 3, 16
	v_add_u32_e32 v31, 0x2007, v71
	v_and_b32_e32 v26, 0x3fff, v26
	v_bfrev_b32_e32 v31, v31
	v_bfrev_b32_e32 v26, v26
	v_lshrrev_b32_e32 v31, 18, v31
	v_lshrrev_b32_e32 v27, 18, v26
	v_lshrrev_b32_e32 v26, 23, v26
	v_sub_u32_e32 v31, 0, v31
	v_bitop3_b32 v26, v26, v27, 31 bitop3:0x6c
	v_and_b32_e32 v31, 0xfff, v31
	v_lshl_add_u32 v26, v26, 3, 16
	v_bfrev_b32_e32 v31, v31
	ds_read_b64 v[26:27], v26
	v_lshrrev_b32_e32 v33, 18, v31
	v_lshrrev_b32_e32 v31, 23, v31
	v_bitop3_b32 v31, v31, v33, 31 bitop3:0x6c
	v_lshl_add_u32 v30, v30, 3, 16
	v_lshl_add_u32 v34, v31, 3, 16
	ds_read_b64 v[30:31], v30
	ds_read_b64 v[32:33], v32
	ds_read_b64 v[34:35], v34
	s_waitcnt lgkmcnt(3)
	v_pk_add_f32 v[36:37], v[24:25], v[26:27]
	v_sub_f32_e32 v25, v25, v27
	v_sub_f32_e32 v24, v26, v24
	v_mul_f32_e32 v27, 0.5, v25
	v_mul_f32_e32 v26, 0.5, v24
	s_waitcnt lgkmcnt(2)
	v_pk_add_f32 v[24:25], v[22:23], v[30:31]
	v_sub_f32_e32 v23, v23, v31
	v_sub_f32_e32 v22, v30, v22
	v_mul_f32_e32 v31, 0.5, v23
	v_mul_f32_e32 v30, 0.5, v22
	s_waitcnt lgkmcnt(1)
	v_pk_add_f32 v[22:23], v[20:21], v[32:33]
	v_sub_f32_e32 v21, v21, v33
	v_sub_f32_e32 v20, v32, v20
	v_mul_f32_e32 v33, 0.5, v21
	v_mul_f32_e32 v32, 0.5, v20
	s_waitcnt lgkmcnt(0)
	v_pk_add_f32 v[20:21], v[18:19], v[34:35]
	v_sub_f32_e32 v19, v19, v35
	v_mul_f32_e32 v36, 0.5, v36
	v_mul_f32_e32 v24, 0.5, v24
	v_mul_f32_e32 v22, 0.5, v22
	v_mul_f32_e32 v20, 0.5, v20
	v_mul_f32_e32 v19, 0.5, v19
	v_sub_f32_e32 v18, v34, v18
	v_mul_f32_e32 v37, 0.5, v37
	v_mul_f32_e32 v25, 0.5, v25
	v_mul_f32_e32 v23, 0.5, v23
	v_mul_f32_e32 v35, 0.5, v21
	v_mul_f32_e32 v34, 0.5, v18
	v_cvt_pk_f16_f32 v21, v20, v19
	v_cvt_pk_f16_f32 v20, v22, v33
	v_cvt_pk_f16_f32 v19, v24, v31
	v_cvt_pk_f16_f32 v18, v36, v27
	global_store_dwordx4 v[28:29], v[18:21], off offset:1024
	s_add_u32 s14, s30, s0
	s_addc_u32 s15, s31, s1
	v_cvt_pk_f16_f32 v21, v35, v34
	v_cvt_pk_f16_f32 v20, v23, v32
	v_cvt_pk_f16_f32 v19, v25, v30
	v_cvt_pk_f16_f32 v18, v37, v26
	global_store_dwordx4 v[0:1], v[18:21], off offset:1024
	v_cmp_lt_i32_e32 vcc, s33, v146
	v_add_u32_e32 v52, 0x800, v146
	v_add_u32_e32 v20, 0x2009, v71
	v_bfrev_b32_e32 v20, v20
	v_lshrrev_b32_e32 v20, 18, v20
	v_sub_u32_e32 v20, 0, v20
	v_and_b32_e32 v20, 0x1fff, v20
	v_bfrev_b32_e32 v20, v20
	v_lshrrev_b32_e32 v21, 18, v20
	v_lshrrev_b32_e32 v20, 23, v20
	v_bitop3_b32 v20, v20, v21, 31 bitop3:0x6c
	v_add_u32_e32 v21, 0x200a, v71
	v_bfrev_b32_e32 v21, v21
	v_lshrrev_b32_e32 v21, 18, v21
	v_sub_u32_e32 v21, 0, v21
	v_and_b32_e32 v21, 0x2fff, v21
	v_add_u32_e32 v18, 0x2008, v71
	v_bfrev_b32_e32 v21, v21
	v_bfrev_b32_e32 v18, v18
	v_lshrrev_b32_e32 v22, 18, v21
	v_lshrrev_b32_e32 v21, 23, v21
	v_lshrrev_b32_e32 v18, 18, v18
	v_bitop3_b32 v21, v21, v22, 31 bitop3:0x6c
	v_sub_u32_e32 v18, 0, v18
	v_lshl_add_u32 v22, v21, 3, 16
	v_add_u32_e32 v21, 0x200b, v71
	v_and_b32_e32 v18, 0x3fff, v18
	v_bfrev_b32_e32 v21, v21
	v_bfrev_b32_e32 v18, v18
	v_lshrrev_b32_e32 v21, 18, v21
	v_lshrrev_b32_e32 v19, 18, v18
	v_lshrrev_b32_e32 v18, 23, v18
	v_sub_u32_e32 v21, 0, v21
	v_bitop3_b32 v18, v18, v19, 31 bitop3:0x6c
	v_and_b32_e32 v21, 0xfff, v21
	v_lshl_add_u32 v18, v18, 3, 16
	v_bfrev_b32_e32 v21, v21
	ds_read_b64 v[18:19], v18
	v_lshrrev_b32_e32 v23, 18, v21
	v_lshrrev_b32_e32 v21, 23, v21
	v_bitop3_b32 v21, v21, v23, 31 bitop3:0x6c
	v_lshl_add_u32 v20, v20, 3, 16
	v_lshl_add_u32 v24, v21, 3, 16
	ds_read_b64 v[20:21], v20
	ds_read_b64 v[22:23], v22
	ds_read_b64 v[24:25], v24
	s_waitcnt lgkmcnt(3)
	v_pk_add_f32 v[26:27], v[16:17], v[18:19]
	v_sub_f32_e32 v17, v17, v19
	v_sub_f32_e32 v16, v18, v16
	v_mul_f32_e32 v19, 0.5, v17
	v_mul_f32_e32 v18, 0.5, v16
	s_waitcnt lgkmcnt(2)
	v_pk_add_f32 v[16:17], v[14:15], v[20:21]
	v_sub_f32_e32 v15, v15, v21
	v_sub_f32_e32 v14, v20, v14
	v_mul_f32_e32 v21, 0.5, v15
	v_mul_f32_e32 v20, 0.5, v14
	s_waitcnt lgkmcnt(1)
	v_pk_add_f32 v[14:15], v[12:13], v[22:23]
	v_sub_f32_e32 v13, v13, v23
	v_sub_f32_e32 v12, v22, v12
	v_mul_f32_e32 v23, 0.5, v13
	v_mul_f32_e32 v22, 0.5, v12
	s_waitcnt lgkmcnt(0)
	v_pk_add_f32 v[12:13], v[10:11], v[24:25]
	v_sub_f32_e32 v11, v11, v25
	v_mul_f32_e32 v26, 0.5, v26
	v_mul_f32_e32 v16, 0.5, v16
	v_mul_f32_e32 v14, 0.5, v14
	v_mul_f32_e32 v12, 0.5, v12
	v_mul_f32_e32 v11, 0.5, v11
	v_sub_f32_e32 v10, v24, v10
	v_mul_f32_e32 v27, 0.5, v27
	v_mul_f32_e32 v17, 0.5, v17
	v_mul_f32_e32 v15, 0.5, v15
	v_mul_f32_e32 v25, 0.5, v13
	v_mul_f32_e32 v24, 0.5, v10
	v_cvt_pk_f16_f32 v13, v12, v11
	v_cvt_pk_f16_f32 v12, v14, v23
	v_cvt_pk_f16_f32 v11, v16, v21
	v_cvt_pk_f16_f32 v10, v26, v19
	global_store_dwordx4 v[28:29], v[10:13], off offset:2048
	v_add_u32_e32 v53, 0xa00, v146
	v_add_u32_e32 v54, 0xc00, v146
	v_cvt_pk_f16_f32 v13, v25, v24
	v_cvt_pk_f16_f32 v12, v15, v22
	v_cvt_pk_f16_f32 v11, v17, v20
	v_cvt_pk_f16_f32 v10, v27, v18
	global_store_dwordx4 v[0:1], v[10:13], off offset:2048
	v_add_u32_e32 v55, 0xe00, v146
	v_add_u32_e32 v47, 0x1000, v146
	v_add_u32_e32 v12, 0x200d, v71
	v_bfrev_b32_e32 v12, v12
	v_lshrrev_b32_e32 v12, 18, v12
	v_sub_u32_e32 v12, 0, v12
	v_and_b32_e32 v12, 0x17ff, v12
	v_bfrev_b32_e32 v12, v12
	v_lshrrev_b32_e32 v13, 18, v12
	v_lshrrev_b32_e32 v12, 23, v12
	v_bitop3_b32 v12, v12, v13, 31 bitop3:0x6c
	v_add_u32_e32 v13, 0x200e, v71
	v_bfrev_b32_e32 v13, v13
	v_lshrrev_b32_e32 v13, 18, v13
	v_sub_u32_e32 v13, 0, v13
	v_and_b32_e32 v13, 0x27ff, v13
	v_add_u32_e32 v10, 0x200c, v71
	v_bfrev_b32_e32 v13, v13
	v_bfrev_b32_e32 v10, v10
	v_lshrrev_b32_e32 v14, 18, v13
	v_lshrrev_b32_e32 v13, 23, v13
	v_lshrrev_b32_e32 v10, 18, v10
	v_bitop3_b32 v13, v13, v14, 31 bitop3:0x6c
	v_sub_u32_e32 v10, 0, v10
	v_lshl_add_u32 v14, v13, 3, 16
	v_add_u32_e32 v13, 0x200f, v71
	v_and_b32_e32 v10, 0x37ff, v10
	v_bfrev_b32_e32 v13, v13
	v_bfrev_b32_e32 v10, v10
	v_lshrrev_b32_e32 v13, 18, v13
	v_lshrrev_b32_e32 v11, 18, v10
	v_lshrrev_b32_e32 v10, 23, v10
	v_sub_u32_e32 v13, 0, v13
	v_bitop3_b32 v10, v10, v11, 31 bitop3:0x6c
	v_and_b32_e32 v13, 0x7ff, v13
	v_lshl_add_u32 v10, v10, 3, 16
	v_bfrev_b32_e32 v13, v13
	ds_read_b64 v[10:11], v10
	v_lshrrev_b32_e32 v15, 18, v13
	v_lshrrev_b32_e32 v13, 23, v13
	v_bitop3_b32 v13, v13, v15, 31 bitop3:0x6c
	v_lshl_add_u32 v12, v12, 3, 16
	v_lshl_add_u32 v16, v13, 3, 16
	ds_read_b64 v[12:13], v12
	ds_read_b64 v[14:15], v14
	ds_read_b64 v[16:17], v16
	s_waitcnt lgkmcnt(3)
	v_pk_add_f32 v[18:19], v[8:9], v[10:11]
	v_sub_f32_e32 v9, v9, v11
	v_sub_f32_e32 v8, v10, v8
	v_mul_f32_e32 v11, 0.5, v9
	v_mul_f32_e32 v10, 0.5, v8
	s_waitcnt lgkmcnt(2)
	v_pk_add_f32 v[8:9], v[6:7], v[12:13]
	v_sub_f32_e32 v7, v7, v13
	v_sub_f32_e32 v6, v12, v6
	v_mul_f32_e32 v13, 0.5, v7
	v_mul_f32_e32 v12, 0.5, v6
	s_waitcnt lgkmcnt(1)
	v_pk_add_f32 v[6:7], v[4:5], v[14:15]
	v_sub_f32_e32 v5, v5, v15
	v_sub_f32_e32 v4, v14, v4
	v_mul_f32_e32 v15, 0.5, v5
	v_mul_f32_e32 v14, 0.5, v4
	s_waitcnt lgkmcnt(0)
	v_pk_add_f32 v[4:5], v[2:3], v[16:17]
	v_sub_f32_e32 v3, v3, v17
	v_mul_f32_e32 v18, 0.5, v18
	v_mul_f32_e32 v8, 0.5, v8
	v_mul_f32_e32 v6, 0.5, v6
	v_mul_f32_e32 v4, 0.5, v4
	v_mul_f32_e32 v3, 0.5, v3
	v_sub_f32_e32 v2, v16, v2
	v_mul_f32_e32 v19, 0.5, v19
	v_mul_f32_e32 v9, 0.5, v9
	v_mul_f32_e32 v7, 0.5, v7
	v_mul_f32_e32 v17, 0.5, v5
	v_mul_f32_e32 v16, 0.5, v2
	v_cvt_pk_f16_f32 v5, v4, v3
	v_cvt_pk_f16_f32 v4, v6, v15
	v_cvt_pk_f16_f32 v3, v8, v13
	v_cvt_pk_f16_f32 v2, v18, v11
	global_store_dwordx4 v[28:29], v[2:5], off offset:3072
	v_add_u32_e32 v46, 0x1200, v146
	v_add_u32_e32 v27, 0x1400, v146
	v_cvt_pk_f16_f32 v5, v17, v16
	v_cvt_pk_f16_f32 v4, v7, v14
	v_cvt_pk_f16_f32 v3, v9, v12
	v_cvt_pk_f16_f32 v2, v19, v10
	global_store_dwordx4 v[0:1], v[2:5], off offset:3072
	global_load_dword v2, v151, s[64:65] offset:2048
	global_load_dword v0, v152, s[64:65]
	global_load_dword v6, v145, s[64:65]
	global_load_dword v4, v145, s[68:69]
	v_lshlrev_b32_e32 v8, 1, v146
	v_max_i32_e32 v12, 1, v146
	v_add_u32_e32 v13, 0x1e00, v146
	v_cmp_lt_i32_e32 vcc, 0, v146
	v_add_u32_e32 v9, 0x1000, v8
	v_add_u32_e32 v10, 0x2000, v8
	v_add_u32_e32 v11, 0x3000, v8
	v_lshlrev_b32_e32 v12, 1, v12
	v_cndmask_b32_e64 v14, 0, 1.0, vcc
	v_cmp_gt_i32_e32 vcc, 0x1fff, v13
	v_min_i32_e32 v13, 0x1ffe, v13
	v_lshlrev_b32_e32 v13, 1, v13
	s_nop 0
	v_cndmask_b32_e64 v15, 0, 1.0, vcc
	global_load_ushort v163, v12, s[12:13] offset:-2
	global_load_ushort v164, v8, s[12:13]
	global_load_ushort v165, v8, s[12:13] offset:2
	global_load_ushort v166, v12, s[14:15] offset:-2
	global_load_ushort v167, v8, s[14:15]
	global_load_ushort v168, v8, s[14:15] offset:2
	global_load_ushort v169, v8, s[12:13] offset:1022
	global_load_ushort v170, v8, s[12:13] offset:1024
	global_load_ushort v171, v8, s[12:13] offset:1026
	global_load_ushort v172, v8, s[14:15] offset:1022
	global_load_ushort v173, v8, s[14:15] offset:1024
	global_load_ushort v174, v8, s[14:15] offset:1026
	global_load_ushort v175, v8, s[12:13] offset:2046
	global_load_ushort v176, v8, s[12:13] offset:2048
	global_load_ushort v177, v8, s[12:13] offset:2050
	global_load_ushort v178, v8, s[14:15] offset:2046
	global_load_ushort v179, v8, s[14:15] offset:2048
	global_load_ushort v180, v8, s[14:15] offset:2050
	global_load_ushort v181, v8, s[12:13] offset:3070
	global_load_ushort v182, v8, s[12:13] offset:3072
	global_load_ushort v183, v8, s[12:13] offset:3074
	global_load_ushort v184, v8, s[14:15] offset:3070
	global_load_ushort v185, v8, s[14:15] offset:3072
	global_load_ushort v186, v8, s[14:15] offset:3074
	global_load_ushort v187, v9, s[12:13] offset:-2
	global_load_ushort v188, v9, s[12:13]
	global_load_ushort v189, v9, s[12:13] offset:2
	global_load_ushort v190, v9, s[14:15] offset:-2
	global_load_ushort v191, v9, s[14:15]
	global_load_ushort v192, v9, s[14:15] offset:2
	global_load_ushort v193, v9, s[12:13] offset:1022
	global_load_ushort v194, v9, s[12:13] offset:1024
	global_load_ushort v195, v9, s[12:13] offset:1026
	global_load_ushort v196, v9, s[14:15] offset:1022
	global_load_ushort v197, v9, s[14:15] offset:1024
	global_load_ushort v198, v9, s[14:15] offset:1026
	global_load_ushort v199, v9, s[12:13] offset:2046
	global_load_ushort v200, v9, s[12:13] offset:2048
	global_load_ushort v201, v9, s[12:13] offset:2050
	global_load_ushort v202, v9, s[14:15] offset:2046
	global_load_ushort v203, v9, s[14:15] offset:2048
	global_load_ushort v204, v9, s[14:15] offset:2050
	global_load_ushort v205, v9, s[12:13] offset:3070
	global_load_ushort v206, v9, s[12:13] offset:3072
	global_load_ushort v207, v9, s[12:13] offset:3074
	global_load_ushort v208, v9, s[14:15] offset:3070
	global_load_ushort v209, v9, s[14:15] offset:3072
	global_load_ushort v210, v9, s[14:15] offset:3074
	global_load_ushort v211, v10, s[12:13] offset:-2
	global_load_ushort v212, v10, s[12:13]
	global_load_ushort v213, v10, s[12:13] offset:2
	global_load_ushort v221, v10, s[14:15] offset:-2
	global_load_ushort v222, v10, s[14:15]
	global_load_ushort v223, v10, s[14:15] offset:2
	global_load_ushort v224, v10, s[12:13] offset:1022
	global_load_ushort v225, v10, s[12:13] offset:1024
	global_load_ushort v226, v10, s[12:13] offset:1026
	global_load_ushort v227, v10, s[14:15] offset:1022
	global_load_ushort v228, v10, s[14:15] offset:1024
	global_load_ushort v229, v10, s[14:15] offset:1026
	global_load_ushort v230, v10, s[12:13] offset:2046
	global_load_ushort v231, v10, s[12:13] offset:2048
	global_load_ushort v232, v10, s[12:13] offset:2050
	global_load_ushort v233, v10, s[14:15] offset:2046
	global_load_ushort v234, v10, s[14:15] offset:2048
	global_load_ushort v235, v10, s[14:15] offset:2050
	global_load_ushort v236, v10, s[12:13] offset:3070
	global_load_ushort v237, v10, s[12:13] offset:3072
	global_load_ushort v238, v10, s[12:13] offset:3074
	global_load_ushort v239, v10, s[14:15] offset:3070
	global_load_ushort v240, v10, s[14:15] offset:3072
	global_load_ushort v241, v10, s[14:15] offset:3074
	global_load_ushort v242, v11, s[12:13] offset:-2
	global_load_ushort v243, v11, s[12:13]
	global_load_ushort v244, v11, s[12:13] offset:2
	global_load_ushort v245, v11, s[14:15] offset:-2
	global_load_ushort v246, v11, s[14:15]
	global_load_ushort v247, v11, s[14:15] offset:2
	global_load_ushort v248, v11, s[12:13] offset:1022
	global_load_ushort v249, v11, s[12:13] offset:1024
	global_load_ushort v250, v11, s[12:13] offset:1026
	global_load_ushort v251, v11, s[14:15] offset:1022
	global_load_ushort v253, v11, s[14:15] offset:1024
	global_load_ushort v254, v11, s[14:15] offset:1026
	global_load_ushort v255, v11, s[12:13] offset:2046
	global_load_ushort v1, v11, s[12:13] offset:2048
	global_load_ushort v3, v11, s[12:13] offset:2050
	global_load_ushort v5, v11, s[14:15] offset:2046
	global_load_ushort v7, v11, s[14:15] offset:2048
	global_load_ushort v16, v11, s[14:15] offset:2050
	global_load_ushort v17, v11, s[12:13] offset:3070
	global_load_ushort v18, v11, s[12:13] offset:3072
	global_load_ushort v19, v13, s[12:13] offset:2
	global_load_ushort v20, v11, s[14:15] offset:3070
	global_load_ushort v21, v11, s[14:15] offset:3072
	global_load_ushort v22, v13, s[14:15] offset:2
	s_waitcnt vmcnt(48)
	v_lshlrev_b32_e32 v163, 16, v163
	v_lshlrev_b32_e32 v164, 16, v164
	v_lshlrev_b32_e32 v165, 16, v165
	v_mul_f32_e32 v163, v14, v163
	v_mul_f32_e32 v163, v6, v163
	v_fmac_f32_e32 v163, v2, v164
	v_fmac_f32_e32 v163, v0, v165
	v_add_f32_e32 v32, v4, v163
	v_lshlrev_b32_e32 v166, 16, v166
	v_lshlrev_b32_e32 v167, 16, v167
	v_lshlrev_b32_e32 v168, 16, v168
	v_mul_f32_e32 v166, v14, v166
	v_mul_f32_e32 v166, v6, v166
	v_fmac_f32_e32 v166, v2, v167
	v_fmac_f32_e32 v166, v0, v168
	v_add_f32_e32 v34, v4, v166
	v_lshlrev_b32_e32 v169, 16, v169
	v_lshlrev_b32_e32 v170, 16, v170
	v_lshlrev_b32_e32 v171, 16, v171
	v_mul_f32_e32 v169, v6, v169
	v_fmac_f32_e32 v169, v2, v170
	v_fmac_f32_e32 v169, v0, v171
	v_add_f32_e32 v33, v4, v169
	v_lshlrev_b32_e32 v172, 16, v172
	v_lshlrev_b32_e32 v173, 16, v173
	v_lshlrev_b32_e32 v174, 16, v174
	v_mul_f32_e32 v172, v6, v172
	v_fmac_f32_e32 v172, v2, v173
	v_fmac_f32_e32 v172, v0, v174
	v_add_f32_e32 v35, v4, v172
	v_lshlrev_b32_e32 v175, 16, v175
	v_lshlrev_b32_e32 v176, 16, v176
	v_lshlrev_b32_e32 v177, 16, v177
	v_mul_f32_e32 v175, v6, v175
	v_fmac_f32_e32 v175, v2, v176
	v_fmac_f32_e32 v175, v0, v177
	v_add_f32_e32 v37, v4, v175
	v_lshlrev_b32_e32 v178, 16, v178
	v_lshlrev_b32_e32 v179, 16, v179
	v_lshlrev_b32_e32 v180, 16, v180
	v_mul_f32_e32 v178, v6, v178
	v_fmac_f32_e32 v178, v2, v179
	v_fmac_f32_e32 v178, v0, v180
	v_add_f32_e32 v31, v4, v178
	v_lshlrev_b32_e32 v181, 16, v181
	v_lshlrev_b32_e32 v182, 16, v182
	v_lshlrev_b32_e32 v183, 16, v183
	v_mul_f32_e32 v181, v6, v181
	v_fmac_f32_e32 v181, v2, v182
	v_fmac_f32_e32 v181, v0, v183
	v_add_f32_e32 v36, v4, v181
	v_lshlrev_b32_e32 v184, 16, v184
	v_lshlrev_b32_e32 v185, 16, v185
	v_lshlrev_b32_e32 v186, 16, v186
	v_mul_f32_e32 v184, v6, v184
	v_fmac_f32_e32 v184, v2, v185
	v_fmac_f32_e32 v184, v0, v186
	v_add_f32_e32 v30, v4, v184
	v_lshlrev_b32_e32 v187, 16, v187
	v_lshlrev_b32_e32 v188, 16, v188
	v_lshlrev_b32_e32 v189, 16, v189
	v_mul_f32_e32 v187, v6, v187
	v_fmac_f32_e32 v187, v2, v188
	v_fmac_f32_e32 v187, v0, v189
	v_add_f32_e32 v39, v4, v187
	v_lshlrev_b32_e32 v190, 16, v190
	v_lshlrev_b32_e32 v191, 16, v191
	v_lshlrev_b32_e32 v192, 16, v192
	v_mul_f32_e32 v190, v6, v190
	v_fmac_f32_e32 v190, v2, v191
	v_fmac_f32_e32 v190, v0, v192
	v_add_f32_e32 v41, v4, v190
	v_lshlrev_b32_e32 v193, 16, v193
	v_lshlrev_b32_e32 v194, 16, v194
	v_lshlrev_b32_e32 v195, 16, v195
	v_mul_f32_e32 v193, v6, v193
	v_fmac_f32_e32 v193, v2, v194
	v_fmac_f32_e32 v193, v0, v195
	v_add_f32_e32 v38, v4, v193
	v_lshlrev_b32_e32 v196, 16, v196
	v_lshlrev_b32_e32 v197, 16, v197
	v_lshlrev_b32_e32 v198, 16, v198
	v_mul_f32_e32 v196, v6, v196
	v_fmac_f32_e32 v196, v2, v197
	v_fmac_f32_e32 v196, v0, v198
	v_add_f32_e32 v40, v4, v196
	v_lshlrev_b32_e32 v199, 16, v199
	v_lshlrev_b32_e32 v200, 16, v200
	v_lshlrev_b32_e32 v201, 16, v201
	v_mul_f32_e32 v199, v6, v199
	v_fmac_f32_e32 v199, v2, v200
	v_fmac_f32_e32 v199, v0, v201
	v_add_f32_e32 v43, v4, v199
	v_lshlrev_b32_e32 v202, 16, v202
	v_lshlrev_b32_e32 v203, 16, v203
	v_lshlrev_b32_e32 v204, 16, v204
	v_mul_f32_e32 v202, v6, v202
	v_fmac_f32_e32 v202, v2, v203
	v_fmac_f32_e32 v202, v0, v204
	v_add_f32_e32 v45, v4, v202
	v_lshlrev_b32_e32 v205, 16, v205
	v_lshlrev_b32_e32 v206, 16, v206
	v_lshlrev_b32_e32 v207, 16, v207
	v_mul_f32_e32 v205, v6, v205
	v_fmac_f32_e32 v205, v2, v206
	v_fmac_f32_e32 v205, v0, v207
	v_add_f32_e32 v42, v4, v205
	v_lshlrev_b32_e32 v208, 16, v208
	v_lshlrev_b32_e32 v209, 16, v209
	v_lshlrev_b32_e32 v210, 16, v210
	v_mul_f32_e32 v208, v6, v208
	v_fmac_f32_e32 v208, v2, v209
	v_fmac_f32_e32 v208, v0, v210
	v_add_f32_e32 v44, v4, v208
	s_waitcnt vmcnt(0)
	v_lshlrev_b32_e32 v211, 16, v211
	v_lshlrev_b32_e32 v212, 16, v212
	v_lshlrev_b32_e32 v213, 16, v213
	v_mul_f32_e32 v211, v6, v211
	v_fmac_f32_e32 v211, v2, v212
	v_fmac_f32_e32 v211, v0, v213
	v_add_f32_e32 v47, v4, v211
	v_lshlrev_b32_e32 v221, 16, v221
	v_lshlrev_b32_e32 v222, 16, v222
	v_lshlrev_b32_e32 v223, 16, v223
	v_mul_f32_e32 v221, v6, v221
	v_fmac_f32_e32 v221, v2, v222
	v_fmac_f32_e32 v221, v0, v223
	v_add_f32_e32 v49, v4, v221
	v_lshlrev_b32_e32 v224, 16, v224
	v_lshlrev_b32_e32 v225, 16, v225
	v_lshlrev_b32_e32 v226, 16, v226
	v_mul_f32_e32 v224, v6, v224
	v_fmac_f32_e32 v224, v2, v225
	v_fmac_f32_e32 v224, v0, v226
	v_add_f32_e32 v46, v4, v224
	v_lshlrev_b32_e32 v227, 16, v227
	v_lshlrev_b32_e32 v228, 16, v228
	v_lshlrev_b32_e32 v229, 16, v229
	v_mul_f32_e32 v227, v6, v227
	v_fmac_f32_e32 v227, v2, v228
	v_fmac_f32_e32 v227, v0, v229
	v_add_f32_e32 v48, v4, v227
	v_lshlrev_b32_e32 v230, 16, v230
	v_lshlrev_b32_e32 v231, 16, v231
	v_lshlrev_b32_e32 v232, 16, v232
	v_mul_f32_e32 v230, v6, v230
	v_fmac_f32_e32 v230, v2, v231
	v_fmac_f32_e32 v230, v0, v232
	v_add_f32_e32 v51, v4, v230
	v_lshlrev_b32_e32 v233, 16, v233
	v_lshlrev_b32_e32 v234, 16, v234
	v_lshlrev_b32_e32 v235, 16, v235
	v_mul_f32_e32 v233, v6, v233
	v_fmac_f32_e32 v233, v2, v234
	v_fmac_f32_e32 v233, v0, v235
	v_add_f32_e32 v53, v4, v233
	v_lshlrev_b32_e32 v236, 16, v236
	v_lshlrev_b32_e32 v237, 16, v237
	v_lshlrev_b32_e32 v238, 16, v238
	v_mul_f32_e32 v236, v6, v236
	v_fmac_f32_e32 v236, v2, v237
	v_fmac_f32_e32 v236, v0, v238
	v_add_f32_e32 v50, v4, v236
	v_lshlrev_b32_e32 v239, 16, v239
	v_lshlrev_b32_e32 v240, 16, v240
	v_lshlrev_b32_e32 v241, 16, v241
	v_mul_f32_e32 v239, v6, v239
	v_fmac_f32_e32 v239, v2, v240
	v_fmac_f32_e32 v239, v0, v241
	v_add_f32_e32 v52, v4, v239
	v_lshlrev_b32_e32 v242, 16, v242
	v_lshlrev_b32_e32 v243, 16, v243
	v_lshlrev_b32_e32 v244, 16, v244
	v_mul_f32_e32 v242, v6, v242
	v_fmac_f32_e32 v242, v2, v243
	v_fmac_f32_e32 v242, v0, v244
	v_add_f32_e32 v55, v4, v242
	v_lshlrev_b32_e32 v245, 16, v245
	v_lshlrev_b32_e32 v246, 16, v246
	v_lshlrev_b32_e32 v247, 16, v247
	v_mul_f32_e32 v245, v6, v245
	v_fmac_f32_e32 v245, v2, v246
	v_fmac_f32_e32 v245, v0, v247
	v_add_f32_e32 v57, v4, v245
	v_lshlrev_b32_e32 v248, 16, v248
	v_lshlrev_b32_e32 v249, 16, v249
	v_lshlrev_b32_e32 v250, 16, v250
	v_mul_f32_e32 v248, v6, v248
	v_fmac_f32_e32 v248, v2, v249
	v_fmac_f32_e32 v248, v0, v250
	v_add_f32_e32 v54, v4, v248
	v_lshlrev_b32_e32 v251, 16, v251
	v_lshlrev_b32_e32 v253, 16, v253
	v_lshlrev_b32_e32 v254, 16, v254
	v_mul_f32_e32 v251, v6, v251
	v_fmac_f32_e32 v251, v2, v253
	v_fmac_f32_e32 v251, v0, v254
	v_add_f32_e32 v56, v4, v251
	v_lshlrev_b32_e32 v255, 16, v255
	v_lshlrev_b32_e32 v1, 16, v1
	v_lshlrev_b32_e32 v3, 16, v3
	v_mul_f32_e32 v255, v6, v255
	v_fmac_f32_e32 v255, v2, v1
	v_fmac_f32_e32 v255, v0, v3
	v_add_f32_e32 v59, v4, v255
	v_lshlrev_b32_e32 v5, 16, v5
	v_lshlrev_b32_e32 v7, 16, v7
	v_lshlrev_b32_e32 v16, 16, v16
	v_mul_f32_e32 v5, v6, v5
	v_fmac_f32_e32 v5, v2, v7
	v_fmac_f32_e32 v5, v0, v16
	v_add_f32_e32 v61, v4, v5
	v_lshlrev_b32_e32 v17, 16, v17
	v_lshlrev_b32_e32 v18, 16, v18
	v_lshlrev_b32_e32 v19, 16, v19
	v_mul_f32_e32 v19, v15, v19
	v_mul_f32_e32 v17, v6, v17
	v_fmac_f32_e32 v17, v2, v18
	v_fmac_f32_e32 v17, v0, v19
	v_add_f32_e32 v58, v4, v17
	v_lshlrev_b32_e32 v20, 16, v20
	v_lshlrev_b32_e32 v21, 16, v21
	v_lshlrev_b32_e32 v22, 16, v22
	v_mul_f32_e32 v22, v15, v22
	v_mul_f32_e32 v20, v6, v20
	v_fmac_f32_e32 v20, v2, v21
	v_fmac_f32_e32 v20, v0, v22
	v_add_f32_e32 v60, v4, v20
	v_readlane_b32 s0, v252, 43
	s_add_u32 s45, s0, s10
	v_readlane_b32 s0, v252, 42
	s_addc_u32 s24, s0, s11
	s_lshl_b64 s[0:1], s[62:63], 1
	v_readlane_b32 s4, v252, 60
	s_add_u32 s70, s4, s0
	v_readlane_b32 s0, v252, 61
	s_addc_u32 s71, s0, s1
	s_mov_b64 s[14:15], -1
	s_branch .LBB0_910

.LBB0_910:
	s_lshl_b32 s98, s16, 16
	s_mov_b32 s99, 0
	v_lshl_add_u64 v[196:197], s[98:99], 0, v[28:29]
	global_load_dwordx4 v[164:167], v[196:197], off offset:-4096
	global_load_dwordx4 v[168:171], v[196:197], off offset:-3072
	global_load_dwordx4 v[172:175], v[196:197], off offset:-2048
	global_load_dwordx4 v[176:179], v[196:197], off offset:-1024
	global_load_dwordx4 v[180:183], v[196:197], off
	global_load_dwordx4 v[184:187], v[196:197], off offset:1024
	global_load_dwordx4 v[188:191], v[196:197], off offset:2048
	global_load_dwordx4 v[192:195], v[196:197], off offset:3072
	v_mov_b32_e32 v20, v46
	v_mov_b32_e32 v21, v48
	v_mov_b32_e32 v22, v51
	v_mov_b32_e32 v23, v53
	v_pk_add_f32 v[88:89], v[20:21], 0 op_sel_hi:[1,0]
	v_pk_mul_f32 v[20:21], v[20:21], s[48:49] op_sel_hi:[1,0]
	v_xor_b32_e32 v91, 0x80000000, v46
	v_mov_b32_e32 v90, v48
	v_pk_add_f32 v[92:93], v[50:51], 0 neg_lo:[1,1] neg_hi:[1,1]
	v_mov_b32_e32 v24, v50
	v_mov_b32_e32 v25, v52
	v_pk_fma_f32 v[20:21], v[90:91], s[44:45], v[20:21] op_sel_hi:[1,0,1] neg_lo:[0,0,1] neg_hi:[0,0,1]
	v_pk_add_f32 v[90:91], v[22:23], 0 op_sel_hi:[1,0]
	v_pk_mul_f32 v[22:23], v[22:23], s[54:55] op_sel_hi:[1,0]
	v_mov_b32_e32 v92, v53
	v_mov_b32_e32 v26, v55
	v_mov_b32_e32 v27, v57
	v_pk_fma_f32 v[22:23], v[92:93], s[52:53], v[22:23] op_sel_hi:[1,0,1] neg_lo:[0,0,1] neg_hi:[0,0,1]
	v_pk_add_f32 v[92:93], v[24:25], 0 op_sel_hi:[1,0]
	v_pk_mul_f32 v[24:25], v[24:25], s[58:59] op_sel_hi:[1,0]
	v_xor_b32_e32 v95, 0x80000000, v50
	v_mov_b32_e32 v94, v52
	v_pk_add_f32 v[96:97], v[54:55], 0 neg_lo:[1,1] neg_hi:[1,1]
	v_mov_b32_e32 v64, v54
	v_mov_b32_e32 v65, v56
	v_pk_fma_f32 v[24:25], v[94:95], s[56:57], v[24:25] op_sel_hi:[1,0,1] neg_lo:[0,0,1] neg_hi:[0,0,1]
	v_pk_add_f32 v[94:95], v[26:27], 0 op_sel_hi:[1,0]
	v_pk_mul_f32 v[26:27], v[26:27], s[60:61] op_sel_hi:[1,0]
	v_mov_b32_e32 v96, v57
	v_mov_b32_e32 v66, v59
	v_mov_b32_e32 v67, v61
	v_pk_fma_f32 v[26:27], v[96:97], s[60:61], v[26:27] op_sel_hi:[1,0,1] neg_lo:[0,0,1] neg_hi:[0,0,1]
	v_pk_add_f32 v[96:97], v[64:65], 0 op_sel_hi:[1,0]
	v_pk_mul_f32 v[64:65], v[64:65], s[56:57] op_sel_hi:[1,0]
	v_xor_b32_e32 v99, 0x80000000, v54
	v_mov_b32_e32 v98, v56
	v_pk_add_f32 v[100:101], v[58:59], 0 neg_lo:[1,1] neg_hi:[1,1]
	v_mov_b32_e32 v2, v32
	v_mov_b32_e32 v3, v34
	v_mov_b32_e32 v4, v33
	v_mov_b32_e32 v5, v35
	v_mov_b32_e32 v18, v47
	v_mov_b32_e32 v19, v49
	v_mov_b32_e32 v68, v58
	v_mov_b32_e32 v69, v60
	v_pk_fma_f32 v[64:65], v[98:99], s[58:59], v[64:65] op_sel_hi:[1,0,1] neg_lo:[0,0,1] neg_hi:[0,0,1]
	v_pk_add_f32 v[98:99], v[66:67], 0 op_sel_hi:[1,0]
	v_pk_mul_f32 v[66:67], v[66:67], s[52:53] op_sel_hi:[1,0]
	v_mov_b32_e32 v100, v61
	v_pk_add_f32 v[70:71], v[2:3], 0 op_sel_hi:[1,0]
	v_pk_add_f32 v[72:73], v[4:5], 0 op_sel_hi:[1,0]
	v_pk_add_f32 v[74:75], v[32:33], 0 neg_lo:[1,1] neg_hi:[1,1]
	v_pk_add_f32 v[18:19], v[18:19], 0 op_sel_hi:[1,0]
	v_pk_fma_f32 v[66:67], v[100:101], s[54:55], v[66:67] op_sel_hi:[1,0,1] neg_lo:[0,0,1] neg_hi:[0,0,1]
	v_pk_add_f32 v[100:101], v[68:69], 0 op_sel_hi:[1,0]
	v_pk_mul_f32 v[68:69], v[68:69], s[44:45] op_sel_hi:[1,0]
	v_xor_b32_e32 v103, 0x80000000, v58
	v_mov_b32_e32 v102, v60
	v_mov_b32_e32 v74, v35
	v_pk_fma_f32 v[68:69], v[102:103], s[48:49], v[68:69] op_sel_hi:[1,0,1] neg_lo:[0,0,1] neg_hi:[0,0,1]
	v_pk_add_f32 v[102:103], v[18:19], v[70:71]
	v_pk_add_f32 v[18:19], v[70:71], v[18:19] neg_lo:[0,1] neg_hi:[0,1]
	v_pk_add_f32 v[70:71], v[88:89], v[72:73]
	v_pk_add_f32 v[72:73], v[72:73], v[88:89] neg_lo:[0,1] neg_hi:[0,1]
	v_mov_b32_e32 v6, v37
	v_mov_b32_e32 v7, v31
	v_pk_mul_f32 v[74:75], v[74:75], s[48:49] op_sel_hi:[1,0]
	s_nop 0
	v_pk_fma_f32 v[4:5], v[4:5], s[44:45], v[74:75] op_sel_hi:[1,0,1]
	v_pk_add_f32 v[74:75], v[6:7], 0 op_sel_hi:[1,0]
	v_pk_add_f32 v[76:77], v[36:37], 0 neg_lo:[1,1] neg_hi:[1,1]
	v_pk_mul_f32 v[88:89], v[72:73], s[54:55] op_sel:[1,0] op_sel_hi:[0,0] neg_hi:[1,0]
	v_mov_b32_e32 v76, v31
	v_pk_fma_f32 v[72:73], v[72:73], s[52:53], v[88:89] op_sel_hi:[1,0,1]
	v_pk_add_f32 v[88:89], v[90:91], v[74:75]
	v_pk_add_f32 v[74:75], v[74:75], v[90:91] neg_lo:[0,1] neg_hi:[0,1]
	v_mov_b32_e32 v8, v36
	v_mov_b32_e32 v9, v30
	v_pk_mul_f32 v[76:77], v[76:77], s[54:55] op_sel_hi:[1,0]
	s_nop 0
	v_pk_fma_f32 v[6:7], v[6:7], s[52:53], v[76:77] op_sel_hi:[1,0,1]
	v_pk_add_f32 v[76:77], v[8:9], 0 op_sel_hi:[1,0]
	v_pk_mul_f32 v[90:91], v[74:75], s[60:61] op_sel:[1,0] op_sel_hi:[0,0] neg_hi:[1,0]
	v_xor_b32_e32 v79, 0x80000000, v36
	v_mov_b32_e32 v78, v30
	v_pk_add_f32 v[80:81], v[38:39], 0 neg_lo:[1,1] neg_hi:[1,1]
	v_pk_fma_f32 v[74:75], v[74:75], s[60:61], v[90:91] op_sel_hi:[1,0,1]
	v_pk_add_f32 v[90:91], v[92:93], v[76:77]
	v_pk_add_f32 v[76:77], v[76:77], v[92:93] neg_lo:[0,1] neg_hi:[0,1]
	v_mov_b32_e32 v10, v39
	v_mov_b32_e32 v11, v41
	v_pk_mul_f32 v[78:79], v[78:79], s[58:59] op_sel_hi:[1,0]
	v_mov_b32_e32 v80, v41
	v_mov_b32_e32 v12, v38
	v_mov_b32_e32 v13, v40
	v_pk_fma_f32 v[8:9], v[8:9], s[56:57], v[78:79] op_sel_hi:[1,0,1]
	v_pk_add_f32 v[78:79], v[10:11], 0 op_sel_hi:[1,0]
	v_pk_mul_f32 v[80:81], v[80:81], s[60:61] op_sel_hi:[1,0]
	v_pk_mul_f32 v[92:93], v[76:77], s[52:53] op_sel:[1,0] op_sel_hi:[0,0] neg_hi:[1,0]
	v_pk_fma_f32 v[10:11], v[10:11], s[60:61], v[80:81] op_sel_hi:[1,0,1]
	v_pk_add_f32 v[80:81], v[12:13], 0 op_sel_hi:[1,0]
	v_xor_b32_e32 v83, 0x80000000, v38
	v_mov_b32_e32 v82, v40
	v_pk_fma_f32 v[76:77], v[76:77], s[54:55], v[92:93] op_sel_hi:[1,0,1]
	v_pk_add_f32 v[92:93], v[94:95], v[78:79]
	v_pk_add_f32 v[78:79], v[78:79], v[94:95] neg_lo:[0,1] neg_hi:[0,1]
	v_mov_b32_e32 v14, v43
	v_mov_b32_e32 v15, v45
	v_pk_mul_f32 v[82:83], v[82:83], s[56:57] op_sel_hi:[1,0]
	v_pk_add_f32 v[84:85], v[42:43], 0 neg_lo:[1,1] neg_hi:[1,1]
	v_xor_b32_e32 v95, 0x80000000, v78
	v_mov_b32_e32 v94, v79
	v_pk_add_f32 v[78:79], v[96:97], v[80:81]
	v_pk_add_f32 v[80:81], v[80:81], v[96:97] neg_lo:[0,1] neg_hi:[0,1]
	v_pk_fma_f32 v[12:13], v[12:13], s[58:59], v[82:83] op_sel_hi:[1,0,1]
	v_pk_add_f32 v[82:83], v[14:15], 0 op_sel_hi:[1,0]
	v_mov_b32_e32 v84, v45
	v_pk_mul_f32 v[96:97], v[80:81], s[54:55] op_sel_hi:[1,0]
	v_xor_b32_e32 v105, 0x80000000, v80
	v_mov_b32_e32 v104, v81
	v_mov_b32_e32 v16, v42
	v_mov_b32_e32 v17, v44
	v_pk_mul_f32 v[84:85], v[84:85], s[52:53] op_sel_hi:[1,0]
	v_xor_b32_e32 v87, 0x80000000, v42
	v_mov_b32_e32 v86, v44
	v_pk_fma_f32 v[80:81], v[104:105], s[52:53], v[96:97] op_sel_hi:[1,0,1] neg_lo:[0,0,1] neg_hi:[0,0,1]
	v_pk_add_f32 v[96:97], v[98:99], v[82:83]
	v_pk_add_f32 v[82:83], v[82:83], v[98:99] neg_lo:[0,1] neg_hi:[0,1]
	v_pk_fma_f32 v[14:15], v[14:15], s[54:55], v[84:85] op_sel_hi:[1,0,1]
	v_pk_add_f32 v[84:85], v[16:17], 0 op_sel_hi:[1,0]
	v_pk_mul_f32 v[86:87], v[86:87], s[44:45] op_sel_hi:[1,0]
	v_pk_mul_f32 v[98:99], v[82:83], s[60:61] op_sel_hi:[1,0]
	v_xor_b32_e32 v105, 0x80000000, v82
	v_mov_b32_e32 v104, v83
	v_pk_fma_f32 v[16:17], v[16:17], s[48:49], v[86:87] op_sel_hi:[1,0,1]
	v_pk_add_f32 v[86:87], v[46:47], 0 neg_lo:[1,1] neg_hi:[1,1]
	v_pk_fma_f32 v[82:83], v[104:105], s[60:61], v[98:99] op_sel_hi:[1,0,1] neg_lo:[0,0,1] neg_hi:[0,0,1]
	v_pk_add_f32 v[98:99], v[100:101], v[84:85]
	v_pk_add_f32 v[84:85], v[84:85], v[100:101] neg_lo:[0,1] neg_hi:[0,1]
	v_mov_b32_e32 v86, v49
	v_pk_mul_f32 v[100:101], v[84:85], s[52:53] op_sel_hi:[1,0]
	v_xor_b32_e32 v105, 0x80000000, v84
	v_mov_b32_e32 v104, v85
	v_pk_fma_f32 v[84:85], v[104:105], s[54:55], v[100:101] op_sel_hi:[1,0,1] neg_lo:[0,0,1] neg_hi:[0,0,1]
	v_pk_add_f32 v[100:101], v[86:87], v[2:3]
	v_pk_add_f32 v[2:3], v[2:3], v[86:87] neg_lo:[0,1] neg_hi:[0,1]
	v_pk_add_f32 v[86:87], v[20:21], v[4:5]
	v_pk_add_f32 v[4:5], v[4:5], v[20:21] neg_lo:[0,1] neg_hi:[0,1]
	v_mov_b32_e32 v63, v146
	v_pk_mul_f32 v[20:21], v[4:5], s[54:55] op_sel:[1,0] op_sel_hi:[0,0] neg_hi:[1,0]
	s_nop 0
	v_pk_fma_f32 v[4:5], v[4:5], s[52:53], v[20:21] op_sel_hi:[1,0,1]
	v_pk_add_f32 v[20:21], v[22:23], v[6:7]
	v_pk_add_f32 v[6:7], v[6:7], v[22:23] neg_lo:[0,1] neg_hi:[0,1]
	s_barrier
	v_pk_mul_f32 v[22:23], v[6:7], s[60:61] op_sel:[1,0] op_sel_hi:[0,0] neg_hi:[1,0]
	s_nop 0
	v_pk_fma_f32 v[6:7], v[6:7], s[60:61], v[22:23] op_sel_hi:[1,0,1]
	v_pk_add_f32 v[22:23], v[24:25], v[8:9]
	v_pk_add_f32 v[8:9], v[8:9], v[24:25] neg_lo:[0,1] neg_hi:[0,1]
	s_add_i32 s19, 16, 0x11000
	v_pk_mul_f32 v[24:25], v[8:9], s[52:53] op_sel:[1,0] op_sel_hi:[0,0] neg_hi:[1,0]
	s_add_i32 s18, 16, 0x12000
	v_pk_fma_f32 v[8:9], v[8:9], s[54:55], v[24:25] op_sel_hi:[1,0,1]
	v_pk_add_f32 v[24:25], v[26:27], v[10:11]
	v_pk_add_f32 v[10:11], v[10:11], v[26:27] neg_lo:[0,1] neg_hi:[0,1]
	s_add_i32 s17, 16, 0x13000
	v_xor_b32_e32 v27, 0x80000000, v10
	v_mov_b32_e32 v26, v11
	v_pk_add_f32 v[10:11], v[64:65], v[12:13]
	v_pk_add_f32 v[12:13], v[12:13], v[64:65] neg_lo:[0,1] neg_hi:[0,1]
	s_add_i32 s13, 16, 0x14000
	v_pk_mul_f32 v[64:65], v[12:13], s[54:55] op_sel_hi:[1,0]
	v_xor_b32_e32 v105, 0x80000000, v12
	v_mov_b32_e32 v104, v13
	v_pk_fma_f32 v[12:13], v[104:105], s[52:53], v[64:65] op_sel_hi:[1,0,1] neg_lo:[0,0,1] neg_hi:[0,0,1]
	v_pk_add_f32 v[64:65], v[66:67], v[14:15]
	v_pk_add_f32 v[14:15], v[14:15], v[66:67] neg_lo:[0,1] neg_hi:[0,1]
	s_add_i32 s12, 16, 0x15000
	v_pk_mul_f32 v[66:67], v[14:15], s[60:61] op_sel_hi:[1,0]
	v_xor_b32_e32 v105, 0x80000000, v14
	v_mov_b32_e32 v104, v15
	v_pk_fma_f32 v[14:15], v[104:105], s[60:61], v[66:67] op_sel_hi:[1,0,1] neg_lo:[0,0,1] neg_hi:[0,0,1]
	v_pk_add_f32 v[66:67], v[68:69], v[16:17]
	v_pk_add_f32 v[16:17], v[16:17], v[68:69] neg_lo:[0,1] neg_hi:[0,1]
	s_add_i32 s11, 16, 0x16000
	v_pk_mul_f32 v[68:69], v[16:17], s[52:53] op_sel_hi:[1,0]
	v_xor_b32_e32 v105, 0x80000000, v16
	v_mov_b32_e32 v104, v17
	v_pk_fma_f32 v[16:17], v[104:105], s[54:55], v[68:69] op_sel_hi:[1,0,1] neg_lo:[0,0,1] neg_hi:[0,0,1]
	v_pk_add_f32 v[68:69], v[92:93], v[102:103]
	v_pk_add_f32 v[92:93], v[102:103], v[92:93] neg_lo:[0,1] neg_hi:[0,1]
	v_pk_add_f32 v[102:103], v[78:79], v[70:71]
	v_pk_add_f32 v[70:71], v[70:71], v[78:79] neg_lo:[0,1] neg_hi:[0,1]
	s_add_i32 s10, 16, 0x17000
	v_pk_mul_f32 v[78:79], v[70:71], s[60:61] op_sel:[1,0] op_sel_hi:[0,0] neg_hi:[1,0]
	s_add_i32 s9, 16, 0x18000
	v_pk_fma_f32 v[70:71], v[70:71], s[60:61], v[78:79] op_sel_hi:[1,0,1]
	v_pk_add_f32 v[78:79], v[96:97], v[88:89]
	v_pk_add_f32 v[88:89], v[88:89], v[96:97] neg_lo:[0,1] neg_hi:[0,1]
	s_add_i32 s8, 16, 0x19000
	v_xor_b32_e32 v97, 0x80000000, v88
	v_mov_b32_e32 v96, v89
	v_pk_add_f32 v[88:89], v[98:99], v[90:91]
	v_pk_add_f32 v[90:91], v[90:91], v[98:99] neg_lo:[0,1] neg_hi:[0,1]
	s_add_i32 s7, 16, 0x1a000
	v_pk_mul_f32 v[98:99], v[90:91], s[60:61] op_sel_hi:[1,0]
	v_xor_b32_e32 v105, 0x80000000, v90
	v_mov_b32_e32 v104, v91
	v_pk_fma_f32 v[90:91], v[104:105], s[60:61], v[98:99] op_sel_hi:[1,0,1] neg_lo:[0,0,1] neg_hi:[0,0,1]
	v_pk_add_f32 v[98:99], v[94:95], v[18:19]
	v_pk_add_f32 v[18:19], v[18:19], v[94:95] neg_lo:[0,1] neg_hi:[0,1]
	v_pk_add_f32 v[94:95], v[80:81], v[72:73]
	v_pk_add_f32 v[72:73], v[72:73], v[80:81] neg_lo:[0,1] neg_hi:[0,1]
	s_add_i32 s6, 16, 0x1b000
	v_pk_mul_f32 v[80:81], v[72:73], s[60:61] op_sel:[1,0] op_sel_hi:[0,0] neg_hi:[1,0]
	s_add_i32 s5, 16, 0x1c000
	v_pk_fma_f32 v[72:73], v[72:73], s[60:61], v[80:81] op_sel_hi:[1,0,1]
	v_pk_add_f32 v[80:81], v[82:83], v[74:75]
	v_pk_add_f32 v[74:75], v[74:75], v[82:83] neg_lo:[0,1] neg_hi:[0,1]
	s_add_i32 s4, 16, 0x1d000
	v_xor_b32_e32 v83, 0x80000000, v74
	v_mov_b32_e32 v82, v75
	v_pk_add_f32 v[74:75], v[84:85], v[76:77]
	v_pk_add_f32 v[76:77], v[76:77], v[84:85] neg_lo:[0,1] neg_hi:[0,1]
	v_pk_add_f32 v[106:107], v[18:19], v[82:83]
	v_pk_mul_f32 v[84:85], v[76:77], s[60:61] op_sel_hi:[1,0]
	v_xor_b32_e32 v105, 0x80000000, v76
	v_mov_b32_e32 v104, v77
	v_pk_fma_f32 v[76:77], v[104:105], s[60:61], v[84:85] op_sel_hi:[1,0,1] neg_lo:[0,0,1] neg_hi:[0,0,1]
	v_pk_add_f32 v[84:85], v[24:25], v[100:101]
	v_pk_add_f32 v[24:25], v[100:101], v[24:25] neg_lo:[0,1] neg_hi:[0,1]
	v_pk_add_f32 v[100:101], v[10:11], v[86:87]
	v_pk_add_f32 v[10:11], v[86:87], v[10:11] neg_lo:[0,1] neg_hi:[0,1]
	v_pk_add_f32 v[18:19], v[18:19], v[82:83] neg_lo:[0,1] neg_hi:[0,1]
	v_pk_mul_f32 v[86:87], v[10:11], s[60:61] op_sel:[1,0] op_sel_hi:[0,0] neg_hi:[1,0]
	v_pk_add_f32 v[82:83], v[76:77], v[72:73]
	v_pk_fma_f32 v[10:11], v[10:11], s[60:61], v[86:87] op_sel_hi:[1,0,1]
	v_pk_add_f32 v[86:87], v[64:65], v[20:21]
	v_pk_add_f32 v[20:21], v[20:21], v[64:65] neg_lo:[0,1] neg_hi:[0,1]
	v_pk_add_f32 v[72:73], v[72:73], v[76:77] neg_lo:[0,1] neg_hi:[0,1]
	v_xor_b32_e32 v65, 0x80000000, v20
	v_mov_b32_e32 v64, v21
	v_pk_add_f32 v[20:21], v[66:67], v[22:23]
	v_pk_add_f32 v[22:23], v[22:23], v[66:67] neg_lo:[0,1] neg_hi:[0,1]
	v_xor_b32_e32 v77, 0x80000000, v72
	v_pk_mul_f32 v[66:67], v[22:23], s[60:61] op_sel_hi:[1,0]
	v_xor_b32_e32 v105, 0x80000000, v22
	v_mov_b32_e32 v104, v23
	v_pk_fma_f32 v[22:23], v[104:105], s[60:61], v[66:67] op_sel_hi:[1,0,1] neg_lo:[0,0,1] neg_hi:[0,0,1]
	v_pk_add_f32 v[66:67], v[2:3], v[26:27]
	v_pk_add_f32 v[2:3], v[2:3], v[26:27] neg_lo:[0,1] neg_hi:[0,1]
	v_pk_add_f32 v[26:27], v[12:13], v[4:5]
	v_pk_add_f32 v[4:5], v[4:5], v[12:13] neg_lo:[0,1] neg_hi:[0,1]
	v_mov_b32_e32 v76, v73
	v_pk_mul_f32 v[12:13], v[4:5], s[60:61] op_sel:[1,0] op_sel_hi:[0,0] neg_hi:[1,0]
	v_pk_add_f32 v[72:73], v[84:85], v[86:87]
	v_pk_fma_f32 v[4:5], v[4:5], s[60:61], v[12:13] op_sel_hi:[1,0,1]
	v_pk_add_f32 v[12:13], v[14:15], v[6:7]
	v_pk_add_f32 v[6:7], v[6:7], v[14:15] neg_lo:[0,1] neg_hi:[0,1]
	v_pk_add_f32 v[84:85], v[84:85], v[86:87] neg_lo:[0,1] neg_hi:[0,1]
	v_xor_b32_e32 v15, 0x80000000, v6
	v_mov_b32_e32 v14, v7
	v_pk_add_f32 v[6:7], v[16:17], v[8:9]
	v_pk_add_f32 v[8:9], v[8:9], v[16:17] neg_lo:[0,1] neg_hi:[0,1]
	v_pk_add_f32 v[86:87], v[20:21], v[100:101]
	v_pk_mul_f32 v[16:17], v[8:9], s[60:61] op_sel_hi:[1,0]
	s_nop 0
	v_pk_fma_f32 v[8:9], v[8:9], s[60:61], v[16:17] op_sel:[1,0,0] op_sel_hi:[0,0,1] neg_lo:[0,0,1] neg_hi:[1,0,1]
	v_pk_add_f32 v[104:105], v[92:93], v[96:97]
	v_pk_add_f32 v[92:93], v[92:93], v[96:97] neg_lo:[0,1] neg_hi:[0,1]
	v_pk_add_f32 v[96:97], v[90:91], v[70:71]
	v_pk_add_f32 v[70:71], v[70:71], v[90:91] neg_lo:[0,1] neg_hi:[0,1]
	v_pk_add_f32 v[16:17], v[78:79], v[68:69]
	v_pk_add_f32 v[68:69], v[68:69], v[78:79] neg_lo:[0,1] neg_hi:[0,1]
	v_pk_add_f32 v[78:79], v[88:89], v[102:103]
	v_pk_add_f32 v[88:89], v[102:103], v[88:89] neg_lo:[0,1] neg_hi:[0,1]
	v_xor_b32_e32 v91, 0x80000000, v70
	v_mov_b32_e32 v90, v71
	v_pk_add_f32 v[70:71], v[98:99], v[80:81]
	v_pk_add_f32 v[98:99], v[98:99], v[80:81] neg_lo:[0,1] neg_hi:[0,1]
	v_pk_add_f32 v[80:81], v[74:75], v[94:95]
	v_pk_add_f32 v[74:75], v[94:95], v[74:75] neg_lo:[0,1] neg_hi:[0,1]
	v_pk_add_f32 v[20:21], v[100:101], v[20:21] neg_lo:[0,1] neg_hi:[0,1]
	v_pk_add_f32 v[108:109], v[24:25], v[64:65]
	v_pk_add_f32 v[24:25], v[24:25], v[64:65] neg_lo:[0,1] neg_hi:[0,1]
	v_pk_add_f32 v[64:65], v[22:23], v[10:11]
	v_pk_add_f32 v[10:11], v[10:11], v[22:23] neg_lo:[0,1] neg_hi:[0,1]
	v_pk_add_f32 v[114:115], v[6:7], v[26:27]
	v_pk_add_f32 v[6:7], v[26:27], v[6:7] neg_lo:[0,1] neg_hi:[0,1]
	v_xor_b32_e32 v103, 0x80000000, v88
	v_mov_b32_e32 v102, v89
	v_xor_b32_e32 v95, 0x80000000, v74
	v_mov_b32_e32 v94, v75
	v_xor_b32_e32 v101, 0x80000000, v20
	v_mov_b32_e32 v100, v21
	v_xor_b32_e32 v27, 0x80000000, v6
	v_mov_b32_e32 v26, v7
	v_pk_add_f32 v[6:7], v[2:3], v[14:15]
	v_pk_add_f32 v[116:117], v[2:3], v[14:15] neg_lo:[0,1] neg_hi:[0,1]
	v_pk_add_f32 v[2:3], v[4:5], v[8:9] neg_lo:[0,1] neg_hi:[0,1]
	v_pk_add_f32 v[112:113], v[66:67], v[12:13]
	v_pk_add_f32 v[66:67], v[66:67], v[12:13] neg_lo:[0,1] neg_hi:[0,1]
	v_pk_add_f32 v[118:119], v[8:9], v[4:5]
	v_xor_b32_e32 v121, 0x80000000, v2
	v_mov_b32_e32 v120, v3
	v_pk_add_f32 v[2:3], v[78:79], v[16:17]
	v_pk_add_f32 v[88:89], v[16:17], v[78:79] neg_lo:[0,1] neg_hi:[0,1]
	v_pk_add_f32 v[122:123], v[68:69], v[102:103]
	v_pk_add_f32 v[20:21], v[68:69], v[102:103] neg_lo:[0,1] neg_hi:[0,1]
	v_pk_add_f32 v[78:79], v[104:105], v[96:97]
	v_pk_add_f32 v[74:75], v[104:105], v[96:97] neg_lo:[0,1] neg_hi:[0,1]
	v_pk_add_f32 v[96:97], v[92:93], v[90:91]
	v_pk_add_f32 v[8:9], v[92:93], v[90:91] neg_lo:[0,1] neg_hi:[0,1]
	v_pk_add_f32 v[102:103], v[98:99], v[94:95]
	v_pk_add_f32 v[12:13], v[98:99], v[94:95] neg_lo:[0,1] neg_hi:[0,1]
	v_pk_add_f32 v[98:99], v[18:19], v[76:77]
	v_pk_add_f32 v[4:5], v[18:19], v[76:77] neg_lo:[0,1] neg_hi:[0,1]
	v_pk_add_f32 v[18:19], v[72:73], v[86:87]
	v_pk_add_f32 v[92:93], v[72:73], v[86:87] neg_lo:[0,1] neg_hi:[0,1]
	v_pk_add_f32 v[86:87], v[84:85], v[100:101]
	v_pk_add_f32 v[22:23], v[84:85], v[100:101] neg_lo:[0,1] neg_hi:[0,1]
	v_pk_add_f32 v[100:101], v[24:25], v[10:11] op_sel:[0,1] op_sel_hi:[1,0] neg_hi:[0,1]
	v_pk_add_f32 v[10:11], v[24:25], v[10:11] op_sel:[0,1] op_sel_hi:[1,0] neg_lo:[0,1]
	v_mov_b32_e32 v24, v63
	v_pk_add_f32 v[84:85], v[108:109], v[64:65]
	v_cvt_f32_i32_e32 v24, v24
	v_pk_add_f32 v[76:77], v[108:109], v[64:65] neg_lo:[0,1] neg_hi:[0,1]
	v_pk_add_f32 v[104:105], v[66:67], v[26:27]
	v_pk_add_f32 v[14:15], v[66:67], v[26:27] neg_lo:[0,1] neg_hi:[0,1]
	v_mul_f32_e32 v25, 0x38800000, v24
	v_cos_f32_e32 v24, v25
	v_sin_f32_e32 v25, v25
	s_nop 0
	s_nop 0
	v_add_f32_e32 v62, v24, v24
	v_pk_mul_f32 v[26:27], v[24:25], v[24:25]
	v_mul_f32_e32 v62, v25, v62
	s_nop 0
	s_nop 0
	v_mov_b32_e32 v108, v25
	v_pk_add_f32 v[26:27], v[26:27], v[26:27] op_sel:[0,1] op_sel_hi:[0,1] neg_lo:[0,1] neg_hi:[0,1]
	v_pk_mul_f32 v[72:73], v[24:25], v[62:63] op_sel:[1,0] op_sel_hi:[0,0] neg_lo:[1,0]
	v_pk_mul_f32 v[94:95], v[18:19], v[108:109] op_sel:[1,0] op_sel_hi:[0,0] neg_hi:[1,0]
	v_pk_add_f32 v[16:17], v[70:71], v[80:81]
	v_pk_fma_f32 v[72:73], v[24:25], v[26:27], v[72:73]
	v_pk_fma_f32 v[18:19], v[18:19], v[24:25], v[94:95] op_sel_hi:[1,0,1]
	v_pk_mul_f32 v[24:25], v[62:63], s[46:47] op_sel_hi:[0,1]
	v_pk_fma_f32 v[94:95], v[26:27], s[40:41], v[24:25]
	s_nop 0
	v_pk_mul_f32 v[24:25], v[16:17], v[94:95] op_sel:[1,1] op_sel_hi:[0,1] neg_hi:[1,0]
	v_pk_add_f32 v[64:65], v[112:113], v[114:115]
	v_pk_fma_f32 v[24:25], v[16:17], v[94:95], v[24:25] op_sel_hi:[1,0,1]
	v_pk_mul_f32 v[16:17], v[62:63], v[72:73] op_sel:[0,1] op_sel_hi:[0,0] neg_lo:[0,1]
	v_pk_fma_f32 v[108:109], v[26:27], v[72:73], v[16:17]
	v_pk_mul_f32 v[16:17], v[64:65], v[72:73] op_sel:[1,1] op_sel_hi:[0,1] neg_hi:[1,0]
	v_pk_add_f32 v[90:91], v[106:107], v[82:83]
	v_pk_fma_f32 v[16:17], v[64:65], v[72:73], v[16:17] op_sel_hi:[1,0,1]
	v_pk_mul_f32 v[64:65], v[62:63], v[94:95] op_sel:[0,1] op_sel_hi:[0,0] neg_lo:[0,1]
	v_pk_fma_f32 v[94:95], v[26:27], v[94:95], v[64:65]
	s_nop 0
	v_pk_mul_f32 v[64:65], v[78:79], v[94:95] op_sel:[1,1] op_sel_hi:[0,1] neg_hi:[1,0]
	v_pk_add_f32 v[66:67], v[6:7], v[118:119]
	v_pk_fma_f32 v[72:73], v[78:79], v[94:95], v[64:65] op_sel_hi:[1,0,1]
	v_pk_mul_f32 v[64:65], v[62:63], v[108:109] op_sel:[0,1] op_sel_hi:[0,0] neg_lo:[0,1]
	v_pk_fma_f32 v[110:111], v[26:27], v[108:109], v[64:65]
	v_pk_mul_f32 v[64:65], v[84:85], v[108:109] op_sel:[1,1] op_sel_hi:[0,1] neg_hi:[1,0]
	v_pk_mul_f32 v[78:79], v[62:63], v[94:95] op_sel:[0,1] op_sel_hi:[0,0] neg_lo:[0,1]
	v_pk_fma_f32 v[64:65], v[84:85], v[108:109], v[64:65] op_sel_hi:[1,0,1]
	v_pk_fma_f32 v[84:85], v[26:27], v[94:95], v[78:79]
	s_nop 0
	v_pk_mul_f32 v[78:79], v[90:91], v[84:85] op_sel:[1,1] op_sel_hi:[0,1] neg_hi:[1,0]
	v_pk_add_f32 v[68:69], v[106:107], v[82:83] neg_lo:[0,1] neg_hi:[0,1]
	v_pk_fma_f32 v[78:79], v[90:91], v[84:85], v[78:79] op_sel_hi:[1,0,1]
	v_pk_mul_f32 v[90:91], v[62:63], v[110:111] op_sel:[0,1] op_sel_hi:[0,0] neg_lo:[0,1]
	v_pk_fma_f32 v[94:95], v[26:27], v[110:111], v[90:91]
	v_pk_mul_f32 v[90:91], v[66:67], v[110:111] op_sel:[1,1] op_sel_hi:[0,1] neg_hi:[1,0]
	v_pk_add_f32 v[106:107], v[116:117], v[120:121]
	v_pk_fma_f32 v[66:67], v[66:67], v[110:111], v[90:91] op_sel_hi:[1,0,1]
	v_pk_mul_f32 v[90:91], v[62:63], v[84:85] op_sel:[0,1] op_sel_hi:[0,0] neg_lo:[0,1]
	v_pk_fma_f32 v[108:109], v[26:27], v[84:85], v[90:91]
	s_nop 0
	v_pk_mul_f32 v[84:85], v[122:123], v[108:109] op_sel:[1,1] op_sel_hi:[0,1] neg_hi:[1,0]
	v_pk_add_f32 v[80:81], v[70:71], v[80:81] neg_lo:[0,1] neg_hi:[0,1]
	v_pk_fma_f32 v[90:91], v[122:123], v[108:109], v[84:85] op_sel_hi:[1,0,1]
	v_pk_mul_f32 v[84:85], v[62:63], v[94:95] op_sel:[0,1] op_sel_hi:[0,0] neg_lo:[0,1]
	v_pk_fma_f32 v[110:111], v[26:27], v[94:95], v[84:85]
	v_pk_mul_f32 v[84:85], v[86:87], v[94:95] op_sel:[1,1] op_sel_hi:[0,1] neg_hi:[1,0]
	v_pk_add_f32 v[82:83], v[112:113], v[114:115] neg_lo:[0,1] neg_hi:[0,1]
	v_pk_fma_f32 v[84:85], v[86:87], v[94:95], v[84:85] op_sel_hi:[1,0,1]
	v_pk_mul_f32 v[86:87], v[62:63], v[108:109] op_sel:[0,1] op_sel_hi:[0,0] neg_lo:[0,1]
	v_pk_fma_f32 v[108:109], v[26:27], v[108:109], v[86:87]
	s_nop 0
	v_pk_mul_f32 v[86:87], v[102:103], v[108:109] op_sel:[1,1] op_sel_hi:[0,1] neg_hi:[1,0]
	v_pk_add_f32 v[70:71], v[6:7], v[118:119] neg_lo:[0,1] neg_hi:[0,1]
	v_pk_fma_f32 v[94:95], v[102:103], v[108:109], v[86:87] op_sel_hi:[1,0,1]
	v_pk_mul_f32 v[86:87], v[62:63], v[110:111] op_sel:[0,1] op_sel_hi:[0,0] neg_lo:[0,1]
	v_pk_fma_f32 v[102:103], v[26:27], v[110:111], v[86:87]
	v_pk_mul_f32 v[86:87], v[104:105], v[110:111] op_sel:[1,1] op_sel_hi:[0,1] neg_hi:[1,0]
	v_pk_add_f32 v[6:7], v[116:117], v[120:121] neg_lo:[0,1] neg_hi:[0,1]
	v_pk_fma_f32 v[86:87], v[104:105], v[110:111], v[86:87] op_sel_hi:[1,0,1]
	v_pk_mul_f32 v[104:105], v[62:63], v[108:109] op_sel:[0,1] op_sel_hi:[0,0] neg_lo:[0,1]
	v_pk_fma_f32 v[104:105], v[26:27], v[108:109], v[104:105]
	s_nop 0
	v_pk_mul_f32 v[108:109], v[96:97], v[104:105] op_sel:[1,1] op_sel_hi:[0,1] neg_hi:[1,0]
	s_nop 0
	v_pk_fma_f32 v[96:97], v[96:97], v[104:105], v[108:109] op_sel_hi:[1,0,1]
	v_pk_mul_f32 v[108:109], v[62:63], v[102:103] op_sel:[0,1] op_sel_hi:[0,0] neg_lo:[0,1]
	v_pk_mul_f32 v[110:111], v[100:101], v[102:103] op_sel:[1,1] op_sel_hi:[0,1] neg_hi:[1,0]
	v_pk_fma_f32 v[108:109], v[26:27], v[102:103], v[108:109]
	v_pk_fma_f32 v[100:101], v[100:101], v[102:103], v[110:111] op_sel_hi:[1,0,1]
	v_pk_mul_f32 v[102:103], v[62:63], v[104:105] op_sel:[0,1] op_sel_hi:[0,0] neg_lo:[0,1]
	v_pk_fma_f32 v[102:103], v[26:27], v[104:105], v[102:103]
	s_nop 0
	v_pk_mul_f32 v[104:105], v[98:99], v[102:103] op_sel:[1,1] op_sel_hi:[0,1] neg_hi:[1,0]
	s_nop 0
	v_pk_fma_f32 v[98:99], v[98:99], v[102:103], v[104:105] op_sel_hi:[1,0,1]
	v_pk_mul_f32 v[104:105], v[62:63], v[108:109] op_sel:[0,1] op_sel_hi:[0,0] neg_lo:[0,1]
	v_pk_mul_f32 v[110:111], v[106:107], v[108:109] op_sel:[1,1] op_sel_hi:[0,1] neg_hi:[1,0]
	v_pk_fma_f32 v[104:105], v[26:27], v[108:109], v[104:105]
	v_pk_fma_f32 v[106:107], v[106:107], v[108:109], v[110:111] op_sel_hi:[1,0,1]
	v_pk_mul_f32 v[108:109], v[62:63], v[102:103] op_sel:[0,1] op_sel_hi:[0,0] neg_lo:[0,1]
	v_pk_fma_f32 v[102:103], v[26:27], v[102:103], v[108:109]
	s_nop 0
	v_pk_mul_f32 v[108:109], v[88:89], v[102:103] op_sel:[1,1] op_sel_hi:[0,1] neg_hi:[1,0]
	s_nop 0
	v_pk_fma_f32 v[88:89], v[88:89], v[102:103], v[108:109] op_sel_hi:[1,0,1]
	v_pk_mul_f32 v[108:109], v[62:63], v[104:105] op_sel:[0,1] op_sel_hi:[0,0] neg_lo:[0,1]
	v_pk_mul_f32 v[110:111], v[92:93], v[104:105] op_sel:[1,1] op_sel_hi:[0,1] neg_hi:[1,0]
	v_pk_fma_f32 v[108:109], v[26:27], v[104:105], v[108:109]
	v_pk_fma_f32 v[92:93], v[92:93], v[104:105], v[110:111] op_sel_hi:[1,0,1]
	v_pk_mul_f32 v[104:105], v[62:63], v[102:103] op_sel:[0,1] op_sel_hi:[0,0] neg_lo:[0,1]
	v_pk_fma_f32 v[102:103], v[26:27], v[102:103], v[104:105]
	s_nop 0
	v_pk_mul_f32 v[104:105], v[80:81], v[102:103] op_sel:[1,1] op_sel_hi:[0,1] neg_hi:[1,0]
	s_nop 0
	v_pk_fma_f32 v[80:81], v[80:81], v[102:103], v[104:105] op_sel_hi:[1,0,1]
	v_pk_mul_f32 v[104:105], v[62:63], v[108:109] op_sel:[0,1] op_sel_hi:[0,0] neg_lo:[0,1]
	v_pk_mul_f32 v[110:111], v[82:83], v[108:109] op_sel:[1,1] op_sel_hi:[0,1] neg_hi:[1,0]
	v_pk_fma_f32 v[104:105], v[26:27], v[108:109], v[104:105]
	v_pk_fma_f32 v[82:83], v[82:83], v[108:109], v[110:111] op_sel_hi:[1,0,1]
	v_pk_mul_f32 v[108:109], v[62:63], v[102:103] op_sel:[0,1] op_sel_hi:[0,0] neg_lo:[0,1]
	v_pk_fma_f32 v[102:103], v[26:27], v[102:103], v[108:109]
	s_nop 0
	v_pk_mul_f32 v[108:109], v[74:75], v[102:103] op_sel:[1,1] op_sel_hi:[0,1] neg_hi:[1,0]
	s_nop 0
	v_pk_fma_f32 v[74:75], v[74:75], v[102:103], v[108:109] op_sel_hi:[1,0,1]
	v_pk_mul_f32 v[108:109], v[62:63], v[104:105] op_sel:[0,1] op_sel_hi:[0,0] neg_lo:[0,1]
	v_pk_mul_f32 v[110:111], v[76:77], v[104:105] op_sel:[1,1] op_sel_hi:[0,1] neg_hi:[1,0]
	v_pk_fma_f32 v[108:109], v[26:27], v[104:105], v[108:109]
	v_pk_fma_f32 v[76:77], v[76:77], v[104:105], v[110:111] op_sel_hi:[1,0,1]
	v_pk_mul_f32 v[104:105], v[62:63], v[102:103] op_sel:[0,1] op_sel_hi:[0,0] neg_lo:[0,1]
	v_pk_fma_f32 v[102:103], v[26:27], v[102:103], v[104:105]
	s_nop 0
	v_pk_mul_f32 v[104:105], v[68:69], v[102:103] op_sel:[1,1] op_sel_hi:[0,1] neg_hi:[1,0]
	s_nop 0
	v_pk_fma_f32 v[68:69], v[68:69], v[102:103], v[104:105] op_sel_hi:[1,0,1]
	v_pk_mul_f32 v[104:105], v[62:63], v[108:109] op_sel:[0,1] op_sel_hi:[0,0] neg_lo:[0,1]
	v_pk_mul_f32 v[110:111], v[70:71], v[108:109] op_sel:[1,1] op_sel_hi:[0,1] neg_hi:[1,0]
	v_pk_fma_f32 v[104:105], v[26:27], v[108:109], v[104:105]
	v_pk_fma_f32 v[70:71], v[70:71], v[108:109], v[110:111] op_sel_hi:[1,0,1]
	v_pk_mul_f32 v[108:109], v[62:63], v[102:103] op_sel:[0,1] op_sel_hi:[0,0] neg_lo:[0,1]
	v_pk_fma_f32 v[102:103], v[26:27], v[102:103], v[108:109]
	s_nop 0
	v_pk_mul_f32 v[108:109], v[20:21], v[102:103] op_sel:[1,1] op_sel_hi:[0,1] neg_hi:[1,0]
	s_nop 0
	v_pk_fma_f32 v[20:21], v[20:21], v[102:103], v[108:109] op_sel_hi:[1,0,1]
	v_pk_mul_f32 v[108:109], v[62:63], v[104:105] op_sel:[0,1] op_sel_hi:[0,0] neg_lo:[0,1]
	v_pk_mul_f32 v[110:111], v[22:23], v[104:105] op_sel:[1,1] op_sel_hi:[0,1] neg_hi:[1,0]
	v_pk_fma_f32 v[108:109], v[26:27], v[104:105], v[108:109]
	v_pk_fma_f32 v[22:23], v[22:23], v[104:105], v[110:111] op_sel_hi:[1,0,1]
	v_pk_mul_f32 v[104:105], v[62:63], v[102:103] op_sel:[0,1] op_sel_hi:[0,0] neg_lo:[0,1]
	v_pk_fma_f32 v[102:103], v[26:27], v[102:103], v[104:105]
	s_nop 0
	v_pk_mul_f32 v[104:105], v[12:13], v[102:103] op_sel:[1,1] op_sel_hi:[0,1] neg_hi:[1,0]
	s_nop 0
	v_pk_fma_f32 v[12:13], v[12:13], v[102:103], v[104:105] op_sel_hi:[1,0,1]
	v_pk_mul_f32 v[104:105], v[62:63], v[108:109] op_sel:[0,1] op_sel_hi:[0,0] neg_lo:[0,1]
	v_pk_mul_f32 v[110:111], v[14:15], v[108:109] op_sel:[1,1] op_sel_hi:[0,1] neg_hi:[1,0]
	v_pk_fma_f32 v[104:105], v[26:27], v[108:109], v[104:105]
	v_pk_fma_f32 v[14:15], v[14:15], v[108:109], v[110:111] op_sel_hi:[1,0,1]
	v_pk_mul_f32 v[108:109], v[62:63], v[102:103] op_sel:[0,1] op_sel_hi:[0,0] neg_lo:[0,1]
	v_pk_fma_f32 v[102:103], v[26:27], v[102:103], v[108:109]
	s_nop 0
	v_pk_mul_f32 v[108:109], v[8:9], v[102:103] op_sel:[1,1] op_sel_hi:[0,1] neg_hi:[1,0]
	s_nop 0
	v_pk_fma_f32 v[8:9], v[8:9], v[102:103], v[108:109] op_sel_hi:[1,0,1]
	v_pk_mul_f32 v[108:109], v[62:63], v[104:105] op_sel:[0,1] op_sel_hi:[0,0] neg_lo:[0,1]
	v_pk_mul_f32 v[110:111], v[10:11], v[104:105] op_sel:[1,1] op_sel_hi:[0,1] neg_hi:[1,0]
	v_pk_fma_f32 v[108:109], v[26:27], v[104:105], v[108:109]
	v_pk_fma_f32 v[10:11], v[10:11], v[104:105], v[110:111] op_sel_hi:[1,0,1]
	v_pk_mul_f32 v[104:105], v[62:63], v[102:103] op_sel:[0,1] op_sel_hi:[0,0] neg_lo:[0,1]
	v_pk_fma_f32 v[26:27], v[26:27], v[102:103], v[104:105]
	s_nop 0
	v_pk_mul_f32 v[102:103], v[4:5], v[26:27] op_sel:[1,1] op_sel_hi:[0,1] neg_hi:[1,0]
	s_add_i32 s1, 16, 0x1e000
	v_pk_fma_f32 v[4:5], v[4:5], v[26:27], v[102:103] op_sel_hi:[1,0,1]
	s_nop 0
	s_nop 0
	v_pk_mul_f32 v[26:27], v[6:7], v[108:109] op_sel:[1,1] op_sel_hi:[0,1] neg_hi:[1,0]
	s_add_i32 s0, 16, 0x1f000
	v_pk_fma_f32 v[6:7], v[6:7], v[108:109], v[26:27] op_sel_hi:[1,0,1]
	v_lshrrev_b32_e32 v26, 5, v63
	v_bitop3_b32 v26, v26, v63, 15 bitop3:0x6c
	v_lshlrev_b32_e32 v26, 3, v26
	v_bfe_u32 v27, v63, 5, 4
	v_add_u32_e32 v62, 16, v26
	ds_write_b64 v62, v[2:3]
	v_bitop3_b32 v2, v27, v63, 16 bitop3:0x36
	v_lshlrev_b32_e32 v2, 3, v2
	v_add_u32_e32 v3, 16, v2
	ds_write_b64 v3, v[88:89] offset:4096
	ds_write_b64 v62, v[90:91] offset:8192
	ds_write_b64 v3, v[20:21] offset:12288
	ds_write_b64 v62, v[72:73] offset:16384
	ds_write_b64 v3, v[74:75] offset:20480
	ds_write_b64 v62, v[96:97] offset:24576
	ds_write_b64 v3, v[8:9] offset:28672
	ds_write_b64 v62, v[24:25] offset:32768
	ds_write_b64 v3, v[80:81] offset:36864
	ds_write_b64 v62, v[94:95] offset:40960
	ds_write_b64 v3, v[12:13] offset:45056
	ds_write_b64 v62, v[78:79] offset:49152
	ds_write_b64 v3, v[68:69] offset:53248
	ds_write_b64 v62, v[98:99] offset:57344
	ds_write_b64 v3, v[4:5] offset:61440
	v_add_u32_e32 v3, s79, v26
	ds_write_b64 v3, v[18:19]
	v_add_u32_e32 v3, s19, v2
	ds_write_b64 v3, v[92:93]
	v_add_u32_e32 v3, s18, v26
	ds_write_b64 v3, v[84:85]
	v_add_u32_e32 v3, s17, v2
	ds_write_b64 v3, v[22:23]
	v_add_u32_e32 v3, s13, v26
	ds_write_b64 v3, v[64:65]
	v_add_u32_e32 v3, s12, v2
	ds_write_b64 v3, v[76:77]
	v_add_u32_e32 v3, s11, v26
	ds_write_b64 v3, v[100:101]
	v_add_u32_e32 v3, s10, v2
	ds_write_b64 v3, v[10:11]
	v_add_u32_e32 v3, s9, v26
	ds_write_b64 v3, v[16:17]
	v_add_u32_e32 v3, s8, v2
	ds_write_b64 v3, v[82:83]
	v_add_u32_e32 v3, s7, v26
	ds_write_b64 v3, v[86:87]
	v_add_u32_e32 v3, s6, v2
	ds_write_b64 v3, v[14:15]
	v_add_u32_e32 v3, s5, v26
	ds_write_b64 v3, v[66:67]
	v_add_u32_e32 v3, s4, v2
	ds_write_b64 v3, v[70:71]
	v_add_u32_e32 v3, s1, v26
	v_add_u32_e32 v2, s0, v2
	v_mov_b32_e32 v21, v146
	ds_write_b64 v3, v[106:107]
	ds_write_b64 v2, v[6:7]
	s_waitcnt lgkmcnt(0)
	s_barrier
	s_lshl_b32 s42, s16, 14
	v_lshlrev_b32_e32 v2, 5, v21
	v_and_b32_e32 v4, 0xfffffe00, v2
	v_and_b32_e32 v20, 15, v21
	v_and_or_b32 v2, v21, 16, v4
	v_bitop3_b32 v4, v4, 16, v21 bitop3:0x34
	v_bitop3_b32 v72, v21, 8, 15 bitop3:0x6c
	v_lshl_add_u32 v26, v2, 3, 16
	v_lshlrev_b32_e32 v5, 3, v20
	v_lshl_add_u32 v126, v4, 3, 16
	v_lshlrev_b32_e32 v74, 3, v72
	v_add_u32_e32 v27, v26, v5
	v_add_u32_e32 v96, v126, v5
	v_add_u32_e32 v111, v26, v74
	v_add_u32_e32 v112, v126, v74
	ds_read_b64 v[2:3], v27
	ds_read_b64 v[4:5], v96
	v_bitop3_b32 v6, v21, 1, 15 bitop3:0x6c
	ds_read_b64 v[72:73], v111 offset:2048
	ds_read_b64 v[74:75], v112 offset:2048
	v_bitop3_b32 v76, v21, 9, 15 bitop3:0x6c
	v_lshlrev_b32_e32 v8, 3, v6
	v_lshlrev_b32_e32 v78, 3, v76
	v_add_u32_e32 v97, v26, v8
	v_add_u32_e32 v113, v26, v78
	ds_read_b64 v[6:7], v97 offset:256
	ds_read_b64 v[76:77], v113 offset:2304
	v_add_u32_e32 v98, v126, v8
	v_add_u32_e32 v114, v126, v78
	ds_read_b64 v[8:9], v98 offset:256
	ds_read_b64 v[78:79], v114 offset:2304
	s_waitcnt lgkmcnt(5)
	v_pk_add_f32 v[136:137], v[2:3], v[72:73]
	v_pk_add_f32 v[2:3], v[2:3], v[72:73] neg_lo:[0,1] neg_hi:[0,1]
	s_waitcnt lgkmcnt(4)
	v_pk_add_f32 v[72:73], v[4:5], v[74:75]
	v_pk_add_f32 v[4:5], v[4:5], v[74:75] neg_lo:[0,1] neg_hi:[0,1]
	v_bitop3_b32 v10, v21, 2, 15 bitop3:0x6c
	v_bitop3_b32 v80, v21, 10, 15 bitop3:0x6c
	v_lshlrev_b32_e32 v12, 3, v10
	v_lshlrev_b32_e32 v82, 3, v80
	v_pk_mul_f32 v[74:75], v[4:5], s[48:49] op_sel:[1,0] op_sel_hi:[0,0] neg_hi:[1,0]
	v_add_u32_e32 v99, v26, v12
	v_add_u32_e32 v115, v26, v82
	v_pk_fma_f32 v[4:5], v[4:5], s[44:45], v[74:75] op_sel_hi:[1,0,1]
	s_waitcnt lgkmcnt(2)
	v_pk_add_f32 v[74:75], v[6:7], v[76:77]
	v_pk_add_f32 v[6:7], v[6:7], v[76:77] neg_lo:[0,1] neg_hi:[0,1]
	ds_read_b64 v[10:11], v99 offset:512
	ds_read_b64 v[80:81], v115 offset:2560
	v_pk_mul_f32 v[76:77], v[6:7], s[54:55] op_sel:[1,0] op_sel_hi:[0,0] neg_hi:[1,0]
	v_add_u32_e32 v100, v126, v12
	v_bitop3_b32 v14, v21, 3, 15 bitop3:0x6c
	v_add_u32_e32 v116, v126, v82
	v_bitop3_b32 v84, v21, 11, 15 bitop3:0x6c
	v_pk_fma_f32 v[6:7], v[6:7], s[52:53], v[76:77] op_sel_hi:[1,0,1]
	s_waitcnt lgkmcnt(2)
	v_pk_add_f32 v[76:77], v[8:9], v[78:79]
	v_pk_add_f32 v[8:9], v[8:9], v[78:79] neg_lo:[0,1] neg_hi:[0,1]
	ds_read_b64 v[12:13], v100 offset:512
	v_lshlrev_b32_e32 v16, 3, v14
	ds_read_b64 v[82:83], v116 offset:2560
	v_lshlrev_b32_e32 v86, 3, v84
	v_add_u32_e32 v101, v26, v16
	v_add_u32_e32 v102, v126, v16
	v_add_u32_e32 v117, v26, v86
	v_add_u32_e32 v118, v126, v86
	v_pk_mul_f32 v[78:79], v[8:9], s[58:59] op_sel:[1,0] op_sel_hi:[0,0] neg_hi:[1,0]
	ds_read_b64 v[14:15], v101 offset:768
	ds_read_b64 v[16:17], v102 offset:768
	ds_read_b64 v[84:85], v117 offset:2816
	ds_read_b64 v[86:87], v118 offset:2816
	v_pk_fma_f32 v[8:9], v[8:9], s[56:57], v[78:79] op_sel_hi:[1,0,1]
	s_waitcnt lgkmcnt(6)
	v_pk_add_f32 v[78:79], v[10:11], v[80:81]
	v_pk_add_f32 v[10:11], v[10:11], v[80:81] neg_lo:[0,1] neg_hi:[0,1]
	v_bitop3_b32 v18, v21, 4, 15 bitop3:0x6c
	v_pk_mul_f32 v[80:81], v[10:11], s[60:61] op_sel:[1,0] op_sel_hi:[0,0] neg_hi:[1,0]
	v_bitop3_b32 v88, v21, 12, 15 bitop3:0x6c
	v_pk_fma_f32 v[10:11], v[10:11], s[60:61], v[80:81] op_sel_hi:[1,0,1]
	s_waitcnt lgkmcnt(4)
	v_pk_add_f32 v[80:81], v[12:13], v[82:83]
	v_pk_add_f32 v[12:13], v[12:13], v[82:83] neg_lo:[0,1] neg_hi:[0,1]
	v_lshlrev_b32_e32 v22, 3, v18
	v_lshlrev_b32_e32 v90, 3, v88
	v_pk_mul_f32 v[82:83], v[12:13], s[56:57] op_sel:[1,0] op_sel_hi:[0,0] neg_hi:[1,0]
	v_add_u32_e32 v103, v26, v22
	v_add_u32_e32 v119, v26, v90
	v_pk_fma_f32 v[12:13], v[12:13], s[58:59], v[82:83] op_sel_hi:[1,0,1]
	s_waitcnt lgkmcnt(1)
	v_pk_add_f32 v[82:83], v[14:15], v[84:85]
	v_pk_add_f32 v[14:15], v[14:15], v[84:85] neg_lo:[0,1] neg_hi:[0,1]
	ds_read_b64 v[18:19], v103 offset:1024
	v_add_u32_e32 v104, v126, v22
	v_bitop3_b32 v24, v21, 5, 15 bitop3:0x6c
	ds_read_b64 v[88:89], v119 offset:3072
	v_add_u32_e32 v120, v126, v90
	v_bitop3_b32 v92, v21, 13, 15 bitop3:0x6c
	ds_read_b64 v[22:23], v104 offset:1024
	v_lshlrev_b32_e32 v62, 3, v24
	ds_read_b64 v[90:91], v120 offset:3072
	v_lshlrev_b32_e32 v94, 3, v92
	v_pk_mul_f32 v[84:85], v[14:15], s[52:53] op_sel:[1,0] op_sel_hi:[0,0] neg_hi:[1,0]
	v_add_u32_e32 v105, v26, v62
	v_add_u32_e32 v121, v26, v94
	v_pk_fma_f32 v[14:15], v[14:15], s[54:55], v[84:85] op_sel_hi:[1,0,1]
	s_waitcnt lgkmcnt(4)
	v_pk_add_f32 v[84:85], v[16:17], v[86:87]
	v_pk_add_f32 v[16:17], v[16:17], v[86:87] neg_lo:[0,1] neg_hi:[0,1]
	ds_read_b64 v[24:25], v105 offset:1280
	ds_read_b64 v[92:93], v121 offset:3328
	v_add_u32_e32 v106, v126, v62
	v_bitop3_b32 v64, v21, 6, 15 bitop3:0x6c
	v_add_u32_e32 v122, v126, v94
	v_bitop3_b32 v123, v21, 14, 15 bitop3:0x6c
	v_pk_mul_f32 v[86:87], v[16:17], s[44:45] op_sel:[1,0] op_sel_hi:[0,0] neg_hi:[1,0]
	ds_read_b64 v[62:63], v106 offset:1280
	v_lshlrev_b32_e32 v66, 3, v64
	ds_read_b64 v[94:95], v122 offset:3328
	v_lshlrev_b32_e32 v124, 3, v123
	v_pk_fma_f32 v[16:17], v[16:17], s[48:49], v[86:87] op_sel_hi:[1,0,1]
	s_waitcnt lgkmcnt(6)
	v_pk_add_f32 v[86:87], v[18:19], v[88:89]
	v_pk_add_f32 v[18:19], v[18:19], v[88:89] neg_lo:[0,1] neg_hi:[0,1]
	v_add_u32_e32 v107, v26, v66
	v_add_u32_e32 v123, v26, v124
	v_xor_b32_e32 v89, 0x80000000, v18
	v_mov_b32_e32 v88, v19
	s_waitcnt lgkmcnt(4)
	v_pk_add_f32 v[18:19], v[22:23], v[90:91]
	v_pk_add_f32 v[22:23], v[22:23], v[90:91] neg_lo:[0,1] neg_hi:[0,1]
	ds_read_b64 v[64:65], v107 offset:1536
	ds_read_b64 v[128:129], v123 offset:3584
	v_pk_mul_f32 v[90:91], v[22:23], s[48:49] op_sel_hi:[1,0]
	v_xor_b32_e32 v139, 0x80000000, v22
	v_mov_b32_e32 v138, v23
	v_add_u32_e32 v108, v126, v66
	v_bitop3_b32 v68, v21, 7, 15 bitop3:0x6c
	v_add_u32_e32 v124, v126, v124
	v_bitop3_b32 v21, v21, 15, v21 bitop3:0xc
	v_pk_fma_f32 v[22:23], v[138:139], s[44:45], v[90:91] op_sel_hi:[1,0,1] neg_lo:[0,0,1] neg_hi:[0,0,1]
	s_waitcnt lgkmcnt(4)
	v_pk_add_f32 v[90:91], v[24:25], v[92:93]
	v_pk_add_f32 v[24:25], v[24:25], v[92:93] neg_lo:[0,1] neg_hi:[0,1]
	ds_read_b64 v[66:67], v108 offset:1536
	v_lshlrev_b32_e32 v70, 3, v68
	ds_read_b64 v[130:131], v124 offset:3584
	v_lshlrev_b32_e32 v21, 3, v21
	v_pk_mul_f32 v[92:93], v[24:25], s[54:55] op_sel_hi:[1,0]
	v_xor_b32_e32 v139, 0x80000000, v24
	v_mov_b32_e32 v138, v25
	v_add_u32_e32 v109, v26, v70
	v_add_u32_e32 v125, v26, v21
	v_pk_fma_f32 v[24:25], v[138:139], s[52:53], v[92:93] op_sel_hi:[1,0,1] neg_lo:[0,0,1] neg_hi:[0,0,1]
	s_waitcnt lgkmcnt(4)
	v_pk_add_f32 v[92:93], v[62:63], v[94:95]
	v_pk_add_f32 v[62:63], v[62:63], v[94:95] neg_lo:[0,1] neg_hi:[0,1]
	ds_read_b64 v[68:69], v109 offset:1792
	v_add_u32_e32 v110, v126, v70
	ds_read_b64 v[132:133], v125 offset:3840
	v_add_u32_e32 v126, v126, v21
	v_pk_mul_f32 v[94:95], v[62:63], s[58:59] op_sel_hi:[1,0]
	v_xor_b32_e32 v139, 0x80000000, v62
	v_mov_b32_e32 v138, v63
	ds_read_b64 v[70:71], v110 offset:1792
	ds_read_b64 v[134:135], v126 offset:3840
	v_pk_fma_f32 v[62:63], v[138:139], s[56:57], v[94:95] op_sel_hi:[1,0,1] neg_lo:[0,0,1] neg_hi:[0,0,1]
	s_waitcnt lgkmcnt(6)
	v_pk_add_f32 v[94:95], v[64:65], v[128:129]
	v_pk_add_f32 v[64:65], v[64:65], v[128:129] neg_lo:[0,1] neg_hi:[0,1]
	v_lshl_add_u64 v[0:1], s[42:43], 2, v[28:29]
	v_pk_mul_f32 v[128:129], v[64:65], s[60:61] op_sel_hi:[1,0]
	v_xor_b32_e32 v139, 0x80000000, v64
	v_mov_b32_e32 v138, v65
	v_pk_fma_f32 v[64:65], v[138:139], s[60:61], v[128:129] op_sel_hi:[1,0,1] neg_lo:[0,0,1] neg_hi:[0,0,1]
	s_waitcnt lgkmcnt(4)
	v_pk_add_f32 v[128:129], v[66:67], v[130:131]
	v_pk_add_f32 v[66:67], v[66:67], v[130:131] neg_lo:[0,1] neg_hi:[0,1]
	v_cvt_f32_i32_e32 v20, v20
	v_pk_mul_f32 v[130:131], v[66:67], s[56:57] op_sel_hi:[1,0]
	v_xor_b32_e32 v139, 0x80000000, v66
	v_mov_b32_e32 v138, v67
	v_pk_fma_f32 v[66:67], v[138:139], s[58:59], v[130:131] op_sel_hi:[1,0,1] neg_lo:[0,0,1] neg_hi:[0,0,1]
	s_waitcnt lgkmcnt(2)
	v_pk_add_f32 v[130:131], v[68:69], v[132:133]
	v_pk_add_f32 v[68:69], v[68:69], v[132:133] neg_lo:[0,1] neg_hi:[0,1]
	v_mul_f32_e32 v21, 0x3b000000, v20
	v_pk_mul_f32 v[132:133], v[68:69], s[52:53] op_sel_hi:[1,0]
	v_xor_b32_e32 v139, 0x80000000, v68
	v_mov_b32_e32 v138, v69
	v_pk_fma_f32 v[68:69], v[138:139], s[54:55], v[132:133] op_sel_hi:[1,0,1] neg_lo:[0,0,1] neg_hi:[0,0,1]
	s_waitcnt lgkmcnt(0)
	v_pk_add_f32 v[132:133], v[70:71], v[134:135]
	v_pk_add_f32 v[70:71], v[70:71], v[134:135] neg_lo:[0,1] neg_hi:[0,1]
	v_cos_f32_e32 v20, v21
	v_pk_mul_f32 v[134:135], v[70:71], s[44:45] op_sel_hi:[1,0]
	v_xor_b32_e32 v139, 0x80000000, v70
	v_mov_b32_e32 v138, v71
	v_pk_fma_f32 v[70:71], v[138:139], s[48:49], v[134:135] op_sel_hi:[1,0,1] neg_lo:[0,0,1] neg_hi:[0,0,1]
	v_pk_add_f32 v[134:135], v[136:137], v[86:87]
	v_pk_add_f32 v[86:87], v[136:137], v[86:87] neg_lo:[0,1] neg_hi:[0,1]
	v_pk_add_f32 v[136:137], v[72:73], v[18:19]
	v_pk_add_f32 v[18:19], v[72:73], v[18:19] neg_lo:[0,1] neg_hi:[0,1]
	v_sin_f32_e32 v21, v21
	s_nop 0
	s_nop 0
	v_pk_mul_f32 v[72:73], v[18:19], s[54:55] op_sel:[1,0] op_sel_hi:[0,0] neg_hi:[1,0]
	v_add_f32_e32 v26, v20, v20
	v_pk_fma_f32 v[18:19], v[18:19], s[52:53], v[72:73] op_sel_hi:[1,0,1]
	v_pk_add_f32 v[72:73], v[74:75], v[90:91]
	v_pk_add_f32 v[74:75], v[74:75], v[90:91] neg_lo:[0,1] neg_hi:[0,1]
	v_mul_f32_e32 v26, v21, v26
	s_nop 0
	s_nop 0
	v_pk_mul_f32 v[90:91], v[74:75], s[60:61] op_sel:[1,0] op_sel_hi:[0,0] neg_hi:[1,0]
	s_lshl_b32 s42, s16, 9
	v_pk_fma_f32 v[74:75], v[74:75], s[60:61], v[90:91] op_sel_hi:[1,0,1]
	v_pk_add_f32 v[90:91], v[76:77], v[92:93]
	v_pk_add_f32 v[76:77], v[76:77], v[92:93] neg_lo:[0,1] neg_hi:[0,1]
	s_mov_b64 s[74:75], -1
	s_nop 0
	s_nop 0
	v_pk_mul_f32 v[92:93], v[76:77], s[52:53] op_sel:[1,0] op_sel_hi:[0,0] neg_hi:[1,0]
	s_nop 0
	v_pk_fma_f32 v[76:77], v[76:77], s[54:55], v[92:93] op_sel_hi:[1,0,1]
	v_pk_add_f32 v[92:93], v[78:79], v[94:95]
	v_pk_add_f32 v[78:79], v[78:79], v[94:95] neg_lo:[0,1] neg_hi:[0,1]
	s_nop 0
	v_xor_b32_e32 v95, 0x80000000, v78
	v_mov_b32_e32 v94, v79
	v_pk_add_f32 v[78:79], v[80:81], v[128:129]
	v_pk_add_f32 v[80:81], v[80:81], v[128:129] neg_lo:[0,1] neg_hi:[0,1]
	s_nop 0
	v_pk_mul_f32 v[128:129], v[80:81], s[54:55] op_sel_hi:[1,0]
	v_xor_b32_e32 v139, 0x80000000, v80
	v_mov_b32_e32 v138, v81
	v_pk_fma_f32 v[80:81], v[138:139], s[52:53], v[128:129] op_sel_hi:[1,0,1] neg_lo:[0,0,1] neg_hi:[0,0,1]
	v_pk_add_f32 v[128:129], v[82:83], v[130:131]
	v_pk_add_f32 v[82:83], v[82:83], v[130:131] neg_lo:[0,1] neg_hi:[0,1]
	s_nop 0
	v_pk_mul_f32 v[130:131], v[82:83], s[60:61] op_sel_hi:[1,0]
	v_xor_b32_e32 v139, 0x80000000, v82
	v_mov_b32_e32 v138, v83
	v_pk_fma_f32 v[82:83], v[138:139], s[60:61], v[130:131] op_sel_hi:[1,0,1] neg_lo:[0,0,1] neg_hi:[0,0,1]
	v_pk_add_f32 v[130:131], v[84:85], v[132:133]
	v_pk_add_f32 v[84:85], v[84:85], v[132:133] neg_lo:[0,1] neg_hi:[0,1]
	s_nop 0
	v_pk_mul_f32 v[132:133], v[84:85], s[52:53] op_sel_hi:[1,0]
	v_xor_b32_e32 v139, 0x80000000, v84
	v_mov_b32_e32 v138, v85
	v_pk_fma_f32 v[84:85], v[138:139], s[54:55], v[132:133] op_sel_hi:[1,0,1] neg_lo:[0,0,1] neg_hi:[0,0,1]
	v_pk_add_f32 v[132:133], v[2:3], v[88:89]
	v_pk_add_f32 v[2:3], v[2:3], v[88:89] neg_lo:[0,1] neg_hi:[0,1]
	v_pk_add_f32 v[88:89], v[4:5], v[22:23]
	v_pk_add_f32 v[4:5], v[4:5], v[22:23] neg_lo:[0,1] neg_hi:[0,1]
	s_nop 0
	v_pk_mul_f32 v[22:23], v[4:5], s[54:55] op_sel:[1,0] op_sel_hi:[0,0] neg_hi:[1,0]
	s_nop 0
	v_pk_fma_f32 v[4:5], v[4:5], s[52:53], v[22:23] op_sel_hi:[1,0,1]
	v_pk_add_f32 v[22:23], v[6:7], v[24:25]
	v_pk_add_f32 v[6:7], v[6:7], v[24:25] neg_lo:[0,1] neg_hi:[0,1]
	s_nop 0
	v_pk_mul_f32 v[24:25], v[6:7], s[60:61] op_sel:[1,0] op_sel_hi:[0,0] neg_hi:[1,0]
	s_nop 0
	v_pk_fma_f32 v[6:7], v[6:7], s[60:61], v[24:25] op_sel_hi:[1,0,1]
	v_pk_add_f32 v[24:25], v[8:9], v[62:63]
	v_pk_add_f32 v[8:9], v[8:9], v[62:63] neg_lo:[0,1] neg_hi:[0,1]
	s_nop 0
	v_pk_mul_f32 v[62:63], v[8:9], s[52:53] op_sel:[1,0] op_sel_hi:[0,0] neg_hi:[1,0]
	s_nop 0
	v_pk_fma_f32 v[8:9], v[8:9], s[54:55], v[62:63] op_sel_hi:[1,0,1]
	v_pk_add_f32 v[62:63], v[10:11], v[64:65]
	v_pk_add_f32 v[10:11], v[10:11], v[64:65] neg_lo:[0,1] neg_hi:[0,1]
	s_nop 0
	v_xor_b32_e32 v65, 0x80000000, v10
	v_mov_b32_e32 v64, v11
	v_pk_add_f32 v[10:11], v[12:13], v[66:67]
	v_pk_add_f32 v[12:13], v[12:13], v[66:67] neg_lo:[0,1] neg_hi:[0,1]
	s_nop 0
	v_pk_mul_f32 v[66:67], v[12:13], s[54:55] op_sel_hi:[1,0]
	v_xor_b32_e32 v139, 0x80000000, v12
	v_mov_b32_e32 v138, v13
	v_pk_fma_f32 v[12:13], v[138:139], s[52:53], v[66:67] op_sel_hi:[1,0,1] neg_lo:[0,0,1] neg_hi:[0,0,1]
	v_pk_add_f32 v[66:67], v[14:15], v[68:69]
	v_pk_add_f32 v[14:15], v[14:15], v[68:69] neg_lo:[0,1] neg_hi:[0,1]
	s_nop 0
	v_pk_mul_f32 v[68:69], v[14:15], s[60:61] op_sel_hi:[1,0]
	v_xor_b32_e32 v139, 0x80000000, v14
	v_mov_b32_e32 v138, v15
	v_pk_fma_f32 v[14:15], v[138:139], s[60:61], v[68:69] op_sel_hi:[1,0,1] neg_lo:[0,0,1] neg_hi:[0,0,1]
	v_pk_add_f32 v[68:69], v[16:17], v[70:71]
	v_pk_add_f32 v[16:17], v[16:17], v[70:71] neg_lo:[0,1] neg_hi:[0,1]
	s_nop 0
	v_pk_mul_f32 v[70:71], v[16:17], s[52:53] op_sel_hi:[1,0]
	v_xor_b32_e32 v139, 0x80000000, v16
	v_mov_b32_e32 v138, v17
	v_pk_fma_f32 v[16:17], v[138:139], s[54:55], v[70:71] op_sel_hi:[1,0,1] neg_lo:[0,0,1] neg_hi:[0,0,1]
	v_pk_add_f32 v[70:71], v[134:135], v[92:93]
	v_pk_add_f32 v[92:93], v[134:135], v[92:93] neg_lo:[0,1] neg_hi:[0,1]
	v_pk_add_f32 v[134:135], v[136:137], v[78:79]
	v_pk_add_f32 v[78:79], v[136:137], v[78:79] neg_lo:[0,1] neg_hi:[0,1]
	s_nop 0
	v_pk_mul_f32 v[136:137], v[78:79], s[60:61] op_sel:[1,0] op_sel_hi:[0,0] neg_hi:[1,0]
	s_nop 0
	v_pk_fma_f32 v[78:79], v[78:79], s[60:61], v[136:137] op_sel_hi:[1,0,1]
	v_pk_add_f32 v[136:137], v[72:73], v[128:129]
	v_pk_add_f32 v[72:73], v[72:73], v[128:129] neg_lo:[0,1] neg_hi:[0,1]
	s_nop 0
	v_xor_b32_e32 v129, 0x80000000, v72
	v_mov_b32_e32 v128, v73
	v_pk_add_f32 v[72:73], v[90:91], v[130:131]
	v_pk_add_f32 v[90:91], v[90:91], v[130:131] neg_lo:[0,1] neg_hi:[0,1]
	s_nop 0
	v_pk_mul_f32 v[130:131], v[90:91], s[60:61] op_sel_hi:[1,0]
	v_xor_b32_e32 v139, 0x80000000, v90
	v_mov_b32_e32 v138, v91
	v_pk_fma_f32 v[90:91], v[138:139], s[60:61], v[130:131] op_sel_hi:[1,0,1] neg_lo:[0,0,1] neg_hi:[0,0,1]
	v_pk_add_f32 v[130:131], v[86:87], v[94:95]
	v_pk_add_f32 v[86:87], v[86:87], v[94:95] neg_lo:[0,1] neg_hi:[0,1]
	v_pk_add_f32 v[94:95], v[18:19], v[80:81]
	v_pk_add_f32 v[18:19], v[18:19], v[80:81] neg_lo:[0,1] neg_hi:[0,1]
	s_nop 0
	v_pk_mul_f32 v[80:81], v[18:19], s[60:61] op_sel:[1,0] op_sel_hi:[0,0] neg_hi:[1,0]
	s_nop 0
	v_pk_fma_f32 v[18:19], v[18:19], s[60:61], v[80:81] op_sel_hi:[1,0,1]
	v_pk_add_f32 v[80:81], v[74:75], v[82:83]
	v_pk_add_f32 v[74:75], v[74:75], v[82:83] neg_lo:[0,1] neg_hi:[0,1]
	s_nop 0
	v_xor_b32_e32 v83, 0x80000000, v74
	v_mov_b32_e32 v82, v75
	v_pk_add_f32 v[74:75], v[76:77], v[84:85]
	v_pk_add_f32 v[76:77], v[76:77], v[84:85] neg_lo:[0,1] neg_hi:[0,1]
	s_nop 0
	v_pk_mul_f32 v[84:85], v[76:77], s[60:61] op_sel_hi:[1,0]
	v_xor_b32_e32 v139, 0x80000000, v76
	v_mov_b32_e32 v138, v77
	v_pk_fma_f32 v[76:77], v[138:139], s[60:61], v[84:85] op_sel_hi:[1,0,1] neg_lo:[0,0,1] neg_hi:[0,0,1]
	v_pk_add_f32 v[84:85], v[132:133], v[62:63]
	v_pk_add_f32 v[62:63], v[132:133], v[62:63] neg_lo:[0,1] neg_hi:[0,1]
	v_pk_add_f32 v[132:133], v[88:89], v[10:11]
	v_pk_add_f32 v[10:11], v[88:89], v[10:11] neg_lo:[0,1] neg_hi:[0,1]
	s_nop 0
	v_pk_mul_f32 v[88:89], v[10:11], s[60:61] op_sel:[1,0] op_sel_hi:[0,0] neg_hi:[1,0]
	s_nop 0
	v_pk_fma_f32 v[10:11], v[10:11], s[60:61], v[88:89] op_sel_hi:[1,0,1]
	v_pk_add_f32 v[88:89], v[22:23], v[66:67]
	v_pk_add_f32 v[22:23], v[22:23], v[66:67] neg_lo:[0,1] neg_hi:[0,1]
	s_nop 0
	v_xor_b32_e32 v67, 0x80000000, v22
	v_mov_b32_e32 v66, v23
	v_pk_add_f32 v[22:23], v[24:25], v[68:69]
	v_pk_add_f32 v[24:25], v[24:25], v[68:69] neg_lo:[0,1] neg_hi:[0,1]
	s_nop 0
	v_pk_mul_f32 v[68:69], v[24:25], s[60:61] op_sel_hi:[1,0]
	v_xor_b32_e32 v139, 0x80000000, v24
	v_mov_b32_e32 v138, v25
	v_pk_fma_f32 v[24:25], v[138:139], s[60:61], v[68:69] op_sel_hi:[1,0,1] neg_lo:[0,0,1] neg_hi:[0,0,1]
	v_pk_add_f32 v[68:69], v[2:3], v[64:65]
	v_pk_add_f32 v[2:3], v[2:3], v[64:65] neg_lo:[0,1] neg_hi:[0,1]
	v_pk_add_f32 v[64:65], v[4:5], v[12:13]
	v_pk_add_f32 v[4:5], v[4:5], v[12:13] neg_lo:[0,1] neg_hi:[0,1]
	s_nop 0
	v_pk_mul_f32 v[12:13], v[4:5], s[60:61] op_sel:[1,0] op_sel_hi:[0,0] neg_hi:[1,0]
	s_nop 0
	v_pk_fma_f32 v[4:5], v[4:5], s[60:61], v[12:13] op_sel_hi:[1,0,1]
	v_pk_add_f32 v[12:13], v[6:7], v[14:15]
	v_pk_add_f32 v[6:7], v[6:7], v[14:15] neg_lo:[0,1] neg_hi:[0,1]
	v_pk_add_f32 v[140:141], v[68:69], v[12:13]
	v_xor_b32_e32 v15, 0x80000000, v6
	v_mov_b32_e32 v14, v7
	v_pk_add_f32 v[6:7], v[8:9], v[16:17]
	v_pk_add_f32 v[8:9], v[8:9], v[16:17] neg_lo:[0,1] neg_hi:[0,1]
	v_pk_add_f32 v[142:143], v[64:65], v[6:7]
	v_pk_mul_f32 v[16:17], v[8:9], s[60:61] op_sel_hi:[1,0]
	s_nop 0
	v_pk_fma_f32 v[8:9], v[8:9], s[60:61], v[16:17] op_sel:[1,0,0] op_sel_hi:[0,0,1] neg_lo:[0,0,1] neg_hi:[1,0,1]
	v_pk_add_f32 v[16:17], v[70:71], v[136:137]
	v_pk_add_f32 v[70:71], v[70:71], v[136:137] neg_lo:[0,1] neg_hi:[0,1]
	v_pk_add_f32 v[136:137], v[134:135], v[72:73]
	v_pk_add_f32 v[72:73], v[134:135], v[72:73] neg_lo:[0,1] neg_hi:[0,1]
	v_pk_add_f32 v[138:139], v[84:85], v[88:89] neg_lo:[0,1] neg_hi:[0,1]
	v_xor_b32_e32 v135, 0x80000000, v72
	v_mov_b32_e32 v134, v73
	v_pk_add_f32 v[72:73], v[92:93], v[128:129]
	v_pk_add_f32 v[92:93], v[92:93], v[128:129] neg_lo:[0,1] neg_hi:[0,1]
	v_pk_add_f32 v[128:129], v[78:79], v[90:91]
	v_pk_add_f32 v[78:79], v[78:79], v[90:91] neg_lo:[0,1] neg_hi:[0,1]
	v_pk_add_f32 v[6:7], v[64:65], v[6:7] neg_lo:[0,1] neg_hi:[0,1]
	v_xor_b32_e32 v91, 0x80000000, v78
	v_mov_b32_e32 v90, v79
	v_pk_add_f32 v[78:79], v[130:131], v[80:81]
	v_pk_add_f32 v[130:131], v[130:131], v[80:81] neg_lo:[0,1] neg_hi:[0,1]
	v_pk_add_f32 v[80:81], v[94:95], v[74:75]
	v_pk_add_f32 v[74:75], v[94:95], v[74:75] neg_lo:[0,1] neg_hi:[0,1]
	v_xor_b32_e32 v149, 0x80000000, v6
	v_xor_b32_e32 v95, 0x80000000, v74
	v_mov_b32_e32 v94, v75
	v_pk_add_f32 v[74:75], v[86:87], v[82:83]
	v_pk_add_f32 v[82:83], v[86:87], v[82:83] neg_lo:[0,1] neg_hi:[0,1]
	v_pk_add_f32 v[86:87], v[18:19], v[76:77]
	v_pk_add_f32 v[18:19], v[18:19], v[76:77] neg_lo:[0,1] neg_hi:[0,1]
	v_mov_b32_e32 v148, v7
	v_xor_b32_e32 v77, 0x80000000, v18
	v_mov_b32_e32 v76, v19
	v_pk_add_f32 v[18:19], v[84:85], v[88:89]
	v_pk_add_f32 v[88:89], v[132:133], v[22:23]
	v_pk_add_f32 v[22:23], v[132:133], v[22:23] neg_lo:[0,1] neg_hi:[0,1]
	v_pk_add_f32 v[6:7], v[2:3], v[14:15]
	v_xor_b32_e32 v133, 0x80000000, v22
	v_mov_b32_e32 v132, v23
	v_pk_add_f32 v[22:23], v[62:63], v[66:67]
	v_pk_add_f32 v[62:63], v[62:63], v[66:67] neg_lo:[0,1] neg_hi:[0,1]
	v_pk_add_f32 v[66:67], v[10:11], v[24:25]
	v_pk_add_f32 v[10:11], v[10:11], v[24:25] neg_lo:[0,1] neg_hi:[0,1]
	v_pk_add_f32 v[154:155], v[2:3], v[14:15] neg_lo:[0,1] neg_hi:[0,1]
	v_pk_add_f32 v[2:3], v[4:5], v[8:9] neg_lo:[0,1] neg_hi:[0,1]
	v_pk_add_f32 v[68:69], v[68:69], v[12:13] neg_lo:[0,1] neg_hi:[0,1]
	v_pk_add_f32 v[156:157], v[4:5], v[8:9]
	v_xor_b32_e32 v159, 0x80000000, v2
	v_mov_b32_e32 v158, v3
	v_pk_add_f32 v[2:3], v[16:17], v[136:137]
	v_pk_add_f32 v[84:85], v[16:17], v[136:137] neg_lo:[0,1] neg_hi:[0,1]
	v_pk_add_f32 v[136:137], v[70:71], v[134:135]
	v_pk_add_f32 v[16:17], v[70:71], v[134:135] neg_lo:[0,1] neg_hi:[0,1]
	v_pk_add_f32 v[134:135], v[72:73], v[128:129]
	v_pk_add_f32 v[70:71], v[72:73], v[128:129] neg_lo:[0,1] neg_hi:[0,1]
	v_pk_add_f32 v[128:129], v[92:93], v[90:91]
	v_pk_add_f32 v[8:9], v[92:93], v[90:91] neg_lo:[0,1] neg_hi:[0,1]
	v_pk_add_f32 v[72:73], v[78:79], v[80:81]
	v_pk_add_f32 v[80:81], v[78:79], v[80:81] neg_lo:[0,1] neg_hi:[0,1]
	v_pk_add_f32 v[92:93], v[130:131], v[94:95]
	v_pk_add_f32 v[12:13], v[130:131], v[94:95] neg_lo:[0,1] neg_hi:[0,1]
	v_pk_add_f32 v[78:79], v[74:75], v[86:87]
	v_pk_add_f32 v[64:65], v[74:75], v[86:87] neg_lo:[0,1] neg_hi:[0,1]
	v_pk_add_f32 v[130:131], v[82:83], v[76:77]
	v_pk_add_f32 v[4:5], v[82:83], v[76:77] neg_lo:[0,1] neg_hi:[0,1]
	v_pk_add_f32 v[76:77], v[18:19], v[88:89]
	v_pk_add_f32 v[88:89], v[18:19], v[88:89] neg_lo:[0,1] neg_hi:[0,1]
	v_pk_add_f32 v[86:87], v[138:139], v[132:133]
	v_pk_add_f32 v[18:19], v[138:139], v[132:133] neg_lo:[0,1] neg_hi:[0,1]
	v_pk_add_f32 v[132:133], v[62:63], v[10:11] op_sel:[0,1] op_sel_hi:[1,0] neg_hi:[0,1]
	v_pk_add_f32 v[10:11], v[62:63], v[10:11] op_sel:[0,1] op_sel_hi:[1,0] neg_lo:[0,1]
	v_pk_mul_f32 v[24:25], v[20:21], v[20:21]
	s_nop 0
	v_pk_add_f32 v[24:25], v[24:25], v[24:25] op_sel:[0,1] op_sel_hi:[0,1] neg_lo:[0,1] neg_hi:[0,1]
	v_pk_mul_f32 v[62:63], v[20:21], v[26:27] op_sel:[1,0] op_sel_hi:[0,0] neg_lo:[1,0]
	v_pk_add_f32 v[90:91], v[22:23], v[66:67]
	v_pk_add_f32 v[74:75], v[22:23], v[66:67] neg_lo:[0,1] neg_hi:[0,1]
	v_pk_add_f32 v[22:23], v[140:141], v[142:143]
	v_pk_add_f32 v[82:83], v[140:141], v[142:143] neg_lo:[0,1] neg_hi:[0,1]
	v_pk_add_f32 v[138:139], v[68:69], v[148:149]
	v_pk_add_f32 v[14:15], v[68:69], v[148:149] neg_lo:[0,1] neg_hi:[0,1]
	v_pk_fma_f32 v[68:69], v[20:21], v[24:25], v[62:63]
	v_mov_b32_e32 v142, v21
	s_nop 0
	v_pk_mul_f32 v[62:63], v[142:143], v[76:77] op_sel:[0,1] op_sel_hi:[0,0] neg_hi:[0,1]
	v_pk_fma_f32 v[20:21], v[20:21], v[76:77], v[62:63] op_sel_hi:[0,1,1]
	v_pk_mul_f32 v[62:63], v[26:27], s[46:47] op_sel_hi:[0,1]
	v_pk_fma_f32 v[76:77], v[24:25], s[40:41], v[62:63]
	s_nop 0
	v_pk_mul_f32 v[62:63], v[76:77], v[72:73] op_sel:[1,1] op_sel_hi:[1,0] neg_hi:[0,1]
	v_pk_add_f32 v[94:95], v[6:7], v[156:157]
	v_pk_fma_f32 v[62:63], v[72:73], v[76:77], v[62:63] op_sel_hi:[1,0,1]
	v_pk_mul_f32 v[72:73], v[26:27], v[68:69] op_sel:[0,1] op_sel_hi:[0,0] neg_lo:[0,1]
	v_pk_fma_f32 v[142:143], v[24:25], v[68:69], v[72:73]
	v_pk_mul_f32 v[72:73], v[68:69], v[22:23] op_sel:[1,1] op_sel_hi:[1,0] neg_hi:[0,1]
	v_pk_add_f32 v[140:141], v[154:155], v[158:159]
	v_pk_fma_f32 v[22:23], v[68:69], v[22:23], v[72:73] op_sel_hi:[0,1,1]
	v_pk_mul_f32 v[68:69], v[26:27], v[76:77] op_sel:[0,1] op_sel_hi:[0,0] neg_lo:[0,1]
	v_pk_fma_f32 v[76:77], v[24:25], v[76:77], v[68:69]
	s_nop 0
	v_pk_mul_f32 v[68:69], v[134:135], v[76:77] op_sel:[1,1] op_sel_hi:[0,1] neg_hi:[1,0]
	v_pk_add_f32 v[66:67], v[6:7], v[156:157] neg_lo:[0,1] neg_hi:[0,1]
	v_pk_fma_f32 v[72:73], v[134:135], v[76:77], v[68:69] op_sel_hi:[1,0,1]
	v_pk_mul_f32 v[68:69], v[26:27], v[142:143] op_sel:[0,1] op_sel_hi:[0,0] neg_lo:[0,1]
	v_pk_fma_f32 v[134:135], v[24:25], v[142:143], v[68:69]
	v_pk_mul_f32 v[68:69], v[142:143], v[90:91] op_sel:[1,1] op_sel_hi:[1,0] neg_hi:[0,1]
	v_pk_add_f32 v[6:7], v[154:155], v[158:159] neg_lo:[0,1] neg_hi:[0,1]
	v_pk_fma_f32 v[68:69], v[90:91], v[142:143], v[68:69] op_sel_hi:[1,0,1]
	v_pk_mul_f32 v[90:91], v[26:27], v[76:77] op_sel:[0,1] op_sel_hi:[0,0] neg_lo:[0,1]
	v_pk_fma_f32 v[90:91], v[24:25], v[76:77], v[90:91]
	s_nop 0
	v_pk_mul_f32 v[76:77], v[78:79], v[90:91] op_sel:[1,1] op_sel_hi:[0,1] neg_hi:[1,0]
	s_nop 0
	v_pk_fma_f32 v[78:79], v[78:79], v[90:91], v[76:77] op_sel_hi:[1,0,1]
	v_pk_mul_f32 v[76:77], v[26:27], v[134:135] op_sel:[0,1] op_sel_hi:[0,0] neg_lo:[0,1]
	v_pk_fma_f32 v[142:143], v[24:25], v[134:135], v[76:77]
	v_pk_mul_f32 v[76:77], v[134:135], v[94:95] op_sel:[1,1] op_sel_hi:[1,0] neg_hi:[0,1]
	s_nop 0
	v_pk_fma_f32 v[76:77], v[94:95], v[134:135], v[76:77] op_sel_hi:[1,0,1]
	v_pk_mul_f32 v[94:95], v[26:27], v[90:91] op_sel:[0,1] op_sel_hi:[0,0] neg_lo:[0,1]
	v_pk_fma_f32 v[94:95], v[24:25], v[90:91], v[94:95]
	s_nop 0
	v_pk_mul_f32 v[90:91], v[136:137], v[94:95] op_sel:[1,1] op_sel_hi:[0,1] neg_hi:[1,0]
	v_xor_b32_e32 v134, 0x80000000, v143
	v_pk_fma_f32 v[90:91], v[136:137], v[94:95], v[90:91] op_sel_hi:[1,0,1]
	v_pk_mul_f32 v[136:137], v[86:87], v[142:143] op_sel:[1,1] op_sel_hi:[0,1] neg_hi:[1,0]
	v_mov_b32_e32 v135, v142
	v_pk_fma_f32 v[86:87], v[86:87], v[142:143], v[136:137] op_sel_hi:[1,0,1]
	v_pk_mul_f32 v[136:137], v[26:27], v[94:95] op_sel:[0,1] op_sel_hi:[0,0] neg_lo:[0,1]
	v_pk_mul_f32 v[134:135], v[26:27], v[134:135] op_sel_hi:[0,1]
	v_pk_fma_f32 v[136:137], v[24:25], v[94:95], v[136:137]
	v_pk_fma_f32 v[134:135], v[24:25], v[142:143], v[134:135]
	v_pk_mul_f32 v[94:95], v[92:93], v[136:137] op_sel:[1,1] op_sel_hi:[0,1] neg_hi:[1,0]
	s_nop 0
	v_pk_fma_f32 v[94:95], v[92:93], v[136:137], v[94:95] op_sel_hi:[1,0,1]
	v_pk_mul_f32 v[92:93], v[26:27], v[134:135] op_sel:[0,1] op_sel_hi:[0,0] neg_lo:[0,1]
	v_pk_fma_f32 v[142:143], v[24:25], v[134:135], v[92:93]
	v_pk_mul_f32 v[92:93], v[138:139], v[134:135] op_sel:[1,1] op_sel_hi:[0,1] neg_hi:[1,0]
	s_nop 0
	v_pk_fma_f32 v[92:93], v[138:139], v[134:135], v[92:93] op_sel_hi:[1,0,1]
	v_pk_mul_f32 v[134:135], v[26:27], v[136:137] op_sel:[0,1] op_sel_hi:[0,0] neg_lo:[0,1]
	s_nop 0
	v_pk_fma_f32 v[134:135], v[24:25], v[136:137], v[134:135]
	v_pk_mul_f32 v[138:139], v[132:133], v[142:143] op_sel:[1,1] op_sel_hi:[0,1] neg_hi:[1,0]
	v_pk_mul_f32 v[136:137], v[128:129], v[134:135] op_sel:[1,1] op_sel_hi:[0,1] neg_hi:[1,0]
	v_pk_fma_f32 v[132:133], v[132:133], v[142:143], v[138:139] op_sel_hi:[1,0,1]
	v_pk_fma_f32 v[128:129], v[128:129], v[134:135], v[136:137] op_sel_hi:[1,0,1]
	v_pk_mul_f32 v[138:139], v[26:27], v[134:135] op_sel:[0,1] op_sel_hi:[0,0] neg_lo:[0,1]
	v_pk_mul_f32 v[136:137], v[26:27], v[142:143] op_sel:[0,1] op_sel_hi:[0,0] neg_lo:[0,1]
	v_pk_fma_f32 v[134:135], v[24:25], v[134:135], v[138:139]
	v_pk_fma_f32 v[136:137], v[24:25], v[142:143], v[136:137]
	v_pk_mul_f32 v[138:139], v[130:131], v[134:135] op_sel:[1,1] op_sel_hi:[0,1] neg_hi:[1,0]
	s_nop 0
	v_pk_fma_f32 v[130:131], v[130:131], v[134:135], v[138:139] op_sel_hi:[1,0,1]
	v_pk_mul_f32 v[138:139], v[26:27], v[136:137] op_sel:[0,1] op_sel_hi:[0,0] neg_lo:[0,1]
	v_pk_mul_f32 v[142:143], v[140:141], v[136:137] op_sel:[1,1] op_sel_hi:[0,1] neg_hi:[1,0]
	v_pk_fma_f32 v[138:139], v[24:25], v[136:137], v[138:139]
	v_pk_fma_f32 v[136:137], v[140:141], v[136:137], v[142:143] op_sel_hi:[1,0,1]
	v_pk_mul_f32 v[140:141], v[26:27], v[134:135] op_sel:[0,1] op_sel_hi:[0,0] neg_lo:[0,1]
	v_pk_fma_f32 v[134:135], v[24:25], v[134:135], v[140:141]
	s_nop 0
	v_pk_mul_f32 v[140:141], v[84:85], v[134:135] op_sel:[1,1] op_sel_hi:[0,1] neg_hi:[1,0]
	s_nop 0
	v_pk_fma_f32 v[84:85], v[84:85], v[134:135], v[140:141] op_sel_hi:[1,0,1]
	v_pk_mul_f32 v[140:141], v[26:27], v[138:139] op_sel:[0,1] op_sel_hi:[0,0] neg_lo:[0,1]
	v_pk_mul_f32 v[142:143], v[88:89], v[138:139] op_sel:[1,1] op_sel_hi:[0,1] neg_hi:[1,0]
	v_pk_fma_f32 v[140:141], v[24:25], v[138:139], v[140:141]
	v_pk_fma_f32 v[88:89], v[88:89], v[138:139], v[142:143] op_sel_hi:[1,0,1]
	v_pk_mul_f32 v[138:139], v[26:27], v[134:135] op_sel:[0,1] op_sel_hi:[0,0] neg_lo:[0,1]
	v_pk_fma_f32 v[134:135], v[24:25], v[134:135], v[138:139]
	s_nop 0
	v_pk_mul_f32 v[138:139], v[80:81], v[134:135] op_sel:[1,1] op_sel_hi:[0,1] neg_hi:[1,0]
	s_nop 0
	v_pk_fma_f32 v[80:81], v[80:81], v[134:135], v[138:139] op_sel_hi:[1,0,1]
	v_pk_mul_f32 v[138:139], v[26:27], v[140:141] op_sel:[0,1] op_sel_hi:[0,0] neg_lo:[0,1]
	v_pk_mul_f32 v[142:143], v[82:83], v[140:141] op_sel:[1,1] op_sel_hi:[0,1] neg_hi:[1,0]
	v_pk_fma_f32 v[138:139], v[24:25], v[140:141], v[138:139]
	v_pk_fma_f32 v[82:83], v[82:83], v[140:141], v[142:143] op_sel_hi:[1,0,1]
	v_pk_mul_f32 v[140:141], v[26:27], v[134:135] op_sel:[0,1] op_sel_hi:[0,0] neg_lo:[0,1]
	v_pk_fma_f32 v[134:135], v[24:25], v[134:135], v[140:141]
	s_nop 0
	v_pk_mul_f32 v[140:141], v[70:71], v[134:135] op_sel:[1,1] op_sel_hi:[0,1] neg_hi:[1,0]
	s_nop 0
	v_pk_fma_f32 v[70:71], v[70:71], v[134:135], v[140:141] op_sel_hi:[1,0,1]
	v_pk_mul_f32 v[140:141], v[26:27], v[138:139] op_sel:[0,1] op_sel_hi:[0,0] neg_lo:[0,1]
	v_pk_mul_f32 v[142:143], v[74:75], v[138:139] op_sel:[1,1] op_sel_hi:[0,1] neg_hi:[1,0]
	v_pk_fma_f32 v[140:141], v[24:25], v[138:139], v[140:141]
	v_pk_fma_f32 v[74:75], v[74:75], v[138:139], v[142:143] op_sel_hi:[1,0,1]
	v_pk_mul_f32 v[138:139], v[26:27], v[134:135] op_sel:[0,1] op_sel_hi:[0,0] neg_lo:[0,1]
	v_pk_fma_f32 v[134:135], v[24:25], v[134:135], v[138:139]
	s_nop 0
	v_pk_mul_f32 v[138:139], v[64:65], v[134:135] op_sel:[1,1] op_sel_hi:[0,1] neg_hi:[1,0]
	s_nop 0
	v_pk_fma_f32 v[64:65], v[64:65], v[134:135], v[138:139] op_sel_hi:[1,0,1]
	v_pk_mul_f32 v[138:139], v[26:27], v[140:141] op_sel:[0,1] op_sel_hi:[0,0] neg_lo:[0,1]
	v_pk_mul_f32 v[142:143], v[66:67], v[140:141] op_sel:[1,1] op_sel_hi:[0,1] neg_hi:[1,0]
	v_pk_fma_f32 v[138:139], v[24:25], v[140:141], v[138:139]
	v_pk_fma_f32 v[66:67], v[66:67], v[140:141], v[142:143] op_sel_hi:[1,0,1]
	v_pk_mul_f32 v[140:141], v[26:27], v[134:135] op_sel:[0,1] op_sel_hi:[0,0] neg_lo:[0,1]
	v_pk_fma_f32 v[134:135], v[24:25], v[134:135], v[140:141]
	s_nop 0
	v_pk_mul_f32 v[140:141], v[16:17], v[134:135] op_sel:[1,1] op_sel_hi:[0,1] neg_hi:[1,0]
	s_nop 0
	v_pk_fma_f32 v[16:17], v[16:17], v[134:135], v[140:141] op_sel_hi:[1,0,1]
	v_pk_mul_f32 v[140:141], v[26:27], v[138:139] op_sel:[0,1] op_sel_hi:[0,0] neg_lo:[0,1]
	v_pk_mul_f32 v[142:143], v[18:19], v[138:139] op_sel:[1,1] op_sel_hi:[0,1] neg_hi:[1,0]
	v_pk_fma_f32 v[140:141], v[24:25], v[138:139], v[140:141]
	v_pk_fma_f32 v[18:19], v[18:19], v[138:139], v[142:143] op_sel_hi:[1,0,1]
	v_pk_mul_f32 v[138:139], v[26:27], v[134:135] op_sel:[0,1] op_sel_hi:[0,0] neg_lo:[0,1]
	v_pk_fma_f32 v[134:135], v[24:25], v[134:135], v[138:139]
	s_nop 0
	v_pk_mul_f32 v[138:139], v[12:13], v[134:135] op_sel:[1,1] op_sel_hi:[0,1] neg_hi:[1,0]
	s_nop 0
	v_pk_fma_f32 v[12:13], v[12:13], v[134:135], v[138:139] op_sel_hi:[1,0,1]
	v_pk_mul_f32 v[138:139], v[26:27], v[140:141] op_sel:[0,1] op_sel_hi:[0,0] neg_lo:[0,1]
	v_pk_mul_f32 v[142:143], v[14:15], v[140:141] op_sel:[1,1] op_sel_hi:[0,1] neg_hi:[1,0]
	v_pk_fma_f32 v[138:139], v[24:25], v[140:141], v[138:139]
	v_pk_fma_f32 v[14:15], v[14:15], v[140:141], v[142:143] op_sel_hi:[1,0,1]
	v_pk_mul_f32 v[140:141], v[26:27], v[134:135] op_sel:[0,1] op_sel_hi:[0,0] neg_lo:[0,1]
	v_pk_fma_f32 v[134:135], v[24:25], v[134:135], v[140:141]
	s_nop 0
	v_pk_mul_f32 v[140:141], v[8:9], v[134:135] op_sel:[1,1] op_sel_hi:[0,1] neg_hi:[1,0]
	s_nop 0
	v_pk_fma_f32 v[8:9], v[8:9], v[134:135], v[140:141] op_sel_hi:[1,0,1]
	v_pk_mul_f32 v[140:141], v[26:27], v[138:139] op_sel:[0,1] op_sel_hi:[0,0] neg_lo:[0,1]
	v_pk_mul_f32 v[142:143], v[10:11], v[138:139] op_sel:[1,1] op_sel_hi:[0,1] neg_hi:[1,0]
	v_pk_fma_f32 v[140:141], v[24:25], v[138:139], v[140:141]
	v_pk_fma_f32 v[10:11], v[10:11], v[138:139], v[142:143] op_sel_hi:[1,0,1]
	v_pk_mul_f32 v[138:139], v[26:27], v[134:135] op_sel:[0,1] op_sel_hi:[0,0] neg_lo:[0,1]
	v_pk_fma_f32 v[24:25], v[24:25], v[134:135], v[138:139]
	s_nop 0
	v_pk_mul_f32 v[134:135], v[4:5], v[24:25] op_sel:[1,1] op_sel_hi:[0,1] neg_hi:[1,0]
	s_nop 0
	v_pk_fma_f32 v[4:5], v[4:5], v[24:25], v[134:135] op_sel_hi:[1,0,1]
	v_pk_mul_f32 v[24:25], v[6:7], v[140:141] op_sel:[1,1] op_sel_hi:[0,1] neg_hi:[1,0]
	s_nop 0
	v_pk_fma_f32 v[6:7], v[6:7], v[140:141], v[24:25] op_sel_hi:[1,0,1]
	ds_write_b64 v27, v[2:3]
	ds_write_b64 v96, v[84:85]
	ds_write_b64 v97, v[90:91] offset:256
	ds_write_b64 v98, v[16:17] offset:256
	ds_write_b64 v99, v[72:73] offset:512
	ds_write_b64 v100, v[70:71] offset:512
	ds_write_b64 v101, v[128:129] offset:768
	ds_write_b64 v102, v[8:9] offset:768
	ds_write_b64 v103, v[62:63] offset:1024
	ds_write_b64 v104, v[80:81] offset:1024
	ds_write_b64 v105, v[94:95] offset:1280
	ds_write_b64 v106, v[12:13] offset:1280
	ds_write_b64 v107, v[78:79] offset:1536
	ds_write_b64 v108, v[64:65] offset:1536
	ds_write_b64 v109, v[130:131] offset:1792
	ds_write_b64 v110, v[4:5] offset:1792
	ds_write_b64 v111, v[20:21] offset:2048
	ds_write_b64 v112, v[88:89] offset:2048
	ds_write_b64 v113, v[86:87] offset:2304
	ds_write_b64 v114, v[18:19] offset:2304
	ds_write_b64 v115, v[68:69] offset:2560
	ds_write_b64 v116, v[74:75] offset:2560
	ds_write_b64 v117, v[132:133] offset:2816
	ds_write_b64 v118, v[10:11] offset:2816
	ds_write_b64 v119, v[22:23] offset:3072
	ds_write_b64 v120, v[82:83] offset:3072
	ds_write_b64 v121, v[92:93] offset:3328
	ds_write_b64 v122, v[14:15] offset:3328
	ds_write_b64 v123, v[76:77] offset:3584
	ds_write_b64 v124, v[66:67] offset:3584
	ds_write_b64 v125, v[136:137] offset:3840
	ds_write_b64 v126, v[6:7] offset:3840
	v_mov_b32_e32 v2, v146
	s_waitcnt lgkmcnt(0)
	s_barrier
	s_nop 0
	v_lshlrev_b32_e32 v3, 4, v2
	v_lshrrev_b32_e32 v4, 1, v2
	v_bfe_u32 v2, v2, 1, 4
	v_bitop3_b32 v5, v4, v3, 16 bitop3:0x6c
	v_lshl_add_u32 v5, v5, 3, 16
	v_lshlrev_b32_e32 v2, 3, v2
	v_add_u32_e32 v6, v5, v2
	ds_read_b64 v[12:13], v6
	v_bitop3_b32 v6, v4, 1, 15 bitop3:0x6c
	v_lshlrev_b32_e32 v8, 3, v6
	v_add_u32_e32 v6, v5, v8
	ds_read_b64 v[14:15], v6
	v_bitop3_b32 v6, v4, 2, 15 bitop3:0x6c
	v_lshlrev_b32_e32 v9, 3, v6
	v_add_u32_e32 v6, v5, v9
	ds_read_b64 v[16:17], v6
	v_bitop3_b32 v6, v4, 3, 15 bitop3:0x6c
	v_lshlrev_b32_e32 v10, 3, v6
	v_add_u32_e32 v6, v5, v10
	ds_read_b64 v[18:19], v6
	v_bitop3_b32 v6, v4, 4, 15 bitop3:0x6c
	v_lshlrev_b32_e32 v11, 3, v6
	v_add_u32_e32 v6, v5, v11
	ds_read_b64 v[20:21], v6
	v_bitop3_b32 v6, v4, 5, 15 bitop3:0x6c
	v_lshlrev_b32_e32 v82, 3, v6
	v_add_u32_e32 v6, v5, v82
	ds_read_b64 v[22:23], v6
	v_bitop3_b32 v6, v4, 6, 15 bitop3:0x6c
	v_lshlrev_b32_e32 v83, 3, v6
	v_add_u32_e32 v6, v5, v83
	ds_read_b64 v[24:25], v6
	v_bitop3_b32 v6, v4, 7, 15 bitop3:0x6c
	v_lshlrev_b32_e32 v84, 3, v6
	v_add_u32_e32 v6, v5, v84
	ds_read_b64 v[26:27], v6
	v_bitop3_b32 v6, v4, 8, 15 bitop3:0x6c
	v_lshlrev_b32_e32 v85, 3, v6
	v_add_u32_e32 v6, v5, v85
	ds_read_b64 v[62:63], v6
	v_bitop3_b32 v6, v4, 9, 15 bitop3:0x6c
	v_lshlrev_b32_e32 v86, 3, v6
	v_add_u32_e32 v6, v5, v86
	ds_read_b64 v[64:65], v6
	v_bitop3_b32 v6, v4, 10, 15 bitop3:0x6c
	v_lshlrev_b32_e32 v87, 3, v6
	v_add_u32_e32 v6, v5, v87
	ds_read_b64 v[66:67], v6
	v_bitop3_b32 v6, v4, 11, 15 bitop3:0x6c
	v_lshlrev_b32_e32 v88, 3, v6
	v_add_u32_e32 v6, v5, v88
	ds_read_b64 v[68:69], v6
	v_bitop3_b32 v6, v4, 12, 15 bitop3:0x6c
	v_lshlrev_b32_e32 v89, 3, v6
	v_add_u32_e32 v6, v5, v89
	ds_read_b64 v[70:71], v6
	v_bitop3_b32 v6, v4, 13, 15 bitop3:0x6c
	v_lshlrev_b32_e32 v90, 3, v6
	v_add_u32_e32 v6, v5, v90
	ds_read_b64 v[72:73], v6
	v_bitop3_b32 v6, v4, 14, 15 bitop3:0x6c
	v_lshlrev_b32_e32 v91, 3, v6
	v_add_u32_e32 v6, v5, v91
	v_add_u32_e32 v3, 0x2000, v3
	ds_read_b64 v[74:75], v6
	v_bitop3_b32 v6, v4, 15, v4 bitop3:0xc
	v_bitop3_b32 v3, v3, v4, 16 bitop3:0x78
	v_lshlrev_b32_e32 v106, 3, v6
	v_lshl_add_u32 v107, v3, 3, 16
	v_add_u32_e32 v5, v5, v106
	v_add_u32_e32 v2, v107, v2
	ds_read_b64 v[76:77], v5
	ds_read_b64 v[6:7], v2
	v_add_u32_e32 v2, v107, v8
	ds_read_b64 v[78:79], v2
	v_add_u32_e32 v2, v107, v9
	ds_read_b64 v[8:9], v2
	v_add_u32_e32 v2, v107, v10
	ds_read_b64 v[80:81], v2
	v_add_u32_e32 v2, v107, v11
	ds_read_b64 v[10:11], v2
	v_add_u32_e32 v2, v107, v82
	v_add_u32_e32 v82, v107, v84
	v_add_u32_e32 v84, v107, v85
	ds_read_b64 v[4:5], v2
	ds_read_b64 v[92:93], v84
	v_add_u32_e32 v2, v107, v83
	v_add_u32_e32 v84, v107, v86
	ds_read_b64 v[2:3], v2
	ds_read_b64 v[82:83], v82
	ds_read_b64 v[94:95], v84
	v_add_u32_e32 v84, v107, v87
	ds_read_b64 v[96:97], v84
	v_add_u32_e32 v84, v107, v88
	ds_read_b64 v[98:99], v84
	v_add_u32_e32 v84, v107, v89
	ds_read_b64 v[100:101], v84
	v_add_u32_e32 v84, v107, v90
	ds_read_b64 v[102:103], v84
	v_add_u32_e32 v84, v107, v91
	ds_read_b64 v[104:105], v84
	v_add_u32_e32 v84, v107, v106
	ds_read_b64 v[106:107], v84
	s_waitcnt lgkmcnt(14)
	v_pk_add_f32 v[84:85], v[12:13], v[62:63]
	v_pk_add_f32 v[12:13], v[12:13], v[62:63] neg_lo:[0,1] neg_hi:[0,1]
	v_pk_add_f32 v[62:63], v[14:15], v[64:65]
	v_pk_add_f32 v[14:15], v[14:15], v[64:65] neg_lo:[0,1] neg_hi:[0,1]
	s_nop 0
	v_pk_mul_f32 v[64:65], v[14:15], s[54:55] op_sel:[1,0] op_sel_hi:[0,0] neg_hi:[1,0]
	s_nop 0
	v_pk_fma_f32 v[14:15], v[14:15], s[52:53], v[64:65] op_sel_hi:[1,0,1]
	v_pk_add_f32 v[64:65], v[16:17], v[66:67]
	v_pk_add_f32 v[16:17], v[16:17], v[66:67] neg_lo:[0,1] neg_hi:[0,1]
	s_nop 0
	v_pk_mul_f32 v[66:67], v[16:17], s[60:61] op_sel:[1,0] op_sel_hi:[0,0] neg_hi:[1,0]
	s_nop 0
	v_pk_fma_f32 v[16:17], v[16:17], s[60:61], v[66:67] op_sel_hi:[1,0,1]
	v_pk_add_f32 v[66:67], v[18:19], v[68:69]
	v_pk_add_f32 v[18:19], v[18:19], v[68:69] neg_lo:[0,1] neg_hi:[0,1]
	s_nop 0
	v_pk_mul_f32 v[68:69], v[18:19], s[52:53] op_sel:[1,0] op_sel_hi:[0,0] neg_hi:[1,0]
	s_nop 0
	v_pk_fma_f32 v[18:19], v[18:19], s[54:55], v[68:69] op_sel_hi:[1,0,1]
	v_pk_add_f32 v[68:69], v[20:21], v[70:71]
	v_pk_add_f32 v[20:21], v[20:21], v[70:71] neg_lo:[0,1] neg_hi:[0,1]
	s_nop 0
	v_xor_b32_e32 v71, 0x80000000, v20
	v_mov_b32_e32 v70, v21
	v_pk_add_f32 v[20:21], v[22:23], v[72:73]
	v_pk_add_f32 v[22:23], v[22:23], v[72:73] neg_lo:[0,1] neg_hi:[0,1]
	s_nop 0
	v_pk_mul_f32 v[72:73], v[22:23], s[54:55] op_sel_hi:[1,0]
	v_xor_b32_e32 v87, 0x80000000, v22
	v_mov_b32_e32 v86, v23
	v_pk_fma_f32 v[22:23], v[86:87], s[52:53], v[72:73] op_sel_hi:[1,0,1] neg_lo:[0,0,1] neg_hi:[0,0,1]
	v_pk_add_f32 v[72:73], v[24:25], v[74:75]
	v_pk_add_f32 v[24:25], v[24:25], v[74:75] neg_lo:[0,1] neg_hi:[0,1]
	s_nop 0
	v_pk_mul_f32 v[74:75], v[24:25], s[60:61] op_sel_hi:[1,0]
	v_xor_b32_e32 v87, 0x80000000, v24
	v_mov_b32_e32 v86, v25
	v_pk_fma_f32 v[24:25], v[86:87], s[60:61], v[74:75] op_sel_hi:[1,0,1] neg_lo:[0,0,1] neg_hi:[0,0,1]
	v_pk_add_f32 v[74:75], v[26:27], v[76:77]
	v_pk_add_f32 v[26:27], v[26:27], v[76:77] neg_lo:[0,1] neg_hi:[0,1]
	s_nop 0
	v_pk_mul_f32 v[76:77], v[26:27], s[52:53] op_sel_hi:[1,0]
	v_xor_b32_e32 v87, 0x80000000, v26
	v_mov_b32_e32 v86, v27
	v_pk_fma_f32 v[26:27], v[86:87], s[54:55], v[76:77] op_sel_hi:[1,0,1] neg_lo:[0,0,1] neg_hi:[0,0,1]
	v_pk_add_f32 v[76:77], v[84:85], v[68:69]
	v_pk_add_f32 v[68:69], v[84:85], v[68:69] neg_lo:[0,1] neg_hi:[0,1]
	v_pk_add_f32 v[84:85], v[62:63], v[20:21]
	v_pk_add_f32 v[20:21], v[62:63], v[20:21] neg_lo:[0,1] neg_hi:[0,1]
	s_nop 0
	v_pk_mul_f32 v[62:63], v[20:21], s[60:61] op_sel:[1,0] op_sel_hi:[0,0] neg_hi:[1,0]
	s_nop 0
	v_pk_fma_f32 v[20:21], v[20:21], s[60:61], v[62:63] op_sel_hi:[1,0,1]
	v_pk_add_f32 v[62:63], v[64:65], v[72:73]
	v_pk_add_f32 v[64:65], v[64:65], v[72:73] neg_lo:[0,1] neg_hi:[0,1]
	s_nop 0
	v_xor_b32_e32 v73, 0x80000000, v64
	v_mov_b32_e32 v72, v65
	v_pk_add_f32 v[64:65], v[66:67], v[74:75]
	v_pk_add_f32 v[66:67], v[66:67], v[74:75] neg_lo:[0,1] neg_hi:[0,1]
	s_nop 0
	v_pk_mul_f32 v[74:75], v[66:67], s[60:61] op_sel_hi:[1,0]
	v_xor_b32_e32 v87, 0x80000000, v66
	v_mov_b32_e32 v86, v67
	v_pk_fma_f32 v[66:67], v[86:87], s[60:61], v[74:75] op_sel_hi:[1,0,1] neg_lo:[0,0,1] neg_hi:[0,0,1]
	v_pk_add_f32 v[74:75], v[12:13], v[70:71]
	v_pk_add_f32 v[12:13], v[12:13], v[70:71] neg_lo:[0,1] neg_hi:[0,1]
	v_pk_add_f32 v[70:71], v[14:15], v[22:23]
	v_pk_add_f32 v[14:15], v[14:15], v[22:23] neg_lo:[0,1] neg_hi:[0,1]
	s_nop 0
	v_pk_mul_f32 v[22:23], v[14:15], s[60:61] op_sel:[1,0] op_sel_hi:[0,0] neg_hi:[1,0]
	s_nop 0
	v_pk_fma_f32 v[14:15], v[14:15], s[60:61], v[22:23] op_sel_hi:[1,0,1]
	v_pk_add_f32 v[22:23], v[16:17], v[24:25]
	v_pk_add_f32 v[16:17], v[16:17], v[24:25] neg_lo:[0,1] neg_hi:[0,1]
	s_nop 0
	v_xor_b32_e32 v25, 0x80000000, v16
	v_mov_b32_e32 v24, v17
	v_pk_add_f32 v[16:17], v[18:19], v[26:27]
	v_pk_add_f32 v[18:19], v[18:19], v[26:27] neg_lo:[0,1] neg_hi:[0,1]
	v_pk_add_f32 v[108:109], v[12:13], v[24:25]
	v_pk_mul_f32 v[26:27], v[18:19], s[60:61] op_sel_hi:[1,0]
	s_nop 0
	v_pk_fma_f32 v[18:19], v[18:19], s[60:61], v[26:27] op_sel:[1,0,0] op_sel_hi:[0,0,1] neg_lo:[0,0,1] neg_hi:[1,0,1]
	v_pk_add_f32 v[26:27], v[76:77], v[62:63]
	v_pk_add_f32 v[62:63], v[76:77], v[62:63] neg_lo:[0,1] neg_hi:[0,1]
	v_pk_add_f32 v[76:77], v[84:85], v[64:65]
	v_pk_add_f32 v[64:65], v[84:85], v[64:65] neg_lo:[0,1] neg_hi:[0,1]
	v_pk_add_f32 v[110:111], v[12:13], v[24:25] neg_lo:[0,1] neg_hi:[0,1]
	v_xor_b32_e32 v85, 0x80000000, v64
	v_mov_b32_e32 v84, v65
	v_pk_add_f32 v[64:65], v[68:69], v[72:73]
	v_pk_add_f32 v[68:69], v[68:69], v[72:73] neg_lo:[0,1] neg_hi:[0,1]
	v_pk_add_f32 v[72:73], v[20:21], v[66:67]
	v_pk_add_f32 v[20:21], v[20:21], v[66:67] neg_lo:[0,1] neg_hi:[0,1]
	v_pk_add_f32 v[12:13], v[14:15], v[18:19] neg_lo:[0,1] neg_hi:[0,1]
	v_pk_add_f32 v[112:113], v[14:15], v[18:19]
	v_xor_b32_e32 v115, 0x80000000, v12
	v_mov_b32_e32 v114, v13
	v_pk_add_f32 v[12:13], v[26:27], v[76:77]
	v_pk_add_f32 v[14:15], v[26:27], v[76:77] neg_lo:[0,1] neg_hi:[0,1]
	v_pk_add_f32 v[24:25], v[68:69], v[20:21] op_sel:[0,1] op_sel_hi:[1,0] neg_hi:[0,1]
	v_pk_add_f32 v[26:27], v[68:69], v[20:21] op_sel:[0,1] op_sel_hi:[1,0] neg_lo:[0,1]
	s_waitcnt lgkmcnt(6)
	v_pk_add_f32 v[66:67], v[78:79], v[94:95] neg_lo:[0,1] neg_hi:[0,1]
	v_pk_add_f32 v[86:87], v[74:75], v[22:23]
	v_pk_mul_f32 v[76:77], v[66:67], s[54:55] op_sel:[1,0] op_sel_hi:[0,0] neg_hi:[1,0]
	v_pk_add_f32 v[74:75], v[74:75], v[22:23] neg_lo:[0,1] neg_hi:[0,1]
	v_pk_fma_f32 v[66:67], v[66:67], s[52:53], v[76:77] op_sel_hi:[1,0,1]
	s_waitcnt lgkmcnt(5)
	v_pk_add_f32 v[76:77], v[8:9], v[96:97]
	v_pk_add_f32 v[8:9], v[8:9], v[96:97] neg_lo:[0,1] neg_hi:[0,1]
	v_pk_add_f32 v[20:21], v[64:65], v[72:73]
	v_pk_add_f32 v[22:23], v[64:65], v[72:73] neg_lo:[0,1] neg_hi:[0,1]
	v_pk_add_f32 v[64:65], v[78:79], v[94:95]
	v_pk_mul_f32 v[78:79], v[8:9], s[60:61] op_sel:[1,0] op_sel_hi:[0,0] neg_hi:[1,0]
	v_pk_add_f32 v[88:89], v[70:71], v[16:17]
	v_pk_add_f32 v[16:17], v[70:71], v[16:17] neg_lo:[0,1] neg_hi:[0,1]
	v_pk_fma_f32 v[8:9], v[8:9], s[60:61], v[78:79] op_sel_hi:[1,0,1]
	s_waitcnt lgkmcnt(4)
	v_pk_add_f32 v[78:79], v[80:81], v[98:99]
	v_pk_add_f32 v[80:81], v[80:81], v[98:99] neg_lo:[0,1] neg_hi:[0,1]
	v_xor_b32_e32 v91, 0x80000000, v16
	v_mov_b32_e32 v90, v17
	v_pk_add_f32 v[16:17], v[62:63], v[84:85]
	v_pk_add_f32 v[18:19], v[62:63], v[84:85] neg_lo:[0,1] neg_hi:[0,1]
	v_pk_add_f32 v[62:63], v[6:7], v[92:93]
	v_pk_add_f32 v[6:7], v[6:7], v[92:93] neg_lo:[0,1] neg_hi:[0,1]
	v_pk_mul_f32 v[92:93], v[80:81], s[52:53] op_sel:[1,0] op_sel_hi:[0,0] neg_hi:[1,0]
	v_pk_add_f32 v[68:69], v[86:87], v[88:89]
	v_pk_fma_f32 v[80:81], v[80:81], s[54:55], v[92:93] op_sel_hi:[1,0,1]
	s_waitcnt lgkmcnt(3)
	v_pk_add_f32 v[92:93], v[10:11], v[100:101]
	v_pk_add_f32 v[10:11], v[10:11], v[100:101] neg_lo:[0,1] neg_hi:[0,1]
	v_pk_add_f32 v[70:71], v[86:87], v[88:89] neg_lo:[0,1] neg_hi:[0,1]
	v_xor_b32_e32 v95, 0x80000000, v10
	v_mov_b32_e32 v94, v11
	s_waitcnt lgkmcnt(2)
	v_pk_add_f32 v[10:11], v[4:5], v[102:103]
	v_pk_add_f32 v[4:5], v[4:5], v[102:103] neg_lo:[0,1] neg_hi:[0,1]
	v_pk_add_f32 v[84:85], v[108:109], v[112:113]
	v_pk_mul_f32 v[96:97], v[4:5], s[54:55] op_sel_hi:[1,0]
	s_nop 0
	v_pk_fma_f32 v[4:5], v[4:5], s[52:53], v[96:97] op_sel:[1,0,0] op_sel_hi:[0,0,1] neg_lo:[0,0,1] neg_hi:[1,0,1]
	s_waitcnt lgkmcnt(1)
	v_pk_add_f32 v[96:97], v[2:3], v[104:105]
	v_pk_add_f32 v[2:3], v[2:3], v[104:105] neg_lo:[0,1] neg_hi:[0,1]
	v_pk_add_f32 v[86:87], v[108:109], v[112:113] neg_lo:[0,1] neg_hi:[0,1]
	v_pk_mul_f32 v[98:99], v[2:3], s[60:61] op_sel_hi:[1,0]
	s_nop 0
	v_pk_fma_f32 v[2:3], v[2:3], s[60:61], v[98:99] op_sel:[1,0,0] op_sel_hi:[0,0,1] neg_lo:[0,0,1] neg_hi:[1,0,1]
	s_waitcnt lgkmcnt(0)
	v_pk_add_f32 v[98:99], v[82:83], v[106:107]
	v_pk_add_f32 v[82:83], v[82:83], v[106:107] neg_lo:[0,1] neg_hi:[0,1]
	v_pk_add_f32 v[72:73], v[74:75], v[90:91]
	v_pk_mul_f32 v[100:101], v[82:83], s[52:53] op_sel_hi:[1,0]
	v_xor_b32_e32 v103, 0x80000000, v82
	v_mov_b32_e32 v102, v83
	v_pk_fma_f32 v[82:83], v[102:103], s[54:55], v[100:101] op_sel_hi:[1,0,1] neg_lo:[0,0,1] neg_hi:[0,0,1]
	v_pk_add_f32 v[100:101], v[62:63], v[92:93]
	v_pk_add_f32 v[62:63], v[62:63], v[92:93] neg_lo:[0,1] neg_hi:[0,1]
	v_pk_add_f32 v[92:93], v[64:65], v[10:11]
	v_pk_add_f32 v[10:11], v[64:65], v[10:11] neg_lo:[0,1] neg_hi:[0,1]
	v_pk_add_f32 v[74:75], v[74:75], v[90:91] neg_lo:[0,1] neg_hi:[0,1]
	v_pk_mul_f32 v[64:65], v[10:11], s[60:61] op_sel:[1,0] op_sel_hi:[0,0] neg_hi:[1,0]
	v_pk_add_f32 v[88:89], v[110:111], v[114:115]
	v_pk_fma_f32 v[10:11], v[10:11], s[60:61], v[64:65] op_sel_hi:[1,0,1]
	v_pk_add_f32 v[64:65], v[76:77], v[96:97]
	v_pk_add_f32 v[76:77], v[76:77], v[96:97] neg_lo:[0,1] neg_hi:[0,1]
	v_pk_add_f32 v[90:91], v[110:111], v[114:115] neg_lo:[0,1] neg_hi:[0,1]
	v_xor_b32_e32 v97, 0x80000000, v76
	v_mov_b32_e32 v96, v77
	v_pk_add_f32 v[76:77], v[78:79], v[98:99]
	v_pk_add_f32 v[78:79], v[78:79], v[98:99] neg_lo:[0,1] neg_hi:[0,1]
	s_nop 0
	v_pk_mul_f32 v[98:99], v[78:79], s[60:61] op_sel_hi:[1,0]
	v_xor_b32_e32 v103, 0x80000000, v78
	v_mov_b32_e32 v102, v79
	v_pk_fma_f32 v[78:79], v[102:103], s[60:61], v[98:99] op_sel_hi:[1,0,1] neg_lo:[0,0,1] neg_hi:[0,0,1]
	v_pk_add_f32 v[98:99], v[6:7], v[94:95]
	v_pk_add_f32 v[6:7], v[6:7], v[94:95] neg_lo:[0,1] neg_hi:[0,1]
	v_pk_add_f32 v[94:95], v[66:67], v[4:5]
	v_pk_add_f32 v[4:5], v[66:67], v[4:5] neg_lo:[0,1] neg_hi:[0,1]
	s_nop 0
	v_pk_mul_f32 v[66:67], v[4:5], s[60:61] op_sel:[1,0] op_sel_hi:[0,0] neg_hi:[1,0]
	s_nop 0
	v_pk_fma_f32 v[4:5], v[4:5], s[60:61], v[66:67] op_sel_hi:[1,0,1]
	v_pk_add_f32 v[66:67], v[8:9], v[2:3]
	v_pk_add_f32 v[2:3], v[8:9], v[2:3] neg_lo:[0,1] neg_hi:[0,1]
	v_pk_add_f32 v[106:107], v[98:99], v[66:67] neg_lo:[0,1] neg_hi:[0,1]
	v_xor_b32_e32 v9, 0x80000000, v2
	v_mov_b32_e32 v8, v3
	v_pk_add_f32 v[2:3], v[80:81], v[82:83]
	v_pk_add_f32 v[80:81], v[80:81], v[82:83] neg_lo:[0,1] neg_hi:[0,1]
	v_pk_add_f32 v[108:109], v[94:95], v[2:3]
	v_pk_mul_f32 v[82:83], v[80:81], s[60:61] op_sel_hi:[1,0]
	s_nop 0
	v_pk_fma_f32 v[80:81], v[80:81], s[60:61], v[82:83] op_sel:[1,0,0] op_sel_hi:[0,0,1] neg_lo:[0,0,1] neg_hi:[1,0,1]
	v_pk_add_f32 v[82:83], v[100:101], v[64:65]
	v_pk_add_f32 v[64:65], v[100:101], v[64:65] neg_lo:[0,1] neg_hi:[0,1]
	v_pk_add_f32 v[100:101], v[92:93], v[76:77]
	v_pk_add_f32 v[76:77], v[92:93], v[76:77] neg_lo:[0,1] neg_hi:[0,1]
	v_pk_add_f32 v[102:103], v[10:11], v[78:79]
	v_xor_b32_e32 v93, 0x80000000, v76
	v_mov_b32_e32 v92, v77
	v_pk_add_f32 v[76:77], v[62:63], v[96:97]
	v_pk_add_f32 v[10:11], v[10:11], v[78:79] neg_lo:[0,1] neg_hi:[0,1]
	v_pk_add_f32 v[2:3], v[94:95], v[2:3] neg_lo:[0,1] neg_hi:[0,1]
	v_pk_add_f32 v[62:63], v[62:63], v[96:97] neg_lo:[0,1] neg_hi:[0,1]
	v_xor_b32_e32 v105, 0x80000000, v10
	v_mov_b32_e32 v104, v11
	v_pk_add_f32 v[10:11], v[98:99], v[66:67]
	v_xor_b32_e32 v111, 0x80000000, v2
	v_mov_b32_e32 v110, v3
	v_pk_add_f32 v[112:113], v[6:7], v[8:9]
	v_pk_add_f32 v[114:115], v[6:7], v[8:9] neg_lo:[0,1] neg_hi:[0,1]
	v_pk_add_f32 v[6:7], v[4:5], v[80:81]
	v_pk_add_f32 v[2:3], v[4:5], v[80:81] neg_lo:[0,1] neg_hi:[0,1]
	v_pk_add_f32 v[98:99], v[82:83], v[100:101]
	v_pk_add_f32 v[96:97], v[82:83], v[100:101] neg_lo:[0,1] neg_hi:[0,1]
	v_pk_add_f32 v[82:83], v[76:77], v[102:103]
	v_pk_add_f32 v[80:81], v[76:77], v[102:103] neg_lo:[0,1] neg_hi:[0,1]
	s_waitcnt vmcnt(7)
	v_mov_b64 v[100:101], v[164:165]
	v_mov_b64 v[102:103], v[166:167]
	v_pk_add_f32 v[78:79], v[62:63], v[104:105]
	v_pk_add_f32 v[76:77], v[62:63], v[104:105] neg_lo:[0,1] neg_hi:[0,1]
	v_xor_b32_e32 v5, 0x80000000, v2
	v_mov_b32_e32 v4, v3
	v_pk_add_f32 v[62:63], v[106:107], v[110:111]
	v_pk_add_f32 v[2:3], v[106:107], v[110:111] neg_lo:[0,1] neg_hi:[0,1]
	v_pk_add_f32 v[94:95], v[64:65], v[92:93]
	v_pk_add_f32 v[92:93], v[64:65], v[92:93] neg_lo:[0,1] neg_hi:[0,1]
	v_pk_add_f32 v[66:67], v[10:11], v[108:109]
	v_pk_add_f32 v[64:65], v[10:11], v[108:109] neg_lo:[0,1] neg_hi:[0,1]
	v_pk_add_f32 v[10:11], v[112:113], v[6:7]
	v_pk_add_f32 v[8:9], v[112:113], v[6:7] neg_lo:[0,1] neg_hi:[0,1]
	v_pk_add_f32 v[6:7], v[114:115], v[4:5]
	v_pk_add_f32 v[4:5], v[114:115], v[4:5] neg_lo:[0,1] neg_hi:[0,1]
	v_cvt_f32_f16_e32 v104, v100
	v_cvt_f32_f16_sdwa v100, v100 dst_sel:DWORD dst_unused:UNUSED_PAD src0_sel:WORD_1
	v_mul_f32_e32 v104, 0x38800000, v104
	v_mul_f32_e32 v100, 0x38800000, v100
	s_nop 0
	v_pk_mul_f32 v[106:107], v[12:13], v[100:101] op_sel:[1,0] op_sel_hi:[0,0] neg_lo:[1,0]
	v_cvt_f32_f16_e32 v100, v101
	v_cvt_f32_f16_sdwa v101, v101 dst_sel:DWORD dst_unused:UNUSED_PAD src0_sel:WORD_1
	v_pk_fma_f32 v[12:13], v[12:13], v[104:105], v[106:107] op_sel_hi:[1,0,1]
	v_xor_b32_e32 v106, 0x80000000, v15
	v_mov_b32_e32 v107, v14
	v_mul_f32_e32 v104, 0x38800000, v101
	v_mul_f32_e32 v100, 0x38800000, v100
	v_pk_mul_f32 v[104:105], v[106:107], v[104:105] op_sel_hi:[1,0]
	v_xor_b32_e32 v106, 0x80000000, v21
	v_pk_fma_f32 v[14:15], v[14:15], v[100:101], v[104:105] op_sel_hi:[1,0,1]
	v_cvt_f32_f16_sdwa v101, v102 dst_sel:DWORD dst_unused:UNUSED_PAD src0_sel:WORD_1
	v_cvt_f32_f16_e32 v100, v102
	s_nop 0
	s_nop 0
	v_mul_f32_e32 v102, 0x38800000, v101
	v_mul_f32_e32 v100, 0x38800000, v100
	v_pk_mul_f32 v[104:105], v[16:17], v[102:103] op_sel:[1,0] op_sel_hi:[0,0] neg_lo:[1,0]
	v_mov_b32_e32 v107, v20
	v_pk_fma_f32 v[16:17], v[16:17], v[100:101], v[104:105] op_sel_hi:[1,0,1]
	v_cvt_f32_f16_sdwa v101, v103 dst_sel:DWORD dst_unused:UNUSED_PAD src0_sel:WORD_1
	v_cvt_f32_f16_e32 v100, v103
	v_xor_b32_e32 v104, 0x80000000, v19
	v_mov_b32_e32 v105, v18
	v_mul_f32_e32 v102, 0x38800000, v101
	v_mul_f32_e32 v100, 0x38800000, v100
	v_pk_mul_f32 v[102:103], v[104:105], v[102:103] op_sel_hi:[1,0]
	s_nop 0
	v_pk_fma_f32 v[18:19], v[18:19], v[100:101], v[102:103] op_sel_hi:[1,0,1]
	s_waitcnt vmcnt(6)
	v_mov_b64 v[100:101], v[168:169]
	v_mov_b64 v[102:103], v[170:171]
	v_cvt_f32_f16_e32 v104, v100
	v_cvt_f32_f16_sdwa v100, v100 dst_sel:DWORD dst_unused:UNUSED_PAD src0_sel:WORD_1
	v_mul_f32_e32 v104, 0x38800000, v104
	v_mul_f32_e32 v100, 0x38800000, v100
	v_pk_mul_f32 v[106:107], v[106:107], v[100:101] op_sel_hi:[1,0]
	v_cvt_f32_f16_e32 v100, v101
	v_cvt_f32_f16_sdwa v101, v101 dst_sel:DWORD dst_unused:UNUSED_PAD src0_sel:WORD_1
	v_pk_fma_f32 v[20:21], v[20:21], v[104:105], v[106:107] op_sel_hi:[1,0,1]
	v_xor_b32_e32 v106, 0x80000000, v23
	v_mov_b32_e32 v107, v22
	v_mul_f32_e32 v104, 0x38800000, v101
	v_mul_f32_e32 v100, 0x38800000, v100
	v_pk_mul_f32 v[104:105], v[106:107], v[104:105] op_sel_hi:[1,0]
	v_xor_b32_e32 v106, 0x80000000, v69
	v_pk_fma_f32 v[22:23], v[22:23], v[100:101], v[104:105] op_sel_hi:[1,0,1]
	v_cvt_f32_f16_sdwa v101, v102 dst_sel:DWORD dst_unused:UNUSED_PAD src0_sel:WORD_1
	v_cvt_f32_f16_e32 v100, v102
	s_nop 0
	s_nop 0
	v_mul_f32_e32 v102, 0x38800000, v101
	v_mul_f32_e32 v100, 0x38800000, v100
	v_pk_mul_f32 v[104:105], v[24:25], v[102:103] op_sel:[1,0] op_sel_hi:[0,0] neg_lo:[1,0]
	v_mov_b32_e32 v107, v68
	v_pk_fma_f32 v[24:25], v[24:25], v[100:101], v[104:105] op_sel_hi:[1,0,1]
	v_cvt_f32_f16_sdwa v101, v103 dst_sel:DWORD dst_unused:UNUSED_PAD src0_sel:WORD_1
	v_cvt_f32_f16_e32 v100, v103
	v_xor_b32_e32 v104, 0x80000000, v27
	v_mov_b32_e32 v105, v26
	v_mul_f32_e32 v102, 0x38800000, v101
	v_mul_f32_e32 v100, 0x38800000, v100
	v_pk_mul_f32 v[102:103], v[104:105], v[102:103] op_sel_hi:[1,0]
	s_nop 0
	v_pk_fma_f32 v[26:27], v[26:27], v[100:101], v[102:103] op_sel_hi:[1,0,1]
	s_waitcnt vmcnt(5)
	v_mov_b64 v[100:101], v[172:173]
	v_mov_b64 v[102:103], v[174:175]
	v_cvt_f32_f16_e32 v104, v100
	v_cvt_f32_f16_sdwa v100, v100 dst_sel:DWORD dst_unused:UNUSED_PAD src0_sel:WORD_1
	v_mul_f32_e32 v104, 0x38800000, v104
	v_mul_f32_e32 v100, 0x38800000, v100
	v_pk_mul_f32 v[106:107], v[106:107], v[100:101] op_sel_hi:[1,0]
	v_cvt_f32_f16_e32 v100, v101
	v_cvt_f32_f16_sdwa v101, v101 dst_sel:DWORD dst_unused:UNUSED_PAD src0_sel:WORD_1
	v_pk_fma_f32 v[68:69], v[68:69], v[104:105], v[106:107] op_sel_hi:[1,0,1]
	v_xor_b32_e32 v106, 0x80000000, v71
	v_mov_b32_e32 v107, v70
	v_mul_f32_e32 v104, 0x38800000, v101
	v_mul_f32_e32 v100, 0x38800000, v100
	v_pk_mul_f32 v[104:105], v[106:107], v[104:105] op_sel_hi:[1,0]
	v_xor_b32_e32 v106, 0x80000000, v85
	v_pk_fma_f32 v[70:71], v[70:71], v[100:101], v[104:105] op_sel_hi:[1,0,1]
	v_cvt_f32_f16_sdwa v101, v102 dst_sel:DWORD dst_unused:UNUSED_PAD src0_sel:WORD_1
	v_cvt_f32_f16_e32 v100, v102
	s_nop 0
	s_nop 0
	v_mul_f32_e32 v102, 0x38800000, v101
	v_mul_f32_e32 v100, 0x38800000, v100
	v_pk_mul_f32 v[104:105], v[72:73], v[102:103] op_sel:[1,0] op_sel_hi:[0,0] neg_lo:[1,0]
	v_mov_b32_e32 v107, v84
	v_pk_fma_f32 v[72:73], v[72:73], v[100:101], v[104:105] op_sel_hi:[1,0,1]
	v_cvt_f32_f16_sdwa v101, v103 dst_sel:DWORD dst_unused:UNUSED_PAD src0_sel:WORD_1
	v_cvt_f32_f16_e32 v100, v103
	v_xor_b32_e32 v104, 0x80000000, v75
	v_mov_b32_e32 v105, v74
	v_mul_f32_e32 v102, 0x38800000, v101
	v_mul_f32_e32 v100, 0x38800000, v100
	v_pk_mul_f32 v[102:103], v[104:105], v[102:103] op_sel_hi:[1,0]
	s_nop 0
	v_pk_fma_f32 v[74:75], v[74:75], v[100:101], v[102:103] op_sel_hi:[1,0,1]
	s_waitcnt vmcnt(4)
	v_mov_b64 v[100:101], v[176:177]
	v_mov_b64 v[102:103], v[178:179]
	v_cvt_f32_f16_e32 v104, v100
	v_cvt_f32_f16_sdwa v100, v100 dst_sel:DWORD dst_unused:UNUSED_PAD src0_sel:WORD_1
	v_mul_f32_e32 v104, 0x38800000, v104
	v_mul_f32_e32 v100, 0x38800000, v100
	v_pk_mul_f32 v[106:107], v[106:107], v[100:101] op_sel_hi:[1,0]
	v_cvt_f32_f16_e32 v100, v101
	v_cvt_f32_f16_sdwa v101, v101 dst_sel:DWORD dst_unused:UNUSED_PAD src0_sel:WORD_1
	v_pk_fma_f32 v[84:85], v[84:85], v[104:105], v[106:107] op_sel_hi:[1,0,1]
	v_xor_b32_e32 v106, 0x80000000, v87
	v_mov_b32_e32 v107, v86
	v_mul_f32_e32 v104, 0x38800000, v101
	v_mul_f32_e32 v100, 0x38800000, v100
	v_pk_mul_f32 v[104:105], v[106:107], v[104:105] op_sel_hi:[1,0]
	v_xor_b32_e32 v106, 0x80000000, v99
	v_pk_fma_f32 v[86:87], v[86:87], v[100:101], v[104:105] op_sel_hi:[1,0,1]
	v_cvt_f32_f16_sdwa v101, v102 dst_sel:DWORD dst_unused:UNUSED_PAD src0_sel:WORD_1
	v_cvt_f32_f16_e32 v100, v102
	s_nop 0
	s_nop 0
	v_mul_f32_e32 v102, 0x38800000, v101
	v_mul_f32_e32 v100, 0x38800000, v100
	v_pk_mul_f32 v[104:105], v[88:89], v[102:103] op_sel:[1,0] op_sel_hi:[0,0] neg_lo:[1,0]
	v_mov_b32_e32 v107, v98
	v_pk_fma_f32 v[88:89], v[88:89], v[100:101], v[104:105] op_sel_hi:[1,0,1]
	v_cvt_f32_f16_sdwa v101, v103 dst_sel:DWORD dst_unused:UNUSED_PAD src0_sel:WORD_1
	v_cvt_f32_f16_e32 v100, v103
	v_xor_b32_e32 v104, 0x80000000, v91
	v_mov_b32_e32 v105, v90
	v_mul_f32_e32 v102, 0x38800000, v101
	v_mul_f32_e32 v100, 0x38800000, v100
	v_pk_mul_f32 v[102:103], v[104:105], v[102:103] op_sel_hi:[1,0]
	s_nop 0
	v_pk_fma_f32 v[90:91], v[90:91], v[100:101], v[102:103] op_sel_hi:[1,0,1]
	s_waitcnt vmcnt(3)
	v_mov_b64 v[100:101], v[180:181]
	v_mov_b64 v[102:103], v[182:183]
	v_cvt_f32_f16_e32 v104, v100
	v_cvt_f32_f16_sdwa v100, v100 dst_sel:DWORD dst_unused:UNUSED_PAD src0_sel:WORD_1
	v_mul_f32_e32 v104, 0x38800000, v104
	v_mul_f32_e32 v100, 0x38800000, v100
	v_pk_mul_f32 v[106:107], v[106:107], v[100:101] op_sel_hi:[1,0]
	v_cvt_f32_f16_e32 v100, v101
	v_cvt_f32_f16_sdwa v101, v101 dst_sel:DWORD dst_unused:UNUSED_PAD src0_sel:WORD_1
	v_pk_fma_f32 v[98:99], v[98:99], v[104:105], v[106:107] op_sel_hi:[1,0,1]
	v_xor_b32_e32 v106, 0x80000000, v97
	v_mov_b32_e32 v107, v96
	v_mul_f32_e32 v104, 0x38800000, v101
	v_mul_f32_e32 v100, 0x38800000, v100
	v_pk_mul_f32 v[104:105], v[106:107], v[104:105] op_sel_hi:[1,0]
	v_xor_b32_e32 v106, 0x80000000, v83
	v_pk_fma_f32 v[96:97], v[96:97], v[100:101], v[104:105] op_sel_hi:[1,0,1]
	v_cvt_f32_f16_sdwa v101, v102 dst_sel:DWORD dst_unused:UNUSED_PAD src0_sel:WORD_1
	v_cvt_f32_f16_e32 v100, v102
	s_nop 0
	s_nop 0
	v_mul_f32_e32 v102, 0x38800000, v101
	v_mul_f32_e32 v100, 0x38800000, v100
	v_pk_mul_f32 v[104:105], v[94:95], v[102:103] op_sel:[1,0] op_sel_hi:[0,0] neg_lo:[1,0]
	v_mov_b32_e32 v107, v82
	v_pk_fma_f32 v[94:95], v[94:95], v[100:101], v[104:105] op_sel_hi:[1,0,1]
	v_cvt_f32_f16_sdwa v101, v103 dst_sel:DWORD dst_unused:UNUSED_PAD src0_sel:WORD_1
	v_cvt_f32_f16_e32 v100, v103
	v_xor_b32_e32 v104, 0x80000000, v93
	v_mov_b32_e32 v105, v92
	v_mul_f32_e32 v102, 0x38800000, v101
	v_mul_f32_e32 v100, 0x38800000, v100
	v_pk_mul_f32 v[102:103], v[104:105], v[102:103] op_sel_hi:[1,0]
	s_nop 0
	v_pk_fma_f32 v[92:93], v[92:93], v[100:101], v[102:103] op_sel_hi:[1,0,1]
	s_waitcnt vmcnt(2)
	v_mov_b64 v[100:101], v[184:185]
	v_mov_b64 v[102:103], v[186:187]
	v_cvt_f32_f16_e32 v104, v100
	v_cvt_f32_f16_sdwa v100, v100 dst_sel:DWORD dst_unused:UNUSED_PAD src0_sel:WORD_1
	v_mul_f32_e32 v104, 0x38800000, v104
	v_mul_f32_e32 v100, 0x38800000, v100
	v_pk_mul_f32 v[106:107], v[106:107], v[100:101] op_sel_hi:[1,0]
	v_cvt_f32_f16_e32 v100, v101
	v_cvt_f32_f16_sdwa v101, v101 dst_sel:DWORD dst_unused:UNUSED_PAD src0_sel:WORD_1
	v_pk_fma_f32 v[82:83], v[82:83], v[104:105], v[106:107] op_sel_hi:[1,0,1]
	v_xor_b32_e32 v106, 0x80000000, v81
	v_mov_b32_e32 v107, v80
	v_mul_f32_e32 v104, 0x38800000, v101
	v_mul_f32_e32 v100, 0x38800000, v100
	v_pk_mul_f32 v[104:105], v[106:107], v[104:105] op_sel_hi:[1,0]
	v_xor_b32_e32 v106, 0x80000000, v67
	v_pk_fma_f32 v[80:81], v[80:81], v[100:101], v[104:105] op_sel_hi:[1,0,1]
	v_cvt_f32_f16_sdwa v101, v102 dst_sel:DWORD dst_unused:UNUSED_PAD src0_sel:WORD_1
	v_cvt_f32_f16_e32 v100, v102
	s_nop 0
	s_nop 0
	v_mul_f32_e32 v102, 0x38800000, v101
	v_mul_f32_e32 v100, 0x38800000, v100
	v_pk_mul_f32 v[104:105], v[78:79], v[102:103] op_sel:[1,0] op_sel_hi:[0,0] neg_lo:[1,0]
	v_mov_b32_e32 v107, v66
	v_pk_fma_f32 v[78:79], v[78:79], v[100:101], v[104:105] op_sel_hi:[1,0,1]
	v_cvt_f32_f16_sdwa v101, v103 dst_sel:DWORD dst_unused:UNUSED_PAD src0_sel:WORD_1
	v_cvt_f32_f16_e32 v100, v103
	v_xor_b32_e32 v104, 0x80000000, v77
	v_mov_b32_e32 v105, v76
	v_mul_f32_e32 v102, 0x38800000, v101
	v_mul_f32_e32 v100, 0x38800000, v100
	v_pk_mul_f32 v[102:103], v[104:105], v[102:103] op_sel_hi:[1,0]
	s_nop 0
	v_pk_fma_f32 v[76:77], v[76:77], v[100:101], v[102:103] op_sel_hi:[1,0,1]
	s_waitcnt vmcnt(1)
	v_mov_b64 v[100:101], v[188:189]
	v_mov_b64 v[102:103], v[190:191]
	v_cvt_f32_f16_e32 v104, v100
	v_cvt_f32_f16_sdwa v100, v100 dst_sel:DWORD dst_unused:UNUSED_PAD src0_sel:WORD_1
	v_mul_f32_e32 v104, 0x38800000, v104
	v_mul_f32_e32 v100, 0x38800000, v100
	v_pk_mul_f32 v[106:107], v[106:107], v[100:101] op_sel_hi:[1,0]
	v_cvt_f32_f16_e32 v100, v101
	v_cvt_f32_f16_sdwa v101, v101 dst_sel:DWORD dst_unused:UNUSED_PAD src0_sel:WORD_1
	v_pk_fma_f32 v[66:67], v[66:67], v[104:105], v[106:107] op_sel_hi:[1,0,1]
	v_xor_b32_e32 v106, 0x80000000, v65
	v_mov_b32_e32 v107, v64
	v_mul_f32_e32 v104, 0x38800000, v101
	v_mul_f32_e32 v100, 0x38800000, v100
	v_pk_mul_f32 v[104:105], v[106:107], v[104:105] op_sel_hi:[1,0]
	s_nop 0
	v_pk_fma_f32 v[64:65], v[64:65], v[100:101], v[104:105] op_sel_hi:[1,0,1]
	v_cvt_f32_f16_sdwa v101, v102 dst_sel:DWORD dst_unused:UNUSED_PAD src0_sel:WORD_1
	v_cvt_f32_f16_e32 v100, v102
	s_nop 0
	s_nop 0
	v_mul_f32_e32 v102, 0x38800000, v101
	v_mul_f32_e32 v100, 0x38800000, v100
	v_pk_mul_f32 v[104:105], v[62:63], v[102:103] op_sel:[1,0] op_sel_hi:[0,0] neg_lo:[1,0]
	s_nop 0
	v_pk_fma_f32 v[62:63], v[62:63], v[100:101], v[104:105] op_sel_hi:[1,0,1]
	v_cvt_f32_f16_sdwa v101, v103 dst_sel:DWORD dst_unused:UNUSED_PAD src0_sel:WORD_1
	v_cvt_f32_f16_e32 v100, v103
	v_xor_b32_e32 v104, 0x80000000, v3
	v_mov_b32_e32 v105, v2
	v_mul_f32_e32 v102, 0x38800000, v101
	v_mul_f32_e32 v100, 0x38800000, v100
	v_pk_mul_f32 v[102:103], v[104:105], v[102:103] op_sel_hi:[1,0]
	v_xor_b32_e32 v104, 0x80000000, v11
	v_pk_fma_f32 v[100:101], v[2:3], v[100:101], v[102:103] op_sel_hi:[1,0,1]
	s_waitcnt vmcnt(0)
	v_mov_b64 v[0:1], v[192:193]
	v_mov_b64 v[2:3], v[194:195]
	v_mov_b32_e32 v105, v10
	v_cvt_f32_f16_e32 v102, v0
	v_cvt_f32_f16_sdwa v0, v0 dst_sel:DWORD dst_unused:UNUSED_PAD src0_sel:WORD_1
	v_mul_f32_e32 v102, 0x38800000, v102
	v_mul_f32_e32 v0, 0x38800000, v0
	v_pk_mul_f32 v[104:105], v[104:105], v[0:1] op_sel_hi:[1,0]
	v_cvt_f32_f16_e32 v0, v1
	v_cvt_f32_f16_sdwa v1, v1 dst_sel:DWORD dst_unused:UNUSED_PAD src0_sel:WORD_1
	v_pk_fma_f32 v[10:11], v[10:11], v[102:103], v[104:105] op_sel_hi:[1,0,1]
	v_xor_b32_e32 v104, 0x80000000, v9
	v_mov_b32_e32 v105, v8
	v_mul_f32_e32 v102, 0x38800000, v1
	v_mul_f32_e32 v0, 0x38800000, v0
	v_pk_mul_f32 v[102:103], v[104:105], v[102:103] op_sel_hi:[1,0]
	s_nop 0
	v_pk_fma_f32 v[0:1], v[8:9], v[0:1], v[102:103] op_sel_hi:[1,0,1]
	v_cvt_f32_f16_e32 v8, v2
	v_cvt_f32_f16_sdwa v2, v2 dst_sel:DWORD dst_unused:UNUSED_PAD src0_sel:WORD_1
	s_nop 0
	s_nop 0
	v_mul_f32_e32 v8, 0x38800000, v8
	v_mul_f32_e32 v2, 0x38800000, v2
	s_nop 0
	v_pk_mul_f32 v[102:103], v[6:7], v[2:3] op_sel:[1,0] op_sel_hi:[0,0] neg_lo:[1,0]
	v_cvt_f32_f16_e32 v2, v3
	v_cvt_f32_f16_sdwa v3, v3 dst_sel:DWORD dst_unused:UNUSED_PAD src0_sel:WORD_1
	v_pk_fma_f32 v[6:7], v[6:7], v[8:9], v[102:103] op_sel_hi:[1,0,1]
	v_xor_b32_e32 v102, 0x80000000, v5
	v_mov_b32_e32 v103, v4
	v_mul_f32_e32 v8, 0x38800000, v3
	v_mul_f32_e32 v2, 0x38800000, v2
	v_pk_mul_f32 v[8:9], v[102:103], v[8:9] op_sel_hi:[1,0]
	v_mov_b32_e32 v102, v146
	v_pk_fma_f32 v[2:3], v[4:5], v[2:3], v[8:9] op_sel_hi:[1,0,1]
	v_pk_add_f32 v[4:5], v[12:13], v[14:15]
	v_pk_add_f32 v[8:9], v[12:13], v[14:15] neg_lo:[0,1] neg_hi:[0,1]
	v_pk_add_f32 v[12:13], v[16:17], v[18:19]
	v_pk_add_f32 v[14:15], v[16:17], v[18:19] neg_lo:[0,1] neg_hi:[0,1]
	v_pk_add_f32 v[16:17], v[20:21], v[22:23]
	v_pk_add_f32 v[18:19], v[20:21], v[22:23] neg_lo:[0,1] neg_hi:[0,1]
	v_pk_add_f32 v[20:21], v[24:25], v[26:27]
	v_pk_add_f32 v[22:23], v[24:25], v[26:27] neg_lo:[0,1] neg_hi:[0,1]
	v_pk_add_f32 v[24:25], v[68:69], v[70:71]
	v_pk_add_f32 v[26:27], v[68:69], v[70:71] neg_lo:[0,1] neg_hi:[0,1]
	v_pk_add_f32 v[68:69], v[72:73], v[74:75]
	v_pk_add_f32 v[70:71], v[72:73], v[74:75] neg_lo:[0,1] neg_hi:[0,1]
	v_pk_add_f32 v[72:73], v[84:85], v[86:87]
	v_pk_add_f32 v[74:75], v[84:85], v[86:87] neg_lo:[0,1] neg_hi:[0,1]
	v_pk_add_f32 v[84:85], v[88:89], v[90:91]
	v_pk_add_f32 v[86:87], v[88:89], v[90:91] neg_lo:[0,1] neg_hi:[0,1]
	v_pk_add_f32 v[88:89], v[4:5], v[12:13]
	v_pk_add_f32 v[4:5], v[4:5], v[12:13] neg_lo:[0,1] neg_hi:[0,1]
	v_xor_b32_e32 v12, 0x80000000, v15
	v_mov_b32_e32 v13, v14
	v_pk_add_f32 v[14:15], v[8:9], v[12:13]
	v_pk_add_f32 v[8:9], v[8:9], v[12:13] neg_lo:[0,1] neg_hi:[0,1]
	v_pk_add_f32 v[12:13], v[16:17], v[20:21]
	v_pk_add_f32 v[16:17], v[16:17], v[20:21] neg_lo:[0,1] neg_hi:[0,1]
	v_xor_b32_e32 v20, 0x80000000, v23
	v_mov_b32_e32 v21, v22
	v_pk_add_f32 v[22:23], v[18:19], v[20:21]
	v_pk_add_f32 v[18:19], v[18:19], v[20:21] neg_lo:[0,1] neg_hi:[0,1]
	v_pk_add_f32 v[20:21], v[24:25], v[68:69]
	v_pk_add_f32 v[24:25], v[24:25], v[68:69] neg_lo:[0,1] neg_hi:[0,1]
	v_xor_b32_e32 v68, 0x80000000, v71
	v_mov_b32_e32 v69, v70
	v_pk_add_f32 v[70:71], v[26:27], v[68:69]
	v_pk_add_f32 v[26:27], v[26:27], v[68:69] neg_lo:[0,1] neg_hi:[0,1]
	v_pk_add_f32 v[68:69], v[72:73], v[84:85]
	v_pk_add_f32 v[72:73], v[72:73], v[84:85] neg_lo:[0,1] neg_hi:[0,1]
	v_xor_b32_e32 v84, 0x80000000, v87
	v_mov_b32_e32 v85, v86
	v_pk_add_f32 v[86:87], v[74:75], v[84:85]
	v_pk_add_f32 v[74:75], v[74:75], v[84:85] neg_lo:[0,1] neg_hi:[0,1]
	v_pk_add_f32 v[84:85], v[88:89], v[12:13]
	v_pk_add_f32 v[12:13], v[88:89], v[12:13] neg_lo:[0,1] neg_hi:[0,1]
	v_pk_mul_f32 v[88:89], v[22:23], s[60:61] op_sel:[1,0] op_sel_hi:[0,0] neg_lo:[1,0]
	v_xor_b32_e32 v90, 0x80000000, v19
	v_pk_fma_f32 v[22:23], v[22:23], s[60:61], v[88:89] op_sel_hi:[1,0,1]
	v_mov_b32_e32 v91, v18
	v_pk_add_f32 v[88:89], v[14:15], v[22:23]
	v_pk_add_f32 v[14:15], v[14:15], v[22:23] neg_lo:[0,1] neg_hi:[0,1]
	v_xor_b32_e32 v22, 0x80000000, v17
	v_mov_b32_e32 v23, v16
	v_pk_add_f32 v[16:17], v[4:5], v[22:23]
	v_pk_add_f32 v[4:5], v[4:5], v[22:23] neg_lo:[0,1] neg_hi:[0,1]
	v_pk_mul_f32 v[22:23], v[18:19], s[60:61] op_sel_hi:[1,0]
	s_nop 0
	v_pk_fma_f32 v[18:19], v[90:91], s[60:61], v[22:23] op_sel_hi:[1,0,1] neg_lo:[0,0,1] neg_hi:[0,0,1]
	v_xor_b32_e32 v90, 0x80000000, v75
	v_pk_add_f32 v[22:23], v[8:9], v[18:19]
	v_pk_add_f32 v[8:9], v[8:9], v[18:19] neg_lo:[0,1] neg_hi:[0,1]
	v_pk_add_f32 v[18:19], v[20:21], v[68:69]
	v_pk_add_f32 v[20:21], v[20:21], v[68:69] neg_lo:[0,1] neg_hi:[0,1]
	v_pk_mul_f32 v[68:69], v[86:87], s[60:61] op_sel:[1,0] op_sel_hi:[0,0] neg_lo:[1,0]
	v_mov_b32_e32 v91, v74
	v_pk_fma_f32 v[68:69], v[86:87], s[60:61], v[68:69] op_sel_hi:[1,0,1]
	s_nop 0
	v_pk_add_f32 v[86:87], v[70:71], v[68:69]
	v_pk_add_f32 v[68:69], v[70:71], v[68:69] neg_lo:[0,1] neg_hi:[0,1]
	v_xor_b32_e32 v70, 0x80000000, v73
	v_mov_b32_e32 v71, v72
	v_pk_add_f32 v[72:73], v[24:25], v[70:71]
	v_pk_add_f32 v[24:25], v[24:25], v[70:71] neg_lo:[0,1] neg_hi:[0,1]
	v_pk_mul_f32 v[70:71], v[74:75], s[60:61] op_sel_hi:[1,0]
	s_nop 0
	v_pk_fma_f32 v[70:71], v[90:91], s[60:61], v[70:71] op_sel_hi:[1,0,1] neg_lo:[0,0,1] neg_hi:[0,0,1]
	v_xor_b32_e32 v90, 0x80000000, v69
	v_pk_add_f32 v[74:75], v[26:27], v[70:71]
	v_pk_add_f32 v[26:27], v[26:27], v[70:71] neg_lo:[0,1] neg_hi:[0,1]
	v_pk_add_f32 v[70:71], v[84:85], v[18:19]
	v_pk_add_f32 v[18:19], v[84:85], v[18:19] neg_lo:[0,1] neg_hi:[0,1]
	v_pk_mul_f32 v[84:85], v[86:87], s[54:55] op_sel:[1,0] op_sel_hi:[0,0] neg_lo:[1,0]
	v_mov_b32_e32 v91, v68
	v_pk_fma_f32 v[84:85], v[86:87], s[52:53], v[84:85] op_sel_hi:[1,0,1]
	s_nop 0
	v_pk_add_f32 v[86:87], v[88:89], v[84:85]
	v_pk_add_f32 v[84:85], v[88:89], v[84:85] neg_lo:[0,1] neg_hi:[0,1]
	v_pk_mul_f32 v[88:89], v[72:73], s[60:61] op_sel:[1,0] op_sel_hi:[0,0] neg_lo:[1,0]
	s_nop 0
	v_pk_fma_f32 v[72:73], v[72:73], s[60:61], v[88:89] op_sel_hi:[1,0,1]
	s_nop 0
	v_pk_add_f32 v[88:89], v[16:17], v[72:73]
	v_pk_add_f32 v[16:17], v[16:17], v[72:73] neg_lo:[0,1] neg_hi:[0,1]
	v_pk_mul_f32 v[72:73], v[74:75], s[52:53] op_sel:[1,0] op_sel_hi:[0,0] neg_lo:[1,0]
	s_nop 0
	v_pk_fma_f32 v[72:73], v[74:75], s[54:55], v[72:73] op_sel_hi:[1,0,1]
	s_nop 0
	v_pk_add_f32 v[74:75], v[22:23], v[72:73]
	v_pk_add_f32 v[22:23], v[22:23], v[72:73] neg_lo:[0,1] neg_hi:[0,1]
	v_xor_b32_e32 v72, 0x80000000, v21
	v_mov_b32_e32 v73, v20
	v_pk_add_f32 v[20:21], v[12:13], v[72:73]
	v_pk_add_f32 v[12:13], v[12:13], v[72:73] neg_lo:[0,1] neg_hi:[0,1]
	v_pk_mul_f32 v[72:73], v[68:69], s[54:55] op_sel_hi:[1,0]
	s_nop 0
	v_pk_fma_f32 v[68:69], v[90:91], s[52:53], v[72:73] op_sel_hi:[1,0,1] neg_lo:[0,0,1] neg_hi:[0,0,1]
	v_xor_b32_e32 v90, 0x80000000, v25
	v_pk_add_f32 v[72:73], v[14:15], v[68:69]
	v_pk_add_f32 v[14:15], v[14:15], v[68:69] neg_lo:[0,1] neg_hi:[0,1]
	v_pk_mul_f32 v[68:69], v[24:25], s[60:61] op_sel_hi:[1,0]
	v_mov_b32_e32 v91, v24
	v_pk_fma_f32 v[24:25], v[90:91], s[60:61], v[68:69] op_sel_hi:[1,0,1] neg_lo:[0,0,1] neg_hi:[0,0,1]
	s_nop 0
	v_pk_add_f32 v[68:69], v[4:5], v[24:25]
	v_pk_add_f32 v[4:5], v[4:5], v[24:25] neg_lo:[0,1] neg_hi:[0,1]
	v_pk_mul_f32 v[24:25], v[26:27], s[52:53] op_sel_hi:[1,0]
	s_nop 0
	v_pk_fma_f32 v[24:25], v[26:27], s[54:55], v[24:25] op_sel:[1,0,0] op_sel_hi:[0,0,1] neg_lo:[1,0,1] neg_hi:[0,0,1]
	v_pk_add_f32 v[90:91], v[98:99], v[96:97] neg_lo:[0,1] neg_hi:[0,1]
	v_pk_add_f32 v[26:27], v[8:9], v[24:25]
	v_pk_add_f32 v[8:9], v[8:9], v[24:25] neg_lo:[0,1] neg_hi:[0,1]
	v_pk_add_f32 v[24:25], v[98:99], v[96:97]
	v_pk_add_f32 v[96:97], v[94:95], v[92:93]
	v_pk_add_f32 v[92:93], v[94:95], v[92:93] neg_lo:[0,1] neg_hi:[0,1]
	v_pk_add_f32 v[94:95], v[82:83], v[80:81]
	v_pk_add_f32 v[80:81], v[82:83], v[80:81] neg_lo:[0,1] neg_hi:[0,1]
	v_pk_add_f32 v[82:83], v[78:79], v[76:77]
	v_pk_add_f32 v[76:77], v[78:79], v[76:77] neg_lo:[0,1] neg_hi:[0,1]
	v_pk_add_f32 v[98:99], v[10:11], v[0:1]
	v_pk_add_f32 v[0:1], v[10:11], v[0:1] neg_lo:[0,1] neg_hi:[0,1]
	v_pk_add_f32 v[10:11], v[6:7], v[2:3]
	v_pk_add_f32 v[2:3], v[6:7], v[2:3] neg_lo:[0,1] neg_hi:[0,1]
	v_pk_add_f32 v[6:7], v[24:25], v[96:97]
	v_pk_add_f32 v[24:25], v[24:25], v[96:97] neg_lo:[0,1] neg_hi:[0,1]
	v_xor_b32_e32 v96, 0x80000000, v93
	v_mov_b32_e32 v97, v92
	v_pk_add_f32 v[78:79], v[66:67], v[64:65]
	v_pk_add_f32 v[64:65], v[66:67], v[64:65] neg_lo:[0,1] neg_hi:[0,1]
	v_pk_add_f32 v[66:67], v[62:63], v[100:101]
	v_pk_add_f32 v[62:63], v[62:63], v[100:101] neg_lo:[0,1] neg_hi:[0,1]
	v_pk_add_f32 v[92:93], v[90:91], v[96:97]
	v_pk_add_f32 v[90:91], v[90:91], v[96:97] neg_lo:[0,1] neg_hi:[0,1]
	v_pk_add_f32 v[96:97], v[94:95], v[82:83]
	v_pk_add_f32 v[82:83], v[94:95], v[82:83] neg_lo:[0,1] neg_hi:[0,1]
	v_xor_b32_e32 v94, 0x80000000, v77
	v_mov_b32_e32 v95, v76
	v_pk_add_f32 v[76:77], v[80:81], v[94:95]
	v_pk_add_f32 v[80:81], v[80:81], v[94:95] neg_lo:[0,1] neg_hi:[0,1]
	v_pk_add_f32 v[94:95], v[78:79], v[66:67]
	v_pk_add_f32 v[66:67], v[78:79], v[66:67] neg_lo:[0,1] neg_hi:[0,1]
	v_xor_b32_e32 v78, 0x80000000, v63
	v_mov_b32_e32 v79, v62
	v_pk_add_f32 v[62:63], v[64:65], v[78:79]
	v_pk_add_f32 v[64:65], v[64:65], v[78:79] neg_lo:[0,1] neg_hi:[0,1]
	v_pk_add_f32 v[78:79], v[98:99], v[10:11]
	v_pk_add_f32 v[10:11], v[98:99], v[10:11] neg_lo:[0,1] neg_hi:[0,1]
	v_xor_b32_e32 v98, 0x80000000, v3
	v_mov_b32_e32 v99, v2
	v_pk_add_f32 v[2:3], v[0:1], v[98:99]
	v_pk_add_f32 v[0:1], v[0:1], v[98:99] neg_lo:[0,1] neg_hi:[0,1]
	v_pk_add_f32 v[98:99], v[6:7], v[96:97]
	v_pk_add_f32 v[6:7], v[6:7], v[96:97] neg_lo:[0,1] neg_hi:[0,1]
	v_pk_mul_f32 v[96:97], v[76:77], s[60:61] op_sel:[1,0] op_sel_hi:[0,0] neg_lo:[1,0]
	v_xor_b32_e32 v100, 0x80000000, v81
	v_pk_fma_f32 v[76:77], v[76:77], s[60:61], v[96:97] op_sel_hi:[1,0,1]
	v_mov_b32_e32 v101, v80
	v_pk_add_f32 v[96:97], v[92:93], v[76:77]
	v_pk_add_f32 v[76:77], v[92:93], v[76:77] neg_lo:[0,1] neg_hi:[0,1]
	v_xor_b32_e32 v92, 0x80000000, v83
	v_mov_b32_e32 v93, v82
	v_pk_add_f32 v[82:83], v[24:25], v[92:93]
	v_pk_add_f32 v[24:25], v[24:25], v[92:93] neg_lo:[0,1] neg_hi:[0,1]
	v_pk_mul_f32 v[92:93], v[80:81], s[60:61] op_sel_hi:[1,0]
	s_nop 0
	v_pk_fma_f32 v[80:81], v[100:101], s[60:61], v[92:93] op_sel_hi:[1,0,1] neg_lo:[0,0,1] neg_hi:[0,0,1]
	v_xor_b32_e32 v100, 0x80000000, v1
	v_pk_add_f32 v[92:93], v[90:91], v[80:81]
	v_pk_add_f32 v[80:81], v[90:91], v[80:81] neg_lo:[0,1] neg_hi:[0,1]
	v_pk_add_f32 v[90:91], v[94:95], v[78:79]
	v_pk_add_f32 v[78:79], v[94:95], v[78:79] neg_lo:[0,1] neg_hi:[0,1]
	v_pk_mul_f32 v[94:95], v[2:3], s[60:61] op_sel:[1,0] op_sel_hi:[0,0] neg_lo:[1,0]
	v_mov_b32_e32 v101, v0
	v_pk_fma_f32 v[2:3], v[2:3], s[60:61], v[94:95] op_sel_hi:[1,0,1]
	s_nop 0
	v_pk_add_f32 v[94:95], v[62:63], v[2:3]
	v_pk_add_f32 v[2:3], v[62:63], v[2:3] neg_lo:[0,1] neg_hi:[0,1]
	v_xor_b32_e32 v62, 0x80000000, v11
	v_mov_b32_e32 v63, v10
	v_pk_add_f32 v[10:11], v[66:67], v[62:63]
	v_pk_add_f32 v[62:63], v[66:67], v[62:63] neg_lo:[0,1] neg_hi:[0,1]
	v_pk_mul_f32 v[66:67], v[0:1], s[60:61] op_sel_hi:[1,0]
	s_nop 0
	v_pk_fma_f32 v[0:1], v[100:101], s[60:61], v[66:67] op_sel_hi:[1,0,1] neg_lo:[0,0,1] neg_hi:[0,0,1]
	v_xor_b32_e32 v100, 0x80000000, v3
	v_pk_add_f32 v[66:67], v[64:65], v[0:1]
	v_pk_add_f32 v[0:1], v[64:65], v[0:1] neg_lo:[0,1] neg_hi:[0,1]
	v_pk_add_f32 v[64:65], v[98:99], v[90:91]
	v_pk_add_f32 v[90:91], v[98:99], v[90:91] neg_lo:[0,1] neg_hi:[0,1]
	v_pk_mul_f32 v[98:99], v[94:95], s[54:55] op_sel:[1,0] op_sel_hi:[0,0] neg_lo:[1,0]
	v_mov_b32_e32 v101, v2
	v_pk_fma_f32 v[94:95], v[94:95], s[52:53], v[98:99] op_sel_hi:[1,0,1]
	s_nop 0
	v_pk_add_f32 v[98:99], v[96:97], v[94:95]
	v_pk_add_f32 v[94:95], v[96:97], v[94:95] neg_lo:[0,1] neg_hi:[0,1]
	v_pk_mul_f32 v[96:97], v[10:11], s[60:61] op_sel:[1,0] op_sel_hi:[0,0] neg_lo:[1,0]
	s_nop 0
	v_pk_fma_f32 v[10:11], v[10:11], s[60:61], v[96:97] op_sel_hi:[1,0,1]
	s_nop 0
	v_pk_add_f32 v[96:97], v[82:83], v[10:11]
	v_pk_add_f32 v[10:11], v[82:83], v[10:11] neg_lo:[0,1] neg_hi:[0,1]
	v_pk_mul_f32 v[82:83], v[66:67], s[52:53] op_sel:[1,0] op_sel_hi:[0,0] neg_lo:[1,0]
	s_nop 0
	v_pk_fma_f32 v[66:67], v[66:67], s[54:55], v[82:83] op_sel_hi:[1,0,1]
	s_nop 0
	v_pk_add_f32 v[82:83], v[92:93], v[66:67]
	v_pk_add_f32 v[66:67], v[92:93], v[66:67] neg_lo:[0,1] neg_hi:[0,1]
	v_xor_b32_e32 v92, 0x80000000, v79
	v_mov_b32_e32 v93, v78
	v_pk_add_f32 v[78:79], v[6:7], v[92:93]
	v_pk_add_f32 v[6:7], v[6:7], v[92:93] neg_lo:[0,1] neg_hi:[0,1]
	v_pk_mul_f32 v[92:93], v[2:3], s[54:55] op_sel_hi:[1,0]
	s_nop 0
	v_pk_fma_f32 v[2:3], v[100:101], s[52:53], v[92:93] op_sel_hi:[1,0,1] neg_lo:[0,0,1] neg_hi:[0,0,1]
	v_xor_b32_e32 v100, 0x80000000, v63
	v_pk_add_f32 v[92:93], v[76:77], v[2:3]
	v_pk_add_f32 v[2:3], v[76:77], v[2:3] neg_lo:[0,1] neg_hi:[0,1]
	v_pk_mul_f32 v[76:77], v[62:63], s[60:61] op_sel_hi:[1,0]
	v_mov_b32_e32 v101, v62
	v_pk_fma_f32 v[62:63], v[100:101], s[60:61], v[76:77] op_sel_hi:[1,0,1] neg_lo:[0,0,1] neg_hi:[0,0,1]
	v_xor_b32_e32 v100, 0x80000000, v1
	v_pk_add_f32 v[76:77], v[24:25], v[62:63]
	v_pk_add_f32 v[24:25], v[24:25], v[62:63] neg_lo:[0,1] neg_hi:[0,1]
	v_pk_mul_f32 v[62:63], v[0:1], s[52:53] op_sel_hi:[1,0]
	v_mov_b32_e32 v101, v0
	v_pk_fma_f32 v[0:1], v[100:101], s[54:55], v[62:63] op_sel_hi:[1,0,1] neg_lo:[0,0,1] neg_hi:[0,0,1]
	v_bfe_u32 v100, v102, 1, 4
	v_pk_add_f32 v[62:63], v[80:81], v[0:1]
	v_pk_add_f32 v[0:1], v[80:81], v[0:1] neg_lo:[0,1] neg_hi:[0,1]
	v_lshlrev_b32_e32 v80, 4, v102
	v_lshrrev_b32_e32 v81, 1, v102
	v_bitop3_b32 v101, v81, v80, 16 bitop3:0x6c
	v_lshl_add_u32 v101, v101, 3, 16
	v_lshlrev_b32_e32 v100, 3, v100
	v_add_u32_e32 v102, v101, v100
	ds_write_b64 v102, v[70:71]
	v_bitop3_b32 v70, v81, 1, 15 bitop3:0x6c
	v_lshlrev_b32_e32 v70, 3, v70
	v_add_u32_e32 v71, v101, v70
	ds_write_b64 v71, v[86:87]
	v_bitop3_b32 v71, v81, 2, 15 bitop3:0x6c
	v_lshlrev_b32_e32 v71, 3, v71
	v_add_u32_e32 v86, v101, v71
	ds_write_b64 v86, v[88:89]
	v_bitop3_b32 v86, v81, 3, 15 bitop3:0x6c
	v_lshlrev_b32_e32 v86, 3, v86
	v_add_u32_e32 v87, v101, v86
	ds_write_b64 v87, v[74:75]
	v_bitop3_b32 v74, v81, 4, 15 bitop3:0x6c
	v_lshlrev_b32_e32 v74, 3, v74
	v_add_u32_e32 v75, v101, v74
	ds_write_b64 v75, v[20:21]
	v_bitop3_b32 v20, v81, 5, 15 bitop3:0x6c
	v_lshlrev_b32_e32 v20, 3, v20
	v_add_u32_e32 v21, v101, v20
	ds_write_b64 v21, v[72:73]
	v_bitop3_b32 v21, v81, 6, 15 bitop3:0x6c
	v_lshlrev_b32_e32 v21, 3, v21
	v_add_u32_e32 v72, v101, v21
	ds_write_b64 v72, v[68:69]
	v_bitop3_b32 v68, v81, 7, 15 bitop3:0x6c
	v_lshlrev_b32_e32 v68, 3, v68
	v_add_u32_e32 v69, v101, v68
	ds_write_b64 v69, v[26:27]
	v_bitop3_b32 v26, v81, 8, 15 bitop3:0x6c
	v_lshlrev_b32_e32 v26, 3, v26
	v_add_u32_e32 v27, v101, v26
	ds_write_b64 v27, v[18:19]
	v_bitop3_b32 v18, v81, 9, 15 bitop3:0x6c
	v_lshlrev_b32_e32 v18, 3, v18
	v_add_u32_e32 v19, v101, v18
	ds_write_b64 v19, v[84:85]
	v_bitop3_b32 v19, v81, 10, 15 bitop3:0x6c
	v_lshlrev_b32_e32 v19, 3, v19
	v_add_u32_e32 v27, v101, v19
	ds_write_b64 v27, v[16:17]
	v_bitop3_b32 v16, v81, 11, 15 bitop3:0x6c
	v_lshlrev_b32_e32 v16, 3, v16
	v_add_u32_e32 v17, v101, v16
	ds_write_b64 v17, v[22:23]
	v_bitop3_b32 v17, v81, 12, 15 bitop3:0x6c
	v_lshlrev_b32_e32 v17, 3, v17
	v_add_u32_e32 v22, v101, v17
	ds_write_b64 v22, v[12:13]
	v_bitop3_b32 v12, v81, 13, 15 bitop3:0x6c
	v_lshlrev_b32_e32 v12, 3, v12
	v_add_u32_e32 v13, v101, v12
	ds_write_b64 v13, v[14:15]
	v_bitop3_b32 v13, v81, 14, 15 bitop3:0x6c
	v_lshlrev_b32_e32 v13, 3, v13
	v_add_u32_e32 v14, v101, v13
	ds_write_b64 v14, v[4:5]
	v_bitop3_b32 v4, v81, 15, v81 bitop3:0xc
	v_lshlrev_b32_e32 v4, 3, v4
	v_add_u32_e32 v5, v101, v4
	ds_write_b64 v5, v[8:9]
	v_add_u32_e32 v5, 0x2000, v80
	v_bitop3_b32 v5, v5, v81, 16 bitop3:0x78
	v_lshl_add_u32 v5, v5, 3, 16
	v_add_u32_e32 v8, v5, v100
	ds_write_b64 v8, v[64:65]
	v_add_u32_e32 v8, v5, v70
	ds_write_b64 v8, v[98:99]
	v_add_u32_e32 v8, v5, v71
	ds_write_b64 v8, v[96:97]
	v_add_u32_e32 v8, v5, v86
	ds_write_b64 v8, v[82:83]
	v_add_u32_e32 v8, v5, v74
	ds_write_b64 v8, v[78:79]
	v_add_u32_e32 v8, v5, v20
	ds_write_b64 v8, v[92:93]
	v_add_u32_e32 v8, v5, v21
	ds_write_b64 v8, v[76:77]
	v_add_u32_e32 v8, v5, v68
	ds_write_b64 v8, v[62:63]
	v_add_u32_e32 v8, v5, v26
	ds_write_b64 v8, v[90:91]
	v_add_u32_e32 v8, v5, v18
	ds_write_b64 v8, v[94:95]
	v_add_u32_e32 v8, v5, v19
	ds_write_b64 v8, v[10:11]
	v_add_u32_e32 v8, v5, v16
	ds_write_b64 v8, v[66:67]
	v_add_u32_e32 v8, v5, v17
	ds_write_b64 v8, v[6:7]
	v_add_u32_e32 v6, v5, v12
	ds_write_b64 v6, v[2:3]
	v_add_u32_e32 v2, v5, v13
	ds_write_b64 v2, v[24:25]
	v_add_u32_e32 v2, v5, v4
	v_mov_b32_e32 v22, v146
	ds_write_b64 v2, v[0:1]
	s_waitcnt lgkmcnt(0)
	s_barrier
	s_nop 0
	v_lshlrev_b32_e32 v0, 5, v22
	v_and_b32_e32 v2, 0xfffffe00, v0
	v_and_or_b32 v0, v22, 16, v2
	v_bitop3_b32 v2, v2, 16, v22 bitop3:0x34
	v_bitop3_b32 v6, v22, 4, 15 bitop3:0x6c
	v_bitop3_b32 v14, v22, 8, 15 bitop3:0x6c
	v_lshl_add_u32 v23, v0, 3, 16
	v_lshl_add_u32 v65, v2, 3, 16
	v_lshlrev_b32_e32 v6, 3, v6
	v_lshlrev_b32_e32 v14, 3, v14
	v_bitop3_b32 v2, v22, 1, 15 bitop3:0x6c
	v_add_u32_e32 v105, v23, v6
	v_add_u32_e32 v106, v65, v6
	v_bitop3_b32 v6, v22, 5, 15 bitop3:0x6c
	v_add_u32_e32 v113, v23, v14
	v_add_u32_e32 v114, v65, v14
	v_bitop3_b32 v14, v22, 9, 15 bitop3:0x6c
	v_lshlrev_b32_e32 v2, 3, v2
	v_lshlrev_b32_e32 v6, 3, v6
	v_lshlrev_b32_e32 v14, 3, v14
	v_add_u32_e32 v99, v23, v2
	v_add_u32_e32 v100, v65, v2
	v_bitop3_b32 v2, v22, 2, 15 bitop3:0x6c
	v_add_u32_e32 v107, v23, v6
	v_add_u32_e32 v108, v65, v6
	v_bitop3_b32 v6, v22, 6, 15 bitop3:0x6c
	v_add_u32_e32 v115, v23, v14
	v_add_u32_e32 v116, v65, v14
	v_bitop3_b32 v14, v22, 10, 15 bitop3:0x6c
	v_bitop3_b32 v26, v22, 12, 15 bitop3:0x6c
	v_lshlrev_b32_e32 v2, 3, v2
	v_lshlrev_b32_e32 v6, 3, v6
	v_lshlrev_b32_e32 v14, 3, v14
	v_lshlrev_b32_e32 v26, 3, v26
	v_and_b32_e32 v64, 15, v22
	v_add_u32_e32 v101, v23, v2
	v_add_u32_e32 v102, v65, v2
	v_bitop3_b32 v2, v22, 3, 15 bitop3:0x6c
	v_add_u32_e32 v109, v23, v6
	v_add_u32_e32 v110, v65, v6
	v_bitop3_b32 v6, v22, 7, 15 bitop3:0x6c
	v_add_u32_e32 v117, v23, v14
	v_add_u32_e32 v118, v65, v14
	v_bitop3_b32 v14, v22, 11, 15 bitop3:0x6c
	v_add_u32_e32 v121, v23, v26
	v_add_u32_e32 v122, v65, v26
	v_bitop3_b32 v26, v22, 13, 15 bitop3:0x6c
	v_bitop3_b32 v66, v22, 14, 15 bitop3:0x6c
	v_bitop3_b32 v22, v22, 15, v22 bitop3:0xc
	v_lshlrev_b32_e32 v3, 3, v64
	v_lshlrev_b32_e32 v2, 3, v2
	v_lshlrev_b32_e32 v6, 3, v6
	v_lshlrev_b32_e32 v14, 3, v14
	v_lshlrev_b32_e32 v26, 3, v26
	v_lshlrev_b32_e32 v66, 3, v66
	v_lshlrev_b32_e32 v22, 3, v22
	v_add_u32_e32 v67, v23, v3
	v_add_u32_e32 v98, v65, v3
	v_add_u32_e32 v103, v23, v2
	v_add_u32_e32 v104, v65, v2
	v_add_u32_e32 v111, v23, v6
	v_add_u32_e32 v112, v65, v6
	v_add_u32_e32 v119, v23, v14
	v_add_u32_e32 v120, v65, v14
	v_add_u32_e32 v123, v23, v26
	v_add_u32_e32 v124, v65, v26
	v_add_u32_e32 v125, v23, v66
	v_add_u32_e32 v126, v65, v66
	v_add_u32_e32 v127, v23, v22
	v_add_u32_e32 v128, v65, v22
	ds_read_b64 v[0:1], v67
	ds_read_b64 v[12:13], v98
	ds_read_b64 v[74:75], v99 offset:256
	ds_read_b64 v[4:5], v100 offset:256
	ds_read_b64 v[76:77], v101 offset:512
	ds_read_b64 v[10:11], v102 offset:512
	ds_read_b64 v[70:71], v103 offset:768
	ds_read_b64 v[2:3], v104 offset:768
	ds_read_b64 v[62:63], v105 offset:1024
	ds_read_b64 v[20:21], v106 offset:1024
	ds_read_b64 v[90:91], v107 offset:1280
	ds_read_b64 v[8:9], v108 offset:1280
	ds_read_b64 v[84:85], v109 offset:1536
	ds_read_b64 v[16:17], v110 offset:1536
	ds_read_b64 v[82:83], v111 offset:1792
	ds_read_b64 v[6:7], v112 offset:1792
	ds_read_b64 v[24:25], v113 offset:2048
	ds_read_b64 v[78:79], v114 offset:2048
	ds_read_b64 v[96:97], v115 offset:2304
	ds_read_b64 v[18:19], v116 offset:2304
	ds_read_b64 v[86:87], v117 offset:2560
	ds_read_b64 v[72:73], v118 offset:2560
	ds_read_b64 v[130:131], v119 offset:2816
	ds_read_b64 v[14:15], v120 offset:2816
	ds_read_b64 v[80:81], v121 offset:3072
	ds_read_b64 v[92:93], v122 offset:3072
	ds_read_b64 v[132:133], v123 offset:3328
	ds_read_b64 v[26:27], v124 offset:3328
	ds_read_b64 v[94:95], v125 offset:3584
	ds_read_b64 v[88:89], v126 offset:3584
	ds_read_b64 v[134:135], v127 offset:3840
	ds_read_b64 v[22:23], v128 offset:3840
	s_waitcnt lgkmcnt(14)
	s_nop 0
	v_cvt_f32_i32_e32 v64, v64
	s_nop 0
	v_mul_f32_e32 v64, 0x3b000000, v64
	v_cos_f32_e32 v68, v64
	v_sin_f32_e32 v69, v64
	v_add_f32_e32 v66, v68, v68
	v_pk_mul_f32 v[64:65], v[68:69], v[68:69]
	v_mul_f32_e32 v66, v69, v66
	s_nop 0
	s_nop 0
	v_mov_b32_e32 v140, v69
	v_pk_add_f32 v[64:65], v[64:65], v[64:65] op_sel:[0,1] op_sel_hi:[0,1] neg_lo:[0,1] neg_hi:[0,1]
	v_pk_mul_f32 v[136:137], v[68:69], v[66:67] op_sel:[1,0] op_sel_hi:[0,0] neg_lo:[1,0]
	v_pk_mul_f32 v[138:139], v[24:25], v[140:141] op_sel:[1,0] op_sel_hi:[0,0] neg_lo:[1,0]
	v_pk_fma_f32 v[136:137], v[68:69], v[64:65], v[136:137]
	v_pk_fma_f32 v[24:25], v[24:25], v[68:69], v[138:139] op_sel_hi:[1,0,1]
	v_pk_mul_f32 v[68:69], v[66:67], s[46:47] op_sel_hi:[0,1]
	v_pk_fma_f32 v[138:139], v[64:65], s[40:41], v[68:69]
	s_nop 0
	v_pk_mul_f32 v[68:69], v[62:63], v[138:139] op_sel:[1,1] op_sel_hi:[0,1] neg_lo:[1,0]
	s_nop 0
	v_pk_fma_f32 v[68:69], v[62:63], v[138:139], v[68:69] op_sel_hi:[1,0,1]
	v_pk_mul_f32 v[62:63], v[66:67], v[136:137] op_sel:[0,1] op_sel_hi:[0,0] neg_lo:[0,1]
	v_pk_fma_f32 v[140:141], v[64:65], v[136:137], v[62:63]
	s_waitcnt lgkmcnt(7)
	v_pk_mul_f32 v[62:63], v[80:81], v[136:137] op_sel:[1,1] op_sel_hi:[0,1] neg_lo:[1,0]
	s_nop 0
	v_pk_fma_f32 v[62:63], v[80:81], v[136:137], v[62:63] op_sel_hi:[1,0,1]
	v_pk_mul_f32 v[80:81], v[66:67], v[138:139] op_sel:[0,1] op_sel_hi:[0,0] neg_lo:[0,1]
	v_pk_fma_f32 v[136:137], v[64:65], v[138:139], v[80:81]
	s_nop 0
	v_pk_mul_f32 v[80:81], v[76:77], v[136:137] op_sel:[1,1] op_sel_hi:[0,1] neg_lo:[1,0]
	s_nop 0
	v_pk_fma_f32 v[80:81], v[76:77], v[136:137], v[80:81] op_sel_hi:[1,0,1]
	v_pk_mul_f32 v[76:77], v[66:67], v[140:141] op_sel:[0,1] op_sel_hi:[0,0] neg_lo:[0,1]
	v_pk_fma_f32 v[138:139], v[64:65], v[140:141], v[76:77]
	v_pk_mul_f32 v[76:77], v[86:87], v[140:141] op_sel:[1,1] op_sel_hi:[0,1] neg_lo:[1,0]
	s_nop 0
	v_pk_fma_f32 v[76:77], v[86:87], v[140:141], v[76:77] op_sel_hi:[1,0,1]
	v_pk_mul_f32 v[86:87], v[66:67], v[136:137] op_sel:[0,1] op_sel_hi:[0,0] neg_lo:[0,1]
	v_pk_fma_f32 v[136:137], v[64:65], v[136:137], v[86:87]
	s_nop 0
	v_pk_mul_f32 v[86:87], v[84:85], v[136:137] op_sel:[1,1] op_sel_hi:[0,1] neg_lo:[1,0]
	s_nop 0
	v_pk_fma_f32 v[86:87], v[84:85], v[136:137], v[86:87] op_sel_hi:[1,0,1]
	v_pk_mul_f32 v[84:85], v[66:67], v[138:139] op_sel:[0,1] op_sel_hi:[0,0] neg_lo:[0,1]
	v_pk_fma_f32 v[140:141], v[64:65], v[138:139], v[84:85]
	s_waitcnt lgkmcnt(3)
	v_pk_mul_f32 v[84:85], v[94:95], v[138:139] op_sel:[1,1] op_sel_hi:[0,1] neg_lo:[1,0]
	s_nop 0
	v_pk_fma_f32 v[84:85], v[94:95], v[138:139], v[84:85] op_sel_hi:[1,0,1]
	v_pk_mul_f32 v[94:95], v[66:67], v[136:137] op_sel:[0,1] op_sel_hi:[0,0] neg_lo:[0,1]
	v_pk_fma_f32 v[136:137], v[64:65], v[136:137], v[94:95]
	s_nop 0
	v_pk_mul_f32 v[94:95], v[74:75], v[136:137] op_sel:[1,1] op_sel_hi:[0,1] neg_lo:[1,0]
	s_nop 0
	v_pk_fma_f32 v[94:95], v[74:75], v[136:137], v[94:95] op_sel_hi:[1,0,1]
	v_pk_mul_f32 v[74:75], v[66:67], v[140:141] op_sel:[0,1] op_sel_hi:[0,0] neg_lo:[0,1]
	v_pk_fma_f32 v[138:139], v[64:65], v[140:141], v[74:75]
	v_pk_mul_f32 v[74:75], v[96:97], v[140:141] op_sel:[1,1] op_sel_hi:[0,1] neg_lo:[1,0]
	s_nop 0
	v_pk_fma_f32 v[74:75], v[96:97], v[140:141], v[74:75] op_sel_hi:[1,0,1]
	v_pk_mul_f32 v[96:97], v[66:67], v[136:137] op_sel:[0,1] op_sel_hi:[0,0] neg_lo:[0,1]
	v_pk_fma_f32 v[136:137], v[64:65], v[136:137], v[96:97]
	s_nop 0
	v_pk_mul_f32 v[96:97], v[90:91], v[136:137] op_sel:[1,1] op_sel_hi:[0,1] neg_lo:[1,0]
	s_nop 0
	v_pk_fma_f32 v[96:97], v[90:91], v[136:137], v[96:97] op_sel_hi:[1,0,1]
	v_pk_mul_f32 v[90:91], v[66:67], v[138:139] op_sel:[0,1] op_sel_hi:[0,0] neg_lo:[0,1]
	v_pk_fma_f32 v[140:141], v[64:65], v[138:139], v[90:91]
	v_pk_mul_f32 v[90:91], v[132:133], v[138:139] op_sel:[1,1] op_sel_hi:[0,1] neg_lo:[1,0]
	s_nop 0
	v_pk_fma_f32 v[90:91], v[132:133], v[138:139], v[90:91] op_sel_hi:[1,0,1]
	v_pk_mul_f32 v[132:133], v[66:67], v[136:137] op_sel:[0,1] op_sel_hi:[0,0] neg_lo:[0,1]
	s_nop 0
	v_pk_fma_f32 v[132:133], v[64:65], v[136:137], v[132:133]
	v_pk_mul_f32 v[138:139], v[130:131], v[140:141] op_sel:[1,1] op_sel_hi:[0,1] neg_lo:[1,0]
	v_pk_mul_f32 v[136:137], v[70:71], v[132:133] op_sel:[1,1] op_sel_hi:[0,1] neg_lo:[1,0]
	v_pk_fma_f32 v[130:131], v[130:131], v[140:141], v[138:139] op_sel_hi:[1,0,1]
	v_pk_fma_f32 v[70:71], v[70:71], v[132:133], v[136:137] op_sel_hi:[1,0,1]
	v_pk_mul_f32 v[138:139], v[66:67], v[132:133] op_sel:[0,1] op_sel_hi:[0,0] neg_lo:[0,1]
	v_pk_mul_f32 v[136:137], v[66:67], v[140:141] op_sel:[0,1] op_sel_hi:[0,0] neg_lo:[0,1]
	v_pk_fma_f32 v[132:133], v[64:65], v[132:133], v[138:139]
	v_pk_fma_f32 v[136:137], v[64:65], v[140:141], v[136:137]
	v_pk_mul_f32 v[138:139], v[82:83], v[132:133] op_sel:[1,1] op_sel_hi:[0,1] neg_lo:[1,0]
	s_waitcnt lgkmcnt(1)
	v_pk_fma_f32 v[82:83], v[82:83], v[132:133], v[138:139] op_sel_hi:[1,0,1]
	v_pk_mul_f32 v[138:139], v[66:67], v[136:137] op_sel:[0,1] op_sel_hi:[0,0] neg_lo:[0,1]
	v_pk_mul_f32 v[140:141], v[134:135], v[136:137] op_sel:[1,1] op_sel_hi:[0,1] neg_lo:[1,0]
	v_pk_fma_f32 v[138:139], v[64:65], v[136:137], v[138:139]
	v_pk_fma_f32 v[134:135], v[134:135], v[136:137], v[140:141] op_sel_hi:[1,0,1]
	v_pk_mul_f32 v[136:137], v[66:67], v[132:133] op_sel:[0,1] op_sel_hi:[0,0] neg_lo:[0,1]
	v_pk_fma_f32 v[132:133], v[64:65], v[132:133], v[136:137]
	s_nop 0
	v_pk_mul_f32 v[136:137], v[12:13], v[132:133] op_sel:[1,1] op_sel_hi:[0,1] neg_lo:[1,0]
	s_nop 0
	v_pk_fma_f32 v[12:13], v[12:13], v[132:133], v[136:137] op_sel_hi:[1,0,1]
	v_pk_mul_f32 v[136:137], v[66:67], v[138:139] op_sel:[0,1] op_sel_hi:[0,0] neg_lo:[0,1]
	v_pk_mul_f32 v[140:141], v[78:79], v[138:139] op_sel:[1,1] op_sel_hi:[0,1] neg_lo:[1,0]
	v_pk_fma_f32 v[136:137], v[64:65], v[138:139], v[136:137]
	v_pk_fma_f32 v[78:79], v[78:79], v[138:139], v[140:141] op_sel_hi:[1,0,1]
	v_pk_mul_f32 v[138:139], v[66:67], v[132:133] op_sel:[0,1] op_sel_hi:[0,0] neg_lo:[0,1]
	v_pk_fma_f32 v[132:133], v[64:65], v[132:133], v[138:139]
	s_nop 0
	v_pk_mul_f32 v[138:139], v[20:21], v[132:133] op_sel:[1,1] op_sel_hi:[0,1] neg_lo:[1,0]
	s_nop 0
	v_pk_fma_f32 v[20:21], v[20:21], v[132:133], v[138:139] op_sel_hi:[1,0,1]
	v_pk_mul_f32 v[138:139], v[66:67], v[136:137] op_sel:[0,1] op_sel_hi:[0,0] neg_lo:[0,1]
	v_pk_mul_f32 v[140:141], v[92:93], v[136:137] op_sel:[1,1] op_sel_hi:[0,1] neg_lo:[1,0]
	v_pk_fma_f32 v[138:139], v[64:65], v[136:137], v[138:139]
	v_pk_fma_f32 v[92:93], v[92:93], v[136:137], v[140:141] op_sel_hi:[1,0,1]
	v_pk_mul_f32 v[136:137], v[66:67], v[132:133] op_sel:[0,1] op_sel_hi:[0,0] neg_lo:[0,1]
	v_pk_fma_f32 v[132:133], v[64:65], v[132:133], v[136:137]
	s_nop 0
	v_pk_mul_f32 v[136:137], v[10:11], v[132:133] op_sel:[1,1] op_sel_hi:[0,1] neg_lo:[1,0]
	s_nop 0
	v_pk_fma_f32 v[10:11], v[10:11], v[132:133], v[136:137] op_sel_hi:[1,0,1]
	v_pk_mul_f32 v[136:137], v[66:67], v[138:139] op_sel:[0,1] op_sel_hi:[0,0] neg_lo:[0,1]
	v_pk_mul_f32 v[140:141], v[72:73], v[138:139] op_sel:[1,1] op_sel_hi:[0,1] neg_lo:[1,0]
	v_pk_fma_f32 v[136:137], v[64:65], v[138:139], v[136:137]
	v_pk_fma_f32 v[72:73], v[72:73], v[138:139], v[140:141] op_sel_hi:[1,0,1]
	v_pk_mul_f32 v[138:139], v[66:67], v[132:133] op_sel:[0,1] op_sel_hi:[0,0] neg_lo:[0,1]
	v_pk_fma_f32 v[132:133], v[64:65], v[132:133], v[138:139]
	s_nop 0
	v_pk_mul_f32 v[138:139], v[16:17], v[132:133] op_sel:[1,1] op_sel_hi:[0,1] neg_lo:[1,0]
	s_nop 0
	v_pk_fma_f32 v[16:17], v[16:17], v[132:133], v[138:139] op_sel_hi:[1,0,1]
	v_pk_mul_f32 v[138:139], v[66:67], v[136:137] op_sel:[0,1] op_sel_hi:[0,0] neg_lo:[0,1]
	v_pk_mul_f32 v[140:141], v[88:89], v[136:137] op_sel:[1,1] op_sel_hi:[0,1] neg_lo:[1,0]
	v_pk_fma_f32 v[138:139], v[64:65], v[136:137], v[138:139]
	v_pk_fma_f32 v[88:89], v[88:89], v[136:137], v[140:141] op_sel_hi:[1,0,1]
	v_pk_mul_f32 v[136:137], v[66:67], v[132:133] op_sel:[0,1] op_sel_hi:[0,0] neg_lo:[0,1]
	v_pk_fma_f32 v[132:133], v[64:65], v[132:133], v[136:137]
	s_nop 0
	v_pk_mul_f32 v[136:137], v[4:5], v[132:133] op_sel:[1,1] op_sel_hi:[0,1] neg_lo:[1,0]
	s_nop 0
	v_pk_fma_f32 v[4:5], v[4:5], v[132:133], v[136:137] op_sel_hi:[1,0,1]
	v_pk_mul_f32 v[136:137], v[66:67], v[138:139] op_sel:[0,1] op_sel_hi:[0,0] neg_lo:[0,1]
	v_pk_mul_f32 v[140:141], v[18:19], v[138:139] op_sel:[1,1] op_sel_hi:[0,1] neg_lo:[1,0]
	v_pk_fma_f32 v[136:137], v[64:65], v[138:139], v[136:137]
	v_pk_fma_f32 v[18:19], v[18:19], v[138:139], v[140:141] op_sel_hi:[1,0,1]
	v_pk_mul_f32 v[138:139], v[66:67], v[132:133] op_sel:[0,1] op_sel_hi:[0,0] neg_lo:[0,1]
	v_pk_fma_f32 v[132:133], v[64:65], v[132:133], v[138:139]
	s_nop 0
	v_pk_mul_f32 v[138:139], v[8:9], v[132:133] op_sel:[1,1] op_sel_hi:[0,1] neg_lo:[1,0]
	s_nop 0
	v_pk_fma_f32 v[8:9], v[8:9], v[132:133], v[138:139] op_sel_hi:[1,0,1]
	v_pk_mul_f32 v[138:139], v[66:67], v[136:137] op_sel:[0,1] op_sel_hi:[0,0] neg_lo:[0,1]
	v_pk_mul_f32 v[140:141], v[26:27], v[136:137] op_sel:[1,1] op_sel_hi:[0,1] neg_lo:[1,0]
	v_pk_fma_f32 v[138:139], v[64:65], v[136:137], v[138:139]
	v_pk_fma_f32 v[26:27], v[26:27], v[136:137], v[140:141] op_sel_hi:[1,0,1]
	v_pk_mul_f32 v[136:137], v[66:67], v[132:133] op_sel:[0,1] op_sel_hi:[0,0] neg_lo:[0,1]
	v_pk_fma_f32 v[132:133], v[64:65], v[132:133], v[136:137]
	s_nop 0
	v_pk_mul_f32 v[136:137], v[2:3], v[132:133] op_sel:[1,1] op_sel_hi:[0,1] neg_lo:[1,0]
	s_nop 0
	v_pk_fma_f32 v[2:3], v[2:3], v[132:133], v[136:137] op_sel_hi:[1,0,1]
	v_pk_mul_f32 v[136:137], v[66:67], v[138:139] op_sel:[0,1] op_sel_hi:[0,0] neg_lo:[0,1]
	v_pk_mul_f32 v[140:141], v[14:15], v[138:139] op_sel:[1,1] op_sel_hi:[0,1] neg_lo:[1,0]
	v_pk_fma_f32 v[136:137], v[64:65], v[138:139], v[136:137]
	v_pk_fma_f32 v[14:15], v[14:15], v[138:139], v[140:141] op_sel_hi:[1,0,1]
	v_pk_mul_f32 v[138:139], v[66:67], v[132:133] op_sel:[0,1] op_sel_hi:[0,0] neg_lo:[0,1]
	v_pk_fma_f32 v[64:65], v[64:65], v[132:133], v[138:139]
	s_nop 0
	v_pk_mul_f32 v[132:133], v[6:7], v[64:65] op_sel:[1,1] op_sel_hi:[0,1] neg_lo:[1,0]
	s_nop 0
	v_pk_fma_f32 v[6:7], v[6:7], v[64:65], v[132:133] op_sel_hi:[1,0,1]
	s_waitcnt lgkmcnt(0)
	v_pk_mul_f32 v[64:65], v[22:23], v[136:137] op_sel:[1,1] op_sel_hi:[0,1] neg_lo:[1,0]
	s_nop 0
	v_pk_fma_f32 v[22:23], v[22:23], v[136:137], v[64:65] op_sel_hi:[1,0,1]
	v_pk_add_f32 v[64:65], v[0:1], v[12:13]
	v_pk_add_f32 v[0:1], v[0:1], v[12:13] neg_lo:[0,1] neg_hi:[0,1]
	v_pk_add_f32 v[12:13], v[94:95], v[4:5]
	v_pk_add_f32 v[4:5], v[94:95], v[4:5] neg_lo:[0,1] neg_hi:[0,1]
	v_pk_add_f32 v[94:95], v[80:81], v[10:11]
	v_pk_add_f32 v[10:11], v[80:81], v[10:11] neg_lo:[0,1] neg_hi:[0,1]
	v_pk_add_f32 v[80:81], v[70:71], v[2:3]
	v_pk_add_f32 v[2:3], v[70:71], v[2:3] neg_lo:[0,1] neg_hi:[0,1]
	v_pk_add_f32 v[132:133], v[64:65], v[12:13]
	v_pk_add_f32 v[12:13], v[64:65], v[12:13] neg_lo:[0,1] neg_hi:[0,1]
	v_xor_b32_e32 v64, 0x80000000, v5
	v_mov_b32_e32 v65, v4
	v_pk_add_f32 v[70:71], v[68:69], v[20:21]
	v_pk_add_f32 v[20:21], v[68:69], v[20:21] neg_lo:[0,1] neg_hi:[0,1]
	v_pk_add_f32 v[68:69], v[96:97], v[8:9]
	v_pk_add_f32 v[8:9], v[96:97], v[8:9] neg_lo:[0,1] neg_hi:[0,1]
	v_pk_add_f32 v[4:5], v[0:1], v[64:65]
	v_pk_add_f32 v[0:1], v[0:1], v[64:65] neg_lo:[0,1] neg_hi:[0,1]
	v_pk_add_f32 v[64:65], v[94:95], v[80:81]
	v_pk_add_f32 v[80:81], v[94:95], v[80:81] neg_lo:[0,1] neg_hi:[0,1]
	v_xor_b32_e32 v94, 0x80000000, v3
	v_mov_b32_e32 v95, v2
	v_pk_add_f32 v[96:97], v[86:87], v[16:17]
	v_pk_add_f32 v[16:17], v[86:87], v[16:17] neg_lo:[0,1] neg_hi:[0,1]
	v_pk_add_f32 v[86:87], v[82:83], v[6:7]
	v_pk_add_f32 v[6:7], v[82:83], v[6:7] neg_lo:[0,1] neg_hi:[0,1]
	v_pk_add_f32 v[2:3], v[10:11], v[94:95]
	v_pk_add_f32 v[10:11], v[10:11], v[94:95] neg_lo:[0,1] neg_hi:[0,1]
	v_pk_add_f32 v[94:95], v[70:71], v[68:69]
	v_pk_add_f32 v[68:69], v[70:71], v[68:69] neg_lo:[0,1] neg_hi:[0,1]
	v_xor_b32_e32 v70, 0x80000000, v9
	v_mov_b32_e32 v71, v8
	v_pk_add_f32 v[82:83], v[24:25], v[78:79]
	v_pk_add_f32 v[24:25], v[24:25], v[78:79] neg_lo:[0,1] neg_hi:[0,1]
	v_pk_add_f32 v[78:79], v[74:75], v[18:19]
	v_pk_add_f32 v[18:19], v[74:75], v[18:19] neg_lo:[0,1] neg_hi:[0,1]
	v_pk_add_f32 v[8:9], v[20:21], v[70:71]
	v_pk_add_f32 v[20:21], v[20:21], v[70:71] neg_lo:[0,1] neg_hi:[0,1]
	v_pk_add_f32 v[70:71], v[96:97], v[86:87]
	v_pk_add_f32 v[86:87], v[96:97], v[86:87] neg_lo:[0,1] neg_hi:[0,1]
	v_xor_b32_e32 v96, 0x80000000, v7
	v_mov_b32_e32 v97, v6
	v_pk_add_f32 v[74:75], v[76:77], v[72:73]
	v_pk_add_f32 v[72:73], v[76:77], v[72:73] neg_lo:[0,1] neg_hi:[0,1]
	v_pk_add_f32 v[76:77], v[130:131], v[14:15]
	v_pk_add_f32 v[14:15], v[130:131], v[14:15] neg_lo:[0,1] neg_hi:[0,1]
	v_pk_add_f32 v[6:7], v[16:17], v[96:97]
	v_pk_add_f32 v[16:17], v[16:17], v[96:97] neg_lo:[0,1] neg_hi:[0,1]
	v_pk_add_f32 v[96:97], v[82:83], v[78:79]
	v_pk_add_f32 v[78:79], v[82:83], v[78:79] neg_lo:[0,1] neg_hi:[0,1]
	v_xor_b32_e32 v82, 0x80000000, v19
	v_mov_b32_e32 v83, v18
	v_pk_add_f32 v[130:131], v[62:63], v[92:93]
	v_pk_add_f32 v[62:63], v[62:63], v[92:93] neg_lo:[0,1] neg_hi:[0,1]
	v_pk_add_f32 v[92:93], v[90:91], v[26:27]
	v_pk_add_f32 v[26:27], v[90:91], v[26:27] neg_lo:[0,1] neg_hi:[0,1]
	v_pk_add_f32 v[18:19], v[24:25], v[82:83]
	v_pk_add_f32 v[24:25], v[24:25], v[82:83] neg_lo:[0,1] neg_hi:[0,1]
	v_pk_add_f32 v[82:83], v[74:75], v[76:77]
	v_pk_add_f32 v[74:75], v[74:75], v[76:77] neg_lo:[0,1] neg_hi:[0,1]
	v_xor_b32_e32 v76, 0x80000000, v15
	v_mov_b32_e32 v77, v14
	v_pk_add_f32 v[90:91], v[84:85], v[88:89]
	v_pk_add_f32 v[84:85], v[84:85], v[88:89] neg_lo:[0,1] neg_hi:[0,1]
	v_pk_add_f32 v[88:89], v[134:135], v[22:23]
	v_pk_add_f32 v[22:23], v[134:135], v[22:23] neg_lo:[0,1] neg_hi:[0,1]
	v_pk_add_f32 v[14:15], v[72:73], v[76:77]
	v_pk_add_f32 v[72:73], v[72:73], v[76:77] neg_lo:[0,1] neg_hi:[0,1]
	v_pk_add_f32 v[76:77], v[130:131], v[92:93]
	v_pk_add_f32 v[92:93], v[130:131], v[92:93] neg_lo:[0,1] neg_hi:[0,1]
	v_xor_b32_e32 v130, 0x80000000, v27
	v_mov_b32_e32 v131, v26
	v_pk_add_f32 v[26:27], v[62:63], v[130:131]
	v_pk_add_f32 v[62:63], v[62:63], v[130:131] neg_lo:[0,1] neg_hi:[0,1]
	v_pk_add_f32 v[130:131], v[90:91], v[88:89]
	v_pk_add_f32 v[88:89], v[90:91], v[88:89] neg_lo:[0,1] neg_hi:[0,1]
	v_xor_b32_e32 v90, 0x80000000, v23
	v_mov_b32_e32 v91, v22
	v_pk_add_f32 v[22:23], v[84:85], v[90:91]
	v_pk_add_f32 v[84:85], v[84:85], v[90:91] neg_lo:[0,1] neg_hi:[0,1]
	v_pk_add_f32 v[90:91], v[132:133], v[64:65]
	v_pk_add_f32 v[64:65], v[132:133], v[64:65] neg_lo:[0,1] neg_hi:[0,1]
	v_pk_mul_f32 v[132:133], v[2:3], s[60:61] op_sel:[1,0] op_sel_hi:[0,0] neg_lo:[1,0]
	v_xor_b32_e32 v134, 0x80000000, v11
	v_pk_fma_f32 v[2:3], v[2:3], s[60:61], v[132:133] op_sel_hi:[1,0,1]
	v_mov_b32_e32 v135, v10
	v_pk_add_f32 v[132:133], v[4:5], v[2:3]
	v_pk_add_f32 v[2:3], v[4:5], v[2:3] neg_lo:[0,1] neg_hi:[0,1]
	v_xor_b32_e32 v4, 0x80000000, v81
	v_mov_b32_e32 v5, v80
	v_pk_add_f32 v[80:81], v[12:13], v[4:5]
	v_pk_add_f32 v[4:5], v[12:13], v[4:5] neg_lo:[0,1] neg_hi:[0,1]
	v_pk_mul_f32 v[12:13], v[10:11], s[60:61] op_sel_hi:[1,0]
	s_nop 0
	v_pk_fma_f32 v[10:11], v[134:135], s[60:61], v[12:13] op_sel_hi:[1,0,1] neg_lo:[0,0,1] neg_hi:[0,0,1]
	v_xor_b32_e32 v134, 0x80000000, v17
	v_pk_add_f32 v[12:13], v[0:1], v[10:11]
	v_pk_add_f32 v[0:1], v[0:1], v[10:11] neg_lo:[0,1] neg_hi:[0,1]
	v_pk_add_f32 v[10:11], v[94:95], v[70:71]
	v_pk_add_f32 v[70:71], v[94:95], v[70:71] neg_lo:[0,1] neg_hi:[0,1]
	v_pk_mul_f32 v[94:95], v[6:7], s[60:61] op_sel:[1,0] op_sel_hi:[0,0] neg_lo:[1,0]
	v_mov_b32_e32 v135, v16
	v_pk_fma_f32 v[6:7], v[6:7], s[60:61], v[94:95] op_sel_hi:[1,0,1]
	s_nop 0
	v_pk_add_f32 v[94:95], v[8:9], v[6:7]
	v_pk_add_f32 v[6:7], v[8:9], v[6:7] neg_lo:[0,1] neg_hi:[0,1]
	v_xor_b32_e32 v8, 0x80000000, v87
	v_mov_b32_e32 v9, v86
	v_pk_add_f32 v[86:87], v[68:69], v[8:9]
	v_pk_add_f32 v[8:9], v[68:69], v[8:9] neg_lo:[0,1] neg_hi:[0,1]
	v_pk_mul_f32 v[68:69], v[16:17], s[60:61] op_sel_hi:[1,0]
	s_nop 0
	v_pk_fma_f32 v[16:17], v[134:135], s[60:61], v[68:69] op_sel_hi:[1,0,1] neg_lo:[0,0,1] neg_hi:[0,0,1]
	v_xor_b32_e32 v134, 0x80000000, v73
	v_pk_add_f32 v[68:69], v[20:21], v[16:17]
	v_pk_add_f32 v[16:17], v[20:21], v[16:17] neg_lo:[0,1] neg_hi:[0,1]
	v_pk_add_f32 v[20:21], v[96:97], v[82:83]
	v_pk_add_f32 v[82:83], v[96:97], v[82:83] neg_lo:[0,1] neg_hi:[0,1]
	v_pk_mul_f32 v[96:97], v[14:15], s[60:61] op_sel:[1,0] op_sel_hi:[0,0] neg_lo:[1,0]
	v_mov_b32_e32 v135, v72
	v_pk_fma_f32 v[14:15], v[14:15], s[60:61], v[96:97] op_sel_hi:[1,0,1]
	s_nop 0
	v_pk_add_f32 v[96:97], v[18:19], v[14:15]
	v_pk_add_f32 v[14:15], v[18:19], v[14:15] neg_lo:[0,1] neg_hi:[0,1]
	v_xor_b32_e32 v18, 0x80000000, v75
	v_mov_b32_e32 v19, v74
	v_pk_add_f32 v[74:75], v[78:79], v[18:19]
	v_pk_add_f32 v[18:19], v[78:79], v[18:19] neg_lo:[0,1] neg_hi:[0,1]
	v_pk_mul_f32 v[78:79], v[72:73], s[60:61] op_sel_hi:[1,0]
	s_nop 0
	v_pk_fma_f32 v[72:73], v[134:135], s[60:61], v[78:79] op_sel_hi:[1,0,1] neg_lo:[0,0,1] neg_hi:[0,0,1]
	v_xor_b32_e32 v134, 0x80000000, v85
	v_pk_add_f32 v[78:79], v[24:25], v[72:73]
	v_pk_add_f32 v[24:25], v[24:25], v[72:73] neg_lo:[0,1] neg_hi:[0,1]
	v_pk_add_f32 v[72:73], v[76:77], v[130:131]
	v_pk_add_f32 v[76:77], v[76:77], v[130:131] neg_lo:[0,1] neg_hi:[0,1]
	v_pk_mul_f32 v[130:131], v[22:23], s[60:61] op_sel:[1,0] op_sel_hi:[0,0] neg_lo:[1,0]
	v_mov_b32_e32 v135, v84
	v_pk_fma_f32 v[22:23], v[22:23], s[60:61], v[130:131] op_sel_hi:[1,0,1]
	s_nop 0
	v_pk_add_f32 v[130:131], v[26:27], v[22:23]
	v_pk_add_f32 v[22:23], v[26:27], v[22:23] neg_lo:[0,1] neg_hi:[0,1]
	v_xor_b32_e32 v26, 0x80000000, v89
	v_mov_b32_e32 v27, v88
	v_pk_add_f32 v[88:89], v[92:93], v[26:27]
	v_pk_add_f32 v[26:27], v[92:93], v[26:27] neg_lo:[0,1] neg_hi:[0,1]
	v_pk_mul_f32 v[92:93], v[84:85], s[60:61] op_sel_hi:[1,0]
	s_nop 0
	v_pk_fma_f32 v[84:85], v[134:135], s[60:61], v[92:93] op_sel_hi:[1,0,1] neg_lo:[0,0,1] neg_hi:[0,0,1]
	v_xor_b32_e32 v134, 0x80000000, v7
	v_pk_add_f32 v[92:93], v[62:63], v[84:85]
	v_pk_add_f32 v[62:63], v[62:63], v[84:85] neg_lo:[0,1] neg_hi:[0,1]
	v_pk_add_f32 v[84:85], v[90:91], v[10:11]
	v_pk_add_f32 v[10:11], v[90:91], v[10:11] neg_lo:[0,1] neg_hi:[0,1]
	v_pk_mul_f32 v[90:91], v[94:95], s[54:55] op_sel:[1,0] op_sel_hi:[0,0] neg_lo:[1,0]
	v_mov_b32_e32 v135, v6
	v_pk_fma_f32 v[90:91], v[94:95], s[52:53], v[90:91] op_sel_hi:[1,0,1]
	s_nop 0
	v_pk_add_f32 v[94:95], v[132:133], v[90:91]
	v_pk_add_f32 v[90:91], v[132:133], v[90:91] neg_lo:[0,1] neg_hi:[0,1]
	v_pk_mul_f32 v[132:133], v[86:87], s[60:61] op_sel:[1,0] op_sel_hi:[0,0] neg_lo:[1,0]
	s_nop 0
	v_pk_fma_f32 v[86:87], v[86:87], s[60:61], v[132:133] op_sel_hi:[1,0,1]
	s_nop 0
	v_pk_add_f32 v[132:133], v[80:81], v[86:87]
	v_pk_add_f32 v[80:81], v[80:81], v[86:87] neg_lo:[0,1] neg_hi:[0,1]
	v_pk_mul_f32 v[86:87], v[68:69], s[52:53] op_sel:[1,0] op_sel_hi:[0,0] neg_lo:[1,0]
	s_nop 0
	v_pk_fma_f32 v[68:69], v[68:69], s[54:55], v[86:87] op_sel_hi:[1,0,1]
	s_nop 0
	v_pk_add_f32 v[86:87], v[12:13], v[68:69]
	v_pk_add_f32 v[12:13], v[12:13], v[68:69] neg_lo:[0,1] neg_hi:[0,1]
	v_xor_b32_e32 v68, 0x80000000, v71
	v_mov_b32_e32 v69, v70
	v_pk_add_f32 v[70:71], v[64:65], v[68:69]
	v_pk_add_f32 v[64:65], v[64:65], v[68:69] neg_lo:[0,1] neg_hi:[0,1]
	v_pk_mul_f32 v[68:69], v[6:7], s[54:55] op_sel_hi:[1,0]
	s_nop 0
	v_pk_fma_f32 v[6:7], v[134:135], s[52:53], v[68:69] op_sel_hi:[1,0,1] neg_lo:[0,0,1] neg_hi:[0,0,1]
	v_xor_b32_e32 v134, 0x80000000, v9
	v_pk_add_f32 v[68:69], v[2:3], v[6:7]
	v_pk_add_f32 v[2:3], v[2:3], v[6:7] neg_lo:[0,1] neg_hi:[0,1]
	v_pk_mul_f32 v[6:7], v[8:9], s[60:61] op_sel_hi:[1,0]
	v_mov_b32_e32 v135, v8
	v_pk_fma_f32 v[6:7], v[134:135], s[60:61], v[6:7] op_sel_hi:[1,0,1] neg_lo:[0,0,1] neg_hi:[0,0,1]
	v_xor_b32_e32 v134, 0x80000000, v17
	v_pk_add_f32 v[8:9], v[4:5], v[6:7]
	v_pk_add_f32 v[4:5], v[4:5], v[6:7] neg_lo:[0,1] neg_hi:[0,1]
	v_pk_mul_f32 v[6:7], v[16:17], s[52:53] op_sel_hi:[1,0]
	v_mov_b32_e32 v135, v16
	v_pk_fma_f32 v[6:7], v[134:135], s[54:55], v[6:7] op_sel_hi:[1,0,1] neg_lo:[0,0,1] neg_hi:[0,0,1]
	v_xor_b32_e32 v134, 0x80000000, v23
	v_pk_add_f32 v[16:17], v[0:1], v[6:7]
	v_pk_add_f32 v[0:1], v[0:1], v[6:7] neg_lo:[0,1] neg_hi:[0,1]
	v_pk_add_f32 v[6:7], v[20:21], v[72:73]
	v_pk_add_f32 v[20:21], v[20:21], v[72:73] neg_lo:[0,1] neg_hi:[0,1]
	v_pk_mul_f32 v[72:73], v[130:131], s[54:55] op_sel:[1,0] op_sel_hi:[0,0] neg_lo:[1,0]
	v_mov_b32_e32 v135, v22
	v_pk_fma_f32 v[72:73], v[130:131], s[52:53], v[72:73] op_sel_hi:[1,0,1]
	s_nop 0
	v_pk_add_f32 v[130:131], v[96:97], v[72:73]
	v_pk_add_f32 v[72:73], v[96:97], v[72:73] neg_lo:[0,1] neg_hi:[0,1]
	v_pk_mul_f32 v[96:97], v[88:89], s[60:61] op_sel:[1,0] op_sel_hi:[0,0] neg_lo:[1,0]
	s_nop 0
	v_pk_fma_f32 v[88:89], v[88:89], s[60:61], v[96:97] op_sel_hi:[1,0,1]
	s_nop 0
	v_pk_add_f32 v[96:97], v[74:75], v[88:89]
	v_pk_add_f32 v[74:75], v[74:75], v[88:89] neg_lo:[0,1] neg_hi:[0,1]
	v_pk_mul_f32 v[88:89], v[92:93], s[52:53] op_sel:[1,0] op_sel_hi:[0,0] neg_lo:[1,0]
	s_nop 0
	v_pk_fma_f32 v[88:89], v[92:93], s[54:55], v[88:89] op_sel_hi:[1,0,1]
	s_nop 0
	v_pk_add_f32 v[92:93], v[78:79], v[88:89]
	v_pk_add_f32 v[78:79], v[78:79], v[88:89] neg_lo:[0,1] neg_hi:[0,1]
	v_xor_b32_e32 v88, 0x80000000, v77
	v_mov_b32_e32 v89, v76
	v_pk_add_f32 v[76:77], v[82:83], v[88:89]
	v_pk_add_f32 v[82:83], v[82:83], v[88:89] neg_lo:[0,1] neg_hi:[0,1]
	v_pk_mul_f32 v[88:89], v[22:23], s[54:55] op_sel_hi:[1,0]
	s_nop 0
	v_pk_fma_f32 v[22:23], v[134:135], s[52:53], v[88:89] op_sel_hi:[1,0,1] neg_lo:[0,0,1] neg_hi:[0,0,1]
	v_xor_b32_e32 v134, 0x80000000, v27
	v_pk_add_f32 v[88:89], v[14:15], v[22:23]
	v_pk_add_f32 v[14:15], v[14:15], v[22:23] neg_lo:[0,1] neg_hi:[0,1]
	v_pk_mul_f32 v[22:23], v[26:27], s[60:61] op_sel_hi:[1,0]
	v_mov_b32_e32 v135, v26
	v_pk_fma_f32 v[22:23], v[134:135], s[60:61], v[22:23] op_sel_hi:[1,0,1] neg_lo:[0,0,1] neg_hi:[0,0,1]
	v_xor_b32_e32 v134, 0x80000000, v63
	v_pk_add_f32 v[26:27], v[18:19], v[22:23]
	v_pk_add_f32 v[18:19], v[18:19], v[22:23] neg_lo:[0,1] neg_hi:[0,1]
	v_pk_mul_f32 v[22:23], v[62:63], s[52:53] op_sel_hi:[1,0]
	v_mov_b32_e32 v135, v62
	v_pk_fma_f32 v[22:23], v[134:135], s[54:55], v[22:23] op_sel_hi:[1,0,1] neg_lo:[0,0,1] neg_hi:[0,0,1]
	v_xor_b32_e32 v134, 0x80000000, v73
	v_pk_add_f32 v[62:63], v[24:25], v[22:23]
	v_pk_add_f32 v[22:23], v[24:25], v[22:23] neg_lo:[0,1] neg_hi:[0,1]
	v_pk_add_f32 v[24:25], v[84:85], v[6:7]
	v_pk_add_f32 v[6:7], v[84:85], v[6:7] neg_lo:[0,1] neg_hi:[0,1]
	v_pk_mul_f32 v[84:85], v[130:131], s[48:49] op_sel:[1,0] op_sel_hi:[0,0] neg_lo:[1,0]
	v_mov_b32_e32 v135, v72
	v_pk_fma_f32 v[84:85], v[130:131], s[44:45], v[84:85] op_sel_hi:[1,0,1]
	s_nop 0
	v_pk_add_f32 v[130:131], v[94:95], v[84:85]
	v_pk_add_f32 v[84:85], v[94:95], v[84:85] neg_lo:[0,1] neg_hi:[0,1]
	v_pk_mul_f32 v[94:95], v[96:97], s[54:55] op_sel:[1,0] op_sel_hi:[0,0] neg_lo:[1,0]
	s_nop 0
	v_pk_fma_f32 v[94:95], v[96:97], s[52:53], v[94:95] op_sel_hi:[1,0,1]
	s_nop 0
	v_pk_add_f32 v[96:97], v[132:133], v[94:95]
	v_pk_add_f32 v[94:95], v[132:133], v[94:95] neg_lo:[0,1] neg_hi:[0,1]
	v_pk_mul_f32 v[132:133], v[92:93], s[58:59] op_sel:[1,0] op_sel_hi:[0,0] neg_lo:[1,0]
	s_nop 0
	v_pk_fma_f32 v[92:93], v[92:93], s[56:57], v[132:133] op_sel_hi:[1,0,1]
	s_nop 0
	v_pk_add_f32 v[132:133], v[86:87], v[92:93]
	v_pk_add_f32 v[86:87], v[86:87], v[92:93] neg_lo:[0,1] neg_hi:[0,1]
	v_pk_mul_f32 v[92:93], v[76:77], s[60:61] op_sel:[1,0] op_sel_hi:[0,0] neg_lo:[1,0]
	s_nop 0
	v_pk_fma_f32 v[76:77], v[76:77], s[60:61], v[92:93] op_sel_hi:[1,0,1]
	s_nop 0
	v_pk_add_f32 v[92:93], v[70:71], v[76:77]
	v_pk_add_f32 v[70:71], v[70:71], v[76:77] neg_lo:[0,1] neg_hi:[0,1]
	v_pk_mul_f32 v[76:77], v[88:89], s[56:57] op_sel:[1,0] op_sel_hi:[0,0] neg_lo:[1,0]
	s_nop 0
	v_pk_fma_f32 v[76:77], v[88:89], s[58:59], v[76:77] op_sel_hi:[1,0,1]
	s_nop 0
	v_pk_add_f32 v[88:89], v[68:69], v[76:77]
	v_pk_add_f32 v[68:69], v[68:69], v[76:77] neg_lo:[0,1] neg_hi:[0,1]
	v_pk_mul_f32 v[76:77], v[26:27], s[52:53] op_sel:[1,0] op_sel_hi:[0,0] neg_lo:[1,0]
	s_nop 0
	v_pk_fma_f32 v[26:27], v[26:27], s[54:55], v[76:77] op_sel_hi:[1,0,1]
	s_nop 0
	v_pk_add_f32 v[76:77], v[8:9], v[26:27]
	v_pk_add_f32 v[8:9], v[8:9], v[26:27] neg_lo:[0,1] neg_hi:[0,1]
	v_pk_mul_f32 v[26:27], v[62:63], s[44:45] op_sel:[1,0] op_sel_hi:[0,0] neg_lo:[1,0]
	s_nop 0
	v_pk_fma_f32 v[26:27], v[62:63], s[48:49], v[26:27] op_sel_hi:[1,0,1]
	s_nop 0
	v_pk_add_f32 v[62:63], v[16:17], v[26:27]
	v_pk_add_f32 v[16:17], v[16:17], v[26:27] neg_lo:[0,1] neg_hi:[0,1]
	v_xor_b32_e32 v26, 0x80000000, v21
	v_mov_b32_e32 v27, v20
	v_pk_add_f32 v[20:21], v[10:11], v[26:27]
	v_pk_add_f32 v[10:11], v[10:11], v[26:27] neg_lo:[0,1] neg_hi:[0,1]
	v_pk_mul_f32 v[26:27], v[72:73], s[48:49] op_sel_hi:[1,0]
	s_nop 0
	v_pk_fma_f32 v[26:27], v[134:135], s[44:45], v[26:27] op_sel_hi:[1,0,1] neg_lo:[0,0,1] neg_hi:[0,0,1]
	v_xor_b32_e32 v134, 0x80000000, v75
	v_pk_add_f32 v[72:73], v[90:91], v[26:27]
	v_pk_add_f32 v[26:27], v[90:91], v[26:27] neg_lo:[0,1] neg_hi:[0,1]
	v_pk_mul_f32 v[90:91], v[74:75], s[54:55] op_sel_hi:[1,0]
	v_mov_b32_e32 v135, v74
	v_pk_fma_f32 v[74:75], v[134:135], s[52:53], v[90:91] op_sel_hi:[1,0,1] neg_lo:[0,0,1] neg_hi:[0,0,1]
	v_xor_b32_e32 v134, 0x80000000, v79
	v_pk_add_f32 v[90:91], v[80:81], v[74:75]
	v_pk_add_f32 v[74:75], v[80:81], v[74:75] neg_lo:[0,1] neg_hi:[0,1]
	v_pk_mul_f32 v[80:81], v[78:79], s[58:59] op_sel_hi:[1,0]
	v_mov_b32_e32 v135, v78
	v_pk_fma_f32 v[78:79], v[134:135], s[56:57], v[80:81] op_sel_hi:[1,0,1] neg_lo:[0,0,1] neg_hi:[0,0,1]
	v_xor_b32_e32 v134, 0x80000000, v83
	v_pk_add_f32 v[80:81], v[12:13], v[78:79]
	v_pk_add_f32 v[12:13], v[12:13], v[78:79] neg_lo:[0,1] neg_hi:[0,1]
	v_pk_mul_f32 v[78:79], v[82:83], s[60:61] op_sel_hi:[1,0]
	v_mov_b32_e32 v135, v82
	v_pk_fma_f32 v[78:79], v[134:135], s[60:61], v[78:79] op_sel_hi:[1,0,1] neg_lo:[0,0,1] neg_hi:[0,0,1]
	v_xor_b32_e32 v134, 0x80000000, v15
	v_pk_add_f32 v[82:83], v[64:65], v[78:79]
	v_pk_add_f32 v[64:65], v[64:65], v[78:79] neg_lo:[0,1] neg_hi:[0,1]
	v_pk_mul_f32 v[78:79], v[14:15], s[56:57] op_sel_hi:[1,0]
	v_mov_b32_e32 v135, v14
	v_pk_fma_f32 v[14:15], v[134:135], s[58:59], v[78:79] op_sel_hi:[1,0,1] neg_lo:[0,0,1] neg_hi:[0,0,1]
	v_xor_b32_e32 v134, 0x80000000, v19
	v_pk_add_f32 v[78:79], v[2:3], v[14:15]
	v_pk_add_f32 v[2:3], v[2:3], v[14:15] neg_lo:[0,1] neg_hi:[0,1]
	v_pk_mul_f32 v[14:15], v[18:19], s[52:53] op_sel_hi:[1,0]
	v_mov_b32_e32 v135, v18
	v_pk_fma_f32 v[14:15], v[134:135], s[54:55], v[14:15] op_sel_hi:[1,0,1] neg_lo:[0,0,1] neg_hi:[0,0,1]
	v_xor_b32_e32 v134, 0x80000000, v23
	v_pk_add_f32 v[18:19], v[4:5], v[14:15]
	v_pk_add_f32 v[4:5], v[4:5], v[14:15] neg_lo:[0,1] neg_hi:[0,1]
	v_pk_mul_f32 v[14:15], v[22:23], s[44:45] op_sel_hi:[1,0]
	v_mov_b32_e32 v135, v22
	v_pk_fma_f32 v[14:15], v[134:135], s[48:49], v[14:15] op_sel_hi:[1,0,1] neg_lo:[0,0,1] neg_hi:[0,0,1]
	s_nop 0
	v_pk_add_f32 v[22:23], v[0:1], v[14:15]
	v_pk_add_f32 v[0:1], v[0:1], v[14:15] neg_lo:[0,1] neg_hi:[0,1]
	ds_write_b64 v67, v[24:25]
	ds_write_b64 v98, v[130:131]
	ds_write_b64 v99, v[96:97] offset:256
	ds_write_b64 v100, v[132:133] offset:256
	ds_write_b64 v101, v[92:93] offset:512
	ds_write_b64 v102, v[88:89] offset:512
	ds_write_b64 v103, v[76:77] offset:768
	ds_write_b64 v104, v[62:63] offset:768
	ds_write_b64 v105, v[20:21] offset:1024
	ds_write_b64 v106, v[72:73] offset:1024
	ds_write_b64 v107, v[90:91] offset:1280
	ds_write_b64 v108, v[80:81] offset:1280
	ds_write_b64 v109, v[82:83] offset:1536
	ds_write_b64 v110, v[78:79] offset:1536
	ds_write_b64 v111, v[18:19] offset:1792
	ds_write_b64 v112, v[22:23] offset:1792
	ds_write_b64 v113, v[6:7] offset:2048
	ds_write_b64 v114, v[84:85] offset:2048
	ds_write_b64 v115, v[94:95] offset:2304
	ds_write_b64 v116, v[86:87] offset:2304
	ds_write_b64 v117, v[70:71] offset:2560
	ds_write_b64 v118, v[68:69] offset:2560
	ds_write_b64 v119, v[8:9] offset:2816
	ds_write_b64 v120, v[16:17] offset:2816
	ds_write_b64 v121, v[10:11] offset:3072
	ds_write_b64 v122, v[26:27] offset:3072
	ds_write_b64 v123, v[74:75] offset:3328
	ds_write_b64 v124, v[12:13] offset:3328
	ds_write_b64 v125, v[64:65] offset:3584
	ds_write_b64 v126, v[2:3] offset:3584
	ds_write_b64 v127, v[4:5] offset:3840
	ds_write_b64 v128, v[0:1] offset:3840
	v_mov_b32_e32 v74, v146
	s_waitcnt lgkmcnt(0)
	s_barrier
	s_nop 0
	v_lshrrev_b32_e32 v0, 5, v74
	v_bfe_u32 v4, v74, 5, 4
	v_bitop3_b32 v0, v0, v74, 15 bitop3:0x6c
	v_bitop3_b32 v4, v4, v74, 16 bitop3:0x36
	v_lshlrev_b32_e32 v66, 3, v0
	v_lshlrev_b32_e32 v67, 3, v4
	v_add_u32_e32 v5, 16, v66
	v_add_u32_e32 v4, 16, v67
	v_add_u32_e32 v62, s79, v66
	v_add_u32_e32 v70, s9, v66
	ds_read2st64_b64 v[0:3], v5 offset1:16
	ds_read2st64_b64 v[16:19], v4 offset0:8 offset1:24
	ds_read2st64_b64 v[24:27], v5 offset0:32 offset1:48
	ds_read2st64_b64 v[8:11], v4 offset0:40 offset1:56
	ds_read2st64_b64 v[92:95], v5 offset0:64 offset1:80
	ds_read2st64_b64 v[12:15], v4 offset0:72 offset1:88
	ds_read2st64_b64 v[20:23], v5 offset0:96 offset1:112
	ds_read2st64_b64 v[4:7], v4 offset0:104 offset1:120
	ds_read_b64 v[68:69], v62
	ds_read_b64 v[72:73], v70
	v_add_u32_e32 v62, s19, v67
	v_add_u32_e32 v70, s8, v67
	ds_read_b64 v[84:85], v62
	ds_read_b64 v[90:91], v70
	v_add_u32_e32 v62, s18, v66
	v_add_u32_e32 v70, s7, v66
	ds_read_b64 v[96:97], v62
	ds_read_b64 v[100:101], v70
	v_add_u32_e32 v62, s17, v67
	v_add_u32_e32 v70, s6, v67
	ds_read_b64 v[64:65], v62
	ds_read_b64 v[70:71], v70
	v_add_u32_e32 v62, s13, v66
	v_add_u32_e32 v75, s5, v66
	ds_read_b64 v[86:87], v62
	ds_read_b64 v[102:103], v75
	v_add_u32_e32 v62, s12, v67
	v_add_u32_e32 v75, s4, v67
	ds_read_b64 v[80:81], v62
	ds_read_b64 v[88:89], v75
	v_add_u32_e32 v62, s11, v66
	v_add_u32_e32 v66, s1, v66
	ds_read_b64 v[98:99], v62
	ds_read_b64 v[104:105], v66
	v_add_u32_e32 v62, s10, v67
	v_add_u32_e32 v66, s0, v67
	ds_read_b64 v[62:63], v62
	ds_read_b64 v[66:67], v66
	s_waitcnt lgkmcnt(14)
	s_nop 0
	v_cvt_f32_i32_e32 v74, v74
	s_nop 0
	s_lshl_b64 s[0:1], s[42:43], 2
	s_add_u32 s0, s45, s0
	v_mul_f32_e32 v74, 0x38800000, v74
	v_cos_f32_e32 v78, v74
	v_sin_f32_e32 v79, v74
	s_addc_u32 s1, s24, s1
	s_and_b64 vcc, s[14:15], exec
	v_add_f32_e32 v76, v78, v78
	v_pk_mul_f32 v[74:75], v[78:79], v[78:79]
	v_mul_f32_e32 v76, v79, v76
	s_nop 0
	s_nop 0
	v_mov_b32_e32 v108, v79
	v_pk_add_f32 v[74:75], v[74:75], v[74:75] op_sel:[0,1] op_sel_hi:[0,1] neg_lo:[0,1] neg_hi:[0,1]
	v_pk_mul_f32 v[82:83], v[78:79], v[76:77] op_sel:[1,0] op_sel_hi:[0,0] neg_lo:[1,0]
	v_pk_mul_f32 v[106:107], v[68:69], v[108:109] op_sel:[1,0] op_sel_hi:[0,0] neg_lo:[1,0]
	v_pk_fma_f32 v[82:83], v[78:79], v[74:75], v[82:83]
	v_pk_fma_f32 v[68:69], v[68:69], v[78:79], v[106:107] op_sel_hi:[1,0,1]
	v_pk_mul_f32 v[78:79], v[76:77], s[46:47] op_sel_hi:[0,1]
	v_pk_fma_f32 v[106:107], v[74:75], s[40:41], v[78:79]
	s_nop 0
	v_pk_mul_f32 v[78:79], v[92:93], v[106:107] op_sel:[1,1] op_sel_hi:[0,1] neg_lo:[1,0]
	s_nop 0
	v_pk_fma_f32 v[78:79], v[92:93], v[106:107], v[78:79] op_sel_hi:[1,0,1]
	v_pk_mul_f32 v[92:93], v[76:77], v[82:83] op_sel:[0,1] op_sel_hi:[0,0] neg_lo:[0,1]
	v_pk_mul_f32 v[108:109], v[72:73], v[82:83] op_sel:[1,1] op_sel_hi:[0,1] neg_lo:[1,0]
	v_pk_fma_f32 v[92:93], v[74:75], v[82:83], v[92:93]
	v_pk_fma_f32 v[72:73], v[72:73], v[82:83], v[108:109] op_sel_hi:[1,0,1]
	v_pk_mul_f32 v[82:83], v[76:77], v[106:107] op_sel:[0,1] op_sel_hi:[0,0] neg_lo:[0,1]
	v_pk_fma_f32 v[106:107], v[74:75], v[106:107], v[82:83]
	s_nop 0
	v_pk_mul_f32 v[82:83], v[24:25], v[106:107] op_sel:[1,1] op_sel_hi:[0,1] neg_lo:[1,0]
	s_nop 0
	v_pk_fma_f32 v[82:83], v[24:25], v[106:107], v[82:83] op_sel_hi:[1,0,1]
	v_pk_mul_f32 v[24:25], v[76:77], v[92:93] op_sel:[0,1] op_sel_hi:[0,0] neg_lo:[0,1]
	v_pk_fma_f32 v[108:109], v[74:75], v[92:93], v[24:25]
	s_waitcnt lgkmcnt(7)
	v_pk_mul_f32 v[24:25], v[86:87], v[92:93] op_sel:[1,1] op_sel_hi:[0,1] neg_lo:[1,0]
	s_nop 0
	v_pk_fma_f32 v[24:25], v[86:87], v[92:93], v[24:25] op_sel_hi:[1,0,1]
	v_pk_mul_f32 v[86:87], v[76:77], v[106:107] op_sel:[0,1] op_sel_hi:[0,0] neg_lo:[0,1]
	v_pk_fma_f32 v[92:93], v[74:75], v[106:107], v[86:87]
	s_nop 0
	v_pk_mul_f32 v[86:87], v[20:21], v[92:93] op_sel:[1,1] op_sel_hi:[0,1] neg_lo:[1,0]
	s_nop 0
	v_pk_fma_f32 v[86:87], v[20:21], v[92:93], v[86:87] op_sel_hi:[1,0,1]
	v_pk_mul_f32 v[20:21], v[76:77], v[108:109] op_sel:[0,1] op_sel_hi:[0,0] neg_lo:[0,1]
	v_pk_fma_f32 v[106:107], v[74:75], v[108:109], v[20:21]
	s_waitcnt lgkmcnt(6)
	v_pk_mul_f32 v[20:21], v[102:103], v[108:109] op_sel:[1,1] op_sel_hi:[0,1] neg_lo:[1,0]
	s_nop 0
	v_pk_fma_f32 v[20:21], v[102:103], v[108:109], v[20:21] op_sel_hi:[1,0,1]
	v_pk_mul_f32 v[102:103], v[76:77], v[92:93] op_sel:[0,1] op_sel_hi:[0,0] neg_lo:[0,1]
	v_pk_fma_f32 v[102:103], v[74:75], v[92:93], v[102:103]
	s_nop 0
	v_pk_mul_f32 v[92:93], v[2:3], v[102:103] op_sel:[1,1] op_sel_hi:[0,1] neg_lo:[1,0]
	s_nop 0
	v_pk_fma_f32 v[92:93], v[2:3], v[102:103], v[92:93] op_sel_hi:[1,0,1]
	v_pk_mul_f32 v[2:3], v[76:77], v[106:107] op_sel:[0,1] op_sel_hi:[0,0] neg_lo:[0,1]
	v_pk_fma_f32 v[108:109], v[74:75], v[106:107], v[2:3]
	v_pk_mul_f32 v[2:3], v[96:97], v[106:107] op_sel:[1,1] op_sel_hi:[0,1] neg_lo:[1,0]
	s_nop 0
	v_pk_fma_f32 v[2:3], v[96:97], v[106:107], v[2:3] op_sel_hi:[1,0,1]
	v_pk_mul_f32 v[96:97], v[76:77], v[102:103] op_sel:[0,1] op_sel_hi:[0,0] neg_lo:[0,1]
	v_pk_fma_f32 v[102:103], v[74:75], v[102:103], v[96:97]
	s_nop 0
	v_pk_mul_f32 v[96:97], v[94:95], v[102:103] op_sel:[1,1] op_sel_hi:[0,1] neg_lo:[1,0]
	s_nop 0
	v_pk_fma_f32 v[96:97], v[94:95], v[102:103], v[96:97] op_sel_hi:[1,0,1]
	v_pk_mul_f32 v[94:95], v[76:77], v[108:109] op_sel:[0,1] op_sel_hi:[0,0] neg_lo:[0,1]
	v_pk_fma_f32 v[106:107], v[74:75], v[108:109], v[94:95]
	v_pk_mul_f32 v[94:95], v[100:101], v[108:109] op_sel:[1,1] op_sel_hi:[0,1] neg_lo:[1,0]
	s_nop 0
	v_pk_fma_f32 v[94:95], v[100:101], v[108:109], v[94:95] op_sel_hi:[1,0,1]
	v_pk_mul_f32 v[100:101], v[76:77], v[102:103] op_sel:[0,1] op_sel_hi:[0,0] neg_lo:[0,1]
	v_pk_fma_f32 v[100:101], v[74:75], v[102:103], v[100:101]
	s_nop 0
	v_pk_mul_f32 v[102:103], v[26:27], v[100:101] op_sel:[1,1] op_sel_hi:[0,1] neg_lo:[1,0]
	s_waitcnt lgkmcnt(3)
	v_pk_fma_f32 v[26:27], v[26:27], v[100:101], v[102:103] op_sel_hi:[1,0,1]
	v_pk_mul_f32 v[102:103], v[76:77], v[106:107] op_sel:[0,1] op_sel_hi:[0,0] neg_lo:[0,1]
	v_pk_mul_f32 v[108:109], v[98:99], v[106:107] op_sel:[1,1] op_sel_hi:[0,1] neg_lo:[1,0]
	v_pk_fma_f32 v[102:103], v[74:75], v[106:107], v[102:103]
	v_pk_fma_f32 v[98:99], v[98:99], v[106:107], v[108:109] op_sel_hi:[1,0,1]
	v_pk_mul_f32 v[106:107], v[76:77], v[100:101] op_sel:[0,1] op_sel_hi:[0,0] neg_lo:[0,1]
	v_pk_fma_f32 v[100:101], v[74:75], v[100:101], v[106:107]
	s_nop 0
	v_pk_mul_f32 v[106:107], v[22:23], v[100:101] op_sel:[1,1] op_sel_hi:[0,1] neg_lo:[1,0]
	s_waitcnt lgkmcnt(2)
	v_pk_fma_f32 v[22:23], v[22:23], v[100:101], v[106:107] op_sel_hi:[1,0,1]
	v_pk_mul_f32 v[106:107], v[76:77], v[102:103] op_sel:[0,1] op_sel_hi:[0,0] neg_lo:[0,1]
	v_pk_mul_f32 v[108:109], v[104:105], v[102:103] op_sel:[1,1] op_sel_hi:[0,1] neg_lo:[1,0]
	v_pk_fma_f32 v[106:107], v[74:75], v[102:103], v[106:107]
	v_pk_fma_f32 v[102:103], v[104:105], v[102:103], v[108:109] op_sel_hi:[1,0,1]
	v_pk_mul_f32 v[104:105], v[76:77], v[100:101] op_sel:[0,1] op_sel_hi:[0,0] neg_lo:[0,1]
	v_pk_fma_f32 v[100:101], v[74:75], v[100:101], v[104:105]
	s_nop 0
	v_pk_mul_f32 v[104:105], v[16:17], v[100:101] op_sel:[1,1] op_sel_hi:[0,1] neg_lo:[1,0]
	s_nop 0
	v_pk_fma_f32 v[16:17], v[16:17], v[100:101], v[104:105] op_sel_hi:[1,0,1]
	v_pk_mul_f32 v[104:105], v[76:77], v[106:107] op_sel:[0,1] op_sel_hi:[0,0] neg_lo:[0,1]
	v_pk_mul_f32 v[108:109], v[84:85], v[106:107] op_sel:[1,1] op_sel_hi:[0,1] neg_lo:[1,0]
	v_pk_fma_f32 v[104:105], v[74:75], v[106:107], v[104:105]
	v_pk_fma_f32 v[84:85], v[84:85], v[106:107], v[108:109] op_sel_hi:[1,0,1]
	v_pk_mul_f32 v[106:107], v[76:77], v[100:101] op_sel:[0,1] op_sel_hi:[0,0] neg_lo:[0,1]
	v_pk_fma_f32 v[100:101], v[74:75], v[100:101], v[106:107]
	s_nop 0
	v_pk_mul_f32 v[106:107], v[12:13], v[100:101] op_sel:[1,1] op_sel_hi:[0,1] neg_lo:[1,0]
	s_nop 0
	v_pk_fma_f32 v[12:13], v[12:13], v[100:101], v[106:107] op_sel_hi:[1,0,1]
	v_pk_mul_f32 v[106:107], v[76:77], v[104:105] op_sel:[0,1] op_sel_hi:[0,0] neg_lo:[0,1]
	v_pk_mul_f32 v[108:109], v[90:91], v[104:105] op_sel:[1,1] op_sel_hi:[0,1] neg_lo:[1,0]
	v_pk_fma_f32 v[106:107], v[74:75], v[104:105], v[106:107]
	v_pk_fma_f32 v[90:91], v[90:91], v[104:105], v[108:109] op_sel_hi:[1,0,1]
	v_pk_mul_f32 v[104:105], v[76:77], v[100:101] op_sel:[0,1] op_sel_hi:[0,0] neg_lo:[0,1]
	v_pk_fma_f32 v[100:101], v[74:75], v[100:101], v[104:105]
	s_nop 0
	v_pk_mul_f32 v[104:105], v[8:9], v[100:101] op_sel:[1,1] op_sel_hi:[0,1] neg_lo:[1,0]
	s_nop 0
	v_pk_fma_f32 v[8:9], v[8:9], v[100:101], v[104:105] op_sel_hi:[1,0,1]
	v_pk_mul_f32 v[104:105], v[76:77], v[106:107] op_sel:[0,1] op_sel_hi:[0,0] neg_lo:[0,1]
	v_pk_mul_f32 v[108:109], v[80:81], v[106:107] op_sel:[1,1] op_sel_hi:[0,1] neg_lo:[1,0]
	v_pk_fma_f32 v[104:105], v[74:75], v[106:107], v[104:105]
	v_pk_fma_f32 v[80:81], v[80:81], v[106:107], v[108:109] op_sel_hi:[1,0,1]
	v_pk_mul_f32 v[106:107], v[76:77], v[100:101] op_sel:[0,1] op_sel_hi:[0,0] neg_lo:[0,1]
	v_pk_fma_f32 v[100:101], v[74:75], v[100:101], v[106:107]
	s_nop 0
	v_pk_mul_f32 v[106:107], v[4:5], v[100:101] op_sel:[1,1] op_sel_hi:[0,1] neg_lo:[1,0]
	s_nop 0
	v_pk_fma_f32 v[4:5], v[4:5], v[100:101], v[106:107] op_sel_hi:[1,0,1]
	v_pk_mul_f32 v[106:107], v[76:77], v[104:105] op_sel:[0,1] op_sel_hi:[0,0] neg_lo:[0,1]
	v_pk_mul_f32 v[108:109], v[88:89], v[104:105] op_sel:[1,1] op_sel_hi:[0,1] neg_lo:[1,0]
	v_pk_fma_f32 v[106:107], v[74:75], v[104:105], v[106:107]
	v_pk_fma_f32 v[88:89], v[88:89], v[104:105], v[108:109] op_sel_hi:[1,0,1]
	v_pk_mul_f32 v[104:105], v[76:77], v[100:101] op_sel:[0,1] op_sel_hi:[0,0] neg_lo:[0,1]
	v_pk_fma_f32 v[100:101], v[74:75], v[100:101], v[104:105]
	s_nop 0
	v_pk_mul_f32 v[104:105], v[18:19], v[100:101] op_sel:[1,1] op_sel_hi:[0,1] neg_lo:[1,0]
	s_nop 0
	v_pk_fma_f32 v[18:19], v[18:19], v[100:101], v[104:105] op_sel_hi:[1,0,1]
	v_pk_mul_f32 v[104:105], v[76:77], v[106:107] op_sel:[0,1] op_sel_hi:[0,0] neg_lo:[0,1]
	v_pk_mul_f32 v[108:109], v[64:65], v[106:107] op_sel:[1,1] op_sel_hi:[0,1] neg_lo:[1,0]
	v_pk_fma_f32 v[104:105], v[74:75], v[106:107], v[104:105]
	v_pk_fma_f32 v[64:65], v[64:65], v[106:107], v[108:109] op_sel_hi:[1,0,1]
	v_pk_mul_f32 v[106:107], v[76:77], v[100:101] op_sel:[0,1] op_sel_hi:[0,0] neg_lo:[0,1]
	v_pk_fma_f32 v[100:101], v[74:75], v[100:101], v[106:107]
	s_nop 0
	v_pk_mul_f32 v[106:107], v[14:15], v[100:101] op_sel:[1,1] op_sel_hi:[0,1] neg_lo:[1,0]
	s_nop 0
	v_pk_fma_f32 v[14:15], v[14:15], v[100:101], v[106:107] op_sel_hi:[1,0,1]
	v_pk_mul_f32 v[106:107], v[76:77], v[104:105] op_sel:[0,1] op_sel_hi:[0,0] neg_lo:[0,1]
	v_pk_mul_f32 v[108:109], v[70:71], v[104:105] op_sel:[1,1] op_sel_hi:[0,1] neg_lo:[1,0]
	v_pk_fma_f32 v[106:107], v[74:75], v[104:105], v[106:107]
	v_pk_fma_f32 v[70:71], v[70:71], v[104:105], v[108:109] op_sel_hi:[1,0,1]
	v_pk_mul_f32 v[104:105], v[76:77], v[100:101] op_sel:[0,1] op_sel_hi:[0,0] neg_lo:[0,1]
	v_pk_fma_f32 v[100:101], v[74:75], v[100:101], v[104:105]
	s_nop 0
	v_pk_mul_f32 v[104:105], v[10:11], v[100:101] op_sel:[1,1] op_sel_hi:[0,1] neg_lo:[1,0]
	s_waitcnt lgkmcnt(1)
	v_pk_fma_f32 v[10:11], v[10:11], v[100:101], v[104:105] op_sel_hi:[1,0,1]
	v_pk_mul_f32 v[104:105], v[76:77], v[106:107] op_sel:[0,1] op_sel_hi:[0,0] neg_lo:[0,1]
	v_pk_mul_f32 v[108:109], v[62:63], v[106:107] op_sel:[1,1] op_sel_hi:[0,1] neg_lo:[1,0]
	v_pk_fma_f32 v[104:105], v[74:75], v[106:107], v[104:105]
	v_pk_fma_f32 v[62:63], v[62:63], v[106:107], v[108:109] op_sel_hi:[1,0,1]
	v_pk_mul_f32 v[76:77], v[76:77], v[100:101] op_sel:[0,1] op_sel_hi:[0,0] neg_lo:[0,1]
	v_pk_fma_f32 v[74:75], v[74:75], v[100:101], v[76:77]
	s_nop 0
	v_pk_mul_f32 v[76:77], v[6:7], v[74:75] op_sel:[1,1] op_sel_hi:[0,1] neg_lo:[1,0]
	s_nop 0
	v_pk_fma_f32 v[6:7], v[6:7], v[74:75], v[76:77] op_sel_hi:[1,0,1]
	s_waitcnt lgkmcnt(0)
	v_pk_mul_f32 v[74:75], v[66:67], v[104:105] op_sel:[1,1] op_sel_hi:[0,1] neg_lo:[1,0]
	v_pk_add_f32 v[76:77], v[82:83], v[8:9]
	v_pk_fma_f32 v[66:67], v[66:67], v[104:105], v[74:75] op_sel_hi:[1,0,1]
	v_pk_add_f32 v[74:75], v[0:1], v[16:17]
	v_pk_add_f32 v[0:1], v[0:1], v[16:17] neg_lo:[0,1] neg_hi:[0,1]
	v_pk_add_f32 v[16:17], v[92:93], v[18:19]
	v_pk_add_f32 v[18:19], v[92:93], v[18:19] neg_lo:[0,1] neg_hi:[0,1]
	v_pk_add_f32 v[8:9], v[82:83], v[8:9] neg_lo:[0,1] neg_hi:[0,1]
	v_pk_add_f32 v[82:83], v[26:27], v[10:11]
	v_pk_add_f32 v[10:11], v[26:27], v[10:11] neg_lo:[0,1] neg_hi:[0,1]
	v_pk_add_f32 v[92:93], v[86:87], v[4:5]
	v_pk_add_f32 v[4:5], v[86:87], v[4:5] neg_lo:[0,1] neg_hi:[0,1]
	v_pk_add_f32 v[86:87], v[22:23], v[6:7]
	v_pk_add_f32 v[6:7], v[22:23], v[6:7] neg_lo:[0,1] neg_hi:[0,1]
	v_pk_add_f32 v[22:23], v[68:69], v[84:85]
	v_pk_add_f32 v[68:69], v[68:69], v[84:85] neg_lo:[0,1] neg_hi:[0,1]
	v_pk_add_f32 v[84:85], v[2:3], v[64:65]
	v_pk_add_f32 v[2:3], v[2:3], v[64:65] neg_lo:[0,1] neg_hi:[0,1]
	v_pk_add_f32 v[64:65], v[24:25], v[80:81]
	v_pk_add_f32 v[24:25], v[24:25], v[80:81] neg_lo:[0,1] neg_hi:[0,1]
	v_pk_add_f32 v[80:81], v[98:99], v[62:63]
	v_pk_add_f32 v[62:63], v[98:99], v[62:63] neg_lo:[0,1] neg_hi:[0,1]
	v_pk_add_f32 v[98:99], v[74:75], v[16:17]
	v_pk_add_f32 v[16:17], v[74:75], v[16:17] neg_lo:[0,1] neg_hi:[0,1]
	v_xor_b32_e32 v74, 0x80000000, v19
	v_mov_b32_e32 v75, v18
	v_pk_add_f32 v[26:27], v[78:79], v[12:13]
	v_pk_add_f32 v[12:13], v[78:79], v[12:13] neg_lo:[0,1] neg_hi:[0,1]
	v_pk_add_f32 v[78:79], v[96:97], v[14:15]
	v_pk_add_f32 v[14:15], v[96:97], v[14:15] neg_lo:[0,1] neg_hi:[0,1]
	v_pk_add_f32 v[18:19], v[0:1], v[74:75]
	v_pk_add_f32 v[0:1], v[0:1], v[74:75] neg_lo:[0,1] neg_hi:[0,1]
	v_pk_add_f32 v[74:75], v[76:77], v[82:83]
	v_pk_add_f32 v[76:77], v[76:77], v[82:83] neg_lo:[0,1] neg_hi:[0,1]
	v_xor_b32_e32 v82, 0x80000000, v11
	v_mov_b32_e32 v83, v10
	v_pk_add_f32 v[10:11], v[8:9], v[82:83]
	v_pk_add_f32 v[8:9], v[8:9], v[82:83] neg_lo:[0,1] neg_hi:[0,1]
	v_pk_add_f32 v[82:83], v[26:27], v[78:79]
	v_pk_add_f32 v[26:27], v[26:27], v[78:79] neg_lo:[0,1] neg_hi:[0,1]
	v_xor_b32_e32 v78, 0x80000000, v15
	v_mov_b32_e32 v79, v14
	v_pk_add_f32 v[14:15], v[12:13], v[78:79]
	v_pk_add_f32 v[12:13], v[12:13], v[78:79] neg_lo:[0,1] neg_hi:[0,1]
	v_pk_add_f32 v[78:79], v[92:93], v[86:87]
	v_pk_add_f32 v[86:87], v[92:93], v[86:87] neg_lo:[0,1] neg_hi:[0,1]
	v_xor_b32_e32 v92, 0x80000000, v7
	v_mov_b32_e32 v93, v6
	v_pk_add_f32 v[6:7], v[4:5], v[92:93]
	v_pk_add_f32 v[4:5], v[4:5], v[92:93] neg_lo:[0,1] neg_hi:[0,1]
	v_pk_add_f32 v[92:93], v[22:23], v[84:85]
	v_pk_add_f32 v[22:23], v[22:23], v[84:85] neg_lo:[0,1] neg_hi:[0,1]
	v_xor_b32_e32 v84, 0x80000000, v3
	v_mov_b32_e32 v85, v2
	v_pk_add_f32 v[96:97], v[72:73], v[90:91]
	v_pk_add_f32 v[72:73], v[72:73], v[90:91] neg_lo:[0,1] neg_hi:[0,1]
	v_pk_add_f32 v[90:91], v[94:95], v[70:71]
	v_pk_add_f32 v[70:71], v[94:95], v[70:71] neg_lo:[0,1] neg_hi:[0,1]
	v_pk_add_f32 v[2:3], v[68:69], v[84:85]
	v_pk_add_f32 v[68:69], v[68:69], v[84:85] neg_lo:[0,1] neg_hi:[0,1]
	v_pk_add_f32 v[84:85], v[64:65], v[80:81]
	v_pk_add_f32 v[64:65], v[64:65], v[80:81] neg_lo:[0,1] neg_hi:[0,1]
	v_xor_b32_e32 v80, 0x80000000, v63
	v_mov_b32_e32 v81, v62
	v_pk_add_f32 v[94:95], v[20:21], v[88:89]
	v_pk_add_f32 v[20:21], v[20:21], v[88:89] neg_lo:[0,1] neg_hi:[0,1]
	v_pk_add_f32 v[88:89], v[102:103], v[66:67]
	v_pk_add_f32 v[66:67], v[102:103], v[66:67] neg_lo:[0,1] neg_hi:[0,1]
	v_pk_add_f32 v[62:63], v[24:25], v[80:81]
	v_pk_add_f32 v[24:25], v[24:25], v[80:81] neg_lo:[0,1] neg_hi:[0,1]
	v_pk_add_f32 v[80:81], v[96:97], v[90:91]
	v_pk_add_f32 v[90:91], v[96:97], v[90:91] neg_lo:[0,1] neg_hi:[0,1]
	v_xor_b32_e32 v96, 0x80000000, v71
	v_mov_b32_e32 v97, v70
	v_pk_add_f32 v[70:71], v[72:73], v[96:97]
	v_pk_add_f32 v[72:73], v[72:73], v[96:97] neg_lo:[0,1] neg_hi:[0,1]
	v_pk_add_f32 v[96:97], v[94:95], v[88:89]
	v_pk_add_f32 v[88:89], v[94:95], v[88:89] neg_lo:[0,1] neg_hi:[0,1]
	v_xor_b32_e32 v94, 0x80000000, v67
	v_mov_b32_e32 v95, v66
	v_pk_add_f32 v[66:67], v[20:21], v[94:95]
	v_pk_add_f32 v[20:21], v[20:21], v[94:95] neg_lo:[0,1] neg_hi:[0,1]
	v_pk_add_f32 v[94:95], v[98:99], v[74:75]
	v_pk_add_f32 v[74:75], v[98:99], v[74:75] neg_lo:[0,1] neg_hi:[0,1]
	v_pk_mul_f32 v[98:99], v[10:11], s[60:61] op_sel:[1,0] op_sel_hi:[0,0] neg_lo:[1,0]
	v_xor_b32_e32 v100, 0x80000000, v9
	v_pk_fma_f32 v[10:11], v[10:11], s[60:61], v[98:99] op_sel_hi:[1,0,1]
	v_mov_b32_e32 v101, v8
	v_pk_add_f32 v[98:99], v[18:19], v[10:11]
	v_pk_add_f32 v[10:11], v[18:19], v[10:11] neg_lo:[0,1] neg_hi:[0,1]
	v_xor_b32_e32 v18, 0x80000000, v77
	v_mov_b32_e32 v19, v76
	v_pk_add_f32 v[76:77], v[16:17], v[18:19]
	v_pk_add_f32 v[16:17], v[16:17], v[18:19] neg_lo:[0,1] neg_hi:[0,1]
	v_pk_mul_f32 v[18:19], v[8:9], s[60:61] op_sel_hi:[1,0]
	s_nop 0
	v_pk_fma_f32 v[8:9], v[100:101], s[60:61], v[18:19] op_sel_hi:[1,0,1] neg_lo:[0,0,1] neg_hi:[0,0,1]
	v_xor_b32_e32 v100, 0x80000000, v5
	v_pk_add_f32 v[18:19], v[0:1], v[8:9]
	v_pk_add_f32 v[0:1], v[0:1], v[8:9] neg_lo:[0,1] neg_hi:[0,1]
	v_pk_add_f32 v[8:9], v[82:83], v[78:79]
	v_pk_add_f32 v[78:79], v[82:83], v[78:79] neg_lo:[0,1] neg_hi:[0,1]
	v_pk_mul_f32 v[82:83], v[6:7], s[60:61] op_sel:[1,0] op_sel_hi:[0,0] neg_lo:[1,0]
	v_mov_b32_e32 v101, v4
	v_pk_fma_f32 v[6:7], v[6:7], s[60:61], v[82:83] op_sel_hi:[1,0,1]
	s_nop 0
	v_pk_add_f32 v[82:83], v[14:15], v[6:7]
	v_pk_add_f32 v[6:7], v[14:15], v[6:7] neg_lo:[0,1] neg_hi:[0,1]
	v_xor_b32_e32 v14, 0x80000000, v87
	v_mov_b32_e32 v15, v86
	v_pk_add_f32 v[86:87], v[26:27], v[14:15]
	v_pk_add_f32 v[14:15], v[26:27], v[14:15] neg_lo:[0,1] neg_hi:[0,1]
	v_pk_mul_f32 v[26:27], v[4:5], s[60:61] op_sel_hi:[1,0]
	s_nop 0
	v_pk_fma_f32 v[4:5], v[100:101], s[60:61], v[26:27] op_sel_hi:[1,0,1] neg_lo:[0,0,1] neg_hi:[0,0,1]
	v_xor_b32_e32 v100, 0x80000000, v25
	v_pk_add_f32 v[26:27], v[12:13], v[4:5]
	v_pk_add_f32 v[4:5], v[12:13], v[4:5] neg_lo:[0,1] neg_hi:[0,1]
	v_pk_add_f32 v[12:13], v[92:93], v[84:85]
	v_pk_add_f32 v[84:85], v[92:93], v[84:85] neg_lo:[0,1] neg_hi:[0,1]
	v_pk_mul_f32 v[92:93], v[62:63], s[60:61] op_sel:[1,0] op_sel_hi:[0,0] neg_lo:[1,0]
	v_mov_b32_e32 v101, v24
	v_pk_fma_f32 v[62:63], v[62:63], s[60:61], v[92:93] op_sel_hi:[1,0,1]
	s_nop 0
	v_pk_add_f32 v[92:93], v[2:3], v[62:63]
	v_pk_add_f32 v[2:3], v[2:3], v[62:63] neg_lo:[0,1] neg_hi:[0,1]
	v_xor_b32_e32 v62, 0x80000000, v65
	v_mov_b32_e32 v63, v64
	v_pk_add_f32 v[64:65], v[22:23], v[62:63]
	v_pk_add_f32 v[22:23], v[22:23], v[62:63] neg_lo:[0,1] neg_hi:[0,1]
	v_pk_mul_f32 v[62:63], v[24:25], s[60:61] op_sel_hi:[1,0]
	s_nop 0
	v_pk_fma_f32 v[24:25], v[100:101], s[60:61], v[62:63] op_sel_hi:[1,0,1] neg_lo:[0,0,1] neg_hi:[0,0,1]
	v_xor_b32_e32 v100, 0x80000000, v21
	v_pk_add_f32 v[62:63], v[68:69], v[24:25]
	v_pk_add_f32 v[24:25], v[68:69], v[24:25] neg_lo:[0,1] neg_hi:[0,1]
	v_pk_add_f32 v[68:69], v[80:81], v[96:97]
	v_pk_add_f32 v[80:81], v[80:81], v[96:97] neg_lo:[0,1] neg_hi:[0,1]
	v_pk_mul_f32 v[96:97], v[66:67], s[60:61] op_sel:[1,0] op_sel_hi:[0,0] neg_lo:[1,0]
	v_mov_b32_e32 v101, v20
	v_pk_fma_f32 v[66:67], v[66:67], s[60:61], v[96:97] op_sel_hi:[1,0,1]
	s_nop 0
	v_pk_add_f32 v[96:97], v[70:71], v[66:67]
	v_pk_add_f32 v[66:67], v[70:71], v[66:67] neg_lo:[0,1] neg_hi:[0,1]
	v_xor_b32_e32 v70, 0x80000000, v89
	v_mov_b32_e32 v71, v88
	v_pk_add_f32 v[88:89], v[90:91], v[70:71]
	v_pk_add_f32 v[70:71], v[90:91], v[70:71] neg_lo:[0,1] neg_hi:[0,1]
	v_pk_mul_f32 v[90:91], v[20:21], s[60:61] op_sel_hi:[1,0]
	s_nop 0
	v_pk_fma_f32 v[20:21], v[100:101], s[60:61], v[90:91] op_sel_hi:[1,0,1] neg_lo:[0,0,1] neg_hi:[0,0,1]
	s_nop 0
	v_pk_add_f32 v[90:91], v[72:73], v[20:21]
	v_pk_add_f32 v[20:21], v[72:73], v[20:21] neg_lo:[0,1] neg_hi:[0,1]
	v_pk_add_f32 v[72:73], v[94:95], v[8:9]
	v_pk_add_f32 v[8:9], v[94:95], v[8:9] neg_lo:[0,1] neg_hi:[0,1]
	v_pk_mul_f32 v[94:95], v[82:83], s[54:55] op_sel:[1,0] op_sel_hi:[0,0] neg_lo:[1,0]
	s_nop 0
	v_pk_fma_f32 v[82:83], v[82:83], s[52:53], v[94:95] op_sel_hi:[1,0,1]
	s_nop 0
	v_pk_add_f32 v[94:95], v[98:99], v[82:83]
	v_pk_add_f32 v[82:83], v[98:99], v[82:83] neg_lo:[0,1] neg_hi:[0,1]
	v_pk_mul_f32 v[98:99], v[86:87], s[60:61] op_sel:[1,0] op_sel_hi:[0,0] neg_lo:[1,0]
	s_nop 0
	v_pk_fma_f32 v[86:87], v[86:87], s[60:61], v[98:99] op_sel_hi:[1,0,1]
	s_nop 0
	v_pk_add_f32 v[98:99], v[76:77], v[86:87]
	v_pk_add_f32 v[86:87], v[76:77], v[86:87] neg_lo:[0,1] neg_hi:[0,1]
	v_pk_mul_f32 v[76:77], v[26:27], s[52:53] op_sel:[1,0] op_sel_hi:[0,0] neg_lo:[1,0]
	s_nop 0
	v_pk_fma_f32 v[26:27], v[26:27], s[54:55], v[76:77] op_sel_hi:[1,0,1]
	v_xor_b32_e32 v76, 0x80000000, v67
	v_pk_add_f32 v[100:101], v[18:19], v[26:27]
	v_pk_add_f32 v[26:27], v[18:19], v[26:27] neg_lo:[0,1] neg_hi:[0,1]
	v_pk_add_f32 v[102:103], v[74:75], v[78:79] op_sel:[0,1] op_sel_hi:[1,0] neg_lo:[0,1]
	v_pk_add_f32 v[104:105], v[74:75], v[78:79] op_sel:[0,1] op_sel_hi:[1,0] neg_hi:[0,1]
	v_pk_mul_f32 v[18:19], v[6:7], s[54:55] op_sel_hi:[1,0]
	v_xor_b32_e32 v74, 0x80000000, v7
	v_mov_b32_e32 v75, v6
	v_pk_fma_f32 v[6:7], v[74:75], s[52:53], v[18:19] op_sel_hi:[1,0,1] neg_lo:[0,0,1] neg_hi:[0,0,1]
	v_xor_b32_e32 v74, 0x80000000, v15
	v_pk_add_f32 v[18:19], v[10:11], v[6:7]
	v_pk_add_f32 v[6:7], v[10:11], v[6:7] neg_lo:[0,1] neg_hi:[0,1]
	v_pk_mul_f32 v[10:11], v[14:15], s[60:61] op_sel_hi:[1,0]
	v_mov_b32_e32 v75, v14
	v_pk_fma_f32 v[10:11], v[74:75], s[60:61], v[10:11] op_sel_hi:[1,0,1] neg_lo:[0,0,1] neg_hi:[0,0,1]
	v_xor_b32_e32 v74, 0x80000000, v5
	v_pk_add_f32 v[14:15], v[16:17], v[10:11]
	v_pk_add_f32 v[10:11], v[16:17], v[10:11] neg_lo:[0,1] neg_hi:[0,1]
	v_pk_mul_f32 v[16:17], v[4:5], s[52:53] op_sel_hi:[1,0]
	v_mov_b32_e32 v75, v4
	v_pk_fma_f32 v[4:5], v[74:75], s[54:55], v[16:17] op_sel_hi:[1,0,1] neg_lo:[0,0,1] neg_hi:[0,0,1]
	v_xor_b32_e32 v74, 0x80000000, v89
	v_pk_add_f32 v[16:17], v[0:1], v[4:5]
	v_pk_add_f32 v[106:107], v[0:1], v[4:5] neg_lo:[0,1] neg_hi:[0,1]
	v_pk_add_f32 v[0:1], v[12:13], v[68:69]
	v_pk_add_f32 v[4:5], v[12:13], v[68:69] neg_lo:[0,1] neg_hi:[0,1]
	v_mov_b32_e32 v75, v88
	v_pk_mul_f32 v[12:13], v[96:97], s[54:55] op_sel:[1,0] op_sel_hi:[0,0] neg_lo:[1,0]
	v_pk_mul_f32 v[74:75], v[74:75], s[60:61] op_sel_hi:[1,0]
	v_pk_fma_f32 v[12:13], v[96:97], s[52:53], v[12:13] op_sel_hi:[1,0,1]
	v_pk_fma_f32 v[74:75], v[88:89], s[60:61], v[74:75] op_sel_hi:[1,0,1]
	v_pk_add_f32 v[68:69], v[92:93], v[12:13]
	v_pk_add_f32 v[12:13], v[92:93], v[12:13] neg_lo:[0,1] neg_hi:[0,1]
	v_pk_add_f32 v[88:89], v[64:65], v[74:75]
	v_pk_add_f32 v[92:93], v[64:65], v[74:75] neg_lo:[0,1] neg_hi:[0,1]
	v_pk_mul_f32 v[64:65], v[90:91], s[52:53] op_sel:[1,0] op_sel_hi:[0,0] neg_lo:[1,0]
	v_pk_add_f32 v[78:79], v[72:73], v[0:1]
	v_pk_fma_f32 v[64:65], v[90:91], s[54:55], v[64:65] op_sel_hi:[1,0,1]
	s_nop 0
	v_pk_add_f32 v[74:75], v[62:63], v[64:65]
	v_pk_add_f32 v[90:91], v[62:63], v[64:65] neg_lo:[0,1] neg_hi:[0,1]
	v_pk_mul_f32 v[0:1], v[68:69], s[48:49] op_sel:[1,0] op_sel_hi:[0,0] neg_lo:[1,0]
	v_pk_add_f32 v[64:65], v[84:85], v[80:81] op_sel:[0,1] op_sel_hi:[1,0] neg_lo:[0,1]
	v_pk_add_f32 v[80:81], v[84:85], v[80:81] op_sel:[0,1] op_sel_hi:[1,0] neg_hi:[0,1]
	v_pk_mul_f32 v[62:63], v[66:67], s[54:55] op_sel_hi:[1,0]
	v_mov_b32_e32 v77, v66
	v_pk_fma_f32 v[0:1], v[68:69], s[44:45], v[0:1] op_sel_hi:[1,0,1]
	v_pk_fma_f32 v[62:63], v[76:77], s[52:53], v[62:63] op_sel_hi:[1,0,1] neg_lo:[0,0,1] neg_hi:[0,0,1]
	v_pk_add_f32 v[76:77], v[94:95], v[0:1]
	v_pk_mul_f32 v[0:1], v[88:89], s[54:55] op_sel:[1,0] op_sel_hi:[0,0] neg_lo:[1,0]
	v_pk_add_f32 v[84:85], v[2:3], v[62:63]
	v_pk_fma_f32 v[0:1], v[88:89], s[52:53], v[0:1] op_sel_hi:[1,0,1]
	v_pk_add_f32 v[2:3], v[2:3], v[62:63] neg_lo:[0,1] neg_hi:[0,1]
	v_pk_add_f32 v[72:73], v[98:99], v[0:1]
	v_pk_mul_f32 v[0:1], v[74:75], s[58:59] op_sel:[1,0] op_sel_hi:[0,0] neg_lo:[1,0]
	v_pk_mul_f32 v[62:63], v[70:71], s[60:61] op_sel_hi:[1,0]
	v_pk_fma_f32 v[0:1], v[74:75], s[56:57], v[0:1] op_sel_hi:[1,0,1]
	v_xor_b32_e32 v66, 0x80000000, v71
	v_pk_add_f32 v[74:75], v[100:101], v[0:1]
	v_pk_mul_f32 v[0:1], v[64:65], s[60:61] op_sel:[1,0] op_sel_hi:[0,0] neg_lo:[1,0]
	v_mov_b32_e32 v67, v70
	v_pk_fma_f32 v[0:1], v[64:65], s[60:61], v[0:1] op_sel_hi:[1,0,1]
	v_pk_fma_f32 v[62:63], v[66:67], s[60:61], v[62:63] op_sel_hi:[1,0,1] neg_lo:[0,0,1] neg_hi:[0,0,1]
	v_pk_add_f32 v[66:67], v[102:103], v[0:1]
	v_pk_mul_f32 v[0:1], v[84:85], s[56:57] op_sel:[1,0] op_sel_hi:[0,0] neg_lo:[1,0]
	v_pk_add_f32 v[70:71], v[22:23], v[62:63]
	v_pk_fma_f32 v[0:1], v[84:85], s[58:59], v[0:1] op_sel_hi:[1,0,1]
	v_pk_add_f32 v[96:97], v[22:23], v[62:63] neg_lo:[0,1] neg_hi:[0,1]
	v_pk_mul_f32 v[22:23], v[20:21], s[52:53] op_sel_hi:[1,0]
	v_pk_add_f32 v[68:69], v[18:19], v[0:1]
	v_pk_fma_f32 v[20:21], v[20:21], s[54:55], v[22:23] op_sel:[1,0,0] op_sel_hi:[0,0,1] neg_lo:[1,0,1] neg_hi:[0,0,1]
	v_pk_mul_f32 v[0:1], v[70:71], s[52:53] op_sel:[1,0] op_sel_hi:[0,0] neg_lo:[1,0]
	v_pk_add_f32 v[22:23], v[24:25], v[20:21]
	v_pk_fma_f32 v[0:1], v[70:71], s[54:55], v[0:1] op_sel_hi:[1,0,1]
	v_pk_add_f32 v[108:109], v[24:25], v[20:21] neg_lo:[0,1] neg_hi:[0,1]
	v_pk_add_f32 v[62:63], v[14:15], v[0:1]
	v_pk_mul_f32 v[0:1], v[22:23], s[44:45] op_sel:[1,0] op_sel_hi:[0,0] neg_lo:[1,0]
	s_nop 0
	v_pk_fma_f32 v[0:1], v[22:23], s[48:49], v[0:1] op_sel_hi:[1,0,1]
	s_nop 0
	v_pk_add_f32 v[64:65], v[16:17], v[0:1]
	v_pk_add_f32 v[22:23], v[8:9], v[4:5] op_sel:[0,1] op_sel_hi:[1,0] neg_lo:[0,1]
	v_pk_mul_f32 v[0:1], v[12:13], s[48:49] op_sel_hi:[1,0]
	v_xor_b32_e32 v4, 0x80000000, v13
	v_mov_b32_e32 v5, v12
	v_pk_fma_f32 v[0:1], v[4:5], s[44:45], v[0:1] op_sel_hi:[1,0,1] neg_lo:[0,0,1] neg_hi:[0,0,1]
	v_xor_b32_e32 v4, 0x80000000, v93
	v_pk_add_f32 v[24:25], v[82:83], v[0:1]
	v_pk_mul_f32 v[0:1], v[92:93], s[54:55] op_sel_hi:[1,0]
	v_mov_b32_e32 v5, v92
	v_pk_fma_f32 v[0:1], v[4:5], s[52:53], v[0:1] op_sel_hi:[1,0,1] neg_lo:[0,0,1] neg_hi:[0,0,1]
	v_xor_b32_e32 v4, 0x80000000, v91
	v_pk_add_f32 v[18:19], v[86:87], v[0:1]
	v_pk_mul_f32 v[0:1], v[90:91], s[58:59] op_sel_hi:[1,0]
	v_mov_b32_e32 v5, v90
	v_pk_fma_f32 v[0:1], v[4:5], s[56:57], v[0:1] op_sel_hi:[1,0,1] neg_lo:[0,0,1] neg_hi:[0,0,1]
	s_nop 0
	v_pk_add_f32 v[20:21], v[26:27], v[0:1]
	v_pk_mul_f32 v[0:1], v[80:81], s[60:61] op_sel_hi:[1,0]
	s_nop 0
	v_pk_fma_f32 v[0:1], v[80:81], s[60:61], v[0:1] op_sel:[1,0,0] op_sel_hi:[0,0,1] neg_lo:[1,0,1] neg_hi:[0,0,1]
	v_xor_b32_e32 v8, 0x80000000, v3
	v_pk_add_f32 v[4:5], v[104:105], v[0:1]
	v_pk_mul_f32 v[0:1], v[2:3], s[56:57] op_sel_hi:[1,0]
	v_mov_b32_e32 v9, v2
	v_pk_fma_f32 v[0:1], v[8:9], s[58:59], v[0:1] op_sel_hi:[1,0,1] neg_lo:[0,0,1] neg_hi:[0,0,1]
	s_nop 0
	v_pk_add_f32 v[6:7], v[6:7], v[0:1]
	v_pk_mul_f32 v[0:1], v[96:97], s[52:53] op_sel_hi:[1,0]
	s_nop 0
	v_pk_fma_f32 v[0:1], v[96:97], s[54:55], v[0:1] op_sel:[1,0,0] op_sel_hi:[0,0,1] neg_lo:[1,0,1] neg_hi:[0,0,1]
	v_pk_mul_f32 v[2:3], v[108:109], s[44:45] op_sel_hi:[1,0]
	v_pk_add_f32 v[0:1], v[10:11], v[0:1]
	v_xor_b32_e32 v8, 0x80000000, v109
	v_mov_b32_e32 v9, v108
	v_mov_b32_e32 v10, v146
	v_pk_fma_f32 v[2:3], v[8:9], s[48:49], v[2:3] op_sel_hi:[1,0,1] neg_lo:[0,0,1] neg_hi:[0,0,1]
	global_load_dword v8, v145, s[0:1]
	s_movk_i32 s0, 0x200
	s_cselect_b32 s4, s0, 0x400
	s_add_i32 s0, s4, s62
	s_ashr_i32 s1, s0, 31
	s_lshl_b32 s6, s4, 2
	s_add_u32 s4, s64, s6
	s_addc_u32 s5, s65, 0
	s_lshl_b64 s[0:1], s[0:1], 14
	v_min_i32_e32 v70, 0x1ffe, v10
	v_mov_b32_e32 v9, s6
	s_add_u32 s36, s26, s0
	v_ashrrev_i32_e32 v11, 31, v10
	v_ashrrev_i32_e32 v71, 31, v70
	global_load_dword v16, v9, s[64:65]
	global_load_dword v14, v151, s[4:5] offset:2048
	global_load_dword v17, v152, s[4:5]
	global_load_dword v12, v9, s[68:69]
	s_addc_u32 s37, s27, s1
	v_max_i32_e32 v9, 1, v10
	v_lshlrev_b64 v[82:83], 1, v[10:11]
	v_lshlrev_b64 v[84:85], 1, v[70:71]
	v_lshl_add_u64 v[26:27], s[36:37], 0, v[82:83]
	v_lshlrev_b32_e32 v9, 1, v9
	v_lshl_add_u64 v[70:71], s[36:37], 0, v[84:85]
	global_load_ushort v13, v[26:27], off
	s_add_u32 s72, s30, s0
	global_load_ushort v70, v[70:71], off offset:2
	s_addc_u32 s73, s31, s1
	global_load_ushort v15, v9, s[36:37] offset:-2
	v_cmp_lt_i32_e64 s[0:1], 0, v10
	v_cmp_gt_i32_e64 s[4:5], s88, v10
	v_pk_add_f32 v[2:3], v[106:107], v[2:3]
	v_cndmask_b32_e64 v81, 0, 1.0, s[0:1]
	v_cndmask_b32_e64 v86, 0, 1.0, s[4:5]
	v_add_u32_e32 v92, 0x200, v10
	v_cmp_lt_i32_e64 s[20:21], s33, v10
	v_cmp_gt_i32_e64 s[18:19], s92, v10
	v_add_u32_e32 v90, 0x400, v10
	v_cmp_lt_i32_e64 s[16:17], s81, v10
	v_cmp_gt_i32_e64 s[0:1], s38, v10
	v_add_u32_e32 v88, 0x600, v10
	v_cmp_lt_i32_e64 s[12:13], s93, v10
	v_cmp_gt_i32_e64 s[10:11], s3, v10
	v_cmp_lt_i32_e64 s[8:9], s50, v10
	v_cmp_gt_i32_e64 s[6:7], s90, v10
	v_cmp_lt_i32_e64 s[4:5], s39, v10
	v_cmp_gt_i32_e64 s[22:23], s51, v10
	s_waitcnt vmcnt(2)
	v_lshlrev_b32_e32 v13, 16, v13
	s_waitcnt vmcnt(1)
	v_lshlrev_b32_e32 v70, 16, v70
	v_mul_f32_e32 v70, v86, v70
	s_waitcnt vmcnt(0)
	v_lshlrev_b32_e32 v15, 16, v15
	v_mul_f32_e32 v15, v81, v15
	v_mul_f32_e32 v15, v16, v15
	v_fmac_f32_e32 v15, v14, v13
	v_fmac_f32_e32 v15, v17, v70
	v_lshl_add_u64 v[70:71], s[72:73], 0, v[82:83]
	v_lshl_add_u64 v[82:83], s[72:73], 0, v[84:85]
	v_add_f32_e32 v80, v12, v15
	global_load_ushort v13, v[70:71], off
	global_load_ushort v15, v[82:83], off offset:2
	v_add_u32_e32 v84, 0x800, v10
	global_load_ushort v9, v9, s[72:73] offset:-2
	v_add_u32_e32 v82, 0xa00, v10
	s_waitcnt vmcnt(2)
	v_lshlrev_b32_e32 v13, 16, v13
	s_waitcnt vmcnt(1)
	v_lshlrev_b32_e32 v15, 16, v15
	v_mul_f32_e32 v15, v86, v15
	s_waitcnt vmcnt(0)
	v_lshlrev_b32_e32 v9, 16, v9
	v_mul_f32_e32 v9, v81, v9
	v_mul_f32_e32 v9, v16, v9
	v_fmac_f32_e32 v9, v14, v13
	v_fmac_f32_e32 v9, v17, v15
	v_add_f32_e32 v86, v12, v9
	s_cbranch_vccnz .LBB0_912
	s_lshl_b64 s[0:1], s[66:67], 1
	s_add_u32 s4, s0, s30
	s_addc_u32 s5, s1, s31
	s_add_u32 s0, s0, s26
	s_addc_u32 s1, s1, s27
	s_add_u32 s18, s70, 0x800000
	s_addc_u32 s19, s71, 0
	v_lshlrev_b32_e32 v109, 1, v10
	global_load_ushort v9, v109, s[0:1]
	global_load_ushort v11, v109, s[4:5]
	global_load_ushort v13, v109, s[36:37] offset:1022
	global_load_ushort v15, v109, s[36:37] offset:1024
	global_load_ushort v81, v109, s[36:37] offset:1026
	global_load_ushort v83, v109, s[72:73] offset:1022
	global_load_ushort v85, v109, s[72:73] offset:1024
	global_load_ushort v87, v109, s[72:73] offset:1026
	global_load_ushort v89, v109, s[0:1] offset:1024
	global_load_ushort v91, v109, s[4:5] offset:1024
	global_load_ushort v93, v109, s[36:37] offset:2046
	global_load_ushort v94, v109, s[36:37] offset:2048
	global_load_ushort v95, v109, s[36:37] offset:2050
	global_load_ushort v96, v109, s[72:73] offset:2046
	global_load_ushort v97, v109, s[72:73] offset:2048
	global_load_ushort v98, v109, s[72:73] offset:2050
	global_load_ushort v99, v109, s[0:1] offset:2048
	global_load_ushort v100, v109, s[4:5] offset:2048
	global_load_ushort v101, v109, s[36:37] offset:3070
	global_load_ushort v102, v109, s[36:37] offset:3072
	global_load_ushort v103, v109, s[36:37] offset:3074
	global_load_ushort v104, v109, s[72:73] offset:3070
	global_load_ushort v105, v109, s[72:73] offset:3072
	global_load_ushort v106, v109, s[72:73] offset:3074
	global_load_ushort v107, v109, s[0:1] offset:3072
	global_load_ushort v108, v109, s[4:5] offset:3072
	s_waitcnt vmcnt(0)
	v_lshlrev_b32_e32 v26, 10, v10
	v_fma_f32 v27, v32, v8, v78
	v_mul_f32_e32 v70, v80, v27
	v_lshlrev_b32_e32 v9, 16, v9
	v_mul_f32_e32 v84, 0xbfb8aa3b, v9
	v_exp_f32_e32 v84, v84
	s_nop 0
	v_add_f32_e32 v84, 1.0, v84
	v_div_scale_f32 v71, s[74:75], v84, v84, v9
	v_rcp_f32_e32 v82, v71
	s_nop 0
	v_fma_f32 v92, -v71, v82, 1.0
	v_fmac_f32_e32 v82, v92, v82
	v_div_scale_f32 v88, vcc, v9, v84, v9
	v_mul_f32_e32 v90, v88, v82
	v_fma_f32 v92, -v71, v90, v88
	v_fmac_f32_e32 v90, v92, v82
	v_fma_f32 v71, -v71, v90, v88
	v_div_fmas_f32 v71, v71, v82, v90
	v_div_fixup_f32 v9, v71, v84, v9
	v_mul_f32_e32 v70, v70, v9
	v_cvt_pk_bf16_f32 v70, v70, s0
	global_store_short v26, v70, s[70:71]
	v_fma_f32 v27, v34, v8, v79
	v_mul_f32_e32 v70, v86, v27
	v_lshlrev_b32_e32 v11, 16, v11
	v_mul_f32_e32 v84, 0xbfb8aa3b, v11
	v_exp_f32_e32 v84, v84
	s_nop 0
	v_add_f32_e32 v84, 1.0, v84
	v_div_scale_f32 v71, s[74:75], v84, v84, v11
	v_rcp_f32_e32 v82, v71
	s_nop 0
	v_fma_f32 v92, -v71, v82, 1.0
	v_fmac_f32_e32 v82, v92, v82
	v_div_scale_f32 v88, vcc, v11, v84, v11
	v_mul_f32_e32 v90, v88, v82
	v_fma_f32 v92, -v71, v90, v88
	v_fmac_f32_e32 v90, v92, v82
	v_fma_f32 v71, -v71, v90, v88
	v_div_fmas_f32 v71, v71, v82, v90
	v_div_fixup_f32 v11, v71, v84, v11
	v_mul_f32_e32 v70, v70, v11
	v_cvt_pk_bf16_f32 v70, v70, s0
	global_store_short v26, v70, s[18:19]
	v_add_u32_e32 v26, 0x80000, v26
	v_lshlrev_b32_e32 v15, 16, v15
	v_lshlrev_b32_e32 v81, 16, v81
	v_lshlrev_b32_e32 v13, 16, v13
	v_mul_f32_e32 v13, v16, v13
	v_fmac_f32_e32 v13, v14, v15
	v_fmac_f32_e32 v13, v17, v81
	v_add_f32_e32 v13, v12, v13
	v_fma_f32 v27, v33, v8, v76
	v_mul_f32_e32 v70, v27, v13
	v_lshlrev_b32_e32 v89, 16, v89
	v_mul_f32_e32 v84, 0xbfb8aa3b, v89
	v_exp_f32_e32 v84, v84
	s_nop 0
	v_add_f32_e32 v84, 1.0, v84
	v_div_scale_f32 v71, s[74:75], v84, v84, v89
	v_rcp_f32_e32 v82, v71
	s_nop 0
	v_fma_f32 v92, -v71, v82, 1.0
	v_fmac_f32_e32 v82, v92, v82
	v_div_scale_f32 v88, vcc, v89, v84, v89
	v_mul_f32_e32 v90, v88, v82
	v_fma_f32 v92, -v71, v90, v88
	v_fmac_f32_e32 v90, v92, v82
	v_fma_f32 v71, -v71, v90, v88
	v_div_fmas_f32 v71, v71, v82, v90
	v_div_fixup_f32 v89, v71, v84, v89
	v_mul_f32_e32 v70, v70, v89
	v_cvt_pk_bf16_f32 v70, v70, s0
	global_store_short v26, v70, s[70:71]
	v_lshlrev_b32_e32 v85, 16, v85
	v_lshlrev_b32_e32 v87, 16, v87
	v_lshlrev_b32_e32 v83, 16, v83
	v_mul_f32_e32 v83, v16, v83
	v_fmac_f32_e32 v83, v14, v85
	v_fmac_f32_e32 v83, v17, v87
	v_add_f32_e32 v83, v12, v83
	v_fma_f32 v27, v35, v8, v77
	v_mul_f32_e32 v70, v27, v83
	v_lshlrev_b32_e32 v91, 16, v91
	v_mul_f32_e32 v84, 0xbfb8aa3b, v91
	v_exp_f32_e32 v84, v84
	s_nop 0
	v_add_f32_e32 v84, 1.0, v84
	v_div_scale_f32 v71, s[74:75], v84, v84, v91
	v_rcp_f32_e32 v82, v71
	s_nop 0
	v_fma_f32 v92, -v71, v82, 1.0
	v_fmac_f32_e32 v82, v92, v82
	v_div_scale_f32 v88, vcc, v91, v84, v91
	v_mul_f32_e32 v90, v88, v82
	v_fma_f32 v92, -v71, v90, v88
	v_fmac_f32_e32 v90, v92, v82
	v_fma_f32 v71, -v71, v90, v88
	v_div_fmas_f32 v71, v71, v82, v90
	v_div_fixup_f32 v91, v71, v84, v91
	v_mul_f32_e32 v70, v70, v91
	v_cvt_pk_bf16_f32 v70, v70, s0
	global_store_short v26, v70, s[18:19]
	v_add_u32_e32 v26, 0x80000, v26
	v_lshlrev_b32_e32 v94, 16, v94
	v_lshlrev_b32_e32 v95, 16, v95
	v_lshlrev_b32_e32 v93, 16, v93
	v_mul_f32_e32 v93, v16, v93
	v_fmac_f32_e32 v93, v14, v94
	v_fmac_f32_e32 v93, v17, v95
	v_add_f32_e32 v93, v12, v93
	v_fma_f32 v27, v37, v8, v72
	v_mul_f32_e32 v70, v27, v93
	v_lshlrev_b32_e32 v99, 16, v99
	v_mul_f32_e32 v84, 0xbfb8aa3b, v99
	v_exp_f32_e32 v84, v84
	s_nop 0
	v_add_f32_e32 v84, 1.0, v84
	v_div_scale_f32 v71, s[74:75], v84, v84, v99
	v_rcp_f32_e32 v82, v71
	s_nop 0
	v_fma_f32 v92, -v71, v82, 1.0
	v_fmac_f32_e32 v82, v92, v82
	v_div_scale_f32 v88, vcc, v99, v84, v99
	v_mul_f32_e32 v90, v88, v82
	v_fma_f32 v92, -v71, v90, v88
	v_fmac_f32_e32 v90, v92, v82
	v_fma_f32 v71, -v71, v90, v88
	v_div_fmas_f32 v71, v71, v82, v90
	v_div_fixup_f32 v99, v71, v84, v99
	v_mul_f32_e32 v70, v70, v99
	v_cvt_pk_bf16_f32 v70, v70, s0
	global_store_short v26, v70, s[70:71]
	v_lshlrev_b32_e32 v97, 16, v97
	v_lshlrev_b32_e32 v98, 16, v98
	v_lshlrev_b32_e32 v96, 16, v96
	v_mul_f32_e32 v96, v16, v96
	v_fmac_f32_e32 v96, v14, v97
	v_fmac_f32_e32 v96, v17, v98
	v_add_f32_e32 v96, v12, v96
	v_fma_f32 v27, v31, v8, v73
	v_mul_f32_e32 v70, v27, v96
	v_lshlrev_b32_e32 v100, 16, v100
	v_mul_f32_e32 v84, 0xbfb8aa3b, v100
	v_exp_f32_e32 v84, v84
	s_nop 0
	v_add_f32_e32 v84, 1.0, v84
	v_div_scale_f32 v71, s[74:75], v84, v84, v100
	v_rcp_f32_e32 v82, v71
	s_nop 0
	v_fma_f32 v92, -v71, v82, 1.0
	v_fmac_f32_e32 v82, v92, v82
	v_div_scale_f32 v88, vcc, v100, v84, v100
	v_mul_f32_e32 v90, v88, v82
	v_fma_f32 v92, -v71, v90, v88
	v_fmac_f32_e32 v90, v92, v82
	v_fma_f32 v71, -v71, v90, v88
	v_div_fmas_f32 v71, v71, v82, v90
	v_div_fixup_f32 v100, v71, v84, v100
	v_mul_f32_e32 v70, v70, v100
	v_cvt_pk_bf16_f32 v70, v70, s0
	global_store_short v26, v70, s[18:19]
	v_add_u32_e32 v26, 0x80000, v26
	v_lshlrev_b32_e32 v102, 16, v102
	v_lshlrev_b32_e32 v103, 16, v103
	v_lshlrev_b32_e32 v101, 16, v101
	v_mul_f32_e32 v101, v16, v101
	v_fmac_f32_e32 v101, v14, v102
	v_fmac_f32_e32 v101, v17, v103
	v_add_f32_e32 v101, v12, v101
	v_fma_f32 v27, v36, v8, v74
	v_mul_f32_e32 v70, v27, v101
	v_lshlrev_b32_e32 v107, 16, v107
	v_mul_f32_e32 v84, 0xbfb8aa3b, v107
	v_exp_f32_e32 v84, v84
	s_nop 0
	v_add_f32_e32 v84, 1.0, v84
	v_div_scale_f32 v71, s[74:75], v84, v84, v107
	v_rcp_f32_e32 v82, v71
	s_nop 0
	v_fma_f32 v92, -v71, v82, 1.0
	v_fmac_f32_e32 v82, v92, v82
	v_div_scale_f32 v88, vcc, v107, v84, v107
	v_mul_f32_e32 v90, v88, v82
	v_fma_f32 v92, -v71, v90, v88
	v_fmac_f32_e32 v90, v92, v82
	v_fma_f32 v71, -v71, v90, v88
	v_div_fmas_f32 v71, v71, v82, v90
	v_div_fixup_f32 v107, v71, v84, v107
	v_mul_f32_e32 v70, v70, v107
	v_cvt_pk_bf16_f32 v70, v70, s0
	global_store_short v26, v70, s[70:71]
	v_lshlrev_b32_e32 v105, 16, v105
	v_lshlrev_b32_e32 v106, 16, v106
	v_lshlrev_b32_e32 v104, 16, v104
	v_mul_f32_e32 v104, v16, v104
	v_fmac_f32_e32 v104, v14, v105
	v_fmac_f32_e32 v104, v17, v106
	v_add_f32_e32 v104, v12, v104
	v_fma_f32 v27, v30, v8, v75
	v_mul_f32_e32 v70, v27, v104
	v_lshlrev_b32_e32 v108, 16, v108
	v_mul_f32_e32 v84, 0xbfb8aa3b, v108
	v_exp_f32_e32 v84, v84
	s_nop 0
	v_add_f32_e32 v84, 1.0, v84
	v_div_scale_f32 v71, s[74:75], v84, v84, v108
	v_rcp_f32_e32 v82, v71
	s_nop 0
	v_fma_f32 v92, -v71, v82, 1.0
	v_fmac_f32_e32 v82, v92, v82
	v_div_scale_f32 v88, vcc, v108, v84, v108
	v_mul_f32_e32 v90, v88, v82
	v_fma_f32 v92, -v71, v90, v88
	v_fmac_f32_e32 v90, v92, v82
	v_fma_f32 v71, -v71, v90, v88
	v_div_fmas_f32 v71, v71, v82, v90
	v_div_fixup_f32 v108, v71, v84, v108
	v_mul_f32_e32 v70, v70, v108
	v_cvt_pk_bf16_f32 v70, v70, s0
	global_store_short v26, v70, s[18:19]
	v_add_u32_e32 v109, 0x1000, v109
	global_load_ushort v9, v109, s[36:37] offset:-2
	global_load_ushort v11, v109, s[36:37]
	global_load_ushort v13, v109, s[36:37] offset:2
	global_load_ushort v15, v109, s[72:73] offset:-2
	global_load_ushort v81, v109, s[72:73]
	global_load_ushort v83, v109, s[72:73] offset:2
	global_load_ushort v85, v109, s[0:1]
	global_load_ushort v87, v109, s[4:5]
	global_load_ushort v89, v109, s[36:37] offset:1022
	global_load_ushort v91, v109, s[36:37] offset:1024
	global_load_ushort v93, v109, s[36:37] offset:1026
	global_load_ushort v94, v109, s[72:73] offset:1022
	global_load_ushort v95, v109, s[72:73] offset:1024
	global_load_ushort v96, v109, s[72:73] offset:1026
	global_load_ushort v97, v109, s[0:1] offset:1024
	global_load_ushort v98, v109, s[4:5] offset:1024
	global_load_ushort v99, v109, s[36:37] offset:2046
	global_load_ushort v100, v109, s[36:37] offset:2048
	global_load_ushort v101, v109, s[36:37] offset:2050
	global_load_ushort v102, v109, s[72:73] offset:2046
	global_load_ushort v103, v109, s[72:73] offset:2048
	global_load_ushort v104, v109, s[72:73] offset:2050
	global_load_ushort v105, v109, s[0:1] offset:2048
	global_load_ushort v106, v109, s[4:5] offset:2048
	global_load_ushort v107, v109, s[36:37] offset:3070
	global_load_ushort v108, v109, s[36:37] offset:3072
	global_load_ushort v32, v109, s[36:37] offset:3074
	global_load_ushort v78, v109, s[72:73] offset:3070
	global_load_ushort v34, v109, s[72:73] offset:3072
	global_load_ushort v79, v109, s[72:73] offset:3074
	global_load_ushort v33, v109, s[0:1] offset:3072
	global_load_ushort v76, v109, s[4:5] offset:3072
	s_waitcnt vmcnt(0)
	v_add_u32_e32 v26, 0x80000, v26
	v_lshlrev_b32_e32 v11, 16, v11
	v_lshlrev_b32_e32 v13, 16, v13
	v_lshlrev_b32_e32 v9, 16, v9
	v_mul_f32_e32 v9, v16, v9
	v_fmac_f32_e32 v9, v14, v11
	v_fmac_f32_e32 v9, v17, v13
	v_add_f32_e32 v9, v12, v9
	v_fma_f32 v27, v39, v8, v66
	v_mul_f32_e32 v70, v27, v9
	v_lshlrev_b32_e32 v85, 16, v85
	v_mul_f32_e32 v84, 0xbfb8aa3b, v85
	v_exp_f32_e32 v84, v84
	s_nop 0
	v_add_f32_e32 v84, 1.0, v84
	v_div_scale_f32 v71, s[74:75], v84, v84, v85
	v_rcp_f32_e32 v82, v71
	s_nop 0
	v_fma_f32 v92, -v71, v82, 1.0
	v_fmac_f32_e32 v82, v92, v82
	v_div_scale_f32 v88, vcc, v85, v84, v85
	v_mul_f32_e32 v90, v88, v82
	v_fma_f32 v92, -v71, v90, v88
	v_fmac_f32_e32 v90, v92, v82
	v_fma_f32 v71, -v71, v90, v88
	v_div_fmas_f32 v71, v71, v82, v90
	v_div_fixup_f32 v85, v71, v84, v85
	v_mul_f32_e32 v70, v70, v85
	v_cvt_pk_bf16_f32 v70, v70, s0
	global_store_short v26, v70, s[70:71]
	v_lshlrev_b32_e32 v81, 16, v81
	v_lshlrev_b32_e32 v83, 16, v83
	v_lshlrev_b32_e32 v15, 16, v15
	v_mul_f32_e32 v15, v16, v15
	v_fmac_f32_e32 v15, v14, v81
	v_fmac_f32_e32 v15, v17, v83
	v_add_f32_e32 v15, v12, v15
	v_fma_f32 v27, v41, v8, v67
	v_mul_f32_e32 v70, v27, v15
	v_lshlrev_b32_e32 v87, 16, v87
	v_mul_f32_e32 v84, 0xbfb8aa3b, v87
	v_exp_f32_e32 v84, v84
	s_nop 0
	v_add_f32_e32 v84, 1.0, v84
	v_div_scale_f32 v71, s[74:75], v84, v84, v87
	v_rcp_f32_e32 v82, v71
	s_nop 0
	v_fma_f32 v92, -v71, v82, 1.0
	v_fmac_f32_e32 v82, v92, v82
	v_div_scale_f32 v88, vcc, v87, v84, v87
	v_mul_f32_e32 v90, v88, v82
	v_fma_f32 v92, -v71, v90, v88
	v_fmac_f32_e32 v90, v92, v82
	v_fma_f32 v71, -v71, v90, v88
	v_div_fmas_f32 v71, v71, v82, v90
	v_div_fixup_f32 v87, v71, v84, v87
	v_mul_f32_e32 v70, v70, v87
	v_cvt_pk_bf16_f32 v70, v70, s0
	global_store_short v26, v70, s[18:19]
	v_add_u32_e32 v26, 0x80000, v26
	v_lshlrev_b32_e32 v91, 16, v91
	v_lshlrev_b32_e32 v93, 16, v93
	v_lshlrev_b32_e32 v89, 16, v89
	v_mul_f32_e32 v89, v16, v89
	v_fmac_f32_e32 v89, v14, v91
	v_fmac_f32_e32 v89, v17, v93
	v_add_f32_e32 v89, v12, v89
	v_fma_f32 v27, v38, v8, v68
	v_mul_f32_e32 v70, v27, v89
	v_lshlrev_b32_e32 v97, 16, v97
	v_mul_f32_e32 v84, 0xbfb8aa3b, v97
	v_exp_f32_e32 v84, v84
	s_nop 0
	v_add_f32_e32 v84, 1.0, v84
	v_div_scale_f32 v71, s[74:75], v84, v84, v97
	v_rcp_f32_e32 v82, v71
	s_nop 0
	v_fma_f32 v92, -v71, v82, 1.0
	v_fmac_f32_e32 v82, v92, v82
	v_div_scale_f32 v88, vcc, v97, v84, v97
	v_mul_f32_e32 v90, v88, v82
	v_fma_f32 v92, -v71, v90, v88
	v_fmac_f32_e32 v90, v92, v82
	v_fma_f32 v71, -v71, v90, v88
	v_div_fmas_f32 v71, v71, v82, v90
	v_div_fixup_f32 v97, v71, v84, v97
	v_mul_f32_e32 v70, v70, v97
	v_cvt_pk_bf16_f32 v70, v70, s0
	global_store_short v26, v70, s[70:71]
	v_lshlrev_b32_e32 v95, 16, v95
	v_lshlrev_b32_e32 v96, 16, v96
	v_lshlrev_b32_e32 v94, 16, v94
	v_mul_f32_e32 v94, v16, v94
	v_fmac_f32_e32 v94, v14, v95
	v_fmac_f32_e32 v94, v17, v96
	v_add_f32_e32 v94, v12, v94
	v_fma_f32 v27, v40, v8, v69
	v_mul_f32_e32 v70, v27, v94
	v_lshlrev_b32_e32 v98, 16, v98
	v_mul_f32_e32 v84, 0xbfb8aa3b, v98
	v_exp_f32_e32 v84, v84
	s_nop 0
	v_add_f32_e32 v84, 1.0, v84
	v_div_scale_f32 v71, s[74:75], v84, v84, v98
	v_rcp_f32_e32 v82, v71
	s_nop 0
	v_fma_f32 v92, -v71, v82, 1.0
	v_fmac_f32_e32 v82, v92, v82
	v_div_scale_f32 v88, vcc, v98, v84, v98
	v_mul_f32_e32 v90, v88, v82
	v_fma_f32 v92, -v71, v90, v88
	v_fmac_f32_e32 v90, v92, v82
	v_fma_f32 v71, -v71, v90, v88
	v_div_fmas_f32 v71, v71, v82, v90
	v_div_fixup_f32 v98, v71, v84, v98
	v_mul_f32_e32 v70, v70, v98
	v_cvt_pk_bf16_f32 v70, v70, s0
	global_store_short v26, v70, s[18:19]
	v_add_u32_e32 v26, 0x80000, v26
	v_lshlrev_b32_e32 v100, 16, v100
	v_lshlrev_b32_e32 v101, 16, v101
	v_lshlrev_b32_e32 v99, 16, v99
	v_mul_f32_e32 v99, v16, v99
	v_fmac_f32_e32 v99, v14, v100
	v_fmac_f32_e32 v99, v17, v101
	v_add_f32_e32 v99, v12, v99
	v_fma_f32 v27, v43, v8, v62
	v_mul_f32_e32 v70, v27, v99
	v_lshlrev_b32_e32 v105, 16, v105
	v_mul_f32_e32 v84, 0xbfb8aa3b, v105
	v_exp_f32_e32 v84, v84
	s_nop 0
	v_add_f32_e32 v84, 1.0, v84
	v_div_scale_f32 v71, s[74:75], v84, v84, v105
	v_rcp_f32_e32 v82, v71
	s_nop 0
	v_fma_f32 v92, -v71, v82, 1.0
	v_fmac_f32_e32 v82, v92, v82
	v_div_scale_f32 v88, vcc, v105, v84, v105
	v_mul_f32_e32 v90, v88, v82
	v_fma_f32 v92, -v71, v90, v88
	v_fmac_f32_e32 v90, v92, v82
	v_fma_f32 v71, -v71, v90, v88
	v_div_fmas_f32 v71, v71, v82, v90
	v_div_fixup_f32 v105, v71, v84, v105
	v_mul_f32_e32 v70, v70, v105
	v_cvt_pk_bf16_f32 v70, v70, s0
	global_store_short v26, v70, s[70:71]
	v_lshlrev_b32_e32 v103, 16, v103
	v_lshlrev_b32_e32 v104, 16, v104
	v_lshlrev_b32_e32 v102, 16, v102
	v_mul_f32_e32 v102, v16, v102
	v_fmac_f32_e32 v102, v14, v103
	v_fmac_f32_e32 v102, v17, v104
	v_add_f32_e32 v102, v12, v102
	v_fma_f32 v27, v45, v8, v63
	v_mul_f32_e32 v70, v27, v102
	v_lshlrev_b32_e32 v106, 16, v106
	v_mul_f32_e32 v84, 0xbfb8aa3b, v106
	v_exp_f32_e32 v84, v84
	s_nop 0
	v_add_f32_e32 v84, 1.0, v84
	v_div_scale_f32 v71, s[74:75], v84, v84, v106
	v_rcp_f32_e32 v82, v71
	s_nop 0
	v_fma_f32 v92, -v71, v82, 1.0
	v_fmac_f32_e32 v82, v92, v82
	v_div_scale_f32 v88, vcc, v106, v84, v106
	v_mul_f32_e32 v90, v88, v82
	v_fma_f32 v92, -v71, v90, v88
	v_fmac_f32_e32 v90, v92, v82
	v_fma_f32 v71, -v71, v90, v88
	v_div_fmas_f32 v71, v71, v82, v90
	v_div_fixup_f32 v106, v71, v84, v106
	v_mul_f32_e32 v70, v70, v106
	v_cvt_pk_bf16_f32 v70, v70, s0
	global_store_short v26, v70, s[18:19]
	v_add_u32_e32 v26, 0x80000, v26
	v_lshlrev_b32_e32 v108, 16, v108
	v_lshlrev_b32_e32 v32, 16, v32
	v_lshlrev_b32_e32 v107, 16, v107
	v_mul_f32_e32 v107, v16, v107
	v_fmac_f32_e32 v107, v14, v108
	v_fmac_f32_e32 v107, v17, v32
	v_add_f32_e32 v107, v12, v107
	v_fma_f32 v27, v42, v8, v64
	v_mul_f32_e32 v70, v27, v107
	v_lshlrev_b32_e32 v33, 16, v33
	v_mul_f32_e32 v84, 0xbfb8aa3b, v33
	v_exp_f32_e32 v84, v84
	s_nop 0
	v_add_f32_e32 v84, 1.0, v84
	v_div_scale_f32 v71, s[74:75], v84, v84, v33
	v_rcp_f32_e32 v82, v71
	s_nop 0
	v_fma_f32 v92, -v71, v82, 1.0
	v_fmac_f32_e32 v82, v92, v82
	v_div_scale_f32 v88, vcc, v33, v84, v33
	v_mul_f32_e32 v90, v88, v82
	v_fma_f32 v92, -v71, v90, v88
	v_fmac_f32_e32 v90, v92, v82
	v_fma_f32 v71, -v71, v90, v88
	v_div_fmas_f32 v71, v71, v82, v90
	v_div_fixup_f32 v33, v71, v84, v33
	v_mul_f32_e32 v70, v70, v33
	v_cvt_pk_bf16_f32 v70, v70, s0
	global_store_short v26, v70, s[70:71]
	v_lshlrev_b32_e32 v34, 16, v34
	v_lshlrev_b32_e32 v79, 16, v79
	v_lshlrev_b32_e32 v78, 16, v78
	v_mul_f32_e32 v78, v16, v78
	v_fmac_f32_e32 v78, v14, v34
	v_fmac_f32_e32 v78, v17, v79
	v_add_f32_e32 v78, v12, v78
	v_fma_f32 v27, v44, v8, v65
	v_mul_f32_e32 v70, v27, v78
	v_lshlrev_b32_e32 v76, 16, v76
	v_mul_f32_e32 v84, 0xbfb8aa3b, v76
	v_exp_f32_e32 v84, v84
	s_nop 0
	v_add_f32_e32 v84, 1.0, v84
	v_div_scale_f32 v71, s[74:75], v84, v84, v76
	v_rcp_f32_e32 v82, v71
	s_nop 0
	v_fma_f32 v92, -v71, v82, 1.0
	v_fmac_f32_e32 v82, v92, v82
	v_div_scale_f32 v88, vcc, v76, v84, v76
	v_mul_f32_e32 v90, v88, v82
	v_fma_f32 v92, -v71, v90, v88
	v_fmac_f32_e32 v90, v92, v82
	v_fma_f32 v71, -v71, v90, v88
	v_div_fmas_f32 v71, v71, v82, v90
	v_div_fixup_f32 v76, v71, v84, v76
	v_mul_f32_e32 v70, v70, v76
	v_cvt_pk_bf16_f32 v70, v70, s0
	global_store_short v26, v70, s[18:19]
	v_add_u32_e32 v109, 0x1000, v109
	global_load_ushort v9, v109, s[36:37] offset:-2
	global_load_ushort v11, v109, s[36:37]
	global_load_ushort v13, v109, s[36:37] offset:2
	global_load_ushort v15, v109, s[72:73] offset:-2
	global_load_ushort v81, v109, s[72:73]
	global_load_ushort v83, v109, s[72:73] offset:2
	global_load_ushort v85, v109, s[0:1]
	global_load_ushort v87, v109, s[4:5]
	global_load_ushort v89, v109, s[36:37] offset:1022
	global_load_ushort v91, v109, s[36:37] offset:1024
	global_load_ushort v93, v109, s[36:37] offset:1026
	global_load_ushort v94, v109, s[72:73] offset:1022
	global_load_ushort v95, v109, s[72:73] offset:1024
	global_load_ushort v96, v109, s[72:73] offset:1026
	global_load_ushort v97, v109, s[0:1] offset:1024
	global_load_ushort v98, v109, s[4:5] offset:1024
	global_load_ushort v99, v109, s[36:37] offset:2046
	global_load_ushort v100, v109, s[36:37] offset:2048
	global_load_ushort v101, v109, s[36:37] offset:2050
	global_load_ushort v102, v109, s[72:73] offset:2046
	global_load_ushort v103, v109, s[72:73] offset:2048
	global_load_ushort v104, v109, s[72:73] offset:2050
	global_load_ushort v105, v109, s[0:1] offset:2048
	global_load_ushort v106, v109, s[4:5] offset:2048
	global_load_ushort v107, v109, s[36:37] offset:3070
	global_load_ushort v108, v109, s[36:37] offset:3072
	global_load_ushort v32, v109, s[36:37] offset:3074
	global_load_ushort v78, v109, s[72:73] offset:3070
	global_load_ushort v34, v109, s[72:73] offset:3072
	global_load_ushort v79, v109, s[72:73] offset:3074
	global_load_ushort v33, v109, s[0:1] offset:3072
	global_load_ushort v76, v109, s[4:5] offset:3072
	s_waitcnt vmcnt(0)
	v_add_u32_e32 v26, 0x80000, v26
	v_lshlrev_b32_e32 v11, 16, v11
	v_lshlrev_b32_e32 v13, 16, v13
	v_lshlrev_b32_e32 v9, 16, v9
	v_mul_f32_e32 v9, v16, v9
	v_fmac_f32_e32 v9, v14, v11
	v_fmac_f32_e32 v9, v17, v13
	v_add_f32_e32 v9, v12, v9
	v_fma_f32 v27, v47, v8, v22
	v_mul_f32_e32 v70, v27, v9
	v_lshlrev_b32_e32 v85, 16, v85
	v_mul_f32_e32 v84, 0xbfb8aa3b, v85
	v_exp_f32_e32 v84, v84
	s_nop 0
	v_add_f32_e32 v84, 1.0, v84
	v_div_scale_f32 v71, s[74:75], v84, v84, v85
	v_rcp_f32_e32 v82, v71
	s_nop 0
	v_fma_f32 v92, -v71, v82, 1.0
	v_fmac_f32_e32 v82, v92, v82
	v_div_scale_f32 v88, vcc, v85, v84, v85
	v_mul_f32_e32 v90, v88, v82
	v_fma_f32 v92, -v71, v90, v88
	v_fmac_f32_e32 v90, v92, v82
	v_fma_f32 v71, -v71, v90, v88
	v_div_fmas_f32 v71, v71, v82, v90
	v_div_fixup_f32 v85, v71, v84, v85
	v_mul_f32_e32 v70, v70, v85
	v_cvt_pk_bf16_f32 v70, v70, s0
	global_store_short v26, v70, s[70:71]
	v_lshlrev_b32_e32 v81, 16, v81
	v_lshlrev_b32_e32 v83, 16, v83
	v_lshlrev_b32_e32 v15, 16, v15
	v_mul_f32_e32 v15, v16, v15
	v_fmac_f32_e32 v15, v14, v81
	v_fmac_f32_e32 v15, v17, v83
	v_add_f32_e32 v15, v12, v15
	v_fma_f32 v27, v49, v8, v23
	v_mul_f32_e32 v70, v27, v15
	v_lshlrev_b32_e32 v87, 16, v87
	v_mul_f32_e32 v84, 0xbfb8aa3b, v87
	v_exp_f32_e32 v84, v84
	s_nop 0
	v_add_f32_e32 v84, 1.0, v84
	v_div_scale_f32 v71, s[74:75], v84, v84, v87
	v_rcp_f32_e32 v82, v71
	s_nop 0
	v_fma_f32 v92, -v71, v82, 1.0
	v_fmac_f32_e32 v82, v92, v82
	v_div_scale_f32 v88, vcc, v87, v84, v87
	v_mul_f32_e32 v90, v88, v82
	v_fma_f32 v92, -v71, v90, v88
	v_fmac_f32_e32 v90, v92, v82
	v_fma_f32 v71, -v71, v90, v88
	v_div_fmas_f32 v71, v71, v82, v90
	v_div_fixup_f32 v87, v71, v84, v87
	v_mul_f32_e32 v70, v70, v87
	v_cvt_pk_bf16_f32 v70, v70, s0
	global_store_short v26, v70, s[18:19]
	v_add_u32_e32 v26, 0x80000, v26
	v_lshlrev_b32_e32 v91, 16, v91
	v_lshlrev_b32_e32 v93, 16, v93
	v_lshlrev_b32_e32 v89, 16, v89
	v_mul_f32_e32 v89, v16, v89
	v_fmac_f32_e32 v89, v14, v91
	v_fmac_f32_e32 v89, v17, v93
	v_add_f32_e32 v89, v12, v89
	v_fma_f32 v27, v46, v8, v24
	v_mul_f32_e32 v70, v27, v89
	v_lshlrev_b32_e32 v97, 16, v97
	v_mul_f32_e32 v84, 0xbfb8aa3b, v97
	v_exp_f32_e32 v84, v84
	s_nop 0
	v_add_f32_e32 v84, 1.0, v84
	v_div_scale_f32 v71, s[74:75], v84, v84, v97
	v_rcp_f32_e32 v82, v71
	s_nop 0
	v_fma_f32 v92, -v71, v82, 1.0
	v_fmac_f32_e32 v82, v92, v82
	v_div_scale_f32 v88, vcc, v97, v84, v97
	v_mul_f32_e32 v90, v88, v82
	v_fma_f32 v92, -v71, v90, v88
	v_fmac_f32_e32 v90, v92, v82
	v_fma_f32 v71, -v71, v90, v88
	v_div_fmas_f32 v71, v71, v82, v90
	v_div_fixup_f32 v97, v71, v84, v97
	v_mul_f32_e32 v70, v70, v97
	v_cvt_pk_bf16_f32 v70, v70, s0
	global_store_short v26, v70, s[70:71]
	v_lshlrev_b32_e32 v95, 16, v95
	v_lshlrev_b32_e32 v96, 16, v96
	v_lshlrev_b32_e32 v94, 16, v94
	v_mul_f32_e32 v94, v16, v94
	v_fmac_f32_e32 v94, v14, v95
	v_fmac_f32_e32 v94, v17, v96
	v_add_f32_e32 v94, v12, v94
	v_fma_f32 v27, v48, v8, v25
	v_mul_f32_e32 v70, v27, v94
	v_lshlrev_b32_e32 v98, 16, v98
	v_mul_f32_e32 v84, 0xbfb8aa3b, v98
	v_exp_f32_e32 v84, v84
	s_nop 0
	v_add_f32_e32 v84, 1.0, v84
	v_div_scale_f32 v71, s[74:75], v84, v84, v98
	v_rcp_f32_e32 v82, v71
	s_nop 0
	v_fma_f32 v92, -v71, v82, 1.0
	v_fmac_f32_e32 v82, v92, v82
	v_div_scale_f32 v88, vcc, v98, v84, v98
	v_mul_f32_e32 v90, v88, v82
	v_fma_f32 v92, -v71, v90, v88
	v_fmac_f32_e32 v90, v92, v82
	v_fma_f32 v71, -v71, v90, v88
	v_div_fmas_f32 v71, v71, v82, v90
	v_div_fixup_f32 v98, v71, v84, v98
	v_mul_f32_e32 v70, v70, v98
	v_cvt_pk_bf16_f32 v70, v70, s0
	global_store_short v26, v70, s[18:19]
	v_add_u32_e32 v26, 0x80000, v26
	v_lshlrev_b32_e32 v100, 16, v100
	v_lshlrev_b32_e32 v101, 16, v101
	v_lshlrev_b32_e32 v99, 16, v99
	v_mul_f32_e32 v99, v16, v99
	v_fmac_f32_e32 v99, v14, v100
	v_fmac_f32_e32 v99, v17, v101
	v_add_f32_e32 v99, v12, v99
	v_fma_f32 v27, v51, v8, v18
	v_mul_f32_e32 v70, v27, v99
	v_lshlrev_b32_e32 v105, 16, v105
	v_mul_f32_e32 v84, 0xbfb8aa3b, v105
	v_exp_f32_e32 v84, v84
	s_nop 0
	v_add_f32_e32 v84, 1.0, v84
	v_div_scale_f32 v71, s[74:75], v84, v84, v105
	v_rcp_f32_e32 v82, v71
	s_nop 0
	v_fma_f32 v92, -v71, v82, 1.0
	v_fmac_f32_e32 v82, v92, v82
	v_div_scale_f32 v88, vcc, v105, v84, v105
	v_mul_f32_e32 v90, v88, v82
	v_fma_f32 v92, -v71, v90, v88
	v_fmac_f32_e32 v90, v92, v82
	v_fma_f32 v71, -v71, v90, v88
	v_div_fmas_f32 v71, v71, v82, v90
	v_div_fixup_f32 v105, v71, v84, v105
	v_mul_f32_e32 v70, v70, v105
	v_cvt_pk_bf16_f32 v70, v70, s0
	global_store_short v26, v70, s[70:71]
	v_lshlrev_b32_e32 v103, 16, v103
	v_lshlrev_b32_e32 v104, 16, v104
	v_lshlrev_b32_e32 v102, 16, v102
	v_mul_f32_e32 v102, v16, v102
	v_fmac_f32_e32 v102, v14, v103
	v_fmac_f32_e32 v102, v17, v104
	v_add_f32_e32 v102, v12, v102
	v_fma_f32 v27, v53, v8, v19
	v_mul_f32_e32 v70, v27, v102
	v_lshlrev_b32_e32 v106, 16, v106
	v_mul_f32_e32 v84, 0xbfb8aa3b, v106
	v_exp_f32_e32 v84, v84
	s_nop 0
	v_add_f32_e32 v84, 1.0, v84
	v_div_scale_f32 v71, s[74:75], v84, v84, v106
	v_rcp_f32_e32 v82, v71
	s_nop 0
	v_fma_f32 v92, -v71, v82, 1.0
	v_fmac_f32_e32 v82, v92, v82
	v_div_scale_f32 v88, vcc, v106, v84, v106
	v_mul_f32_e32 v90, v88, v82
	v_fma_f32 v92, -v71, v90, v88
	v_fmac_f32_e32 v90, v92, v82
	v_fma_f32 v71, -v71, v90, v88
	v_div_fmas_f32 v71, v71, v82, v90
	v_div_fixup_f32 v106, v71, v84, v106
	v_mul_f32_e32 v70, v70, v106
	v_cvt_pk_bf16_f32 v70, v70, s0
	global_store_short v26, v70, s[18:19]
	v_add_u32_e32 v26, 0x80000, v26
	v_lshlrev_b32_e32 v108, 16, v108
	v_lshlrev_b32_e32 v32, 16, v32
	v_lshlrev_b32_e32 v107, 16, v107
	v_mul_f32_e32 v107, v16, v107
	v_fmac_f32_e32 v107, v14, v108
	v_fmac_f32_e32 v107, v17, v32
	v_add_f32_e32 v107, v12, v107
	v_fma_f32 v27, v50, v8, v20
	v_mul_f32_e32 v70, v27, v107
	v_lshlrev_b32_e32 v33, 16, v33
	v_mul_f32_e32 v84, 0xbfb8aa3b, v33
	v_exp_f32_e32 v84, v84
	s_nop 0
	v_add_f32_e32 v84, 1.0, v84
	v_div_scale_f32 v71, s[74:75], v84, v84, v33
	v_rcp_f32_e32 v82, v71
	s_nop 0
	v_fma_f32 v92, -v71, v82, 1.0
	v_fmac_f32_e32 v82, v92, v82
	v_div_scale_f32 v88, vcc, v33, v84, v33
	v_mul_f32_e32 v90, v88, v82
	v_fma_f32 v92, -v71, v90, v88
	v_fmac_f32_e32 v90, v92, v82
	v_fma_f32 v71, -v71, v90, v88
	v_div_fmas_f32 v71, v71, v82, v90
	v_div_fixup_f32 v33, v71, v84, v33
	v_mul_f32_e32 v70, v70, v33
	v_cvt_pk_bf16_f32 v70, v70, s0
	global_store_short v26, v70, s[70:71]
	v_lshlrev_b32_e32 v34, 16, v34
	v_lshlrev_b32_e32 v79, 16, v79
	v_lshlrev_b32_e32 v78, 16, v78
	v_mul_f32_e32 v78, v16, v78
	v_fmac_f32_e32 v78, v14, v34
	v_fmac_f32_e32 v78, v17, v79
	v_add_f32_e32 v78, v12, v78
	v_fma_f32 v27, v52, v8, v21
	v_mul_f32_e32 v70, v27, v78
	v_lshlrev_b32_e32 v76, 16, v76
	v_mul_f32_e32 v84, 0xbfb8aa3b, v76
	v_exp_f32_e32 v84, v84
	s_nop 0
	v_add_f32_e32 v84, 1.0, v84
	v_div_scale_f32 v71, s[74:75], v84, v84, v76
	v_rcp_f32_e32 v82, v71
	s_nop 0
	v_fma_f32 v92, -v71, v82, 1.0
	v_fmac_f32_e32 v82, v92, v82
	v_div_scale_f32 v88, vcc, v76, v84, v76
	v_mul_f32_e32 v90, v88, v82
	v_fma_f32 v92, -v71, v90, v88
	v_fmac_f32_e32 v90, v92, v82
	v_fma_f32 v71, -v71, v90, v88
	v_div_fmas_f32 v71, v71, v82, v90
	v_div_fixup_f32 v76, v71, v84, v76
	v_mul_f32_e32 v70, v70, v76
	v_cvt_pk_bf16_f32 v70, v70, s0
	global_store_short v26, v70, s[18:19]
	v_add_u32_e32 v52, 0x1e00, v10
	v_cmp_gt_i32_e32 vcc, 0x1fff, v52
	v_min_i32_e32 v52, 0x1ffe, v52
	v_lshlrev_b32_e32 v52, 1, v52
	s_nop 0
	v_cndmask_b32_e64 v21, 0, 1.0, vcc
	v_add_u32_e32 v109, 0x1000, v109
	global_load_ushort v9, v109, s[36:37] offset:-2
	global_load_ushort v11, v109, s[36:37]
	global_load_ushort v13, v109, s[36:37] offset:2
	global_load_ushort v15, v109, s[72:73] offset:-2
	global_load_ushort v81, v109, s[72:73]
	global_load_ushort v83, v109, s[72:73] offset:2
	global_load_ushort v85, v109, s[0:1]
	global_load_ushort v87, v109, s[4:5]
	global_load_ushort v89, v109, s[36:37] offset:1022
	global_load_ushort v91, v109, s[36:37] offset:1024
	global_load_ushort v93, v109, s[36:37] offset:1026
	global_load_ushort v94, v109, s[72:73] offset:1022
	global_load_ushort v95, v109, s[72:73] offset:1024
	global_load_ushort v96, v109, s[72:73] offset:1026
	global_load_ushort v97, v109, s[0:1] offset:1024
	global_load_ushort v98, v109, s[4:5] offset:1024
	global_load_ushort v99, v109, s[36:37] offset:2046
	global_load_ushort v100, v109, s[36:37] offset:2048
	global_load_ushort v101, v109, s[36:37] offset:2050
	global_load_ushort v102, v109, s[72:73] offset:2046
	global_load_ushort v103, v109, s[72:73] offset:2048
	global_load_ushort v104, v109, s[72:73] offset:2050
	global_load_ushort v105, v109, s[0:1] offset:2048
	global_load_ushort v106, v109, s[4:5] offset:2048
	global_load_ushort v107, v109, s[36:37] offset:3070
	global_load_ushort v108, v109, s[36:37] offset:3072
	global_load_ushort v32, v52, s[36:37] offset:2
	global_load_ushort v78, v109, s[72:73] offset:3070
	global_load_ushort v34, v109, s[72:73] offset:3072
	global_load_ushort v79, v52, s[72:73] offset:2
	global_load_ushort v33, v109, s[0:1] offset:3072
	global_load_ushort v76, v109, s[4:5] offset:3072
	s_waitcnt vmcnt(0)
	v_add_u32_e32 v26, 0x80000, v26
	v_lshlrev_b32_e32 v11, 16, v11
	v_lshlrev_b32_e32 v13, 16, v13
	v_lshlrev_b32_e32 v9, 16, v9
	v_mul_f32_e32 v9, v16, v9
	v_fmac_f32_e32 v9, v14, v11
	v_fmac_f32_e32 v9, v17, v13
	v_add_f32_e32 v9, v12, v9
	v_fma_f32 v27, v55, v8, v4
	v_mul_f32_e32 v70, v27, v9
	v_lshlrev_b32_e32 v85, 16, v85
	v_mul_f32_e32 v84, 0xbfb8aa3b, v85
	v_exp_f32_e32 v84, v84
	s_nop 0
	v_add_f32_e32 v84, 1.0, v84
	v_div_scale_f32 v71, s[74:75], v84, v84, v85
	v_rcp_f32_e32 v82, v71
	s_nop 0
	v_fma_f32 v92, -v71, v82, 1.0
	v_fmac_f32_e32 v82, v92, v82
	v_div_scale_f32 v88, vcc, v85, v84, v85
	v_mul_f32_e32 v90, v88, v82
	v_fma_f32 v92, -v71, v90, v88
	v_fmac_f32_e32 v90, v92, v82
	v_fma_f32 v71, -v71, v90, v88
	v_div_fmas_f32 v71, v71, v82, v90
	v_div_fixup_f32 v85, v71, v84, v85
	v_mul_f32_e32 v70, v70, v85
	v_cvt_pk_bf16_f32 v70, v70, s0
	global_store_short v26, v70, s[70:71]
	v_lshlrev_b32_e32 v81, 16, v81
	v_lshlrev_b32_e32 v83, 16, v83
	v_lshlrev_b32_e32 v15, 16, v15
	v_mul_f32_e32 v15, v16, v15
	v_fmac_f32_e32 v15, v14, v81
	v_fmac_f32_e32 v15, v17, v83
	v_add_f32_e32 v15, v12, v15
	v_fma_f32 v27, v57, v8, v5
	v_mul_f32_e32 v70, v27, v15
	v_lshlrev_b32_e32 v87, 16, v87
	v_mul_f32_e32 v84, 0xbfb8aa3b, v87
	v_exp_f32_e32 v84, v84
	s_nop 0
	v_add_f32_e32 v84, 1.0, v84
	v_div_scale_f32 v71, s[74:75], v84, v84, v87
	v_rcp_f32_e32 v82, v71
	s_nop 0
	v_fma_f32 v92, -v71, v82, 1.0
	v_fmac_f32_e32 v82, v92, v82
	v_div_scale_f32 v88, vcc, v87, v84, v87
	v_mul_f32_e32 v90, v88, v82
	v_fma_f32 v92, -v71, v90, v88
	v_fmac_f32_e32 v90, v92, v82
	v_fma_f32 v71, -v71, v90, v88
	v_div_fmas_f32 v71, v71, v82, v90
	v_div_fixup_f32 v87, v71, v84, v87
	v_mul_f32_e32 v70, v70, v87
	v_cvt_pk_bf16_f32 v70, v70, s0
	global_store_short v26, v70, s[18:19]
	v_add_u32_e32 v26, 0x80000, v26
	v_lshlrev_b32_e32 v91, 16, v91
	v_lshlrev_b32_e32 v93, 16, v93
	v_lshlrev_b32_e32 v89, 16, v89
	v_mul_f32_e32 v89, v16, v89
	v_fmac_f32_e32 v89, v14, v91
	v_fmac_f32_e32 v89, v17, v93
	v_add_f32_e32 v89, v12, v89
	v_fma_f32 v27, v54, v8, v6
	v_mul_f32_e32 v70, v27, v89
	v_lshlrev_b32_e32 v97, 16, v97
	v_mul_f32_e32 v84, 0xbfb8aa3b, v97
	v_exp_f32_e32 v84, v84
	s_nop 0
	v_add_f32_e32 v84, 1.0, v84
	v_div_scale_f32 v71, s[74:75], v84, v84, v97
	v_rcp_f32_e32 v82, v71
	s_nop 0
	v_fma_f32 v92, -v71, v82, 1.0
	v_fmac_f32_e32 v82, v92, v82
	v_div_scale_f32 v88, vcc, v97, v84, v97
	v_mul_f32_e32 v90, v88, v82
	v_fma_f32 v92, -v71, v90, v88
	v_fmac_f32_e32 v90, v92, v82
	v_fma_f32 v71, -v71, v90, v88
	v_div_fmas_f32 v71, v71, v82, v90
	v_div_fixup_f32 v97, v71, v84, v97
	v_mul_f32_e32 v70, v70, v97
	v_cvt_pk_bf16_f32 v70, v70, s0
	global_store_short v26, v70, s[70:71]
	v_lshlrev_b32_e32 v95, 16, v95
	v_lshlrev_b32_e32 v96, 16, v96
	v_lshlrev_b32_e32 v94, 16, v94
	v_mul_f32_e32 v94, v16, v94
	v_fmac_f32_e32 v94, v14, v95
	v_fmac_f32_e32 v94, v17, v96
	v_add_f32_e32 v94, v12, v94
	v_fma_f32 v27, v56, v8, v7
	v_mul_f32_e32 v70, v27, v94
	v_lshlrev_b32_e32 v98, 16, v98
	v_mul_f32_e32 v84, 0xbfb8aa3b, v98
	v_exp_f32_e32 v84, v84
	s_nop 0
	v_add_f32_e32 v84, 1.0, v84
	v_div_scale_f32 v71, s[74:75], v84, v84, v98
	v_rcp_f32_e32 v82, v71
	s_nop 0
	v_fma_f32 v92, -v71, v82, 1.0
	v_fmac_f32_e32 v82, v92, v82
	v_div_scale_f32 v88, vcc, v98, v84, v98
	v_mul_f32_e32 v90, v88, v82
	v_fma_f32 v92, -v71, v90, v88
	v_fmac_f32_e32 v90, v92, v82
	v_fma_f32 v71, -v71, v90, v88
	v_div_fmas_f32 v71, v71, v82, v90
	v_div_fixup_f32 v98, v71, v84, v98
	v_mul_f32_e32 v70, v70, v98
	v_cvt_pk_bf16_f32 v70, v70, s0
	global_store_short v26, v70, s[18:19]
	v_add_u32_e32 v26, 0x80000, v26
	v_lshlrev_b32_e32 v100, 16, v100
	v_lshlrev_b32_e32 v101, 16, v101
	v_lshlrev_b32_e32 v99, 16, v99
	v_mul_f32_e32 v99, v16, v99
	v_fmac_f32_e32 v99, v14, v100
	v_fmac_f32_e32 v99, v17, v101
	v_add_f32_e32 v99, v12, v99
	v_fma_f32 v27, v59, v8, v0
	v_mul_f32_e32 v70, v27, v99
	v_lshlrev_b32_e32 v105, 16, v105
	v_mul_f32_e32 v84, 0xbfb8aa3b, v105
	v_exp_f32_e32 v84, v84
	s_nop 0
	v_add_f32_e32 v84, 1.0, v84
	v_div_scale_f32 v71, s[74:75], v84, v84, v105
	v_rcp_f32_e32 v82, v71
	s_nop 0
	v_fma_f32 v92, -v71, v82, 1.0
	v_fmac_f32_e32 v82, v92, v82
	v_div_scale_f32 v88, vcc, v105, v84, v105
	v_mul_f32_e32 v90, v88, v82
	v_fma_f32 v92, -v71, v90, v88
	v_fmac_f32_e32 v90, v92, v82
	v_fma_f32 v71, -v71, v90, v88
	v_div_fmas_f32 v71, v71, v82, v90
	v_div_fixup_f32 v105, v71, v84, v105
	v_mul_f32_e32 v70, v70, v105
	v_cvt_pk_bf16_f32 v70, v70, s0
	global_store_short v26, v70, s[70:71]
	v_lshlrev_b32_e32 v103, 16, v103
	v_lshlrev_b32_e32 v104, 16, v104
	v_lshlrev_b32_e32 v102, 16, v102
	v_mul_f32_e32 v102, v16, v102
	v_fmac_f32_e32 v102, v14, v103
	v_fmac_f32_e32 v102, v17, v104
	v_add_f32_e32 v102, v12, v102
	v_fma_f32 v27, v61, v8, v1
	v_mul_f32_e32 v70, v27, v102
	v_lshlrev_b32_e32 v106, 16, v106
	v_mul_f32_e32 v84, 0xbfb8aa3b, v106
	v_exp_f32_e32 v84, v84
	s_nop 0
	v_add_f32_e32 v84, 1.0, v84
	v_div_scale_f32 v71, s[74:75], v84, v84, v106
	v_rcp_f32_e32 v82, v71
	s_nop 0
	v_fma_f32 v92, -v71, v82, 1.0
	v_fmac_f32_e32 v82, v92, v82
	v_div_scale_f32 v88, vcc, v106, v84, v106
	v_mul_f32_e32 v90, v88, v82
	v_fma_f32 v92, -v71, v90, v88
	v_fmac_f32_e32 v90, v92, v82
	v_fma_f32 v71, -v71, v90, v88
	v_div_fmas_f32 v71, v71, v82, v90
	v_div_fixup_f32 v106, v71, v84, v106
	v_mul_f32_e32 v70, v70, v106
	v_cvt_pk_bf16_f32 v70, v70, s0
	global_store_short v26, v70, s[18:19]
	v_add_u32_e32 v26, 0x80000, v26
	v_lshlrev_b32_e32 v108, 16, v108
	v_lshlrev_b32_e32 v32, 16, v32
	v_lshlrev_b32_e32 v107, 16, v107
	v_mul_f32_e32 v107, v16, v107
	v_mul_f32_e32 v32, v21, v32
	v_fmac_f32_e32 v107, v14, v108
	v_fmac_f32_e32 v107, v17, v32
	v_add_f32_e32 v107, v12, v107
	v_fma_f32 v27, v58, v8, v2
	v_mul_f32_e32 v70, v27, v107
	v_lshlrev_b32_e32 v33, 16, v33
	v_mul_f32_e32 v84, 0xbfb8aa3b, v33
	v_exp_f32_e32 v84, v84
	s_nop 0
	v_add_f32_e32 v84, 1.0, v84
	v_div_scale_f32 v71, s[74:75], v84, v84, v33
	v_rcp_f32_e32 v82, v71
	s_nop 0
	v_fma_f32 v92, -v71, v82, 1.0
	v_fmac_f32_e32 v82, v92, v82
	v_div_scale_f32 v88, vcc, v33, v84, v33
	v_mul_f32_e32 v90, v88, v82
	v_fma_f32 v92, -v71, v90, v88
	v_fmac_f32_e32 v90, v92, v82
	v_fma_f32 v71, -v71, v90, v88
	v_div_fmas_f32 v71, v71, v82, v90
	v_div_fixup_f32 v33, v71, v84, v33
	v_mul_f32_e32 v70, v70, v33
	v_cvt_pk_bf16_f32 v70, v70, s0
	global_store_short v26, v70, s[70:71]
	v_lshlrev_b32_e32 v34, 16, v34
	v_lshlrev_b32_e32 v79, 16, v79
	v_lshlrev_b32_e32 v78, 16, v78
	v_mul_f32_e32 v78, v16, v78
	v_mul_f32_e32 v79, v21, v79
	v_fmac_f32_e32 v78, v14, v34
	v_fmac_f32_e32 v78, v17, v79
	v_add_f32_e32 v78, v12, v78
	v_fma_f32 v27, v60, v8, v3
	v_mul_f32_e32 v70, v27, v78
	v_lshlrev_b32_e32 v76, 16, v76
	v_mul_f32_e32 v84, 0xbfb8aa3b, v76
	v_exp_f32_e32 v84, v84
	s_nop 0
	v_add_f32_e32 v84, 1.0, v84
	v_div_scale_f32 v71, s[74:75], v84, v84, v76
	v_rcp_f32_e32 v82, v71
	s_nop 0
	v_fma_f32 v92, -v71, v82, 1.0
	v_fmac_f32_e32 v82, v92, v82
	v_div_scale_f32 v88, vcc, v76, v84, v76
	v_mul_f32_e32 v90, v88, v82
	v_fma_f32 v92, -v71, v90, v88
	v_fmac_f32_e32 v90, v92, v82
	v_fma_f32 v71, -v71, v90, v88
	v_div_fmas_f32 v71, v71, v82, v90
	v_div_fixup_f32 v76, v71, v84, v76
	v_mul_f32_e32 v70, v70, v76
	v_cvt_pk_bf16_f32 v70, v70, s0
	global_store_short v26, v70, s[18:19]
	s_mov_b64 s[74:75], 0
